# weight-conversion completion counter (write-through conversion stores + device counter checked after the next D-phase barrier) lets post-GU barriers of layers>=1 be XCD-local
# speedup vs baseline: 1.0113x; 1.0113x over previous
; #define LAS __attribute__((address_space(3)))
; #define GSYNC() do { _Pragma("unroll 1") for (int sy_ = 0; sy_ < PROBE_SYNCREP; ++sy_) xcd_barrier(xbar); } while (0)
; __global__ void __launch_bounds__(NTHR, 2) mega_fwd(Args a) {
;     ...
;             { const int first = ((T / 256) * (NGU / 256)) % G, nidle = G - first;
;               const int cl = f ? l + 1 : l, lo = f ? 0 : (l == 0 ? 2 * I_G : PER / 2), hi = f ? PER / 2 : PER;
;               if (cl < DEPTH && bx >= first) { int tid_ = threadIdx.x; asm volatile("" : "+v"(tid_)); const int lane = tid_ & 63, wave = __builtin_amdgcn_readfirstlane(tid_ >> 6);
;                   constexpr int D2_LO = 2 * (2 * I_G + I_D) + I_IN + I_OUT - I_D, D2_HI = D2_LO + I_D;
;                   const int gwt = (bx - first) * NWAVES + wave, ngt = nidle * NWAVES;
;                   if (l == 0 && f == 0) { convert_items(a, lds, 0, lo, D2_LO, gwt, ngt, wave, lane); convert_items(a, lds, 0, D2_HI, PER, gwt, ngt, wave, lane); }
;                   else { convert_items(a, lds, cl, lo, hi, gwt, ngt, wave, lane); if (l == 0 && f == 1) convert_items(a, lds, 0, D2_LO, D2_HI, gwt, ngt, wave, lane); } } }
;             GSYNC();
;             { pg8::Gemm g{HB, wl + (f ? W_D2 : W_D1), T, D, FF}; pg8::StaticOrder S; S.init(T, D, G, bx); pg8::EpiRes E{XB, SS, 0.5f, (LAS float*)(lds + 131072 + 256)};
;               pg8::gemm_phase<pg8::EpiRes, pg8::StaticOrder, true, true>(lds, g, S, E); }
;             GSYNC();
.LBB0_104:
	s_or_b64 exec, exec, s[38:39]
	s_and_saveexec_b64 s[38:39], s[80:81]
	s_cbranch_execz .Lcv_done
	v_mov_b32_e32 v5, 0x2000c
	ds_read_b32 v5, v5
	v_readlane_b32 s4, v254, 51
	s_cmp_eq_u32 s4, 0
	s_cbranch_scc1 .Lcv_done
	s_waitcnt lgkmcnt(0)
	v_readfirstlane_b32 s5, v5
	s_cmp_lg_u32 s5, 0
	s_cbranch_scc1 .Lcv_done
	v_readlane_b32 s5, v255, 10
	s_and_b32 s5, s5, 1
	s_lshl_b32 s4, s4, 1
	s_add_i32 s4, s4, s5
	s_add_i32 s4, s4, 1
	s_lshl_b32 s4, s4, 7
	v_mov_b32_e32 v5, 0x3f00
	s_movk_i32 s5, 0x100
.Lcv_loop:
	global_load_dword v2, v5, s[50:51] sc1
	s_waitcnt vmcnt(0)
	v_readfirstlane_b32 s28, v2
	s_cmp_ge_u32 s28, s4
	s_cbranch_scc1 .Lcv_done
	s_sleep 1
	s_sub_i32 s5, s5, 1
	s_cmp_lg_u32 s5, 0
	s_cbranch_scc1 .Lcv_loop

; template <bool HASG>
; __device__ __forceinline__ void tr_item(const float* W, int K, int N, bf16* WT, int rowmode, const float* g, LAS float* scr, int item, int lane) {
;     ...
;     const float* wp = W + (size_t)(k0 + (lane >> 5)) * N + n0 + (lane & 31);
;     const int c = lane & 7;
;     float v[32];
; #pragma unroll
;     for (int i = 0; i < 32; ++i) v[i] = wp[(size_t)(2 * i) * N];
;     f32x4 g0 = (f32x4){1.f, 1.f, 1.f, 1.f}, g1 = g0;
;     if (HASG) { g0 = *(const f32x4*)(g + k0 + 8 * c); g1 = *(const f32x4*)(g + k0 + 8 * c + 4); }
;     asm volatile("" ::: "memory");
; #pragma unroll
;     for (int i = 0; i < 32; ++i) scr[(2 * i + (lane >> 5)) * 33 + (lane & 31)] = v[i];
; __device__ __forceinline__ void convert_items(const Args& a, LAS unsigned char* lds, int l, int it_lo, int it_hi, int gw, int NGW, int wave, int lane) {
;     ...
;         if (r < I_G) { tr_item<true>(a.in[2] + o_gu, D, FF, wl + W_GU1, 1, a.in[1] + l * D, scr, r, lane); continue; } r -= I_G;
;         if (r < I_G) { tr_item<true>(a.in[3] + o_gu, D, FF, wl + W_GU1, 2, a.in[1] + l * D, scr, r, lane); continue; } r -= I_G;
;         if (r < I_D) { tr_item<false>(a.in[4] + o_d, FF, D, wl + W_D1, 0, nullptr, scr, r, lane); continue; } r -= I_D;
;         if (r < I_IN) { tr_item<true>(a.in[6] + (size_t)l * D * DIN, D, DIN, wl + W_IN, 0, a.in[5] + l * D, scr, r, lane); continue; } r -= I_IN;
;         if (r < I_OUT) { tr_item<false>(a.in[18] + (size_t)l * D * D, D, D, wl + W_OUT, 0, nullptr, scr, r, lane); continue; } r -= I_OUT;
;         if (r < I_G) { tr_item<true>(a.in[20] + o_gu, D, FF, wl + W_GU2, 1, a.in[19] + l * D, scr, r, lane); continue; } r -= I_G;
;         if (r < I_G) { tr_item<true>(a.in[21] + o_gu, D, FF, wl + W_GU2, 2, a.in[19] + l * D, scr, r, lane); continue; } r -= I_G;
;         if (r < I_D) { tr_item<false>(a.in[22] + o_d, FF, D, wl + W_D2, 0, nullptr, scr, r, lane); continue; } r -= I_D;
;         { const int mat = r >> 1, nbk = r & 1, gate = mat & 1, blk = (mat >> 1) & 7, d = mat >> 4;
;           const float* src = (gate ? a.in[11] : a.in[9]) + (size_t)((l * 2 + d) * 8 + blk) * 4096;
;           tr_item<false>(src, 64, 64, wl + W_LRU + (size_t)((d * 8 + blk) * 2 + gate) * 4096, 0, nullptr, scr, nbk, lane); }
.LBB0_477:
	s_cmpk_gt_i32 s67, 0x57f
	s_mov_b64 s[28:29], -1
	s_cbranch_scc0 .LBB0_507
	s_cmpk_gt_u32 s67, 0xaff
	s_cbranch_scc0 .LBB0_504
	s_cmpk_gt_u32 s67, 0x107f
	s_cbranch_scc0 .LBB0_501
	s_cmpk_gt_u32 s67, 0x13ff
	s_cbranch_scc0 .LBB0_498
	s_cmpk_gt_u32 s67, 0x15ff
	s_cbranch_scc0 .LBB0_495
	s_cmpk_gt_u32 s67, 0x1b7f
	s_cbranch_scc0 .LBB0_492
	s_cmpk_gt_u32 s67, 0x20ff
	s_cbranch_scc0 .LBB0_489
	s_cmpk_gt_u32 s67, 0x267f
	s_cbranch_scc0 .LBB0_486
	s_add_i32 s28, s67, 0xffffd980
	s_bfe_u32 s47, s67, 0x10001
	s_bfe_u32 s64, s67, 0x30002
	s_lshr_b32 s65, s28, 5
	v_readlane_b32 s4, v252, 16
	s_cmp_eq_u32 s47, 0
	v_readlane_b32 s6, v252, 18
	v_readlane_b32 s7, v252, 19
	v_readlane_b32 s10, v252, 22
	v_readlane_b32 s11, v252, 23
	s_cselect_b32 s61, s7, s11
	s_cselect_b32 s60, s6, s10
	s_lshl_b32 s28, s65, 3
	v_readlane_b32 s4, v255, 12
	s_add_i32 s28, s28, s4
	s_or_b32 s88, s28, s64
	s_lshl_b64 s[28:29], s[88:89], 14
	s_add_u32 s60, s60, s28
	s_addc_u32 s61, s61, s29
	s_lshl_b32 s28, s65, 4
	s_lshl_b32 s29, s64, 1
	s_or_b32 s28, s28, s29
	s_or_b32 s88, s28, s47
	s_lshl_b32 s28, s67, 5
	s_and_b32 s28, s28, 32
	v_mov_b32_e32 v29, v1
	s_lshl_b64 s[64:65], s[88:89], 13
	v_lshl_add_u64 v[2:3], s[60:61], 0, v[28:29]
	s_lshl_b32 s88, s28, 2
	v_lshl_add_u64 v[2:3], v[2:3], 0, s[88:89]
	v_lshlrev_b32_e32 v0, 2, v6
	v_lshl_add_u64 v[2:3], v[2:3], 0, v[0:1]
	s_movk_i32 s4, 0x1000
	global_load_dword v0, v[2:3], off
	global_load_dword v29, v[2:3], off offset:512
	global_load_dword v40, v[2:3], off offset:1024
	global_load_dword v41, v[2:3], off offset:1536
	global_load_dword v42, v[2:3], off offset:2048
	global_load_dword v43, v[2:3], off offset:2560
	global_load_dword v44, v[2:3], off offset:3072
	global_load_dword v45, v[2:3], off offset:3584
	v_add_co_u32_e32 v4, vcc, s4, v2
	s_movk_i32 s4, 0x2000
	s_nop 0
	v_addc_co_u32_e32 v5, vcc, 0, v3, vcc
	v_add_co_u32_e32 v30, vcc, s4, v2
	s_movk_i32 s4, 0x3000
	s_nop 0
	v_addc_co_u32_e32 v31, vcc, 0, v3, vcc
	global_load_dword v46, v[30:31], off offset:-4096
	global_load_dword v47, v[4:5], off offset:512
	global_load_dword v48, v[4:5], off offset:1024
	global_load_dword v49, v[4:5], off offset:1536
	global_load_dword v50, v[4:5], off offset:2048
	global_load_dword v51, v[4:5], off offset:2560
	global_load_dword v52, v[4:5], off offset:3072
	s_nop 0
	global_load_dword v4, v[4:5], off offset:3584
	s_nop 0
	global_load_dword v5, v[30:31], off
	global_load_dword v53, v[30:31], off offset:512
	global_load_dword v54, v[30:31], off offset:1024
	global_load_dword v55, v[30:31], off offset:1536
	global_load_dword v56, v[30:31], off offset:2048
	global_load_dword v57, v[30:31], off offset:2560
	global_load_dword v58, v[30:31], off offset:3072
	s_nop 0
	global_load_dword v30, v[30:31], off offset:3584
	v_add_co_u32_e32 v2, vcc, s4, v2
	v_readlane_b32 s8, v252, 20
	s_nop 0
	v_addc_co_u32_e32 v3, vcc, 0, v3, vcc
	global_load_dword v31, v[2:3], off
	global_load_dword v59, v[2:3], off offset:512
	global_load_dword v60, v[2:3], off offset:1024
	global_load_dword v61, v[2:3], off offset:1536
	global_load_dword v62, v[2:3], off offset:2048
	global_load_dword v63, v[2:3], off offset:2560
	global_load_dword v64, v[2:3], off offset:3072
	s_nop 0
	global_load_dword v2, v[2:3], off offset:3584
	v_readlane_b32 s9, v252, 21
	v_readlane_b32 s5, v252, 17
	v_readlane_b32 s12, v252, 24
	v_readlane_b32 s13, v252, 25
	v_readlane_b32 s14, v252, 26
	v_readlane_b32 s15, v252, 27
	v_readlane_b32 s16, v252, 28
	v_readlane_b32 s17, v252, 29
	v_readlane_b32 s18, v252, 30
	v_readlane_b32 s19, v252, 31
	s_mov_b64 s[8:9], s[26:27]
	s_waitcnt vmcnt(30)
	ds_write2_b32 v34, v0, v29 offset1:66
	s_waitcnt vmcnt(28)
	ds_write2_b32 v34, v40, v41 offset0:132 offset1:198
	v_add_u32_e32 v0, 0x400, v34
	s_waitcnt vmcnt(26)
	ds_write2_b32 v0, v42, v43 offset0:8 offset1:74
	s_waitcnt vmcnt(24)
	ds_write2_b32 v0, v44, v45 offset0:140 offset1:206
	v_add_u32_e32 v0, 0x800, v34
	s_waitcnt vmcnt(22)
	ds_write2_b32 v0, v46, v47 offset0:16 offset1:82
	s_waitcnt vmcnt(20)
	ds_write2_b32 v0, v48, v49 offset0:148 offset1:214
	v_add_u32_e32 v0, 0xc00, v34
	s_waitcnt vmcnt(18)
	ds_write2_b32 v0, v50, v51 offset0:24 offset1:90
	s_waitcnt vmcnt(16)
	ds_write2_b32 v0, v52, v4 offset0:156 offset1:222
	v_add_u32_e32 v0, 0x1000, v34
	s_waitcnt vmcnt(14)
	ds_write2_b32 v0, v5, v53 offset0:32 offset1:98
	s_waitcnt vmcnt(12)
	ds_write2_b32 v0, v54, v55 offset0:164 offset1:230
	v_add_u32_e32 v0, 0x1400, v34
	s_waitcnt vmcnt(10)
	ds_write2_b32 v0, v56, v57 offset0:40 offset1:106
	s_waitcnt vmcnt(8)
	ds_write2_b32 v0, v58, v30 offset0:172 offset1:238
	v_add_u32_e32 v0, 0x1800, v34
	s_waitcnt vmcnt(6)
	ds_write2_b32 v0, v31, v59 offset0:48 offset1:114
	s_waitcnt vmcnt(4)
	ds_write2_b32 v0, v60, v61 offset0:180 offset1:246
	v_add_u32_e32 v0, 0x1c00, v34
	s_waitcnt vmcnt(2)
	ds_write2_b32 v0, v62, v63 offset0:56 offset1:122
	s_waitcnt vmcnt(0)
	ds_write2_b32 v0, v64, v2 offset0:188 offset1:254
	s_waitcnt lgkmcnt(0)
	ds_read2_b32 v[4:5], v36 offset0:33 offset1:41
	ds_read2_b32 v[30:31], v36 offset1:8
	ds_read2_b32 v[44:45], v36 offset0:66 offset1:74
	ds_read2_b32 v[46:47], v36 offset0:99 offset1:107
	ds_read2_b32 v[48:49], v36 offset0:132 offset1:140
	ds_read2_b32 v[50:51], v36 offset0:165 offset1:173
	ds_read2_b32 v[52:53], v36 offset0:198 offset1:206
	ds_read2_b32 v[54:55], v36 offset0:231 offset1:239
	s_waitcnt lgkmcnt(7)
	v_bfe_u32 v29, v4, 16, 1
	s_waitcnt lgkmcnt(6)
	v_bfe_u32 v0, v30, 16, 1
	v_add3_u32 v0, v30, v0, s91
	v_lshrrev_b32_e32 v0, 16, v0
	v_add3_u32 v4, v4, v29, s91
	v_and_or_b32 v40, v4, s35, v0
	s_waitcnt lgkmcnt(5)
	v_bfe_u32 v0, v44, 16, 1
	v_add3_u32 v0, v44, v0, s91
	s_waitcnt lgkmcnt(4)
; #define LAS __attribute__((address_space(3)))
; __device__ __forceinline__ unsigned pk2(float lo, float hi) { return f2bf(lo) | (f2bf(hi) << 16); }
; #define LDS_WAVE_SYNC() asm volatile("s_waitcnt lgkmcnt(0)" ::: "memory")
; template <bool HASG>
; __device__ __forceinline__ void tr_item(const float* W, int K, int N, bf16* WT, int rowmode, const float* g, LAS float* scr, int item, int lane) {
;     ...
;     for (int i = 0; i < 32; ++i) scr[(2 * i + (lane >> 5)) * 33 + (lane & 31)] = v[i];
;     LDS_WAVE_SYNC();
;     const int drow0 = rowmode == 0 ? n0 : ((n0 >> 7) * 256 + (n0 & 127) + (rowmode == 2 ? 128 : 0));
; #pragma unroll
;     for (int j = 0; j < 4; ++j) { const int n = (lane >> 3) + 8 * j; const LAS float* s = scr + (8 * c) * 33 + n;
;         u32x4 o; o.x = pk2(s[0 * 33] * g0.x, s[1 * 33] * g0.y); o.y = pk2(s[2 * 33] * g0.z, s[3 * 33] * g0.w);
;         o.z = pk2(s[4 * 33] * g1.x, s[5 * 33] * g1.y); o.w = pk2(s[6 * 33] * g1.z, s[7 * 33] * g1.w);
;         *(u32x4*)(WT + (size_t)(drow0 + n) * K + k0 + 8 * c) = o; }
;     LDS_WAVE_SYNC();
; __device__ __forceinline__ void convert_items(const Args& a, LAS unsigned char* lds, int l, int it_lo, int it_hi, int gw, int NGW, int wave, int lane) {
;     ...
;         if (r < I_D) { tr_item<false>(a.in[22] + o_d, FF, D, wl + W_D2, 0, nullptr, scr, r, lane); continue; } r -= I_D;
	v_bfe_u32 v4, v46, 16, 1
	v_lshrrev_b32_e32 v0, 16, v0
	v_add3_u32 v4, v46, v4, s91
	v_and_or_b32 v41, v4, s35, v0
	s_waitcnt lgkmcnt(3)
	v_bfe_u32 v0, v48, 16, 1
	v_add3_u32 v0, v48, v0, s91
	s_waitcnt lgkmcnt(2)
	v_bfe_u32 v4, v50, 16, 1
	v_lshrrev_b32_e32 v0, 16, v0
	v_add3_u32 v4, v50, v4, s91
	v_and_or_b32 v42, v4, s35, v0
	s_waitcnt lgkmcnt(1)
	v_bfe_u32 v0, v52, 16, 1
	v_add3_u32 v0, v52, v0, s91
	s_waitcnt lgkmcnt(0)
	v_bfe_u32 v4, v54, 16, 1
	v_lshrrev_b32_e32 v0, 16, v0
	v_add3_u32 v4, v54, v4, s91
	v_and_or_b32 v43, v4, s35, v0
	v_or_b32_e32 v0, s28, v35
	v_lshl_add_u64 v[2:3], v[10:11], 0, s[64:65]
	v_lshlrev_b32_e32 v0, 7, v0
	v_lshl_add_u64 v[56:57], v[2:3], 0, v[0:1]
	v_bfe_u32 v0, v31, 16, 1
	v_add3_u32 v0, v31, v0, s91
	v_bfe_u32 v4, v5, 16, 1
	v_lshrrev_b32_e32 v0, 16, v0
	v_add3_u32 v4, v5, v4, s91
	global_store_dwordx4 v[56:57], v[40:43], off sc1
	s_nop 1
	v_and_or_b32 v40, v4, s35, v0
	v_bfe_u32 v0, v45, 16, 1
	v_add3_u32 v0, v45, v0, s91
	v_bfe_u32 v4, v47, 16, 1
	v_lshrrev_b32_e32 v0, 16, v0
	v_add3_u32 v4, v47, v4, s91
	v_and_or_b32 v41, v4, s35, v0
	v_bfe_u32 v0, v49, 16, 1
	v_add3_u32 v0, v49, v0, s91
	v_bfe_u32 v4, v51, 16, 1
	v_lshrrev_b32_e32 v0, 16, v0
	v_add3_u32 v4, v51, v4, s91
	v_and_or_b32 v42, v4, s35, v0
	v_bfe_u32 v0, v53, 16, 1
	v_add3_u32 v0, v53, v0, s91
	v_bfe_u32 v4, v55, 16, 1
	v_lshrrev_b32_e32 v0, 16, v0
	v_add3_u32 v4, v55, v4, s91
	v_and_or_b32 v43, v4, s35, v0
	v_or_b32_e32 v0, s28, v37
	v_lshlrev_b32_e32 v0, 7, v0
	v_lshl_add_u64 v[4:5], v[2:3], 0, v[0:1]
	global_store_dwordx4 v[4:5], v[40:43], off sc1
	ds_read2_b32 v[4:5], v36 offset0:49 offset1:57
	ds_read2_b32 v[30:31], v36 offset0:16 offset1:24
	ds_read2_b32 v[44:45], v36 offset0:82 offset1:90
	ds_read2_b32 v[46:47], v36 offset0:115 offset1:123
	ds_read2_b32 v[48:49], v36 offset0:148 offset1:156
	ds_read2_b32 v[50:51], v36 offset0:181 offset1:189
	ds_read2_b32 v[52:53], v36 offset0:214 offset1:222
	ds_read2_b32 v[54:55], v36 offset0:247 offset1:255
	s_waitcnt lgkmcnt(7)
	v_bfe_u32 v29, v4, 16, 1
	s_waitcnt lgkmcnt(6)
	v_bfe_u32 v0, v30, 16, 1
	v_add3_u32 v0, v30, v0, s91
	v_lshrrev_b32_e32 v0, 16, v0
	v_add3_u32 v4, v4, v29, s91
	v_and_or_b32 v40, v4, s35, v0
	s_waitcnt lgkmcnt(5)
	v_bfe_u32 v0, v44, 16, 1
	v_add3_u32 v0, v44, v0, s91
	s_waitcnt lgkmcnt(4)
	v_bfe_u32 v4, v46, 16, 1
	v_lshrrev_b32_e32 v0, 16, v0
	v_add3_u32 v4, v46, v4, s91
	v_and_or_b32 v41, v4, s35, v0
	s_waitcnt lgkmcnt(3)
	v_bfe_u32 v0, v48, 16, 1
	v_add3_u32 v0, v48, v0, s91
	s_waitcnt lgkmcnt(2)
	v_bfe_u32 v4, v50, 16, 1
	v_lshrrev_b32_e32 v0, 16, v0
	v_add3_u32 v4, v50, v4, s91
	v_and_or_b32 v42, v4, s35, v0
	s_waitcnt lgkmcnt(1)
	v_bfe_u32 v0, v52, 16, 1
	v_add3_u32 v0, v52, v0, s91
	s_waitcnt lgkmcnt(0)
	v_bfe_u32 v4, v54, 16, 1
	v_lshrrev_b32_e32 v0, 16, v0
	v_add3_u32 v4, v54, v4, s91
	v_and_or_b32 v43, v4, s35, v0
	v_or_b32_e32 v0, s28, v38
	v_lshlrev_b32_e32 v0, 7, v0
	v_lshl_add_u64 v[56:57], v[2:3], 0, v[0:1]
	v_bfe_u32 v0, v31, 16, 1
	v_add3_u32 v0, v31, v0, s91
	v_bfe_u32 v4, v5, 16, 1
	v_lshrrev_b32_e32 v0, 16, v0
	v_add3_u32 v4, v5, v4, s91
	global_store_dwordx4 v[56:57], v[40:43], off sc1
	s_nop 1
	v_and_or_b32 v40, v4, s35, v0
	v_bfe_u32 v0, v45, 16, 1
	v_add3_u32 v0, v45, v0, s91
	v_bfe_u32 v4, v47, 16, 1
	v_lshrrev_b32_e32 v0, 16, v0
	v_add3_u32 v4, v47, v4, s91
	v_and_or_b32 v41, v4, s35, v0
	v_bfe_u32 v0, v49, 16, 1
	v_add3_u32 v0, v49, v0, s91
	v_bfe_u32 v4, v51, 16, 1
	v_lshrrev_b32_e32 v0, 16, v0
	v_add3_u32 v4, v51, v4, s91
	v_and_or_b32 v42, v4, s35, v0
	v_bfe_u32 v0, v53, 16, 1
	v_add3_u32 v0, v53, v0, s91
	v_bfe_u32 v4, v55, 16, 1
	v_lshrrev_b32_e32 v0, 16, v0
	v_add3_u32 v4, v55, v4, s91
	v_and_or_b32 v43, v4, s35, v0
	v_or_b32_e32 v0, s28, v39
	v_lshlrev_b32_e32 v0, 7, v0
	v_lshl_add_u64 v[2:3], v[2:3], 0, v[0:1]
	global_store_dwordx4 v[2:3], v[40:43], off sc1
	s_waitcnt lgkmcnt(0)
	s_mov_b64 s[28:29], 0
.LBB0_486:
	s_andn2_b64 vcc, exec, s[28:29]
	s_cbranch_vccnz .LBB0_488
	s_and_b32 s29, s66, 0x1ffc0
	s_lshl_b32 s28, s67, 5
	v_or_b32_e32 v0, s29, v33
	v_readlane_b32 s4, v255, 13
	s_and_b32 s28, s28, 0x3e0
	v_lshlrev_b32_e32 v0, 12, v0
	v_readlane_b32 s5, v255, 14
	s_lshl_b32 s88, s28, 2
	s_nop 0
	v_lshl_add_u64 v[2:3], s[4:5], 0, v[0:1]
	v_lshl_add_u64 v[2:3], v[2:3], 0, s[88:89]
	v_lshlrev_b32_e32 v0, 2, v6
	v_lshl_add_u64 v[2:3], v[2:3], 0, v[0:1]
	v_add_co_u32_e32 v4, vcc, 0x2000, v2
	global_load_dword v0, v[2:3], off
	s_nop 0
	v_addc_co_u32_e32 v5, vcc, 0, v3, vcc
	global_load_dword v29, v[4:5], off
	v_add_co_u32_e32 v4, vcc, 0x4000, v2
	s_mov_b32 s4, 0x12000
	s_nop 0
	v_addc_co_u32_e32 v5, vcc, 0, v3, vcc
	global_load_dword v30, v[4:5], off
	v_add_co_u32_e32 v4, vcc, 0x6000, v2
	s_lshl_b32 s88, s29, 1
	s_nop 0
	v_addc_co_u32_e32 v5, vcc, 0, v3, vcc
	global_load_dword v31, v[4:5], off
	v_add_co_u32_e32 v4, vcc, 0x8000, v2
	s_nop 1
	v_addc_co_u32_e32 v5, vcc, 0, v3, vcc
	global_load_dword v40, v[4:5], off
	v_add_co_u32_e32 v4, vcc, 0xa000, v2
	s_nop 1
	v_addc_co_u32_e32 v5, vcc, 0, v3, vcc
	global_load_dword v41, v[4:5], off
	v_add_co_u32_e32 v4, vcc, 0xc000, v2
	s_nop 1
	v_addc_co_u32_e32 v5, vcc, 0, v3, vcc
	global_load_dword v42, v[4:5], off
	v_add_co_u32_e32 v4, vcc, 0xe000, v2
	s_nop 1
	v_addc_co_u32_e32 v5, vcc, 0, v3, vcc
	global_load_dword v43, v[4:5], off
	v_add_co_u32_e32 v4, vcc, s70, v2
	s_nop 1
	v_addc_co_u32_e32 v5, vcc, 0, v3, vcc
	global_load_dword v44, v[4:5], off
	v_add_co_u32_e32 v4, vcc, s4, v2
	s_mov_b32 s4, 0x14000
	s_nop 0
	v_addc_co_u32_e32 v5, vcc, 0, v3, vcc
	global_load_dword v45, v[4:5], off
	v_add_co_u32_e32 v4, vcc, s4, v2
	s_mov_b32 s4, 0x18000
	s_nop 0
	v_addc_co_u32_e32 v5, vcc, 0, v3, vcc
; #define LDS_WAVE_SYNC() asm volatile("s_waitcnt lgkmcnt(0)" ::: "memory")
; template <bool HASG>
; __device__ __forceinline__ void tr_item(const float* W, int K, int N, bf16* WT, int rowmode, const float* g, LAS float* scr, int item, int lane) {
;     ...
;     for (int i = 0; i < 32; ++i) v[i] = wp[(size_t)(2 * i) * N];
;     f32x4 g0 = (f32x4){1.f, 1.f, 1.f, 1.f}, g1 = g0;
;     if (HASG) { g0 = *(const f32x4*)(g + k0 + 8 * c); g1 = *(const f32x4*)(g + k0 + 8 * c + 4); }
;     asm volatile("" ::: "memory");
; #pragma unroll
;     for (int i = 0; i < 32; ++i) scr[(2 * i + (lane >> 5)) * 33 + (lane & 31)] = v[i];
;     LDS_WAVE_SYNC();
	global_load_dword v46, v[4:5], off
	v_add_co_u32_e32 v4, vcc, s71, v2
	s_nop 1
	v_addc_co_u32_e32 v5, vcc, 0, v3, vcc
	global_load_dword v47, v[4:5], off
	v_add_co_u32_e32 v4, vcc, s4, v2
	s_mov_b32 s4, 0x1a000
	s_nop 0
	v_addc_co_u32_e32 v5, vcc, 0, v3, vcc
	global_load_dword v48, v[4:5], off
	v_add_co_u32_e32 v4, vcc, s4, v2
	s_mov_b32 s4, 0x1c000
	s_nop 0
	v_addc_co_u32_e32 v5, vcc, 0, v3, vcc
	global_load_dword v49, v[4:5], off
	v_add_co_u32_e32 v4, vcc, s4, v2
	s_mov_b32 s4, 0x1e000
	s_nop 0
	v_addc_co_u32_e32 v5, vcc, 0, v3, vcc
	global_load_dword v50, v[4:5], off
	v_add_co_u32_e32 v4, vcc, s4, v2
	s_mov_b32 s4, 0x20000
	s_nop 0
	v_addc_co_u32_e32 v5, vcc, 0, v3, vcc
	global_load_dword v51, v[4:5], off
	v_add_co_u32_e32 v4, vcc, s4, v2
	s_mov_b32 s4, 0x22000
	s_nop 0
	v_addc_co_u32_e32 v5, vcc, 0, v3, vcc
	global_load_dword v52, v[4:5], off
	v_add_co_u32_e32 v4, vcc, s4, v2
	s_mov_b32 s4, 0x24000
	s_nop 0
	v_addc_co_u32_e32 v5, vcc, 0, v3, vcc
	global_load_dword v53, v[4:5], off
	v_add_co_u32_e32 v4, vcc, s4, v2
	s_mov_b32 s4, 0x26000
	s_nop 0
	v_addc_co_u32_e32 v5, vcc, 0, v3, vcc
	global_load_dword v54, v[4:5], off
	v_add_co_u32_e32 v4, vcc, s4, v2
	s_mov_b32 s4, 0x28000
	s_nop 0
	v_addc_co_u32_e32 v5, vcc, 0, v3, vcc
	global_load_dword v55, v[4:5], off
	v_add_co_u32_e32 v4, vcc, s4, v2
	s_mov_b32 s4, 0x2a000
	s_nop 0
	v_addc_co_u32_e32 v5, vcc, 0, v3, vcc
	global_load_dword v56, v[4:5], off
	v_add_co_u32_e32 v4, vcc, s4, v2
	s_mov_b32 s4, 0x2c000
	s_nop 0
	v_addc_co_u32_e32 v5, vcc, 0, v3, vcc
	global_load_dword v57, v[4:5], off
	v_add_co_u32_e32 v4, vcc, s4, v2
	s_mov_b32 s4, 0x2e000
	s_nop 0
	v_addc_co_u32_e32 v5, vcc, 0, v3, vcc
	global_load_dword v58, v[4:5], off
	v_add_co_u32_e32 v4, vcc, s4, v2
	s_mov_b32 s4, 0x30000
	s_nop 0
	v_addc_co_u32_e32 v5, vcc, 0, v3, vcc
	global_load_dword v59, v[4:5], off
	v_add_co_u32_e32 v4, vcc, s4, v2
	s_mov_b32 s4, 0x32000
	s_nop 0
	v_addc_co_u32_e32 v5, vcc, 0, v3, vcc
	global_load_dword v60, v[4:5], off
	v_add_co_u32_e32 v4, vcc, s4, v2
	s_mov_b32 s4, 0x34000
	s_nop 0
	v_addc_co_u32_e32 v5, vcc, 0, v3, vcc
	global_load_dword v61, v[4:5], off
	v_add_co_u32_e32 v4, vcc, s4, v2
	s_mov_b32 s4, 0x36000
	s_nop 0
	v_addc_co_u32_e32 v5, vcc, 0, v3, vcc
	global_load_dword v62, v[4:5], off
	v_add_co_u32_e32 v4, vcc, s4, v2
	s_mov_b32 s4, 0x38000
	s_nop 0
	v_addc_co_u32_e32 v5, vcc, 0, v3, vcc
	global_load_dword v63, v[4:5], off
	v_add_co_u32_e32 v4, vcc, s4, v2
	s_mov_b32 s4, 0x3a000
	s_nop 0
	v_addc_co_u32_e32 v5, vcc, 0, v3, vcc
	global_load_dword v64, v[4:5], off
	v_add_co_u32_e32 v4, vcc, s4, v2
	s_mov_b32 s4, 0x3c000
	s_nop 0
	v_addc_co_u32_e32 v5, vcc, 0, v3, vcc
	global_load_dword v65, v[4:5], off
	v_add_co_u32_e32 v4, vcc, s4, v2
	s_mov_b32 s4, 0x3e000
	s_nop 0
	v_addc_co_u32_e32 v5, vcc, 0, v3, vcc
	v_add_co_u32_e32 v2, vcc, s4, v2
	global_load_dword v4, v[4:5], off
	s_nop 0
	v_addc_co_u32_e32 v3, vcc, 0, v3, vcc
	global_load_dword v2, v[2:3], off
	s_waitcnt vmcnt(30)
	ds_write2_b32 v34, v0, v29 offset1:66
	s_waitcnt vmcnt(28)
	ds_write2_b32 v34, v30, v31 offset0:132 offset1:198
	v_add_u32_e32 v0, 0x400, v34
	s_waitcnt vmcnt(26)
	ds_write2_b32 v0, v40, v41 offset0:8 offset1:74
	s_waitcnt vmcnt(24)
	ds_write2_b32 v0, v42, v43 offset0:140 offset1:206
	v_add_u32_e32 v0, 0x800, v34
	s_waitcnt vmcnt(22)
	ds_write2_b32 v0, v44, v45 offset0:16 offset1:82
	s_waitcnt vmcnt(20)
	ds_write2_b32 v0, v46, v47 offset0:148 offset1:214
	v_add_u32_e32 v0, 0xc00, v34
	s_waitcnt vmcnt(18)
	ds_write2_b32 v0, v48, v49 offset0:24 offset1:90
	s_waitcnt vmcnt(16)
	ds_write2_b32 v0, v50, v51 offset0:156 offset1:222
	v_add_u32_e32 v0, 0x1000, v34
	s_waitcnt vmcnt(14)
	ds_write2_b32 v0, v52, v53 offset0:32 offset1:98
	s_waitcnt vmcnt(12)
	ds_write2_b32 v0, v54, v55 offset0:164 offset1:230
	v_add_u32_e32 v0, 0x1400, v34
	s_waitcnt vmcnt(10)
	ds_write2_b32 v0, v56, v57 offset0:40 offset1:106
	s_waitcnt vmcnt(8)
	ds_write2_b32 v0, v58, v59 offset0:172 offset1:238
	v_add_u32_e32 v0, 0x1800, v34
	s_waitcnt vmcnt(6)
	ds_write2_b32 v0, v60, v61 offset0:48 offset1:114
	s_waitcnt vmcnt(4)
	ds_write2_b32 v0, v62, v63 offset0:180 offset1:246
	v_add_u32_e32 v0, 0x1c00, v34
	s_waitcnt vmcnt(2)
	ds_write2_b32 v0, v64, v65 offset0:56 offset1:122
	s_waitcnt vmcnt(0)
	ds_write2_b32 v0, v4, v2 offset0:188 offset1:254
	s_waitcnt lgkmcnt(0)
; #define LAS __attribute__((address_space(3)))
; __device__ __forceinline__ unsigned pk2(float lo, float hi) { return f2bf(lo) | (f2bf(hi) << 16); }
; #define LDS_WAVE_SYNC() asm volatile("s_waitcnt lgkmcnt(0)" ::: "memory")
; template <bool HASG>
; __device__ __forceinline__ void tr_item(const float* W, int K, int N, bf16* WT, int rowmode, const float* g, LAS float* scr, int item, int lane) {
;     ...
;     LDS_WAVE_SYNC();
;     const int drow0 = rowmode == 0 ? n0 : ((n0 >> 7) * 256 + (n0 & 127) + (rowmode == 2 ? 128 : 0));
; #pragma unroll
;     for (int j = 0; j < 4; ++j) { const int n = (lane >> 3) + 8 * j; const LAS float* s = scr + (8 * c) * 33 + n;
;         u32x4 o; o.x = pk2(s[0 * 33] * g0.x, s[1 * 33] * g0.y); o.y = pk2(s[2 * 33] * g0.z, s[3 * 33] * g0.w);
;         o.z = pk2(s[4 * 33] * g1.x, s[5 * 33] * g1.y); o.w = pk2(s[6 * 33] * g1.z, s[7 * 33] * g1.w);
;         *(u32x4*)(WT + (size_t)(drow0 + n) * K + k0 + 8 * c) = o; }
;     LDS_WAVE_SYNC();
	ds_read2_b32 v[4:5], v36 offset0:33 offset1:41
	ds_read2_b32 v[30:31], v36 offset1:8
	ds_read2_b32 v[44:45], v36 offset0:66 offset1:74
	ds_read2_b32 v[46:47], v36 offset0:99 offset1:107
	ds_read2_b32 v[48:49], v36 offset0:132 offset1:140
	ds_read2_b32 v[50:51], v36 offset0:165 offset1:173
	ds_read2_b32 v[52:53], v36 offset0:198 offset1:206
	ds_read2_b32 v[54:55], v36 offset0:231 offset1:239
	s_waitcnt lgkmcnt(7)
	v_bfe_u32 v29, v4, 16, 1
	s_waitcnt lgkmcnt(6)
	v_bfe_u32 v0, v30, 16, 1
	v_add3_u32 v0, v30, v0, s91
	v_lshrrev_b32_e32 v0, 16, v0
	v_add3_u32 v4, v4, v29, s91
	v_and_or_b32 v40, v4, s35, v0
	s_waitcnt lgkmcnt(5)
	v_bfe_u32 v0, v44, 16, 1
	v_add3_u32 v0, v44, v0, s91
	s_waitcnt lgkmcnt(4)
	v_bfe_u32 v4, v46, 16, 1
	v_lshrrev_b32_e32 v0, 16, v0
	v_add3_u32 v4, v46, v4, s91
	v_and_or_b32 v41, v4, s35, v0
	s_waitcnt lgkmcnt(3)
	v_bfe_u32 v0, v48, 16, 1
	v_add3_u32 v0, v48, v0, s91
	s_waitcnt lgkmcnt(2)
	v_bfe_u32 v4, v50, 16, 1
	v_lshrrev_b32_e32 v0, 16, v0
	v_add3_u32 v4, v50, v4, s91
	v_and_or_b32 v42, v4, s35, v0
	s_waitcnt lgkmcnt(1)
	v_bfe_u32 v0, v52, 16, 1
	v_add3_u32 v0, v52, v0, s91
	s_waitcnt lgkmcnt(0)
	v_bfe_u32 v4, v54, 16, 1
	v_lshrrev_b32_e32 v0, 16, v0
	v_add3_u32 v4, v54, v4, s91
	v_and_or_b32 v43, v4, s35, v0
	v_or_b32_e32 v0, s28, v35
	v_mul_u32_u24_e32 v0, 0xb00, v0
	v_lshl_add_u64 v[2:3], v[12:13], 0, s[88:89]
	v_lshlrev_b32_e32 v0, 1, v0
	v_lshl_add_u64 v[56:57], v[2:3], 0, v[0:1]
	v_bfe_u32 v0, v31, 16, 1
	v_add3_u32 v0, v31, v0, s91
	v_bfe_u32 v4, v5, 16, 1
	v_lshrrev_b32_e32 v0, 16, v0
	v_add3_u32 v4, v5, v4, s91
	global_store_dwordx4 v[56:57], v[40:43], off sc1
	s_nop 1
	v_and_or_b32 v40, v4, s35, v0
	v_bfe_u32 v0, v45, 16, 1
	v_add3_u32 v0, v45, v0, s91
	v_bfe_u32 v4, v47, 16, 1
	v_lshrrev_b32_e32 v0, 16, v0
	v_add3_u32 v4, v47, v4, s91
	v_and_or_b32 v41, v4, s35, v0
	v_bfe_u32 v0, v49, 16, 1
	v_add3_u32 v0, v49, v0, s91
	v_bfe_u32 v4, v51, 16, 1
	v_lshrrev_b32_e32 v0, 16, v0
	v_add3_u32 v4, v51, v4, s91
	v_and_or_b32 v42, v4, s35, v0
	v_bfe_u32 v0, v53, 16, 1
	v_add3_u32 v0, v53, v0, s91
	v_bfe_u32 v4, v55, 16, 1
	v_lshrrev_b32_e32 v0, 16, v0
	v_add3_u32 v4, v55, v4, s91
	v_and_or_b32 v43, v4, s35, v0
	v_or_b32_e32 v0, s28, v37
	v_mul_u32_u24_e32 v0, 0xb00, v0
	v_lshlrev_b32_e32 v0, 1, v0
	v_lshl_add_u64 v[4:5], v[2:3], 0, v[0:1]
	global_store_dwordx4 v[4:5], v[40:43], off sc1
	ds_read2_b32 v[4:5], v36 offset0:16 offset1:24
	ds_read2_b32 v[30:31], v36 offset0:49 offset1:57
	ds_read2_b32 v[44:45], v36 offset0:82 offset1:90
	ds_read2_b32 v[46:47], v36 offset0:115 offset1:123
	ds_read2_b32 v[48:49], v36 offset0:148 offset1:156
	ds_read2_b32 v[50:51], v36 offset0:181 offset1:189
	ds_read2_b32 v[52:53], v36 offset0:214 offset1:222
	ds_read2_b32 v[54:55], v36 offset0:247 offset1:255
	s_waitcnt lgkmcnt(7)
	v_bfe_u32 v0, v4, 16, 1
	v_add3_u32 v0, v4, v0, s91
	s_waitcnt lgkmcnt(6)
	v_bfe_u32 v4, v30, 16, 1
	v_lshrrev_b32_e32 v0, 16, v0
	v_add3_u32 v4, v30, v4, s91
	v_and_or_b32 v40, v4, s35, v0
	s_waitcnt lgkmcnt(5)
	v_bfe_u32 v0, v44, 16, 1
	v_add3_u32 v0, v44, v0, s91
	s_waitcnt lgkmcnt(4)
	v_bfe_u32 v4, v46, 16, 1
	v_lshrrev_b32_e32 v0, 16, v0
	v_add3_u32 v4, v46, v4, s91
	v_and_or_b32 v41, v4, s35, v0
	s_waitcnt lgkmcnt(3)
	v_bfe_u32 v0, v48, 16, 1
	v_add3_u32 v0, v48, v0, s91
	s_waitcnt lgkmcnt(2)
	v_bfe_u32 v4, v50, 16, 1
	v_lshrrev_b32_e32 v0, 16, v0
	v_add3_u32 v4, v50, v4, s91
	v_and_or_b32 v42, v4, s35, v0
	s_waitcnt lgkmcnt(1)
	v_bfe_u32 v0, v52, 16, 1
	v_add3_u32 v0, v52, v0, s91
	s_waitcnt lgkmcnt(0)
	v_bfe_u32 v4, v54, 16, 1
	v_lshrrev_b32_e32 v0, 16, v0
	v_add3_u32 v4, v54, v4, s91
	v_and_or_b32 v43, v4, s35, v0
	v_or_b32_e32 v0, s28, v38
	v_mul_u32_u24_e32 v0, 0xb00, v0
	v_lshlrev_b32_e32 v0, 1, v0
	v_lshl_add_u64 v[56:57], v[2:3], 0, v[0:1]
	v_bfe_u32 v0, v5, 16, 1
	v_add3_u32 v0, v5, v0, s91
	v_bfe_u32 v4, v31, 16, 1
	v_lshrrev_b32_e32 v0, 16, v0
	v_add3_u32 v4, v31, v4, s91
	global_store_dwordx4 v[56:57], v[40:43], off sc1
	s_nop 1
	v_and_or_b32 v40, v4, s35, v0
	v_bfe_u32 v0, v45, 16, 1
	v_add3_u32 v0, v45, v0, s91
	v_bfe_u32 v4, v47, 16, 1
	v_lshrrev_b32_e32 v0, 16, v0
	v_add3_u32 v4, v47, v4, s91
	v_and_or_b32 v41, v4, s35, v0
	v_bfe_u32 v0, v49, 16, 1
	v_add3_u32 v0, v49, v0, s91
	v_bfe_u32 v4, v51, 16, 1
	v_lshrrev_b32_e32 v0, 16, v0
	v_add3_u32 v4, v51, v4, s91
	v_and_or_b32 v42, v4, s35, v0
	v_bfe_u32 v0, v53, 16, 1
	v_add3_u32 v0, v53, v0, s91
	v_bfe_u32 v4, v55, 16, 1
	v_lshrrev_b32_e32 v0, 16, v0
	v_add3_u32 v4, v55, v4, s91
	v_and_or_b32 v43, v4, s35, v0
	v_or_b32_e32 v0, s28, v39
	v_mul_u32_u24_e32 v0, 0xb00, v0
	v_lshlrev_b32_e32 v0, 1, v0
	v_lshl_add_u64 v[2:3], v[2:3], 0, v[0:1]
	global_store_dwordx4 v[2:3], v[40:43], off sc1
	s_waitcnt lgkmcnt(0)

; template <bool HASG>
; __device__ __forceinline__ void tr_item(const float* W, int K, int N, bf16* WT, int rowmode, const float* g, LAS float* scr, int item, int lane) {
;     const int nblk = N / 32, kb = item / nblk, nb = item % nblk, k0 = 64 * kb, n0 = 32 * nb;
;     const float* wp = W + (size_t)(k0 + (lane >> 5)) * N + n0 + (lane & 31);
;     const int c = lane & 7;
;     float v[32];
; #pragma unroll
;     for (int i = 0; i < 32; ++i) v[i] = wp[(size_t)(2 * i) * N];
;     f32x4 g0 = (f32x4){1.f, 1.f, 1.f, 1.f}, g1 = g0;
;     if (HASG) { g0 = *(const f32x4*)(g + k0 + 8 * c); g1 = *(const f32x4*)(g + k0 + 8 * c + 4); }
; __device__ __forceinline__ void convert_items(const Args& a, LAS unsigned char* lds, int l, int it_lo, int it_hi, int gw, int NGW, int wave, int lane) {
;     ...
;         if (r < I_G) { tr_item<true>(a.in[21] + o_gu, D, FF, wl + W_GU2, 2, a.in[19] + l * D, scr, r, lane); continue; } r -= I_G;
.LBB0_489:
	s_andn2_b64 vcc, exec, s[28:29]
	s_cbranch_vccnz .LBB0_491
	s_add_i32 s28, s67, 0xe480
	s_and_b32 s29, s28, 0xffff
	s_mul_i32 s29, s29, 0xba2f
	s_lshr_b32 s47, s29, 16
	s_lshr_b32 s29, s29, 22
	s_mulk_i32 s29, 0x58
	s_sub_i32 s28, s28, s29
	s_and_b32 s29, s47, 0xffc0
	v_or_b32_e32 v0, s29, v33
	v_mul_u32_u24_e32 v0, 0xb00, v0
	v_readlane_b32 s4, v255, 15
	s_and_b32 s60, s28, 0xffff
	v_lshlrev_b32_e32 v0, 2, v0
	v_readlane_b32 s5, v255, 16
	s_lshl_b32 s88, s60, 7
	s_lshl_b32 s47, s28, 5
	v_lshl_add_u64 v[2:3], s[4:5], 0, v[0:1]
	v_lshl_add_u64 v[2:3], v[2:3], 0, s[88:89]
	v_lshlrev_b32_e32 v0, 2, v6
	v_lshl_add_u64 v[2:3], v[2:3], 0, v[0:1]
	s_movk_i32 s4, 0x5000
	v_add_co_u32_e32 v4, vcc, s4, v2
	s_mov_b32 s4, 0x1b000
	s_nop 0
	v_addc_co_u32_e32 v5, vcc, 0, v3, vcc
	v_add_co_u32_e32 v30, vcc, s90, v2
	s_lshl_b32 s88, s29, 2
	s_nop 0
	v_addc_co_u32_e32 v31, vcc, 0, v3, vcc
	v_add_co_u32_e32 v40, vcc, s70, v2
	s_lshl_b32 s28, s28, 6
	s_nop 0
	v_addc_co_u32_e32 v41, vcc, 0, v3, vcc
	v_add_co_u32_e32 v42, vcc, s71, v2
	s_and_b32 s28, s28, 0x1f00
	s_nop 0
	v_addc_co_u32_e32 v43, vcc, 0, v3, vcc
	v_add_co_u32_e32 v44, vcc, s4, v2
	s_mov_b32 s4, 0x21000
	s_nop 0
	v_addc_co_u32_e32 v45, vcc, 0, v3, vcc
	v_add_co_u32_e32 v46, vcc, s4, v2
	s_mov_b32 s4, 0x26000
	s_nop 0
	v_addc_co_u32_e32 v47, vcc, 0, v3, vcc
	v_add_co_u32_e32 v48, vcc, s4, v2
	s_mov_b32 s4, 0x2c000
	s_nop 0
	v_addc_co_u32_e32 v49, vcc, 0, v3, vcc
	global_load_dword v0, v[2:3], off
	global_load_dword v29, v[4:5], off offset:2048
	global_load_dword v52, v[30:31], off
	global_load_dword v53, v[40:41], off offset:2048
	global_load_dword v54, v[42:43], off
	global_load_dword v55, v[44:45], off offset:2048
	global_load_dword v56, v[46:47], off
	global_load_dword v57, v[48:49], off offset:2048
	v_add_co_u32_e32 v4, vcc, s4, v2
	s_mov_b32 s4, 0x31000
	s_nop 0
	v_addc_co_u32_e32 v5, vcc, 0, v3, vcc
	v_add_co_u32_e32 v30, vcc, s4, v2
	s_mov_b32 s4, 0x37000
	s_nop 0
	v_addc_co_u32_e32 v31, vcc, 0, v3, vcc
	v_add_co_u32_e32 v40, vcc, s4, v2
	s_mov_b32 s4, 0x3c000
	s_nop 0
	v_addc_co_u32_e32 v41, vcc, 0, v3, vcc
	v_add_co_u32_e32 v42, vcc, s4, v2
	s_mov_b32 s4, 0x42000
	s_nop 0
	v_addc_co_u32_e32 v43, vcc, 0, v3, vcc
	v_add_co_u32_e32 v44, vcc, s4, v2
	s_mov_b32 s4, 0x47000
	s_nop 0
	v_addc_co_u32_e32 v45, vcc, 0, v3, vcc
	v_add_co_u32_e32 v46, vcc, s4, v2
	s_mov_b32 s4, 0x4d000
	s_nop 0
	v_addc_co_u32_e32 v47, vcc, 0, v3, vcc
	v_add_co_u32_e32 v48, vcc, s4, v2
	s_mov_b32 s4, 0x52000
	s_nop 0
	v_addc_co_u32_e32 v49, vcc, 0, v3, vcc
	v_add_co_u32_e32 v50, vcc, s4, v2
	s_mov_b32 s4, 0x58000
	s_nop 0
	v_addc_co_u32_e32 v51, vcc, 0, v3, vcc
	global_load_dword v58, v[4:5], off
	global_load_dword v59, v[30:31], off offset:2048
	global_load_dword v60, v[40:41], off
	global_load_dword v61, v[42:43], off offset:2048
	global_load_dword v62, v[44:45], off
	global_load_dword v63, v[46:47], off offset:2048
	global_load_dword v64, v[48:49], off
	global_load_dword v65, v[50:51], off offset:2048
	v_add_co_u32_e32 v4, vcc, s4, v2
	s_mov_b32 s4, 0x5d000
	s_nop 0
	v_addc_co_u32_e32 v5, vcc, 0, v3, vcc
	v_add_co_u32_e32 v30, vcc, s4, v2
	s_mov_b32 s4, 0x63000
	s_nop 0
	v_addc_co_u32_e32 v31, vcc, 0, v3, vcc
	v_add_co_u32_e32 v40, vcc, s4, v2
	s_mov_b32 s4, 0x68000
	s_nop 0
	v_addc_co_u32_e32 v41, vcc, 0, v3, vcc
	v_add_co_u32_e32 v42, vcc, s4, v2
	s_mov_b32 s4, 0x6e000
	s_nop 0
	v_addc_co_u32_e32 v43, vcc, 0, v3, vcc
	v_add_co_u32_e32 v44, vcc, s4, v2
	s_mov_b32 s4, 0x73000
	s_nop 0
	v_addc_co_u32_e32 v45, vcc, 0, v3, vcc
	v_add_co_u32_e32 v46, vcc, s4, v2
	s_mov_b32 s4, 0x79000
	s_nop 0
	v_addc_co_u32_e32 v47, vcc, 0, v3, vcc
	v_add_co_u32_e32 v48, vcc, s4, v2
	s_mov_b32 s4, 0x7e000
	s_nop 0
	v_addc_co_u32_e32 v49, vcc, 0, v3, vcc
	v_add_co_u32_e32 v50, vcc, s4, v2
	s_mov_b32 s4, 0x84000
	s_nop 0
	v_addc_co_u32_e32 v51, vcc, 0, v3, vcc
	global_load_dword v66, v[4:5], off
	global_load_dword v67, v[30:31], off offset:2048
	global_load_dword v68, v[40:41], off
	global_load_dword v69, v[42:43], off offset:2048
	global_load_dword v70, v[44:45], off
	global_load_dword v71, v[46:47], off offset:2048
	global_load_dword v72, v[48:49], off
	s_nop 0
	global_load_dword v50, v[50:51], off offset:2048
	v_add_co_u32_e32 v4, vcc, s4, v2
	s_mov_b32 s4, 0x89000
	s_nop 0
	v_addc_co_u32_e32 v5, vcc, 0, v3, vcc
	v_add_co_u32_e32 v30, vcc, s4, v2
	s_mov_b32 s4, 0x8f000
	s_nop 0
	v_addc_co_u32_e32 v31, vcc, 0, v3, vcc
	v_add_co_u32_e32 v40, vcc, s4, v2
	s_mov_b32 s4, 0x94000
	s_nop 0
	v_addc_co_u32_e32 v41, vcc, 0, v3, vcc
	v_add_co_u32_e32 v42, vcc, s4, v2
	s_mov_b32 s4, 0x9a000
	s_nop 0
	v_addc_co_u32_e32 v43, vcc, 0, v3, vcc
	v_add_co_u32_e32 v44, vcc, s4, v2
	s_mov_b32 s4, 0x9f000
	s_nop 0
	v_addc_co_u32_e32 v45, vcc, 0, v3, vcc
	v_add_co_u32_e32 v46, vcc, s4, v2
	s_mov_b32 s4, 0xa5000
	s_nop 0
	v_addc_co_u32_e32 v47, vcc, 0, v3, vcc
	v_add_co_u32_e32 v48, vcc, s4, v2
	s_mov_b32 s4, 0xaa000
	s_nop 0
	v_addc_co_u32_e32 v49, vcc, 0, v3, vcc
	v_add_co_u32_e32 v2, vcc, s4, v2
	s_and_b32 s47, s47, 0x60
	s_nop 0
	v_addc_co_u32_e32 v3, vcc, 0, v3, vcc
	global_load_dword v51, v[4:5], off
	s_nop 0
	global_load_dword v30, v[30:31], off offset:2048
	s_nop 0
	global_load_dword v31, v[40:41], off
	global_load_dword v73, v[42:43], off offset:2048
	s_nop 0
	global_load_dword v44, v[44:45], off
	s_nop 0
	global_load_dword v45, v[46:47], off offset:2048
	s_nop 0
	global_load_dword v46, v[48:49], off
	global_load_dword v47, v[2:3], off offset:2048
	v_lshl_add_u64 v[2:3], v[22:23], 0, s[88:89]
	global_load_dwordx4 v[40:43], v[2:3], off
	s_nop 0
	global_load_dwordx4 v[2:5], v[2:3], off offset:16
	s_waitcnt vmcnt(32)
; #define LAS __attribute__((address_space(3)))
; __device__ __forceinline__ unsigned pk2(float lo, float hi) { return f2bf(lo) | (f2bf(hi) << 16); }
; #define LDS_WAVE_SYNC() asm volatile("s_waitcnt lgkmcnt(0)" ::: "memory")
; template <bool HASG>
; __device__ __forceinline__ void tr_item(const float* W, int K, int N, bf16* WT, int rowmode, const float* g, LAS float* scr, int item, int lane) {
;     ...
;     for (int i = 0; i < 32; ++i) scr[(2 * i + (lane >> 5)) * 33 + (lane & 31)] = v[i];
;     LDS_WAVE_SYNC();
;     const int drow0 = rowmode == 0 ? n0 : ((n0 >> 7) * 256 + (n0 & 127) + (rowmode == 2 ? 128 : 0));
; #pragma unroll
;     for (int j = 0; j < 4; ++j) { const int n = (lane >> 3) + 8 * j; const LAS float* s = scr + (8 * c) * 33 + n;
;         u32x4 o; o.x = pk2(s[0 * 33] * g0.x, s[1 * 33] * g0.y); o.y = pk2(s[2 * 33] * g0.z, s[3 * 33] * g0.w);
;         o.z = pk2(s[4 * 33] * g1.x, s[5 * 33] * g1.y); o.w = pk2(s[6 * 33] * g1.z, s[7 * 33] * g1.w);
;         *(u32x4*)(WT + (size_t)(drow0 + n) * K + k0 + 8 * c) = o; }
	ds_write2_b32 v34, v0, v29 offset1:66
	s_waitcnt vmcnt(30)
	ds_write2_b32 v34, v52, v53 offset0:132 offset1:198
	v_add_u32_e32 v0, 0x400, v34
	s_waitcnt vmcnt(28)
	ds_write2_b32 v0, v54, v55 offset0:8 offset1:74
	s_waitcnt vmcnt(26)
	ds_write2_b32 v0, v56, v57 offset0:140 offset1:206
	v_add_u32_e32 v0, 0x800, v34
	s_waitcnt vmcnt(24)
	ds_write2_b32 v0, v58, v59 offset0:16 offset1:82
	s_waitcnt vmcnt(22)
	ds_write2_b32 v0, v60, v61 offset0:148 offset1:214
	v_add_u32_e32 v0, 0xc00, v34
	s_waitcnt vmcnt(20)
	ds_write2_b32 v0, v62, v63 offset0:24 offset1:90
	s_waitcnt vmcnt(18)
	ds_write2_b32 v0, v64, v65 offset0:156 offset1:222
	v_add_u32_e32 v0, 0x1000, v34
	s_waitcnt vmcnt(16)
	ds_write2_b32 v0, v66, v67 offset0:32 offset1:98
	s_waitcnt vmcnt(14)
	ds_write2_b32 v0, v68, v69 offset0:164 offset1:230
	v_add_u32_e32 v0, 0x1400, v34
	s_waitcnt vmcnt(12)
	ds_write2_b32 v0, v70, v71 offset0:40 offset1:106
	s_waitcnt vmcnt(10)
	ds_write2_b32 v0, v72, v50 offset0:172 offset1:238
	v_add_u32_e32 v0, 0x1800, v34
	s_waitcnt vmcnt(8)
	ds_write2_b32 v0, v51, v30 offset0:48 offset1:114
	s_waitcnt vmcnt(6)
	ds_write2_b32 v0, v31, v73 offset0:180 offset1:246
	v_add_u32_e32 v0, 0x1c00, v34
	s_waitcnt vmcnt(4)
	ds_write2_b32 v0, v44, v45 offset0:56 offset1:122
	s_waitcnt vmcnt(2)
	ds_write2_b32 v0, v46, v47 offset0:188 offset1:254
	s_waitcnt lgkmcnt(0)
	ds_read2_b32 v[48:49], v36 offset0:33 offset1:41
	ds_read2_b32 v[50:51], v36 offset1:8
	ds_read2_b32 v[52:53], v36 offset0:66 offset1:74
	ds_read2_b32 v[54:55], v36 offset0:99 offset1:107
	ds_read2_b32 v[58:59], v36 offset0:132 offset1:140
	ds_read2_b32 v[60:61], v36 offset0:165 offset1:173
	ds_read2_b32 v[62:63], v36 offset0:198 offset1:206
	ds_read2_b32 v[64:65], v36 offset0:231 offset1:239
	s_waitcnt vmcnt(1)
	v_mov_b32_e32 v56, v40
	v_mov_b32_e32 v57, v42
	v_mov_b32_e32 v42, v41
	s_waitcnt lgkmcnt(7)
	v_mov_b32_e32 v40, v48
	s_waitcnt lgkmcnt(4)
	v_mov_b32_e32 v41, v54
	v_pk_mul_f32 v[40:41], v[42:43], v[40:41]
	s_waitcnt vmcnt(0)
	v_mov_b32_e32 v66, v2
	v_mov_b32_e32 v67, v4
	s_waitcnt lgkmcnt(3)
	v_mov_b32_e32 v46, v58
	s_waitcnt lgkmcnt(1)
	v_mov_b32_e32 v47, v62
	v_mov_b32_e32 v4, v3
	v_mov_b32_e32 v2, v60
	s_waitcnt lgkmcnt(0)
	v_mov_b32_e32 v3, v64
	v_mov_b32_e32 v44, v50
	v_mov_b32_e32 v45, v52
	v_pk_mul_f32 v[46:47], v[66:67], v[46:47]
	v_pk_mul_f32 v[2:3], v[4:5], v[2:3]
	v_bfe_u32 v50, v40, 16, 1
	v_pk_mul_f32 v[44:45], v[56:57], v[44:45]
	v_bfe_u32 v29, v2, 16, 1
	v_add3_u32 v40, v40, v50, s91
	v_bfe_u32 v50, v47, 16, 1
	s_or_b32 s28, s47, s28
	v_bfe_u32 v0, v3, 16, 1
	v_bfe_u32 v48, v41, 16, 1
	v_add3_u32 v2, v2, v29, s91
	v_bfe_u32 v29, v45, 16, 1
	v_add3_u32 v47, v47, v50, s91
	s_bitset1_b32 s28, 7
	v_add3_u32 v41, v41, v48, s91
	v_add3_u32 v0, v3, v0, s91
	v_bfe_u32 v3, v44, 16, 1
	v_bfe_u32 v48, v46, 16, 1
	v_add3_u32 v29, v45, v29, s91
	v_lshrrev_b32_e32 v45, 16, v47
	s_lshl_b32 s88, s29, 1
	v_add3_u32 v46, v46, v48, s91
	v_add3_u32 v3, v44, v3, s91
	v_and_or_b32 v47, v0, s35, v45
	v_or_b32_e32 v0, s28, v35
	v_lshl_add_u64 v[30:31], v[14:15], 0, s[88:89]
	v_lshrrev_b32_e32 v3, 16, v3
	v_lshrrev_b32_e32 v29, 16, v29
	v_lshrrev_b32_e32 v44, 16, v46
	v_lshlrev_b32_e32 v0, 11, v0
	v_mov_b32_e32 v54, v49
	v_and_or_b32 v46, v2, s35, v44
	v_and_or_b32 v45, v41, s35, v29
	v_and_or_b32 v44, v40, s35, v3
	v_lshl_add_u64 v[2:3], v[30:31], 0, v[0:1]
	v_pk_mul_f32 v[40:41], v[42:43], v[54:55]
	v_mov_b32_e32 v62, v59
	global_store_dwordx4 v[2:3], v[44:47], off sc1
	v_mov_b32_e32 v64, v61
	v_bfe_u32 v49, v40, 16, 1
	v_pk_mul_f32 v[44:45], v[66:67], v[62:63]
	v_mov_b32_e32 v52, v51
	v_pk_mul_f32 v[46:47], v[4:5], v[64:65]
	v_add3_u32 v40, v40, v49, s91
	v_bfe_u32 v49, v45, 16, 1
	v_pk_mul_f32 v[2:3], v[56:57], v[52:53]
	v_bfe_u32 v0, v47, 16, 1
	v_bfe_u32 v29, v46, 16, 1
	v_bfe_u32 v48, v41, 16, 1
	v_add3_u32 v45, v45, v49, s91
	v_add3_u32 v41, v41, v48, s91
	v_add3_u32 v29, v46, v29, s91
	v_add3_u32 v0, v47, v0, s91
	v_bfe_u32 v46, v2, 16, 1
	v_bfe_u32 v47, v3, 16, 1
	v_bfe_u32 v48, v44, 16, 1
	v_lshrrev_b32_e32 v45, 16, v45
	v_add3_u32 v44, v44, v48, s91
	v_add3_u32 v3, v3, v47, s91
	v_add3_u32 v2, v2, v46, s91
	v_and_or_b32 v47, v0, s35, v45
	v_or_b32_e32 v0, s28, v37
	v_lshrrev_b32_e32 v2, 16, v2
	v_lshrrev_b32_e32 v3, 16, v3
	v_lshrrev_b32_e32 v44, 16, v44
	v_lshlrev_b32_e32 v0, 11, v0
	v_and_or_b32 v46, v29, s35, v44
	v_and_or_b32 v45, v41, s35, v3
	v_and_or_b32 v44, v40, s35, v2
	v_lshl_add_u64 v[2:3], v[30:31], 0, v[0:1]
	ds_read2_b32 v[40:41], v36 offset0:16 offset1:24
	ds_read2_b32 v[48:49], v36 offset0:82 offset1:90
	global_store_dwordx4 v[2:3], v[44:47], off sc1
	ds_read2_b32 v[2:3], v36 offset0:49 offset1:57
	ds_read2_b32 v[50:51], v36 offset0:115 offset1:123
	ds_read2_b32 v[52:53], v36 offset0:148 offset1:156
	ds_read2_b32 v[54:55], v36 offset0:214 offset1:222
	ds_read2_b32 v[58:59], v36 offset0:181 offset1:189
	ds_read2_b32 v[60:61], v36 offset0:247 offset1:255
	s_waitcnt lgkmcnt(7)
; #define LAS __attribute__((address_space(3)))
; __device__ __forceinline__ unsigned pk2(float lo, float hi) { return f2bf(lo) | (f2bf(hi) << 16); }
; #define LDS_WAVE_SYNC() asm volatile("s_waitcnt lgkmcnt(0)" ::: "memory")
; template <bool HASG>
; __device__ __forceinline__ void tr_item(const float* W, int K, int N, bf16* WT, int rowmode, const float* g, LAS float* scr, int item, int lane) {
;     ...
;     for (int j = 0; j < 4; ++j) { const int n = (lane >> 3) + 8 * j; const LAS float* s = scr + (8 * c) * 33 + n;
;         u32x4 o; o.x = pk2(s[0 * 33] * g0.x, s[1 * 33] * g0.y); o.y = pk2(s[2 * 33] * g0.z, s[3 * 33] * g0.w);
;         o.z = pk2(s[4 * 33] * g1.x, s[5 * 33] * g1.y); o.w = pk2(s[6 * 33] * g1.z, s[7 * 33] * g1.w);
;         *(u32x4*)(WT + (size_t)(drow0 + n) * K + k0 + 8 * c) = o; }
;     LDS_WAVE_SYNC();
	v_mov_b32_e32 v44, v40
	s_waitcnt lgkmcnt(5)
	v_mov_b32_e32 v46, v2
	s_waitcnt lgkmcnt(4)
	v_mov_b32_e32 v47, v50
	s_waitcnt lgkmcnt(3)
	v_mov_b32_e32 v62, v52
	s_waitcnt lgkmcnt(2)
	v_mov_b32_e32 v63, v54
	v_mov_b32_e32 v45, v48
	v_pk_mul_f32 v[46:47], v[42:43], v[46:47]
	v_pk_mul_f32 v[62:63], v[66:67], v[62:63]
	s_waitcnt lgkmcnt(1)
	v_mov_b32_e32 v64, v58
	s_waitcnt lgkmcnt(0)
	v_mov_b32_e32 v65, v60
	v_pk_mul_f32 v[44:45], v[56:57], v[44:45]
	v_pk_mul_f32 v[64:65], v[4:5], v[64:65]
	v_bfe_u32 v29, v47, 16, 1
	v_bfe_u32 v50, v63, 16, 1
	v_bfe_u32 v0, v65, 16, 1
	v_bfe_u32 v40, v46, 16, 1
	v_add3_u32 v29, v47, v29, s91
	v_bfe_u32 v47, v45, 16, 1
	v_add3_u32 v50, v63, v50, s91
	v_add3_u32 v40, v46, v40, s91
	v_add3_u32 v0, v65, v0, s91
	v_bfe_u32 v46, v44, 16, 1
	v_bfe_u32 v48, v62, 16, 1
	v_add3_u32 v45, v45, v47, s91
	v_lshrrev_b32_e32 v47, 16, v50
	v_bfe_u32 v2, v64, 16, 1
	v_add3_u32 v48, v62, v48, s91
	v_add3_u32 v44, v44, v46, s91
	v_and_or_b32 v47, v0, s35, v47
	v_or_b32_e32 v0, s28, v38
	v_add3_u32 v2, v64, v2, s91
	v_lshrrev_b32_e32 v44, 16, v44
	v_lshrrev_b32_e32 v45, 16, v45
	v_lshrrev_b32_e32 v46, 16, v48
	v_lshlrev_b32_e32 v0, 11, v0
	v_mov_b32_e32 v50, v3
	v_mov_b32_e32 v60, v59
	v_and_or_b32 v46, v2, s35, v46
	v_and_or_b32 v45, v29, s35, v45
	v_and_or_b32 v44, v40, s35, v44
	v_lshl_add_u64 v[62:63], v[30:31], 0, v[0:1]
	v_mov_b32_e32 v48, v41
	v_pk_mul_f32 v[2:3], v[42:43], v[50:51]
	v_mov_b32_e32 v54, v53
	v_pk_mul_f32 v[4:5], v[4:5], v[60:61]
	global_store_dwordx4 v[62:63], v[44:47], off sc1
	v_pk_mul_f32 v[40:41], v[56:57], v[48:49]
	v_pk_mul_f32 v[42:43], v[66:67], v[54:55]
	v_bfe_u32 v0, v5, 16, 1
	v_bfe_u32 v45, v2, 16, 1
	v_add3_u32 v2, v2, v45, s91
	v_add3_u32 v0, v5, v0, s91
	v_bfe_u32 v5, v40, 16, 1
	v_bfe_u32 v45, v43, 16, 1
	v_bfe_u32 v29, v4, 16, 1
	v_bfe_u32 v44, v3, 16, 1
	v_add3_u32 v43, v43, v45, s91
	v_add3_u32 v5, v40, v5, s91
	v_add3_u32 v3, v3, v44, s91
	v_add3_u32 v4, v4, v29, s91
	v_bfe_u32 v29, v41, 16, 1
	v_bfe_u32 v44, v42, 16, 1
	v_lshrrev_b32_e32 v40, 16, v5
	v_lshrrev_b32_e32 v5, 16, v43
	v_add3_u32 v42, v42, v44, s91
	v_add3_u32 v29, v41, v29, s91
	v_and_or_b32 v5, v0, s35, v5
	v_or_b32_e32 v0, s28, v39
	v_lshrrev_b32_e32 v29, 16, v29
	v_lshrrev_b32_e32 v41, 16, v42
	v_lshlrev_b32_e32 v0, 11, v0
	v_and_or_b32 v4, v4, s35, v41
	v_and_or_b32 v3, v3, s35, v29
	v_and_or_b32 v2, v2, s35, v40
	v_lshl_add_u64 v[30:31], v[30:31], 0, v[0:1]
	global_store_dwordx4 v[30:31], v[2:5], off sc1
	s_waitcnt lgkmcnt(0)

; template <bool HASG>
; __device__ __forceinline__ void tr_item(const float* W, int K, int N, bf16* WT, int rowmode, const float* g, LAS float* scr, int item, int lane) {
;     const int nblk = N / 32, kb = item / nblk, nb = item % nblk, k0 = 64 * kb, n0 = 32 * nb;
;     const float* wp = W + (size_t)(k0 + (lane >> 5)) * N + n0 + (lane & 31);
;     const int c = lane & 7;
;     float v[32];
; #pragma unroll
;     for (int i = 0; i < 32; ++i) v[i] = wp[(size_t)(2 * i) * N];
;     f32x4 g0 = (f32x4){1.f, 1.f, 1.f, 1.f}, g1 = g0;
;     if (HASG) { g0 = *(const f32x4*)(g + k0 + 8 * c); g1 = *(const f32x4*)(g + k0 + 8 * c + 4); }
; __device__ __forceinline__ void convert_items(const Args& a, LAS unsigned char* lds, int l, int it_lo, int it_hi, int gw, int NGW, int wave, int lane) {
;     ...
;         if (r < I_G) { tr_item<true>(a.in[20] + o_gu, D, FF, wl + W_GU2, 1, a.in[19] + l * D, scr, r, lane); continue; } r -= I_G;
.LBB0_492:
	s_andn2_b64 vcc, exec, s[28:29]
	s_cbranch_vccnz .LBB0_494
	s_add_i32 s28, s67, 0xea00
	s_and_b32 s29, s28, 0xffff
	s_mul_i32 s29, s29, 0xba2f
	s_lshr_b32 s47, s29, 16
	s_lshr_b32 s29, s29, 22
	s_mulk_i32 s29, 0x58
	s_sub_i32 s28, s28, s29
	s_and_b32 s29, s47, 0xffc0
	v_or_b32_e32 v0, s29, v33
	v_mul_u32_u24_e32 v0, 0xb00, v0
	v_readlane_b32 s4, v255, 17
	s_and_b32 s60, s28, 0xffff
	v_lshlrev_b32_e32 v0, 2, v0
	v_readlane_b32 s5, v255, 18
	s_lshl_b32 s88, s60, 7
	s_lshl_b32 s47, s28, 5
	v_lshl_add_u64 v[2:3], s[4:5], 0, v[0:1]
	v_lshl_add_u64 v[2:3], v[2:3], 0, s[88:89]
	v_lshlrev_b32_e32 v0, 2, v6
	v_lshl_add_u64 v[2:3], v[2:3], 0, v[0:1]
	s_movk_i32 s4, 0x5000
	v_add_co_u32_e32 v4, vcc, s4, v2
	s_mov_b32 s4, 0x1b000
	s_nop 0
	v_addc_co_u32_e32 v5, vcc, 0, v3, vcc
	v_add_co_u32_e32 v30, vcc, s90, v2
	s_lshl_b32 s88, s29, 2
	s_nop 0
	v_addc_co_u32_e32 v31, vcc, 0, v3, vcc
	v_add_co_u32_e32 v40, vcc, s70, v2
	s_lshl_b32 s28, s28, 6
	s_nop 0
	v_addc_co_u32_e32 v41, vcc, 0, v3, vcc
	v_add_co_u32_e32 v42, vcc, s71, v2
	s_and_b32 s28, s28, 0x1f00
	s_nop 0
	v_addc_co_u32_e32 v43, vcc, 0, v3, vcc
	v_add_co_u32_e32 v44, vcc, s4, v2
	s_mov_b32 s4, 0x21000
	s_nop 0
	v_addc_co_u32_e32 v45, vcc, 0, v3, vcc
	v_add_co_u32_e32 v46, vcc, s4, v2
	s_mov_b32 s4, 0x26000
	s_nop 0
	v_addc_co_u32_e32 v47, vcc, 0, v3, vcc
	v_add_co_u32_e32 v48, vcc, s4, v2
	s_mov_b32 s4, 0x2c000
	s_nop 0
	v_addc_co_u32_e32 v49, vcc, 0, v3, vcc
	global_load_dword v0, v[2:3], off
	global_load_dword v29, v[4:5], off offset:2048
	global_load_dword v52, v[30:31], off
	global_load_dword v53, v[40:41], off offset:2048
	global_load_dword v54, v[42:43], off
	global_load_dword v55, v[44:45], off offset:2048
	global_load_dword v56, v[46:47], off
	global_load_dword v57, v[48:49], off offset:2048
	v_add_co_u32_e32 v4, vcc, s4, v2
	s_mov_b32 s4, 0x31000
	s_nop 0
	v_addc_co_u32_e32 v5, vcc, 0, v3, vcc
	v_add_co_u32_e32 v30, vcc, s4, v2
	s_mov_b32 s4, 0x37000
	s_nop 0
	v_addc_co_u32_e32 v31, vcc, 0, v3, vcc
	v_add_co_u32_e32 v40, vcc, s4, v2
	s_mov_b32 s4, 0x3c000
	s_nop 0
	v_addc_co_u32_e32 v41, vcc, 0, v3, vcc
	v_add_co_u32_e32 v42, vcc, s4, v2
	s_mov_b32 s4, 0x42000
	s_nop 0
	v_addc_co_u32_e32 v43, vcc, 0, v3, vcc
	v_add_co_u32_e32 v44, vcc, s4, v2
	s_mov_b32 s4, 0x47000
	s_nop 0
	v_addc_co_u32_e32 v45, vcc, 0, v3, vcc
	v_add_co_u32_e32 v46, vcc, s4, v2
	s_mov_b32 s4, 0x4d000
	s_nop 0
	v_addc_co_u32_e32 v47, vcc, 0, v3, vcc
	v_add_co_u32_e32 v48, vcc, s4, v2
	s_mov_b32 s4, 0x52000
	s_nop 0
	v_addc_co_u32_e32 v49, vcc, 0, v3, vcc
	v_add_co_u32_e32 v50, vcc, s4, v2
	s_mov_b32 s4, 0x58000
	s_nop 0
	v_addc_co_u32_e32 v51, vcc, 0, v3, vcc
	global_load_dword v58, v[4:5], off
	global_load_dword v59, v[30:31], off offset:2048
	global_load_dword v60, v[40:41], off
	global_load_dword v61, v[42:43], off offset:2048
	global_load_dword v62, v[44:45], off
	global_load_dword v63, v[46:47], off offset:2048
	global_load_dword v64, v[48:49], off
	global_load_dword v65, v[50:51], off offset:2048
	v_add_co_u32_e32 v4, vcc, s4, v2
	s_mov_b32 s4, 0x5d000
	s_nop 0
	v_addc_co_u32_e32 v5, vcc, 0, v3, vcc
	v_add_co_u32_e32 v30, vcc, s4, v2
	s_mov_b32 s4, 0x63000
	s_nop 0
	v_addc_co_u32_e32 v31, vcc, 0, v3, vcc
	v_add_co_u32_e32 v40, vcc, s4, v2
	s_mov_b32 s4, 0x68000
	s_nop 0
	v_addc_co_u32_e32 v41, vcc, 0, v3, vcc
	v_add_co_u32_e32 v42, vcc, s4, v2
	s_mov_b32 s4, 0x6e000
	s_nop 0
	v_addc_co_u32_e32 v43, vcc, 0, v3, vcc
	v_add_co_u32_e32 v44, vcc, s4, v2
	s_mov_b32 s4, 0x73000
	s_nop 0
	v_addc_co_u32_e32 v45, vcc, 0, v3, vcc
	v_add_co_u32_e32 v46, vcc, s4, v2
	s_mov_b32 s4, 0x79000
	s_nop 0
	v_addc_co_u32_e32 v47, vcc, 0, v3, vcc
	v_add_co_u32_e32 v48, vcc, s4, v2
	s_mov_b32 s4, 0x7e000
	s_nop 0
	v_addc_co_u32_e32 v49, vcc, 0, v3, vcc
	v_add_co_u32_e32 v50, vcc, s4, v2
	s_mov_b32 s4, 0x84000
	s_nop 0
	v_addc_co_u32_e32 v51, vcc, 0, v3, vcc
	global_load_dword v66, v[4:5], off
	global_load_dword v67, v[30:31], off offset:2048
	global_load_dword v68, v[40:41], off
	global_load_dword v69, v[42:43], off offset:2048
	global_load_dword v70, v[44:45], off
	global_load_dword v71, v[46:47], off offset:2048
	global_load_dword v72, v[48:49], off
	s_nop 0
	global_load_dword v50, v[50:51], off offset:2048
	v_add_co_u32_e32 v4, vcc, s4, v2
	s_mov_b32 s4, 0x89000
	s_nop 0
	v_addc_co_u32_e32 v5, vcc, 0, v3, vcc
	v_add_co_u32_e32 v30, vcc, s4, v2
	s_mov_b32 s4, 0x8f000
	s_nop 0
	v_addc_co_u32_e32 v31, vcc, 0, v3, vcc
	v_add_co_u32_e32 v40, vcc, s4, v2
	s_mov_b32 s4, 0x94000
	s_nop 0
	v_addc_co_u32_e32 v41, vcc, 0, v3, vcc
	v_add_co_u32_e32 v42, vcc, s4, v2
	s_mov_b32 s4, 0x9a000
	s_nop 0
	v_addc_co_u32_e32 v43, vcc, 0, v3, vcc
	v_add_co_u32_e32 v44, vcc, s4, v2
	s_mov_b32 s4, 0x9f000
	s_nop 0
	v_addc_co_u32_e32 v45, vcc, 0, v3, vcc
	v_add_co_u32_e32 v46, vcc, s4, v2
	s_mov_b32 s4, 0xa5000
	s_nop 0
	v_addc_co_u32_e32 v47, vcc, 0, v3, vcc
	v_add_co_u32_e32 v48, vcc, s4, v2
	s_mov_b32 s4, 0xaa000
	s_nop 0
	v_addc_co_u32_e32 v49, vcc, 0, v3, vcc
	v_add_co_u32_e32 v2, vcc, s4, v2
	s_and_b32 s47, s47, 0x60
	s_nop 0
	v_addc_co_u32_e32 v3, vcc, 0, v3, vcc
	global_load_dword v51, v[4:5], off
	s_nop 0
	global_load_dword v30, v[30:31], off offset:2048
	s_nop 0
	global_load_dword v31, v[40:41], off
	global_load_dword v73, v[42:43], off offset:2048
	s_nop 0
	global_load_dword v44, v[44:45], off
	s_nop 0
	global_load_dword v45, v[46:47], off offset:2048
	s_nop 0
	global_load_dword v46, v[48:49], off
	global_load_dword v47, v[2:3], off offset:2048
	v_lshl_add_u64 v[2:3], v[22:23], 0, s[88:89]
	global_load_dwordx4 v[40:43], v[2:3], off
	s_nop 0
	global_load_dwordx4 v[2:5], v[2:3], off offset:16
	s_waitcnt vmcnt(32)
; #define LAS __attribute__((address_space(3)))
; __device__ __forceinline__ unsigned pk2(float lo, float hi) { return f2bf(lo) | (f2bf(hi) << 16); }
; #define LDS_WAVE_SYNC() asm volatile("s_waitcnt lgkmcnt(0)" ::: "memory")
; template <bool HASG>
; __device__ __forceinline__ void tr_item(const float* W, int K, int N, bf16* WT, int rowmode, const float* g, LAS float* scr, int item, int lane) {
;     ...
;     for (int i = 0; i < 32; ++i) scr[(2 * i + (lane >> 5)) * 33 + (lane & 31)] = v[i];
;     LDS_WAVE_SYNC();
;     const int drow0 = rowmode == 0 ? n0 : ((n0 >> 7) * 256 + (n0 & 127) + (rowmode == 2 ? 128 : 0));
; #pragma unroll
;     for (int j = 0; j < 4; ++j) { const int n = (lane >> 3) + 8 * j; const LAS float* s = scr + (8 * c) * 33 + n;
;         u32x4 o; o.x = pk2(s[0 * 33] * g0.x, s[1 * 33] * g0.y); o.y = pk2(s[2 * 33] * g0.z, s[3 * 33] * g0.w);
;         o.z = pk2(s[4 * 33] * g1.x, s[5 * 33] * g1.y); o.w = pk2(s[6 * 33] * g1.z, s[7 * 33] * g1.w);
;         *(u32x4*)(WT + (size_t)(drow0 + n) * K + k0 + 8 * c) = o; }
	ds_write2_b32 v34, v0, v29 offset1:66
	s_waitcnt vmcnt(30)
	ds_write2_b32 v34, v52, v53 offset0:132 offset1:198
	v_add_u32_e32 v0, 0x400, v34
	s_waitcnt vmcnt(28)
	ds_write2_b32 v0, v54, v55 offset0:8 offset1:74
	s_waitcnt vmcnt(26)
	ds_write2_b32 v0, v56, v57 offset0:140 offset1:206
	v_add_u32_e32 v0, 0x800, v34
	s_waitcnt vmcnt(24)
	ds_write2_b32 v0, v58, v59 offset0:16 offset1:82
	s_waitcnt vmcnt(22)
	ds_write2_b32 v0, v60, v61 offset0:148 offset1:214
	v_add_u32_e32 v0, 0xc00, v34
	s_waitcnt vmcnt(20)
	ds_write2_b32 v0, v62, v63 offset0:24 offset1:90
	s_waitcnt vmcnt(18)
	ds_write2_b32 v0, v64, v65 offset0:156 offset1:222
	v_add_u32_e32 v0, 0x1000, v34
	s_waitcnt vmcnt(16)
	ds_write2_b32 v0, v66, v67 offset0:32 offset1:98
	s_waitcnt vmcnt(14)
	ds_write2_b32 v0, v68, v69 offset0:164 offset1:230
	v_add_u32_e32 v0, 0x1400, v34
	s_waitcnt vmcnt(12)
	ds_write2_b32 v0, v70, v71 offset0:40 offset1:106
	s_waitcnt vmcnt(10)
	ds_write2_b32 v0, v72, v50 offset0:172 offset1:238
	v_add_u32_e32 v0, 0x1800, v34
	s_waitcnt vmcnt(8)
	ds_write2_b32 v0, v51, v30 offset0:48 offset1:114
	s_waitcnt vmcnt(6)
	ds_write2_b32 v0, v31, v73 offset0:180 offset1:246
	v_add_u32_e32 v0, 0x1c00, v34
	s_waitcnt vmcnt(4)
	ds_write2_b32 v0, v44, v45 offset0:56 offset1:122
	s_waitcnt vmcnt(2)
	ds_write2_b32 v0, v46, v47 offset0:188 offset1:254
	s_waitcnt lgkmcnt(0)
	ds_read2_b32 v[48:49], v36 offset0:33 offset1:41
	ds_read2_b32 v[50:51], v36 offset1:8
	ds_read2_b32 v[52:53], v36 offset0:66 offset1:74
	ds_read2_b32 v[54:55], v36 offset0:99 offset1:107
	ds_read2_b32 v[58:59], v36 offset0:132 offset1:140
	ds_read2_b32 v[60:61], v36 offset0:165 offset1:173
	ds_read2_b32 v[62:63], v36 offset0:198 offset1:206
	ds_read2_b32 v[64:65], v36 offset0:231 offset1:239
	s_waitcnt vmcnt(1)
	v_mov_b32_e32 v56, v40
	v_mov_b32_e32 v57, v42
	v_mov_b32_e32 v42, v41
	s_waitcnt lgkmcnt(7)
	v_mov_b32_e32 v40, v48
	s_waitcnt lgkmcnt(4)
	v_mov_b32_e32 v41, v54
	v_pk_mul_f32 v[40:41], v[42:43], v[40:41]
	s_waitcnt vmcnt(0)
	v_mov_b32_e32 v66, v2
	v_mov_b32_e32 v67, v4
	s_waitcnt lgkmcnt(3)
	v_mov_b32_e32 v46, v58
	s_waitcnt lgkmcnt(1)
	v_mov_b32_e32 v47, v62
	v_mov_b32_e32 v4, v3
	v_mov_b32_e32 v2, v60
	s_waitcnt lgkmcnt(0)
	v_mov_b32_e32 v3, v64
	v_mov_b32_e32 v44, v50
	v_mov_b32_e32 v45, v52
	v_pk_mul_f32 v[46:47], v[66:67], v[46:47]
	v_pk_mul_f32 v[2:3], v[4:5], v[2:3]
	v_bfe_u32 v50, v40, 16, 1
	v_pk_mul_f32 v[44:45], v[56:57], v[44:45]
	v_bfe_u32 v29, v2, 16, 1
	v_add3_u32 v40, v40, v50, s91
	v_bfe_u32 v50, v47, 16, 1
	v_bfe_u32 v0, v3, 16, 1
	v_bfe_u32 v48, v41, 16, 1
	v_add3_u32 v2, v2, v29, s91
	v_bfe_u32 v29, v45, 16, 1
	v_add3_u32 v47, v47, v50, s91
	s_or_b32 s28, s47, s28
	v_add3_u32 v41, v41, v48, s91
	v_add3_u32 v0, v3, v0, s91
	v_bfe_u32 v3, v44, 16, 1
	v_bfe_u32 v48, v46, 16, 1
	v_add3_u32 v29, v45, v29, s91
	v_lshrrev_b32_e32 v45, 16, v47
	s_lshl_b32 s88, s29, 1
	v_add3_u32 v46, v46, v48, s91
	v_add3_u32 v3, v44, v3, s91
	v_and_or_b32 v47, v0, s35, v45
	v_or_b32_e32 v0, s28, v35
	v_lshl_add_u64 v[30:31], v[14:15], 0, s[88:89]
	v_lshrrev_b32_e32 v3, 16, v3
	v_lshrrev_b32_e32 v29, 16, v29
	v_lshrrev_b32_e32 v44, 16, v46
	v_lshlrev_b32_e32 v0, 11, v0
	v_mov_b32_e32 v54, v49
	v_and_or_b32 v46, v2, s35, v44
	v_and_or_b32 v45, v41, s35, v29
	v_and_or_b32 v44, v40, s35, v3
	v_lshl_add_u64 v[2:3], v[30:31], 0, v[0:1]
	v_pk_mul_f32 v[40:41], v[42:43], v[54:55]
	v_mov_b32_e32 v62, v59
	global_store_dwordx4 v[2:3], v[44:47], off sc1
	v_mov_b32_e32 v64, v61
	v_bfe_u32 v49, v40, 16, 1
	v_pk_mul_f32 v[44:45], v[66:67], v[62:63]
	v_mov_b32_e32 v52, v51
	v_pk_mul_f32 v[46:47], v[4:5], v[64:65]
	v_add3_u32 v40, v40, v49, s91
	v_bfe_u32 v49, v45, 16, 1
	v_pk_mul_f32 v[2:3], v[56:57], v[52:53]
	v_bfe_u32 v0, v47, 16, 1
	v_bfe_u32 v29, v46, 16, 1
	v_bfe_u32 v48, v41, 16, 1
	v_add3_u32 v45, v45, v49, s91
	v_add3_u32 v41, v41, v48, s91
	v_add3_u32 v29, v46, v29, s91
	v_add3_u32 v0, v47, v0, s91
	v_bfe_u32 v46, v2, 16, 1
	v_bfe_u32 v47, v3, 16, 1
	v_bfe_u32 v48, v44, 16, 1
	v_lshrrev_b32_e32 v45, 16, v45
	v_add3_u32 v44, v44, v48, s91
	v_add3_u32 v3, v3, v47, s91
	v_add3_u32 v2, v2, v46, s91
	v_and_or_b32 v47, v0, s35, v45
	v_or_b32_e32 v0, s28, v37
	v_lshrrev_b32_e32 v2, 16, v2
	v_lshrrev_b32_e32 v3, 16, v3
	v_lshrrev_b32_e32 v44, 16, v44
	v_lshlrev_b32_e32 v0, 11, v0
	v_and_or_b32 v46, v29, s35, v44
	v_and_or_b32 v45, v41, s35, v3
	v_and_or_b32 v44, v40, s35, v2
	v_lshl_add_u64 v[2:3], v[30:31], 0, v[0:1]
	ds_read2_b32 v[40:41], v36 offset0:16 offset1:24
	ds_read2_b32 v[48:49], v36 offset0:82 offset1:90
	global_store_dwordx4 v[2:3], v[44:47], off sc1
	ds_read2_b32 v[2:3], v36 offset0:49 offset1:57
	ds_read2_b32 v[50:51], v36 offset0:115 offset1:123
	ds_read2_b32 v[52:53], v36 offset0:148 offset1:156
	ds_read2_b32 v[54:55], v36 offset0:214 offset1:222
	ds_read2_b32 v[58:59], v36 offset0:181 offset1:189
	ds_read2_b32 v[60:61], v36 offset0:247 offset1:255
	s_waitcnt lgkmcnt(7)
; #define LAS __attribute__((address_space(3)))
; __device__ __forceinline__ unsigned pk2(float lo, float hi) { return f2bf(lo) | (f2bf(hi) << 16); }
; #define LDS_WAVE_SYNC() asm volatile("s_waitcnt lgkmcnt(0)" ::: "memory")
; template <bool HASG>
; __device__ __forceinline__ void tr_item(const float* W, int K, int N, bf16* WT, int rowmode, const float* g, LAS float* scr, int item, int lane) {
;     ...
;     for (int j = 0; j < 4; ++j) { const int n = (lane >> 3) + 8 * j; const LAS float* s = scr + (8 * c) * 33 + n;
;         u32x4 o; o.x = pk2(s[0 * 33] * g0.x, s[1 * 33] * g0.y); o.y = pk2(s[2 * 33] * g0.z, s[3 * 33] * g0.w);
;         o.z = pk2(s[4 * 33] * g1.x, s[5 * 33] * g1.y); o.w = pk2(s[6 * 33] * g1.z, s[7 * 33] * g1.w);
;         *(u32x4*)(WT + (size_t)(drow0 + n) * K + k0 + 8 * c) = o; }
;     LDS_WAVE_SYNC();
	v_mov_b32_e32 v44, v40
	s_waitcnt lgkmcnt(5)
	v_mov_b32_e32 v46, v2
	s_waitcnt lgkmcnt(4)
	v_mov_b32_e32 v47, v50
	s_waitcnt lgkmcnt(3)
	v_mov_b32_e32 v62, v52
	s_waitcnt lgkmcnt(2)
	v_mov_b32_e32 v63, v54
	v_mov_b32_e32 v45, v48
	v_pk_mul_f32 v[46:47], v[42:43], v[46:47]
	v_pk_mul_f32 v[62:63], v[66:67], v[62:63]
	s_waitcnt lgkmcnt(1)
	v_mov_b32_e32 v64, v58
	s_waitcnt lgkmcnt(0)
	v_mov_b32_e32 v65, v60
	v_pk_mul_f32 v[44:45], v[56:57], v[44:45]
	v_pk_mul_f32 v[64:65], v[4:5], v[64:65]
	v_bfe_u32 v29, v47, 16, 1
	v_bfe_u32 v50, v63, 16, 1
	v_bfe_u32 v0, v65, 16, 1
	v_bfe_u32 v40, v46, 16, 1
	v_add3_u32 v29, v47, v29, s91
	v_bfe_u32 v47, v45, 16, 1
	v_add3_u32 v50, v63, v50, s91
	v_add3_u32 v40, v46, v40, s91
	v_add3_u32 v0, v65, v0, s91
	v_bfe_u32 v46, v44, 16, 1
	v_bfe_u32 v48, v62, 16, 1
	v_add3_u32 v45, v45, v47, s91
	v_lshrrev_b32_e32 v47, 16, v50
	v_bfe_u32 v2, v64, 16, 1
	v_add3_u32 v48, v62, v48, s91
	v_add3_u32 v44, v44, v46, s91
	v_and_or_b32 v47, v0, s35, v47
	v_or_b32_e32 v0, s28, v38
	v_add3_u32 v2, v64, v2, s91
	v_lshrrev_b32_e32 v44, 16, v44
	v_lshrrev_b32_e32 v45, 16, v45
	v_lshrrev_b32_e32 v46, 16, v48
	v_lshlrev_b32_e32 v0, 11, v0
	v_mov_b32_e32 v50, v3
	v_mov_b32_e32 v60, v59
	v_and_or_b32 v46, v2, s35, v46
	v_and_or_b32 v45, v29, s35, v45
	v_and_or_b32 v44, v40, s35, v44
	v_lshl_add_u64 v[62:63], v[30:31], 0, v[0:1]
	v_mov_b32_e32 v48, v41
	v_pk_mul_f32 v[2:3], v[42:43], v[50:51]
	v_mov_b32_e32 v54, v53
	v_pk_mul_f32 v[4:5], v[4:5], v[60:61]
	global_store_dwordx4 v[62:63], v[44:47], off sc1
	v_pk_mul_f32 v[40:41], v[56:57], v[48:49]
	v_pk_mul_f32 v[42:43], v[66:67], v[54:55]
	v_bfe_u32 v0, v5, 16, 1
	v_bfe_u32 v45, v2, 16, 1
	v_add3_u32 v2, v2, v45, s91
	v_add3_u32 v0, v5, v0, s91
	v_bfe_u32 v5, v40, 16, 1
	v_bfe_u32 v45, v43, 16, 1
	v_bfe_u32 v29, v4, 16, 1
	v_bfe_u32 v44, v3, 16, 1
	v_add3_u32 v43, v43, v45, s91
	v_add3_u32 v5, v40, v5, s91
	v_add3_u32 v3, v3, v44, s91
	v_add3_u32 v4, v4, v29, s91
	v_bfe_u32 v29, v41, 16, 1
	v_bfe_u32 v44, v42, 16, 1
	v_lshrrev_b32_e32 v40, 16, v5
	v_lshrrev_b32_e32 v5, 16, v43
	v_add3_u32 v42, v42, v44, s91
	v_add3_u32 v29, v41, v29, s91
	v_and_or_b32 v5, v0, s35, v5
	v_or_b32_e32 v0, s28, v39
	v_lshrrev_b32_e32 v29, 16, v29
	v_lshrrev_b32_e32 v41, 16, v42
	v_lshlrev_b32_e32 v0, 11, v0
	v_and_or_b32 v4, v4, s35, v41
	v_and_or_b32 v3, v3, s35, v29
	v_and_or_b32 v2, v2, s35, v40
	v_lshl_add_u64 v[30:31], v[30:31], 0, v[0:1]
	global_store_dwordx4 v[30:31], v[2:5], off sc1
	s_waitcnt lgkmcnt(0)

; template <bool HASG>
; __device__ __forceinline__ void tr_item(const float* W, int K, int N, bf16* WT, int rowmode, const float* g, LAS float* scr, int item, int lane) {
;     const int nblk = N / 32, kb = item / nblk, nb = item % nblk, k0 = 64 * kb, n0 = 32 * nb;
;     const float* wp = W + (size_t)(k0 + (lane >> 5)) * N + n0 + (lane & 31);
;     const int c = lane & 7;
;     float v[32];
; #pragma unroll
;     for (int i = 0; i < 32; ++i) v[i] = wp[(size_t)(2 * i) * N];
;     f32x4 g0 = (f32x4){1.f, 1.f, 1.f, 1.f}, g1 = g0;
;     if (HASG) { g0 = *(const f32x4*)(g + k0 + 8 * c); g1 = *(const f32x4*)(g + k0 + 8 * c + 4); }
;     asm volatile("" ::: "memory");
; #pragma unroll
;     for (int i = 0; i < 32; ++i) scr[(2 * i + (lane >> 5)) * 33 + (lane & 31)] = v[i];
; __device__ __forceinline__ void convert_items(const Args& a, LAS unsigned char* lds, int l, int it_lo, int it_hi, int gw, int NGW, int wave, int lane) {
;     ...
;         if (r < I_OUT) { tr_item<false>(a.in[18] + (size_t)l * D * D, D, D, wl + W_OUT, 0, nullptr, scr, r, lane); continue; } r -= I_OUT;
.LBB0_495:
	s_andn2_b64 vcc, exec, s[28:29]
	s_cbranch_vccnz .LBB0_497
	s_add_i32 s28, s66, 0x1a00
	s_and_b32 s29, s28, 0x1ffc0
	s_lshl_b32 s28, s67, 5
	v_or_b32_e32 v0, s29, v33
	v_readlane_b32 s4, v255, 8
	s_and_b32 s28, s28, 0x3e0
	v_lshlrev_b32_e32 v0, 12, v0
	v_readlane_b32 s5, v255, 9
	s_lshl_b32 s88, s28, 2
	s_nop 0
	v_lshl_add_u64 v[2:3], s[4:5], 0, v[0:1]
	v_lshl_add_u64 v[2:3], v[2:3], 0, s[88:89]
	v_lshlrev_b32_e32 v0, 2, v6
	v_lshl_add_u64 v[2:3], v[2:3], 0, v[0:1]
	s_movk_i32 s4, 0x2000
	v_add_co_u32_e32 v4, vcc, s4, v2
	s_movk_i32 s4, 0x4000
	s_nop 0
	v_addc_co_u32_e32 v5, vcc, 0, v3, vcc
	global_load_dword v0, v[2:3], off
	global_load_dword v29, v[4:5], off
	v_add_co_u32_e32 v4, vcc, s4, v2
	s_movk_i32 s4, 0x6000
	s_nop 0
	v_addc_co_u32_e32 v5, vcc, 0, v3, vcc
	global_load_dword v30, v[4:5], off
	v_add_co_u32_e32 v4, vcc, s4, v2
	s_mov_b32 s4, 0x8000
	s_nop 0
	v_addc_co_u32_e32 v5, vcc, 0, v3, vcc
	global_load_dword v31, v[4:5], off
	v_add_co_u32_e32 v4, vcc, s4, v2
	s_mov_b32 s4, 0xa000
	s_nop 0
	v_addc_co_u32_e32 v5, vcc, 0, v3, vcc
	global_load_dword v40, v[4:5], off
	v_add_co_u32_e32 v4, vcc, s4, v2
	s_mov_b32 s4, 0xc000
	s_nop 0
	v_addc_co_u32_e32 v5, vcc, 0, v3, vcc
	global_load_dword v41, v[4:5], off
	v_add_co_u32_e32 v4, vcc, s4, v2
	s_mov_b32 s4, 0xe000
	s_nop 0
	v_addc_co_u32_e32 v5, vcc, 0, v3, vcc
	global_load_dword v42, v[4:5], off
	v_add_co_u32_e32 v4, vcc, s4, v2
	s_mov_b32 s4, 0x12000
	s_nop 0
	v_addc_co_u32_e32 v5, vcc, 0, v3, vcc
	global_load_dword v43, v[4:5], off
	v_add_co_u32_e32 v4, vcc, s70, v2
	s_lshl_b32 s88, s29, 1
	s_nop 0
	v_addc_co_u32_e32 v5, vcc, 0, v3, vcc
	global_load_dword v44, v[4:5], off
	v_add_co_u32_e32 v4, vcc, s4, v2
	s_mov_b32 s4, 0x14000
	s_nop 0
	v_addc_co_u32_e32 v5, vcc, 0, v3, vcc
	global_load_dword v45, v[4:5], off
	v_add_co_u32_e32 v4, vcc, s4, v2
	s_mov_b32 s4, 0x18000
	s_nop 0
	v_addc_co_u32_e32 v5, vcc, 0, v3, vcc
	global_load_dword v46, v[4:5], off
	v_add_co_u32_e32 v4, vcc, s71, v2
	s_nop 1
	v_addc_co_u32_e32 v5, vcc, 0, v3, vcc
	global_load_dword v47, v[4:5], off
	v_add_co_u32_e32 v4, vcc, s4, v2
	s_mov_b32 s4, 0x1a000
	s_nop 0
	v_addc_co_u32_e32 v5, vcc, 0, v3, vcc
	global_load_dword v48, v[4:5], off
	v_add_co_u32_e32 v4, vcc, s4, v2
	s_mov_b32 s4, 0x1c000
	s_nop 0
	v_addc_co_u32_e32 v5, vcc, 0, v3, vcc
	global_load_dword v49, v[4:5], off
	v_add_co_u32_e32 v4, vcc, s4, v2
	s_mov_b32 s4, 0x1e000
	s_nop 0
	v_addc_co_u32_e32 v5, vcc, 0, v3, vcc
	global_load_dword v50, v[4:5], off
	v_add_co_u32_e32 v4, vcc, s4, v2
	s_mov_b32 s4, 0x20000
	s_nop 0
	v_addc_co_u32_e32 v5, vcc, 0, v3, vcc
	global_load_dword v51, v[4:5], off
	v_add_co_u32_e32 v4, vcc, s4, v2
	s_mov_b32 s4, 0x22000
	s_nop 0
	v_addc_co_u32_e32 v5, vcc, 0, v3, vcc
	global_load_dword v52, v[4:5], off
	v_add_co_u32_e32 v4, vcc, s4, v2
	s_mov_b32 s4, 0x24000
	s_nop 0
	v_addc_co_u32_e32 v5, vcc, 0, v3, vcc
	global_load_dword v53, v[4:5], off
	v_add_co_u32_e32 v4, vcc, s4, v2
	s_mov_b32 s4, 0x26000
	s_nop 0
	v_addc_co_u32_e32 v5, vcc, 0, v3, vcc
	global_load_dword v54, v[4:5], off
	v_add_co_u32_e32 v4, vcc, s4, v2
	s_mov_b32 s4, 0x28000
	s_nop 0
	v_addc_co_u32_e32 v5, vcc, 0, v3, vcc
	global_load_dword v55, v[4:5], off
	v_add_co_u32_e32 v4, vcc, s4, v2
	s_mov_b32 s4, 0x2a000
	s_nop 0
	v_addc_co_u32_e32 v5, vcc, 0, v3, vcc
	global_load_dword v56, v[4:5], off
	v_add_co_u32_e32 v4, vcc, s4, v2
	s_mov_b32 s4, 0x2c000
	s_nop 0
	v_addc_co_u32_e32 v5, vcc, 0, v3, vcc
	global_load_dword v57, v[4:5], off
	v_add_co_u32_e32 v4, vcc, s4, v2
	s_mov_b32 s4, 0x2e000
	s_nop 0
	v_addc_co_u32_e32 v5, vcc, 0, v3, vcc
	global_load_dword v58, v[4:5], off
	v_add_co_u32_e32 v4, vcc, s4, v2
	s_mov_b32 s4, 0x30000
	s_nop 0
	v_addc_co_u32_e32 v5, vcc, 0, v3, vcc
	global_load_dword v59, v[4:5], off
	v_add_co_u32_e32 v4, vcc, s4, v2
	s_mov_b32 s4, 0x32000
	s_nop 0
	v_addc_co_u32_e32 v5, vcc, 0, v3, vcc
	global_load_dword v60, v[4:5], off
	v_add_co_u32_e32 v4, vcc, s4, v2
	s_mov_b32 s4, 0x34000
	s_nop 0
	v_addc_co_u32_e32 v5, vcc, 0, v3, vcc
	global_load_dword v61, v[4:5], off
	v_add_co_u32_e32 v4, vcc, s4, v2
	s_mov_b32 s4, 0x36000
	s_nop 0
	v_addc_co_u32_e32 v5, vcc, 0, v3, vcc
	global_load_dword v62, v[4:5], off
	v_add_co_u32_e32 v4, vcc, s4, v2
	s_mov_b32 s4, 0x38000
	s_nop 0
	v_addc_co_u32_e32 v5, vcc, 0, v3, vcc
	global_load_dword v63, v[4:5], off
	v_add_co_u32_e32 v4, vcc, s4, v2
	s_mov_b32 s4, 0x3a000
	s_nop 0
	v_addc_co_u32_e32 v5, vcc, 0, v3, vcc
	global_load_dword v64, v[4:5], off
	v_add_co_u32_e32 v4, vcc, s4, v2
	s_mov_b32 s4, 0x3c000
	s_nop 0
	v_addc_co_u32_e32 v5, vcc, 0, v3, vcc
	global_load_dword v65, v[4:5], off
	v_add_co_u32_e32 v4, vcc, s4, v2
	s_mov_b32 s4, 0x3e000
	s_nop 0
	v_addc_co_u32_e32 v5, vcc, 0, v3, vcc
	v_add_co_u32_e32 v2, vcc, s4, v2
	global_load_dword v4, v[4:5], off
	s_nop 0
	v_addc_co_u32_e32 v3, vcc, 0, v3, vcc
	global_load_dword v2, v[2:3], off
	s_waitcnt vmcnt(30)
	ds_write2_b32 v34, v0, v29 offset1:66
	s_waitcnt vmcnt(28)
	ds_write2_b32 v34, v30, v31 offset0:132 offset1:198
	v_add_u32_e32 v0, 0x400, v34
	s_waitcnt vmcnt(26)
	ds_write2_b32 v0, v40, v41 offset0:8 offset1:74
	s_waitcnt vmcnt(24)
	ds_write2_b32 v0, v42, v43 offset0:140 offset1:206
	v_add_u32_e32 v0, 0x800, v34
	s_waitcnt vmcnt(22)
	ds_write2_b32 v0, v44, v45 offset0:16 offset1:82
	s_waitcnt vmcnt(20)
	ds_write2_b32 v0, v46, v47 offset0:148 offset1:214
	v_add_u32_e32 v0, 0xc00, v34
	s_waitcnt vmcnt(18)
; #define LAS __attribute__((address_space(3)))
; __device__ __forceinline__ unsigned pk2(float lo, float hi) { return f2bf(lo) | (f2bf(hi) << 16); }
; #define LDS_WAVE_SYNC() asm volatile("s_waitcnt lgkmcnt(0)" ::: "memory")
; template <bool HASG>
; __device__ __forceinline__ void tr_item(const float* W, int K, int N, bf16* WT, int rowmode, const float* g, LAS float* scr, int item, int lane) {
;     ...
;     for (int i = 0; i < 32; ++i) scr[(2 * i + (lane >> 5)) * 33 + (lane & 31)] = v[i];
;     LDS_WAVE_SYNC();
;     const int drow0 = rowmode == 0 ? n0 : ((n0 >> 7) * 256 + (n0 & 127) + (rowmode == 2 ? 128 : 0));
; #pragma unroll
;     for (int j = 0; j < 4; ++j) { const int n = (lane >> 3) + 8 * j; const LAS float* s = scr + (8 * c) * 33 + n;
;         u32x4 o; o.x = pk2(s[0 * 33] * g0.x, s[1 * 33] * g0.y); o.y = pk2(s[2 * 33] * g0.z, s[3 * 33] * g0.w);
;         o.z = pk2(s[4 * 33] * g1.x, s[5 * 33] * g1.y); o.w = pk2(s[6 * 33] * g1.z, s[7 * 33] * g1.w);
;         *(u32x4*)(WT + (size_t)(drow0 + n) * K + k0 + 8 * c) = o; }
;     LDS_WAVE_SYNC();
	ds_write2_b32 v0, v48, v49 offset0:24 offset1:90
	s_waitcnt vmcnt(16)
	ds_write2_b32 v0, v50, v51 offset0:156 offset1:222
	v_add_u32_e32 v0, 0x1000, v34
	s_waitcnt vmcnt(14)
	ds_write2_b32 v0, v52, v53 offset0:32 offset1:98
	s_waitcnt vmcnt(12)
	ds_write2_b32 v0, v54, v55 offset0:164 offset1:230
	v_add_u32_e32 v0, 0x1400, v34
	s_waitcnt vmcnt(10)
	ds_write2_b32 v0, v56, v57 offset0:40 offset1:106
	s_waitcnt vmcnt(8)
	ds_write2_b32 v0, v58, v59 offset0:172 offset1:238
	v_add_u32_e32 v0, 0x1800, v34
	s_waitcnt vmcnt(6)
	ds_write2_b32 v0, v60, v61 offset0:48 offset1:114
	s_waitcnt vmcnt(4)
	ds_write2_b32 v0, v62, v63 offset0:180 offset1:246
	v_add_u32_e32 v0, 0x1c00, v34
	s_waitcnt vmcnt(2)
	ds_write2_b32 v0, v64, v65 offset0:56 offset1:122
	s_waitcnt vmcnt(0)
	ds_write2_b32 v0, v4, v2 offset0:188 offset1:254
	s_waitcnt lgkmcnt(0)
	ds_read2_b32 v[4:5], v36 offset0:33 offset1:41
	ds_read2_b32 v[30:31], v36 offset1:8
	ds_read2_b32 v[44:45], v36 offset0:66 offset1:74
	ds_read2_b32 v[46:47], v36 offset0:99 offset1:107
	ds_read2_b32 v[48:49], v36 offset0:132 offset1:140
	ds_read2_b32 v[50:51], v36 offset0:165 offset1:173
	ds_read2_b32 v[52:53], v36 offset0:198 offset1:206
	ds_read2_b32 v[54:55], v36 offset0:231 offset1:239
	s_waitcnt lgkmcnt(7)
	v_bfe_u32 v29, v4, 16, 1
	s_waitcnt lgkmcnt(6)
	v_bfe_u32 v0, v30, 16, 1
	v_add3_u32 v0, v30, v0, s91
	v_lshrrev_b32_e32 v0, 16, v0
	v_add3_u32 v4, v4, v29, s91
	v_and_or_b32 v40, v4, s35, v0
	s_waitcnt lgkmcnt(5)
	v_bfe_u32 v0, v44, 16, 1
	v_add3_u32 v0, v44, v0, s91
	s_waitcnt lgkmcnt(4)
	v_bfe_u32 v4, v46, 16, 1
	v_lshrrev_b32_e32 v0, 16, v0
	v_add3_u32 v4, v46, v4, s91
	v_and_or_b32 v41, v4, s35, v0
	s_waitcnt lgkmcnt(3)
	v_bfe_u32 v0, v48, 16, 1
	v_add3_u32 v0, v48, v0, s91
	s_waitcnt lgkmcnt(2)
	v_bfe_u32 v4, v50, 16, 1
	v_lshrrev_b32_e32 v0, 16, v0
	v_add3_u32 v4, v50, v4, s91
	v_and_or_b32 v42, v4, s35, v0
	s_waitcnt lgkmcnt(1)
	v_bfe_u32 v0, v52, 16, 1
	v_add3_u32 v0, v52, v0, s91
	s_waitcnt lgkmcnt(0)
	v_bfe_u32 v4, v54, 16, 1
	v_lshrrev_b32_e32 v0, 16, v0
	v_add3_u32 v4, v54, v4, s91
	v_and_or_b32 v43, v4, s35, v0
	v_or_b32_e32 v0, s28, v35
	v_lshl_add_u64 v[2:3], v[16:17], 0, s[88:89]
	v_lshlrev_b32_e32 v0, 11, v0
	v_lshl_add_u64 v[56:57], v[2:3], 0, v[0:1]
	v_bfe_u32 v0, v31, 16, 1
	v_add3_u32 v0, v31, v0, s91
	v_bfe_u32 v4, v5, 16, 1
	v_lshrrev_b32_e32 v0, 16, v0
	v_add3_u32 v4, v5, v4, s91
	global_store_dwordx4 v[56:57], v[40:43], off sc1
	s_nop 1
	v_and_or_b32 v40, v4, s35, v0
	v_bfe_u32 v0, v45, 16, 1
	v_add3_u32 v0, v45, v0, s91
	v_bfe_u32 v4, v47, 16, 1
	v_lshrrev_b32_e32 v0, 16, v0
	v_add3_u32 v4, v47, v4, s91
	v_and_or_b32 v41, v4, s35, v0
	v_bfe_u32 v0, v49, 16, 1
	v_add3_u32 v0, v49, v0, s91
	v_bfe_u32 v4, v51, 16, 1
	v_lshrrev_b32_e32 v0, 16, v0
	v_add3_u32 v4, v51, v4, s91
	v_and_or_b32 v42, v4, s35, v0
	v_bfe_u32 v0, v53, 16, 1
	v_add3_u32 v0, v53, v0, s91
	v_bfe_u32 v4, v55, 16, 1
	v_lshrrev_b32_e32 v0, 16, v0
	v_add3_u32 v4, v55, v4, s91
	v_and_or_b32 v43, v4, s35, v0
	v_or_b32_e32 v0, s28, v37
	v_lshlrev_b32_e32 v0, 11, v0
	v_lshl_add_u64 v[4:5], v[2:3], 0, v[0:1]
	global_store_dwordx4 v[4:5], v[40:43], off sc1
	ds_read2_b32 v[4:5], v36 offset0:49 offset1:57
	ds_read2_b32 v[30:31], v36 offset0:16 offset1:24
	ds_read2_b32 v[44:45], v36 offset0:82 offset1:90
	ds_read2_b32 v[46:47], v36 offset0:115 offset1:123
	ds_read2_b32 v[48:49], v36 offset0:148 offset1:156
	ds_read2_b32 v[50:51], v36 offset0:181 offset1:189
	ds_read2_b32 v[52:53], v36 offset0:214 offset1:222
	ds_read2_b32 v[54:55], v36 offset0:247 offset1:255
	s_waitcnt lgkmcnt(7)
	v_bfe_u32 v29, v4, 16, 1
	s_waitcnt lgkmcnt(6)
	v_bfe_u32 v0, v30, 16, 1
	v_add3_u32 v0, v30, v0, s91
	v_lshrrev_b32_e32 v0, 16, v0
	v_add3_u32 v4, v4, v29, s91
	v_and_or_b32 v40, v4, s35, v0
	s_waitcnt lgkmcnt(5)
	v_bfe_u32 v0, v44, 16, 1
	v_add3_u32 v0, v44, v0, s91
	s_waitcnt lgkmcnt(4)
	v_bfe_u32 v4, v46, 16, 1
	v_lshrrev_b32_e32 v0, 16, v0
	v_add3_u32 v4, v46, v4, s91
	v_and_or_b32 v41, v4, s35, v0
	s_waitcnt lgkmcnt(3)
	v_bfe_u32 v0, v48, 16, 1
	v_add3_u32 v0, v48, v0, s91
	s_waitcnt lgkmcnt(2)
	v_bfe_u32 v4, v50, 16, 1
	v_lshrrev_b32_e32 v0, 16, v0
	v_add3_u32 v4, v50, v4, s91
	v_and_or_b32 v42, v4, s35, v0
	s_waitcnt lgkmcnt(1)
	v_bfe_u32 v0, v52, 16, 1
	v_add3_u32 v0, v52, v0, s91
	s_waitcnt lgkmcnt(0)
	v_bfe_u32 v4, v54, 16, 1
	v_lshrrev_b32_e32 v0, 16, v0
	v_add3_u32 v4, v54, v4, s91
	v_and_or_b32 v43, v4, s35, v0
	v_or_b32_e32 v0, s28, v38
	v_lshlrev_b32_e32 v0, 11, v0
	v_lshl_add_u64 v[56:57], v[2:3], 0, v[0:1]
	v_bfe_u32 v0, v31, 16, 1
	v_add3_u32 v0, v31, v0, s91
	v_bfe_u32 v4, v5, 16, 1
	v_lshrrev_b32_e32 v0, 16, v0
	v_add3_u32 v4, v5, v4, s91
	global_store_dwordx4 v[56:57], v[40:43], off sc1
	s_nop 1
	v_and_or_b32 v40, v4, s35, v0
	v_bfe_u32 v0, v45, 16, 1
	v_add3_u32 v0, v45, v0, s91
	v_bfe_u32 v4, v47, 16, 1
	v_lshrrev_b32_e32 v0, 16, v0
	v_add3_u32 v4, v47, v4, s91
	v_and_or_b32 v41, v4, s35, v0
	v_bfe_u32 v0, v49, 16, 1
	v_add3_u32 v0, v49, v0, s91
	v_bfe_u32 v4, v51, 16, 1
	v_lshrrev_b32_e32 v0, 16, v0
	v_add3_u32 v4, v51, v4, s91
	v_and_or_b32 v42, v4, s35, v0
	v_bfe_u32 v0, v53, 16, 1
	v_add3_u32 v0, v53, v0, s91
	v_bfe_u32 v4, v55, 16, 1
	v_lshrrev_b32_e32 v0, 16, v0
	v_add3_u32 v4, v55, v4, s91
	v_and_or_b32 v43, v4, s35, v0
	v_or_b32_e32 v0, s28, v39
	v_lshlrev_b32_e32 v0, 11, v0
	v_lshl_add_u64 v[2:3], v[2:3], 0, v[0:1]
	global_store_dwordx4 v[2:3], v[40:43], off sc1
	s_waitcnt lgkmcnt(0)

; template <bool HASG>
; __device__ __forceinline__ void tr_item(const float* W, int K, int N, bf16* WT, int rowmode, const float* g, LAS float* scr, int item, int lane) {
;     const int nblk = N / 32, kb = item / nblk, nb = item % nblk, k0 = 64 * kb, n0 = 32 * nb;
;     const float* wp = W + (size_t)(k0 + (lane >> 5)) * N + n0 + (lane & 31);
;     const int c = lane & 7;
;     float v[32];
; #pragma unroll
;     for (int i = 0; i < 32; ++i) v[i] = wp[(size_t)(2 * i) * N];
;     f32x4 g0 = (f32x4){1.f, 1.f, 1.f, 1.f}, g1 = g0;
;     if (HASG) { g0 = *(const f32x4*)(g + k0 + 8 * c); g1 = *(const f32x4*)(g + k0 + 8 * c + 4); }
; __device__ __forceinline__ void convert_items(const Args& a, LAS unsigned char* lds, int l, int it_lo, int it_hi, int gw, int NGW, int wave, int lane) {
;     ...
;         if (r < I_IN) { tr_item<true>(a.in[6] + (size_t)l * D * DIN, D, DIN, wl + W_IN, 0, a.in[5] + l * D, scr, r, lane); continue; } r -= I_IN;
.LBB0_498:
	s_andn2_b64 vcc, exec, s[28:29]
	s_cbranch_vccnz .LBB0_500
	s_add_i32 s28, s67, 0xef80
	s_bfe_u32 s29, s28, 0xd0003
	s_mulk_i32 s29, 0x2493
	s_lshr_b32 s29, s29, 16
	s_mul_i32 s47, s29, 56
	s_sub_i32 s28, s28, s47
	s_lshl_b32 s28, s28, 5
	v_lshl_or_b32 v0, s29, 6, v33
	s_and_b32 s28, s28, 0xffe0
	v_mul_u32_u24_e32 v0, 0x700, v0
	v_lshl_add_u64 v[2:3], v[0:1], 2, s[78:79]
	s_lshl_b32 s88, s28, 2
	v_lshl_add_u64 v[2:3], v[2:3], 0, s[88:89]
	v_lshlrev_b32_e32 v0, 2, v6
	v_lshl_add_u64 v[2:3], v[2:3], 0, v[0:1]
	s_movk_i32 s4, 0x3000
	v_add_co_u32_e32 v4, vcc, s4, v2
	s_movk_i32 s4, 0x7000
	s_nop 0
	v_addc_co_u32_e32 v5, vcc, 0, v3, vcc
	v_add_co_u32_e32 v30, vcc, s4, v2
	s_mov_b32 s4, 0xa000
	s_nop 0
	v_addc_co_u32_e32 v31, vcc, 0, v3, vcc
	v_add_co_u32_e32 v40, vcc, s4, v2
	s_mov_b32 s4, 0xe000
	s_nop 0
	v_addc_co_u32_e32 v41, vcc, 0, v3, vcc
	v_add_co_u32_e32 v42, vcc, s4, v2
	s_mov_b32 s4, 0x11000
	s_nop 0
	v_addc_co_u32_e32 v43, vcc, 0, v3, vcc
	v_add_co_u32_e32 v44, vcc, s4, v2
	s_mov_b32 s4, 0x15000
	s_nop 0
	v_addc_co_u32_e32 v45, vcc, 0, v3, vcc
	v_add_co_u32_e32 v46, vcc, s4, v2
	s_mov_b32 s4, 0x18000
	s_nop 0
	v_addc_co_u32_e32 v47, vcc, 0, v3, vcc
	v_add_co_u32_e32 v48, vcc, s4, v2
	s_mov_b32 s4, 0x1c000
	s_nop 0
	v_addc_co_u32_e32 v49, vcc, 0, v3, vcc
	global_load_dword v0, v[2:3], off
	global_load_dword v29, v[4:5], off offset:2048
	global_load_dword v52, v[30:31], off
	global_load_dword v53, v[40:41], off offset:2048
	global_load_dword v54, v[42:43], off
	global_load_dword v55, v[44:45], off offset:2048
	global_load_dword v56, v[46:47], off
	global_load_dword v57, v[48:49], off offset:2048
	v_add_co_u32_e32 v4, vcc, s4, v2
	s_mov_b32 s4, 0x1f000
	s_nop 0
	v_addc_co_u32_e32 v5, vcc, 0, v3, vcc
	v_add_co_u32_e32 v30, vcc, s4, v2
	s_mov_b32 s4, 0x23000
	s_nop 0
	v_addc_co_u32_e32 v31, vcc, 0, v3, vcc
	v_add_co_u32_e32 v40, vcc, s4, v2
	s_mov_b32 s4, 0x26000
	s_nop 0
	v_addc_co_u32_e32 v41, vcc, 0, v3, vcc
	v_add_co_u32_e32 v42, vcc, s4, v2
	s_mov_b32 s4, 0x2a000
	s_nop 0
	v_addc_co_u32_e32 v43, vcc, 0, v3, vcc
	v_add_co_u32_e32 v44, vcc, s4, v2
	s_mov_b32 s4, 0x2d000
	s_nop 0
	v_addc_co_u32_e32 v45, vcc, 0, v3, vcc
	v_add_co_u32_e32 v46, vcc, s4, v2
	s_mov_b32 s4, 0x31000
	s_nop 0
	v_addc_co_u32_e32 v47, vcc, 0, v3, vcc
	v_add_co_u32_e32 v48, vcc, s4, v2
	s_mov_b32 s4, 0x34000
	s_nop 0
	v_addc_co_u32_e32 v49, vcc, 0, v3, vcc
	v_add_co_u32_e32 v50, vcc, s4, v2
	s_mov_b32 s4, 0x38000
	s_nop 0
	v_addc_co_u32_e32 v51, vcc, 0, v3, vcc
	global_load_dword v58, v[4:5], off
	global_load_dword v59, v[30:31], off offset:2048
	global_load_dword v60, v[40:41], off
	global_load_dword v61, v[42:43], off offset:2048
	global_load_dword v62, v[44:45], off
	global_load_dword v63, v[46:47], off offset:2048
	global_load_dword v64, v[48:49], off
	global_load_dword v65, v[50:51], off offset:2048
	v_add_co_u32_e32 v4, vcc, s4, v2
	s_mov_b32 s4, 0x3b000
	s_nop 0
	v_addc_co_u32_e32 v5, vcc, 0, v3, vcc
	v_add_co_u32_e32 v30, vcc, s4, v2
	s_mov_b32 s4, 0x3f000
	s_nop 0
	v_addc_co_u32_e32 v31, vcc, 0, v3, vcc
	v_add_co_u32_e32 v40, vcc, s4, v2
	s_mov_b32 s4, 0x42000
	s_nop 0
	v_addc_co_u32_e32 v41, vcc, 0, v3, vcc
	v_add_co_u32_e32 v42, vcc, s4, v2
	s_mov_b32 s4, 0x46000
	s_nop 0
	v_addc_co_u32_e32 v43, vcc, 0, v3, vcc
	v_add_co_u32_e32 v44, vcc, s4, v2
	s_mov_b32 s4, 0x49000
	s_nop 0
	v_addc_co_u32_e32 v45, vcc, 0, v3, vcc
	v_add_co_u32_e32 v46, vcc, s4, v2
	s_mov_b32 s4, 0x4d000
	s_nop 0
	v_addc_co_u32_e32 v47, vcc, 0, v3, vcc
	v_add_co_u32_e32 v48, vcc, s4, v2
	s_mov_b32 s4, 0x50000
	s_nop 0
	v_addc_co_u32_e32 v49, vcc, 0, v3, vcc
	v_add_co_u32_e32 v50, vcc, s4, v2
	s_mov_b32 s4, 0x54000
	s_nop 0
	v_addc_co_u32_e32 v51, vcc, 0, v3, vcc
	global_load_dword v66, v[4:5], off
	global_load_dword v67, v[30:31], off offset:2048
	global_load_dword v68, v[40:41], off
	global_load_dword v69, v[42:43], off offset:2048
	global_load_dword v70, v[44:45], off
	global_load_dword v71, v[46:47], off offset:2048
	global_load_dword v72, v[48:49], off
	s_nop 0
	global_load_dword v50, v[50:51], off offset:2048
	v_add_co_u32_e32 v4, vcc, s4, v2
	s_mov_b32 s4, 0x57000
	s_nop 0
	v_addc_co_u32_e32 v5, vcc, 0, v3, vcc
	v_add_co_u32_e32 v30, vcc, s4, v2
	s_mov_b32 s4, 0x5b000
	s_nop 0
	v_addc_co_u32_e32 v31, vcc, 0, v3, vcc
	v_add_co_u32_e32 v40, vcc, s4, v2
	s_mov_b32 s4, 0x5e000
	s_nop 0
	v_addc_co_u32_e32 v41, vcc, 0, v3, vcc
	v_add_co_u32_e32 v42, vcc, s4, v2
	s_mov_b32 s4, 0x62000
	s_nop 0
	v_addc_co_u32_e32 v43, vcc, 0, v3, vcc
	v_add_co_u32_e32 v44, vcc, s4, v2
	s_mov_b32 s4, 0x65000
	s_nop 0
	v_addc_co_u32_e32 v45, vcc, 0, v3, vcc
	v_add_co_u32_e32 v46, vcc, s4, v2
	s_mov_b32 s4, 0x69000
	s_nop 0
	v_addc_co_u32_e32 v47, vcc, 0, v3, vcc
	v_add_co_u32_e32 v48, vcc, s4, v2
	s_mov_b32 s4, 0x6c000
	s_nop 0
	v_addc_co_u32_e32 v49, vcc, 0, v3, vcc
	v_add_co_u32_e32 v2, vcc, s4, v2
	s_lshl_b32 s88, s29, 8
	s_nop 0
	v_addc_co_u32_e32 v3, vcc, 0, v3, vcc
	global_load_dword v51, v[4:5], off
	global_load_dword v73, v[30:31], off offset:2048
	global_load_dword v74, v[40:41], off
	global_load_dword v75, v[42:43], off offset:2048
	s_nop 0
	global_load_dword v44, v[44:45], off
	s_nop 0
	global_load_dword v45, v[46:47], off offset:2048
	s_nop 0
	global_load_dword v46, v[48:49], off
	global_load_dword v47, v[2:3], off offset:2048
	v_lshl_add_u64 v[30:31], v[24:25], 0, s[88:89]
	global_load_dwordx4 v[2:5], v[30:31], off
	global_load_dwordx4 v[40:43], v[30:31], off offset:16
	s_waitcnt vmcnt(32)
	ds_write2_b32 v34, v0, v29 offset1:66
	s_waitcnt vmcnt(30)
	ds_write2_b32 v34, v52, v53 offset0:132 offset1:198
	v_add_u32_e32 v0, 0x400, v34
	s_waitcnt vmcnt(28)
; #define LAS __attribute__((address_space(3)))
; __device__ __forceinline__ unsigned pk2(float lo, float hi) { return f2bf(lo) | (f2bf(hi) << 16); }
; #define LDS_WAVE_SYNC() asm volatile("s_waitcnt lgkmcnt(0)" ::: "memory")
; template <bool HASG>
; __device__ __forceinline__ void tr_item(const float* W, int K, int N, bf16* WT, int rowmode, const float* g, LAS float* scr, int item, int lane) {
;     ...
;     for (int i = 0; i < 32; ++i) scr[(2 * i + (lane >> 5)) * 33 + (lane & 31)] = v[i];
;     LDS_WAVE_SYNC();
;     const int drow0 = rowmode == 0 ? n0 : ((n0 >> 7) * 256 + (n0 & 127) + (rowmode == 2 ? 128 : 0));
; #pragma unroll
;     for (int j = 0; j < 4; ++j) { const int n = (lane >> 3) + 8 * j; const LAS float* s = scr + (8 * c) * 33 + n;
;         u32x4 o; o.x = pk2(s[0 * 33] * g0.x, s[1 * 33] * g0.y); o.y = pk2(s[2 * 33] * g0.z, s[3 * 33] * g0.w);
;         o.z = pk2(s[4 * 33] * g1.x, s[5 * 33] * g1.y); o.w = pk2(s[6 * 33] * g1.z, s[7 * 33] * g1.w);
;         *(u32x4*)(WT + (size_t)(drow0 + n) * K + k0 + 8 * c) = o; }
	ds_write2_b32 v0, v54, v55 offset0:8 offset1:74
	s_waitcnt vmcnt(26)
	ds_write2_b32 v0, v56, v57 offset0:140 offset1:206
	v_add_u32_e32 v0, 0x800, v34
	s_waitcnt vmcnt(24)
	ds_write2_b32 v0, v58, v59 offset0:16 offset1:82
	s_waitcnt vmcnt(22)
	ds_write2_b32 v0, v60, v61 offset0:148 offset1:214
	v_add_u32_e32 v0, 0xc00, v34
	s_waitcnt vmcnt(20)
	ds_write2_b32 v0, v62, v63 offset0:24 offset1:90
	s_waitcnt vmcnt(18)
	ds_write2_b32 v0, v64, v65 offset0:156 offset1:222
	v_add_u32_e32 v0, 0x1000, v34
	s_waitcnt vmcnt(16)
	ds_write2_b32 v0, v66, v67 offset0:32 offset1:98
	s_waitcnt vmcnt(14)
	ds_write2_b32 v0, v68, v69 offset0:164 offset1:230
	v_add_u32_e32 v0, 0x1400, v34
	s_waitcnt vmcnt(12)
	ds_write2_b32 v0, v70, v71 offset0:40 offset1:106
	s_waitcnt vmcnt(10)
	ds_write2_b32 v0, v72, v50 offset0:172 offset1:238
	v_add_u32_e32 v0, 0x1800, v34
	s_waitcnt vmcnt(8)
	ds_write2_b32 v0, v51, v73 offset0:48 offset1:114
	s_waitcnt vmcnt(6)
	ds_write2_b32 v0, v74, v75 offset0:180 offset1:246
	v_add_u32_e32 v0, 0x1c00, v34
	s_waitcnt vmcnt(4)
	ds_write2_b32 v0, v44, v45 offset0:56 offset1:122
	s_waitcnt vmcnt(2)
	ds_write2_b32 v0, v46, v47 offset0:188 offset1:254
	s_waitcnt lgkmcnt(0)
	ds_read2_b32 v[48:49], v36 offset0:33 offset1:41
	ds_read2_b32 v[50:51], v36 offset1:8
	ds_read2_b32 v[52:53], v36 offset0:66 offset1:74
	ds_read2_b32 v[54:55], v36 offset0:99 offset1:107
	ds_read2_b32 v[58:59], v36 offset0:132 offset1:140
	ds_read2_b32 v[60:61], v36 offset0:165 offset1:173
	ds_read2_b32 v[62:63], v36 offset0:198 offset1:206
	ds_read2_b32 v[64:65], v36 offset0:231 offset1:239
	s_waitcnt vmcnt(1)
	v_mov_b32_e32 v56, v2
	v_mov_b32_e32 v57, v4
	v_mov_b32_e32 v4, v3
	s_waitcnt lgkmcnt(7)
	v_mov_b32_e32 v2, v48
	s_waitcnt lgkmcnt(4)
	v_mov_b32_e32 v3, v54
	v_pk_mul_f32 v[2:3], v[4:5], v[2:3]
	s_waitcnt vmcnt(0)
	v_mov_b32_e32 v66, v40
	v_mov_b32_e32 v67, v42
	s_waitcnt lgkmcnt(3)
	v_mov_b32_e32 v46, v58
	s_waitcnt lgkmcnt(1)
	v_mov_b32_e32 v47, v62
	v_mov_b32_e32 v42, v41
	v_mov_b32_e32 v40, v60
	s_waitcnt lgkmcnt(0)
	v_mov_b32_e32 v41, v64
	v_mov_b32_e32 v44, v50
	v_mov_b32_e32 v45, v52
	v_pk_mul_f32 v[46:47], v[66:67], v[46:47]
	v_pk_mul_f32 v[40:41], v[42:43], v[40:41]
	v_bfe_u32 v50, v2, 16, 1
	v_pk_mul_f32 v[44:45], v[56:57], v[44:45]
	v_bfe_u32 v0, v41, 16, 1
	v_add3_u32 v2, v2, v50, s91
	v_bfe_u32 v50, v47, 16, 1
	v_bfe_u32 v29, v40, 16, 1
	v_bfe_u32 v48, v3, 16, 1
	v_add3_u32 v0, v41, v0, s91
	v_bfe_u32 v41, v45, 16, 1
	v_add3_u32 v47, v47, v50, s91
	v_add3_u32 v3, v3, v48, s91
	v_add3_u32 v29, v40, v29, s91
	v_bfe_u32 v40, v44, 16, 1
	v_bfe_u32 v48, v46, 16, 1
	v_add3_u32 v41, v45, v41, s91
	v_lshrrev_b32_e32 v45, 16, v47
	s_lshl_b32 s88, s29, 7
	v_add3_u32 v46, v46, v48, s91
	v_add3_u32 v40, v44, v40, s91
	v_and_or_b32 v47, v0, s35, v45
	v_or_b32_e32 v0, s28, v35
	v_lshl_add_u64 v[30:31], v[18:19], 0, s[88:89]
	v_lshrrev_b32_e32 v40, 16, v40
	v_lshrrev_b32_e32 v41, 16, v41
	v_lshrrev_b32_e32 v44, 16, v46
	v_lshlrev_b32_e32 v0, 11, v0
	v_mov_b32_e32 v54, v49
	v_and_or_b32 v46, v29, s35, v44
	v_and_or_b32 v45, v3, s35, v41
	v_and_or_b32 v44, v2, s35, v40
	v_lshl_add_u64 v[2:3], v[30:31], 0, v[0:1]
	v_pk_mul_f32 v[40:41], v[4:5], v[54:55]
	v_mov_b32_e32 v62, v59
	global_store_dwordx4 v[2:3], v[44:47], off sc1
	v_mov_b32_e32 v64, v61
	v_bfe_u32 v49, v40, 16, 1
	v_pk_mul_f32 v[44:45], v[66:67], v[62:63]
	v_mov_b32_e32 v52, v51
	v_pk_mul_f32 v[46:47], v[42:43], v[64:65]
	v_add3_u32 v40, v40, v49, s91
	v_bfe_u32 v49, v45, 16, 1
	v_pk_mul_f32 v[2:3], v[56:57], v[52:53]
	v_bfe_u32 v0, v47, 16, 1
	v_bfe_u32 v29, v46, 16, 1
	v_bfe_u32 v48, v41, 16, 1
	v_add3_u32 v45, v45, v49, s91
	v_add3_u32 v41, v41, v48, s91
	v_add3_u32 v29, v46, v29, s91
	v_add3_u32 v0, v47, v0, s91
	v_bfe_u32 v46, v2, 16, 1
	v_bfe_u32 v47, v3, 16, 1
	v_bfe_u32 v48, v44, 16, 1
	v_lshrrev_b32_e32 v45, 16, v45
	v_add3_u32 v44, v44, v48, s91
	v_add3_u32 v3, v3, v47, s91
	v_add3_u32 v2, v2, v46, s91
	v_and_or_b32 v47, v0, s35, v45
	v_or_b32_e32 v0, s28, v37
	v_lshrrev_b32_e32 v2, 16, v2
	v_lshrrev_b32_e32 v3, 16, v3
	v_lshrrev_b32_e32 v44, 16, v44
	v_lshlrev_b32_e32 v0, 11, v0
	v_and_or_b32 v46, v29, s35, v44
	v_and_or_b32 v45, v41, s35, v3
	v_and_or_b32 v44, v40, s35, v2
	v_lshl_add_u64 v[2:3], v[30:31], 0, v[0:1]
	ds_read2_b32 v[40:41], v36 offset0:16 offset1:24
	ds_read2_b32 v[48:49], v36 offset0:82 offset1:90
	global_store_dwordx4 v[2:3], v[44:47], off sc1
	ds_read2_b32 v[2:3], v36 offset0:49 offset1:57
	ds_read2_b32 v[50:51], v36 offset0:115 offset1:123
	ds_read2_b32 v[52:53], v36 offset0:148 offset1:156
	ds_read2_b32 v[54:55], v36 offset0:214 offset1:222
	ds_read2_b32 v[58:59], v36 offset0:181 offset1:189
	ds_read2_b32 v[60:61], v36 offset0:247 offset1:255
	s_waitcnt lgkmcnt(7)
; #define LAS __attribute__((address_space(3)))
; __device__ __forceinline__ unsigned pk2(float lo, float hi) { return f2bf(lo) | (f2bf(hi) << 16); }
; #define LDS_WAVE_SYNC() asm volatile("s_waitcnt lgkmcnt(0)" ::: "memory")
; template <bool HASG>
; __device__ __forceinline__ void tr_item(const float* W, int K, int N, bf16* WT, int rowmode, const float* g, LAS float* scr, int item, int lane) {
;     ...
;     for (int j = 0; j < 4; ++j) { const int n = (lane >> 3) + 8 * j; const LAS float* s = scr + (8 * c) * 33 + n;
;         u32x4 o; o.x = pk2(s[0 * 33] * g0.x, s[1 * 33] * g0.y); o.y = pk2(s[2 * 33] * g0.z, s[3 * 33] * g0.w);
;         o.z = pk2(s[4 * 33] * g1.x, s[5 * 33] * g1.y); o.w = pk2(s[6 * 33] * g1.z, s[7 * 33] * g1.w);
;         *(u32x4*)(WT + (size_t)(drow0 + n) * K + k0 + 8 * c) = o; }
;     LDS_WAVE_SYNC();
	v_mov_b32_e32 v44, v40
	s_waitcnt lgkmcnt(5)
	v_mov_b32_e32 v46, v2
	s_waitcnt lgkmcnt(4)
	v_mov_b32_e32 v47, v50
	s_waitcnt lgkmcnt(3)
	v_mov_b32_e32 v62, v52
	s_waitcnt lgkmcnt(2)
	v_mov_b32_e32 v63, v54
	v_mov_b32_e32 v45, v48
	v_pk_mul_f32 v[46:47], v[4:5], v[46:47]
	v_pk_mul_f32 v[62:63], v[66:67], v[62:63]
	s_waitcnt lgkmcnt(1)
	v_mov_b32_e32 v64, v58
	s_waitcnt lgkmcnt(0)
	v_mov_b32_e32 v65, v60
	v_pk_mul_f32 v[44:45], v[56:57], v[44:45]
	v_pk_mul_f32 v[64:65], v[42:43], v[64:65]
	v_bfe_u32 v29, v47, 16, 1
	v_bfe_u32 v50, v63, 16, 1
	v_bfe_u32 v0, v65, 16, 1
	v_bfe_u32 v40, v46, 16, 1
	v_add3_u32 v29, v47, v29, s91
	v_bfe_u32 v47, v45, 16, 1
	v_add3_u32 v50, v63, v50, s91
	v_add3_u32 v40, v46, v40, s91
	v_add3_u32 v0, v65, v0, s91
	v_bfe_u32 v46, v44, 16, 1
	v_bfe_u32 v48, v62, 16, 1
	v_add3_u32 v45, v45, v47, s91
	v_lshrrev_b32_e32 v47, 16, v50
	v_bfe_u32 v2, v64, 16, 1
	v_add3_u32 v48, v62, v48, s91
	v_add3_u32 v44, v44, v46, s91
	v_and_or_b32 v47, v0, s35, v47
	v_or_b32_e32 v0, s28, v38
	v_add3_u32 v2, v64, v2, s91
	v_lshrrev_b32_e32 v44, 16, v44
	v_lshrrev_b32_e32 v45, 16, v45
	v_lshrrev_b32_e32 v46, 16, v48
	v_lshlrev_b32_e32 v0, 11, v0
	v_mov_b32_e32 v50, v3
	v_and_or_b32 v46, v2, s35, v46
	v_and_or_b32 v45, v29, s35, v45
	v_and_or_b32 v44, v40, s35, v44
	v_lshl_add_u64 v[62:63], v[30:31], 0, v[0:1]
	v_pk_mul_f32 v[2:3], v[4:5], v[50:51]
	v_mov_b32_e32 v54, v53
	global_store_dwordx4 v[62:63], v[44:47], off sc1
	v_pk_mul_f32 v[4:5], v[66:67], v[54:55]
	v_mov_b32_e32 v60, v59
	v_bfe_u32 v45, v2, 16, 1
	v_mov_b32_e32 v48, v41
	v_pk_mul_f32 v[42:43], v[42:43], v[60:61]
	v_add3_u32 v2, v2, v45, s91
	v_bfe_u32 v45, v5, 16, 1
	v_pk_mul_f32 v[40:41], v[56:57], v[48:49]
	v_bfe_u32 v0, v43, 16, 1
	v_bfe_u32 v29, v42, 16, 1
	v_bfe_u32 v44, v3, 16, 1
	v_add3_u32 v5, v5, v45, s91
	v_add3_u32 v3, v3, v44, s91
	v_add3_u32 v29, v42, v29, s91
	v_add3_u32 v0, v43, v0, s91
	v_bfe_u32 v42, v40, 16, 1
	v_bfe_u32 v43, v41, 16, 1
	v_bfe_u32 v44, v4, 16, 1
	v_lshrrev_b32_e32 v5, 16, v5
	v_add3_u32 v4, v4, v44, s91
	v_add3_u32 v41, v41, v43, s91
	v_add3_u32 v40, v40, v42, s91
	v_and_or_b32 v5, v0, s35, v5
	v_or_b32_e32 v0, s28, v39
	v_lshrrev_b32_e32 v40, 16, v40
	v_lshrrev_b32_e32 v41, 16, v41
	v_lshrrev_b32_e32 v4, 16, v4
	v_lshlrev_b32_e32 v0, 11, v0
	v_and_or_b32 v4, v29, s35, v4
	v_and_or_b32 v3, v3, s35, v41
	v_and_or_b32 v2, v2, s35, v40
	v_lshl_add_u64 v[30:31], v[30:31], 0, v[0:1]
	global_store_dwordx4 v[30:31], v[2:5], off sc1
	s_waitcnt lgkmcnt(0)

; template <bool HASG>
; __device__ __forceinline__ void tr_item(const float* W, int K, int N, bf16* WT, int rowmode, const float* g, LAS float* scr, int item, int lane) {
;     const int nblk = N / 32, kb = item / nblk, nb = item % nblk, k0 = 64 * kb, n0 = 32 * nb;
;     const float* wp = W + (size_t)(k0 + (lane >> 5)) * N + n0 + (lane & 31);
;     const int c = lane & 7;
;     float v[32];
; #pragma unroll
;     for (int i = 0; i < 32; ++i) v[i] = wp[(size_t)(2 * i) * N];
;     f32x4 g0 = (f32x4){1.f, 1.f, 1.f, 1.f}, g1 = g0;
;     if (HASG) { g0 = *(const f32x4*)(g + k0 + 8 * c); g1 = *(const f32x4*)(g + k0 + 8 * c + 4); }
;     asm volatile("" ::: "memory");
; #pragma unroll
;     for (int i = 0; i < 32; ++i) scr[(2 * i + (lane >> 5)) * 33 + (lane & 31)] = v[i];
; __device__ __forceinline__ void convert_items(const Args& a, LAS unsigned char* lds, int l, int it_lo, int it_hi, int gw, int NGW, int wave, int lane) {
;     ...
;         if (r < I_D) { tr_item<false>(a.in[4] + o_d, FF, D, wl + W_D1, 0, nullptr, scr, r, lane); continue; } r -= I_D;
.LBB0_501:
	s_andn2_b64 vcc, exec, s[28:29]
	s_cbranch_vccnz .LBB0_503
	s_add_i32 s28, s66, 0x2c00
	s_and_b32 s29, s28, 0x1ffc0
	s_lshl_b32 s28, s67, 5
	v_or_b32_e32 v0, s29, v33
	s_and_b32 s28, s28, 0x3e0
	v_lshlrev_b32_e32 v0, 12, v0
	v_lshl_add_u64 v[2:3], s[62:63], 0, v[0:1]
	s_lshl_b32 s88, s28, 2
	v_lshl_add_u64 v[2:3], v[2:3], 0, s[88:89]
	v_lshlrev_b32_e32 v0, 2, v6
	v_lshl_add_u64 v[2:3], v[2:3], 0, v[0:1]
	s_movk_i32 s4, 0x2000
	v_add_co_u32_e32 v4, vcc, s4, v2
	s_movk_i32 s4, 0x4000
	s_nop 0
	v_addc_co_u32_e32 v5, vcc, 0, v3, vcc
	global_load_dword v0, v[2:3], off
	global_load_dword v29, v[4:5], off
	v_add_co_u32_e32 v4, vcc, s4, v2
	s_movk_i32 s4, 0x6000
	s_nop 0
	v_addc_co_u32_e32 v5, vcc, 0, v3, vcc
	global_load_dword v30, v[4:5], off
	v_add_co_u32_e32 v4, vcc, s4, v2
	s_mov_b32 s4, 0x8000
	s_nop 0
	v_addc_co_u32_e32 v5, vcc, 0, v3, vcc
	global_load_dword v31, v[4:5], off
	v_add_co_u32_e32 v4, vcc, s4, v2
	s_mov_b32 s4, 0xa000
	s_nop 0
	v_addc_co_u32_e32 v5, vcc, 0, v3, vcc
	global_load_dword v40, v[4:5], off
	v_add_co_u32_e32 v4, vcc, s4, v2
	s_mov_b32 s4, 0xc000
	s_nop 0
	v_addc_co_u32_e32 v5, vcc, 0, v3, vcc
	global_load_dword v41, v[4:5], off
	v_add_co_u32_e32 v4, vcc, s4, v2
	s_mov_b32 s4, 0xe000
	s_nop 0
	v_addc_co_u32_e32 v5, vcc, 0, v3, vcc
	global_load_dword v42, v[4:5], off
	v_add_co_u32_e32 v4, vcc, s4, v2
	s_mov_b32 s4, 0x12000
	s_nop 0
	v_addc_co_u32_e32 v5, vcc, 0, v3, vcc
	global_load_dword v43, v[4:5], off
	v_add_co_u32_e32 v4, vcc, s70, v2
	s_lshl_b32 s88, s29, 1
	s_nop 0
	v_addc_co_u32_e32 v5, vcc, 0, v3, vcc
	global_load_dword v44, v[4:5], off
	v_add_co_u32_e32 v4, vcc, s4, v2
	s_mov_b32 s4, 0x14000
	s_nop 0
	v_addc_co_u32_e32 v5, vcc, 0, v3, vcc
	global_load_dword v45, v[4:5], off
	v_add_co_u32_e32 v4, vcc, s4, v2
	s_mov_b32 s4, 0x18000
	s_nop 0
	v_addc_co_u32_e32 v5, vcc, 0, v3, vcc
	global_load_dword v46, v[4:5], off
	v_add_co_u32_e32 v4, vcc, s71, v2
	s_nop 1
	v_addc_co_u32_e32 v5, vcc, 0, v3, vcc
	global_load_dword v47, v[4:5], off
	v_add_co_u32_e32 v4, vcc, s4, v2
	s_mov_b32 s4, 0x1a000
	s_nop 0
	v_addc_co_u32_e32 v5, vcc, 0, v3, vcc
	global_load_dword v48, v[4:5], off
	v_add_co_u32_e32 v4, vcc, s4, v2
	s_mov_b32 s4, 0x1c000
	s_nop 0
	v_addc_co_u32_e32 v5, vcc, 0, v3, vcc
	global_load_dword v49, v[4:5], off
	v_add_co_u32_e32 v4, vcc, s4, v2
	s_mov_b32 s4, 0x1e000
	s_nop 0
	v_addc_co_u32_e32 v5, vcc, 0, v3, vcc
	global_load_dword v50, v[4:5], off
	v_add_co_u32_e32 v4, vcc, s4, v2
	s_mov_b32 s4, 0x20000
	s_nop 0
	v_addc_co_u32_e32 v5, vcc, 0, v3, vcc
	global_load_dword v51, v[4:5], off
	v_add_co_u32_e32 v4, vcc, s4, v2
	s_mov_b32 s4, 0x22000
	s_nop 0
	v_addc_co_u32_e32 v5, vcc, 0, v3, vcc
	global_load_dword v52, v[4:5], off
	v_add_co_u32_e32 v4, vcc, s4, v2
	s_mov_b32 s4, 0x24000
	s_nop 0
	v_addc_co_u32_e32 v5, vcc, 0, v3, vcc
	global_load_dword v53, v[4:5], off
	v_add_co_u32_e32 v4, vcc, s4, v2
	s_mov_b32 s4, 0x26000
	s_nop 0
	v_addc_co_u32_e32 v5, vcc, 0, v3, vcc
	global_load_dword v54, v[4:5], off
	v_add_co_u32_e32 v4, vcc, s4, v2
	s_mov_b32 s4, 0x28000
	s_nop 0
	v_addc_co_u32_e32 v5, vcc, 0, v3, vcc
	global_load_dword v55, v[4:5], off
	v_add_co_u32_e32 v4, vcc, s4, v2
	s_mov_b32 s4, 0x2a000
	s_nop 0
	v_addc_co_u32_e32 v5, vcc, 0, v3, vcc
	global_load_dword v56, v[4:5], off
	v_add_co_u32_e32 v4, vcc, s4, v2
	s_mov_b32 s4, 0x2c000
	s_nop 0
	v_addc_co_u32_e32 v5, vcc, 0, v3, vcc
	global_load_dword v57, v[4:5], off
	v_add_co_u32_e32 v4, vcc, s4, v2
	s_mov_b32 s4, 0x2e000
	s_nop 0
	v_addc_co_u32_e32 v5, vcc, 0, v3, vcc
	global_load_dword v58, v[4:5], off
	v_add_co_u32_e32 v4, vcc, s4, v2
	s_mov_b32 s4, 0x30000
	s_nop 0
	v_addc_co_u32_e32 v5, vcc, 0, v3, vcc
	global_load_dword v59, v[4:5], off
	v_add_co_u32_e32 v4, vcc, s4, v2
	s_mov_b32 s4, 0x32000
	s_nop 0
	v_addc_co_u32_e32 v5, vcc, 0, v3, vcc
	global_load_dword v60, v[4:5], off
	v_add_co_u32_e32 v4, vcc, s4, v2
	s_mov_b32 s4, 0x34000
	s_nop 0
	v_addc_co_u32_e32 v5, vcc, 0, v3, vcc
	global_load_dword v61, v[4:5], off
	v_add_co_u32_e32 v4, vcc, s4, v2
	s_mov_b32 s4, 0x36000
	s_nop 0
	v_addc_co_u32_e32 v5, vcc, 0, v3, vcc
	global_load_dword v62, v[4:5], off
	v_add_co_u32_e32 v4, vcc, s4, v2
	s_mov_b32 s4, 0x38000
	s_nop 0
	v_addc_co_u32_e32 v5, vcc, 0, v3, vcc
	global_load_dword v63, v[4:5], off
	v_add_co_u32_e32 v4, vcc, s4, v2
	s_mov_b32 s4, 0x3a000
	s_nop 0
	v_addc_co_u32_e32 v5, vcc, 0, v3, vcc
	global_load_dword v64, v[4:5], off
	v_add_co_u32_e32 v4, vcc, s4, v2
	s_mov_b32 s4, 0x3c000
	s_nop 0
	v_addc_co_u32_e32 v5, vcc, 0, v3, vcc
	global_load_dword v65, v[4:5], off
	v_add_co_u32_e32 v4, vcc, s4, v2
	s_mov_b32 s4, 0x3e000
	s_nop 0
	v_addc_co_u32_e32 v5, vcc, 0, v3, vcc
	v_add_co_u32_e32 v2, vcc, s4, v2
	global_load_dword v4, v[4:5], off
	s_nop 0
	v_addc_co_u32_e32 v3, vcc, 0, v3, vcc
	global_load_dword v2, v[2:3], off
	s_waitcnt vmcnt(30)
	ds_write2_b32 v34, v0, v29 offset1:66
	s_waitcnt vmcnt(28)
	ds_write2_b32 v34, v30, v31 offset0:132 offset1:198
	v_add_u32_e32 v0, 0x400, v34
	s_waitcnt vmcnt(26)
	ds_write2_b32 v0, v40, v41 offset0:8 offset1:74
	s_waitcnt vmcnt(24)
	ds_write2_b32 v0, v42, v43 offset0:140 offset1:206
	v_add_u32_e32 v0, 0x800, v34
	s_waitcnt vmcnt(22)
	ds_write2_b32 v0, v44, v45 offset0:16 offset1:82
	s_waitcnt vmcnt(20)
	ds_write2_b32 v0, v46, v47 offset0:148 offset1:214
	v_add_u32_e32 v0, 0xc00, v34
	s_waitcnt vmcnt(18)
	ds_write2_b32 v0, v48, v49 offset0:24 offset1:90
	s_waitcnt vmcnt(16)
; #define LAS __attribute__((address_space(3)))
; __device__ __forceinline__ unsigned pk2(float lo, float hi) { return f2bf(lo) | (f2bf(hi) << 16); }
; #define LDS_WAVE_SYNC() asm volatile("s_waitcnt lgkmcnt(0)" ::: "memory")
; template <bool HASG>
; __device__ __forceinline__ void tr_item(const float* W, int K, int N, bf16* WT, int rowmode, const float* g, LAS float* scr, int item, int lane) {
;     ...
;     for (int i = 0; i < 32; ++i) scr[(2 * i + (lane >> 5)) * 33 + (lane & 31)] = v[i];
;     LDS_WAVE_SYNC();
;     const int drow0 = rowmode == 0 ? n0 : ((n0 >> 7) * 256 + (n0 & 127) + (rowmode == 2 ? 128 : 0));
; #pragma unroll
;     for (int j = 0; j < 4; ++j) { const int n = (lane >> 3) + 8 * j; const LAS float* s = scr + (8 * c) * 33 + n;
;         u32x4 o; o.x = pk2(s[0 * 33] * g0.x, s[1 * 33] * g0.y); o.y = pk2(s[2 * 33] * g0.z, s[3 * 33] * g0.w);
;         o.z = pk2(s[4 * 33] * g1.x, s[5 * 33] * g1.y); o.w = pk2(s[6 * 33] * g1.z, s[7 * 33] * g1.w);
;         *(u32x4*)(WT + (size_t)(drow0 + n) * K + k0 + 8 * c) = o; }
;     LDS_WAVE_SYNC();
	ds_write2_b32 v0, v50, v51 offset0:156 offset1:222
	v_add_u32_e32 v0, 0x1000, v34
	s_waitcnt vmcnt(14)
	ds_write2_b32 v0, v52, v53 offset0:32 offset1:98
	s_waitcnt vmcnt(12)
	ds_write2_b32 v0, v54, v55 offset0:164 offset1:230
	v_add_u32_e32 v0, 0x1400, v34
	s_waitcnt vmcnt(10)
	ds_write2_b32 v0, v56, v57 offset0:40 offset1:106
	s_waitcnt vmcnt(8)
	ds_write2_b32 v0, v58, v59 offset0:172 offset1:238
	v_add_u32_e32 v0, 0x1800, v34
	s_waitcnt vmcnt(6)
	ds_write2_b32 v0, v60, v61 offset0:48 offset1:114
	s_waitcnt vmcnt(4)
	ds_write2_b32 v0, v62, v63 offset0:180 offset1:246
	v_add_u32_e32 v0, 0x1c00, v34
	s_waitcnt vmcnt(2)
	ds_write2_b32 v0, v64, v65 offset0:56 offset1:122
	s_waitcnt vmcnt(0)
	ds_write2_b32 v0, v4, v2 offset0:188 offset1:254
	s_waitcnt lgkmcnt(0)
	ds_read2_b32 v[4:5], v36 offset0:33 offset1:41
	ds_read2_b32 v[30:31], v36 offset1:8
	ds_read2_b32 v[44:45], v36 offset0:66 offset1:74
	ds_read2_b32 v[46:47], v36 offset0:99 offset1:107
	ds_read2_b32 v[48:49], v36 offset0:132 offset1:140
	ds_read2_b32 v[50:51], v36 offset0:165 offset1:173
	ds_read2_b32 v[52:53], v36 offset0:198 offset1:206
	ds_read2_b32 v[54:55], v36 offset0:231 offset1:239
	s_waitcnt lgkmcnt(7)
	v_bfe_u32 v29, v4, 16, 1
	s_waitcnt lgkmcnt(6)
	v_bfe_u32 v0, v30, 16, 1
	v_add3_u32 v0, v30, v0, s91
	v_lshrrev_b32_e32 v0, 16, v0
	v_add3_u32 v4, v4, v29, s91
	v_and_or_b32 v40, v4, s35, v0
	s_waitcnt lgkmcnt(5)
	v_bfe_u32 v0, v44, 16, 1
	v_add3_u32 v0, v44, v0, s91
	s_waitcnt lgkmcnt(4)
	v_bfe_u32 v4, v46, 16, 1
	v_lshrrev_b32_e32 v0, 16, v0
	v_add3_u32 v4, v46, v4, s91
	v_and_or_b32 v41, v4, s35, v0
	s_waitcnt lgkmcnt(3)
	v_bfe_u32 v0, v48, 16, 1
	v_add3_u32 v0, v48, v0, s91
	s_waitcnt lgkmcnt(2)
	v_bfe_u32 v4, v50, 16, 1
	v_lshrrev_b32_e32 v0, 16, v0
	v_add3_u32 v4, v50, v4, s91
	v_and_or_b32 v42, v4, s35, v0
	s_waitcnt lgkmcnt(1)
	v_bfe_u32 v0, v52, 16, 1
	v_add3_u32 v0, v52, v0, s91
	s_waitcnt lgkmcnt(0)
	v_bfe_u32 v4, v54, 16, 1
	v_lshrrev_b32_e32 v0, 16, v0
	v_add3_u32 v4, v54, v4, s91
	v_and_or_b32 v43, v4, s35, v0
	v_or_b32_e32 v0, s28, v35
	v_mul_u32_u24_e32 v0, 0xb00, v0
	v_lshl_add_u64 v[2:3], v[20:21], 0, s[88:89]
	v_lshlrev_b32_e32 v0, 1, v0
	v_lshl_add_u64 v[56:57], v[2:3], 0, v[0:1]
	v_bfe_u32 v0, v31, 16, 1
	v_add3_u32 v0, v31, v0, s91
	v_bfe_u32 v4, v5, 16, 1
	v_lshrrev_b32_e32 v0, 16, v0
	v_add3_u32 v4, v5, v4, s91
	global_store_dwordx4 v[56:57], v[40:43], off sc1
	s_nop 1
	v_and_or_b32 v40, v4, s35, v0
	v_bfe_u32 v0, v45, 16, 1
	v_add3_u32 v0, v45, v0, s91
	v_bfe_u32 v4, v47, 16, 1
	v_lshrrev_b32_e32 v0, 16, v0
	v_add3_u32 v4, v47, v4, s91
	v_and_or_b32 v41, v4, s35, v0
	v_bfe_u32 v0, v49, 16, 1
	v_add3_u32 v0, v49, v0, s91
	v_bfe_u32 v4, v51, 16, 1
	v_lshrrev_b32_e32 v0, 16, v0
	v_add3_u32 v4, v51, v4, s91
	v_and_or_b32 v42, v4, s35, v0
	v_bfe_u32 v0, v53, 16, 1
	v_add3_u32 v0, v53, v0, s91
	v_bfe_u32 v4, v55, 16, 1
	v_lshrrev_b32_e32 v0, 16, v0
	v_add3_u32 v4, v55, v4, s91
	v_and_or_b32 v43, v4, s35, v0
	v_or_b32_e32 v0, s28, v37
	v_mul_u32_u24_e32 v0, 0xb00, v0
	v_lshlrev_b32_e32 v0, 1, v0
	v_lshl_add_u64 v[4:5], v[2:3], 0, v[0:1]
	global_store_dwordx4 v[4:5], v[40:43], off sc1
	ds_read2_b32 v[4:5], v36 offset0:16 offset1:24
	ds_read2_b32 v[30:31], v36 offset0:49 offset1:57
	ds_read2_b32 v[44:45], v36 offset0:82 offset1:90
	ds_read2_b32 v[46:47], v36 offset0:115 offset1:123
	ds_read2_b32 v[48:49], v36 offset0:148 offset1:156
	ds_read2_b32 v[50:51], v36 offset0:181 offset1:189
	ds_read2_b32 v[52:53], v36 offset0:214 offset1:222
	ds_read2_b32 v[54:55], v36 offset0:247 offset1:255
	s_waitcnt lgkmcnt(7)
	v_bfe_u32 v0, v4, 16, 1
	v_add3_u32 v0, v4, v0, s91
	s_waitcnt lgkmcnt(6)
	v_bfe_u32 v4, v30, 16, 1
	v_lshrrev_b32_e32 v0, 16, v0
	v_add3_u32 v4, v30, v4, s91
	v_and_or_b32 v40, v4, s35, v0
	s_waitcnt lgkmcnt(5)
	v_bfe_u32 v0, v44, 16, 1
	v_add3_u32 v0, v44, v0, s91
	s_waitcnt lgkmcnt(4)
	v_bfe_u32 v4, v46, 16, 1
	v_lshrrev_b32_e32 v0, 16, v0
	v_add3_u32 v4, v46, v4, s91
	v_and_or_b32 v41, v4, s35, v0
	s_waitcnt lgkmcnt(3)
	v_bfe_u32 v0, v48, 16, 1
	v_add3_u32 v0, v48, v0, s91
	s_waitcnt lgkmcnt(2)
	v_bfe_u32 v4, v50, 16, 1
	v_lshrrev_b32_e32 v0, 16, v0
	v_add3_u32 v4, v50, v4, s91
	v_and_or_b32 v42, v4, s35, v0
	s_waitcnt lgkmcnt(1)
	v_bfe_u32 v0, v52, 16, 1
	v_add3_u32 v0, v52, v0, s91
	s_waitcnt lgkmcnt(0)
	v_bfe_u32 v4, v54, 16, 1
	v_lshrrev_b32_e32 v0, 16, v0
	v_add3_u32 v4, v54, v4, s91
	v_and_or_b32 v43, v4, s35, v0
	v_or_b32_e32 v0, s28, v38
	v_mul_u32_u24_e32 v0, 0xb00, v0
	v_lshlrev_b32_e32 v0, 1, v0
	v_lshl_add_u64 v[56:57], v[2:3], 0, v[0:1]
	v_bfe_u32 v0, v5, 16, 1
	v_add3_u32 v0, v5, v0, s91
	v_bfe_u32 v4, v31, 16, 1
	v_lshrrev_b32_e32 v0, 16, v0
	v_add3_u32 v4, v31, v4, s91
	global_store_dwordx4 v[56:57], v[40:43], off sc1
	s_nop 1
	v_and_or_b32 v40, v4, s35, v0
	v_bfe_u32 v0, v45, 16, 1
	v_add3_u32 v0, v45, v0, s91
	v_bfe_u32 v4, v47, 16, 1
	v_lshrrev_b32_e32 v0, 16, v0
	v_add3_u32 v4, v47, v4, s91
	v_and_or_b32 v41, v4, s35, v0
	v_bfe_u32 v0, v49, 16, 1
	v_add3_u32 v0, v49, v0, s91
	v_bfe_u32 v4, v51, 16, 1
	v_lshrrev_b32_e32 v0, 16, v0
	v_add3_u32 v4, v51, v4, s91
	v_and_or_b32 v42, v4, s35, v0
	v_bfe_u32 v0, v53, 16, 1
	v_add3_u32 v0, v53, v0, s91
	v_bfe_u32 v4, v55, 16, 1
	v_lshrrev_b32_e32 v0, 16, v0
	v_add3_u32 v4, v55, v4, s91
	v_and_or_b32 v43, v4, s35, v0
	v_or_b32_e32 v0, s28, v39
	v_mul_u32_u24_e32 v0, 0xb00, v0
	v_lshlrev_b32_e32 v0, 1, v0
	v_lshl_add_u64 v[2:3], v[2:3], 0, v[0:1]
	global_store_dwordx4 v[2:3], v[40:43], off sc1
	s_waitcnt lgkmcnt(0)

; template <bool HASG>
; __device__ __forceinline__ void tr_item(const float* W, int K, int N, bf16* WT, int rowmode, const float* g, LAS float* scr, int item, int lane) {
;     const int nblk = N / 32, kb = item / nblk, nb = item % nblk, k0 = 64 * kb, n0 = 32 * nb;
;     const float* wp = W + (size_t)(k0 + (lane >> 5)) * N + n0 + (lane & 31);
;     const int c = lane & 7;
;     float v[32];
; #pragma unroll
;     for (int i = 0; i < 32; ++i) v[i] = wp[(size_t)(2 * i) * N];
;     f32x4 g0 = (f32x4){1.f, 1.f, 1.f, 1.f}, g1 = g0;
;     if (HASG) { g0 = *(const f32x4*)(g + k0 + 8 * c); g1 = *(const f32x4*)(g + k0 + 8 * c + 4); }
; __device__ __forceinline__ void convert_items(const Args& a, LAS unsigned char* lds, int l, int it_lo, int it_hi, int gw, int NGW, int wave, int lane) {
;     ...
;         if (r < I_G) { tr_item<true>(a.in[3] + o_gu, D, FF, wl + W_GU1, 2, a.in[1] + l * D, scr, r, lane); continue; } r -= I_G;
.LBB0_504:
	s_andn2_b64 vcc, exec, s[28:29]
	s_cbranch_vccnz .LBB0_506
	s_add_i32 s28, s67, 0xfa80
	s_and_b32 s29, s28, 0xffff
	s_mul_i32 s29, s29, 0xba2f
	s_lshr_b32 s47, s29, 16
	s_lshr_b32 s29, s29, 22
	s_mulk_i32 s29, 0x58
	s_sub_i32 s28, s28, s29
	s_and_b32 s29, s47, 0xffc0
	v_or_b32_e32 v0, s29, v33
	v_mul_u32_u24_e32 v0, 0xb00, v0
	s_and_b32 s60, s28, 0xffff
	v_lshlrev_b32_e32 v0, 2, v0
	v_lshl_add_u64 v[2:3], s[0:1], 0, v[0:1]
	s_lshl_b32 s88, s60, 7
	v_lshl_add_u64 v[2:3], v[2:3], 0, s[88:89]
	v_lshlrev_b32_e32 v0, 2, v6
	v_lshl_add_u64 v[2:3], v[2:3], 0, v[0:1]
	s_movk_i32 s4, 0x5000
	v_add_co_u32_e32 v4, vcc, s4, v2
	s_mov_b32 s4, 0x1b000
	s_nop 0
	v_addc_co_u32_e32 v5, vcc, 0, v3, vcc
	v_add_co_u32_e32 v30, vcc, s90, v2
	s_lshl_b32 s88, s29, 2
	s_nop 0
	v_addc_co_u32_e32 v31, vcc, 0, v3, vcc
	v_add_co_u32_e32 v40, vcc, s70, v2
	s_lshl_b32 s47, s28, 5
	s_nop 0
	v_addc_co_u32_e32 v41, vcc, 0, v3, vcc
	v_add_co_u32_e32 v42, vcc, s71, v2
	s_lshl_b32 s28, s28, 6
	s_nop 0
	v_addc_co_u32_e32 v43, vcc, 0, v3, vcc
	v_add_co_u32_e32 v44, vcc, s4, v2
	s_mov_b32 s4, 0x21000
	s_nop 0
	v_addc_co_u32_e32 v45, vcc, 0, v3, vcc
	v_add_co_u32_e32 v46, vcc, s4, v2
	s_mov_b32 s4, 0x26000
	s_nop 0
	v_addc_co_u32_e32 v47, vcc, 0, v3, vcc
	v_add_co_u32_e32 v48, vcc, s4, v2
	s_mov_b32 s4, 0x2c000
	s_nop 0
	v_addc_co_u32_e32 v49, vcc, 0, v3, vcc
	global_load_dword v0, v[2:3], off
	global_load_dword v29, v[4:5], off offset:2048
	global_load_dword v52, v[30:31], off
	global_load_dword v53, v[40:41], off offset:2048
	global_load_dword v54, v[42:43], off
	global_load_dword v55, v[44:45], off offset:2048
	global_load_dword v56, v[46:47], off
	global_load_dword v57, v[48:49], off offset:2048
	v_add_co_u32_e32 v4, vcc, s4, v2
	s_mov_b32 s4, 0x31000
	s_nop 0
	v_addc_co_u32_e32 v5, vcc, 0, v3, vcc
	v_add_co_u32_e32 v30, vcc, s4, v2
	s_mov_b32 s4, 0x37000
	s_nop 0
	v_addc_co_u32_e32 v31, vcc, 0, v3, vcc
	v_add_co_u32_e32 v40, vcc, s4, v2
	s_mov_b32 s4, 0x3c000
	s_nop 0
	v_addc_co_u32_e32 v41, vcc, 0, v3, vcc
	v_add_co_u32_e32 v42, vcc, s4, v2
	s_mov_b32 s4, 0x42000
	s_nop 0
	v_addc_co_u32_e32 v43, vcc, 0, v3, vcc
	v_add_co_u32_e32 v44, vcc, s4, v2
	s_mov_b32 s4, 0x47000
	s_nop 0
	v_addc_co_u32_e32 v45, vcc, 0, v3, vcc
	v_add_co_u32_e32 v46, vcc, s4, v2
	s_mov_b32 s4, 0x4d000
	s_nop 0
	v_addc_co_u32_e32 v47, vcc, 0, v3, vcc
	v_add_co_u32_e32 v48, vcc, s4, v2
	s_mov_b32 s4, 0x52000
	s_nop 0
	v_addc_co_u32_e32 v49, vcc, 0, v3, vcc
	v_add_co_u32_e32 v50, vcc, s4, v2
	s_mov_b32 s4, 0x58000
	s_nop 0
	v_addc_co_u32_e32 v51, vcc, 0, v3, vcc
	global_load_dword v58, v[4:5], off
	global_load_dword v59, v[30:31], off offset:2048
	global_load_dword v60, v[40:41], off
	global_load_dword v61, v[42:43], off offset:2048
	global_load_dword v62, v[44:45], off
	global_load_dword v63, v[46:47], off offset:2048
	global_load_dword v64, v[48:49], off
	global_load_dword v65, v[50:51], off offset:2048
	v_add_co_u32_e32 v4, vcc, s4, v2
	s_mov_b32 s4, 0x5d000
	s_nop 0
	v_addc_co_u32_e32 v5, vcc, 0, v3, vcc
	v_add_co_u32_e32 v30, vcc, s4, v2
	s_mov_b32 s4, 0x63000
	s_nop 0
	v_addc_co_u32_e32 v31, vcc, 0, v3, vcc
	v_add_co_u32_e32 v40, vcc, s4, v2
	s_mov_b32 s4, 0x68000
	s_nop 0
	v_addc_co_u32_e32 v41, vcc, 0, v3, vcc
	v_add_co_u32_e32 v42, vcc, s4, v2
	s_mov_b32 s4, 0x6e000
	s_nop 0
	v_addc_co_u32_e32 v43, vcc, 0, v3, vcc
	v_add_co_u32_e32 v44, vcc, s4, v2
	s_mov_b32 s4, 0x73000
	s_nop 0
	v_addc_co_u32_e32 v45, vcc, 0, v3, vcc
	v_add_co_u32_e32 v46, vcc, s4, v2
	s_mov_b32 s4, 0x79000
	s_nop 0
	v_addc_co_u32_e32 v47, vcc, 0, v3, vcc
	v_add_co_u32_e32 v48, vcc, s4, v2
	s_mov_b32 s4, 0x7e000
	s_nop 0
	v_addc_co_u32_e32 v49, vcc, 0, v3, vcc
	v_add_co_u32_e32 v50, vcc, s4, v2
	s_mov_b32 s4, 0x84000
	s_nop 0
	v_addc_co_u32_e32 v51, vcc, 0, v3, vcc
	global_load_dword v66, v[4:5], off
	global_load_dword v67, v[30:31], off offset:2048
	global_load_dword v68, v[40:41], off
	global_load_dword v69, v[42:43], off offset:2048
	global_load_dword v70, v[44:45], off
	global_load_dword v71, v[46:47], off offset:2048
	global_load_dword v72, v[48:49], off
	s_nop 0
	global_load_dword v50, v[50:51], off offset:2048
	v_add_co_u32_e32 v4, vcc, s4, v2
	s_mov_b32 s4, 0x89000
	s_nop 0
	v_addc_co_u32_e32 v5, vcc, 0, v3, vcc
	v_add_co_u32_e32 v30, vcc, s4, v2
	s_mov_b32 s4, 0x8f000
	s_nop 0
	v_addc_co_u32_e32 v31, vcc, 0, v3, vcc
	v_add_co_u32_e32 v40, vcc, s4, v2
	s_mov_b32 s4, 0x94000
	s_nop 0
	v_addc_co_u32_e32 v41, vcc, 0, v3, vcc
	v_add_co_u32_e32 v42, vcc, s4, v2
	s_mov_b32 s4, 0x9a000
	s_nop 0
	v_addc_co_u32_e32 v43, vcc, 0, v3, vcc
	v_add_co_u32_e32 v44, vcc, s4, v2
	s_mov_b32 s4, 0x9f000
	s_nop 0
	v_addc_co_u32_e32 v45, vcc, 0, v3, vcc
	v_add_co_u32_e32 v46, vcc, s4, v2
	s_mov_b32 s4, 0xa5000
	s_nop 0
	v_addc_co_u32_e32 v47, vcc, 0, v3, vcc
	v_add_co_u32_e32 v48, vcc, s4, v2
	s_mov_b32 s4, 0xaa000
	s_nop 0
	v_addc_co_u32_e32 v49, vcc, 0, v3, vcc
	v_add_co_u32_e32 v2, vcc, s4, v2
	s_and_b32 s28, s28, 0x1f00
	s_nop 0
	v_addc_co_u32_e32 v3, vcc, 0, v3, vcc
	global_load_dword v51, v[4:5], off
	s_nop 0
	global_load_dword v30, v[30:31], off offset:2048
	s_nop 0
	global_load_dword v31, v[40:41], off
	global_load_dword v73, v[42:43], off offset:2048
	s_nop 0
	global_load_dword v44, v[44:45], off
	s_nop 0
	global_load_dword v45, v[46:47], off offset:2048
	s_nop 0
	global_load_dword v46, v[48:49], off
	global_load_dword v47, v[2:3], off offset:2048
	v_lshl_add_u64 v[2:3], v[26:27], 0, s[88:89]
	global_load_dwordx4 v[40:43], v[2:3], off
	s_nop 0
	global_load_dwordx4 v[2:5], v[2:3], off offset:16
	s_waitcnt vmcnt(32)
	ds_write2_b32 v34, v0, v29 offset1:66
	s_waitcnt vmcnt(30)
; #define LAS __attribute__((address_space(3)))
; __device__ __forceinline__ unsigned pk2(float lo, float hi) { return f2bf(lo) | (f2bf(hi) << 16); }
; #define LDS_WAVE_SYNC() asm volatile("s_waitcnt lgkmcnt(0)" ::: "memory")
; template <bool HASG>
; __device__ __forceinline__ void tr_item(const float* W, int K, int N, bf16* WT, int rowmode, const float* g, LAS float* scr, int item, int lane) {
;     ...
;     for (int i = 0; i < 32; ++i) scr[(2 * i + (lane >> 5)) * 33 + (lane & 31)] = v[i];
;     LDS_WAVE_SYNC();
;     const int drow0 = rowmode == 0 ? n0 : ((n0 >> 7) * 256 + (n0 & 127) + (rowmode == 2 ? 128 : 0));
; #pragma unroll
;     for (int j = 0; j < 4; ++j) { const int n = (lane >> 3) + 8 * j; const LAS float* s = scr + (8 * c) * 33 + n;
;         u32x4 o; o.x = pk2(s[0 * 33] * g0.x, s[1 * 33] * g0.y); o.y = pk2(s[2 * 33] * g0.z, s[3 * 33] * g0.w);
;         o.z = pk2(s[4 * 33] * g1.x, s[5 * 33] * g1.y); o.w = pk2(s[6 * 33] * g1.z, s[7 * 33] * g1.w);
;         *(u32x4*)(WT + (size_t)(drow0 + n) * K + k0 + 8 * c) = o; }
	ds_write2_b32 v34, v52, v53 offset0:132 offset1:198
	v_add_u32_e32 v0, 0x400, v34
	s_waitcnt vmcnt(28)
	ds_write2_b32 v0, v54, v55 offset0:8 offset1:74
	s_waitcnt vmcnt(26)
	ds_write2_b32 v0, v56, v57 offset0:140 offset1:206
	v_add_u32_e32 v0, 0x800, v34
	s_waitcnt vmcnt(24)
	ds_write2_b32 v0, v58, v59 offset0:16 offset1:82
	s_waitcnt vmcnt(22)
	ds_write2_b32 v0, v60, v61 offset0:148 offset1:214
	v_add_u32_e32 v0, 0xc00, v34
	s_waitcnt vmcnt(20)
	ds_write2_b32 v0, v62, v63 offset0:24 offset1:90
	s_waitcnt vmcnt(18)
	ds_write2_b32 v0, v64, v65 offset0:156 offset1:222
	v_add_u32_e32 v0, 0x1000, v34
	s_waitcnt vmcnt(16)
	ds_write2_b32 v0, v66, v67 offset0:32 offset1:98
	s_waitcnt vmcnt(14)
	ds_write2_b32 v0, v68, v69 offset0:164 offset1:230
	v_add_u32_e32 v0, 0x1400, v34
	s_waitcnt vmcnt(12)
	ds_write2_b32 v0, v70, v71 offset0:40 offset1:106
	s_waitcnt vmcnt(10)
	ds_write2_b32 v0, v72, v50 offset0:172 offset1:238
	v_add_u32_e32 v0, 0x1800, v34
	s_waitcnt vmcnt(8)
	ds_write2_b32 v0, v51, v30 offset0:48 offset1:114
	s_waitcnt vmcnt(6)
	ds_write2_b32 v0, v31, v73 offset0:180 offset1:246
	v_add_u32_e32 v0, 0x1c00, v34
	s_waitcnt vmcnt(4)
	ds_write2_b32 v0, v44, v45 offset0:56 offset1:122
	s_waitcnt vmcnt(2)
	ds_write2_b32 v0, v46, v47 offset0:188 offset1:254
	s_waitcnt lgkmcnt(0)
	ds_read2_b32 v[48:49], v36 offset0:33 offset1:41
	ds_read2_b32 v[50:51], v36 offset1:8
	ds_read2_b32 v[52:53], v36 offset0:66 offset1:74
	ds_read2_b32 v[54:55], v36 offset0:99 offset1:107
	ds_read2_b32 v[58:59], v36 offset0:132 offset1:140
	ds_read2_b32 v[60:61], v36 offset0:165 offset1:173
	ds_read2_b32 v[62:63], v36 offset0:198 offset1:206
	ds_read2_b32 v[64:65], v36 offset0:231 offset1:239
	s_waitcnt vmcnt(1)
	v_mov_b32_e32 v56, v40
	v_mov_b32_e32 v57, v42
	v_mov_b32_e32 v42, v41
	s_waitcnt lgkmcnt(7)
	v_mov_b32_e32 v40, v48
	s_waitcnt lgkmcnt(4)
	v_mov_b32_e32 v41, v54
	v_pk_mul_f32 v[40:41], v[42:43], v[40:41]
	s_waitcnt vmcnt(0)
	v_mov_b32_e32 v66, v2
	v_mov_b32_e32 v67, v4
	s_waitcnt lgkmcnt(3)
	v_mov_b32_e32 v46, v58
	s_waitcnt lgkmcnt(1)
	v_mov_b32_e32 v47, v62
	v_mov_b32_e32 v4, v3
	v_mov_b32_e32 v2, v60
	s_waitcnt lgkmcnt(0)
	v_mov_b32_e32 v3, v64
	v_mov_b32_e32 v44, v50
	v_mov_b32_e32 v45, v52
	v_pk_mul_f32 v[46:47], v[66:67], v[46:47]
	v_pk_mul_f32 v[2:3], v[4:5], v[2:3]
	v_bfe_u32 v50, v40, 16, 1
	s_and_b32 s47, s47, 0x60
	v_pk_mul_f32 v[44:45], v[56:57], v[44:45]
	v_bfe_u32 v29, v2, 16, 1
	v_add3_u32 v40, v40, v50, s91
	v_bfe_u32 v50, v47, 16, 1
	s_or_b32 s28, s47, s28
	v_bfe_u32 v0, v3, 16, 1
	v_bfe_u32 v48, v41, 16, 1
	v_add3_u32 v2, v2, v29, s91
	v_bfe_u32 v29, v45, 16, 1
	v_add3_u32 v47, v47, v50, s91
	s_bitset1_b32 s28, 7
	v_add3_u32 v41, v41, v48, s91
	v_add3_u32 v0, v3, v0, s91
	v_bfe_u32 v3, v44, 16, 1
	v_bfe_u32 v48, v46, 16, 1
	v_add3_u32 v29, v45, v29, s91
	v_lshrrev_b32_e32 v45, 16, v47
	s_lshl_b32 s88, s29, 1
	v_add3_u32 v46, v46, v48, s91
	v_add3_u32 v3, v44, v3, s91
	v_and_or_b32 v47, v0, s35, v45
	v_or_b32_e32 v0, s28, v35
	v_lshl_add_u64 v[30:31], v[8:9], 0, s[88:89]
	v_lshrrev_b32_e32 v3, 16, v3
	v_lshrrev_b32_e32 v29, 16, v29
	v_lshrrev_b32_e32 v44, 16, v46
	v_lshlrev_b32_e32 v0, 11, v0
	v_mov_b32_e32 v54, v49
	v_and_or_b32 v46, v2, s35, v44
	v_and_or_b32 v45, v41, s35, v29
	v_and_or_b32 v44, v40, s35, v3
	v_lshl_add_u64 v[2:3], v[30:31], 0, v[0:1]
	v_pk_mul_f32 v[40:41], v[42:43], v[54:55]
	v_mov_b32_e32 v62, v59
	global_store_dwordx4 v[2:3], v[44:47], off sc1
	v_mov_b32_e32 v64, v61
	v_bfe_u32 v49, v40, 16, 1
	v_pk_mul_f32 v[44:45], v[66:67], v[62:63]
	v_mov_b32_e32 v52, v51
	v_pk_mul_f32 v[46:47], v[4:5], v[64:65]
	v_add3_u32 v40, v40, v49, s91
	v_bfe_u32 v49, v45, 16, 1
	v_pk_mul_f32 v[2:3], v[56:57], v[52:53]
	v_bfe_u32 v0, v47, 16, 1
	v_bfe_u32 v29, v46, 16, 1
	v_bfe_u32 v48, v41, 16, 1
	v_add3_u32 v45, v45, v49, s91
	v_add3_u32 v41, v41, v48, s91
	v_add3_u32 v29, v46, v29, s91
	v_add3_u32 v0, v47, v0, s91
	v_bfe_u32 v46, v2, 16, 1
	v_bfe_u32 v47, v3, 16, 1
	v_bfe_u32 v48, v44, 16, 1
	v_lshrrev_b32_e32 v45, 16, v45
	v_add3_u32 v44, v44, v48, s91
	v_add3_u32 v3, v3, v47, s91
	v_add3_u32 v2, v2, v46, s91
	v_and_or_b32 v47, v0, s35, v45
	v_or_b32_e32 v0, s28, v37
	v_lshrrev_b32_e32 v2, 16, v2
	v_lshrrev_b32_e32 v3, 16, v3
	v_lshrrev_b32_e32 v44, 16, v44
	v_lshlrev_b32_e32 v0, 11, v0
	v_and_or_b32 v46, v29, s35, v44
	v_and_or_b32 v45, v41, s35, v3
	v_and_or_b32 v44, v40, s35, v2
	v_lshl_add_u64 v[2:3], v[30:31], 0, v[0:1]
	ds_read2_b32 v[40:41], v36 offset0:16 offset1:24
	ds_read2_b32 v[48:49], v36 offset0:82 offset1:90
	global_store_dwordx4 v[2:3], v[44:47], off sc1
	ds_read2_b32 v[2:3], v36 offset0:49 offset1:57
	ds_read2_b32 v[50:51], v36 offset0:115 offset1:123
	ds_read2_b32 v[52:53], v36 offset0:148 offset1:156
	ds_read2_b32 v[54:55], v36 offset0:214 offset1:222
	ds_read2_b32 v[58:59], v36 offset0:181 offset1:189
	ds_read2_b32 v[60:61], v36 offset0:247 offset1:255
	s_waitcnt lgkmcnt(7)
; #define LAS __attribute__((address_space(3)))
; __device__ __forceinline__ unsigned pk2(float lo, float hi) { return f2bf(lo) | (f2bf(hi) << 16); }
; #define LDS_WAVE_SYNC() asm volatile("s_waitcnt lgkmcnt(0)" ::: "memory")
; template <bool HASG>
; __device__ __forceinline__ void tr_item(const float* W, int K, int N, bf16* WT, int rowmode, const float* g, LAS float* scr, int item, int lane) {
;     ...
;     for (int j = 0; j < 4; ++j) { const int n = (lane >> 3) + 8 * j; const LAS float* s = scr + (8 * c) * 33 + n;
;         u32x4 o; o.x = pk2(s[0 * 33] * g0.x, s[1 * 33] * g0.y); o.y = pk2(s[2 * 33] * g0.z, s[3 * 33] * g0.w);
;         o.z = pk2(s[4 * 33] * g1.x, s[5 * 33] * g1.y); o.w = pk2(s[6 * 33] * g1.z, s[7 * 33] * g1.w);
;         *(u32x4*)(WT + (size_t)(drow0 + n) * K + k0 + 8 * c) = o; }
;     LDS_WAVE_SYNC();
	v_mov_b32_e32 v44, v40
	s_waitcnt lgkmcnt(5)
	v_mov_b32_e32 v46, v2
	s_waitcnt lgkmcnt(4)
	v_mov_b32_e32 v47, v50
	s_waitcnt lgkmcnt(3)
	v_mov_b32_e32 v62, v52
	s_waitcnt lgkmcnt(2)
	v_mov_b32_e32 v63, v54
	v_mov_b32_e32 v45, v48
	v_pk_mul_f32 v[46:47], v[42:43], v[46:47]
	v_pk_mul_f32 v[62:63], v[66:67], v[62:63]
	s_waitcnt lgkmcnt(1)
	v_mov_b32_e32 v64, v58
	s_waitcnt lgkmcnt(0)
	v_mov_b32_e32 v65, v60
	v_pk_mul_f32 v[44:45], v[56:57], v[44:45]
	v_pk_mul_f32 v[64:65], v[4:5], v[64:65]
	v_bfe_u32 v29, v47, 16, 1
	v_bfe_u32 v50, v63, 16, 1
	v_bfe_u32 v0, v65, 16, 1
	v_bfe_u32 v40, v46, 16, 1
	v_add3_u32 v29, v47, v29, s91
	v_bfe_u32 v47, v45, 16, 1
	v_add3_u32 v50, v63, v50, s91
	v_add3_u32 v40, v46, v40, s91
	v_add3_u32 v0, v65, v0, s91
	v_bfe_u32 v46, v44, 16, 1
	v_bfe_u32 v48, v62, 16, 1
	v_add3_u32 v45, v45, v47, s91
	v_lshrrev_b32_e32 v47, 16, v50
	v_bfe_u32 v2, v64, 16, 1
	v_add3_u32 v48, v62, v48, s91
	v_add3_u32 v44, v44, v46, s91
	v_and_or_b32 v47, v0, s35, v47
	v_or_b32_e32 v0, s28, v38
	v_add3_u32 v2, v64, v2, s91
	v_lshrrev_b32_e32 v44, 16, v44
	v_lshrrev_b32_e32 v45, 16, v45
	v_lshrrev_b32_e32 v46, 16, v48
	v_lshlrev_b32_e32 v0, 11, v0
	v_mov_b32_e32 v50, v3
	v_mov_b32_e32 v60, v59
	v_and_or_b32 v46, v2, s35, v46
	v_and_or_b32 v45, v29, s35, v45
	v_and_or_b32 v44, v40, s35, v44
	v_lshl_add_u64 v[62:63], v[30:31], 0, v[0:1]
	v_mov_b32_e32 v48, v41
	v_pk_mul_f32 v[2:3], v[42:43], v[50:51]
	v_mov_b32_e32 v54, v53
	v_pk_mul_f32 v[4:5], v[4:5], v[60:61]
	global_store_dwordx4 v[62:63], v[44:47], off sc1
	v_pk_mul_f32 v[40:41], v[56:57], v[48:49]
	v_pk_mul_f32 v[42:43], v[66:67], v[54:55]
	v_bfe_u32 v0, v5, 16, 1
	v_bfe_u32 v45, v2, 16, 1
	v_add3_u32 v2, v2, v45, s91
	v_add3_u32 v0, v5, v0, s91
	v_bfe_u32 v5, v40, 16, 1
	v_bfe_u32 v45, v43, 16, 1
	v_bfe_u32 v29, v4, 16, 1
	v_bfe_u32 v44, v3, 16, 1
	v_add3_u32 v43, v43, v45, s91
	v_add3_u32 v5, v40, v5, s91
	v_add3_u32 v3, v3, v44, s91
	v_add3_u32 v4, v4, v29, s91
	v_bfe_u32 v29, v41, 16, 1
	v_bfe_u32 v44, v42, 16, 1
	v_lshrrev_b32_e32 v40, 16, v5
	v_lshrrev_b32_e32 v5, 16, v43
	v_add3_u32 v42, v42, v44, s91
	v_add3_u32 v29, v41, v29, s91
	v_and_or_b32 v5, v0, s35, v5
	v_or_b32_e32 v0, s28, v39
	v_lshrrev_b32_e32 v29, 16, v29
	v_lshrrev_b32_e32 v41, 16, v42
	v_lshlrev_b32_e32 v0, 11, v0
	v_and_or_b32 v4, v4, s35, v41
	v_and_or_b32 v3, v3, s35, v29
	v_and_or_b32 v2, v2, s35, v40
	v_lshl_add_u64 v[30:31], v[30:31], 0, v[0:1]
	global_store_dwordx4 v[30:31], v[2:5], off sc1
	s_waitcnt lgkmcnt(0)

; template <bool HASG>
; __device__ __forceinline__ void tr_item(const float* W, int K, int N, bf16* WT, int rowmode, const float* g, LAS float* scr, int item, int lane) {
;     const int nblk = N / 32, kb = item / nblk, nb = item % nblk, k0 = 64 * kb, n0 = 32 * nb;
;     const float* wp = W + (size_t)(k0 + (lane >> 5)) * N + n0 + (lane & 31);
;     const int c = lane & 7;
;     float v[32];
; #pragma unroll
;     for (int i = 0; i < 32; ++i) v[i] = wp[(size_t)(2 * i) * N];
;     f32x4 g0 = (f32x4){1.f, 1.f, 1.f, 1.f}, g1 = g0;
;     if (HASG) { g0 = *(const f32x4*)(g + k0 + 8 * c); g1 = *(const f32x4*)(g + k0 + 8 * c + 4); }
; __device__ __forceinline__ void convert_items(const Args& a, LAS unsigned char* lds, int l, int it_lo, int it_hi, int gw, int NGW, int wave, int lane) {
;     ...
;         if (r < I_G) { tr_item<true>(a.in[2] + o_gu, D, FF, wl + W_GU1, 1, a.in[1] + l * D, scr, r, lane); continue; } r -= I_G;
.LBB0_507:
	s_andn2_b64 vcc, exec, s[28:29]
	s_cbranch_vccnz .LBB0_476
	s_mul_hi_i32 s28, s67, 0x2e8ba2e9
	s_lshr_b32 s29, s28, 31
	s_ashr_i32 s28, s28, 4
	s_add_i32 s28, s28, s29
	s_lshl_b32 s64, s28, 6
	s_mul_i32 s29, s28, 0xfffff500
	s_add_i32 s92, s42, s29
	v_or_b32_e32 v0, s64, v33
	v_mov_b64_e32 v[2:3], s[38:39]
	s_movk_i32 s4, 0x2c00
	v_mad_i64_i32 v[2:3], s[60:61], v0, s4, v[2:3]
	s_ashr_i32 s93, s92, 31
	v_lshl_add_u64 v[2:3], s[92:93], 2, v[2:3]
	v_lshlrev_b32_e32 v0, 2, v6
	v_lshl_add_u64 v[2:3], v[2:3], 0, v[0:1]
	s_movk_i32 s4, 0x5000
	v_add_co_u32_e32 v4, vcc, s4, v2
	s_mov_b32 s4, 0x1b000
	s_nop 0
	v_addc_co_u32_e32 v5, vcc, 0, v3, vcc
	v_add_co_u32_e32 v30, vcc, s90, v2
	s_ashr_i32 s65, s64, 31
	s_nop 0
	v_addc_co_u32_e32 v31, vcc, 0, v3, vcc
	v_add_co_u32_e32 v40, vcc, s70, v2
	s_mulk_i32 s28, 0xea00
	s_nop 0
	v_addc_co_u32_e32 v41, vcc, 0, v3, vcc
	v_add_co_u32_e32 v42, vcc, s71, v2
	s_add_i32 s28, s44, s28
	s_nop 0
	v_addc_co_u32_e32 v43, vcc, 0, v3, vcc
	v_add_co_u32_e32 v44, vcc, s4, v2
	s_mov_b32 s4, 0x21000
	s_nop 0
	v_addc_co_u32_e32 v45, vcc, 0, v3, vcc
	v_add_co_u32_e32 v46, vcc, s4, v2
	s_mov_b32 s4, 0x26000
	s_nop 0
	v_addc_co_u32_e32 v47, vcc, 0, v3, vcc
	v_add_co_u32_e32 v48, vcc, s4, v2
	s_mov_b32 s4, 0x2c000
	s_nop 0
	v_addc_co_u32_e32 v49, vcc, 0, v3, vcc
	global_load_dword v0, v[2:3], off
	global_load_dword v29, v[4:5], off offset:2048
	global_load_dword v52, v[30:31], off
	global_load_dword v53, v[40:41], off offset:2048
	global_load_dword v54, v[42:43], off
	global_load_dword v55, v[44:45], off offset:2048
	global_load_dword v56, v[46:47], off
	global_load_dword v57, v[48:49], off offset:2048
	v_add_co_u32_e32 v4, vcc, s4, v2
	s_mov_b32 s4, 0x31000
	s_nop 0
	v_addc_co_u32_e32 v5, vcc, 0, v3, vcc
	v_add_co_u32_e32 v30, vcc, s4, v2
	s_mov_b32 s4, 0x37000
	s_nop 0
	v_addc_co_u32_e32 v31, vcc, 0, v3, vcc
	v_add_co_u32_e32 v40, vcc, s4, v2
	s_mov_b32 s4, 0x3c000
	s_nop 0
	v_addc_co_u32_e32 v41, vcc, 0, v3, vcc
	v_add_co_u32_e32 v42, vcc, s4, v2
	s_mov_b32 s4, 0x42000
	s_nop 0
	v_addc_co_u32_e32 v43, vcc, 0, v3, vcc
	v_add_co_u32_e32 v44, vcc, s4, v2
	s_mov_b32 s4, 0x47000
	s_nop 0
	v_addc_co_u32_e32 v45, vcc, 0, v3, vcc
	v_add_co_u32_e32 v46, vcc, s4, v2
	s_mov_b32 s4, 0x4d000
	s_nop 0
	v_addc_co_u32_e32 v47, vcc, 0, v3, vcc
	v_add_co_u32_e32 v48, vcc, s4, v2
	s_mov_b32 s4, 0x52000
	s_nop 0
	v_addc_co_u32_e32 v49, vcc, 0, v3, vcc
	v_add_co_u32_e32 v50, vcc, s4, v2
	s_mov_b32 s4, 0x58000
	s_nop 0
	v_addc_co_u32_e32 v51, vcc, 0, v3, vcc
	global_load_dword v58, v[4:5], off
	global_load_dword v59, v[30:31], off offset:2048
	global_load_dword v60, v[40:41], off
	global_load_dword v61, v[42:43], off offset:2048
	global_load_dword v62, v[44:45], off
	global_load_dword v63, v[46:47], off offset:2048
	global_load_dword v64, v[48:49], off
	global_load_dword v65, v[50:51], off offset:2048
	v_add_co_u32_e32 v4, vcc, s4, v2
	s_mov_b32 s4, 0x5d000
	s_nop 0
	v_addc_co_u32_e32 v5, vcc, 0, v3, vcc
	v_add_co_u32_e32 v30, vcc, s4, v2
	s_mov_b32 s4, 0x63000
	s_nop 0
	v_addc_co_u32_e32 v31, vcc, 0, v3, vcc
	v_add_co_u32_e32 v40, vcc, s4, v2
	s_mov_b32 s4, 0x68000
	s_nop 0
	v_addc_co_u32_e32 v41, vcc, 0, v3, vcc
	v_add_co_u32_e32 v42, vcc, s4, v2
	s_mov_b32 s4, 0x6e000
	s_nop 0
	v_addc_co_u32_e32 v43, vcc, 0, v3, vcc
	v_add_co_u32_e32 v44, vcc, s4, v2
	s_mov_b32 s4, 0x73000
	s_nop 0
	v_addc_co_u32_e32 v45, vcc, 0, v3, vcc
	v_add_co_u32_e32 v46, vcc, s4, v2
	s_mov_b32 s4, 0x79000
	s_nop 0
	v_addc_co_u32_e32 v47, vcc, 0, v3, vcc
	v_add_co_u32_e32 v48, vcc, s4, v2
	s_mov_b32 s4, 0x7e000
	s_nop 0
	v_addc_co_u32_e32 v49, vcc, 0, v3, vcc
	v_add_co_u32_e32 v50, vcc, s4, v2
	s_mov_b32 s4, 0x84000
	s_nop 0
	v_addc_co_u32_e32 v51, vcc, 0, v3, vcc
	global_load_dword v66, v[4:5], off
	global_load_dword v67, v[30:31], off offset:2048
	global_load_dword v68, v[40:41], off
	global_load_dword v69, v[42:43], off offset:2048
	global_load_dword v70, v[44:45], off
	global_load_dword v71, v[46:47], off offset:2048
	global_load_dword v72, v[48:49], off
	s_nop 0
	global_load_dword v50, v[50:51], off offset:2048
	v_add_co_u32_e32 v4, vcc, s4, v2
	s_mov_b32 s4, 0x89000
	s_nop 0
	v_addc_co_u32_e32 v5, vcc, 0, v3, vcc
	v_add_co_u32_e32 v30, vcc, s4, v2
	s_mov_b32 s4, 0x8f000
	s_nop 0
	v_addc_co_u32_e32 v31, vcc, 0, v3, vcc
	v_add_co_u32_e32 v40, vcc, s4, v2
	s_mov_b32 s4, 0x94000
	s_nop 0
	v_addc_co_u32_e32 v41, vcc, 0, v3, vcc
	v_add_co_u32_e32 v42, vcc, s4, v2
	s_mov_b32 s4, 0x9a000
	s_nop 0
	v_addc_co_u32_e32 v43, vcc, 0, v3, vcc
	v_add_co_u32_e32 v44, vcc, s4, v2
	s_mov_b32 s4, 0x9f000
	s_nop 0
	v_addc_co_u32_e32 v45, vcc, 0, v3, vcc
	v_add_co_u32_e32 v46, vcc, s4, v2
	s_mov_b32 s4, 0xa5000
	s_nop 0
	v_addc_co_u32_e32 v47, vcc, 0, v3, vcc
	v_add_co_u32_e32 v48, vcc, s4, v2
	s_mov_b32 s4, 0xaa000
	s_nop 0
	v_addc_co_u32_e32 v49, vcc, 0, v3, vcc
	v_add_co_u32_e32 v2, vcc, s4, v2
	s_and_b32 s28, s28, 0xffffff00
	s_nop 0
	v_addc_co_u32_e32 v3, vcc, 0, v3, vcc
	global_load_dword v51, v[4:5], off
	s_nop 0
	global_load_dword v30, v[30:31], off offset:2048
	s_nop 0
	global_load_dword v31, v[40:41], off
	global_load_dword v73, v[42:43], off offset:2048
	s_nop 0
	global_load_dword v44, v[44:45], off
	s_nop 0
	global_load_dword v45, v[46:47], off offset:2048
	s_nop 0
	global_load_dword v46, v[48:49], off
	global_load_dword v47, v[2:3], off offset:2048
	v_lshl_add_u64 v[2:3], s[64:65], 2, v[26:27]
	global_load_dwordx4 v[40:43], v[2:3], off
	s_nop 0
	global_load_dwordx4 v[2:5], v[2:3], off offset:16
	s_waitcnt vmcnt(32)
	ds_write2_b32 v34, v0, v29 offset1:66
	s_waitcnt vmcnt(30)
	ds_write2_b32 v34, v52, v53 offset0:132 offset1:198
	v_add_u32_e32 v0, 0x400, v34
	s_waitcnt vmcnt(28)
; #define LAS __attribute__((address_space(3)))
; __device__ __forceinline__ unsigned pk2(float lo, float hi) { return f2bf(lo) | (f2bf(hi) << 16); }
; #define LDS_WAVE_SYNC() asm volatile("s_waitcnt lgkmcnt(0)" ::: "memory")
; template <bool HASG>
; __device__ __forceinline__ void tr_item(const float* W, int K, int N, bf16* WT, int rowmode, const float* g, LAS float* scr, int item, int lane) {
;     ...
;     for (int i = 0; i < 32; ++i) scr[(2 * i + (lane >> 5)) * 33 + (lane & 31)] = v[i];
;     LDS_WAVE_SYNC();
;     const int drow0 = rowmode == 0 ? n0 : ((n0 >> 7) * 256 + (n0 & 127) + (rowmode == 2 ? 128 : 0));
; #pragma unroll
;     for (int j = 0; j < 4; ++j) { const int n = (lane >> 3) + 8 * j; const LAS float* s = scr + (8 * c) * 33 + n;
;         u32x4 o; o.x = pk2(s[0 * 33] * g0.x, s[1 * 33] * g0.y); o.y = pk2(s[2 * 33] * g0.z, s[3 * 33] * g0.w);
;         o.z = pk2(s[4 * 33] * g1.x, s[5 * 33] * g1.y); o.w = pk2(s[6 * 33] * g1.z, s[7 * 33] * g1.w);
;         *(u32x4*)(WT + (size_t)(drow0 + n) * K + k0 + 8 * c) = o; }
	ds_write2_b32 v0, v54, v55 offset0:8 offset1:74
	s_waitcnt vmcnt(26)
	ds_write2_b32 v0, v56, v57 offset0:140 offset1:206
	v_add_u32_e32 v0, 0x800, v34
	s_waitcnt vmcnt(24)
	ds_write2_b32 v0, v58, v59 offset0:16 offset1:82
	s_waitcnt vmcnt(22)
	ds_write2_b32 v0, v60, v61 offset0:148 offset1:214
	v_add_u32_e32 v0, 0xc00, v34
	s_waitcnt vmcnt(20)
	ds_write2_b32 v0, v62, v63 offset0:24 offset1:90
	s_waitcnt vmcnt(18)
	ds_write2_b32 v0, v64, v65 offset0:156 offset1:222
	v_add_u32_e32 v0, 0x1000, v34
	s_waitcnt vmcnt(16)
	ds_write2_b32 v0, v66, v67 offset0:32 offset1:98
	s_waitcnt vmcnt(14)
	ds_write2_b32 v0, v68, v69 offset0:164 offset1:230
	v_add_u32_e32 v0, 0x1400, v34
	s_waitcnt vmcnt(12)
	ds_write2_b32 v0, v70, v71 offset0:40 offset1:106
	s_waitcnt vmcnt(10)
	ds_write2_b32 v0, v72, v50 offset0:172 offset1:238
	v_add_u32_e32 v0, 0x1800, v34
	s_waitcnt vmcnt(8)
	ds_write2_b32 v0, v51, v30 offset0:48 offset1:114
	s_waitcnt vmcnt(6)
	ds_write2_b32 v0, v31, v73 offset0:180 offset1:246
	v_add_u32_e32 v0, 0x1c00, v34
	s_waitcnt vmcnt(4)
	ds_write2_b32 v0, v44, v45 offset0:56 offset1:122
	s_waitcnt vmcnt(2)
	ds_write2_b32 v0, v46, v47 offset0:188 offset1:254
	s_waitcnt lgkmcnt(0)
	ds_read2_b32 v[48:49], v36 offset0:33 offset1:41
	ds_read2_b32 v[50:51], v36 offset1:8
	ds_read2_b32 v[52:53], v36 offset0:66 offset1:74
	ds_read2_b32 v[54:55], v36 offset0:99 offset1:107
	ds_read2_b32 v[58:59], v36 offset0:132 offset1:140
	ds_read2_b32 v[60:61], v36 offset0:165 offset1:173
	ds_read2_b32 v[62:63], v36 offset0:198 offset1:206
	ds_read2_b32 v[64:65], v36 offset0:231 offset1:239
	s_waitcnt vmcnt(1)
	v_mov_b32_e32 v56, v40
	v_mov_b32_e32 v57, v42
	v_mov_b32_e32 v42, v41
	s_waitcnt lgkmcnt(7)
	v_mov_b32_e32 v40, v48
	s_waitcnt lgkmcnt(4)
	v_mov_b32_e32 v41, v54
	v_pk_mul_f32 v[40:41], v[42:43], v[40:41]
	s_waitcnt vmcnt(0)
	v_mov_b32_e32 v66, v2
	v_mov_b32_e32 v67, v4
	s_waitcnt lgkmcnt(3)
	v_mov_b32_e32 v46, v58
	s_waitcnt lgkmcnt(1)
	v_mov_b32_e32 v47, v62
	v_mov_b32_e32 v4, v3
	v_mov_b32_e32 v2, v60
	s_waitcnt lgkmcnt(0)
	v_mov_b32_e32 v3, v64
	v_mov_b32_e32 v44, v50
	v_mov_b32_e32 v45, v52
	v_pk_mul_f32 v[46:47], v[66:67], v[46:47]
	v_pk_mul_f32 v[2:3], v[4:5], v[2:3]
	v_bfe_u32 v48, v41, 16, 1
	v_pk_mul_f32 v[44:45], v[56:57], v[44:45]
	v_bfe_u32 v0, v3, 16, 1
	v_add3_u32 v41, v41, v48, s91
	v_bfe_u32 v48, v46, 16, 1
	s_and_b32 s29, s92, 0x60
	v_bfe_u32 v29, v2, 16, 1
	v_add3_u32 v0, v3, v0, s91
	v_bfe_u32 v3, v44, 16, 1
	v_add3_u32 v46, v46, v48, s91
	s_or_b32 s28, s29, s28
	v_bfe_u32 v50, v40, 16, 1
	v_add3_u32 v2, v2, v29, s91
	v_add3_u32 v3, v44, v3, s91
	v_lshrrev_b32_e32 v44, 16, v46
	v_add3_u32 v40, v40, v50, s91
	v_bfe_u32 v29, v45, 16, 1
	v_bfe_u32 v50, v47, 16, 1
	v_lshrrev_b32_e32 v3, 16, v3
	v_and_or_b32 v46, v2, s35, v44
	v_or_b32_e32 v2, s28, v35
	v_add3_u32 v47, v47, v50, s91
	v_add3_u32 v29, v45, v29, s91
	v_and_or_b32 v44, v40, s35, v3
	v_ashrrev_i32_e32 v3, 31, v2
	v_lshl_add_u64 v[30:31], s[64:65], 1, v[8:9]
	v_lshrrev_b32_e32 v29, 16, v29
	v_lshrrev_b32_e32 v45, 16, v47
	v_lshlrev_b64 v[2:3], 11, v[2:3]
	v_and_or_b32 v47, v0, s35, v45
	v_and_or_b32 v45, v41, s35, v29
	v_lshl_add_u64 v[2:3], v[30:31], 0, v[2:3]
	v_mov_b32_e32 v54, v49
	v_mov_b32_e32 v64, v61
	global_store_dwordx4 v[2:3], v[44:47], off sc1
	v_mov_b32_e32 v52, v51
	v_pk_mul_f32 v[40:41], v[42:43], v[54:55]
	v_mov_b32_e32 v62, v59
	v_pk_mul_f32 v[46:47], v[4:5], v[64:65]
	v_pk_mul_f32 v[2:3], v[56:57], v[52:53]
	v_pk_mul_f32 v[44:45], v[66:67], v[62:63]
	v_bfe_u32 v29, v46, 16, 1
	v_bfe_u32 v48, v41, 16, 1
	v_bfe_u32 v0, v47, 16, 1
	v_bfe_u32 v49, v40, 16, 1
	v_add3_u32 v41, v41, v48, s91
	v_add3_u32 v29, v46, v29, s91
	v_bfe_u32 v46, v2, 16, 1
	v_bfe_u32 v48, v44, 16, 1
	v_add3_u32 v40, v40, v49, s91
	v_add3_u32 v0, v47, v0, s91
	v_bfe_u32 v47, v3, 16, 1
	v_bfe_u32 v49, v45, 16, 1
	v_add3_u32 v44, v44, v48, s91
	v_add3_u32 v2, v2, v46, s91
	v_add3_u32 v45, v45, v49, s91
	v_add3_u32 v3, v3, v47, s91
	v_lshrrev_b32_e32 v2, 16, v2
	v_lshrrev_b32_e32 v44, 16, v44
	v_lshrrev_b32_e32 v3, 16, v3
	v_lshrrev_b32_e32 v45, 16, v45
	v_and_or_b32 v46, v29, s35, v44
	v_and_or_b32 v44, v40, s35, v2
	v_or_b32_e32 v2, s28, v37
	v_and_or_b32 v47, v0, s35, v45
	v_and_or_b32 v45, v41, s35, v3
	v_ashrrev_i32_e32 v3, 31, v2
	v_lshlrev_b64 v[2:3], 11, v[2:3]
	v_lshl_add_u64 v[2:3], v[30:31], 0, v[2:3]
	ds_read2_b32 v[40:41], v36 offset0:16 offset1:24
	ds_read2_b32 v[48:49], v36 offset0:82 offset1:90
	global_store_dwordx4 v[2:3], v[44:47], off sc1
	ds_read2_b32 v[2:3], v36 offset0:49 offset1:57
	ds_read2_b32 v[50:51], v36 offset0:115 offset1:123
	ds_read2_b32 v[52:53], v36 offset0:148 offset1:156
	ds_read2_b32 v[54:55], v36 offset0:214 offset1:222
	ds_read2_b32 v[58:59], v36 offset0:181 offset1:189
	ds_read2_b32 v[60:61], v36 offset0:247 offset1:255
	s_waitcnt lgkmcnt(7)
; #define LAS __attribute__((address_space(3)))
; __device__ __forceinline__ unsigned pk2(float lo, float hi) { return f2bf(lo) | (f2bf(hi) << 16); }
; #define LDS_WAVE_SYNC() asm volatile("s_waitcnt lgkmcnt(0)" ::: "memory")
; template <bool HASG>
; __device__ __forceinline__ void tr_item(const float* W, int K, int N, bf16* WT, int rowmode, const float* g, LAS float* scr, int item, int lane) {
;     ...
;     for (int j = 0; j < 4; ++j) { const int n = (lane >> 3) + 8 * j; const LAS float* s = scr + (8 * c) * 33 + n;
;         u32x4 o; o.x = pk2(s[0 * 33] * g0.x, s[1 * 33] * g0.y); o.y = pk2(s[2 * 33] * g0.z, s[3 * 33] * g0.w);
;         o.z = pk2(s[4 * 33] * g1.x, s[5 * 33] * g1.y); o.w = pk2(s[6 * 33] * g1.z, s[7 * 33] * g1.w);
;         *(u32x4*)(WT + (size_t)(drow0 + n) * K + k0 + 8 * c) = o; }
;     LDS_WAVE_SYNC();
	v_mov_b32_e32 v44, v40
	s_waitcnt lgkmcnt(5)
	v_mov_b32_e32 v46, v2
	s_waitcnt lgkmcnt(4)
	v_mov_b32_e32 v47, v50
	s_waitcnt lgkmcnt(3)
	v_mov_b32_e32 v62, v52
	s_waitcnt lgkmcnt(2)
	v_mov_b32_e32 v63, v54
	v_mov_b32_e32 v45, v48
	v_pk_mul_f32 v[46:47], v[42:43], v[46:47]
	v_pk_mul_f32 v[62:63], v[66:67], v[62:63]
	v_pk_mul_f32 v[44:45], v[56:57], v[44:45]
	s_waitcnt lgkmcnt(1)
	v_mov_b32_e32 v64, v58
	s_waitcnt lgkmcnt(0)
	v_mov_b32_e32 v65, v60
	v_bfe_u32 v29, v47, 16, 1
	v_bfe_u32 v40, v46, 16, 1
	v_bfe_u32 v48, v62, 16, 1
	v_pk_mul_f32 v[64:65], v[4:5], v[64:65]
	v_add3_u32 v40, v46, v40, s91
	v_add3_u32 v29, v47, v29, s91
	v_bfe_u32 v46, v44, 16, 1
	v_bfe_u32 v47, v45, 16, 1
	v_bfe_u32 v50, v63, 16, 1
	v_add3_u32 v48, v62, v48, s91
	v_or_b32_e32 v62, s28, v38
	v_bfe_u32 v0, v65, 16, 1
	v_bfe_u32 v2, v64, 16, 1
	v_add3_u32 v50, v63, v50, s91
	v_add3_u32 v45, v45, v47, s91
	v_add3_u32 v44, v44, v46, s91
	v_ashrrev_i32_e32 v63, 31, v62
	v_mov_b32_e32 v60, v59
	v_add3_u32 v2, v64, v2, s91
	v_add3_u32 v0, v65, v0, s91
	v_lshrrev_b32_e32 v44, 16, v44
	v_lshrrev_b32_e32 v45, 16, v45
	v_lshrrev_b32_e32 v46, 16, v48
	v_lshrrev_b32_e32 v47, 16, v50
	v_lshlrev_b64 v[62:63], 11, v[62:63]
	v_mov_b32_e32 v48, v41
	v_mov_b32_e32 v50, v3
	v_pk_mul_f32 v[4:5], v[4:5], v[60:61]
	v_and_or_b32 v47, v0, s35, v47
	v_and_or_b32 v46, v2, s35, v46
	v_and_or_b32 v45, v29, s35, v45
	v_and_or_b32 v44, v40, s35, v44
	v_lshl_add_u64 v[62:63], v[30:31], 0, v[62:63]
	v_pk_mul_f32 v[40:41], v[56:57], v[48:49]
	v_pk_mul_f32 v[2:3], v[42:43], v[50:51]
	v_mov_b32_e32 v54, v53
	v_bfe_u32 v0, v5, 16, 1
	global_store_dwordx4 v[62:63], v[44:47], off sc1
	v_pk_mul_f32 v[42:43], v[66:67], v[54:55]
	v_add3_u32 v0, v5, v0, s91
	v_bfe_u32 v44, v3, 16, 1
	v_bfe_u32 v5, v40, 16, 1
	v_bfe_u32 v29, v4, 16, 1
	v_bfe_u32 v45, v2, 16, 1
	v_add3_u32 v3, v3, v44, s91
	v_bfe_u32 v44, v42, 16, 1
	v_add3_u32 v5, v40, v5, s91
	v_add3_u32 v2, v2, v45, s91
	v_add3_u32 v4, v4, v29, s91
	v_bfe_u32 v29, v41, 16, 1
	v_add3_u32 v42, v42, v44, s91
	v_lshrrev_b32_e32 v40, 16, v5
	v_bfe_u32 v45, v43, 16, 1
	v_add3_u32 v29, v41, v29, s91
	v_lshrrev_b32_e32 v41, 16, v42
	v_and_or_b32 v2, v2, s35, v40
	v_or_b32_e32 v40, s28, v39
	v_add3_u32 v43, v43, v45, s91
	v_and_or_b32 v4, v4, s35, v41
	v_ashrrev_i32_e32 v41, 31, v40
	v_lshrrev_b32_e32 v29, 16, v29
	v_lshrrev_b32_e32 v5, 16, v43
	v_lshlrev_b64 v[40:41], 11, v[40:41]
	v_and_or_b32 v5, v0, s35, v5
	v_and_or_b32 v3, v3, s35, v29
	v_lshl_add_u64 v[30:31], v[30:31], 0, v[40:41]
	global_store_dwordx4 v[30:31], v[2:5], off sc1
	s_waitcnt lgkmcnt(0)
	s_branch .LBB0_476

; template <bool HASG>
; __device__ __forceinline__ void tr_item(const float* W, int K, int N, bf16* WT, int rowmode, const float* g, LAS float* scr, int item, int lane) {
;     const int nblk = N / 32, kb = item / nblk, nb = item % nblk, k0 = 64 * kb, n0 = 32 * nb;
;     const float* wp = W + (size_t)(k0 + (lane >> 5)) * N + n0 + (lane & 31);
;     const int c = lane & 7;
;     float v[32];
; #pragma unroll
;     for (int i = 0; i < 32; ++i) v[i] = wp[(size_t)(2 * i) * N];
;     f32x4 g0 = (f32x4){1.f, 1.f, 1.f, 1.f}, g1 = g0;
;     if (HASG) { g0 = *(const f32x4*)(g + k0 + 8 * c); g1 = *(const f32x4*)(g + k0 + 8 * c + 4); }
;     asm volatile("" ::: "memory");
; #pragma unroll
;     for (int i = 0; i < 32; ++i) scr[(2 * i + (lane >> 5)) * 33 + (lane & 31)] = v[i];
; __device__ __forceinline__ void convert_items(const Args& a, LAS unsigned char* lds, int l, int it_lo, int it_hi, int gw, int NGW, int wave, int lane) {
;     ...
;     for (int it = it_lo + gw; it < it_hi; it += NGW) {
;         int r = it; bf16* wl = WB + (size_t)l * W_LAYER;
;         const size_t o_gu = (size_t)l * D * FF, o_d = (size_t)l * FF * D;
;         if (r < I_G) { tr_item<true>(a.in[2] + o_gu, D, FF, wl + W_GU1, 1, a.in[1] + l * D, scr, r, lane); continue; } r -= I_G;
;         if (r < I_G) { tr_item<true>(a.in[3] + o_gu, D, FF, wl + W_GU1, 2, a.in[1] + l * D, scr, r, lane); continue; } r -= I_G;
;         if (r < I_D) { tr_item<false>(a.in[4] + o_d, FF, D, wl + W_D1, 0, nullptr, scr, r, lane); continue; } r -= I_D;
;         if (r < I_IN) { tr_item<true>(a.in[6] + (size_t)l * D * DIN, D, DIN, wl + W_IN, 0, a.in[5] + l * D, scr, r, lane); continue; } r -= I_IN;
;         if (r < I_OUT) { tr_item<false>(a.in[18] + (size_t)l * D * D, D, D, wl + W_OUT, 0, nullptr, scr, r, lane); continue; } r -= I_OUT;
;         if (r < I_G) { tr_item<true>(a.in[20] + o_gu, D, FF, wl + W_GU2, 1, a.in[19] + l * D, scr, r, lane); continue; } r -= I_G;
;         if (r < I_G) { tr_item<true>(a.in[21] + o_gu, D, FF, wl + W_GU2, 2, a.in[19] + l * D, scr, r, lane); continue; } r -= I_G;
;         if (r < I_D) { tr_item<false>(a.in[22] + o_d, FF, D, wl + W_D2, 0, nullptr, scr, r, lane); continue; } r -= I_D;
.LBB0_512:
	s_cmpk_gt_i32 s28, 0x57f
	s_mov_b64 s[0:1], -1
	s_cbranch_scc0 .LBB0_538
	s_cmpk_gt_u32 s28, 0xaff
	s_cbranch_scc0 .LBB0_535
	s_cmpk_gt_u32 s28, 0x107f
	s_cbranch_scc0 .LBB0_532
	s_cmpk_gt_u32 s28, 0x13ff
	s_cbranch_scc0 .LBB0_529
	s_cmpk_gt_u32 s28, 0x15ff
	s_cbranch_scc0 .LBB0_526
	s_cmpk_gt_u32 s28, 0x1b7f
	s_cbranch_scc0 .LBB0_523
	s_cmpk_gt_u32 s28, 0x20ff
	s_cbranch_scc0 .LBB0_520
	s_and_b32 s1, s44, 0x1ffc0
	s_lshl_b32 s0, s28, 5
	v_or_b32_e32 v0, s1, v28
	v_readlane_b32 s4, v252, 32
	s_and_b32 s0, s0, 0x3e0
	v_lshlrev_b32_e32 v0, 12, v0
	v_readlane_b32 s16, v252, 44
	v_readlane_b32 s17, v252, 45
	s_lshl_b32 s88, s0, 2
	v_readlane_b32 s5, v252, 33
	v_lshl_add_u64 v[2:3], s[16:17], 0, v[0:1]
	v_lshl_add_u64 v[2:3], v[2:3], 0, s[88:89]
	v_lshlrev_b32_e32 v0, 2, v6
	v_lshl_add_u64 v[2:3], v[2:3], 0, v[0:1]
	v_add_co_u32_e32 v4, vcc, 0x2000, v2
	global_load_dword v0, v[2:3], off
	s_nop 0
	v_addc_co_u32_e32 v5, vcc, 0, v3, vcc
	global_load_dword v26, v[4:5], off
	v_add_co_u32_e32 v4, vcc, 0x4000, v2
	v_readlane_b32 s6, v252, 34
	s_nop 0
	v_addc_co_u32_e32 v5, vcc, 0, v3, vcc
	global_load_dword v27, v[4:5], off
	v_add_co_u32_e32 v4, vcc, 0x6000, v2
	v_readlane_b32 s7, v252, 35
	s_nop 0
	v_addc_co_u32_e32 v5, vcc, 0, v3, vcc
	global_load_dword v36, v[4:5], off
	v_add_co_u32_e32 v4, vcc, 0x8000, v2
	v_readlane_b32 s8, v252, 36
	s_nop 0
	v_addc_co_u32_e32 v5, vcc, 0, v3, vcc
	global_load_dword v37, v[4:5], off
	v_add_co_u32_e32 v4, vcc, 0xa000, v2
	v_readlane_b32 s9, v252, 37
	s_nop 0
	v_addc_co_u32_e32 v5, vcc, 0, v3, vcc
	global_load_dword v38, v[4:5], off
	v_add_co_u32_e32 v4, vcc, 0xc000, v2
	v_readlane_b32 s10, v252, 38
	s_nop 0
	v_addc_co_u32_e32 v5, vcc, 0, v3, vcc
	global_load_dword v39, v[4:5], off
	v_add_co_u32_e32 v4, vcc, 0xe000, v2
	v_readlane_b32 s11, v252, 39
	v_readlane_b32 s12, v252, 40
	v_readlane_b32 s13, v252, 41
	v_readlane_b32 s14, v252, 42
	v_readlane_b32 s15, v252, 43
	v_readlane_b32 s18, v252, 46
	v_readlane_b32 s19, v252, 47
	v_addc_co_u32_e32 v5, vcc, 0, v3, vcc
	v_readlane_b32 s4, v252, 0
	global_load_dword v40, v[4:5], off
	v_add_co_u32_e32 v4, vcc, s70, v2
	s_mov_b32 s4, 0x12000
	s_nop 0
	v_addc_co_u32_e32 v5, vcc, 0, v3, vcc
	global_load_dword v41, v[4:5], off
	v_add_co_u32_e32 v4, vcc, s4, v2
	s_mov_b32 s4, 0x14000
	s_nop 0
	v_addc_co_u32_e32 v5, vcc, 0, v3, vcc
	global_load_dword v42, v[4:5], off
	v_add_co_u32_e32 v4, vcc, s4, v2
	s_mov_b32 s4, 0x18000
	s_nop 0
	v_addc_co_u32_e32 v5, vcc, 0, v3, vcc
	global_load_dword v43, v[4:5], off
	v_add_co_u32_e32 v4, vcc, s71, v2
	s_lshl_b32 s88, s1, 1
	s_nop 0
	v_addc_co_u32_e32 v5, vcc, 0, v3, vcc
	global_load_dword v44, v[4:5], off
	v_add_co_u32_e32 v4, vcc, s4, v2
	s_mov_b32 s4, 0x1a000
	s_nop 0
	v_addc_co_u32_e32 v5, vcc, 0, v3, vcc
	global_load_dword v45, v[4:5], off
	v_add_co_u32_e32 v4, vcc, s4, v2
	s_mov_b32 s4, 0x1c000
	s_nop 0
	v_addc_co_u32_e32 v5, vcc, 0, v3, vcc
	global_load_dword v46, v[4:5], off
	v_add_co_u32_e32 v4, vcc, s4, v2
	s_mov_b32 s4, 0x1e000
	s_nop 0
	v_addc_co_u32_e32 v5, vcc, 0, v3, vcc
	global_load_dword v47, v[4:5], off
	v_add_co_u32_e32 v4, vcc, s4, v2
	s_mov_b32 s4, 0x20000
	s_nop 0
	v_addc_co_u32_e32 v5, vcc, 0, v3, vcc
	global_load_dword v48, v[4:5], off
	v_add_co_u32_e32 v4, vcc, s4, v2
	s_mov_b32 s4, 0x22000
	s_nop 0
	v_addc_co_u32_e32 v5, vcc, 0, v3, vcc
	global_load_dword v49, v[4:5], off
	v_add_co_u32_e32 v4, vcc, s4, v2
	s_mov_b32 s4, 0x24000
	s_nop 0
	v_addc_co_u32_e32 v5, vcc, 0, v3, vcc
	global_load_dword v50, v[4:5], off
	v_add_co_u32_e32 v4, vcc, s4, v2
	s_mov_b32 s4, 0x26000
	s_nop 0
	v_addc_co_u32_e32 v5, vcc, 0, v3, vcc
	global_load_dword v51, v[4:5], off
	v_add_co_u32_e32 v4, vcc, s4, v2
	s_mov_b32 s4, 0x28000
	s_nop 0
	v_addc_co_u32_e32 v5, vcc, 0, v3, vcc
	global_load_dword v52, v[4:5], off
	v_add_co_u32_e32 v4, vcc, s4, v2
	s_mov_b32 s4, 0x2a000
	s_nop 0
	v_addc_co_u32_e32 v5, vcc, 0, v3, vcc
	global_load_dword v53, v[4:5], off
	v_add_co_u32_e32 v4, vcc, s4, v2
	s_mov_b32 s4, 0x2c000
	s_nop 0
	v_addc_co_u32_e32 v5, vcc, 0, v3, vcc
	global_load_dword v54, v[4:5], off
	v_add_co_u32_e32 v4, vcc, s4, v2
	s_mov_b32 s4, 0x2e000
	s_nop 0
	v_addc_co_u32_e32 v5, vcc, 0, v3, vcc
	global_load_dword v55, v[4:5], off
	v_add_co_u32_e32 v4, vcc, s4, v2
	s_mov_b32 s4, 0x30000
	s_nop 0
	v_addc_co_u32_e32 v5, vcc, 0, v3, vcc
	global_load_dword v56, v[4:5], off
	v_add_co_u32_e32 v4, vcc, s4, v2
	s_mov_b32 s4, 0x32000
	s_nop 0
	v_addc_co_u32_e32 v5, vcc, 0, v3, vcc
	global_load_dword v57, v[4:5], off
	v_add_co_u32_e32 v4, vcc, s4, v2
	s_mov_b32 s4, 0x34000
	s_nop 0
	v_addc_co_u32_e32 v5, vcc, 0, v3, vcc
	global_load_dword v58, v[4:5], off
	v_add_co_u32_e32 v4, vcc, s4, v2
	s_mov_b32 s4, 0x36000
	s_nop 0
	v_addc_co_u32_e32 v5, vcc, 0, v3, vcc
	global_load_dword v59, v[4:5], off
	v_add_co_u32_e32 v4, vcc, s4, v2
	s_mov_b32 s4, 0x38000
	s_nop 0
	v_addc_co_u32_e32 v5, vcc, 0, v3, vcc
	global_load_dword v60, v[4:5], off
	v_add_co_u32_e32 v4, vcc, s4, v2
	s_mov_b32 s4, 0x3a000
	s_nop 0
	v_addc_co_u32_e32 v5, vcc, 0, v3, vcc
	global_load_dword v61, v[4:5], off
	v_add_co_u32_e32 v4, vcc, s4, v2
	s_mov_b32 s4, 0x3c000
	s_nop 0
	v_addc_co_u32_e32 v5, vcc, 0, v3, vcc
	global_load_dword v62, v[4:5], off
	v_add_co_u32_e32 v4, vcc, s4, v2
	s_mov_b32 s4, 0x3e000
	s_nop 0
	v_addc_co_u32_e32 v5, vcc, 0, v3, vcc
	v_add_co_u32_e32 v2, vcc, s4, v2
	global_load_dword v4, v[4:5], off
	s_nop 0
	v_addc_co_u32_e32 v3, vcc, 0, v3, vcc
	global_load_dword v2, v[2:3], off
	s_waitcnt vmcnt(30)
	ds_write2_b32 v29, v0, v26 offset1:66
	s_waitcnt vmcnt(28)
	ds_write2_b32 v29, v27, v36 offset0:132 offset1:198
	v_add_u32_e32 v0, 0x400, v29
	s_waitcnt vmcnt(26)
; #define LAS __attribute__((address_space(3)))
; __device__ __forceinline__ unsigned pk2(float lo, float hi) { return f2bf(lo) | (f2bf(hi) << 16); }
; #define LDS_WAVE_SYNC() asm volatile("s_waitcnt lgkmcnt(0)" ::: "memory")
; template <bool HASG>
; __device__ __forceinline__ void tr_item(const float* W, int K, int N, bf16* WT, int rowmode, const float* g, LAS float* scr, int item, int lane) {
;     ...
;     for (int i = 0; i < 32; ++i) scr[(2 * i + (lane >> 5)) * 33 + (lane & 31)] = v[i];
;     LDS_WAVE_SYNC();
;     const int drow0 = rowmode == 0 ? n0 : ((n0 >> 7) * 256 + (n0 & 127) + (rowmode == 2 ? 128 : 0));
; #pragma unroll
;     for (int j = 0; j < 4; ++j) { const int n = (lane >> 3) + 8 * j; const LAS float* s = scr + (8 * c) * 33 + n;
;         u32x4 o; o.x = pk2(s[0 * 33] * g0.x, s[1 * 33] * g0.y); o.y = pk2(s[2 * 33] * g0.z, s[3 * 33] * g0.w);
;         o.z = pk2(s[4 * 33] * g1.x, s[5 * 33] * g1.y); o.w = pk2(s[6 * 33] * g1.z, s[7 * 33] * g1.w);
;         *(u32x4*)(WT + (size_t)(drow0 + n) * K + k0 + 8 * c) = o; }
;     LDS_WAVE_SYNC();
	ds_write2_b32 v0, v37, v38 offset0:8 offset1:74
	s_waitcnt vmcnt(24)
	ds_write2_b32 v0, v39, v40 offset0:140 offset1:206
	v_add_u32_e32 v0, 0x800, v29
	s_waitcnt vmcnt(22)
	ds_write2_b32 v0, v41, v42 offset0:16 offset1:82
	s_waitcnt vmcnt(20)
	ds_write2_b32 v0, v43, v44 offset0:148 offset1:214
	v_add_u32_e32 v0, 0xc00, v29
	s_waitcnt vmcnt(18)
	ds_write2_b32 v0, v45, v46 offset0:24 offset1:90
	s_waitcnt vmcnt(16)
	ds_write2_b32 v0, v47, v48 offset0:156 offset1:222
	v_add_u32_e32 v0, 0x1000, v29
	s_waitcnt vmcnt(14)
	ds_write2_b32 v0, v49, v50 offset0:32 offset1:98
	s_waitcnt vmcnt(12)
	ds_write2_b32 v0, v51, v52 offset0:164 offset1:230
	v_add_u32_e32 v0, 0x1400, v29
	s_waitcnt vmcnt(10)
	ds_write2_b32 v0, v53, v54 offset0:40 offset1:106
	s_waitcnt vmcnt(8)
	ds_write2_b32 v0, v55, v56 offset0:172 offset1:238
	v_add_u32_e32 v0, 0x1800, v29
	s_waitcnt vmcnt(6)
	ds_write2_b32 v0, v57, v58 offset0:48 offset1:114
	s_waitcnt vmcnt(4)
	ds_write2_b32 v0, v59, v60 offset0:180 offset1:246
	v_add_u32_e32 v0, 0x1c00, v29
	s_waitcnt vmcnt(2)
	ds_write2_b32 v0, v61, v62 offset0:56 offset1:122
	s_waitcnt vmcnt(0)
	ds_write2_b32 v0, v4, v2 offset0:188 offset1:254
	s_waitcnt lgkmcnt(0)
	ds_read2_b32 v[4:5], v31 offset0:33 offset1:41
	ds_read2_b32 v[26:27], v31 offset1:8
	ds_read2_b32 v[40:41], v31 offset0:66 offset1:74
	ds_read2_b32 v[42:43], v31 offset0:99 offset1:107
	ds_read2_b32 v[44:45], v31 offset0:132 offset1:140
	ds_read2_b32 v[46:47], v31 offset0:165 offset1:173
	ds_read2_b32 v[48:49], v31 offset0:198 offset1:206
	ds_read2_b32 v[50:51], v31 offset0:231 offset1:239
	v_lshl_add_u64 v[2:3], v[8:9], 0, s[88:89]
	s_waitcnt lgkmcnt(6)
	v_bfe_u32 v0, v26, 16, 1
	v_add3_u32 v0, v26, v0, s91
	v_bfe_u32 v26, v4, 16, 1
	v_lshrrev_b32_e32 v0, 16, v0
	v_add3_u32 v4, v4, v26, s91
	v_and_or_b32 v36, v4, s35, v0
	s_waitcnt lgkmcnt(5)
	v_bfe_u32 v0, v40, 16, 1
	v_add3_u32 v0, v40, v0, s91
	s_waitcnt lgkmcnt(4)
	v_bfe_u32 v4, v42, 16, 1
	v_lshrrev_b32_e32 v0, 16, v0
	v_add3_u32 v4, v42, v4, s91
	v_and_or_b32 v37, v4, s35, v0
	s_waitcnt lgkmcnt(3)
	v_bfe_u32 v0, v44, 16, 1
	v_add3_u32 v0, v44, v0, s91
	s_waitcnt lgkmcnt(2)
	v_bfe_u32 v4, v46, 16, 1
	v_lshrrev_b32_e32 v0, 16, v0
	v_add3_u32 v4, v46, v4, s91
	v_and_or_b32 v38, v4, s35, v0
	s_waitcnt lgkmcnt(1)
	v_bfe_u32 v0, v48, 16, 1
	v_add3_u32 v0, v48, v0, s91
	s_waitcnt lgkmcnt(0)
	v_bfe_u32 v4, v50, 16, 1
	v_lshrrev_b32_e32 v0, 16, v0
	v_add3_u32 v4, v50, v4, s91
	v_and_or_b32 v39, v4, s35, v0
	v_or_b32_e32 v0, s0, v30
	v_mul_u32_u24_e32 v0, 0xb00, v0
	v_lshlrev_b32_e32 v0, 1, v0
	v_lshl_add_u64 v[52:53], v[2:3], 0, v[0:1]
	v_bfe_u32 v0, v27, 16, 1
	v_add3_u32 v0, v27, v0, s91
	v_bfe_u32 v4, v5, 16, 1
	v_lshrrev_b32_e32 v0, 16, v0
	v_add3_u32 v4, v5, v4, s91
	global_store_dwordx4 v[52:53], v[36:39], off sc1
	v_readlane_b32 s8, v252, 4
	v_readlane_b32 s9, v252, 5
	v_and_or_b32 v36, v4, s35, v0
	v_bfe_u32 v0, v41, 16, 1
	v_add3_u32 v0, v41, v0, s91
	v_bfe_u32 v4, v43, 16, 1
	v_lshrrev_b32_e32 v0, 16, v0
	v_add3_u32 v4, v43, v4, s91
	v_and_or_b32 v37, v4, s35, v0
	v_bfe_u32 v0, v45, 16, 1
	v_add3_u32 v0, v45, v0, s91
	v_bfe_u32 v4, v47, 16, 1
	v_lshrrev_b32_e32 v0, 16, v0
	v_add3_u32 v4, v47, v4, s91
	v_and_or_b32 v38, v4, s35, v0
	v_bfe_u32 v0, v49, 16, 1
	v_add3_u32 v0, v49, v0, s91
	v_bfe_u32 v4, v51, 16, 1
	v_lshrrev_b32_e32 v0, 16, v0
	v_add3_u32 v4, v51, v4, s91
	v_and_or_b32 v39, v4, s35, v0
	v_or_b32_e32 v0, s0, v33
	v_mul_u32_u24_e32 v0, 0xb00, v0
	v_lshlrev_b32_e32 v0, 1, v0
	v_lshl_add_u64 v[4:5], v[2:3], 0, v[0:1]
	global_store_dwordx4 v[4:5], v[36:39], off sc1
	ds_read2_b32 v[4:5], v31 offset0:16 offset1:24
	ds_read2_b32 v[26:27], v31 offset0:49 offset1:57
	ds_read2_b32 v[40:41], v31 offset0:82 offset1:90
	ds_read2_b32 v[42:43], v31 offset0:115 offset1:123
	ds_read2_b32 v[44:45], v31 offset0:148 offset1:156
	ds_read2_b32 v[46:47], v31 offset0:181 offset1:189
	ds_read2_b32 v[48:49], v31 offset0:214 offset1:222
	ds_read2_b32 v[50:51], v31 offset0:247 offset1:255
	s_waitcnt lgkmcnt(7)
	v_bfe_u32 v0, v4, 16, 1
	v_add3_u32 v0, v4, v0, s91
	s_waitcnt lgkmcnt(6)
	v_bfe_u32 v4, v26, 16, 1
	v_lshrrev_b32_e32 v0, 16, v0
	v_add3_u32 v4, v26, v4, s91
	v_and_or_b32 v36, v4, s35, v0
	s_waitcnt lgkmcnt(5)
	v_bfe_u32 v0, v40, 16, 1
	v_add3_u32 v0, v40, v0, s91
	s_waitcnt lgkmcnt(4)
	v_bfe_u32 v4, v42, 16, 1
	v_lshrrev_b32_e32 v0, 16, v0
	v_add3_u32 v4, v42, v4, s91
	v_and_or_b32 v37, v4, s35, v0
	s_waitcnt lgkmcnt(3)
	v_bfe_u32 v0, v44, 16, 1
	v_add3_u32 v0, v44, v0, s91
	s_waitcnt lgkmcnt(2)
	v_bfe_u32 v4, v46, 16, 1
	v_lshrrev_b32_e32 v0, 16, v0
	v_add3_u32 v4, v46, v4, s91
	v_and_or_b32 v38, v4, s35, v0
	s_waitcnt lgkmcnt(1)
	v_bfe_u32 v0, v48, 16, 1
	v_add3_u32 v0, v48, v0, s91
	s_waitcnt lgkmcnt(0)
	v_bfe_u32 v4, v50, 16, 1
	v_lshrrev_b32_e32 v0, 16, v0
	v_add3_u32 v4, v50, v4, s91
	v_and_or_b32 v39, v4, s35, v0
	v_or_b32_e32 v0, s0, v34
	v_mul_u32_u24_e32 v0, 0xb00, v0
	v_lshlrev_b32_e32 v0, 1, v0
	v_lshl_add_u64 v[52:53], v[2:3], 0, v[0:1]
	v_bfe_u32 v0, v5, 16, 1
	v_add3_u32 v0, v5, v0, s91
	v_bfe_u32 v4, v27, 16, 1
	v_lshrrev_b32_e32 v0, 16, v0
	v_add3_u32 v4, v27, v4, s91
	global_store_dwordx4 v[52:53], v[36:39], off sc1
	v_readlane_b32 s5, v252, 1
	v_readlane_b32 s6, v252, 2
	v_and_or_b32 v36, v4, s35, v0
	v_bfe_u32 v0, v41, 16, 1
	v_add3_u32 v0, v41, v0, s91
	v_bfe_u32 v4, v43, 16, 1
	v_lshrrev_b32_e32 v0, 16, v0
	v_add3_u32 v4, v43, v4, s91
	v_and_or_b32 v37, v4, s35, v0
	v_bfe_u32 v0, v45, 16, 1
	v_add3_u32 v0, v45, v0, s91
	v_bfe_u32 v4, v47, 16, 1
	v_lshrrev_b32_e32 v0, 16, v0
	v_add3_u32 v4, v47, v4, s91
	v_and_or_b32 v38, v4, s35, v0
	v_bfe_u32 v0, v49, 16, 1
	v_add3_u32 v0, v49, v0, s91
	v_bfe_u32 v4, v51, 16, 1
	v_lshrrev_b32_e32 v0, 16, v0
	v_add3_u32 v4, v51, v4, s91
	v_and_or_b32 v39, v4, s35, v0
	v_or_b32_e32 v0, s0, v35
	v_mul_u32_u24_e32 v0, 0xb00, v0
	v_lshlrev_b32_e32 v0, 1, v0
	v_lshl_add_u64 v[2:3], v[2:3], 0, v[0:1]
	global_store_dwordx4 v[2:3], v[36:39], off sc1
	s_waitcnt lgkmcnt(0)
	v_readlane_b32 s7, v252, 3
	v_readlane_b32 s10, v252, 6
	v_readlane_b32 s11, v252, 7
	v_readlane_b32 s12, v252, 8
	v_readlane_b32 s13, v252, 9
	v_readlane_b32 s14, v252, 10
	v_readlane_b32 s15, v252, 11
	v_readlane_b32 s16, v252, 12
	v_readlane_b32 s17, v252, 13
	v_readlane_b32 s18, v252, 14
	v_readlane_b32 s19, v252, 15
	s_mov_b64 s[8:9], s[26:27]
	s_mov_b64 s[0:1], 0
; template <bool HASG>
; __device__ __forceinline__ void tr_item(const float* W, int K, int N, bf16* WT, int rowmode, const float* g, LAS float* scr, int item, int lane) {
;     const int nblk = N / 32, kb = item / nblk, nb = item % nblk, k0 = 64 * kb, n0 = 32 * nb;
;     const float* wp = W + (size_t)(k0 + (lane >> 5)) * N + n0 + (lane & 31);
;     const int c = lane & 7;
;     float v[32];
; #pragma unroll
;     for (int i = 0; i < 32; ++i) v[i] = wp[(size_t)(2 * i) * N];
;     f32x4 g0 = (f32x4){1.f, 1.f, 1.f, 1.f}, g1 = g0;
;     if (HASG) { g0 = *(const f32x4*)(g + k0 + 8 * c); g1 = *(const f32x4*)(g + k0 + 8 * c + 4); }
; __device__ __forceinline__ void convert_items(const Args& a, LAS unsigned char* lds, int l, int it_lo, int it_hi, int gw, int NGW, int wave, int lane) {
;     ...
;         if (r < I_G) { tr_item<true>(a.in[21] + o_gu, D, FF, wl + W_GU2, 2, a.in[19] + l * D, scr, r, lane); continue; } r -= I_G;
.LBB0_520:
	s_andn2_b64 vcc, exec, s[0:1]
	s_cbranch_vccnz .LBB0_522
	s_add_i32 s0, s28, 0xe480
	s_and_b32 s1, s0, 0xffff
	s_mul_i32 s1, s1, 0xba2f
	s_lshr_b32 s38, s1, 16
	s_lshr_b32 s1, s1, 22
	s_mulk_i32 s1, 0x58
	s_sub_i32 s0, s0, s1
	s_and_b32 s1, s38, 0xffc0
	v_or_b32_e32 v0, s1, v28
	v_mul_u32_u24_e32 v0, 0xb00, v0
	v_readlane_b32 s4, v252, 32
	s_and_b32 s39, s0, 0xffff
	v_lshlrev_b32_e32 v0, 2, v0
	v_readlane_b32 s14, v252, 42
	v_readlane_b32 s15, v252, 43
	v_readlane_b32 s5, v252, 33
	v_readlane_b32 s6, v252, 34
	v_readlane_b32 s7, v252, 35
	v_readlane_b32 s8, v252, 36
	v_readlane_b32 s9, v252, 37
	v_readlane_b32 s10, v252, 38
	v_readlane_b32 s11, v252, 39
	v_readlane_b32 s12, v252, 40
	v_readlane_b32 s13, v252, 41
	v_readlane_b32 s16, v252, 44
	v_readlane_b32 s17, v252, 45
	v_readlane_b32 s18, v252, 46
	v_readlane_b32 s19, v252, 47
	v_lshl_add_u64 v[2:3], s[14:15], 0, v[0:1]
	s_lshl_b32 s88, s39, 7
	v_readlane_b32 s4, v252, 0
	v_lshl_add_u64 v[2:3], v[2:3], 0, s[88:89]
	v_lshlrev_b32_e32 v0, 2, v6
	v_lshl_add_u64 v[2:3], v[2:3], 0, v[0:1]
	s_movk_i32 s4, 0x5000
	v_add_co_u32_e32 v4, vcc, s4, v2
	s_mov_b32 s4, 0x1b000
	s_nop 0
	v_addc_co_u32_e32 v5, vcc, 0, v3, vcc
	v_add_co_u32_e32 v26, vcc, s90, v2
	s_lshl_b32 s88, s1, 2
	s_nop 0
	v_addc_co_u32_e32 v27, vcc, 0, v3, vcc
	v_add_co_u32_e32 v36, vcc, s70, v2
	s_lshl_b32 s38, s0, 5
	s_nop 0
	v_addc_co_u32_e32 v37, vcc, 0, v3, vcc
	v_add_co_u32_e32 v38, vcc, s71, v2
	s_lshl_b32 s0, s0, 6
	s_nop 0
	v_addc_co_u32_e32 v39, vcc, 0, v3, vcc
	v_add_co_u32_e32 v40, vcc, s4, v2
	s_mov_b32 s4, 0x21000
	s_nop 0
	v_addc_co_u32_e32 v41, vcc, 0, v3, vcc
	v_add_co_u32_e32 v42, vcc, s4, v2
	s_mov_b32 s4, 0x26000
	s_nop 0
	v_addc_co_u32_e32 v43, vcc, 0, v3, vcc
	v_add_co_u32_e32 v44, vcc, s4, v2
	s_mov_b32 s4, 0x2c000
	s_nop 0
	v_addc_co_u32_e32 v45, vcc, 0, v3, vcc
	global_load_dword v0, v[2:3], off
	global_load_dword v48, v[4:5], off offset:2048
	global_load_dword v49, v[26:27], off
	global_load_dword v50, v[36:37], off offset:2048
	global_load_dword v51, v[38:39], off
	global_load_dword v52, v[40:41], off offset:2048
	global_load_dword v53, v[42:43], off
	global_load_dword v54, v[44:45], off offset:2048
	v_add_co_u32_e32 v4, vcc, s4, v2
	s_mov_b32 s4, 0x31000
	s_nop 0
	v_addc_co_u32_e32 v5, vcc, 0, v3, vcc
	v_add_co_u32_e32 v26, vcc, s4, v2
	s_mov_b32 s4, 0x37000
	s_nop 0
	v_addc_co_u32_e32 v27, vcc, 0, v3, vcc
	v_add_co_u32_e32 v36, vcc, s4, v2
	s_mov_b32 s4, 0x3c000
	s_nop 0
	v_addc_co_u32_e32 v37, vcc, 0, v3, vcc
	v_add_co_u32_e32 v38, vcc, s4, v2
	s_mov_b32 s4, 0x42000
	s_nop 0
	v_addc_co_u32_e32 v39, vcc, 0, v3, vcc
	v_add_co_u32_e32 v40, vcc, s4, v2
	s_mov_b32 s4, 0x47000
	s_nop 0
	v_addc_co_u32_e32 v41, vcc, 0, v3, vcc
	v_add_co_u32_e32 v42, vcc, s4, v2
	s_mov_b32 s4, 0x4d000
	s_nop 0
	v_addc_co_u32_e32 v43, vcc, 0, v3, vcc
	v_add_co_u32_e32 v44, vcc, s4, v2
	s_mov_b32 s4, 0x52000
	s_nop 0
	v_addc_co_u32_e32 v45, vcc, 0, v3, vcc
	v_add_co_u32_e32 v46, vcc, s4, v2
	s_mov_b32 s4, 0x58000
	s_nop 0
	v_addc_co_u32_e32 v47, vcc, 0, v3, vcc
	global_load_dword v55, v[4:5], off
	global_load_dword v56, v[26:27], off offset:2048
	global_load_dword v57, v[36:37], off
	global_load_dword v58, v[38:39], off offset:2048
	global_load_dword v59, v[40:41], off
	global_load_dword v60, v[42:43], off offset:2048
	global_load_dword v61, v[44:45], off
	global_load_dword v62, v[46:47], off offset:2048
	v_add_co_u32_e32 v4, vcc, s4, v2
	s_mov_b32 s4, 0x5d000
	s_nop 0
	v_addc_co_u32_e32 v5, vcc, 0, v3, vcc
	v_add_co_u32_e32 v26, vcc, s4, v2
	s_mov_b32 s4, 0x63000
	s_nop 0
	v_addc_co_u32_e32 v27, vcc, 0, v3, vcc
	v_add_co_u32_e32 v36, vcc, s4, v2
	s_mov_b32 s4, 0x68000
	s_nop 0
	v_addc_co_u32_e32 v37, vcc, 0, v3, vcc
	v_add_co_u32_e32 v38, vcc, s4, v2
	s_mov_b32 s4, 0x6e000
	s_nop 0
	v_addc_co_u32_e32 v39, vcc, 0, v3, vcc
	v_add_co_u32_e32 v40, vcc, s4, v2
	s_mov_b32 s4, 0x73000
	s_nop 0
	v_addc_co_u32_e32 v41, vcc, 0, v3, vcc
	v_add_co_u32_e32 v42, vcc, s4, v2
	s_mov_b32 s4, 0x79000
	s_nop 0
	v_addc_co_u32_e32 v43, vcc, 0, v3, vcc
	v_add_co_u32_e32 v44, vcc, s4, v2
	s_mov_b32 s4, 0x7e000
	s_nop 0
	v_addc_co_u32_e32 v45, vcc, 0, v3, vcc
	v_add_co_u32_e32 v46, vcc, s4, v2
	s_mov_b32 s4, 0x84000
	s_nop 0
	v_addc_co_u32_e32 v47, vcc, 0, v3, vcc
	global_load_dword v63, v[4:5], off
	global_load_dword v64, v[26:27], off offset:2048
	global_load_dword v65, v[36:37], off
	global_load_dword v66, v[38:39], off offset:2048
	global_load_dword v67, v[40:41], off
	global_load_dword v68, v[42:43], off offset:2048
	global_load_dword v69, v[44:45], off
	s_nop 0
	global_load_dword v46, v[46:47], off offset:2048
	v_add_co_u32_e32 v4, vcc, s4, v2
	s_mov_b32 s4, 0x89000
	s_nop 0
	v_addc_co_u32_e32 v5, vcc, 0, v3, vcc
	v_add_co_u32_e32 v26, vcc, s4, v2
	s_mov_b32 s4, 0x8f000
	s_nop 0
	v_addc_co_u32_e32 v27, vcc, 0, v3, vcc
	v_add_co_u32_e32 v36, vcc, s4, v2
	s_mov_b32 s4, 0x94000
	s_nop 0
	v_addc_co_u32_e32 v37, vcc, 0, v3, vcc
	v_add_co_u32_e32 v38, vcc, s4, v2
	s_mov_b32 s4, 0x9a000
	s_nop 0
	v_addc_co_u32_e32 v39, vcc, 0, v3, vcc
	v_add_co_u32_e32 v40, vcc, s4, v2
	s_mov_b32 s4, 0x9f000
	s_nop 0
	v_addc_co_u32_e32 v41, vcc, 0, v3, vcc
	v_add_co_u32_e32 v42, vcc, s4, v2
	s_mov_b32 s4, 0xa5000
	s_nop 0
	v_addc_co_u32_e32 v43, vcc, 0, v3, vcc
	v_add_co_u32_e32 v44, vcc, s4, v2
	s_mov_b32 s4, 0xaa000
	s_nop 0
	v_addc_co_u32_e32 v45, vcc, 0, v3, vcc
	v_add_co_u32_e32 v2, vcc, s4, v2
	s_and_b32 s0, s0, 0x1f00
	s_nop 0
	v_addc_co_u32_e32 v3, vcc, 0, v3, vcc
	global_load_dword v47, v[4:5], off
	s_nop 0
	global_load_dword v26, v[26:27], off offset:2048
	s_nop 0
	global_load_dword v27, v[36:37], off
	global_load_dword v70, v[38:39], off offset:2048
	s_nop 0
	global_load_dword v40, v[40:41], off
	s_nop 0
	global_load_dword v41, v[42:43], off offset:2048
	s_nop 0
	global_load_dword v42, v[44:45], off
	global_load_dword v43, v[2:3], off offset:2048
	v_lshl_add_u64 v[2:3], v[20:21], 0, s[88:89]
	global_load_dwordx4 v[36:39], v[2:3], off
	s_nop 0
	global_load_dwordx4 v[2:5], v[2:3], off offset:16
	s_waitcnt vmcnt(32)
; #define LAS __attribute__((address_space(3)))
; __device__ __forceinline__ unsigned pk2(float lo, float hi) { return f2bf(lo) | (f2bf(hi) << 16); }
; #define LDS_WAVE_SYNC() asm volatile("s_waitcnt lgkmcnt(0)" ::: "memory")
; template <bool HASG>
; __device__ __forceinline__ void tr_item(const float* W, int K, int N, bf16* WT, int rowmode, const float* g, LAS float* scr, int item, int lane) {
;     ...
;     for (int i = 0; i < 32; ++i) scr[(2 * i + (lane >> 5)) * 33 + (lane & 31)] = v[i];
;     LDS_WAVE_SYNC();
;     const int drow0 = rowmode == 0 ? n0 : ((n0 >> 7) * 256 + (n0 & 127) + (rowmode == 2 ? 128 : 0));
; #pragma unroll
;     for (int j = 0; j < 4; ++j) { const int n = (lane >> 3) + 8 * j; const LAS float* s = scr + (8 * c) * 33 + n;
;         u32x4 o; o.x = pk2(s[0 * 33] * g0.x, s[1 * 33] * g0.y); o.y = pk2(s[2 * 33] * g0.z, s[3 * 33] * g0.w);
;         o.z = pk2(s[4 * 33] * g1.x, s[5 * 33] * g1.y); o.w = pk2(s[6 * 33] * g1.z, s[7 * 33] * g1.w);
;         *(u32x4*)(WT + (size_t)(drow0 + n) * K + k0 + 8 * c) = o; }
	ds_write2_b32 v29, v0, v48 offset1:66
	s_waitcnt vmcnt(30)
	ds_write2_b32 v29, v49, v50 offset0:132 offset1:198
	v_add_u32_e32 v0, 0x400, v29
	s_waitcnt vmcnt(28)
	ds_write2_b32 v0, v51, v52 offset0:8 offset1:74
	s_waitcnt vmcnt(26)
	ds_write2_b32 v0, v53, v54 offset0:140 offset1:206
	v_add_u32_e32 v0, 0x800, v29
	s_waitcnt vmcnt(24)
	ds_write2_b32 v0, v55, v56 offset0:16 offset1:82
	s_waitcnt vmcnt(22)
	ds_write2_b32 v0, v57, v58 offset0:148 offset1:214
	v_add_u32_e32 v0, 0xc00, v29
	s_waitcnt vmcnt(20)
	ds_write2_b32 v0, v59, v60 offset0:24 offset1:90
	s_waitcnt vmcnt(18)
	ds_write2_b32 v0, v61, v62 offset0:156 offset1:222
	v_add_u32_e32 v0, 0x1000, v29
	s_waitcnt vmcnt(16)
	ds_write2_b32 v0, v63, v64 offset0:32 offset1:98
	s_waitcnt vmcnt(14)
	ds_write2_b32 v0, v65, v66 offset0:164 offset1:230
	v_add_u32_e32 v0, 0x1400, v29
	s_waitcnt vmcnt(12)
	ds_write2_b32 v0, v67, v68 offset0:40 offset1:106
	s_waitcnt vmcnt(10)
	ds_write2_b32 v0, v69, v46 offset0:172 offset1:238
	v_add_u32_e32 v0, 0x1800, v29
	s_waitcnt vmcnt(8)
	ds_write2_b32 v0, v47, v26 offset0:48 offset1:114
	s_waitcnt vmcnt(6)
	ds_write2_b32 v0, v27, v70 offset0:180 offset1:246
	v_add_u32_e32 v0, 0x1c00, v29
	s_waitcnt vmcnt(4)
	ds_write2_b32 v0, v40, v41 offset0:56 offset1:122
	s_waitcnt vmcnt(2)
	ds_write2_b32 v0, v42, v43 offset0:188 offset1:254
	s_waitcnt lgkmcnt(0)
	ds_read2_b32 v[44:45], v31 offset0:33 offset1:41
	ds_read2_b32 v[46:47], v31 offset1:8
	ds_read2_b32 v[48:49], v31 offset0:66 offset1:74
	ds_read2_b32 v[50:51], v31 offset0:99 offset1:107
	ds_read2_b32 v[54:55], v31 offset0:132 offset1:140
	ds_read2_b32 v[56:57], v31 offset0:165 offset1:173
	ds_read2_b32 v[58:59], v31 offset0:198 offset1:206
	ds_read2_b32 v[60:61], v31 offset0:231 offset1:239
	s_waitcnt vmcnt(1)
	v_mov_b32_e32 v52, v36
	v_mov_b32_e32 v53, v38
	v_mov_b32_e32 v38, v37
	s_waitcnt lgkmcnt(7)
	v_mov_b32_e32 v36, v44
	s_waitcnt lgkmcnt(4)
	v_mov_b32_e32 v37, v50
	s_waitcnt vmcnt(0)
	v_mov_b32_e32 v62, v2
	v_mov_b32_e32 v63, v4
	v_mov_b32_e32 v4, v3
	s_waitcnt lgkmcnt(2)
	v_mov_b32_e32 v2, v56
	s_waitcnt lgkmcnt(0)
	v_mov_b32_e32 v3, v60
	v_mov_b32_e32 v40, v46
	v_mov_b32_e32 v41, v48
	v_pk_mul_f32 v[36:37], v[38:39], v[36:37]
	v_mov_b32_e32 v42, v54
	v_mov_b32_e32 v43, v58
	v_pk_mul_f32 v[2:3], v[4:5], v[2:3]
	v_pk_mul_f32 v[40:41], v[52:53], v[40:41]
	v_pk_mul_f32 v[42:43], v[62:63], v[42:43]
	v_bfe_u32 v44, v2, 16, 1
	v_bfe_u32 v46, v37, 16, 1
	v_bfe_u32 v48, v36, 16, 1
	s_and_b32 s38, s38, 0x60
	v_bfe_u32 v0, v3, 16, 1
	v_add3_u32 v36, v36, v48, s91
	v_add3_u32 v37, v37, v46, s91
	v_add3_u32 v2, v2, v44, s91
	v_bfe_u32 v44, v41, 16, 1
	v_bfe_u32 v46, v42, 16, 1
	v_bfe_u32 v48, v43, 16, 1
	s_or_b32 s0, s38, s0
	v_add3_u32 v0, v3, v0, s91
	v_bfe_u32 v3, v40, 16, 1
	v_add3_u32 v43, v43, v48, s91
	v_add3_u32 v42, v42, v46, s91
	v_add3_u32 v41, v41, v44, s91
	s_bitset1_b32 s0, 7
	v_add3_u32 v3, v40, v3, s91
	v_lshrrev_b32_e32 v40, 16, v41
	v_lshrrev_b32_e32 v41, 16, v42
	v_lshrrev_b32_e32 v42, 16, v43
	s_lshl_b32 s88, s1, 1
	v_and_or_b32 v43, v0, s35, v42
	v_or_b32_e32 v0, s0, v30
	v_lshl_add_u64 v[26:27], v[10:11], 0, s[88:89]
	v_lshrrev_b32_e32 v3, 16, v3
	v_lshlrev_b32_e32 v0, 11, v0
	v_mov_b32_e32 v50, v45
	v_and_or_b32 v42, v2, s35, v41
	v_and_or_b32 v41, v37, s35, v40
	v_and_or_b32 v40, v36, s35, v3
	v_lshl_add_u64 v[2:3], v[26:27], 0, v[0:1]
	v_pk_mul_f32 v[36:37], v[38:39], v[50:51]
	v_mov_b32_e32 v58, v55
	global_store_dwordx4 v[2:3], v[40:43], off sc1
	v_mov_b32_e32 v60, v57
	v_bfe_u32 v46, v36, 16, 1
	v_pk_mul_f32 v[40:41], v[62:63], v[58:59]
	v_mov_b32_e32 v48, v47
	v_pk_mul_f32 v[42:43], v[4:5], v[60:61]
	v_add3_u32 v36, v36, v46, s91
	v_bfe_u32 v46, v41, 16, 1
	v_pk_mul_f32 v[2:3], v[52:53], v[48:49]
	v_bfe_u32 v0, v43, 16, 1
	v_bfe_u32 v44, v42, 16, 1
	v_bfe_u32 v45, v37, 16, 1
	v_add3_u32 v41, v41, v46, s91
	v_add3_u32 v37, v37, v45, s91
	v_add3_u32 v42, v42, v44, s91
	v_add3_u32 v0, v43, v0, s91
	v_bfe_u32 v43, v2, 16, 1
	v_bfe_u32 v44, v3, 16, 1
	v_bfe_u32 v45, v40, 16, 1
	v_lshrrev_b32_e32 v41, 16, v41
	v_add3_u32 v40, v40, v45, s91
	v_add3_u32 v3, v3, v44, s91
	v_add3_u32 v2, v2, v43, s91
	v_and_or_b32 v43, v0, s35, v41
	v_or_b32_e32 v0, s0, v33
	v_lshrrev_b32_e32 v2, 16, v2
	v_lshrrev_b32_e32 v3, 16, v3
	v_lshrrev_b32_e32 v40, 16, v40
	v_lshlrev_b32_e32 v0, 11, v0
	v_and_or_b32 v42, v42, s35, v40
	v_and_or_b32 v41, v37, s35, v3
	v_and_or_b32 v40, v36, s35, v2
	v_lshl_add_u64 v[2:3], v[26:27], 0, v[0:1]
	ds_read2_b32 v[36:37], v31 offset0:16 offset1:24
	ds_read2_b32 v[44:45], v31 offset0:82 offset1:90
	global_store_dwordx4 v[2:3], v[40:43], off sc1
	ds_read2_b32 v[2:3], v31 offset0:49 offset1:57
	ds_read2_b32 v[46:47], v31 offset0:115 offset1:123
	ds_read2_b32 v[48:49], v31 offset0:148 offset1:156
	ds_read2_b32 v[50:51], v31 offset0:214 offset1:222
	ds_read2_b32 v[54:55], v31 offset0:181 offset1:189
	ds_read2_b32 v[56:57], v31 offset0:247 offset1:255
	s_waitcnt lgkmcnt(7)
; #define LAS __attribute__((address_space(3)))
; __device__ __forceinline__ unsigned pk2(float lo, float hi) { return f2bf(lo) | (f2bf(hi) << 16); }
; #define LDS_WAVE_SYNC() asm volatile("s_waitcnt lgkmcnt(0)" ::: "memory")
; template <bool HASG>
; __device__ __forceinline__ void tr_item(const float* W, int K, int N, bf16* WT, int rowmode, const float* g, LAS float* scr, int item, int lane) {
;     ...
;     for (int j = 0; j < 4; ++j) { const int n = (lane >> 3) + 8 * j; const LAS float* s = scr + (8 * c) * 33 + n;
;         u32x4 o; o.x = pk2(s[0 * 33] * g0.x, s[1 * 33] * g0.y); o.y = pk2(s[2 * 33] * g0.z, s[3 * 33] * g0.w);
;         o.z = pk2(s[4 * 33] * g1.x, s[5 * 33] * g1.y); o.w = pk2(s[6 * 33] * g1.z, s[7 * 33] * g1.w);
;         *(u32x4*)(WT + (size_t)(drow0 + n) * K + k0 + 8 * c) = o; }
;     LDS_WAVE_SYNC();
	v_mov_b32_e32 v40, v36
	s_waitcnt lgkmcnt(5)
	v_mov_b32_e32 v42, v2
	s_waitcnt lgkmcnt(4)
	v_mov_b32_e32 v43, v46
	s_waitcnt lgkmcnt(3)
	v_mov_b32_e32 v58, v48
	s_waitcnt lgkmcnt(2)
	v_mov_b32_e32 v59, v50
	v_mov_b32_e32 v41, v44
	v_pk_mul_f32 v[42:43], v[38:39], v[42:43]
	v_pk_mul_f32 v[58:59], v[62:63], v[58:59]
	s_waitcnt lgkmcnt(1)
	v_mov_b32_e32 v60, v54
	s_waitcnt lgkmcnt(0)
	v_mov_b32_e32 v61, v56
	v_pk_mul_f32 v[40:41], v[52:53], v[40:41]
	v_pk_mul_f32 v[60:61], v[4:5], v[60:61]
	v_bfe_u32 v36, v43, 16, 1
	v_bfe_u32 v48, v59, 16, 1
	v_bfe_u32 v0, v61, 16, 1
	v_bfe_u32 v44, v42, 16, 1
	v_add3_u32 v36, v43, v36, s91
	v_bfe_u32 v43, v41, 16, 1
	v_add3_u32 v48, v59, v48, s91
	v_add3_u32 v44, v42, v44, s91
	v_add3_u32 v0, v61, v0, s91
	v_bfe_u32 v42, v40, 16, 1
	v_bfe_u32 v46, v58, 16, 1
	v_add3_u32 v41, v41, v43, s91
	v_lshrrev_b32_e32 v43, 16, v48
	v_bfe_u32 v2, v60, 16, 1
	v_add3_u32 v46, v58, v46, s91
	v_add3_u32 v40, v40, v42, s91
	v_and_or_b32 v43, v0, s35, v43
	v_or_b32_e32 v0, s0, v34
	v_add3_u32 v2, v60, v2, s91
	v_lshrrev_b32_e32 v40, 16, v40
	v_lshrrev_b32_e32 v41, 16, v41
	v_lshrrev_b32_e32 v42, 16, v46
	v_lshlrev_b32_e32 v0, 11, v0
	v_mov_b32_e32 v46, v3
	v_mov_b32_e32 v56, v55
	v_and_or_b32 v42, v2, s35, v42
	v_and_or_b32 v41, v36, s35, v41
	v_and_or_b32 v40, v44, s35, v40
	v_lshl_add_u64 v[58:59], v[26:27], 0, v[0:1]
	v_mov_b32_e32 v44, v37
	v_pk_mul_f32 v[2:3], v[38:39], v[46:47]
	v_mov_b32_e32 v50, v49
	v_pk_mul_f32 v[4:5], v[4:5], v[56:57]
	global_store_dwordx4 v[58:59], v[40:43], off sc1
	v_pk_mul_f32 v[36:37], v[52:53], v[44:45]
	v_pk_mul_f32 v[38:39], v[62:63], v[50:51]
	v_bfe_u32 v0, v5, 16, 1
	v_bfe_u32 v42, v2, 16, 1
	v_add3_u32 v2, v2, v42, s91
	v_add3_u32 v0, v5, v0, s91
	v_bfe_u32 v5, v36, 16, 1
	v_bfe_u32 v42, v39, 16, 1
	v_bfe_u32 v40, v4, 16, 1
	v_bfe_u32 v41, v3, 16, 1
	v_add3_u32 v39, v39, v42, s91
	v_add3_u32 v5, v36, v5, s91
	v_add3_u32 v3, v3, v41, s91
	v_add3_u32 v4, v4, v40, s91
	v_bfe_u32 v40, v37, 16, 1
	v_bfe_u32 v41, v38, 16, 1
	v_lshrrev_b32_e32 v36, 16, v5
	v_lshrrev_b32_e32 v5, 16, v39
	v_add3_u32 v38, v38, v41, s91
	v_add3_u32 v37, v37, v40, s91
	v_and_or_b32 v5, v0, s35, v5
	v_or_b32_e32 v0, s0, v35
	v_lshrrev_b32_e32 v37, 16, v37
	v_lshrrev_b32_e32 v38, 16, v38
	v_lshlrev_b32_e32 v0, 11, v0
	v_and_or_b32 v4, v4, s35, v38
	v_and_or_b32 v3, v3, s35, v37
	v_and_or_b32 v2, v2, s35, v36
	v_lshl_add_u64 v[26:27], v[26:27], 0, v[0:1]
	global_store_dwordx4 v[26:27], v[2:5], off sc1
	s_waitcnt lgkmcnt(0)
	v_readlane_b32 s8, v252, 4
	v_readlane_b32 s9, v252, 5
	s_mov_b64 s[8:9], s[26:27]
	v_readlane_b32 s5, v252, 1
	v_readlane_b32 s6, v252, 2
	v_readlane_b32 s7, v252, 3
	v_readlane_b32 s10, v252, 6
	v_readlane_b32 s11, v252, 7
	v_readlane_b32 s12, v252, 8
	v_readlane_b32 s13, v252, 9
	v_readlane_b32 s14, v252, 10
	v_readlane_b32 s15, v252, 11
	v_readlane_b32 s16, v252, 12
	v_readlane_b32 s17, v252, 13
	v_readlane_b32 s18, v252, 14
	v_readlane_b32 s19, v252, 15

; template <bool HASG>
; __device__ __forceinline__ void tr_item(const float* W, int K, int N, bf16* WT, int rowmode, const float* g, LAS float* scr, int item, int lane) {
;     const int nblk = N / 32, kb = item / nblk, nb = item % nblk, k0 = 64 * kb, n0 = 32 * nb;
;     const float* wp = W + (size_t)(k0 + (lane >> 5)) * N + n0 + (lane & 31);
;     const int c = lane & 7;
;     float v[32];
; #pragma unroll
;     for (int i = 0; i < 32; ++i) v[i] = wp[(size_t)(2 * i) * N];
;     f32x4 g0 = (f32x4){1.f, 1.f, 1.f, 1.f}, g1 = g0;
;     if (HASG) { g0 = *(const f32x4*)(g + k0 + 8 * c); g1 = *(const f32x4*)(g + k0 + 8 * c + 4); }
; __device__ __forceinline__ void convert_items(const Args& a, LAS unsigned char* lds, int l, int it_lo, int it_hi, int gw, int NGW, int wave, int lane) {
;     ...
;         if (r < I_G) { tr_item<true>(a.in[20] + o_gu, D, FF, wl + W_GU2, 1, a.in[19] + l * D, scr, r, lane); continue; } r -= I_G;
.LBB0_523:
	s_andn2_b64 vcc, exec, s[0:1]
	s_cbranch_vccnz .LBB0_525
	s_add_i32 s0, s28, 0xea00
	s_and_b32 s1, s0, 0xffff
	s_mul_i32 s1, s1, 0xba2f
	s_lshr_b32 s38, s1, 16
	s_lshr_b32 s1, s1, 22
	s_mulk_i32 s1, 0x58
	s_sub_i32 s0, s0, s1
	s_and_b32 s1, s38, 0xffc0
	v_or_b32_e32 v0, s1, v28
	v_mul_u32_u24_e32 v0, 0xb00, v0
	v_readlane_b32 s4, v252, 32
	s_and_b32 s39, s0, 0xffff
	v_lshlrev_b32_e32 v0, 2, v0
	v_readlane_b32 s12, v252, 40
	v_readlane_b32 s13, v252, 41
	v_readlane_b32 s5, v252, 33
	v_readlane_b32 s6, v252, 34
	v_readlane_b32 s7, v252, 35
	v_readlane_b32 s8, v252, 36
	v_readlane_b32 s9, v252, 37
	v_readlane_b32 s10, v252, 38
	v_readlane_b32 s11, v252, 39
	v_readlane_b32 s14, v252, 42
	v_readlane_b32 s15, v252, 43
	v_readlane_b32 s16, v252, 44
	v_readlane_b32 s17, v252, 45
	v_readlane_b32 s18, v252, 46
	v_readlane_b32 s19, v252, 47
	v_lshl_add_u64 v[2:3], s[12:13], 0, v[0:1]
	s_lshl_b32 s88, s39, 7
	v_readlane_b32 s4, v252, 0
	v_lshl_add_u64 v[2:3], v[2:3], 0, s[88:89]
	v_lshlrev_b32_e32 v0, 2, v6
	v_lshl_add_u64 v[2:3], v[2:3], 0, v[0:1]
	s_movk_i32 s4, 0x5000
	v_add_co_u32_e32 v4, vcc, s4, v2
	s_mov_b32 s4, 0x1b000
	s_nop 0
	v_addc_co_u32_e32 v5, vcc, 0, v3, vcc
	v_add_co_u32_e32 v26, vcc, s90, v2
	s_lshl_b32 s88, s1, 2
	s_nop 0
	v_addc_co_u32_e32 v27, vcc, 0, v3, vcc
	v_add_co_u32_e32 v36, vcc, s70, v2
	s_lshl_b32 s38, s0, 5
	s_nop 0
	v_addc_co_u32_e32 v37, vcc, 0, v3, vcc
	v_add_co_u32_e32 v38, vcc, s71, v2
	s_lshl_b32 s0, s0, 6
	s_nop 0
	v_addc_co_u32_e32 v39, vcc, 0, v3, vcc
	v_add_co_u32_e32 v40, vcc, s4, v2
	s_mov_b32 s4, 0x21000
	s_nop 0
	v_addc_co_u32_e32 v41, vcc, 0, v3, vcc
	v_add_co_u32_e32 v42, vcc, s4, v2
	s_mov_b32 s4, 0x26000
	s_nop 0
	v_addc_co_u32_e32 v43, vcc, 0, v3, vcc
	v_add_co_u32_e32 v44, vcc, s4, v2
	s_mov_b32 s4, 0x2c000
	s_nop 0
	v_addc_co_u32_e32 v45, vcc, 0, v3, vcc
	global_load_dword v0, v[2:3], off
	global_load_dword v48, v[4:5], off offset:2048
	global_load_dword v49, v[26:27], off
	global_load_dword v50, v[36:37], off offset:2048
	global_load_dword v51, v[38:39], off
	global_load_dword v52, v[40:41], off offset:2048
	global_load_dword v53, v[42:43], off
	global_load_dword v54, v[44:45], off offset:2048
	v_add_co_u32_e32 v4, vcc, s4, v2
	s_mov_b32 s4, 0x31000
	s_nop 0
	v_addc_co_u32_e32 v5, vcc, 0, v3, vcc
	v_add_co_u32_e32 v26, vcc, s4, v2
	s_mov_b32 s4, 0x37000
	s_nop 0
	v_addc_co_u32_e32 v27, vcc, 0, v3, vcc
	v_add_co_u32_e32 v36, vcc, s4, v2
	s_mov_b32 s4, 0x3c000
	s_nop 0
	v_addc_co_u32_e32 v37, vcc, 0, v3, vcc
	v_add_co_u32_e32 v38, vcc, s4, v2
	s_mov_b32 s4, 0x42000
	s_nop 0
	v_addc_co_u32_e32 v39, vcc, 0, v3, vcc
	v_add_co_u32_e32 v40, vcc, s4, v2
	s_mov_b32 s4, 0x47000
	s_nop 0
	v_addc_co_u32_e32 v41, vcc, 0, v3, vcc
	v_add_co_u32_e32 v42, vcc, s4, v2
	s_mov_b32 s4, 0x4d000
	s_nop 0
	v_addc_co_u32_e32 v43, vcc, 0, v3, vcc
	v_add_co_u32_e32 v44, vcc, s4, v2
	s_mov_b32 s4, 0x52000
	s_nop 0
	v_addc_co_u32_e32 v45, vcc, 0, v3, vcc
	v_add_co_u32_e32 v46, vcc, s4, v2
	s_mov_b32 s4, 0x58000
	s_nop 0
	v_addc_co_u32_e32 v47, vcc, 0, v3, vcc
	global_load_dword v55, v[4:5], off
	global_load_dword v56, v[26:27], off offset:2048
	global_load_dword v57, v[36:37], off
	global_load_dword v58, v[38:39], off offset:2048
	global_load_dword v59, v[40:41], off
	global_load_dword v60, v[42:43], off offset:2048
	global_load_dword v61, v[44:45], off
	global_load_dword v62, v[46:47], off offset:2048
	v_add_co_u32_e32 v4, vcc, s4, v2
	s_mov_b32 s4, 0x5d000
	s_nop 0
	v_addc_co_u32_e32 v5, vcc, 0, v3, vcc
	v_add_co_u32_e32 v26, vcc, s4, v2
	s_mov_b32 s4, 0x63000
	s_nop 0
	v_addc_co_u32_e32 v27, vcc, 0, v3, vcc
	v_add_co_u32_e32 v36, vcc, s4, v2
	s_mov_b32 s4, 0x68000
	s_nop 0
	v_addc_co_u32_e32 v37, vcc, 0, v3, vcc
	v_add_co_u32_e32 v38, vcc, s4, v2
	s_mov_b32 s4, 0x6e000
	s_nop 0
	v_addc_co_u32_e32 v39, vcc, 0, v3, vcc
	v_add_co_u32_e32 v40, vcc, s4, v2
	s_mov_b32 s4, 0x73000
	s_nop 0
	v_addc_co_u32_e32 v41, vcc, 0, v3, vcc
	v_add_co_u32_e32 v42, vcc, s4, v2
	s_mov_b32 s4, 0x79000
	s_nop 0
	v_addc_co_u32_e32 v43, vcc, 0, v3, vcc
	v_add_co_u32_e32 v44, vcc, s4, v2
	s_mov_b32 s4, 0x7e000
	s_nop 0
	v_addc_co_u32_e32 v45, vcc, 0, v3, vcc
	v_add_co_u32_e32 v46, vcc, s4, v2
	s_mov_b32 s4, 0x84000
	s_nop 0
	v_addc_co_u32_e32 v47, vcc, 0, v3, vcc
	global_load_dword v63, v[4:5], off
	global_load_dword v64, v[26:27], off offset:2048
	global_load_dword v65, v[36:37], off
	global_load_dword v66, v[38:39], off offset:2048
	global_load_dword v67, v[40:41], off
	global_load_dword v68, v[42:43], off offset:2048
	global_load_dword v69, v[44:45], off
	s_nop 0
	global_load_dword v46, v[46:47], off offset:2048
	v_add_co_u32_e32 v4, vcc, s4, v2
	s_mov_b32 s4, 0x89000
	s_nop 0
	v_addc_co_u32_e32 v5, vcc, 0, v3, vcc
	v_add_co_u32_e32 v26, vcc, s4, v2
	s_mov_b32 s4, 0x8f000
	s_nop 0
	v_addc_co_u32_e32 v27, vcc, 0, v3, vcc
	v_add_co_u32_e32 v36, vcc, s4, v2
	s_mov_b32 s4, 0x94000
	s_nop 0
	v_addc_co_u32_e32 v37, vcc, 0, v3, vcc
	v_add_co_u32_e32 v38, vcc, s4, v2
	s_mov_b32 s4, 0x9a000
	s_nop 0
	v_addc_co_u32_e32 v39, vcc, 0, v3, vcc
	v_add_co_u32_e32 v40, vcc, s4, v2
	s_mov_b32 s4, 0x9f000
	s_nop 0
	v_addc_co_u32_e32 v41, vcc, 0, v3, vcc
	v_add_co_u32_e32 v42, vcc, s4, v2
	s_mov_b32 s4, 0xa5000
	s_nop 0
	v_addc_co_u32_e32 v43, vcc, 0, v3, vcc
	v_add_co_u32_e32 v44, vcc, s4, v2
	s_mov_b32 s4, 0xaa000
	s_nop 0
	v_addc_co_u32_e32 v45, vcc, 0, v3, vcc
	v_add_co_u32_e32 v2, vcc, s4, v2
	s_and_b32 s0, s0, 0x1f00
	s_nop 0
	v_addc_co_u32_e32 v3, vcc, 0, v3, vcc
	global_load_dword v47, v[4:5], off
	s_nop 0
	global_load_dword v26, v[26:27], off offset:2048
	s_nop 0
	global_load_dword v27, v[36:37], off
	global_load_dword v70, v[38:39], off offset:2048
	s_nop 0
	global_load_dword v40, v[40:41], off
	s_nop 0
	global_load_dword v41, v[42:43], off offset:2048
	s_nop 0
	global_load_dword v42, v[44:45], off
	global_load_dword v43, v[2:3], off offset:2048
	v_lshl_add_u64 v[2:3], v[20:21], 0, s[88:89]
	global_load_dwordx4 v[36:39], v[2:3], off
	s_nop 0
	global_load_dwordx4 v[2:5], v[2:3], off offset:16
	s_waitcnt vmcnt(32)
; #define LAS __attribute__((address_space(3)))
; __device__ __forceinline__ unsigned pk2(float lo, float hi) { return f2bf(lo) | (f2bf(hi) << 16); }
; #define LDS_WAVE_SYNC() asm volatile("s_waitcnt lgkmcnt(0)" ::: "memory")
; template <bool HASG>
; __device__ __forceinline__ void tr_item(const float* W, int K, int N, bf16* WT, int rowmode, const float* g, LAS float* scr, int item, int lane) {
;     ...
;     for (int i = 0; i < 32; ++i) scr[(2 * i + (lane >> 5)) * 33 + (lane & 31)] = v[i];
;     LDS_WAVE_SYNC();
;     const int drow0 = rowmode == 0 ? n0 : ((n0 >> 7) * 256 + (n0 & 127) + (rowmode == 2 ? 128 : 0));
; #pragma unroll
;     for (int j = 0; j < 4; ++j) { const int n = (lane >> 3) + 8 * j; const LAS float* s = scr + (8 * c) * 33 + n;
;         u32x4 o; o.x = pk2(s[0 * 33] * g0.x, s[1 * 33] * g0.y); o.y = pk2(s[2 * 33] * g0.z, s[3 * 33] * g0.w);
;         o.z = pk2(s[4 * 33] * g1.x, s[5 * 33] * g1.y); o.w = pk2(s[6 * 33] * g1.z, s[7 * 33] * g1.w);
;         *(u32x4*)(WT + (size_t)(drow0 + n) * K + k0 + 8 * c) = o; }
	ds_write2_b32 v29, v0, v48 offset1:66
	s_waitcnt vmcnt(30)
	ds_write2_b32 v29, v49, v50 offset0:132 offset1:198
	v_add_u32_e32 v0, 0x400, v29
	s_waitcnt vmcnt(28)
	ds_write2_b32 v0, v51, v52 offset0:8 offset1:74
	s_waitcnt vmcnt(26)
	ds_write2_b32 v0, v53, v54 offset0:140 offset1:206
	v_add_u32_e32 v0, 0x800, v29
	s_waitcnt vmcnt(24)
	ds_write2_b32 v0, v55, v56 offset0:16 offset1:82
	s_waitcnt vmcnt(22)
	ds_write2_b32 v0, v57, v58 offset0:148 offset1:214
	v_add_u32_e32 v0, 0xc00, v29
	s_waitcnt vmcnt(20)
	ds_write2_b32 v0, v59, v60 offset0:24 offset1:90
	s_waitcnt vmcnt(18)
	ds_write2_b32 v0, v61, v62 offset0:156 offset1:222
	v_add_u32_e32 v0, 0x1000, v29
	s_waitcnt vmcnt(16)
	ds_write2_b32 v0, v63, v64 offset0:32 offset1:98
	s_waitcnt vmcnt(14)
	ds_write2_b32 v0, v65, v66 offset0:164 offset1:230
	v_add_u32_e32 v0, 0x1400, v29
	s_waitcnt vmcnt(12)
	ds_write2_b32 v0, v67, v68 offset0:40 offset1:106
	s_waitcnt vmcnt(10)
	ds_write2_b32 v0, v69, v46 offset0:172 offset1:238
	v_add_u32_e32 v0, 0x1800, v29
	s_waitcnt vmcnt(8)
	ds_write2_b32 v0, v47, v26 offset0:48 offset1:114
	s_waitcnt vmcnt(6)
	ds_write2_b32 v0, v27, v70 offset0:180 offset1:246
	v_add_u32_e32 v0, 0x1c00, v29
	s_waitcnt vmcnt(4)
	ds_write2_b32 v0, v40, v41 offset0:56 offset1:122
	s_waitcnt vmcnt(2)
	ds_write2_b32 v0, v42, v43 offset0:188 offset1:254
	s_waitcnt lgkmcnt(0)
	ds_read2_b32 v[44:45], v31 offset0:33 offset1:41
	ds_read2_b32 v[46:47], v31 offset1:8
	ds_read2_b32 v[48:49], v31 offset0:66 offset1:74
	ds_read2_b32 v[50:51], v31 offset0:99 offset1:107
	ds_read2_b32 v[54:55], v31 offset0:132 offset1:140
	ds_read2_b32 v[56:57], v31 offset0:165 offset1:173
	ds_read2_b32 v[58:59], v31 offset0:198 offset1:206
	ds_read2_b32 v[60:61], v31 offset0:231 offset1:239
	s_waitcnt vmcnt(1)
	v_mov_b32_e32 v52, v36
	v_mov_b32_e32 v53, v38
	v_mov_b32_e32 v38, v37
	s_waitcnt lgkmcnt(7)
	v_mov_b32_e32 v36, v44
	s_waitcnt lgkmcnt(4)
	v_mov_b32_e32 v37, v50
	s_waitcnt vmcnt(0)
	v_mov_b32_e32 v62, v2
	v_mov_b32_e32 v63, v4
	v_mov_b32_e32 v4, v3
	s_waitcnt lgkmcnt(2)
	v_mov_b32_e32 v2, v56
	s_waitcnt lgkmcnt(0)
	v_mov_b32_e32 v3, v60
	v_mov_b32_e32 v40, v46
	v_mov_b32_e32 v41, v48
	v_pk_mul_f32 v[36:37], v[38:39], v[36:37]
	v_mov_b32_e32 v42, v54
	v_mov_b32_e32 v43, v58
	v_pk_mul_f32 v[2:3], v[4:5], v[2:3]
	v_pk_mul_f32 v[40:41], v[52:53], v[40:41]
	v_pk_mul_f32 v[42:43], v[62:63], v[42:43]
	v_bfe_u32 v44, v2, 16, 1
	v_bfe_u32 v46, v37, 16, 1
	v_bfe_u32 v48, v36, 16, 1
	v_bfe_u32 v0, v3, 16, 1
	v_add3_u32 v36, v36, v48, s91
	v_add3_u32 v37, v37, v46, s91
	v_add3_u32 v2, v2, v44, s91
	v_bfe_u32 v44, v41, 16, 1
	v_bfe_u32 v46, v42, 16, 1
	v_bfe_u32 v48, v43, 16, 1
	s_and_b32 s38, s38, 0x60
	v_add3_u32 v0, v3, v0, s91
	v_bfe_u32 v3, v40, 16, 1
	v_add3_u32 v43, v43, v48, s91
	v_add3_u32 v42, v42, v46, s91
	v_add3_u32 v41, v41, v44, s91
	s_or_b32 s0, s38, s0
	v_add3_u32 v3, v40, v3, s91
	v_lshrrev_b32_e32 v40, 16, v41
	v_lshrrev_b32_e32 v41, 16, v42
	v_lshrrev_b32_e32 v42, 16, v43
	s_lshl_b32 s88, s1, 1
	v_and_or_b32 v43, v0, s35, v42
	v_or_b32_e32 v0, s0, v30
	v_lshl_add_u64 v[26:27], v[10:11], 0, s[88:89]
	v_lshrrev_b32_e32 v3, 16, v3
	v_lshlrev_b32_e32 v0, 11, v0
	v_mov_b32_e32 v50, v45
	v_and_or_b32 v42, v2, s35, v41
	v_and_or_b32 v41, v37, s35, v40
	v_and_or_b32 v40, v36, s35, v3
	v_lshl_add_u64 v[2:3], v[26:27], 0, v[0:1]
	v_pk_mul_f32 v[36:37], v[38:39], v[50:51]
	v_mov_b32_e32 v58, v55
	global_store_dwordx4 v[2:3], v[40:43], off sc1
	v_mov_b32_e32 v60, v57
	v_bfe_u32 v46, v36, 16, 1
	v_pk_mul_f32 v[40:41], v[62:63], v[58:59]
	v_mov_b32_e32 v48, v47
	v_pk_mul_f32 v[42:43], v[4:5], v[60:61]
	v_add3_u32 v36, v36, v46, s91
	v_bfe_u32 v46, v41, 16, 1
	v_pk_mul_f32 v[2:3], v[52:53], v[48:49]
	v_bfe_u32 v0, v43, 16, 1
	v_bfe_u32 v44, v42, 16, 1
	v_bfe_u32 v45, v37, 16, 1
	v_add3_u32 v41, v41, v46, s91
	v_add3_u32 v37, v37, v45, s91
	v_add3_u32 v42, v42, v44, s91
	v_add3_u32 v0, v43, v0, s91
	v_bfe_u32 v43, v2, 16, 1
	v_bfe_u32 v44, v3, 16, 1
	v_bfe_u32 v45, v40, 16, 1
	v_lshrrev_b32_e32 v41, 16, v41
	v_add3_u32 v40, v40, v45, s91
	v_add3_u32 v3, v3, v44, s91
	v_add3_u32 v2, v2, v43, s91
	v_and_or_b32 v43, v0, s35, v41
	v_or_b32_e32 v0, s0, v33
	v_lshrrev_b32_e32 v2, 16, v2
	v_lshrrev_b32_e32 v3, 16, v3
	v_lshrrev_b32_e32 v40, 16, v40
	v_lshlrev_b32_e32 v0, 11, v0
	v_and_or_b32 v42, v42, s35, v40
	v_and_or_b32 v41, v37, s35, v3
	v_and_or_b32 v40, v36, s35, v2
	v_lshl_add_u64 v[2:3], v[26:27], 0, v[0:1]
	ds_read2_b32 v[36:37], v31 offset0:16 offset1:24
	ds_read2_b32 v[44:45], v31 offset0:82 offset1:90
	global_store_dwordx4 v[2:3], v[40:43], off sc1
	ds_read2_b32 v[2:3], v31 offset0:49 offset1:57
	ds_read2_b32 v[46:47], v31 offset0:115 offset1:123
	ds_read2_b32 v[48:49], v31 offset0:148 offset1:156
	ds_read2_b32 v[50:51], v31 offset0:214 offset1:222
	ds_read2_b32 v[54:55], v31 offset0:181 offset1:189
	ds_read2_b32 v[56:57], v31 offset0:247 offset1:255
	s_waitcnt lgkmcnt(7)
; #define LAS __attribute__((address_space(3)))
; __device__ __forceinline__ unsigned pk2(float lo, float hi) { return f2bf(lo) | (f2bf(hi) << 16); }
; #define LDS_WAVE_SYNC() asm volatile("s_waitcnt lgkmcnt(0)" ::: "memory")
; template <bool HASG>
; __device__ __forceinline__ void tr_item(const float* W, int K, int N, bf16* WT, int rowmode, const float* g, LAS float* scr, int item, int lane) {
;     ...
;     for (int j = 0; j < 4; ++j) { const int n = (lane >> 3) + 8 * j; const LAS float* s = scr + (8 * c) * 33 + n;
;         u32x4 o; o.x = pk2(s[0 * 33] * g0.x, s[1 * 33] * g0.y); o.y = pk2(s[2 * 33] * g0.z, s[3 * 33] * g0.w);
;         o.z = pk2(s[4 * 33] * g1.x, s[5 * 33] * g1.y); o.w = pk2(s[6 * 33] * g1.z, s[7 * 33] * g1.w);
;         *(u32x4*)(WT + (size_t)(drow0 + n) * K + k0 + 8 * c) = o; }
;     LDS_WAVE_SYNC();
	v_mov_b32_e32 v40, v36
	s_waitcnt lgkmcnt(5)
	v_mov_b32_e32 v42, v2
	s_waitcnt lgkmcnt(4)
	v_mov_b32_e32 v43, v46
	s_waitcnt lgkmcnt(3)
	v_mov_b32_e32 v58, v48
	s_waitcnt lgkmcnt(2)
	v_mov_b32_e32 v59, v50
	v_mov_b32_e32 v41, v44
	v_pk_mul_f32 v[42:43], v[38:39], v[42:43]
	v_pk_mul_f32 v[58:59], v[62:63], v[58:59]
	s_waitcnt lgkmcnt(1)
	v_mov_b32_e32 v60, v54
	s_waitcnt lgkmcnt(0)
	v_mov_b32_e32 v61, v56
	v_pk_mul_f32 v[40:41], v[52:53], v[40:41]
	v_pk_mul_f32 v[60:61], v[4:5], v[60:61]
	v_bfe_u32 v36, v43, 16, 1
	v_bfe_u32 v48, v59, 16, 1
	v_bfe_u32 v0, v61, 16, 1
	v_bfe_u32 v44, v42, 16, 1
	v_add3_u32 v36, v43, v36, s91
	v_bfe_u32 v43, v41, 16, 1
	v_add3_u32 v48, v59, v48, s91
	v_add3_u32 v44, v42, v44, s91
	v_add3_u32 v0, v61, v0, s91
	v_bfe_u32 v42, v40, 16, 1
	v_bfe_u32 v46, v58, 16, 1
	v_add3_u32 v41, v41, v43, s91
	v_lshrrev_b32_e32 v43, 16, v48
	v_bfe_u32 v2, v60, 16, 1
	v_add3_u32 v46, v58, v46, s91
	v_add3_u32 v40, v40, v42, s91
	v_and_or_b32 v43, v0, s35, v43
	v_or_b32_e32 v0, s0, v34
	v_add3_u32 v2, v60, v2, s91
	v_lshrrev_b32_e32 v40, 16, v40
	v_lshrrev_b32_e32 v41, 16, v41
	v_lshrrev_b32_e32 v42, 16, v46
	v_lshlrev_b32_e32 v0, 11, v0
	v_mov_b32_e32 v46, v3
	v_mov_b32_e32 v56, v55
	v_and_or_b32 v42, v2, s35, v42
	v_and_or_b32 v41, v36, s35, v41
	v_and_or_b32 v40, v44, s35, v40
	v_lshl_add_u64 v[58:59], v[26:27], 0, v[0:1]
	v_mov_b32_e32 v44, v37
	v_pk_mul_f32 v[2:3], v[38:39], v[46:47]
	v_mov_b32_e32 v50, v49
	v_pk_mul_f32 v[4:5], v[4:5], v[56:57]
	global_store_dwordx4 v[58:59], v[40:43], off sc1
	v_pk_mul_f32 v[36:37], v[52:53], v[44:45]
	v_pk_mul_f32 v[38:39], v[62:63], v[50:51]
	v_bfe_u32 v0, v5, 16, 1
	v_bfe_u32 v42, v2, 16, 1
	v_add3_u32 v2, v2, v42, s91
	v_add3_u32 v0, v5, v0, s91
	v_bfe_u32 v5, v36, 16, 1
	v_bfe_u32 v42, v39, 16, 1
	v_bfe_u32 v40, v4, 16, 1
	v_bfe_u32 v41, v3, 16, 1
	v_add3_u32 v39, v39, v42, s91
	v_add3_u32 v5, v36, v5, s91
	v_add3_u32 v3, v3, v41, s91
	v_add3_u32 v4, v4, v40, s91
	v_bfe_u32 v40, v37, 16, 1
	v_bfe_u32 v41, v38, 16, 1
	v_lshrrev_b32_e32 v36, 16, v5
	v_lshrrev_b32_e32 v5, 16, v39
	v_add3_u32 v38, v38, v41, s91
	v_add3_u32 v37, v37, v40, s91
	v_and_or_b32 v5, v0, s35, v5
	v_or_b32_e32 v0, s0, v35
	v_lshrrev_b32_e32 v37, 16, v37
	v_lshrrev_b32_e32 v38, 16, v38
	v_lshlrev_b32_e32 v0, 11, v0
	v_and_or_b32 v4, v4, s35, v38
	v_and_or_b32 v3, v3, s35, v37
	v_and_or_b32 v2, v2, s35, v36
	v_lshl_add_u64 v[26:27], v[26:27], 0, v[0:1]
	global_store_dwordx4 v[26:27], v[2:5], off sc1
	s_waitcnt lgkmcnt(0)
	v_readlane_b32 s8, v252, 4
	v_readlane_b32 s9, v252, 5
	s_mov_b64 s[8:9], s[26:27]
	v_readlane_b32 s5, v252, 1
	v_readlane_b32 s6, v252, 2
	v_readlane_b32 s7, v252, 3
	v_readlane_b32 s10, v252, 6
	v_readlane_b32 s11, v252, 7
	v_readlane_b32 s12, v252, 8
	v_readlane_b32 s13, v252, 9
	v_readlane_b32 s14, v252, 10
	v_readlane_b32 s15, v252, 11
	v_readlane_b32 s16, v252, 12
	v_readlane_b32 s17, v252, 13
	v_readlane_b32 s18, v252, 14
	v_readlane_b32 s19, v252, 15

; template <bool HASG>
; __device__ __forceinline__ void tr_item(const float* W, int K, int N, bf16* WT, int rowmode, const float* g, LAS float* scr, int item, int lane) {
;     const int nblk = N / 32, kb = item / nblk, nb = item % nblk, k0 = 64 * kb, n0 = 32 * nb;
;     const float* wp = W + (size_t)(k0 + (lane >> 5)) * N + n0 + (lane & 31);
;     const int c = lane & 7;
;     float v[32];
; #pragma unroll
;     for (int i = 0; i < 32; ++i) v[i] = wp[(size_t)(2 * i) * N];
;     f32x4 g0 = (f32x4){1.f, 1.f, 1.f, 1.f}, g1 = g0;
;     if (HASG) { g0 = *(const f32x4*)(g + k0 + 8 * c); g1 = *(const f32x4*)(g + k0 + 8 * c + 4); }
;     asm volatile("" ::: "memory");
; #pragma unroll
;     for (int i = 0; i < 32; ++i) scr[(2 * i + (lane >> 5)) * 33 + (lane & 31)] = v[i];
; __device__ __forceinline__ void convert_items(const Args& a, LAS unsigned char* lds, int l, int it_lo, int it_hi, int gw, int NGW, int wave, int lane) {
;     ...
;         if (r < I_OUT) { tr_item<false>(a.in[18] + (size_t)l * D * D, D, D, wl + W_OUT, 0, nullptr, scr, r, lane); continue; } r -= I_OUT;
.LBB0_526:
	s_andn2_b64 vcc, exec, s[0:1]
	s_cbranch_vccnz .LBB0_528
	s_add_i32 s0, s44, 0x1a00
	s_and_b32 s1, s0, 0x1ffc0
	s_lshl_b32 s0, s28, 5
	v_or_b32_e32 v0, s1, v28
	v_readlane_b32 s4, v252, 32
	s_and_b32 s0, s0, 0x3e0
	v_lshlrev_b32_e32 v0, 12, v0
	v_readlane_b32 s8, v252, 36
	v_readlane_b32 s9, v252, 37
	v_readlane_b32 s5, v252, 33
	v_readlane_b32 s6, v252, 34
	v_readlane_b32 s7, v252, 35
	v_readlane_b32 s10, v252, 38
	v_readlane_b32 s11, v252, 39
	v_readlane_b32 s12, v252, 40
	v_readlane_b32 s13, v252, 41
	v_readlane_b32 s14, v252, 42
	v_readlane_b32 s15, v252, 43
	v_readlane_b32 s16, v252, 44
	v_readlane_b32 s17, v252, 45
	v_readlane_b32 s18, v252, 46
	v_readlane_b32 s19, v252, 47
	v_lshl_add_u64 v[2:3], s[8:9], 0, v[0:1]
	s_lshl_b32 s88, s0, 2
	v_readlane_b32 s4, v252, 0
	v_lshl_add_u64 v[2:3], v[2:3], 0, s[88:89]
	v_lshlrev_b32_e32 v0, 2, v6
	v_lshl_add_u64 v[2:3], v[2:3], 0, v[0:1]
	s_movk_i32 s4, 0x2000
	v_add_co_u32_e32 v4, vcc, s4, v2
	s_movk_i32 s4, 0x4000
	s_nop 0
	v_addc_co_u32_e32 v5, vcc, 0, v3, vcc
	global_load_dword v0, v[2:3], off
	global_load_dword v26, v[4:5], off
	v_add_co_u32_e32 v4, vcc, s4, v2
	s_movk_i32 s4, 0x6000
	s_nop 0
	v_addc_co_u32_e32 v5, vcc, 0, v3, vcc
	global_load_dword v27, v[4:5], off
	v_add_co_u32_e32 v4, vcc, s4, v2
	s_mov_b32 s4, 0x8000
	s_nop 0
	v_addc_co_u32_e32 v5, vcc, 0, v3, vcc
	global_load_dword v36, v[4:5], off
	v_add_co_u32_e32 v4, vcc, s4, v2
	s_mov_b32 s4, 0xa000
	s_nop 0
	v_addc_co_u32_e32 v5, vcc, 0, v3, vcc
	global_load_dword v37, v[4:5], off
	v_add_co_u32_e32 v4, vcc, s4, v2
	s_mov_b32 s4, 0xc000
	s_nop 0
	v_addc_co_u32_e32 v5, vcc, 0, v3, vcc
	global_load_dword v38, v[4:5], off
	v_add_co_u32_e32 v4, vcc, s4, v2
	s_mov_b32 s4, 0xe000
	s_nop 0
	v_addc_co_u32_e32 v5, vcc, 0, v3, vcc
	global_load_dword v39, v[4:5], off
	v_add_co_u32_e32 v4, vcc, s4, v2
	s_mov_b32 s4, 0x12000
	s_nop 0
	v_addc_co_u32_e32 v5, vcc, 0, v3, vcc
	global_load_dword v40, v[4:5], off
	v_add_co_u32_e32 v4, vcc, s70, v2
	s_lshl_b32 s88, s1, 1
	s_nop 0
	v_addc_co_u32_e32 v5, vcc, 0, v3, vcc
	global_load_dword v41, v[4:5], off
	v_add_co_u32_e32 v4, vcc, s4, v2
	s_mov_b32 s4, 0x14000
	s_nop 0
	v_addc_co_u32_e32 v5, vcc, 0, v3, vcc
	global_load_dword v42, v[4:5], off
	v_add_co_u32_e32 v4, vcc, s4, v2
	s_mov_b32 s4, 0x18000
	s_nop 0
	v_addc_co_u32_e32 v5, vcc, 0, v3, vcc
	global_load_dword v43, v[4:5], off
	v_add_co_u32_e32 v4, vcc, s71, v2
	v_readlane_b32 s8, v252, 4
	s_nop 0
	v_addc_co_u32_e32 v5, vcc, 0, v3, vcc
	global_load_dword v44, v[4:5], off
	v_add_co_u32_e32 v4, vcc, s4, v2
	s_mov_b32 s4, 0x1a000
	s_nop 0
	v_addc_co_u32_e32 v5, vcc, 0, v3, vcc
	global_load_dword v45, v[4:5], off
	v_add_co_u32_e32 v4, vcc, s4, v2
	s_mov_b32 s4, 0x1c000
	s_nop 0
	v_addc_co_u32_e32 v5, vcc, 0, v3, vcc
	global_load_dword v46, v[4:5], off
	v_add_co_u32_e32 v4, vcc, s4, v2
	s_mov_b32 s4, 0x1e000
	s_nop 0
	v_addc_co_u32_e32 v5, vcc, 0, v3, vcc
	global_load_dword v47, v[4:5], off
	v_add_co_u32_e32 v4, vcc, s4, v2
	s_mov_b32 s4, 0x20000
	s_nop 0
	v_addc_co_u32_e32 v5, vcc, 0, v3, vcc
	global_load_dword v48, v[4:5], off
	v_add_co_u32_e32 v4, vcc, s4, v2
	s_mov_b32 s4, 0x22000
	s_nop 0
	v_addc_co_u32_e32 v5, vcc, 0, v3, vcc
	global_load_dword v49, v[4:5], off
	v_add_co_u32_e32 v4, vcc, s4, v2
	s_mov_b32 s4, 0x24000
	s_nop 0
	v_addc_co_u32_e32 v5, vcc, 0, v3, vcc
	global_load_dword v50, v[4:5], off
	v_add_co_u32_e32 v4, vcc, s4, v2
	s_mov_b32 s4, 0x26000
	s_nop 0
	v_addc_co_u32_e32 v5, vcc, 0, v3, vcc
	global_load_dword v51, v[4:5], off
	v_add_co_u32_e32 v4, vcc, s4, v2
	s_mov_b32 s4, 0x28000
	s_nop 0
	v_addc_co_u32_e32 v5, vcc, 0, v3, vcc
	global_load_dword v52, v[4:5], off
	v_add_co_u32_e32 v4, vcc, s4, v2
	s_mov_b32 s4, 0x2a000
	s_nop 0
	v_addc_co_u32_e32 v5, vcc, 0, v3, vcc
	global_load_dword v53, v[4:5], off
	v_add_co_u32_e32 v4, vcc, s4, v2
	s_mov_b32 s4, 0x2c000
	s_nop 0
	v_addc_co_u32_e32 v5, vcc, 0, v3, vcc
	global_load_dword v54, v[4:5], off
	v_add_co_u32_e32 v4, vcc, s4, v2
	s_mov_b32 s4, 0x2e000
	s_nop 0
	v_addc_co_u32_e32 v5, vcc, 0, v3, vcc
	global_load_dword v55, v[4:5], off
	v_add_co_u32_e32 v4, vcc, s4, v2
	s_mov_b32 s4, 0x30000
	s_nop 0
	v_addc_co_u32_e32 v5, vcc, 0, v3, vcc
	global_load_dword v56, v[4:5], off
	v_add_co_u32_e32 v4, vcc, s4, v2
	s_mov_b32 s4, 0x32000
	s_nop 0
	v_addc_co_u32_e32 v5, vcc, 0, v3, vcc
	global_load_dword v57, v[4:5], off
	v_add_co_u32_e32 v4, vcc, s4, v2
	s_mov_b32 s4, 0x34000
	s_nop 0
	v_addc_co_u32_e32 v5, vcc, 0, v3, vcc
	global_load_dword v58, v[4:5], off
	v_add_co_u32_e32 v4, vcc, s4, v2
	s_mov_b32 s4, 0x36000
	s_nop 0
	v_addc_co_u32_e32 v5, vcc, 0, v3, vcc
	global_load_dword v59, v[4:5], off
	v_add_co_u32_e32 v4, vcc, s4, v2
	s_mov_b32 s4, 0x38000
	s_nop 0
	v_addc_co_u32_e32 v5, vcc, 0, v3, vcc
	global_load_dword v60, v[4:5], off
	v_add_co_u32_e32 v4, vcc, s4, v2
	s_mov_b32 s4, 0x3a000
	s_nop 0
	v_addc_co_u32_e32 v5, vcc, 0, v3, vcc
	global_load_dword v61, v[4:5], off
	v_add_co_u32_e32 v4, vcc, s4, v2
	s_mov_b32 s4, 0x3c000
	s_nop 0
	v_addc_co_u32_e32 v5, vcc, 0, v3, vcc
	global_load_dword v62, v[4:5], off
	v_add_co_u32_e32 v4, vcc, s4, v2
	s_mov_b32 s4, 0x3e000
	s_nop 0
	v_addc_co_u32_e32 v5, vcc, 0, v3, vcc
	v_add_co_u32_e32 v2, vcc, s4, v2
	global_load_dword v4, v[4:5], off
	s_nop 0
	v_addc_co_u32_e32 v3, vcc, 0, v3, vcc
	global_load_dword v2, v[2:3], off
	s_waitcnt vmcnt(30)
	ds_write2_b32 v29, v0, v26 offset1:66
	s_waitcnt vmcnt(28)
	ds_write2_b32 v29, v27, v36 offset0:132 offset1:198
	v_add_u32_e32 v0, 0x400, v29
	s_waitcnt vmcnt(26)
	ds_write2_b32 v0, v37, v38 offset0:8 offset1:74
	s_waitcnt vmcnt(24)
	ds_write2_b32 v0, v39, v40 offset0:140 offset1:206
	v_add_u32_e32 v0, 0x800, v29
	s_waitcnt vmcnt(22)
; #define LAS __attribute__((address_space(3)))
; __device__ __forceinline__ unsigned pk2(float lo, float hi) { return f2bf(lo) | (f2bf(hi) << 16); }
; #define LDS_WAVE_SYNC() asm volatile("s_waitcnt lgkmcnt(0)" ::: "memory")
; template <bool HASG>
; __device__ __forceinline__ void tr_item(const float* W, int K, int N, bf16* WT, int rowmode, const float* g, LAS float* scr, int item, int lane) {
;     ...
;     for (int i = 0; i < 32; ++i) scr[(2 * i + (lane >> 5)) * 33 + (lane & 31)] = v[i];
;     LDS_WAVE_SYNC();
;     const int drow0 = rowmode == 0 ? n0 : ((n0 >> 7) * 256 + (n0 & 127) + (rowmode == 2 ? 128 : 0));
; #pragma unroll
;     for (int j = 0; j < 4; ++j) { const int n = (lane >> 3) + 8 * j; const LAS float* s = scr + (8 * c) * 33 + n;
;         u32x4 o; o.x = pk2(s[0 * 33] * g0.x, s[1 * 33] * g0.y); o.y = pk2(s[2 * 33] * g0.z, s[3 * 33] * g0.w);
;         o.z = pk2(s[4 * 33] * g1.x, s[5 * 33] * g1.y); o.w = pk2(s[6 * 33] * g1.z, s[7 * 33] * g1.w);
;         *(u32x4*)(WT + (size_t)(drow0 + n) * K + k0 + 8 * c) = o; }
;     LDS_WAVE_SYNC();
	ds_write2_b32 v0, v41, v42 offset0:16 offset1:82
	s_waitcnt vmcnt(20)
	ds_write2_b32 v0, v43, v44 offset0:148 offset1:214
	v_add_u32_e32 v0, 0xc00, v29
	s_waitcnt vmcnt(18)
	ds_write2_b32 v0, v45, v46 offset0:24 offset1:90
	s_waitcnt vmcnt(16)
	ds_write2_b32 v0, v47, v48 offset0:156 offset1:222
	v_add_u32_e32 v0, 0x1000, v29
	s_waitcnt vmcnt(14)
	ds_write2_b32 v0, v49, v50 offset0:32 offset1:98
	s_waitcnt vmcnt(12)
	ds_write2_b32 v0, v51, v52 offset0:164 offset1:230
	v_add_u32_e32 v0, 0x1400, v29
	s_waitcnt vmcnt(10)
	ds_write2_b32 v0, v53, v54 offset0:40 offset1:106
	s_waitcnt vmcnt(8)
	ds_write2_b32 v0, v55, v56 offset0:172 offset1:238
	v_add_u32_e32 v0, 0x1800, v29
	s_waitcnt vmcnt(6)
	ds_write2_b32 v0, v57, v58 offset0:48 offset1:114
	s_waitcnt vmcnt(4)
	ds_write2_b32 v0, v59, v60 offset0:180 offset1:246
	v_add_u32_e32 v0, 0x1c00, v29
	s_waitcnt vmcnt(2)
	ds_write2_b32 v0, v61, v62 offset0:56 offset1:122
	s_waitcnt vmcnt(0)
	ds_write2_b32 v0, v4, v2 offset0:188 offset1:254
	s_waitcnt lgkmcnt(0)
	ds_read2_b32 v[4:5], v31 offset0:33 offset1:41
	ds_read2_b32 v[26:27], v31 offset1:8
	ds_read2_b32 v[40:41], v31 offset0:66 offset1:74
	ds_read2_b32 v[42:43], v31 offset0:99 offset1:107
	ds_read2_b32 v[44:45], v31 offset0:132 offset1:140
	ds_read2_b32 v[46:47], v31 offset0:165 offset1:173
	ds_read2_b32 v[48:49], v31 offset0:198 offset1:206
	ds_read2_b32 v[50:51], v31 offset0:231 offset1:239
	v_lshl_add_u64 v[2:3], v[12:13], 0, s[88:89]
	s_waitcnt lgkmcnt(6)
	v_bfe_u32 v0, v26, 16, 1
	v_add3_u32 v0, v26, v0, s91
	v_bfe_u32 v26, v4, 16, 1
	v_lshrrev_b32_e32 v0, 16, v0
	v_add3_u32 v4, v4, v26, s91
	v_and_or_b32 v36, v4, s35, v0
	s_waitcnt lgkmcnt(5)
	v_bfe_u32 v0, v40, 16, 1
	v_add3_u32 v0, v40, v0, s91
	s_waitcnt lgkmcnt(4)
	v_bfe_u32 v4, v42, 16, 1
	v_lshrrev_b32_e32 v0, 16, v0
	v_add3_u32 v4, v42, v4, s91
	v_and_or_b32 v37, v4, s35, v0
	s_waitcnt lgkmcnt(3)
	v_bfe_u32 v0, v44, 16, 1
	v_add3_u32 v0, v44, v0, s91
	s_waitcnt lgkmcnt(2)
	v_bfe_u32 v4, v46, 16, 1
	v_lshrrev_b32_e32 v0, 16, v0
	v_add3_u32 v4, v46, v4, s91
	v_and_or_b32 v38, v4, s35, v0
	s_waitcnt lgkmcnt(1)
	v_bfe_u32 v0, v48, 16, 1
	v_add3_u32 v0, v48, v0, s91
	s_waitcnt lgkmcnt(0)
	v_bfe_u32 v4, v50, 16, 1
	v_lshrrev_b32_e32 v0, 16, v0
	v_add3_u32 v4, v50, v4, s91
	v_and_or_b32 v39, v4, s35, v0
	v_or_b32_e32 v0, s0, v30
	v_lshlrev_b32_e32 v0, 11, v0
	v_lshl_add_u64 v[52:53], v[2:3], 0, v[0:1]
	v_bfe_u32 v0, v27, 16, 1
	v_add3_u32 v0, v27, v0, s91
	v_bfe_u32 v4, v5, 16, 1
	v_lshrrev_b32_e32 v0, 16, v0
	v_add3_u32 v4, v5, v4, s91
	global_store_dwordx4 v[52:53], v[36:39], off sc1
	v_readlane_b32 s9, v252, 5
	s_mov_b64 s[8:9], s[26:27]
	v_and_or_b32 v36, v4, s35, v0
	v_bfe_u32 v0, v41, 16, 1
	v_add3_u32 v0, v41, v0, s91
	v_bfe_u32 v4, v43, 16, 1
	v_lshrrev_b32_e32 v0, 16, v0
	v_add3_u32 v4, v43, v4, s91
	v_and_or_b32 v37, v4, s35, v0
	v_bfe_u32 v0, v45, 16, 1
	v_add3_u32 v0, v45, v0, s91
	v_bfe_u32 v4, v47, 16, 1
	v_lshrrev_b32_e32 v0, 16, v0
	v_add3_u32 v4, v47, v4, s91
	v_and_or_b32 v38, v4, s35, v0
	v_bfe_u32 v0, v49, 16, 1
	v_add3_u32 v0, v49, v0, s91
	v_bfe_u32 v4, v51, 16, 1
	v_lshrrev_b32_e32 v0, 16, v0
	v_add3_u32 v4, v51, v4, s91
	v_and_or_b32 v39, v4, s35, v0
	v_or_b32_e32 v0, s0, v33
	v_lshlrev_b32_e32 v0, 11, v0
	v_lshl_add_u64 v[4:5], v[2:3], 0, v[0:1]
	global_store_dwordx4 v[4:5], v[36:39], off sc1
	ds_read2_b32 v[4:5], v31 offset0:49 offset1:57
	ds_read2_b32 v[26:27], v31 offset0:16 offset1:24
	ds_read2_b32 v[40:41], v31 offset0:82 offset1:90
	ds_read2_b32 v[42:43], v31 offset0:115 offset1:123
	ds_read2_b32 v[44:45], v31 offset0:148 offset1:156
	ds_read2_b32 v[46:47], v31 offset0:181 offset1:189
	ds_read2_b32 v[48:49], v31 offset0:214 offset1:222
	ds_read2_b32 v[50:51], v31 offset0:247 offset1:255
	v_readlane_b32 s5, v252, 1
	s_waitcnt lgkmcnt(6)
	v_bfe_u32 v0, v26, 16, 1
	v_add3_u32 v0, v26, v0, s91
	v_bfe_u32 v26, v4, 16, 1
	v_lshrrev_b32_e32 v0, 16, v0
	v_add3_u32 v4, v4, v26, s91
	v_and_or_b32 v36, v4, s35, v0
	s_waitcnt lgkmcnt(5)
	v_bfe_u32 v0, v40, 16, 1
	v_add3_u32 v0, v40, v0, s91
	s_waitcnt lgkmcnt(4)
	v_bfe_u32 v4, v42, 16, 1
	v_lshrrev_b32_e32 v0, 16, v0
	v_add3_u32 v4, v42, v4, s91
	v_and_or_b32 v37, v4, s35, v0
	s_waitcnt lgkmcnt(3)
	v_bfe_u32 v0, v44, 16, 1
	v_add3_u32 v0, v44, v0, s91
	s_waitcnt lgkmcnt(2)
	v_bfe_u32 v4, v46, 16, 1
	v_lshrrev_b32_e32 v0, 16, v0
	v_add3_u32 v4, v46, v4, s91
	v_and_or_b32 v38, v4, s35, v0
	s_waitcnt lgkmcnt(1)
	v_bfe_u32 v0, v48, 16, 1
	v_add3_u32 v0, v48, v0, s91
	s_waitcnt lgkmcnt(0)
	v_bfe_u32 v4, v50, 16, 1
	v_lshrrev_b32_e32 v0, 16, v0
	v_add3_u32 v4, v50, v4, s91
	v_and_or_b32 v39, v4, s35, v0
	v_or_b32_e32 v0, s0, v34
	v_lshlrev_b32_e32 v0, 11, v0
	v_lshl_add_u64 v[52:53], v[2:3], 0, v[0:1]
	v_bfe_u32 v0, v27, 16, 1
	v_add3_u32 v0, v27, v0, s91
	v_bfe_u32 v4, v5, 16, 1
	v_lshrrev_b32_e32 v0, 16, v0
	v_add3_u32 v4, v5, v4, s91
	global_store_dwordx4 v[52:53], v[36:39], off sc1
	v_readlane_b32 s6, v252, 2
	v_readlane_b32 s7, v252, 3
	v_and_or_b32 v36, v4, s35, v0
	v_bfe_u32 v0, v41, 16, 1
	v_add3_u32 v0, v41, v0, s91
	v_bfe_u32 v4, v43, 16, 1
	v_lshrrev_b32_e32 v0, 16, v0
	v_add3_u32 v4, v43, v4, s91
	v_and_or_b32 v37, v4, s35, v0
	v_bfe_u32 v0, v45, 16, 1
	v_add3_u32 v0, v45, v0, s91
	v_bfe_u32 v4, v47, 16, 1
	v_lshrrev_b32_e32 v0, 16, v0
	v_add3_u32 v4, v47, v4, s91
	v_and_or_b32 v38, v4, s35, v0
	v_bfe_u32 v0, v49, 16, 1
	v_add3_u32 v0, v49, v0, s91
	v_bfe_u32 v4, v51, 16, 1
	v_lshrrev_b32_e32 v0, 16, v0
	v_add3_u32 v4, v51, v4, s91
	v_and_or_b32 v39, v4, s35, v0
	v_or_b32_e32 v0, s0, v35
	v_lshlrev_b32_e32 v0, 11, v0
	v_lshl_add_u64 v[2:3], v[2:3], 0, v[0:1]
	global_store_dwordx4 v[2:3], v[36:39], off sc1
	s_waitcnt lgkmcnt(0)
	v_readlane_b32 s10, v252, 6
	v_readlane_b32 s11, v252, 7
	v_readlane_b32 s12, v252, 8
	v_readlane_b32 s13, v252, 9
	v_readlane_b32 s14, v252, 10
	v_readlane_b32 s15, v252, 11
	v_readlane_b32 s16, v252, 12
	v_readlane_b32 s17, v252, 13
	v_readlane_b32 s18, v252, 14
	v_readlane_b32 s19, v252, 15

; template <bool HASG>
; __device__ __forceinline__ void tr_item(const float* W, int K, int N, bf16* WT, int rowmode, const float* g, LAS float* scr, int item, int lane) {
;     const int nblk = N / 32, kb = item / nblk, nb = item % nblk, k0 = 64 * kb, n0 = 32 * nb;
;     const float* wp = W + (size_t)(k0 + (lane >> 5)) * N + n0 + (lane & 31);
;     const int c = lane & 7;
;     float v[32];
; #pragma unroll
;     for (int i = 0; i < 32; ++i) v[i] = wp[(size_t)(2 * i) * N];
;     f32x4 g0 = (f32x4){1.f, 1.f, 1.f, 1.f}, g1 = g0;
;     if (HASG) { g0 = *(const f32x4*)(g + k0 + 8 * c); g1 = *(const f32x4*)(g + k0 + 8 * c + 4); }
; __device__ __forceinline__ void convert_items(const Args& a, LAS unsigned char* lds, int l, int it_lo, int it_hi, int gw, int NGW, int wave, int lane) {
;     ...
;         if (r < I_IN) { tr_item<true>(a.in[6] + (size_t)l * D * DIN, D, DIN, wl + W_IN, 0, a.in[5] + l * D, scr, r, lane); continue; } r -= I_IN;
.LBB0_529:
	s_andn2_b64 vcc, exec, s[0:1]
	s_cbranch_vccnz .LBB0_531
	s_add_i32 s0, s28, 0xef80
	s_bfe_u32 s1, s0, 0xd0003
	s_mulk_i32 s1, 0x2493
	s_lshr_b32 s1, s1, 16
	s_mul_i32 s38, s1, 56
	s_sub_i32 s0, s0, s38
	s_lshl_b32 s0, s0, 5
	v_lshl_or_b32 v0, s1, 6, v28
	v_readlane_b32 s4, v252, 0
	s_and_b32 s0, s0, 0xffe0
	v_mul_u32_u24_e32 v0, 0x700, v0
	v_readlane_b32 s16, v252, 12
	v_readlane_b32 s17, v252, 13
	s_lshl_b32 s88, s0, 2
	s_movk_i32 s4, 0x3000
	v_lshl_add_u64 v[2:3], v[0:1], 2, s[16:17]
	v_lshl_add_u64 v[2:3], v[2:3], 0, s[88:89]
	v_lshlrev_b32_e32 v0, 2, v6
	v_lshl_add_u64 v[2:3], v[2:3], 0, v[0:1]
	v_add_co_u32_e32 v4, vcc, s4, v2
	s_movk_i32 s4, 0x7000
	s_nop 0
	v_addc_co_u32_e32 v5, vcc, 0, v3, vcc
	v_add_co_u32_e32 v26, vcc, s4, v2
	s_mov_b32 s4, 0xa000
	s_nop 0
	v_addc_co_u32_e32 v27, vcc, 0, v3, vcc
	v_add_co_u32_e32 v36, vcc, s4, v2
	s_mov_b32 s4, 0xe000
	s_nop 0
	v_addc_co_u32_e32 v37, vcc, 0, v3, vcc
	v_add_co_u32_e32 v38, vcc, s4, v2
	s_mov_b32 s4, 0x11000
	s_nop 0
	v_addc_co_u32_e32 v39, vcc, 0, v3, vcc
	v_add_co_u32_e32 v40, vcc, s4, v2
	s_mov_b32 s4, 0x15000
	s_nop 0
	v_addc_co_u32_e32 v41, vcc, 0, v3, vcc
	v_add_co_u32_e32 v42, vcc, s4, v2
	s_mov_b32 s4, 0x18000
	s_nop 0
	v_addc_co_u32_e32 v43, vcc, 0, v3, vcc
	v_add_co_u32_e32 v44, vcc, s4, v2
	s_mov_b32 s4, 0x1c000
	s_nop 0
	v_addc_co_u32_e32 v45, vcc, 0, v3, vcc
	global_load_dword v0, v[2:3], off
	global_load_dword v48, v[4:5], off offset:2048
	global_load_dword v49, v[26:27], off
	global_load_dword v50, v[36:37], off offset:2048
	global_load_dword v51, v[38:39], off
	global_load_dword v52, v[40:41], off offset:2048
	global_load_dword v53, v[42:43], off
	global_load_dword v54, v[44:45], off offset:2048
	v_add_co_u32_e32 v4, vcc, s4, v2
	s_mov_b32 s4, 0x1f000
	s_nop 0
	v_addc_co_u32_e32 v5, vcc, 0, v3, vcc
	v_add_co_u32_e32 v26, vcc, s4, v2
	s_mov_b32 s4, 0x23000
	s_nop 0
	v_addc_co_u32_e32 v27, vcc, 0, v3, vcc
	v_add_co_u32_e32 v36, vcc, s4, v2
	s_mov_b32 s4, 0x26000
	s_nop 0
	v_addc_co_u32_e32 v37, vcc, 0, v3, vcc
	v_add_co_u32_e32 v38, vcc, s4, v2
	s_mov_b32 s4, 0x2a000
	s_nop 0
	v_addc_co_u32_e32 v39, vcc, 0, v3, vcc
	v_add_co_u32_e32 v40, vcc, s4, v2
	s_mov_b32 s4, 0x2d000
	s_nop 0
	v_addc_co_u32_e32 v41, vcc, 0, v3, vcc
	v_add_co_u32_e32 v42, vcc, s4, v2
	s_mov_b32 s4, 0x31000
	s_nop 0
	v_addc_co_u32_e32 v43, vcc, 0, v3, vcc
	v_add_co_u32_e32 v44, vcc, s4, v2
	s_mov_b32 s4, 0x34000
	s_nop 0
	v_addc_co_u32_e32 v45, vcc, 0, v3, vcc
	v_add_co_u32_e32 v46, vcc, s4, v2
	s_mov_b32 s4, 0x38000
	s_nop 0
	v_addc_co_u32_e32 v47, vcc, 0, v3, vcc
	global_load_dword v55, v[4:5], off
	global_load_dword v56, v[26:27], off offset:2048
	global_load_dword v57, v[36:37], off
	global_load_dword v58, v[38:39], off offset:2048
	global_load_dword v59, v[40:41], off
	global_load_dword v60, v[42:43], off offset:2048
	global_load_dword v61, v[44:45], off
	global_load_dword v62, v[46:47], off offset:2048
	v_add_co_u32_e32 v4, vcc, s4, v2
	s_mov_b32 s4, 0x3b000
	s_nop 0
	v_addc_co_u32_e32 v5, vcc, 0, v3, vcc
	v_add_co_u32_e32 v26, vcc, s4, v2
	s_mov_b32 s4, 0x3f000
	s_nop 0
	v_addc_co_u32_e32 v27, vcc, 0, v3, vcc
	v_add_co_u32_e32 v36, vcc, s4, v2
	s_mov_b32 s4, 0x42000
	s_nop 0
	v_addc_co_u32_e32 v37, vcc, 0, v3, vcc
	v_add_co_u32_e32 v38, vcc, s4, v2
	s_mov_b32 s4, 0x46000
	s_nop 0
	v_addc_co_u32_e32 v39, vcc, 0, v3, vcc
	v_add_co_u32_e32 v40, vcc, s4, v2
	s_mov_b32 s4, 0x49000
	s_nop 0
	v_addc_co_u32_e32 v41, vcc, 0, v3, vcc
	v_add_co_u32_e32 v42, vcc, s4, v2
	s_mov_b32 s4, 0x4d000
	s_nop 0
	v_addc_co_u32_e32 v43, vcc, 0, v3, vcc
	v_add_co_u32_e32 v44, vcc, s4, v2
	s_mov_b32 s4, 0x50000
	s_nop 0
	v_addc_co_u32_e32 v45, vcc, 0, v3, vcc
	v_add_co_u32_e32 v46, vcc, s4, v2
	s_mov_b32 s4, 0x54000
	s_nop 0
	v_addc_co_u32_e32 v47, vcc, 0, v3, vcc
	global_load_dword v63, v[4:5], off
	global_load_dword v64, v[26:27], off offset:2048
	global_load_dword v65, v[36:37], off
	global_load_dword v66, v[38:39], off offset:2048
	global_load_dword v67, v[40:41], off
	global_load_dword v68, v[42:43], off offset:2048
	global_load_dword v69, v[44:45], off
	s_nop 0
	global_load_dword v46, v[46:47], off offset:2048
	v_add_co_u32_e32 v4, vcc, s4, v2
	s_mov_b32 s4, 0x57000
	s_nop 0
	v_addc_co_u32_e32 v5, vcc, 0, v3, vcc
	v_add_co_u32_e32 v26, vcc, s4, v2
	s_mov_b32 s4, 0x5b000
	s_nop 0
	v_addc_co_u32_e32 v27, vcc, 0, v3, vcc
	v_add_co_u32_e32 v36, vcc, s4, v2
	s_mov_b32 s4, 0x5e000
	s_nop 0
	v_addc_co_u32_e32 v37, vcc, 0, v3, vcc
	v_add_co_u32_e32 v38, vcc, s4, v2
	s_mov_b32 s4, 0x62000
	s_nop 0
	v_addc_co_u32_e32 v39, vcc, 0, v3, vcc
	v_add_co_u32_e32 v40, vcc, s4, v2
	s_mov_b32 s4, 0x65000
	s_nop 0
	v_addc_co_u32_e32 v41, vcc, 0, v3, vcc
	v_add_co_u32_e32 v42, vcc, s4, v2
	s_mov_b32 s4, 0x69000
	s_nop 0
	v_addc_co_u32_e32 v43, vcc, 0, v3, vcc
	v_add_co_u32_e32 v44, vcc, s4, v2
	s_mov_b32 s4, 0x6c000
	s_nop 0
	v_addc_co_u32_e32 v45, vcc, 0, v3, vcc
	v_add_co_u32_e32 v2, vcc, s4, v2
	s_lshl_b32 s88, s1, 8
	s_nop 0
	v_addc_co_u32_e32 v3, vcc, 0, v3, vcc
	global_load_dword v47, v[4:5], off
	global_load_dword v70, v[26:27], off offset:2048
	global_load_dword v71, v[36:37], off
	global_load_dword v72, v[38:39], off offset:2048
	s_nop 0
	global_load_dword v40, v[40:41], off
	s_nop 0
	global_load_dword v41, v[42:43], off offset:2048
	s_nop 0
	global_load_dword v42, v[44:45], off
	global_load_dword v43, v[2:3], off offset:2048
	v_lshl_add_u64 v[26:27], v[22:23], 0, s[88:89]
	global_load_dwordx4 v[2:5], v[26:27], off
	global_load_dwordx4 v[36:39], v[26:27], off offset:16
	s_waitcnt vmcnt(32)
	ds_write2_b32 v29, v0, v48 offset1:66
	s_waitcnt vmcnt(30)
	ds_write2_b32 v29, v49, v50 offset0:132 offset1:198
	v_add_u32_e32 v0, 0x400, v29
	s_waitcnt vmcnt(28)
; #define LAS __attribute__((address_space(3)))
; __device__ __forceinline__ unsigned pk2(float lo, float hi) { return f2bf(lo) | (f2bf(hi) << 16); }
; #define LDS_WAVE_SYNC() asm volatile("s_waitcnt lgkmcnt(0)" ::: "memory")
; template <bool HASG>
; __device__ __forceinline__ void tr_item(const float* W, int K, int N, bf16* WT, int rowmode, const float* g, LAS float* scr, int item, int lane) {
;     ...
;     for (int i = 0; i < 32; ++i) scr[(2 * i + (lane >> 5)) * 33 + (lane & 31)] = v[i];
;     LDS_WAVE_SYNC();
;     const int drow0 = rowmode == 0 ? n0 : ((n0 >> 7) * 256 + (n0 & 127) + (rowmode == 2 ? 128 : 0));
; #pragma unroll
;     for (int j = 0; j < 4; ++j) { const int n = (lane >> 3) + 8 * j; const LAS float* s = scr + (8 * c) * 33 + n;
;         u32x4 o; o.x = pk2(s[0 * 33] * g0.x, s[1 * 33] * g0.y); o.y = pk2(s[2 * 33] * g0.z, s[3 * 33] * g0.w);
;         o.z = pk2(s[4 * 33] * g1.x, s[5 * 33] * g1.y); o.w = pk2(s[6 * 33] * g1.z, s[7 * 33] * g1.w);
;         *(u32x4*)(WT + (size_t)(drow0 + n) * K + k0 + 8 * c) = o; }
	ds_write2_b32 v0, v51, v52 offset0:8 offset1:74
	s_waitcnt vmcnt(26)
	ds_write2_b32 v0, v53, v54 offset0:140 offset1:206
	v_add_u32_e32 v0, 0x800, v29
	s_waitcnt vmcnt(24)
	ds_write2_b32 v0, v55, v56 offset0:16 offset1:82
	s_waitcnt vmcnt(22)
	ds_write2_b32 v0, v57, v58 offset0:148 offset1:214
	v_add_u32_e32 v0, 0xc00, v29
	s_waitcnt vmcnt(20)
	ds_write2_b32 v0, v59, v60 offset0:24 offset1:90
	s_waitcnt vmcnt(18)
	ds_write2_b32 v0, v61, v62 offset0:156 offset1:222
	v_add_u32_e32 v0, 0x1000, v29
	s_waitcnt vmcnt(16)
	ds_write2_b32 v0, v63, v64 offset0:32 offset1:98
	s_waitcnt vmcnt(14)
	ds_write2_b32 v0, v65, v66 offset0:164 offset1:230
	v_add_u32_e32 v0, 0x1400, v29
	s_waitcnt vmcnt(12)
	ds_write2_b32 v0, v67, v68 offset0:40 offset1:106
	s_waitcnt vmcnt(10)
	ds_write2_b32 v0, v69, v46 offset0:172 offset1:238
	v_add_u32_e32 v0, 0x1800, v29
	s_waitcnt vmcnt(8)
	ds_write2_b32 v0, v47, v70 offset0:48 offset1:114
	s_waitcnt vmcnt(6)
	ds_write2_b32 v0, v71, v72 offset0:180 offset1:246
	v_add_u32_e32 v0, 0x1c00, v29
	s_waitcnt vmcnt(4)
	ds_write2_b32 v0, v40, v41 offset0:56 offset1:122
	s_waitcnt vmcnt(2)
	ds_write2_b32 v0, v42, v43 offset0:188 offset1:254
	s_waitcnt lgkmcnt(0)
	ds_read2_b32 v[44:45], v31 offset0:33 offset1:41
	ds_read2_b32 v[46:47], v31 offset1:8
	ds_read2_b32 v[48:49], v31 offset0:66 offset1:74
	ds_read2_b32 v[50:51], v31 offset0:99 offset1:107
	ds_read2_b32 v[54:55], v31 offset0:132 offset1:140
	ds_read2_b32 v[56:57], v31 offset0:165 offset1:173
	ds_read2_b32 v[58:59], v31 offset0:198 offset1:206
	ds_read2_b32 v[60:61], v31 offset0:231 offset1:239
	s_waitcnt vmcnt(1)
	v_mov_b32_e32 v52, v2
	v_mov_b32_e32 v53, v4
	v_mov_b32_e32 v4, v3
	s_waitcnt lgkmcnt(7)
	v_mov_b32_e32 v2, v44
	s_waitcnt lgkmcnt(4)
	v_mov_b32_e32 v3, v50
	s_waitcnt vmcnt(0)
	v_mov_b32_e32 v62, v36
	v_mov_b32_e32 v63, v38
	v_mov_b32_e32 v38, v37
	s_waitcnt lgkmcnt(2)
	v_mov_b32_e32 v36, v56
	s_waitcnt lgkmcnt(0)
	v_mov_b32_e32 v37, v60
	v_mov_b32_e32 v40, v46
	v_mov_b32_e32 v41, v48
	v_pk_mul_f32 v[2:3], v[4:5], v[2:3]
	v_mov_b32_e32 v42, v54
	v_mov_b32_e32 v43, v58
	v_pk_mul_f32 v[36:37], v[38:39], v[36:37]
	v_pk_mul_f32 v[40:41], v[52:53], v[40:41]
	v_pk_mul_f32 v[42:43], v[62:63], v[42:43]
	v_bfe_u32 v44, v36, 16, 1
	v_bfe_u32 v46, v3, 16, 1
	v_bfe_u32 v48, v2, 16, 1
	v_bfe_u32 v0, v37, 16, 1
	v_add3_u32 v2, v2, v48, s91
	v_add3_u32 v3, v3, v46, s91
	v_add3_u32 v36, v36, v44, s91
	v_bfe_u32 v44, v41, 16, 1
	v_bfe_u32 v46, v42, 16, 1
	v_bfe_u32 v48, v43, 16, 1
	v_add3_u32 v0, v37, v0, s91
	v_bfe_u32 v37, v40, 16, 1
	v_add3_u32 v43, v43, v48, s91
	v_add3_u32 v42, v42, v46, s91
	v_add3_u32 v41, v41, v44, s91
	v_add3_u32 v37, v40, v37, s91
	v_lshrrev_b32_e32 v40, 16, v41
	v_lshrrev_b32_e32 v41, 16, v42
	v_lshrrev_b32_e32 v42, 16, v43
	s_lshl_b32 s88, s1, 7
	v_and_or_b32 v43, v0, s35, v42
	v_or_b32_e32 v0, s0, v30
	v_lshl_add_u64 v[26:27], v[14:15], 0, s[88:89]
	v_lshrrev_b32_e32 v37, 16, v37
	v_lshlrev_b32_e32 v0, 11, v0
	v_mov_b32_e32 v50, v45
	v_and_or_b32 v42, v36, s35, v41
	v_and_or_b32 v41, v3, s35, v40
	v_and_or_b32 v40, v2, s35, v37
	v_lshl_add_u64 v[2:3], v[26:27], 0, v[0:1]
	v_pk_mul_f32 v[36:37], v[4:5], v[50:51]
	v_mov_b32_e32 v58, v55
	global_store_dwordx4 v[2:3], v[40:43], off sc1
	v_mov_b32_e32 v60, v57
	v_bfe_u32 v46, v36, 16, 1
	v_pk_mul_f32 v[40:41], v[62:63], v[58:59]
	v_mov_b32_e32 v48, v47
	v_pk_mul_f32 v[42:43], v[38:39], v[60:61]
	v_add3_u32 v36, v36, v46, s91
	v_bfe_u32 v46, v41, 16, 1
	v_pk_mul_f32 v[2:3], v[52:53], v[48:49]
	v_bfe_u32 v0, v43, 16, 1
	v_bfe_u32 v44, v42, 16, 1
	v_bfe_u32 v45, v37, 16, 1
	v_add3_u32 v41, v41, v46, s91
	v_add3_u32 v37, v37, v45, s91
	v_add3_u32 v42, v42, v44, s91
	v_add3_u32 v0, v43, v0, s91
	v_bfe_u32 v43, v2, 16, 1
	v_bfe_u32 v44, v3, 16, 1
	v_bfe_u32 v45, v40, 16, 1
	v_lshrrev_b32_e32 v41, 16, v41
	v_add3_u32 v40, v40, v45, s91
	v_add3_u32 v3, v3, v44, s91
	v_add3_u32 v2, v2, v43, s91
	v_and_or_b32 v43, v0, s35, v41
	v_or_b32_e32 v0, s0, v33
	v_lshrrev_b32_e32 v2, 16, v2
	v_lshrrev_b32_e32 v3, 16, v3
	v_lshrrev_b32_e32 v40, 16, v40
	v_lshlrev_b32_e32 v0, 11, v0
	v_and_or_b32 v42, v42, s35, v40
	v_and_or_b32 v41, v37, s35, v3
	v_and_or_b32 v40, v36, s35, v2
	v_lshl_add_u64 v[2:3], v[26:27], 0, v[0:1]
	ds_read2_b32 v[36:37], v31 offset0:16 offset1:24
	ds_read2_b32 v[44:45], v31 offset0:82 offset1:90
	global_store_dwordx4 v[2:3], v[40:43], off sc1
	ds_read2_b32 v[2:3], v31 offset0:49 offset1:57
	ds_read2_b32 v[46:47], v31 offset0:115 offset1:123
	ds_read2_b32 v[48:49], v31 offset0:148 offset1:156
	ds_read2_b32 v[50:51], v31 offset0:214 offset1:222
	ds_read2_b32 v[54:55], v31 offset0:181 offset1:189
	ds_read2_b32 v[56:57], v31 offset0:247 offset1:255
	s_waitcnt lgkmcnt(7)
; #define LAS __attribute__((address_space(3)))
; __device__ __forceinline__ unsigned pk2(float lo, float hi) { return f2bf(lo) | (f2bf(hi) << 16); }
; #define LDS_WAVE_SYNC() asm volatile("s_waitcnt lgkmcnt(0)" ::: "memory")
; template <bool HASG>
; __device__ __forceinline__ void tr_item(const float* W, int K, int N, bf16* WT, int rowmode, const float* g, LAS float* scr, int item, int lane) {
;     ...
;     for (int j = 0; j < 4; ++j) { const int n = (lane >> 3) + 8 * j; const LAS float* s = scr + (8 * c) * 33 + n;
;         u32x4 o; o.x = pk2(s[0 * 33] * g0.x, s[1 * 33] * g0.y); o.y = pk2(s[2 * 33] * g0.z, s[3 * 33] * g0.w);
;         o.z = pk2(s[4 * 33] * g1.x, s[5 * 33] * g1.y); o.w = pk2(s[6 * 33] * g1.z, s[7 * 33] * g1.w);
;         *(u32x4*)(WT + (size_t)(drow0 + n) * K + k0 + 8 * c) = o; }
;     LDS_WAVE_SYNC();
	v_mov_b32_e32 v40, v36
	s_waitcnt lgkmcnt(5)
	v_mov_b32_e32 v42, v2
	s_waitcnt lgkmcnt(4)
	v_mov_b32_e32 v43, v46
	s_waitcnt lgkmcnt(3)
	v_mov_b32_e32 v58, v48
	s_waitcnt lgkmcnt(2)
	v_mov_b32_e32 v59, v50
	v_mov_b32_e32 v41, v44
	v_pk_mul_f32 v[42:43], v[4:5], v[42:43]
	v_pk_mul_f32 v[58:59], v[62:63], v[58:59]
	s_waitcnt lgkmcnt(1)
	v_mov_b32_e32 v60, v54
	s_waitcnt lgkmcnt(0)
	v_mov_b32_e32 v61, v56
	v_pk_mul_f32 v[40:41], v[52:53], v[40:41]
	v_pk_mul_f32 v[60:61], v[38:39], v[60:61]
	v_bfe_u32 v36, v43, 16, 1
	v_bfe_u32 v48, v59, 16, 1
	v_bfe_u32 v0, v61, 16, 1
	v_bfe_u32 v44, v42, 16, 1
	v_add3_u32 v36, v43, v36, s91
	v_bfe_u32 v43, v41, 16, 1
	v_add3_u32 v48, v59, v48, s91
	v_add3_u32 v44, v42, v44, s91
	v_add3_u32 v0, v61, v0, s91
	v_bfe_u32 v42, v40, 16, 1
	v_bfe_u32 v46, v58, 16, 1
	v_add3_u32 v41, v41, v43, s91
	v_lshrrev_b32_e32 v43, 16, v48
	v_bfe_u32 v2, v60, 16, 1
	v_add3_u32 v46, v58, v46, s91
	v_add3_u32 v40, v40, v42, s91
	v_and_or_b32 v43, v0, s35, v43
	v_or_b32_e32 v0, s0, v34
	v_add3_u32 v2, v60, v2, s91
	v_lshrrev_b32_e32 v40, 16, v40
	v_lshrrev_b32_e32 v41, 16, v41
	v_lshrrev_b32_e32 v42, 16, v46
	v_lshlrev_b32_e32 v0, 11, v0
	v_mov_b32_e32 v46, v3
	v_and_or_b32 v42, v2, s35, v42
	v_and_or_b32 v41, v36, s35, v41
	v_and_or_b32 v40, v44, s35, v40
	v_lshl_add_u64 v[58:59], v[26:27], 0, v[0:1]
	v_pk_mul_f32 v[2:3], v[4:5], v[46:47]
	v_mov_b32_e32 v50, v49
	global_store_dwordx4 v[58:59], v[40:43], off sc1
	v_pk_mul_f32 v[4:5], v[62:63], v[50:51]
	v_mov_b32_e32 v56, v55
	v_bfe_u32 v42, v2, 16, 1
	v_mov_b32_e32 v44, v37
	v_pk_mul_f32 v[38:39], v[38:39], v[56:57]
	v_add3_u32 v2, v2, v42, s91
	v_bfe_u32 v42, v5, 16, 1
	v_pk_mul_f32 v[36:37], v[52:53], v[44:45]
	v_bfe_u32 v0, v39, 16, 1
	v_bfe_u32 v40, v38, 16, 1
	v_bfe_u32 v41, v3, 16, 1
	v_add3_u32 v5, v5, v42, s91
	v_add3_u32 v3, v3, v41, s91
	v_add3_u32 v38, v38, v40, s91
	v_add3_u32 v0, v39, v0, s91
	v_bfe_u32 v39, v36, 16, 1
	v_bfe_u32 v40, v37, 16, 1
	v_bfe_u32 v41, v4, 16, 1
	v_lshrrev_b32_e32 v5, 16, v5
	v_add3_u32 v4, v4, v41, s91
	v_add3_u32 v37, v37, v40, s91
	v_add3_u32 v36, v36, v39, s91
	v_and_or_b32 v5, v0, s35, v5
	v_or_b32_e32 v0, s0, v35
	v_lshrrev_b32_e32 v36, 16, v36
	v_lshrrev_b32_e32 v37, 16, v37
	v_lshrrev_b32_e32 v4, 16, v4
	v_lshlrev_b32_e32 v0, 11, v0
	v_and_or_b32 v4, v38, s35, v4
	v_and_or_b32 v3, v3, s35, v37
	v_and_or_b32 v2, v2, s35, v36
	v_lshl_add_u64 v[26:27], v[26:27], 0, v[0:1]
	global_store_dwordx4 v[26:27], v[2:5], off sc1
	s_waitcnt lgkmcnt(0)
	v_readlane_b32 s8, v252, 4
	v_readlane_b32 s9, v252, 5
	s_mov_b64 s[8:9], s[26:27]
	v_readlane_b32 s5, v252, 1
	v_readlane_b32 s6, v252, 2
	v_readlane_b32 s7, v252, 3
	v_readlane_b32 s10, v252, 6
	v_readlane_b32 s11, v252, 7
	v_readlane_b32 s12, v252, 8
	v_readlane_b32 s13, v252, 9
	v_readlane_b32 s14, v252, 10
	v_readlane_b32 s15, v252, 11
	v_readlane_b32 s18, v252, 14
	v_readlane_b32 s19, v252, 15

; template <bool HASG>
; __device__ __forceinline__ void tr_item(const float* W, int K, int N, bf16* WT, int rowmode, const float* g, LAS float* scr, int item, int lane) {
;     const int nblk = N / 32, kb = item / nblk, nb = item % nblk, k0 = 64 * kb, n0 = 32 * nb;
;     const float* wp = W + (size_t)(k0 + (lane >> 5)) * N + n0 + (lane & 31);
;     const int c = lane & 7;
;     float v[32];
; #pragma unroll
;     for (int i = 0; i < 32; ++i) v[i] = wp[(size_t)(2 * i) * N];
;     f32x4 g0 = (f32x4){1.f, 1.f, 1.f, 1.f}, g1 = g0;
;     if (HASG) { g0 = *(const f32x4*)(g + k0 + 8 * c); g1 = *(const f32x4*)(g + k0 + 8 * c + 4); }
;     asm volatile("" ::: "memory");
; #pragma unroll
;     for (int i = 0; i < 32; ++i) scr[(2 * i + (lane >> 5)) * 33 + (lane & 31)] = v[i];
; __device__ __forceinline__ void convert_items(const Args& a, LAS unsigned char* lds, int l, int it_lo, int it_hi, int gw, int NGW, int wave, int lane) {
;     ...
;         if (r < I_D) { tr_item<false>(a.in[4] + o_d, FF, D, wl + W_D1, 0, nullptr, scr, r, lane); continue; } r -= I_D;
.LBB0_532:
	s_andn2_b64 vcc, exec, s[0:1]
	s_cbranch_vccnz .LBB0_534
	s_add_i32 s0, s44, 0x2c00
	s_and_b32 s1, s0, 0x1ffc0
	s_lshl_b32 s0, s28, 5
	v_or_b32_e32 v0, s1, v28
	v_readlane_b32 s4, v252, 0
	s_and_b32 s0, s0, 0x3e0
	v_lshlrev_b32_e32 v0, 12, v0
	v_readlane_b32 s12, v252, 8
	v_readlane_b32 s13, v252, 9
	s_lshl_b32 s88, s0, 2
	s_movk_i32 s4, 0x2000
	v_lshl_add_u64 v[2:3], s[12:13], 0, v[0:1]
	v_lshl_add_u64 v[2:3], v[2:3], 0, s[88:89]
	v_lshlrev_b32_e32 v0, 2, v6
	v_lshl_add_u64 v[2:3], v[2:3], 0, v[0:1]
	v_add_co_u32_e32 v4, vcc, s4, v2
	s_movk_i32 s4, 0x4000
	s_nop 0
	v_addc_co_u32_e32 v5, vcc, 0, v3, vcc
	global_load_dword v0, v[2:3], off
	global_load_dword v26, v[4:5], off
	v_add_co_u32_e32 v4, vcc, s4, v2
	s_movk_i32 s4, 0x6000
	s_nop 0
	v_addc_co_u32_e32 v5, vcc, 0, v3, vcc
	global_load_dword v27, v[4:5], off
	v_add_co_u32_e32 v4, vcc, s4, v2
	s_mov_b32 s4, 0x8000
	s_nop 0
	v_addc_co_u32_e32 v5, vcc, 0, v3, vcc
	global_load_dword v36, v[4:5], off
	v_add_co_u32_e32 v4, vcc, s4, v2
	s_mov_b32 s4, 0xa000
	s_nop 0
	v_addc_co_u32_e32 v5, vcc, 0, v3, vcc
	global_load_dword v37, v[4:5], off
	v_add_co_u32_e32 v4, vcc, s4, v2
	s_mov_b32 s4, 0xc000
	s_nop 0
	v_addc_co_u32_e32 v5, vcc, 0, v3, vcc
	global_load_dword v38, v[4:5], off
	v_add_co_u32_e32 v4, vcc, s4, v2
	s_mov_b32 s4, 0xe000
	s_nop 0
	v_addc_co_u32_e32 v5, vcc, 0, v3, vcc
	global_load_dword v39, v[4:5], off
	v_add_co_u32_e32 v4, vcc, s4, v2
	s_mov_b32 s4, 0x12000
	s_nop 0
	v_addc_co_u32_e32 v5, vcc, 0, v3, vcc
	global_load_dword v40, v[4:5], off
	v_add_co_u32_e32 v4, vcc, s70, v2
	s_lshl_b32 s88, s1, 1
	s_nop 0
	v_addc_co_u32_e32 v5, vcc, 0, v3, vcc
	global_load_dword v41, v[4:5], off
	v_add_co_u32_e32 v4, vcc, s4, v2
	s_mov_b32 s4, 0x14000
	s_nop 0
	v_addc_co_u32_e32 v5, vcc, 0, v3, vcc
	global_load_dword v42, v[4:5], off
	v_add_co_u32_e32 v4, vcc, s4, v2
	s_mov_b32 s4, 0x18000
	s_nop 0
	v_addc_co_u32_e32 v5, vcc, 0, v3, vcc
	global_load_dword v43, v[4:5], off
	v_add_co_u32_e32 v4, vcc, s71, v2
	v_readlane_b32 s8, v252, 4
	s_nop 0
	v_addc_co_u32_e32 v5, vcc, 0, v3, vcc
	global_load_dword v44, v[4:5], off
	v_add_co_u32_e32 v4, vcc, s4, v2
	s_mov_b32 s4, 0x1a000
	s_nop 0
	v_addc_co_u32_e32 v5, vcc, 0, v3, vcc
	global_load_dword v45, v[4:5], off
	v_add_co_u32_e32 v4, vcc, s4, v2
	s_mov_b32 s4, 0x1c000
	s_nop 0
	v_addc_co_u32_e32 v5, vcc, 0, v3, vcc
	global_load_dword v46, v[4:5], off
	v_add_co_u32_e32 v4, vcc, s4, v2
	s_mov_b32 s4, 0x1e000
	s_nop 0
	v_addc_co_u32_e32 v5, vcc, 0, v3, vcc
	global_load_dword v47, v[4:5], off
	v_add_co_u32_e32 v4, vcc, s4, v2
	s_mov_b32 s4, 0x20000
	s_nop 0
	v_addc_co_u32_e32 v5, vcc, 0, v3, vcc
	global_load_dword v48, v[4:5], off
	v_add_co_u32_e32 v4, vcc, s4, v2
	s_mov_b32 s4, 0x22000
	s_nop 0
	v_addc_co_u32_e32 v5, vcc, 0, v3, vcc
	global_load_dword v49, v[4:5], off
	v_add_co_u32_e32 v4, vcc, s4, v2
	s_mov_b32 s4, 0x24000
	s_nop 0
	v_addc_co_u32_e32 v5, vcc, 0, v3, vcc
	global_load_dword v50, v[4:5], off
	v_add_co_u32_e32 v4, vcc, s4, v2
	s_mov_b32 s4, 0x26000
	s_nop 0
	v_addc_co_u32_e32 v5, vcc, 0, v3, vcc
	global_load_dword v51, v[4:5], off
	v_add_co_u32_e32 v4, vcc, s4, v2
	s_mov_b32 s4, 0x28000
	s_nop 0
	v_addc_co_u32_e32 v5, vcc, 0, v3, vcc
	global_load_dword v52, v[4:5], off
	v_add_co_u32_e32 v4, vcc, s4, v2
	s_mov_b32 s4, 0x2a000
	s_nop 0
	v_addc_co_u32_e32 v5, vcc, 0, v3, vcc
	global_load_dword v53, v[4:5], off
	v_add_co_u32_e32 v4, vcc, s4, v2
	s_mov_b32 s4, 0x2c000
	s_nop 0
	v_addc_co_u32_e32 v5, vcc, 0, v3, vcc
	global_load_dword v54, v[4:5], off
	v_add_co_u32_e32 v4, vcc, s4, v2
	s_mov_b32 s4, 0x2e000
	s_nop 0
	v_addc_co_u32_e32 v5, vcc, 0, v3, vcc
	global_load_dword v55, v[4:5], off
	v_add_co_u32_e32 v4, vcc, s4, v2
	s_mov_b32 s4, 0x30000
	s_nop 0
	v_addc_co_u32_e32 v5, vcc, 0, v3, vcc
	global_load_dword v56, v[4:5], off
	v_add_co_u32_e32 v4, vcc, s4, v2
	s_mov_b32 s4, 0x32000
	s_nop 0
	v_addc_co_u32_e32 v5, vcc, 0, v3, vcc
	global_load_dword v57, v[4:5], off
	v_add_co_u32_e32 v4, vcc, s4, v2
	s_mov_b32 s4, 0x34000
	s_nop 0
	v_addc_co_u32_e32 v5, vcc, 0, v3, vcc
	global_load_dword v58, v[4:5], off
	v_add_co_u32_e32 v4, vcc, s4, v2
	s_mov_b32 s4, 0x36000
	s_nop 0
	v_addc_co_u32_e32 v5, vcc, 0, v3, vcc
	global_load_dword v59, v[4:5], off
	v_add_co_u32_e32 v4, vcc, s4, v2
	s_mov_b32 s4, 0x38000
	s_nop 0
	v_addc_co_u32_e32 v5, vcc, 0, v3, vcc
	global_load_dword v60, v[4:5], off
	v_add_co_u32_e32 v4, vcc, s4, v2
	s_mov_b32 s4, 0x3a000
	s_nop 0
	v_addc_co_u32_e32 v5, vcc, 0, v3, vcc
	global_load_dword v61, v[4:5], off
	v_add_co_u32_e32 v4, vcc, s4, v2
	s_mov_b32 s4, 0x3c000
	s_nop 0
	v_addc_co_u32_e32 v5, vcc, 0, v3, vcc
	global_load_dword v62, v[4:5], off
	v_add_co_u32_e32 v4, vcc, s4, v2
	s_mov_b32 s4, 0x3e000
	s_nop 0
	v_addc_co_u32_e32 v5, vcc, 0, v3, vcc
	v_add_co_u32_e32 v2, vcc, s4, v2
	global_load_dword v4, v[4:5], off
	s_nop 0
	v_addc_co_u32_e32 v3, vcc, 0, v3, vcc
	global_load_dword v2, v[2:3], off
	s_waitcnt vmcnt(30)
	ds_write2_b32 v29, v0, v26 offset1:66
	s_waitcnt vmcnt(28)
	ds_write2_b32 v29, v27, v36 offset0:132 offset1:198
	v_add_u32_e32 v0, 0x400, v29
	s_waitcnt vmcnt(26)
	ds_write2_b32 v0, v37, v38 offset0:8 offset1:74
	s_waitcnt vmcnt(24)
	ds_write2_b32 v0, v39, v40 offset0:140 offset1:206
	v_add_u32_e32 v0, 0x800, v29
	s_waitcnt vmcnt(22)
	ds_write2_b32 v0, v41, v42 offset0:16 offset1:82
	s_waitcnt vmcnt(20)
	ds_write2_b32 v0, v43, v44 offset0:148 offset1:214
	v_add_u32_e32 v0, 0xc00, v29
	s_waitcnt vmcnt(18)
	ds_write2_b32 v0, v45, v46 offset0:24 offset1:90
	s_waitcnt vmcnt(16)
	ds_write2_b32 v0, v47, v48 offset0:156 offset1:222
	v_add_u32_e32 v0, 0x1000, v29
	s_waitcnt vmcnt(14)
; #define LAS __attribute__((address_space(3)))
; __device__ __forceinline__ unsigned pk2(float lo, float hi) { return f2bf(lo) | (f2bf(hi) << 16); }
; #define LDS_WAVE_SYNC() asm volatile("s_waitcnt lgkmcnt(0)" ::: "memory")
; template <bool HASG>
; __device__ __forceinline__ void tr_item(const float* W, int K, int N, bf16* WT, int rowmode, const float* g, LAS float* scr, int item, int lane) {
;     ...
;     for (int i = 0; i < 32; ++i) scr[(2 * i + (lane >> 5)) * 33 + (lane & 31)] = v[i];
;     LDS_WAVE_SYNC();
;     const int drow0 = rowmode == 0 ? n0 : ((n0 >> 7) * 256 + (n0 & 127) + (rowmode == 2 ? 128 : 0));
; #pragma unroll
;     for (int j = 0; j < 4; ++j) { const int n = (lane >> 3) + 8 * j; const LAS float* s = scr + (8 * c) * 33 + n;
;         u32x4 o; o.x = pk2(s[0 * 33] * g0.x, s[1 * 33] * g0.y); o.y = pk2(s[2 * 33] * g0.z, s[3 * 33] * g0.w);
;         o.z = pk2(s[4 * 33] * g1.x, s[5 * 33] * g1.y); o.w = pk2(s[6 * 33] * g1.z, s[7 * 33] * g1.w);
;         *(u32x4*)(WT + (size_t)(drow0 + n) * K + k0 + 8 * c) = o; }
;     LDS_WAVE_SYNC();
	ds_write2_b32 v0, v49, v50 offset0:32 offset1:98
	s_waitcnt vmcnt(12)
	ds_write2_b32 v0, v51, v52 offset0:164 offset1:230
	v_add_u32_e32 v0, 0x1400, v29
	s_waitcnt vmcnt(10)
	ds_write2_b32 v0, v53, v54 offset0:40 offset1:106
	s_waitcnt vmcnt(8)
	ds_write2_b32 v0, v55, v56 offset0:172 offset1:238
	v_add_u32_e32 v0, 0x1800, v29
	s_waitcnt vmcnt(6)
	ds_write2_b32 v0, v57, v58 offset0:48 offset1:114
	s_waitcnt vmcnt(4)
	ds_write2_b32 v0, v59, v60 offset0:180 offset1:246
	v_add_u32_e32 v0, 0x1c00, v29
	s_waitcnt vmcnt(2)
	ds_write2_b32 v0, v61, v62 offset0:56 offset1:122
	s_waitcnt vmcnt(0)
	ds_write2_b32 v0, v4, v2 offset0:188 offset1:254
	s_waitcnt lgkmcnt(0)
	ds_read2_b32 v[4:5], v31 offset0:33 offset1:41
	ds_read2_b32 v[26:27], v31 offset1:8
	ds_read2_b32 v[40:41], v31 offset0:66 offset1:74
	ds_read2_b32 v[42:43], v31 offset0:99 offset1:107
	ds_read2_b32 v[44:45], v31 offset0:132 offset1:140
	ds_read2_b32 v[46:47], v31 offset0:165 offset1:173
	ds_read2_b32 v[48:49], v31 offset0:198 offset1:206
	ds_read2_b32 v[50:51], v31 offset0:231 offset1:239
	v_lshl_add_u64 v[2:3], v[16:17], 0, s[88:89]
	s_waitcnt lgkmcnt(6)
	v_bfe_u32 v0, v26, 16, 1
	v_add3_u32 v0, v26, v0, s91
	v_bfe_u32 v26, v4, 16, 1
	v_lshrrev_b32_e32 v0, 16, v0
	v_add3_u32 v4, v4, v26, s91
	v_and_or_b32 v36, v4, s35, v0
	s_waitcnt lgkmcnt(5)
	v_bfe_u32 v0, v40, 16, 1
	v_add3_u32 v0, v40, v0, s91
	s_waitcnt lgkmcnt(4)
	v_bfe_u32 v4, v42, 16, 1
	v_lshrrev_b32_e32 v0, 16, v0
	v_add3_u32 v4, v42, v4, s91
	v_and_or_b32 v37, v4, s35, v0
	s_waitcnt lgkmcnt(3)
	v_bfe_u32 v0, v44, 16, 1
	v_add3_u32 v0, v44, v0, s91
	s_waitcnt lgkmcnt(2)
	v_bfe_u32 v4, v46, 16, 1
	v_lshrrev_b32_e32 v0, 16, v0
	v_add3_u32 v4, v46, v4, s91
	v_and_or_b32 v38, v4, s35, v0
	s_waitcnt lgkmcnt(1)
	v_bfe_u32 v0, v48, 16, 1
	v_add3_u32 v0, v48, v0, s91
	s_waitcnt lgkmcnt(0)
	v_bfe_u32 v4, v50, 16, 1
	v_lshrrev_b32_e32 v0, 16, v0
	v_add3_u32 v4, v50, v4, s91
	v_and_or_b32 v39, v4, s35, v0
	v_or_b32_e32 v0, s0, v30
	v_mul_u32_u24_e32 v0, 0xb00, v0
	v_lshlrev_b32_e32 v0, 1, v0
	v_lshl_add_u64 v[52:53], v[2:3], 0, v[0:1]
	v_bfe_u32 v0, v27, 16, 1
	v_add3_u32 v0, v27, v0, s91
	v_bfe_u32 v4, v5, 16, 1
	v_lshrrev_b32_e32 v0, 16, v0
	v_add3_u32 v4, v5, v4, s91
	global_store_dwordx4 v[52:53], v[36:39], off sc1
	v_readlane_b32 s9, v252, 5
	s_mov_b64 s[8:9], s[26:27]
	v_and_or_b32 v36, v4, s35, v0
	v_bfe_u32 v0, v41, 16, 1
	v_add3_u32 v0, v41, v0, s91
	v_bfe_u32 v4, v43, 16, 1
	v_lshrrev_b32_e32 v0, 16, v0
	v_add3_u32 v4, v43, v4, s91
	v_and_or_b32 v37, v4, s35, v0
	v_bfe_u32 v0, v45, 16, 1
	v_add3_u32 v0, v45, v0, s91
	v_bfe_u32 v4, v47, 16, 1
	v_lshrrev_b32_e32 v0, 16, v0
	v_add3_u32 v4, v47, v4, s91
	v_and_or_b32 v38, v4, s35, v0
	v_bfe_u32 v0, v49, 16, 1
	v_add3_u32 v0, v49, v0, s91
	v_bfe_u32 v4, v51, 16, 1
	v_lshrrev_b32_e32 v0, 16, v0
	v_add3_u32 v4, v51, v4, s91
	v_and_or_b32 v39, v4, s35, v0
	v_or_b32_e32 v0, s0, v33
	v_mul_u32_u24_e32 v0, 0xb00, v0
	v_lshlrev_b32_e32 v0, 1, v0
	v_lshl_add_u64 v[4:5], v[2:3], 0, v[0:1]
	global_store_dwordx4 v[4:5], v[36:39], off sc1
	ds_read2_b32 v[4:5], v31 offset0:16 offset1:24
	ds_read2_b32 v[26:27], v31 offset0:49 offset1:57
	ds_read2_b32 v[40:41], v31 offset0:82 offset1:90
	ds_read2_b32 v[42:43], v31 offset0:115 offset1:123
	ds_read2_b32 v[44:45], v31 offset0:148 offset1:156
	ds_read2_b32 v[46:47], v31 offset0:181 offset1:189
	ds_read2_b32 v[48:49], v31 offset0:214 offset1:222
	ds_read2_b32 v[50:51], v31 offset0:247 offset1:255
	s_waitcnt lgkmcnt(7)
	v_bfe_u32 v0, v4, 16, 1
	v_add3_u32 v0, v4, v0, s91
	s_waitcnt lgkmcnt(6)
	v_bfe_u32 v4, v26, 16, 1
	v_lshrrev_b32_e32 v0, 16, v0
	v_add3_u32 v4, v26, v4, s91
	v_and_or_b32 v36, v4, s35, v0
	s_waitcnt lgkmcnt(5)
	v_bfe_u32 v0, v40, 16, 1
	v_add3_u32 v0, v40, v0, s91
	s_waitcnt lgkmcnt(4)
	v_bfe_u32 v4, v42, 16, 1
	v_lshrrev_b32_e32 v0, 16, v0
	v_add3_u32 v4, v42, v4, s91
	v_and_or_b32 v37, v4, s35, v0
	s_waitcnt lgkmcnt(3)
	v_bfe_u32 v0, v44, 16, 1
	v_add3_u32 v0, v44, v0, s91
	s_waitcnt lgkmcnt(2)
	v_bfe_u32 v4, v46, 16, 1
	v_lshrrev_b32_e32 v0, 16, v0
	v_add3_u32 v4, v46, v4, s91
	v_and_or_b32 v38, v4, s35, v0
	s_waitcnt lgkmcnt(1)
	v_bfe_u32 v0, v48, 16, 1
	v_add3_u32 v0, v48, v0, s91
	s_waitcnt lgkmcnt(0)
	v_bfe_u32 v4, v50, 16, 1
	v_lshrrev_b32_e32 v0, 16, v0
	v_add3_u32 v4, v50, v4, s91
	v_and_or_b32 v39, v4, s35, v0
	v_or_b32_e32 v0, s0, v34
	v_mul_u32_u24_e32 v0, 0xb00, v0
	v_lshlrev_b32_e32 v0, 1, v0
	v_lshl_add_u64 v[52:53], v[2:3], 0, v[0:1]
	v_bfe_u32 v0, v5, 16, 1
	v_add3_u32 v0, v5, v0, s91
	v_bfe_u32 v4, v27, 16, 1
	v_lshrrev_b32_e32 v0, 16, v0
	v_add3_u32 v4, v27, v4, s91
	global_store_dwordx4 v[52:53], v[36:39], off sc1
	v_readlane_b32 s5, v252, 1
	v_readlane_b32 s6, v252, 2
	v_and_or_b32 v36, v4, s35, v0
	v_bfe_u32 v0, v41, 16, 1
	v_add3_u32 v0, v41, v0, s91
	v_bfe_u32 v4, v43, 16, 1
	v_lshrrev_b32_e32 v0, 16, v0
	v_add3_u32 v4, v43, v4, s91
	v_and_or_b32 v37, v4, s35, v0
	v_bfe_u32 v0, v45, 16, 1
	v_add3_u32 v0, v45, v0, s91
	v_bfe_u32 v4, v47, 16, 1
	v_lshrrev_b32_e32 v0, 16, v0
	v_add3_u32 v4, v47, v4, s91
	v_and_or_b32 v38, v4, s35, v0
	v_bfe_u32 v0, v49, 16, 1
	v_add3_u32 v0, v49, v0, s91
	v_bfe_u32 v4, v51, 16, 1
	v_lshrrev_b32_e32 v0, 16, v0
	v_add3_u32 v4, v51, v4, s91
	v_and_or_b32 v39, v4, s35, v0
	v_or_b32_e32 v0, s0, v35
	v_mul_u32_u24_e32 v0, 0xb00, v0
	v_lshlrev_b32_e32 v0, 1, v0
	v_lshl_add_u64 v[2:3], v[2:3], 0, v[0:1]
	global_store_dwordx4 v[2:3], v[36:39], off sc1
	s_waitcnt lgkmcnt(0)
	v_readlane_b32 s7, v252, 3
	v_readlane_b32 s10, v252, 6
	v_readlane_b32 s11, v252, 7
	v_readlane_b32 s14, v252, 10
	v_readlane_b32 s15, v252, 11
	v_readlane_b32 s16, v252, 12
	v_readlane_b32 s17, v252, 13
	v_readlane_b32 s18, v252, 14
	v_readlane_b32 s19, v252, 15

; template <bool HASG>
; __device__ __forceinline__ void tr_item(const float* W, int K, int N, bf16* WT, int rowmode, const float* g, LAS float* scr, int item, int lane) {
;     const int nblk = N / 32, kb = item / nblk, nb = item % nblk, k0 = 64 * kb, n0 = 32 * nb;
;     const float* wp = W + (size_t)(k0 + (lane >> 5)) * N + n0 + (lane & 31);
;     const int c = lane & 7;
;     float v[32];
; #pragma unroll
;     for (int i = 0; i < 32; ++i) v[i] = wp[(size_t)(2 * i) * N];
;     f32x4 g0 = (f32x4){1.f, 1.f, 1.f, 1.f}, g1 = g0;
;     if (HASG) { g0 = *(const f32x4*)(g + k0 + 8 * c); g1 = *(const f32x4*)(g + k0 + 8 * c + 4); }
; __device__ __forceinline__ void convert_items(const Args& a, LAS unsigned char* lds, int l, int it_lo, int it_hi, int gw, int NGW, int wave, int lane) {
;     ...
;         if (r < I_G) { tr_item<true>(a.in[3] + o_gu, D, FF, wl + W_GU1, 2, a.in[1] + l * D, scr, r, lane); continue; } r -= I_G;
.LBB0_535:
	s_andn2_b64 vcc, exec, s[0:1]
	s_cbranch_vccnz .LBB0_537
	s_add_i32 s0, s28, 0xfa80
	s_and_b32 s1, s0, 0xffff
	s_mul_i32 s1, s1, 0xba2f
	s_lshr_b32 s38, s1, 16
	s_lshr_b32 s1, s1, 22
	s_mulk_i32 s1, 0x58
	s_sub_i32 s0, s0, s1
	s_and_b32 s1, s38, 0xffc0
	v_or_b32_e32 v0, s1, v28
	v_mul_u32_u24_e32 v0, 0xb00, v0
	v_readlane_b32 s4, v252, 0
	s_and_b32 s39, s0, 0xffff
	v_lshlrev_b32_e32 v0, 2, v0
	v_readlane_b32 s10, v252, 6
	v_readlane_b32 s11, v252, 7
	s_lshl_b32 s88, s39, 7
	s_movk_i32 s4, 0x5000
	v_lshl_add_u64 v[2:3], s[10:11], 0, v[0:1]
	v_lshl_add_u64 v[2:3], v[2:3], 0, s[88:89]
	v_lshlrev_b32_e32 v0, 2, v6
	v_lshl_add_u64 v[2:3], v[2:3], 0, v[0:1]
	v_add_co_u32_e32 v4, vcc, s4, v2
	s_mov_b32 s4, 0x1b000
	s_nop 0
	v_addc_co_u32_e32 v5, vcc, 0, v3, vcc
	v_add_co_u32_e32 v26, vcc, s90, v2
	s_lshl_b32 s88, s1, 2
	s_nop 0
	v_addc_co_u32_e32 v27, vcc, 0, v3, vcc
	v_add_co_u32_e32 v36, vcc, s70, v2
	s_lshl_b32 s38, s0, 5
	s_nop 0
	v_addc_co_u32_e32 v37, vcc, 0, v3, vcc
	v_add_co_u32_e32 v38, vcc, s71, v2
	s_lshl_b32 s0, s0, 6
	s_nop 0
	v_addc_co_u32_e32 v39, vcc, 0, v3, vcc
	v_add_co_u32_e32 v40, vcc, s4, v2
	s_mov_b32 s4, 0x21000
	s_nop 0
	v_addc_co_u32_e32 v41, vcc, 0, v3, vcc
	v_add_co_u32_e32 v42, vcc, s4, v2
	s_mov_b32 s4, 0x26000
	s_nop 0
	v_addc_co_u32_e32 v43, vcc, 0, v3, vcc
	v_add_co_u32_e32 v44, vcc, s4, v2
	s_mov_b32 s4, 0x2c000
	s_nop 0
	v_addc_co_u32_e32 v45, vcc, 0, v3, vcc
	global_load_dword v0, v[2:3], off
	global_load_dword v48, v[4:5], off offset:2048
	global_load_dword v49, v[26:27], off
	global_load_dword v50, v[36:37], off offset:2048
	global_load_dword v51, v[38:39], off
	global_load_dword v52, v[40:41], off offset:2048
	global_load_dword v53, v[42:43], off
	global_load_dword v54, v[44:45], off offset:2048
	v_add_co_u32_e32 v4, vcc, s4, v2
	s_mov_b32 s4, 0x31000
	s_nop 0
	v_addc_co_u32_e32 v5, vcc, 0, v3, vcc
	v_add_co_u32_e32 v26, vcc, s4, v2
	s_mov_b32 s4, 0x37000
	s_nop 0
	v_addc_co_u32_e32 v27, vcc, 0, v3, vcc
	v_add_co_u32_e32 v36, vcc, s4, v2
	s_mov_b32 s4, 0x3c000
	s_nop 0
	v_addc_co_u32_e32 v37, vcc, 0, v3, vcc
	v_add_co_u32_e32 v38, vcc, s4, v2
	s_mov_b32 s4, 0x42000
	s_nop 0
	v_addc_co_u32_e32 v39, vcc, 0, v3, vcc
	v_add_co_u32_e32 v40, vcc, s4, v2
	s_mov_b32 s4, 0x47000
	s_nop 0
	v_addc_co_u32_e32 v41, vcc, 0, v3, vcc
	v_add_co_u32_e32 v42, vcc, s4, v2
	s_mov_b32 s4, 0x4d000
	s_nop 0
	v_addc_co_u32_e32 v43, vcc, 0, v3, vcc
	v_add_co_u32_e32 v44, vcc, s4, v2
	s_mov_b32 s4, 0x52000
	s_nop 0
	v_addc_co_u32_e32 v45, vcc, 0, v3, vcc
	v_add_co_u32_e32 v46, vcc, s4, v2
	s_mov_b32 s4, 0x58000
	s_nop 0
	v_addc_co_u32_e32 v47, vcc, 0, v3, vcc
	global_load_dword v55, v[4:5], off
	global_load_dword v56, v[26:27], off offset:2048
	global_load_dword v57, v[36:37], off
	global_load_dword v58, v[38:39], off offset:2048
	global_load_dword v59, v[40:41], off
	global_load_dword v60, v[42:43], off offset:2048
	global_load_dword v61, v[44:45], off
	global_load_dword v62, v[46:47], off offset:2048
	v_add_co_u32_e32 v4, vcc, s4, v2
	s_mov_b32 s4, 0x5d000
	s_nop 0
	v_addc_co_u32_e32 v5, vcc, 0, v3, vcc
	v_add_co_u32_e32 v26, vcc, s4, v2
	s_mov_b32 s4, 0x63000
	s_nop 0
	v_addc_co_u32_e32 v27, vcc, 0, v3, vcc
	v_add_co_u32_e32 v36, vcc, s4, v2
	s_mov_b32 s4, 0x68000
	s_nop 0
	v_addc_co_u32_e32 v37, vcc, 0, v3, vcc
	v_add_co_u32_e32 v38, vcc, s4, v2
	s_mov_b32 s4, 0x6e000
	s_nop 0
	v_addc_co_u32_e32 v39, vcc, 0, v3, vcc
	v_add_co_u32_e32 v40, vcc, s4, v2
	s_mov_b32 s4, 0x73000
	s_nop 0
	v_addc_co_u32_e32 v41, vcc, 0, v3, vcc
	v_add_co_u32_e32 v42, vcc, s4, v2
	s_mov_b32 s4, 0x79000
	s_nop 0
	v_addc_co_u32_e32 v43, vcc, 0, v3, vcc
	v_add_co_u32_e32 v44, vcc, s4, v2
	s_mov_b32 s4, 0x7e000
	s_nop 0
	v_addc_co_u32_e32 v45, vcc, 0, v3, vcc
	v_add_co_u32_e32 v46, vcc, s4, v2
	s_mov_b32 s4, 0x84000
	s_nop 0
	v_addc_co_u32_e32 v47, vcc, 0, v3, vcc
	global_load_dword v63, v[4:5], off
	global_load_dword v64, v[26:27], off offset:2048
	global_load_dword v65, v[36:37], off
	global_load_dword v66, v[38:39], off offset:2048
	global_load_dword v67, v[40:41], off
	global_load_dword v68, v[42:43], off offset:2048
	global_load_dword v69, v[44:45], off
	s_nop 0
	global_load_dword v46, v[46:47], off offset:2048
	v_add_co_u32_e32 v4, vcc, s4, v2
	s_mov_b32 s4, 0x89000
	s_nop 0
	v_addc_co_u32_e32 v5, vcc, 0, v3, vcc
	v_add_co_u32_e32 v26, vcc, s4, v2
	s_mov_b32 s4, 0x8f000
	s_nop 0
	v_addc_co_u32_e32 v27, vcc, 0, v3, vcc
	v_add_co_u32_e32 v36, vcc, s4, v2
	s_mov_b32 s4, 0x94000
	s_nop 0
	v_addc_co_u32_e32 v37, vcc, 0, v3, vcc
	v_add_co_u32_e32 v38, vcc, s4, v2
	s_mov_b32 s4, 0x9a000
	s_nop 0
	v_addc_co_u32_e32 v39, vcc, 0, v3, vcc
	v_add_co_u32_e32 v40, vcc, s4, v2
	s_mov_b32 s4, 0x9f000
	s_nop 0
	v_addc_co_u32_e32 v41, vcc, 0, v3, vcc
	v_add_co_u32_e32 v42, vcc, s4, v2
	s_mov_b32 s4, 0xa5000
	s_nop 0
	v_addc_co_u32_e32 v43, vcc, 0, v3, vcc
	v_add_co_u32_e32 v44, vcc, s4, v2
	s_mov_b32 s4, 0xaa000
	s_nop 0
	v_addc_co_u32_e32 v45, vcc, 0, v3, vcc
	v_add_co_u32_e32 v2, vcc, s4, v2
	s_and_b32 s0, s0, 0x1f00
	s_nop 0
	v_addc_co_u32_e32 v3, vcc, 0, v3, vcc
	global_load_dword v47, v[4:5], off
	s_nop 0
	global_load_dword v26, v[26:27], off offset:2048
	s_nop 0
	global_load_dword v27, v[36:37], off
	global_load_dword v70, v[38:39], off offset:2048
	s_nop 0
	global_load_dword v40, v[40:41], off
	s_nop 0
	global_load_dword v41, v[42:43], off offset:2048
	s_nop 0
	global_load_dword v42, v[44:45], off
	global_load_dword v43, v[2:3], off offset:2048
	v_lshl_add_u64 v[2:3], v[24:25], 0, s[88:89]
	global_load_dwordx4 v[36:39], v[2:3], off
	s_nop 0
	global_load_dwordx4 v[2:5], v[2:3], off offset:16
	s_waitcnt vmcnt(32)
	ds_write2_b32 v29, v0, v48 offset1:66
	s_waitcnt vmcnt(30)
; #define LAS __attribute__((address_space(3)))
; __device__ __forceinline__ unsigned pk2(float lo, float hi) { return f2bf(lo) | (f2bf(hi) << 16); }
; #define LDS_WAVE_SYNC() asm volatile("s_waitcnt lgkmcnt(0)" ::: "memory")
; template <bool HASG>
; __device__ __forceinline__ void tr_item(const float* W, int K, int N, bf16* WT, int rowmode, const float* g, LAS float* scr, int item, int lane) {
;     ...
;     for (int i = 0; i < 32; ++i) scr[(2 * i + (lane >> 5)) * 33 + (lane & 31)] = v[i];
;     LDS_WAVE_SYNC();
;     const int drow0 = rowmode == 0 ? n0 : ((n0 >> 7) * 256 + (n0 & 127) + (rowmode == 2 ? 128 : 0));
; #pragma unroll
;     for (int j = 0; j < 4; ++j) { const int n = (lane >> 3) + 8 * j; const LAS float* s = scr + (8 * c) * 33 + n;
;         u32x4 o; o.x = pk2(s[0 * 33] * g0.x, s[1 * 33] * g0.y); o.y = pk2(s[2 * 33] * g0.z, s[3 * 33] * g0.w);
;         o.z = pk2(s[4 * 33] * g1.x, s[5 * 33] * g1.y); o.w = pk2(s[6 * 33] * g1.z, s[7 * 33] * g1.w);
;         *(u32x4*)(WT + (size_t)(drow0 + n) * K + k0 + 8 * c) = o; }
	ds_write2_b32 v29, v49, v50 offset0:132 offset1:198
	v_add_u32_e32 v0, 0x400, v29
	s_waitcnt vmcnt(28)
	ds_write2_b32 v0, v51, v52 offset0:8 offset1:74
	s_waitcnt vmcnt(26)
	ds_write2_b32 v0, v53, v54 offset0:140 offset1:206
	v_add_u32_e32 v0, 0x800, v29
	s_waitcnt vmcnt(24)
	ds_write2_b32 v0, v55, v56 offset0:16 offset1:82
	s_waitcnt vmcnt(22)
	ds_write2_b32 v0, v57, v58 offset0:148 offset1:214
	v_add_u32_e32 v0, 0xc00, v29
	s_waitcnt vmcnt(20)
	ds_write2_b32 v0, v59, v60 offset0:24 offset1:90
	s_waitcnt vmcnt(18)
	ds_write2_b32 v0, v61, v62 offset0:156 offset1:222
	v_add_u32_e32 v0, 0x1000, v29
	s_waitcnt vmcnt(16)
	ds_write2_b32 v0, v63, v64 offset0:32 offset1:98
	s_waitcnt vmcnt(14)
	ds_write2_b32 v0, v65, v66 offset0:164 offset1:230
	v_add_u32_e32 v0, 0x1400, v29
	s_waitcnt vmcnt(12)
	ds_write2_b32 v0, v67, v68 offset0:40 offset1:106
	s_waitcnt vmcnt(10)
	ds_write2_b32 v0, v69, v46 offset0:172 offset1:238
	v_add_u32_e32 v0, 0x1800, v29
	s_waitcnt vmcnt(8)
	ds_write2_b32 v0, v47, v26 offset0:48 offset1:114
	s_waitcnt vmcnt(6)
	ds_write2_b32 v0, v27, v70 offset0:180 offset1:246
	v_add_u32_e32 v0, 0x1c00, v29
	s_waitcnt vmcnt(4)
	ds_write2_b32 v0, v40, v41 offset0:56 offset1:122
	s_waitcnt vmcnt(2)
	ds_write2_b32 v0, v42, v43 offset0:188 offset1:254
	s_waitcnt lgkmcnt(0)
	ds_read2_b32 v[44:45], v31 offset0:33 offset1:41
	ds_read2_b32 v[46:47], v31 offset1:8
	ds_read2_b32 v[48:49], v31 offset0:66 offset1:74
	ds_read2_b32 v[50:51], v31 offset0:99 offset1:107
	ds_read2_b32 v[54:55], v31 offset0:132 offset1:140
	ds_read2_b32 v[56:57], v31 offset0:165 offset1:173
	ds_read2_b32 v[58:59], v31 offset0:198 offset1:206
	ds_read2_b32 v[60:61], v31 offset0:231 offset1:239
	s_waitcnt vmcnt(1)
	v_mov_b32_e32 v52, v36
	v_mov_b32_e32 v53, v38
	v_mov_b32_e32 v38, v37
	s_waitcnt lgkmcnt(7)
	v_mov_b32_e32 v36, v44
	s_waitcnt lgkmcnt(4)
	v_mov_b32_e32 v37, v50
	s_waitcnt vmcnt(0)
	v_mov_b32_e32 v62, v2
	v_mov_b32_e32 v63, v4
	v_mov_b32_e32 v4, v3
	s_waitcnt lgkmcnt(2)
	v_mov_b32_e32 v2, v56
	s_waitcnt lgkmcnt(0)
	v_mov_b32_e32 v3, v60
	v_mov_b32_e32 v40, v46
	v_mov_b32_e32 v41, v48
	v_pk_mul_f32 v[36:37], v[38:39], v[36:37]
	v_mov_b32_e32 v42, v54
	v_mov_b32_e32 v43, v58
	v_pk_mul_f32 v[2:3], v[4:5], v[2:3]
	v_pk_mul_f32 v[40:41], v[52:53], v[40:41]
	v_pk_mul_f32 v[42:43], v[62:63], v[42:43]
	v_bfe_u32 v44, v2, 16, 1
	v_bfe_u32 v46, v37, 16, 1
	v_bfe_u32 v48, v36, 16, 1
	s_and_b32 s38, s38, 0x60
	v_bfe_u32 v0, v3, 16, 1
	v_add3_u32 v36, v36, v48, s91
	v_add3_u32 v37, v37, v46, s91
	v_add3_u32 v2, v2, v44, s91
	v_bfe_u32 v44, v41, 16, 1
	v_bfe_u32 v46, v42, 16, 1
	v_bfe_u32 v48, v43, 16, 1
	s_or_b32 s0, s38, s0
	v_add3_u32 v0, v3, v0, s91
	v_bfe_u32 v3, v40, 16, 1
	v_add3_u32 v43, v43, v48, s91
	v_add3_u32 v42, v42, v46, s91
	v_add3_u32 v41, v41, v44, s91
	s_bitset1_b32 s0, 7
	v_add3_u32 v3, v40, v3, s91
	v_lshrrev_b32_e32 v40, 16, v41
	v_lshrrev_b32_e32 v41, 16, v42
	v_lshrrev_b32_e32 v42, 16, v43
	s_lshl_b32 s88, s1, 1
	v_and_or_b32 v43, v0, s35, v42
	v_or_b32_e32 v0, s0, v30
	v_lshl_add_u64 v[26:27], v[18:19], 0, s[88:89]
	v_lshrrev_b32_e32 v3, 16, v3
	v_lshlrev_b32_e32 v0, 11, v0
	v_mov_b32_e32 v50, v45
	v_and_or_b32 v42, v2, s35, v41
	v_and_or_b32 v41, v37, s35, v40
	v_and_or_b32 v40, v36, s35, v3
	v_lshl_add_u64 v[2:3], v[26:27], 0, v[0:1]
	v_pk_mul_f32 v[36:37], v[38:39], v[50:51]
	v_mov_b32_e32 v58, v55
	global_store_dwordx4 v[2:3], v[40:43], off sc1
	v_mov_b32_e32 v60, v57
	v_bfe_u32 v46, v36, 16, 1
	v_pk_mul_f32 v[40:41], v[62:63], v[58:59]
	v_mov_b32_e32 v48, v47
	v_pk_mul_f32 v[42:43], v[4:5], v[60:61]
	v_add3_u32 v36, v36, v46, s91
	v_bfe_u32 v46, v41, 16, 1
	v_pk_mul_f32 v[2:3], v[52:53], v[48:49]
	v_bfe_u32 v0, v43, 16, 1
	v_bfe_u32 v44, v42, 16, 1
	v_bfe_u32 v45, v37, 16, 1
	v_add3_u32 v41, v41, v46, s91
	v_add3_u32 v37, v37, v45, s91
	v_add3_u32 v42, v42, v44, s91
	v_add3_u32 v0, v43, v0, s91
	v_bfe_u32 v43, v2, 16, 1
	v_bfe_u32 v44, v3, 16, 1
	v_bfe_u32 v45, v40, 16, 1
	v_lshrrev_b32_e32 v41, 16, v41
	v_add3_u32 v40, v40, v45, s91
	v_add3_u32 v3, v3, v44, s91
	v_add3_u32 v2, v2, v43, s91
	v_and_or_b32 v43, v0, s35, v41
	v_or_b32_e32 v0, s0, v33
	v_lshrrev_b32_e32 v2, 16, v2
	v_lshrrev_b32_e32 v3, 16, v3
	v_lshrrev_b32_e32 v40, 16, v40
	v_lshlrev_b32_e32 v0, 11, v0
	v_and_or_b32 v42, v42, s35, v40
	v_and_or_b32 v41, v37, s35, v3
	v_and_or_b32 v40, v36, s35, v2
	v_lshl_add_u64 v[2:3], v[26:27], 0, v[0:1]
	ds_read2_b32 v[36:37], v31 offset0:16 offset1:24
	ds_read2_b32 v[44:45], v31 offset0:82 offset1:90
	global_store_dwordx4 v[2:3], v[40:43], off sc1
	ds_read2_b32 v[2:3], v31 offset0:49 offset1:57
	ds_read2_b32 v[46:47], v31 offset0:115 offset1:123
	ds_read2_b32 v[48:49], v31 offset0:148 offset1:156
	ds_read2_b32 v[50:51], v31 offset0:214 offset1:222
	ds_read2_b32 v[54:55], v31 offset0:181 offset1:189
	ds_read2_b32 v[56:57], v31 offset0:247 offset1:255
	s_waitcnt lgkmcnt(7)
; #define LAS __attribute__((address_space(3)))
; __device__ __forceinline__ unsigned pk2(float lo, float hi) { return f2bf(lo) | (f2bf(hi) << 16); }
; #define LDS_WAVE_SYNC() asm volatile("s_waitcnt lgkmcnt(0)" ::: "memory")
; template <bool HASG>
; __device__ __forceinline__ void tr_item(const float* W, int K, int N, bf16* WT, int rowmode, const float* g, LAS float* scr, int item, int lane) {
;     ...
;     for (int j = 0; j < 4; ++j) { const int n = (lane >> 3) + 8 * j; const LAS float* s = scr + (8 * c) * 33 + n;
;         u32x4 o; o.x = pk2(s[0 * 33] * g0.x, s[1 * 33] * g0.y); o.y = pk2(s[2 * 33] * g0.z, s[3 * 33] * g0.w);
;         o.z = pk2(s[4 * 33] * g1.x, s[5 * 33] * g1.y); o.w = pk2(s[6 * 33] * g1.z, s[7 * 33] * g1.w);
;         *(u32x4*)(WT + (size_t)(drow0 + n) * K + k0 + 8 * c) = o; }
;     LDS_WAVE_SYNC();
	v_mov_b32_e32 v40, v36
	s_waitcnt lgkmcnt(5)
	v_mov_b32_e32 v42, v2
	s_waitcnt lgkmcnt(4)
	v_mov_b32_e32 v43, v46
	s_waitcnt lgkmcnt(3)
	v_mov_b32_e32 v58, v48
	s_waitcnt lgkmcnt(2)
	v_mov_b32_e32 v59, v50
	v_mov_b32_e32 v41, v44
	v_pk_mul_f32 v[42:43], v[38:39], v[42:43]
	v_pk_mul_f32 v[58:59], v[62:63], v[58:59]
	s_waitcnt lgkmcnt(1)
	v_mov_b32_e32 v60, v54
	s_waitcnt lgkmcnt(0)
	v_mov_b32_e32 v61, v56
	v_pk_mul_f32 v[40:41], v[52:53], v[40:41]
	v_pk_mul_f32 v[60:61], v[4:5], v[60:61]
	v_bfe_u32 v36, v43, 16, 1
	v_bfe_u32 v48, v59, 16, 1
	v_bfe_u32 v0, v61, 16, 1
	v_bfe_u32 v44, v42, 16, 1
	v_add3_u32 v36, v43, v36, s91
	v_bfe_u32 v43, v41, 16, 1
	v_add3_u32 v48, v59, v48, s91
	v_add3_u32 v44, v42, v44, s91
	v_add3_u32 v0, v61, v0, s91
	v_bfe_u32 v42, v40, 16, 1
	v_bfe_u32 v46, v58, 16, 1
	v_add3_u32 v41, v41, v43, s91
	v_lshrrev_b32_e32 v43, 16, v48
	v_bfe_u32 v2, v60, 16, 1
	v_add3_u32 v46, v58, v46, s91
	v_add3_u32 v40, v40, v42, s91
	v_and_or_b32 v43, v0, s35, v43
	v_or_b32_e32 v0, s0, v34
	v_add3_u32 v2, v60, v2, s91
	v_lshrrev_b32_e32 v40, 16, v40
	v_lshrrev_b32_e32 v41, 16, v41
	v_lshrrev_b32_e32 v42, 16, v46
	v_lshlrev_b32_e32 v0, 11, v0
	v_mov_b32_e32 v46, v3
	v_mov_b32_e32 v56, v55
	v_and_or_b32 v42, v2, s35, v42
	v_and_or_b32 v41, v36, s35, v41
	v_and_or_b32 v40, v44, s35, v40
	v_lshl_add_u64 v[58:59], v[26:27], 0, v[0:1]
	v_mov_b32_e32 v44, v37
	v_pk_mul_f32 v[2:3], v[38:39], v[46:47]
	v_mov_b32_e32 v50, v49
	v_pk_mul_f32 v[4:5], v[4:5], v[56:57]
	global_store_dwordx4 v[58:59], v[40:43], off sc1
	v_pk_mul_f32 v[36:37], v[52:53], v[44:45]
	v_pk_mul_f32 v[38:39], v[62:63], v[50:51]
	v_bfe_u32 v0, v5, 16, 1
	v_bfe_u32 v42, v2, 16, 1
	v_add3_u32 v2, v2, v42, s91
	v_add3_u32 v0, v5, v0, s91
	v_bfe_u32 v5, v36, 16, 1
	v_bfe_u32 v42, v39, 16, 1
	v_bfe_u32 v40, v4, 16, 1
	v_bfe_u32 v41, v3, 16, 1
	v_add3_u32 v39, v39, v42, s91
	v_add3_u32 v5, v36, v5, s91
	v_add3_u32 v3, v3, v41, s91
	v_add3_u32 v4, v4, v40, s91
	v_bfe_u32 v40, v37, 16, 1
	v_bfe_u32 v41, v38, 16, 1
	v_lshrrev_b32_e32 v36, 16, v5
	v_lshrrev_b32_e32 v5, 16, v39
	v_add3_u32 v38, v38, v41, s91
	v_add3_u32 v37, v37, v40, s91
	v_and_or_b32 v5, v0, s35, v5
	v_or_b32_e32 v0, s0, v35
	v_lshrrev_b32_e32 v37, 16, v37
	v_lshrrev_b32_e32 v38, 16, v38
	v_lshlrev_b32_e32 v0, 11, v0
	v_and_or_b32 v4, v4, s35, v38
	v_and_or_b32 v3, v3, s35, v37
	v_and_or_b32 v2, v2, s35, v36
	v_lshl_add_u64 v[26:27], v[26:27], 0, v[0:1]
	global_store_dwordx4 v[26:27], v[2:5], off sc1
	s_waitcnt lgkmcnt(0)
	v_readlane_b32 s8, v252, 4
	v_readlane_b32 s9, v252, 5
	s_mov_b64 s[8:9], s[26:27]
	v_readlane_b32 s5, v252, 1
	v_readlane_b32 s6, v252, 2
	v_readlane_b32 s7, v252, 3
	v_readlane_b32 s12, v252, 8
	v_readlane_b32 s13, v252, 9
	v_readlane_b32 s14, v252, 10
	v_readlane_b32 s15, v252, 11
	v_readlane_b32 s16, v252, 12
	v_readlane_b32 s17, v252, 13
	v_readlane_b32 s18, v252, 14
	v_readlane_b32 s19, v252, 15

; template <bool HASG>
; __device__ __forceinline__ void tr_item(const float* W, int K, int N, bf16* WT, int rowmode, const float* g, LAS float* scr, int item, int lane) {
;     const int nblk = N / 32, kb = item / nblk, nb = item % nblk, k0 = 64 * kb, n0 = 32 * nb;
;     const float* wp = W + (size_t)(k0 + (lane >> 5)) * N + n0 + (lane & 31);
;     const int c = lane & 7;
;     float v[32];
; #pragma unroll
;     for (int i = 0; i < 32; ++i) v[i] = wp[(size_t)(2 * i) * N];
;     f32x4 g0 = (f32x4){1.f, 1.f, 1.f, 1.f}, g1 = g0;
;     if (HASG) { g0 = *(const f32x4*)(g + k0 + 8 * c); g1 = *(const f32x4*)(g + k0 + 8 * c + 4); }
; __device__ __forceinline__ void convert_items(const Args& a, LAS unsigned char* lds, int l, int it_lo, int it_hi, int gw, int NGW, int wave, int lane) {
;     ...
;         if (r < I_G) { tr_item<true>(a.in[2] + o_gu, D, FF, wl + W_GU1, 1, a.in[1] + l * D, scr, r, lane); continue; } r -= I_G;
.LBB0_538:
	s_andn2_b64 vcc, exec, s[0:1]
	s_cbranch_vccnz .LBB0_511
	s_mul_hi_i32 s0, s28, 0x2e8ba2e9
	s_lshr_b32 s1, s0, 31
	s_ashr_i32 s47, s0, 4
	s_add_i32 s47, s47, s1
	v_readlane_b32 s4, v252, 0
	s_lshl_b32 s0, s47, 6
	s_mul_i32 s1, s47, 0xfffff500
	v_readlane_b32 s8, v252, 4
	v_readlane_b32 s9, v252, 5
	s_add_i32 s38, s29, s1
	v_or_b32_e32 v0, s0, v28
	v_mov_b64_e32 v[2:3], s[8:9]
	s_movk_i32 s1, 0x2c00
	v_mad_i64_i32 v[2:3], s[60:61], v0, s1, v[2:3]
	s_ashr_i32 s39, s38, 31
	v_lshl_add_u64 v[2:3], s[38:39], 2, v[2:3]
	v_lshlrev_b32_e32 v0, 2, v6
	v_lshl_add_u64 v[2:3], v[2:3], 0, v[0:1]
	s_movk_i32 s1, 0x5000
	v_add_co_u32_e32 v4, vcc, s1, v2
	s_mov_b32 s1, 0x1b000
	s_nop 0
	v_addc_co_u32_e32 v5, vcc, 0, v3, vcc
	v_add_co_u32_e32 v26, vcc, s90, v2
	s_mulk_i32 s47, 0xea00
	s_nop 0
	v_addc_co_u32_e32 v27, vcc, 0, v3, vcc
	v_add_co_u32_e32 v36, vcc, s70, v2
	s_add_i32 s39, s42, s47
	s_nop 0
	v_addc_co_u32_e32 v37, vcc, 0, v3, vcc
	v_add_co_u32_e32 v38, vcc, s71, v2
	s_and_b32 s39, s39, 0xffffff00
	s_nop 0
	v_addc_co_u32_e32 v39, vcc, 0, v3, vcc
	v_add_co_u32_e32 v40, vcc, s1, v2
	s_mov_b32 s1, 0x21000
	s_nop 0
	v_addc_co_u32_e32 v41, vcc, 0, v3, vcc
	v_add_co_u32_e32 v42, vcc, s1, v2
	s_mov_b32 s1, 0x26000
	s_nop 0
	v_addc_co_u32_e32 v43, vcc, 0, v3, vcc
	v_add_co_u32_e32 v44, vcc, s1, v2
	s_mov_b32 s1, 0x2c000
	s_nop 0
	v_addc_co_u32_e32 v45, vcc, 0, v3, vcc
	global_load_dword v0, v[2:3], off
	global_load_dword v48, v[4:5], off offset:2048
	global_load_dword v49, v[26:27], off
	global_load_dword v50, v[36:37], off offset:2048
	global_load_dword v51, v[38:39], off
	global_load_dword v52, v[40:41], off offset:2048
	global_load_dword v53, v[42:43], off
	global_load_dword v54, v[44:45], off offset:2048
	v_add_co_u32_e32 v4, vcc, s1, v2
	s_mov_b32 s1, 0x31000
	s_nop 0
	v_addc_co_u32_e32 v5, vcc, 0, v3, vcc
	v_add_co_u32_e32 v26, vcc, s1, v2
	s_mov_b32 s1, 0x37000
	s_nop 0
	v_addc_co_u32_e32 v27, vcc, 0, v3, vcc
	v_add_co_u32_e32 v36, vcc, s1, v2
	s_mov_b32 s1, 0x3c000
	s_nop 0
	v_addc_co_u32_e32 v37, vcc, 0, v3, vcc
	v_add_co_u32_e32 v38, vcc, s1, v2
	s_mov_b32 s1, 0x42000
	s_nop 0
	v_addc_co_u32_e32 v39, vcc, 0, v3, vcc
	v_add_co_u32_e32 v40, vcc, s1, v2
	s_mov_b32 s1, 0x47000
	s_nop 0
	v_addc_co_u32_e32 v41, vcc, 0, v3, vcc
	v_add_co_u32_e32 v42, vcc, s1, v2
	s_mov_b32 s1, 0x4d000
	s_nop 0
	v_addc_co_u32_e32 v43, vcc, 0, v3, vcc
	v_add_co_u32_e32 v44, vcc, s1, v2
	s_mov_b32 s1, 0x52000
	s_nop 0
	v_addc_co_u32_e32 v45, vcc, 0, v3, vcc
	v_add_co_u32_e32 v46, vcc, s1, v2
	s_mov_b32 s1, 0x58000
	s_nop 0
	v_addc_co_u32_e32 v47, vcc, 0, v3, vcc
	global_load_dword v55, v[4:5], off
	global_load_dword v56, v[26:27], off offset:2048
	global_load_dword v57, v[36:37], off
	global_load_dword v58, v[38:39], off offset:2048
	global_load_dword v59, v[40:41], off
	global_load_dword v60, v[42:43], off offset:2048
	global_load_dword v61, v[44:45], off
	global_load_dword v62, v[46:47], off offset:2048
	v_add_co_u32_e32 v4, vcc, s1, v2
	s_mov_b32 s1, 0x5d000
	s_nop 0
	v_addc_co_u32_e32 v5, vcc, 0, v3, vcc
	v_add_co_u32_e32 v26, vcc, s1, v2
	s_mov_b32 s1, 0x63000
	s_nop 0
	v_addc_co_u32_e32 v27, vcc, 0, v3, vcc
	v_add_co_u32_e32 v36, vcc, s1, v2
	s_mov_b32 s1, 0x68000
	s_nop 0
	v_addc_co_u32_e32 v37, vcc, 0, v3, vcc
	v_add_co_u32_e32 v38, vcc, s1, v2
	s_mov_b32 s1, 0x6e000
	s_nop 0
	v_addc_co_u32_e32 v39, vcc, 0, v3, vcc
	v_add_co_u32_e32 v40, vcc, s1, v2
	s_mov_b32 s1, 0x73000
	s_nop 0
	v_addc_co_u32_e32 v41, vcc, 0, v3, vcc
	v_add_co_u32_e32 v42, vcc, s1, v2
	s_mov_b32 s1, 0x79000
	s_nop 0
	v_addc_co_u32_e32 v43, vcc, 0, v3, vcc
	v_add_co_u32_e32 v44, vcc, s1, v2
	s_mov_b32 s1, 0x7e000
	s_nop 0
	v_addc_co_u32_e32 v45, vcc, 0, v3, vcc
	v_add_co_u32_e32 v46, vcc, s1, v2
	s_mov_b32 s1, 0x84000
	s_nop 0
	v_addc_co_u32_e32 v47, vcc, 0, v3, vcc
	global_load_dword v63, v[4:5], off
	global_load_dword v64, v[26:27], off offset:2048
	global_load_dword v65, v[36:37], off
	global_load_dword v66, v[38:39], off offset:2048
	global_load_dword v67, v[40:41], off
	global_load_dword v68, v[42:43], off offset:2048
	global_load_dword v69, v[44:45], off
	s_nop 0
	global_load_dword v46, v[46:47], off offset:2048
	v_add_co_u32_e32 v4, vcc, s1, v2
	s_mov_b32 s1, 0x89000
	s_nop 0
	v_addc_co_u32_e32 v5, vcc, 0, v3, vcc
	v_add_co_u32_e32 v26, vcc, s1, v2
	s_mov_b32 s1, 0x8f000
	s_nop 0
	v_addc_co_u32_e32 v27, vcc, 0, v3, vcc
	v_add_co_u32_e32 v36, vcc, s1, v2
	s_mov_b32 s1, 0x94000
	s_nop 0
	v_addc_co_u32_e32 v37, vcc, 0, v3, vcc
	v_add_co_u32_e32 v38, vcc, s1, v2
	s_mov_b32 s1, 0x9a000
	s_nop 0
	v_addc_co_u32_e32 v39, vcc, 0, v3, vcc
	v_add_co_u32_e32 v40, vcc, s1, v2
	s_mov_b32 s1, 0x9f000
	s_nop 0
	v_addc_co_u32_e32 v41, vcc, 0, v3, vcc
	v_add_co_u32_e32 v42, vcc, s1, v2
	s_mov_b32 s1, 0xa5000
	s_nop 0
	v_addc_co_u32_e32 v43, vcc, 0, v3, vcc
	v_add_co_u32_e32 v44, vcc, s1, v2
	s_mov_b32 s1, 0xaa000
	s_nop 0
	v_addc_co_u32_e32 v45, vcc, 0, v3, vcc
	v_add_co_u32_e32 v2, vcc, s1, v2
	s_ashr_i32 s1, s0, 31
	s_nop 0
	v_addc_co_u32_e32 v3, vcc, 0, v3, vcc
	global_load_dword v47, v[4:5], off
	s_nop 0
	global_load_dword v26, v[26:27], off offset:2048
	s_nop 0
	global_load_dword v27, v[36:37], off
	global_load_dword v70, v[38:39], off offset:2048
	s_nop 0
	global_load_dword v40, v[40:41], off
	s_nop 0
	global_load_dword v41, v[42:43], off offset:2048
	s_nop 0
	global_load_dword v42, v[44:45], off
	global_load_dword v43, v[2:3], off offset:2048
	v_lshl_add_u64 v[2:3], s[0:1], 2, v[24:25]
	global_load_dwordx4 v[36:39], v[2:3], off
	s_nop 0
	global_load_dwordx4 v[2:5], v[2:3], off offset:16
	s_waitcnt vmcnt(32)
	ds_write2_b32 v29, v0, v48 offset1:66
	s_waitcnt vmcnt(30)
; #define LAS __attribute__((address_space(3)))
; __device__ __forceinline__ unsigned pk2(float lo, float hi) { return f2bf(lo) | (f2bf(hi) << 16); }
; #define LDS_WAVE_SYNC() asm volatile("s_waitcnt lgkmcnt(0)" ::: "memory")
; template <bool HASG>
; __device__ __forceinline__ void tr_item(const float* W, int K, int N, bf16* WT, int rowmode, const float* g, LAS float* scr, int item, int lane) {
;     ...
;     for (int i = 0; i < 32; ++i) scr[(2 * i + (lane >> 5)) * 33 + (lane & 31)] = v[i];
;     LDS_WAVE_SYNC();
;     const int drow0 = rowmode == 0 ? n0 : ((n0 >> 7) * 256 + (n0 & 127) + (rowmode == 2 ? 128 : 0));
; #pragma unroll
;     for (int j = 0; j < 4; ++j) { const int n = (lane >> 3) + 8 * j; const LAS float* s = scr + (8 * c) * 33 + n;
;         u32x4 o; o.x = pk2(s[0 * 33] * g0.x, s[1 * 33] * g0.y); o.y = pk2(s[2 * 33] * g0.z, s[3 * 33] * g0.w);
;         o.z = pk2(s[4 * 33] * g1.x, s[5 * 33] * g1.y); o.w = pk2(s[6 * 33] * g1.z, s[7 * 33] * g1.w);
;         *(u32x4*)(WT + (size_t)(drow0 + n) * K + k0 + 8 * c) = o; }
	ds_write2_b32 v29, v49, v50 offset0:132 offset1:198
	v_add_u32_e32 v0, 0x400, v29
	s_waitcnt vmcnt(28)
	ds_write2_b32 v0, v51, v52 offset0:8 offset1:74
	s_waitcnt vmcnt(26)
	ds_write2_b32 v0, v53, v54 offset0:140 offset1:206
	v_add_u32_e32 v0, 0x800, v29
	s_waitcnt vmcnt(24)
	ds_write2_b32 v0, v55, v56 offset0:16 offset1:82
	s_waitcnt vmcnt(22)
	ds_write2_b32 v0, v57, v58 offset0:148 offset1:214
	v_add_u32_e32 v0, 0xc00, v29
	s_waitcnt vmcnt(20)
	ds_write2_b32 v0, v59, v60 offset0:24 offset1:90
	s_waitcnt vmcnt(18)
	ds_write2_b32 v0, v61, v62 offset0:156 offset1:222
	v_add_u32_e32 v0, 0x1000, v29
	s_waitcnt vmcnt(16)
	ds_write2_b32 v0, v63, v64 offset0:32 offset1:98
	s_waitcnt vmcnt(14)
	ds_write2_b32 v0, v65, v66 offset0:164 offset1:230
	v_add_u32_e32 v0, 0x1400, v29
	s_waitcnt vmcnt(12)
	ds_write2_b32 v0, v67, v68 offset0:40 offset1:106
	s_waitcnt vmcnt(10)
	ds_write2_b32 v0, v69, v46 offset0:172 offset1:238
	v_add_u32_e32 v0, 0x1800, v29
	s_waitcnt vmcnt(8)
	ds_write2_b32 v0, v47, v26 offset0:48 offset1:114
	s_waitcnt vmcnt(6)
	ds_write2_b32 v0, v27, v70 offset0:180 offset1:246
	v_add_u32_e32 v0, 0x1c00, v29
	s_waitcnt vmcnt(4)
	ds_write2_b32 v0, v40, v41 offset0:56 offset1:122
	s_waitcnt vmcnt(2)
	ds_write2_b32 v0, v42, v43 offset0:188 offset1:254
	s_waitcnt lgkmcnt(0)
	ds_read2_b32 v[44:45], v31 offset0:33 offset1:41
	ds_read2_b32 v[46:47], v31 offset1:8
	ds_read2_b32 v[48:49], v31 offset0:66 offset1:74
	ds_read2_b32 v[50:51], v31 offset0:99 offset1:107
	ds_read2_b32 v[54:55], v31 offset0:132 offset1:140
	ds_read2_b32 v[56:57], v31 offset0:165 offset1:173
	ds_read2_b32 v[58:59], v31 offset0:198 offset1:206
	ds_read2_b32 v[60:61], v31 offset0:231 offset1:239
	s_waitcnt vmcnt(1)
	v_mov_b32_e32 v52, v36
	v_mov_b32_e32 v53, v38
	v_mov_b32_e32 v38, v37
	s_waitcnt lgkmcnt(7)
	v_mov_b32_e32 v36, v44
	s_waitcnt lgkmcnt(4)
	v_mov_b32_e32 v37, v50
	s_waitcnt vmcnt(0)
	v_mov_b32_e32 v62, v2
	v_mov_b32_e32 v63, v4
	v_mov_b32_e32 v4, v3
	s_waitcnt lgkmcnt(2)
	v_mov_b32_e32 v2, v56
	s_waitcnt lgkmcnt(0)
	v_mov_b32_e32 v3, v60
	v_mov_b32_e32 v40, v46
	v_mov_b32_e32 v41, v48
	v_pk_mul_f32 v[36:37], v[38:39], v[36:37]
	v_mov_b32_e32 v42, v54
	v_mov_b32_e32 v43, v58
	v_pk_mul_f32 v[2:3], v[4:5], v[2:3]
	v_pk_mul_f32 v[40:41], v[52:53], v[40:41]
	v_pk_mul_f32 v[42:43], v[62:63], v[42:43]
	v_bfe_u32 v44, v2, 16, 1
	v_bfe_u32 v46, v37, 16, 1
	v_bfe_u32 v48, v36, 16, 1
	v_bfe_u32 v0, v3, 16, 1
	v_add3_u32 v36, v36, v48, s91
	v_add3_u32 v37, v37, v46, s91
	v_add3_u32 v2, v2, v44, s91
	v_bfe_u32 v44, v41, 16, 1
	v_bfe_u32 v46, v42, 16, 1
	v_bfe_u32 v48, v43, 16, 1
	s_and_b32 s38, s38, 0x60
	v_add3_u32 v0, v3, v0, s91
	v_bfe_u32 v3, v40, 16, 1
	v_add3_u32 v43, v43, v48, s91
	v_add3_u32 v42, v42, v46, s91
	v_add3_u32 v41, v41, v44, s91
	s_or_b32 s38, s38, s39
	v_add3_u32 v3, v40, v3, s91
	v_lshrrev_b32_e32 v40, 16, v41
	v_lshrrev_b32_e32 v41, 16, v42
	v_lshrrev_b32_e32 v42, 16, v43
	v_lshrrev_b32_e32 v3, 16, v3
	v_and_or_b32 v43, v0, s35, v42
	v_and_or_b32 v42, v2, s35, v41
	v_or_b32_e32 v2, s38, v30
	v_and_or_b32 v41, v37, s35, v40
	v_and_or_b32 v40, v36, s35, v3
	v_ashrrev_i32_e32 v3, 31, v2
	v_lshl_add_u64 v[26:27], s[0:1], 1, v[18:19]
	v_lshlrev_b64 v[2:3], 11, v[2:3]
	v_lshl_add_u64 v[2:3], v[26:27], 0, v[2:3]
	v_mov_b32_e32 v50, v45
	v_mov_b32_e32 v60, v57
	global_store_dwordx4 v[2:3], v[40:43], off sc1
	v_mov_b32_e32 v48, v47
	v_pk_mul_f32 v[36:37], v[38:39], v[50:51]
	v_mov_b32_e32 v58, v55
	v_pk_mul_f32 v[42:43], v[4:5], v[60:61]
	v_pk_mul_f32 v[2:3], v[52:53], v[48:49]
	v_pk_mul_f32 v[40:41], v[62:63], v[58:59]
	v_bfe_u32 v0, v43, 16, 1
	v_bfe_u32 v45, v37, 16, 1
	v_bfe_u32 v44, v42, 16, 1
	v_bfe_u32 v46, v36, 16, 1
	v_add3_u32 v37, v37, v45, s91
	v_add3_u32 v0, v43, v0, s91
	v_bfe_u32 v43, v2, 16, 1
	v_bfe_u32 v45, v40, 16, 1
	v_add3_u32 v36, v36, v46, s91
	v_add3_u32 v42, v42, v44, s91
	v_bfe_u32 v44, v3, 16, 1
	v_bfe_u32 v46, v41, 16, 1
	v_add3_u32 v40, v40, v45, s91
	v_add3_u32 v2, v2, v43, s91
	v_add3_u32 v41, v41, v46, s91
	v_add3_u32 v3, v3, v44, s91
	v_lshrrev_b32_e32 v2, 16, v2
	v_lshrrev_b32_e32 v40, 16, v40
	v_lshrrev_b32_e32 v3, 16, v3
	v_lshrrev_b32_e32 v41, 16, v41
	v_and_or_b32 v42, v42, s35, v40
	v_and_or_b32 v40, v36, s35, v2
	v_or_b32_e32 v2, s38, v33
	v_and_or_b32 v43, v0, s35, v41
	v_and_or_b32 v41, v37, s35, v3
	v_ashrrev_i32_e32 v3, 31, v2
	v_lshlrev_b64 v[2:3], 11, v[2:3]
	v_lshl_add_u64 v[2:3], v[26:27], 0, v[2:3]
	ds_read2_b32 v[36:37], v31 offset0:16 offset1:24
	ds_read2_b32 v[44:45], v31 offset0:82 offset1:90
	global_store_dwordx4 v[2:3], v[40:43], off sc1
	ds_read2_b32 v[2:3], v31 offset0:49 offset1:57
	ds_read2_b32 v[46:47], v31 offset0:115 offset1:123
	ds_read2_b32 v[48:49], v31 offset0:148 offset1:156
	ds_read2_b32 v[50:51], v31 offset0:214 offset1:222
	ds_read2_b32 v[54:55], v31 offset0:181 offset1:189
	ds_read2_b32 v[56:57], v31 offset0:247 offset1:255
	s_waitcnt lgkmcnt(7)
; #define LAS __attribute__((address_space(3)))
; __device__ __forceinline__ unsigned pk2(float lo, float hi) { return f2bf(lo) | (f2bf(hi) << 16); }
; #define LDS_WAVE_SYNC() asm volatile("s_waitcnt lgkmcnt(0)" ::: "memory")
; template <bool HASG>
; __device__ __forceinline__ void tr_item(const float* W, int K, int N, bf16* WT, int rowmode, const float* g, LAS float* scr, int item, int lane) {
;     ...
;     for (int j = 0; j < 4; ++j) { const int n = (lane >> 3) + 8 * j; const LAS float* s = scr + (8 * c) * 33 + n;
;         u32x4 o; o.x = pk2(s[0 * 33] * g0.x, s[1 * 33] * g0.y); o.y = pk2(s[2 * 33] * g0.z, s[3 * 33] * g0.w);
;         o.z = pk2(s[4 * 33] * g1.x, s[5 * 33] * g1.y); o.w = pk2(s[6 * 33] * g1.z, s[7 * 33] * g1.w);
;         *(u32x4*)(WT + (size_t)(drow0 + n) * K + k0 + 8 * c) = o; }
;     LDS_WAVE_SYNC();
	v_mov_b32_e32 v40, v36
	s_waitcnt lgkmcnt(5)
	v_mov_b32_e32 v42, v2
	s_waitcnt lgkmcnt(4)
	v_mov_b32_e32 v43, v46
	v_mov_b32_e32 v41, v44
	v_pk_mul_f32 v[42:43], v[38:39], v[42:43]
	s_waitcnt lgkmcnt(3)
	v_mov_b32_e32 v58, v48
	s_waitcnt lgkmcnt(2)
	v_mov_b32_e32 v59, v50
	v_pk_mul_f32 v[40:41], v[52:53], v[40:41]
	v_pk_mul_f32 v[58:59], v[62:63], v[58:59]
	v_bfe_u32 v44, v42, 16, 1
	s_waitcnt lgkmcnt(1)
	v_mov_b32_e32 v60, v54
	s_waitcnt lgkmcnt(0)
	v_mov_b32_e32 v61, v56
	v_bfe_u32 v36, v43, 16, 1
	v_add3_u32 v44, v42, v44, s91
	v_bfe_u32 v42, v40, 16, 1
	v_bfe_u32 v46, v58, 16, 1
	v_pk_mul_f32 v[60:61], v[4:5], v[60:61]
	v_add3_u32 v36, v43, v36, s91
	v_bfe_u32 v43, v41, 16, 1
	v_bfe_u32 v48, v59, 16, 1
	v_add3_u32 v46, v58, v46, s91
	v_add3_u32 v40, v40, v42, s91
	v_or_b32_e32 v58, s38, v34
	v_bfe_u32 v0, v61, 16, 1
	v_bfe_u32 v2, v60, 16, 1
	v_add3_u32 v48, v59, v48, s91
	v_add3_u32 v41, v41, v43, s91
	v_lshrrev_b32_e32 v40, 16, v40
	v_ashrrev_i32_e32 v59, 31, v58
	v_mov_b32_e32 v56, v55
	v_add3_u32 v2, v60, v2, s91
	v_add3_u32 v0, v61, v0, s91
	v_lshrrev_b32_e32 v41, 16, v41
	v_lshrrev_b32_e32 v42, 16, v46
	v_lshrrev_b32_e32 v43, 16, v48
	v_and_or_b32 v40, v44, s35, v40
	v_lshlrev_b64 v[58:59], 11, v[58:59]
	v_mov_b32_e32 v44, v37
	v_pk_mul_f32 v[4:5], v[4:5], v[56:57]
	v_and_or_b32 v43, v0, s35, v43
	v_and_or_b32 v42, v2, s35, v42
	v_and_or_b32 v41, v36, s35, v41
	v_lshl_add_u64 v[58:59], v[26:27], 0, v[58:59]
	v_pk_mul_f32 v[36:37], v[52:53], v[44:45]
	v_mov_b32_e32 v46, v3
	v_bfe_u32 v0, v5, 16, 1
	global_store_dwordx4 v[58:59], v[40:43], off sc1
	v_pk_mul_f32 v[2:3], v[38:39], v[46:47]
	v_add3_u32 v0, v5, v0, s91
	v_bfe_u32 v40, v4, 16, 1
	v_bfe_u32 v5, v36, 16, 1
	v_mov_b32_e32 v50, v49
	v_bfe_u32 v42, v2, 16, 1
	v_add3_u32 v4, v4, v40, s91
	v_bfe_u32 v40, v37, 16, 1
	v_add3_u32 v5, v36, v5, s91
	v_pk_mul_f32 v[38:39], v[62:63], v[50:51]
	v_bfe_u32 v41, v3, 16, 1
	v_add3_u32 v2, v2, v42, s91
	v_add3_u32 v37, v37, v40, s91
	v_lshrrev_b32_e32 v36, 16, v5
	v_add3_u32 v3, v3, v41, s91
	v_bfe_u32 v41, v38, 16, 1
	v_bfe_u32 v42, v39, 16, 1
	v_lshrrev_b32_e32 v37, 16, v37
	v_and_or_b32 v2, v2, s35, v36
	v_or_b32_e32 v36, s38, v35
	v_add3_u32 v39, v39, v42, s91
	v_add3_u32 v38, v38, v41, s91
	v_and_or_b32 v3, v3, s35, v37
	v_ashrrev_i32_e32 v37, 31, v36
	v_lshrrev_b32_e32 v38, 16, v38
	v_lshrrev_b32_e32 v5, 16, v39
	v_lshlrev_b64 v[36:37], 11, v[36:37]
	v_and_or_b32 v5, v0, s35, v5
	v_and_or_b32 v4, v4, s35, v38
	v_lshl_add_u64 v[26:27], v[26:27], 0, v[36:37]
	global_store_dwordx4 v[26:27], v[2:5], off sc1
	s_waitcnt lgkmcnt(0)
	s_mov_b64 s[8:9], s[26:27]
	v_readlane_b32 s5, v252, 1
	v_readlane_b32 s6, v252, 2
	v_readlane_b32 s7, v252, 3
	v_readlane_b32 s10, v252, 6
	v_readlane_b32 s11, v252, 7
	v_readlane_b32 s12, v252, 8
	v_readlane_b32 s13, v252, 9
	v_readlane_b32 s14, v252, 10
	v_readlane_b32 s15, v252, 11
	v_readlane_b32 s16, v252, 12
	v_readlane_b32 s17, v252, 13
	v_readlane_b32 s18, v252, 14
	v_readlane_b32 s19, v252, 15
	s_branch .LBB0_511

; template <bool HASG>
; __device__ __forceinline__ void tr_item(const float* W, int K, int N, bf16* WT, int rowmode, const float* g, LAS float* scr, int item, int lane) {
;     const int nblk = N / 32, kb = item / nblk, nb = item % nblk, k0 = 64 * kb, n0 = 32 * nb;
;     const float* wp = W + (size_t)(k0 + (lane >> 5)) * N + n0 + (lane & 31);
;     const int c = lane & 7;
;     float v[32];
; #pragma unroll
;     for (int i = 0; i < 32; ++i) v[i] = wp[(size_t)(2 * i) * N];
;     f32x4 g0 = (f32x4){1.f, 1.f, 1.f, 1.f}, g1 = g0;
;     if (HASG) { g0 = *(const f32x4*)(g + k0 + 8 * c); g1 = *(const f32x4*)(g + k0 + 8 * c + 4); }
; __device__ __forceinline__ void convert_items(const Args& a, LAS unsigned char* lds, int l, int it_lo, int it_hi, int gw, int NGW, int wave, int lane) {
;     ...
;         if (r < I_G) { tr_item<true>(a.in[2] + o_gu, D, FF, wl + W_GU1, 1, a.in[1] + l * D, scr, r, lane); continue; } r -= I_G;
;         if (r < I_G) { tr_item<true>(a.in[3] + o_gu, D, FF, wl + W_GU1, 2, a.in[1] + l * D, scr, r, lane); continue; } r -= I_G;
;         if (r < I_D) { tr_item<false>(a.in[4] + o_d, FF, D, wl + W_D1, 0, nullptr, scr, r, lane); continue; } r -= I_D;
;         if (r < I_IN) { tr_item<true>(a.in[6] + (size_t)l * D * DIN, D, DIN, wl + W_IN, 0, a.in[5] + l * D, scr, r, lane); continue; } r -= I_IN;
;         if (r < I_OUT) { tr_item<false>(a.in[18] + (size_t)l * D * D, D, D, wl + W_OUT, 0, nullptr, scr, r, lane); continue; } r -= I_OUT;
;         if (r < I_G) { tr_item<true>(a.in[20] + o_gu, D, FF, wl + W_GU2, 1, a.in[19] + l * D, scr, r, lane); continue; } r -= I_G;
;         if (r < I_G) { tr_item<true>(a.in[21] + o_gu, D, FF, wl + W_GU2, 2, a.in[19] + l * D, scr, r, lane); continue; } r -= I_G;
.LBB0_545:
	s_cmpk_gt_i32 s46, 0x57f
	s_mov_b64 s[0:1], -1
	s_cbranch_scc0 .LBB0_567
	s_cmpk_gt_u32 s46, 0xaff
	s_cbranch_scc0 .LBB0_564
	s_cmpk_gt_u32 s46, 0x107f
	s_cbranch_scc0 .LBB0_561
	s_cmpk_gt_u32 s46, 0x13ff
	s_cbranch_scc0 .LBB0_558
	s_cmpk_gt_u32 s46, 0x15ff
	s_cbranch_scc0 .LBB0_555
	s_cmpk_gt_u32 s46, 0x1b7f
	s_cbranch_scc0 .LBB0_552
	s_add_i32 s0, s46, 0xe480
	s_and_b32 s1, s0, 0xffff
	s_mul_i32 s1, s1, 0xba2f
	s_lshr_b32 s38, s1, 16
	s_lshr_b32 s1, s1, 22
	s_mulk_i32 s1, 0x58
	s_sub_i32 s0, s0, s1
	s_and_b32 s1, s38, 0xffc0
	v_or_b32_e32 v0, s1, v33
	v_mul_u32_u24_e32 v0, 0xb00, v0
	v_readlane_b32 s4, v252, 32
	s_and_b32 s39, s0, 0xffff
	v_lshlrev_b32_e32 v0, 2, v0
	v_readlane_b32 s14, v252, 42
	v_readlane_b32 s15, v252, 43
	v_readlane_b32 s5, v252, 33
	v_readlane_b32 s6, v252, 34
	v_readlane_b32 s7, v252, 35
	v_readlane_b32 s8, v252, 36
	v_readlane_b32 s9, v252, 37
	v_readlane_b32 s10, v252, 38
	v_readlane_b32 s11, v252, 39
	v_readlane_b32 s12, v252, 40
	v_readlane_b32 s13, v252, 41
	v_readlane_b32 s16, v252, 44
	v_readlane_b32 s17, v252, 45
	v_readlane_b32 s18, v252, 46
	v_readlane_b32 s19, v252, 47
	v_lshl_add_u64 v[2:3], s[14:15], 0, v[0:1]
	s_lshl_b32 s88, s39, 7
	v_readlane_b32 s4, v252, 0
	v_lshl_add_u64 v[2:3], v[2:3], 0, s[88:89]
	v_lshlrev_b32_e32 v0, 2, v6
	v_lshl_add_u64 v[2:3], v[2:3], 0, v[0:1]
	s_movk_i32 s4, 0x5000
	v_add_co_u32_e32 v4, vcc, s4, v2
	s_mov_b32 s4, 0x1b000
	s_nop 0
	v_addc_co_u32_e32 v5, vcc, 0, v3, vcc
	v_add_co_u32_e32 v24, vcc, s90, v2
	s_lshl_b32 s88, s1, 2
	s_nop 0
	v_addc_co_u32_e32 v25, vcc, 0, v3, vcc
	v_add_co_u32_e32 v36, vcc, s70, v2
	s_lshl_b32 s38, s0, 5
	s_nop 0
	v_addc_co_u32_e32 v37, vcc, 0, v3, vcc
	v_add_co_u32_e32 v38, vcc, s71, v2
	s_lshl_b32 s0, s0, 6
	s_nop 0
	v_addc_co_u32_e32 v39, vcc, 0, v3, vcc
	v_add_co_u32_e32 v40, vcc, s4, v2
	s_mov_b32 s4, 0x21000
	s_nop 0
	v_addc_co_u32_e32 v41, vcc, 0, v3, vcc
	v_add_co_u32_e32 v42, vcc, s4, v2
	s_mov_b32 s4, 0x26000
	s_nop 0
	v_addc_co_u32_e32 v43, vcc, 0, v3, vcc
	v_add_co_u32_e32 v44, vcc, s4, v2
	s_mov_b32 s4, 0x2c000
	s_nop 0
	v_addc_co_u32_e32 v45, vcc, 0, v3, vcc
	global_load_dword v0, v[2:3], off
	global_load_dword v48, v[4:5], off offset:2048
	global_load_dword v49, v[24:25], off
	global_load_dword v50, v[36:37], off offset:2048
	global_load_dword v51, v[38:39], off
	global_load_dword v52, v[40:41], off offset:2048
	global_load_dword v53, v[42:43], off
	global_load_dword v54, v[44:45], off offset:2048
	v_add_co_u32_e32 v4, vcc, s4, v2
	s_mov_b32 s4, 0x31000
	s_nop 0
	v_addc_co_u32_e32 v5, vcc, 0, v3, vcc
	v_add_co_u32_e32 v24, vcc, s4, v2
	s_mov_b32 s4, 0x37000
	s_nop 0
	v_addc_co_u32_e32 v25, vcc, 0, v3, vcc
	v_add_co_u32_e32 v36, vcc, s4, v2
	s_mov_b32 s4, 0x3c000
	s_nop 0
	v_addc_co_u32_e32 v37, vcc, 0, v3, vcc
	v_add_co_u32_e32 v38, vcc, s4, v2
	s_mov_b32 s4, 0x42000
	s_nop 0
	v_addc_co_u32_e32 v39, vcc, 0, v3, vcc
	v_add_co_u32_e32 v40, vcc, s4, v2
	s_mov_b32 s4, 0x47000
	s_nop 0
	v_addc_co_u32_e32 v41, vcc, 0, v3, vcc
	v_add_co_u32_e32 v42, vcc, s4, v2
	s_mov_b32 s4, 0x4d000
	s_nop 0
	v_addc_co_u32_e32 v43, vcc, 0, v3, vcc
	v_add_co_u32_e32 v44, vcc, s4, v2
	s_mov_b32 s4, 0x52000
	s_nop 0
	v_addc_co_u32_e32 v45, vcc, 0, v3, vcc
	v_add_co_u32_e32 v46, vcc, s4, v2
	s_mov_b32 s4, 0x58000
	s_nop 0
	v_addc_co_u32_e32 v47, vcc, 0, v3, vcc
	global_load_dword v55, v[4:5], off
	global_load_dword v56, v[24:25], off offset:2048
	global_load_dword v57, v[36:37], off
	global_load_dword v58, v[38:39], off offset:2048
	global_load_dword v59, v[40:41], off
	global_load_dword v60, v[42:43], off offset:2048
	global_load_dword v61, v[44:45], off
	global_load_dword v62, v[46:47], off offset:2048
	v_add_co_u32_e32 v4, vcc, s4, v2
	s_mov_b32 s4, 0x5d000
	s_nop 0
	v_addc_co_u32_e32 v5, vcc, 0, v3, vcc
	v_add_co_u32_e32 v24, vcc, s4, v2
	s_mov_b32 s4, 0x63000
	s_nop 0
	v_addc_co_u32_e32 v25, vcc, 0, v3, vcc
	v_add_co_u32_e32 v36, vcc, s4, v2
	s_mov_b32 s4, 0x68000
	s_nop 0
	v_addc_co_u32_e32 v37, vcc, 0, v3, vcc
	v_add_co_u32_e32 v38, vcc, s4, v2
	s_mov_b32 s4, 0x6e000
	s_nop 0
	v_addc_co_u32_e32 v39, vcc, 0, v3, vcc
	v_add_co_u32_e32 v40, vcc, s4, v2
	s_mov_b32 s4, 0x73000
	s_nop 0
	v_addc_co_u32_e32 v41, vcc, 0, v3, vcc
	v_add_co_u32_e32 v42, vcc, s4, v2
	s_mov_b32 s4, 0x79000
	s_nop 0
	v_addc_co_u32_e32 v43, vcc, 0, v3, vcc
	v_add_co_u32_e32 v44, vcc, s4, v2
	s_mov_b32 s4, 0x7e000
	s_nop 0
	v_addc_co_u32_e32 v45, vcc, 0, v3, vcc
	v_add_co_u32_e32 v46, vcc, s4, v2
	s_mov_b32 s4, 0x84000
	s_nop 0
	v_addc_co_u32_e32 v47, vcc, 0, v3, vcc
	global_load_dword v63, v[4:5], off
	global_load_dword v64, v[24:25], off offset:2048
	global_load_dword v65, v[36:37], off
	global_load_dword v66, v[38:39], off offset:2048
	global_load_dword v67, v[40:41], off
	global_load_dword v68, v[42:43], off offset:2048
	global_load_dword v69, v[44:45], off
	s_nop 0
	global_load_dword v46, v[46:47], off offset:2048
	v_add_co_u32_e32 v4, vcc, s4, v2
	s_mov_b32 s4, 0x89000
	s_nop 0
	v_addc_co_u32_e32 v5, vcc, 0, v3, vcc
	v_add_co_u32_e32 v24, vcc, s4, v2
	s_mov_b32 s4, 0x8f000
	s_nop 0
	v_addc_co_u32_e32 v25, vcc, 0, v3, vcc
	v_add_co_u32_e32 v36, vcc, s4, v2
	s_mov_b32 s4, 0x94000
	s_nop 0
	v_addc_co_u32_e32 v37, vcc, 0, v3, vcc
	v_add_co_u32_e32 v38, vcc, s4, v2
	s_mov_b32 s4, 0x9a000
	s_nop 0
	v_addc_co_u32_e32 v39, vcc, 0, v3, vcc
	v_add_co_u32_e32 v40, vcc, s4, v2
	s_mov_b32 s4, 0x9f000
	s_nop 0
	v_addc_co_u32_e32 v41, vcc, 0, v3, vcc
	v_add_co_u32_e32 v42, vcc, s4, v2
	s_mov_b32 s4, 0xa5000
	s_nop 0
	v_addc_co_u32_e32 v43, vcc, 0, v3, vcc
	v_add_co_u32_e32 v44, vcc, s4, v2
	s_mov_b32 s4, 0xaa000
	s_nop 0
	v_addc_co_u32_e32 v45, vcc, 0, v3, vcc
	v_add_co_u32_e32 v2, vcc, s4, v2
	s_and_b32 s0, s0, 0x1f00
	s_nop 0
	v_addc_co_u32_e32 v3, vcc, 0, v3, vcc
	global_load_dword v47, v[4:5], off
	s_nop 0
	global_load_dword v24, v[24:25], off offset:2048
	s_nop 0
	global_load_dword v25, v[36:37], off
	global_load_dword v70, v[38:39], off offset:2048
	s_nop 0
	global_load_dword v40, v[40:41], off
	s_nop 0
	global_load_dword v41, v[42:43], off offset:2048
	s_nop 0
	global_load_dword v42, v[44:45], off
	global_load_dword v43, v[2:3], off offset:2048
	v_lshl_add_u64 v[2:3], v[18:19], 0, s[88:89]
	global_load_dwordx4 v[36:39], v[2:3], off
	s_nop 0
	global_load_dwordx4 v[2:5], v[2:3], off offset:16
	s_waitcnt vmcnt(32)
; #define LAS __attribute__((address_space(3)))
; __device__ __forceinline__ unsigned pk2(float lo, float hi) { return f2bf(lo) | (f2bf(hi) << 16); }
; #define LDS_WAVE_SYNC() asm volatile("s_waitcnt lgkmcnt(0)" ::: "memory")
; template <bool HASG>
; __device__ __forceinline__ void tr_item(const float* W, int K, int N, bf16* WT, int rowmode, const float* g, LAS float* scr, int item, int lane) {
;     ...
;     for (int i = 0; i < 32; ++i) scr[(2 * i + (lane >> 5)) * 33 + (lane & 31)] = v[i];
;     LDS_WAVE_SYNC();
;     const int drow0 = rowmode == 0 ? n0 : ((n0 >> 7) * 256 + (n0 & 127) + (rowmode == 2 ? 128 : 0));
; #pragma unroll
;     for (int j = 0; j < 4; ++j) { const int n = (lane >> 3) + 8 * j; const LAS float* s = scr + (8 * c) * 33 + n;
;         u32x4 o; o.x = pk2(s[0 * 33] * g0.x, s[1 * 33] * g0.y); o.y = pk2(s[2 * 33] * g0.z, s[3 * 33] * g0.w);
;         o.z = pk2(s[4 * 33] * g1.x, s[5 * 33] * g1.y); o.w = pk2(s[6 * 33] * g1.z, s[7 * 33] * g1.w);
;         *(u32x4*)(WT + (size_t)(drow0 + n) * K + k0 + 8 * c) = o; }
	ds_write2_b32 v30, v0, v48 offset1:66
	s_waitcnt vmcnt(30)
	ds_write2_b32 v30, v49, v50 offset0:132 offset1:198
	v_add_u32_e32 v0, 0x400, v30
	s_waitcnt vmcnt(28)
	ds_write2_b32 v0, v51, v52 offset0:8 offset1:74
	s_waitcnt vmcnt(26)
	ds_write2_b32 v0, v53, v54 offset0:140 offset1:206
	v_add_u32_e32 v0, 0x800, v30
	s_waitcnt vmcnt(24)
	ds_write2_b32 v0, v55, v56 offset0:16 offset1:82
	s_waitcnt vmcnt(22)
	ds_write2_b32 v0, v57, v58 offset0:148 offset1:214
	v_add_u32_e32 v0, 0xc00, v30
	s_waitcnt vmcnt(20)
	ds_write2_b32 v0, v59, v60 offset0:24 offset1:90
	s_waitcnt vmcnt(18)
	ds_write2_b32 v0, v61, v62 offset0:156 offset1:222
	v_add_u32_e32 v0, 0x1000, v30
	s_waitcnt vmcnt(16)
	ds_write2_b32 v0, v63, v64 offset0:32 offset1:98
	s_waitcnt vmcnt(14)
	ds_write2_b32 v0, v65, v66 offset0:164 offset1:230
	v_add_u32_e32 v0, 0x1400, v30
	s_waitcnt vmcnt(12)
	ds_write2_b32 v0, v67, v68 offset0:40 offset1:106
	s_waitcnt vmcnt(10)
	ds_write2_b32 v0, v69, v46 offset0:172 offset1:238
	v_add_u32_e32 v0, 0x1800, v30
	s_waitcnt vmcnt(8)
	ds_write2_b32 v0, v47, v24 offset0:48 offset1:114
	s_waitcnt vmcnt(6)
	ds_write2_b32 v0, v25, v70 offset0:180 offset1:246
	v_add_u32_e32 v0, 0x1c00, v30
	s_waitcnt vmcnt(4)
	ds_write2_b32 v0, v40, v41 offset0:56 offset1:122
	s_waitcnt vmcnt(2)
	ds_write2_b32 v0, v42, v43 offset0:188 offset1:254
	s_waitcnt lgkmcnt(0)
	ds_read2_b32 v[44:45], v31 offset0:33 offset1:41
	ds_read2_b32 v[46:47], v31 offset1:8
	ds_read2_b32 v[48:49], v31 offset0:66 offset1:74
	ds_read2_b32 v[50:51], v31 offset0:99 offset1:107
	ds_read2_b32 v[54:55], v31 offset0:132 offset1:140
	ds_read2_b32 v[56:57], v31 offset0:165 offset1:173
	ds_read2_b32 v[58:59], v31 offset0:198 offset1:206
	ds_read2_b32 v[60:61], v31 offset0:231 offset1:239
	s_waitcnt vmcnt(1)
	v_mov_b32_e32 v52, v36
	v_mov_b32_e32 v53, v38
	v_mov_b32_e32 v38, v37
	s_waitcnt lgkmcnt(7)
	v_mov_b32_e32 v36, v44
	s_waitcnt lgkmcnt(4)
	v_mov_b32_e32 v37, v50
	s_waitcnt vmcnt(0)
	v_mov_b32_e32 v62, v2
	v_mov_b32_e32 v63, v4
	v_mov_b32_e32 v4, v3
	s_waitcnt lgkmcnt(2)
	v_mov_b32_e32 v2, v56
	s_waitcnt lgkmcnt(0)
	v_mov_b32_e32 v3, v60
	v_mov_b32_e32 v40, v46
	v_mov_b32_e32 v41, v48
	v_pk_mul_f32 v[36:37], v[38:39], v[36:37]
	v_mov_b32_e32 v42, v54
	v_mov_b32_e32 v43, v58
	v_pk_mul_f32 v[2:3], v[4:5], v[2:3]
	v_pk_mul_f32 v[40:41], v[52:53], v[40:41]
	v_pk_mul_f32 v[42:43], v[62:63], v[42:43]
	v_bfe_u32 v44, v2, 16, 1
	v_bfe_u32 v46, v37, 16, 1
	v_bfe_u32 v48, v36, 16, 1
	s_and_b32 s38, s38, 0x60
	v_bfe_u32 v0, v3, 16, 1
	v_add3_u32 v36, v36, v48, s91
	v_add3_u32 v37, v37, v46, s91
	v_add3_u32 v2, v2, v44, s91
	v_bfe_u32 v44, v41, 16, 1
	v_bfe_u32 v46, v42, 16, 1
	v_bfe_u32 v48, v43, 16, 1
	s_or_b32 s0, s38, s0
	v_add3_u32 v0, v3, v0, s91
	v_bfe_u32 v3, v40, 16, 1
	v_add3_u32 v43, v43, v48, s91
	v_add3_u32 v42, v42, v46, s91
	v_add3_u32 v41, v41, v44, s91
	s_bitset1_b32 s0, 7
	v_add3_u32 v3, v40, v3, s91
	v_lshrrev_b32_e32 v40, 16, v41
	v_lshrrev_b32_e32 v41, 16, v42
	v_lshrrev_b32_e32 v42, 16, v43
	s_lshl_b32 s88, s1, 1
	v_and_or_b32 v43, v0, s35, v42
	v_or_b32_e32 v0, s0, v7
	v_lshl_add_u64 v[24:25], v[8:9], 0, s[88:89]
	v_lshrrev_b32_e32 v3, 16, v3
	v_lshlrev_b32_e32 v0, 11, v0
	v_mov_b32_e32 v50, v45
	v_and_or_b32 v42, v2, s35, v41
	v_and_or_b32 v41, v37, s35, v40
	v_and_or_b32 v40, v36, s35, v3
	v_lshl_add_u64 v[2:3], v[24:25], 0, v[0:1]
	v_pk_mul_f32 v[36:37], v[38:39], v[50:51]
	v_mov_b32_e32 v58, v55
	global_store_dwordx4 v[2:3], v[40:43], off sc1
	v_mov_b32_e32 v60, v57
	v_bfe_u32 v46, v36, 16, 1
	v_pk_mul_f32 v[40:41], v[62:63], v[58:59]
	v_mov_b32_e32 v48, v47
	v_pk_mul_f32 v[42:43], v[4:5], v[60:61]
	v_add3_u32 v36, v36, v46, s91
	v_bfe_u32 v46, v41, 16, 1
	v_pk_mul_f32 v[2:3], v[52:53], v[48:49]
	v_bfe_u32 v0, v43, 16, 1
	v_bfe_u32 v44, v42, 16, 1
	v_bfe_u32 v45, v37, 16, 1
	v_add3_u32 v41, v41, v46, s91
	v_add3_u32 v37, v37, v45, s91
	v_add3_u32 v42, v42, v44, s91
	v_add3_u32 v0, v43, v0, s91
	v_bfe_u32 v43, v2, 16, 1
	v_bfe_u32 v44, v3, 16, 1
	v_bfe_u32 v45, v40, 16, 1
	v_lshrrev_b32_e32 v41, 16, v41
	v_add3_u32 v40, v40, v45, s91
	v_add3_u32 v3, v3, v44, s91
	v_add3_u32 v2, v2, v43, s91
	v_and_or_b32 v43, v0, s35, v41
	v_or_b32_e32 v0, s0, v32
	v_lshrrev_b32_e32 v2, 16, v2
	v_lshrrev_b32_e32 v3, 16, v3
	v_lshrrev_b32_e32 v40, 16, v40
	v_lshlrev_b32_e32 v0, 11, v0
	v_and_or_b32 v42, v42, s35, v40
	v_and_or_b32 v41, v37, s35, v3
	v_and_or_b32 v40, v36, s35, v2
	v_lshl_add_u64 v[2:3], v[24:25], 0, v[0:1]
	ds_read2_b32 v[36:37], v31 offset0:16 offset1:24
	ds_read2_b32 v[44:45], v31 offset0:82 offset1:90
	global_store_dwordx4 v[2:3], v[40:43], off sc1
	ds_read2_b32 v[2:3], v31 offset0:49 offset1:57
	ds_read2_b32 v[46:47], v31 offset0:115 offset1:123
	ds_read2_b32 v[48:49], v31 offset0:148 offset1:156
	ds_read2_b32 v[50:51], v31 offset0:214 offset1:222
	ds_read2_b32 v[54:55], v31 offset0:181 offset1:189
	ds_read2_b32 v[56:57], v31 offset0:247 offset1:255
	s_waitcnt lgkmcnt(7)
	v_mov_b32_e32 v40, v36
	s_waitcnt lgkmcnt(5)
	v_mov_b32_e32 v42, v2
	s_waitcnt lgkmcnt(4)
	v_mov_b32_e32 v43, v46
	s_waitcnt lgkmcnt(3)
	v_mov_b32_e32 v58, v48
	s_waitcnt lgkmcnt(2)
	v_mov_b32_e32 v59, v50
	v_mov_b32_e32 v41, v44
	v_pk_mul_f32 v[42:43], v[38:39], v[42:43]
	v_pk_mul_f32 v[58:59], v[62:63], v[58:59]
	s_waitcnt lgkmcnt(1)
	v_mov_b32_e32 v60, v54
	s_waitcnt lgkmcnt(0)
; #define LAS __attribute__((address_space(3)))
; __device__ __forceinline__ unsigned pk2(float lo, float hi) { return f2bf(lo) | (f2bf(hi) << 16); }
; #define LDS_WAVE_SYNC() asm volatile("s_waitcnt lgkmcnt(0)" ::: "memory")
; template <bool HASG>
; __device__ __forceinline__ void tr_item(const float* W, int K, int N, bf16* WT, int rowmode, const float* g, LAS float* scr, int item, int lane) {
;     const int nblk = N / 32, kb = item / nblk, nb = item % nblk, k0 = 64 * kb, n0 = 32 * nb;
;     const float* wp = W + (size_t)(k0 + (lane >> 5)) * N + n0 + (lane & 31);
;     const int c = lane & 7;
;     float v[32];
; #pragma unroll
;     for (int i = 0; i < 32; ++i) v[i] = wp[(size_t)(2 * i) * N];
;     ...
;     for (int j = 0; j < 4; ++j) { const int n = (lane >> 3) + 8 * j; const LAS float* s = scr + (8 * c) * 33 + n;
;         u32x4 o; o.x = pk2(s[0 * 33] * g0.x, s[1 * 33] * g0.y); o.y = pk2(s[2 * 33] * g0.z, s[3 * 33] * g0.w);
;         o.z = pk2(s[4 * 33] * g1.x, s[5 * 33] * g1.y); o.w = pk2(s[6 * 33] * g1.z, s[7 * 33] * g1.w);
;         *(u32x4*)(WT + (size_t)(drow0 + n) * K + k0 + 8 * c) = o; }
;     LDS_WAVE_SYNC();
	v_mov_b32_e32 v61, v56
	v_pk_mul_f32 v[40:41], v[52:53], v[40:41]
	v_pk_mul_f32 v[60:61], v[4:5], v[60:61]
	v_bfe_u32 v36, v43, 16, 1
	v_bfe_u32 v48, v59, 16, 1
	v_bfe_u32 v0, v61, 16, 1
	v_bfe_u32 v44, v42, 16, 1
	v_add3_u32 v36, v43, v36, s91
	v_bfe_u32 v43, v41, 16, 1
	v_add3_u32 v48, v59, v48, s91
	v_add3_u32 v44, v42, v44, s91
	v_add3_u32 v0, v61, v0, s91
	v_bfe_u32 v42, v40, 16, 1
	v_bfe_u32 v46, v58, 16, 1
	v_add3_u32 v41, v41, v43, s91
	v_lshrrev_b32_e32 v43, 16, v48
	v_bfe_u32 v2, v60, 16, 1
	v_add3_u32 v46, v58, v46, s91
	v_add3_u32 v40, v40, v42, s91
	v_and_or_b32 v43, v0, s35, v43
	v_or_b32_e32 v0, s0, v34
	v_add3_u32 v2, v60, v2, s91
	v_lshrrev_b32_e32 v40, 16, v40
	v_lshrrev_b32_e32 v41, 16, v41
	v_lshrrev_b32_e32 v42, 16, v46
	v_lshlrev_b32_e32 v0, 11, v0
	v_mov_b32_e32 v46, v3
	v_mov_b32_e32 v56, v55
	v_and_or_b32 v42, v2, s35, v42
	v_and_or_b32 v41, v36, s35, v41
	v_and_or_b32 v40, v44, s35, v40
	v_lshl_add_u64 v[58:59], v[24:25], 0, v[0:1]
	v_mov_b32_e32 v44, v37
	v_pk_mul_f32 v[2:3], v[38:39], v[46:47]
	v_mov_b32_e32 v50, v49
	v_pk_mul_f32 v[4:5], v[4:5], v[56:57]
	global_store_dwordx4 v[58:59], v[40:43], off sc1
	v_pk_mul_f32 v[36:37], v[52:53], v[44:45]
	v_pk_mul_f32 v[38:39], v[62:63], v[50:51]
	v_bfe_u32 v0, v5, 16, 1
	v_bfe_u32 v42, v2, 16, 1
	v_add3_u32 v2, v2, v42, s91
	v_add3_u32 v0, v5, v0, s91
	v_bfe_u32 v5, v36, 16, 1
	v_bfe_u32 v42, v39, 16, 1
	v_bfe_u32 v40, v4, 16, 1
	v_bfe_u32 v41, v3, 16, 1
	v_add3_u32 v39, v39, v42, s91
	v_add3_u32 v5, v36, v5, s91
	v_add3_u32 v3, v3, v41, s91
	v_add3_u32 v4, v4, v40, s91
	v_bfe_u32 v40, v37, 16, 1
	v_bfe_u32 v41, v38, 16, 1
	v_lshrrev_b32_e32 v36, 16, v5
	v_lshrrev_b32_e32 v5, 16, v39
	v_add3_u32 v38, v38, v41, s91
	v_add3_u32 v37, v37, v40, s91
	v_and_or_b32 v5, v0, s35, v5
	v_or_b32_e32 v0, s0, v35
	v_lshrrev_b32_e32 v37, 16, v37
	v_lshrrev_b32_e32 v38, 16, v38
	v_lshlrev_b32_e32 v0, 11, v0
	v_and_or_b32 v4, v4, s35, v38
	v_and_or_b32 v3, v3, s35, v37
	v_and_or_b32 v2, v2, s35, v36
	v_lshl_add_u64 v[24:25], v[24:25], 0, v[0:1]
	global_store_dwordx4 v[24:25], v[2:5], off sc1
	s_waitcnt lgkmcnt(0)
	v_readlane_b32 s8, v252, 4
	v_readlane_b32 s9, v252, 5
	v_readlane_b32 s5, v252, 1
	v_readlane_b32 s6, v252, 2
	v_readlane_b32 s7, v252, 3
	v_readlane_b32 s10, v252, 6
	v_readlane_b32 s11, v252, 7
	v_readlane_b32 s12, v252, 8
	v_readlane_b32 s13, v252, 9
	v_readlane_b32 s14, v252, 10
	v_readlane_b32 s15, v252, 11
	v_readlane_b32 s16, v252, 12
	v_readlane_b32 s17, v252, 13
	v_readlane_b32 s18, v252, 14
	v_readlane_b32 s19, v252, 15
	s_mov_b64 s[8:9], s[26:27]
	s_mov_b64 s[0:1], 0
.LBB0_552:
	s_andn2_b64 vcc, exec, s[0:1]
	s_cbranch_vccnz .LBB0_554
	s_add_i32 s0, s46, 0xea00
	s_and_b32 s1, s0, 0xffff
	s_mul_i32 s1, s1, 0xba2f
	s_lshr_b32 s38, s1, 16
	s_lshr_b32 s1, s1, 22
	s_mulk_i32 s1, 0x58
	s_sub_i32 s0, s0, s1
	s_and_b32 s1, s38, 0xffc0
	v_or_b32_e32 v0, s1, v33
	v_mul_u32_u24_e32 v0, 0xb00, v0
	v_readlane_b32 s4, v252, 32
	s_and_b32 s39, s0, 0xffff
	v_lshlrev_b32_e32 v0, 2, v0
	v_readlane_b32 s12, v252, 40
	v_readlane_b32 s13, v252, 41
	v_readlane_b32 s5, v252, 33
	v_readlane_b32 s6, v252, 34
	v_readlane_b32 s7, v252, 35
	v_readlane_b32 s8, v252, 36
	v_readlane_b32 s9, v252, 37
	v_readlane_b32 s10, v252, 38
	v_readlane_b32 s11, v252, 39
	v_readlane_b32 s14, v252, 42
	v_readlane_b32 s15, v252, 43
	v_readlane_b32 s16, v252, 44
	v_readlane_b32 s17, v252, 45
	v_readlane_b32 s18, v252, 46
	v_readlane_b32 s19, v252, 47
	v_lshl_add_u64 v[2:3], s[12:13], 0, v[0:1]
	s_lshl_b32 s88, s39, 7
	v_readlane_b32 s4, v252, 0
	v_lshl_add_u64 v[2:3], v[2:3], 0, s[88:89]
	v_lshlrev_b32_e32 v0, 2, v6
	v_lshl_add_u64 v[2:3], v[2:3], 0, v[0:1]
	s_movk_i32 s4, 0x5000
	v_add_co_u32_e32 v4, vcc, s4, v2
	s_mov_b32 s4, 0x1b000
	s_nop 0
	v_addc_co_u32_e32 v5, vcc, 0, v3, vcc
	v_add_co_u32_e32 v24, vcc, s90, v2
	s_lshl_b32 s88, s1, 2
	s_nop 0
	v_addc_co_u32_e32 v25, vcc, 0, v3, vcc
	v_add_co_u32_e32 v36, vcc, s70, v2
	s_lshl_b32 s38, s0, 5
	s_nop 0
	v_addc_co_u32_e32 v37, vcc, 0, v3, vcc
	v_add_co_u32_e32 v38, vcc, s71, v2
	s_lshl_b32 s0, s0, 6
	s_nop 0
	v_addc_co_u32_e32 v39, vcc, 0, v3, vcc
	v_add_co_u32_e32 v40, vcc, s4, v2
	s_mov_b32 s4, 0x21000
	s_nop 0
	v_addc_co_u32_e32 v41, vcc, 0, v3, vcc
	v_add_co_u32_e32 v42, vcc, s4, v2
	s_mov_b32 s4, 0x26000
	s_nop 0
	v_addc_co_u32_e32 v43, vcc, 0, v3, vcc
	v_add_co_u32_e32 v44, vcc, s4, v2
	s_mov_b32 s4, 0x2c000
	s_nop 0
	v_addc_co_u32_e32 v45, vcc, 0, v3, vcc
	global_load_dword v0, v[2:3], off
	global_load_dword v48, v[4:5], off offset:2048
	global_load_dword v49, v[24:25], off
	global_load_dword v50, v[36:37], off offset:2048
	global_load_dword v51, v[38:39], off
	global_load_dword v52, v[40:41], off offset:2048
	global_load_dword v53, v[42:43], off
	global_load_dword v54, v[44:45], off offset:2048
	v_add_co_u32_e32 v4, vcc, s4, v2
	s_mov_b32 s4, 0x31000
	s_nop 0
	v_addc_co_u32_e32 v5, vcc, 0, v3, vcc
	v_add_co_u32_e32 v24, vcc, s4, v2
	s_mov_b32 s4, 0x37000
	s_nop 0
	v_addc_co_u32_e32 v25, vcc, 0, v3, vcc
	v_add_co_u32_e32 v36, vcc, s4, v2
	s_mov_b32 s4, 0x3c000
	s_nop 0
	v_addc_co_u32_e32 v37, vcc, 0, v3, vcc
	v_add_co_u32_e32 v38, vcc, s4, v2
	s_mov_b32 s4, 0x42000
	s_nop 0
	v_addc_co_u32_e32 v39, vcc, 0, v3, vcc
	v_add_co_u32_e32 v40, vcc, s4, v2
	s_mov_b32 s4, 0x47000
	s_nop 0
	v_addc_co_u32_e32 v41, vcc, 0, v3, vcc
	v_add_co_u32_e32 v42, vcc, s4, v2
	s_mov_b32 s4, 0x4d000
	s_nop 0
	v_addc_co_u32_e32 v43, vcc, 0, v3, vcc
	v_add_co_u32_e32 v44, vcc, s4, v2
	s_mov_b32 s4, 0x52000
	s_nop 0
	v_addc_co_u32_e32 v45, vcc, 0, v3, vcc
	v_add_co_u32_e32 v46, vcc, s4, v2
	s_mov_b32 s4, 0x58000
	s_nop 0
	v_addc_co_u32_e32 v47, vcc, 0, v3, vcc
; template <bool HASG>
; __device__ __forceinline__ void tr_item(const float* W, int K, int N, bf16* WT, int rowmode, const float* g, LAS float* scr, int item, int lane) {
;     ...
;     const float* wp = W + (size_t)(k0 + (lane >> 5)) * N + n0 + (lane & 31);
;     const int c = lane & 7;
;     float v[32];
; #pragma unroll
;     for (int i = 0; i < 32; ++i) v[i] = wp[(size_t)(2 * i) * N];
;     f32x4 g0 = (f32x4){1.f, 1.f, 1.f, 1.f}, g1 = g0;
;     if (HASG) { g0 = *(const f32x4*)(g + k0 + 8 * c); g1 = *(const f32x4*)(g + k0 + 8 * c + 4); }
;     asm volatile("" ::: "memory");
; #pragma unroll
;     for (int i = 0; i < 32; ++i) scr[(2 * i + (lane >> 5)) * 33 + (lane & 31)] = v[i];
	global_load_dword v55, v[4:5], off
	global_load_dword v56, v[24:25], off offset:2048
	global_load_dword v57, v[36:37], off
	global_load_dword v58, v[38:39], off offset:2048
	global_load_dword v59, v[40:41], off
	global_load_dword v60, v[42:43], off offset:2048
	global_load_dword v61, v[44:45], off
	global_load_dword v62, v[46:47], off offset:2048
	v_add_co_u32_e32 v4, vcc, s4, v2
	s_mov_b32 s4, 0x5d000
	s_nop 0
	v_addc_co_u32_e32 v5, vcc, 0, v3, vcc
	v_add_co_u32_e32 v24, vcc, s4, v2
	s_mov_b32 s4, 0x63000
	s_nop 0
	v_addc_co_u32_e32 v25, vcc, 0, v3, vcc
	v_add_co_u32_e32 v36, vcc, s4, v2
	s_mov_b32 s4, 0x68000
	s_nop 0
	v_addc_co_u32_e32 v37, vcc, 0, v3, vcc
	v_add_co_u32_e32 v38, vcc, s4, v2
	s_mov_b32 s4, 0x6e000
	s_nop 0
	v_addc_co_u32_e32 v39, vcc, 0, v3, vcc
	v_add_co_u32_e32 v40, vcc, s4, v2
	s_mov_b32 s4, 0x73000
	s_nop 0
	v_addc_co_u32_e32 v41, vcc, 0, v3, vcc
	v_add_co_u32_e32 v42, vcc, s4, v2
	s_mov_b32 s4, 0x79000
	s_nop 0
	v_addc_co_u32_e32 v43, vcc, 0, v3, vcc
	v_add_co_u32_e32 v44, vcc, s4, v2
	s_mov_b32 s4, 0x7e000
	s_nop 0
	v_addc_co_u32_e32 v45, vcc, 0, v3, vcc
	v_add_co_u32_e32 v46, vcc, s4, v2
	s_mov_b32 s4, 0x84000
	s_nop 0
	v_addc_co_u32_e32 v47, vcc, 0, v3, vcc
	global_load_dword v63, v[4:5], off
	global_load_dword v64, v[24:25], off offset:2048
	global_load_dword v65, v[36:37], off
	global_load_dword v66, v[38:39], off offset:2048
	global_load_dword v67, v[40:41], off
	global_load_dword v68, v[42:43], off offset:2048
	global_load_dword v69, v[44:45], off
	s_nop 0
	global_load_dword v46, v[46:47], off offset:2048
	v_add_co_u32_e32 v4, vcc, s4, v2
	s_mov_b32 s4, 0x89000
	s_nop 0
	v_addc_co_u32_e32 v5, vcc, 0, v3, vcc
	v_add_co_u32_e32 v24, vcc, s4, v2
	s_mov_b32 s4, 0x8f000
	s_nop 0
	v_addc_co_u32_e32 v25, vcc, 0, v3, vcc
	v_add_co_u32_e32 v36, vcc, s4, v2
	s_mov_b32 s4, 0x94000
	s_nop 0
	v_addc_co_u32_e32 v37, vcc, 0, v3, vcc
	v_add_co_u32_e32 v38, vcc, s4, v2
	s_mov_b32 s4, 0x9a000
	s_nop 0
	v_addc_co_u32_e32 v39, vcc, 0, v3, vcc
	v_add_co_u32_e32 v40, vcc, s4, v2
	s_mov_b32 s4, 0x9f000
	s_nop 0
	v_addc_co_u32_e32 v41, vcc, 0, v3, vcc
	v_add_co_u32_e32 v42, vcc, s4, v2
	s_mov_b32 s4, 0xa5000
	s_nop 0
	v_addc_co_u32_e32 v43, vcc, 0, v3, vcc
	v_add_co_u32_e32 v44, vcc, s4, v2
	s_mov_b32 s4, 0xaa000
	s_nop 0
	v_addc_co_u32_e32 v45, vcc, 0, v3, vcc
	v_add_co_u32_e32 v2, vcc, s4, v2
	s_and_b32 s0, s0, 0x1f00
	s_nop 0
	v_addc_co_u32_e32 v3, vcc, 0, v3, vcc
	global_load_dword v47, v[4:5], off
	s_nop 0
	global_load_dword v24, v[24:25], off offset:2048
	s_nop 0
	global_load_dword v25, v[36:37], off
	global_load_dword v70, v[38:39], off offset:2048
	s_nop 0
	global_load_dword v40, v[40:41], off
	s_nop 0
	global_load_dword v41, v[42:43], off offset:2048
	s_nop 0
	global_load_dword v42, v[44:45], off
	global_load_dword v43, v[2:3], off offset:2048
	v_lshl_add_u64 v[2:3], v[18:19], 0, s[88:89]
	global_load_dwordx4 v[36:39], v[2:3], off
	s_nop 0
	global_load_dwordx4 v[2:5], v[2:3], off offset:16
	s_waitcnt vmcnt(32)
	ds_write2_b32 v30, v0, v48 offset1:66
	s_waitcnt vmcnt(30)
	ds_write2_b32 v30, v49, v50 offset0:132 offset1:198
	v_add_u32_e32 v0, 0x400, v30
	s_waitcnt vmcnt(28)
	ds_write2_b32 v0, v51, v52 offset0:8 offset1:74
	s_waitcnt vmcnt(26)
	ds_write2_b32 v0, v53, v54 offset0:140 offset1:206
	v_add_u32_e32 v0, 0x800, v30
	s_waitcnt vmcnt(24)
	ds_write2_b32 v0, v55, v56 offset0:16 offset1:82
	s_waitcnt vmcnt(22)
	ds_write2_b32 v0, v57, v58 offset0:148 offset1:214
	v_add_u32_e32 v0, 0xc00, v30
	s_waitcnt vmcnt(20)
	ds_write2_b32 v0, v59, v60 offset0:24 offset1:90
	s_waitcnt vmcnt(18)
	ds_write2_b32 v0, v61, v62 offset0:156 offset1:222
	v_add_u32_e32 v0, 0x1000, v30
	s_waitcnt vmcnt(16)
	ds_write2_b32 v0, v63, v64 offset0:32 offset1:98
	s_waitcnt vmcnt(14)
	ds_write2_b32 v0, v65, v66 offset0:164 offset1:230
	v_add_u32_e32 v0, 0x1400, v30
	s_waitcnt vmcnt(12)
	ds_write2_b32 v0, v67, v68 offset0:40 offset1:106
	s_waitcnt vmcnt(10)
	ds_write2_b32 v0, v69, v46 offset0:172 offset1:238
	v_add_u32_e32 v0, 0x1800, v30
	s_waitcnt vmcnt(8)
	ds_write2_b32 v0, v47, v24 offset0:48 offset1:114
	s_waitcnt vmcnt(6)
	ds_write2_b32 v0, v25, v70 offset0:180 offset1:246
	v_add_u32_e32 v0, 0x1c00, v30
	s_waitcnt vmcnt(4)
	ds_write2_b32 v0, v40, v41 offset0:56 offset1:122
	s_waitcnt vmcnt(2)
	ds_write2_b32 v0, v42, v43 offset0:188 offset1:254
	s_waitcnt lgkmcnt(0)
	ds_read2_b32 v[44:45], v31 offset0:33 offset1:41
	ds_read2_b32 v[46:47], v31 offset1:8
	ds_read2_b32 v[48:49], v31 offset0:66 offset1:74
	ds_read2_b32 v[50:51], v31 offset0:99 offset1:107
	ds_read2_b32 v[54:55], v31 offset0:132 offset1:140
	ds_read2_b32 v[56:57], v31 offset0:165 offset1:173
	ds_read2_b32 v[58:59], v31 offset0:198 offset1:206
	ds_read2_b32 v[60:61], v31 offset0:231 offset1:239
	s_waitcnt vmcnt(1)
	v_mov_b32_e32 v52, v36
	v_mov_b32_e32 v53, v38
	v_mov_b32_e32 v38, v37
	s_waitcnt lgkmcnt(7)
	v_mov_b32_e32 v36, v44
	s_waitcnt lgkmcnt(4)
	v_mov_b32_e32 v37, v50
	s_waitcnt vmcnt(0)
	v_mov_b32_e32 v62, v2
	v_mov_b32_e32 v63, v4
	v_mov_b32_e32 v4, v3
	s_waitcnt lgkmcnt(2)
	v_mov_b32_e32 v2, v56
	s_waitcnt lgkmcnt(0)
; #define LAS __attribute__((address_space(3)))
; __device__ __forceinline__ unsigned pk2(float lo, float hi) { return f2bf(lo) | (f2bf(hi) << 16); }
; #define LDS_WAVE_SYNC() asm volatile("s_waitcnt lgkmcnt(0)" ::: "memory")
; template <bool HASG>
; __device__ __forceinline__ void tr_item(const float* W, int K, int N, bf16* WT, int rowmode, const float* g, LAS float* scr, int item, int lane) {
;     ...
;     for (int i = 0; i < 32; ++i) scr[(2 * i + (lane >> 5)) * 33 + (lane & 31)] = v[i];
;     LDS_WAVE_SYNC();
;     const int drow0 = rowmode == 0 ? n0 : ((n0 >> 7) * 256 + (n0 & 127) + (rowmode == 2 ? 128 : 0));
; #pragma unroll
;     for (int j = 0; j < 4; ++j) { const int n = (lane >> 3) + 8 * j; const LAS float* s = scr + (8 * c) * 33 + n;
;         u32x4 o; o.x = pk2(s[0 * 33] * g0.x, s[1 * 33] * g0.y); o.y = pk2(s[2 * 33] * g0.z, s[3 * 33] * g0.w);
;         o.z = pk2(s[4 * 33] * g1.x, s[5 * 33] * g1.y); o.w = pk2(s[6 * 33] * g1.z, s[7 * 33] * g1.w);
;         *(u32x4*)(WT + (size_t)(drow0 + n) * K + k0 + 8 * c) = o; }
;     LDS_WAVE_SYNC();
	v_mov_b32_e32 v3, v60
	v_mov_b32_e32 v40, v46
	v_mov_b32_e32 v41, v48
	v_pk_mul_f32 v[36:37], v[38:39], v[36:37]
	v_mov_b32_e32 v42, v54
	v_mov_b32_e32 v43, v58
	v_pk_mul_f32 v[2:3], v[4:5], v[2:3]
	v_pk_mul_f32 v[40:41], v[52:53], v[40:41]
	v_pk_mul_f32 v[42:43], v[62:63], v[42:43]
	v_bfe_u32 v44, v2, 16, 1
	v_bfe_u32 v46, v37, 16, 1
	v_bfe_u32 v48, v36, 16, 1
	v_bfe_u32 v0, v3, 16, 1
	v_add3_u32 v36, v36, v48, s91
	v_add3_u32 v37, v37, v46, s91
	v_add3_u32 v2, v2, v44, s91
	v_bfe_u32 v44, v41, 16, 1
	v_bfe_u32 v46, v42, 16, 1
	v_bfe_u32 v48, v43, 16, 1
	s_and_b32 s38, s38, 0x60
	v_add3_u32 v0, v3, v0, s91
	v_bfe_u32 v3, v40, 16, 1
	v_add3_u32 v43, v43, v48, s91
	v_add3_u32 v42, v42, v46, s91
	v_add3_u32 v41, v41, v44, s91
	s_or_b32 s0, s38, s0
	v_add3_u32 v3, v40, v3, s91
	v_lshrrev_b32_e32 v40, 16, v41
	v_lshrrev_b32_e32 v41, 16, v42
	v_lshrrev_b32_e32 v42, 16, v43
	s_lshl_b32 s88, s1, 1
	v_and_or_b32 v43, v0, s35, v42
	v_or_b32_e32 v0, s0, v7
	v_lshl_add_u64 v[24:25], v[8:9], 0, s[88:89]
	v_lshrrev_b32_e32 v3, 16, v3
	v_lshlrev_b32_e32 v0, 11, v0
	v_mov_b32_e32 v50, v45
	v_and_or_b32 v42, v2, s35, v41
	v_and_or_b32 v41, v37, s35, v40
	v_and_or_b32 v40, v36, s35, v3
	v_lshl_add_u64 v[2:3], v[24:25], 0, v[0:1]
	v_pk_mul_f32 v[36:37], v[38:39], v[50:51]
	v_mov_b32_e32 v58, v55
	global_store_dwordx4 v[2:3], v[40:43], off sc1
	v_mov_b32_e32 v60, v57
	v_bfe_u32 v46, v36, 16, 1
	v_pk_mul_f32 v[40:41], v[62:63], v[58:59]
	v_mov_b32_e32 v48, v47
	v_pk_mul_f32 v[42:43], v[4:5], v[60:61]
	v_add3_u32 v36, v36, v46, s91
	v_bfe_u32 v46, v41, 16, 1
	v_pk_mul_f32 v[2:3], v[52:53], v[48:49]
	v_bfe_u32 v0, v43, 16, 1
	v_bfe_u32 v44, v42, 16, 1
	v_bfe_u32 v45, v37, 16, 1
	v_add3_u32 v41, v41, v46, s91
	v_add3_u32 v37, v37, v45, s91
	v_add3_u32 v42, v42, v44, s91
	v_add3_u32 v0, v43, v0, s91
	v_bfe_u32 v43, v2, 16, 1
	v_bfe_u32 v44, v3, 16, 1
	v_bfe_u32 v45, v40, 16, 1
	v_lshrrev_b32_e32 v41, 16, v41
	v_add3_u32 v40, v40, v45, s91
	v_add3_u32 v3, v3, v44, s91
	v_add3_u32 v2, v2, v43, s91
	v_and_or_b32 v43, v0, s35, v41
	v_or_b32_e32 v0, s0, v32
	v_lshrrev_b32_e32 v2, 16, v2
	v_lshrrev_b32_e32 v3, 16, v3
	v_lshrrev_b32_e32 v40, 16, v40
	v_lshlrev_b32_e32 v0, 11, v0
	v_and_or_b32 v42, v42, s35, v40
	v_and_or_b32 v41, v37, s35, v3
	v_and_or_b32 v40, v36, s35, v2
	v_lshl_add_u64 v[2:3], v[24:25], 0, v[0:1]
	ds_read2_b32 v[36:37], v31 offset0:16 offset1:24
	ds_read2_b32 v[44:45], v31 offset0:82 offset1:90
	global_store_dwordx4 v[2:3], v[40:43], off sc1
	ds_read2_b32 v[2:3], v31 offset0:49 offset1:57
	ds_read2_b32 v[46:47], v31 offset0:115 offset1:123
	ds_read2_b32 v[48:49], v31 offset0:148 offset1:156
	ds_read2_b32 v[50:51], v31 offset0:214 offset1:222
	ds_read2_b32 v[54:55], v31 offset0:181 offset1:189
	ds_read2_b32 v[56:57], v31 offset0:247 offset1:255
	s_waitcnt lgkmcnt(7)
	v_mov_b32_e32 v40, v36
	s_waitcnt lgkmcnt(5)
	v_mov_b32_e32 v42, v2
	s_waitcnt lgkmcnt(4)
	v_mov_b32_e32 v43, v46
	s_waitcnt lgkmcnt(3)
	v_mov_b32_e32 v58, v48
	s_waitcnt lgkmcnt(2)
	v_mov_b32_e32 v59, v50
	v_mov_b32_e32 v41, v44
	v_pk_mul_f32 v[42:43], v[38:39], v[42:43]
	v_pk_mul_f32 v[58:59], v[62:63], v[58:59]
	s_waitcnt lgkmcnt(1)
	v_mov_b32_e32 v60, v54
	s_waitcnt lgkmcnt(0)
	v_mov_b32_e32 v61, v56
	v_pk_mul_f32 v[40:41], v[52:53], v[40:41]
	v_pk_mul_f32 v[60:61], v[4:5], v[60:61]
	v_bfe_u32 v36, v43, 16, 1
	v_bfe_u32 v48, v59, 16, 1
	v_bfe_u32 v0, v61, 16, 1
	v_bfe_u32 v44, v42, 16, 1
	v_add3_u32 v36, v43, v36, s91
	v_bfe_u32 v43, v41, 16, 1
	v_add3_u32 v48, v59, v48, s91
	v_add3_u32 v44, v42, v44, s91
	v_add3_u32 v0, v61, v0, s91
	v_bfe_u32 v42, v40, 16, 1
	v_bfe_u32 v46, v58, 16, 1
	v_add3_u32 v41, v41, v43, s91
	v_lshrrev_b32_e32 v43, 16, v48
	v_bfe_u32 v2, v60, 16, 1
	v_add3_u32 v46, v58, v46, s91
	v_add3_u32 v40, v40, v42, s91
	v_and_or_b32 v43, v0, s35, v43
	v_or_b32_e32 v0, s0, v34
	v_add3_u32 v2, v60, v2, s91
	v_lshrrev_b32_e32 v40, 16, v40
	v_lshrrev_b32_e32 v41, 16, v41
	v_lshrrev_b32_e32 v42, 16, v46
	v_lshlrev_b32_e32 v0, 11, v0
	v_mov_b32_e32 v46, v3
	v_mov_b32_e32 v56, v55
	v_and_or_b32 v42, v2, s35, v42
	v_and_or_b32 v41, v36, s35, v41
	v_and_or_b32 v40, v44, s35, v40
	v_lshl_add_u64 v[58:59], v[24:25], 0, v[0:1]
	v_mov_b32_e32 v44, v37
	v_pk_mul_f32 v[2:3], v[38:39], v[46:47]
	v_mov_b32_e32 v50, v49
	v_pk_mul_f32 v[4:5], v[4:5], v[56:57]
	global_store_dwordx4 v[58:59], v[40:43], off sc1
	v_pk_mul_f32 v[36:37], v[52:53], v[44:45]
	v_pk_mul_f32 v[38:39], v[62:63], v[50:51]
	v_bfe_u32 v0, v5, 16, 1
	v_bfe_u32 v42, v2, 16, 1
	v_add3_u32 v2, v2, v42, s91
	v_add3_u32 v0, v5, v0, s91
	v_bfe_u32 v5, v36, 16, 1
	v_bfe_u32 v42, v39, 16, 1
	v_bfe_u32 v40, v4, 16, 1
	v_bfe_u32 v41, v3, 16, 1
	v_add3_u32 v39, v39, v42, s91
	v_add3_u32 v5, v36, v5, s91
	v_add3_u32 v3, v3, v41, s91
	v_add3_u32 v4, v4, v40, s91
	v_bfe_u32 v40, v37, 16, 1
	v_bfe_u32 v41, v38, 16, 1
	v_lshrrev_b32_e32 v36, 16, v5
	v_lshrrev_b32_e32 v5, 16, v39
	v_add3_u32 v38, v38, v41, s91
	v_add3_u32 v37, v37, v40, s91
	v_and_or_b32 v5, v0, s35, v5
	v_or_b32_e32 v0, s0, v35
	v_lshrrev_b32_e32 v37, 16, v37
	v_lshrrev_b32_e32 v38, 16, v38
	v_lshlrev_b32_e32 v0, 11, v0
	v_and_or_b32 v4, v4, s35, v38
	v_and_or_b32 v3, v3, s35, v37
	v_and_or_b32 v2, v2, s35, v36
	v_lshl_add_u64 v[24:25], v[24:25], 0, v[0:1]
	global_store_dwordx4 v[24:25], v[2:5], off sc1
	s_waitcnt lgkmcnt(0)
	v_readlane_b32 s8, v252, 4
	v_readlane_b32 s9, v252, 5
	s_mov_b64 s[8:9], s[26:27]
	v_readlane_b32 s5, v252, 1
	v_readlane_b32 s6, v252, 2
	v_readlane_b32 s7, v252, 3
	v_readlane_b32 s10, v252, 6
	v_readlane_b32 s11, v252, 7
	v_readlane_b32 s12, v252, 8
	v_readlane_b32 s13, v252, 9
	v_readlane_b32 s14, v252, 10
	v_readlane_b32 s15, v252, 11
	v_readlane_b32 s16, v252, 12
	v_readlane_b32 s17, v252, 13
	v_readlane_b32 s18, v252, 14
	v_readlane_b32 s19, v252, 15

; template <bool HASG>
; __device__ __forceinline__ void tr_item(const float* W, int K, int N, bf16* WT, int rowmode, const float* g, LAS float* scr, int item, int lane) {
;     const int nblk = N / 32, kb = item / nblk, nb = item % nblk, k0 = 64 * kb, n0 = 32 * nb;
;     const float* wp = W + (size_t)(k0 + (lane >> 5)) * N + n0 + (lane & 31);
;     const int c = lane & 7;
;     float v[32];
; #pragma unroll
;     for (int i = 0; i < 32; ++i) v[i] = wp[(size_t)(2 * i) * N];
;     f32x4 g0 = (f32x4){1.f, 1.f, 1.f, 1.f}, g1 = g0;
;     if (HASG) { g0 = *(const f32x4*)(g + k0 + 8 * c); g1 = *(const f32x4*)(g + k0 + 8 * c + 4); }
;     asm volatile("" ::: "memory");
; #pragma unroll
;     for (int i = 0; i < 32; ++i) scr[(2 * i + (lane >> 5)) * 33 + (lane & 31)] = v[i];
; __device__ __forceinline__ void convert_items(const Args& a, LAS unsigned char* lds, int l, int it_lo, int it_hi, int gw, int NGW, int wave, int lane) {
;     ...
;         if (r < I_OUT) { tr_item<false>(a.in[18] + (size_t)l * D * D, D, D, wl + W_OUT, 0, nullptr, scr, r, lane); continue; } r -= I_OUT;
.LBB0_555:
	s_andn2_b64 vcc, exec, s[0:1]
	s_cbranch_vccnz .LBB0_557
	s_and_b32 s1, s43, 0x1ffc0
	s_lshl_b32 s0, s46, 5
	v_or_b32_e32 v0, s1, v33
	v_readlane_b32 s4, v252, 32
	s_and_b32 s0, s0, 0x3e0
	v_lshlrev_b32_e32 v0, 12, v0
	v_readlane_b32 s8, v252, 36
	v_readlane_b32 s9, v252, 37
	s_lshl_b32 s88, s0, 2
	v_readlane_b32 s5, v252, 33
	v_lshl_add_u64 v[2:3], s[8:9], 0, v[0:1]
	v_lshl_add_u64 v[2:3], v[2:3], 0, s[88:89]
	v_lshlrev_b32_e32 v0, 2, v6
	v_lshl_add_u64 v[2:3], v[2:3], 0, v[0:1]
	v_add_co_u32_e32 v4, vcc, 0x2000, v2
	global_load_dword v0, v[2:3], off
	s_nop 0
	v_addc_co_u32_e32 v5, vcc, 0, v3, vcc
	global_load_dword v24, v[4:5], off
	v_add_co_u32_e32 v4, vcc, 0x4000, v2
	v_readlane_b32 s6, v252, 34
	s_nop 0
	v_addc_co_u32_e32 v5, vcc, 0, v3, vcc
	global_load_dword v25, v[4:5], off
	v_add_co_u32_e32 v4, vcc, 0x6000, v2
	v_readlane_b32 s7, v252, 35
	s_nop 0
	v_addc_co_u32_e32 v5, vcc, 0, v3, vcc
	global_load_dword v36, v[4:5], off
	v_add_co_u32_e32 v4, vcc, 0x8000, v2
	v_readlane_b32 s10, v252, 38
	s_nop 0
	v_addc_co_u32_e32 v5, vcc, 0, v3, vcc
	global_load_dword v37, v[4:5], off
	v_add_co_u32_e32 v4, vcc, 0xa000, v2
	v_readlane_b32 s11, v252, 39
	s_nop 0
	v_addc_co_u32_e32 v5, vcc, 0, v3, vcc
	global_load_dword v38, v[4:5], off
	v_add_co_u32_e32 v4, vcc, 0xc000, v2
	v_readlane_b32 s12, v252, 40
	s_nop 0
	v_addc_co_u32_e32 v5, vcc, 0, v3, vcc
	global_load_dword v39, v[4:5], off
	v_add_co_u32_e32 v4, vcc, 0xe000, v2
	v_readlane_b32 s13, v252, 41
	v_readlane_b32 s14, v252, 42
	v_readlane_b32 s15, v252, 43
	v_readlane_b32 s16, v252, 44
	v_readlane_b32 s17, v252, 45
	v_readlane_b32 s18, v252, 46
	v_readlane_b32 s19, v252, 47
	v_addc_co_u32_e32 v5, vcc, 0, v3, vcc
	v_readlane_b32 s4, v252, 0
	global_load_dword v40, v[4:5], off
	v_add_co_u32_e32 v4, vcc, s70, v2
	s_mov_b32 s4, 0x12000
	s_nop 0
	v_addc_co_u32_e32 v5, vcc, 0, v3, vcc
	global_load_dword v41, v[4:5], off
	v_add_co_u32_e32 v4, vcc, s4, v2
	s_mov_b32 s4, 0x14000
	s_nop 0
	v_addc_co_u32_e32 v5, vcc, 0, v3, vcc
	global_load_dword v42, v[4:5], off
	v_add_co_u32_e32 v4, vcc, s4, v2
	s_mov_b32 s4, 0x18000
	s_nop 0
	v_addc_co_u32_e32 v5, vcc, 0, v3, vcc
	global_load_dword v43, v[4:5], off
	v_add_co_u32_e32 v4, vcc, s71, v2
	s_lshl_b32 s88, s1, 1
	s_nop 0
	v_addc_co_u32_e32 v5, vcc, 0, v3, vcc
	global_load_dword v44, v[4:5], off
	v_add_co_u32_e32 v4, vcc, s4, v2
	s_mov_b32 s4, 0x1a000
	s_nop 0
	v_addc_co_u32_e32 v5, vcc, 0, v3, vcc
	global_load_dword v45, v[4:5], off
	v_add_co_u32_e32 v4, vcc, s4, v2
	s_mov_b32 s4, 0x1c000
	s_nop 0
	v_addc_co_u32_e32 v5, vcc, 0, v3, vcc
	global_load_dword v46, v[4:5], off
	v_add_co_u32_e32 v4, vcc, s4, v2
	s_mov_b32 s4, 0x1e000
	s_nop 0
	v_addc_co_u32_e32 v5, vcc, 0, v3, vcc
	global_load_dword v47, v[4:5], off
	v_add_co_u32_e32 v4, vcc, s4, v2
	s_mov_b32 s4, 0x20000
	s_nop 0
	v_addc_co_u32_e32 v5, vcc, 0, v3, vcc
	global_load_dword v48, v[4:5], off
	v_add_co_u32_e32 v4, vcc, s4, v2
	s_mov_b32 s4, 0x22000
	s_nop 0
	v_addc_co_u32_e32 v5, vcc, 0, v3, vcc
	global_load_dword v49, v[4:5], off
	v_add_co_u32_e32 v4, vcc, s4, v2
	s_mov_b32 s4, 0x24000
	s_nop 0
	v_addc_co_u32_e32 v5, vcc, 0, v3, vcc
	global_load_dword v50, v[4:5], off
	v_add_co_u32_e32 v4, vcc, s4, v2
	s_mov_b32 s4, 0x26000
	s_nop 0
	v_addc_co_u32_e32 v5, vcc, 0, v3, vcc
	global_load_dword v51, v[4:5], off
	v_add_co_u32_e32 v4, vcc, s4, v2
	s_mov_b32 s4, 0x28000
	s_nop 0
	v_addc_co_u32_e32 v5, vcc, 0, v3, vcc
	global_load_dword v52, v[4:5], off
	v_add_co_u32_e32 v4, vcc, s4, v2
	s_mov_b32 s4, 0x2a000
	s_nop 0
	v_addc_co_u32_e32 v5, vcc, 0, v3, vcc
	global_load_dword v53, v[4:5], off
	v_add_co_u32_e32 v4, vcc, s4, v2
	s_mov_b32 s4, 0x2c000
	s_nop 0
	v_addc_co_u32_e32 v5, vcc, 0, v3, vcc
	global_load_dword v54, v[4:5], off
	v_add_co_u32_e32 v4, vcc, s4, v2
	s_mov_b32 s4, 0x2e000
	s_nop 0
	v_addc_co_u32_e32 v5, vcc, 0, v3, vcc
	global_load_dword v55, v[4:5], off
	v_add_co_u32_e32 v4, vcc, s4, v2
	s_mov_b32 s4, 0x30000
	s_nop 0
	v_addc_co_u32_e32 v5, vcc, 0, v3, vcc
	global_load_dword v56, v[4:5], off
	v_add_co_u32_e32 v4, vcc, s4, v2
	s_mov_b32 s4, 0x32000
	s_nop 0
	v_addc_co_u32_e32 v5, vcc, 0, v3, vcc
	global_load_dword v57, v[4:5], off
	v_add_co_u32_e32 v4, vcc, s4, v2
	s_mov_b32 s4, 0x34000
	s_nop 0
	v_addc_co_u32_e32 v5, vcc, 0, v3, vcc
	global_load_dword v58, v[4:5], off
	v_add_co_u32_e32 v4, vcc, s4, v2
	s_mov_b32 s4, 0x36000
	s_nop 0
	v_addc_co_u32_e32 v5, vcc, 0, v3, vcc
	global_load_dword v59, v[4:5], off
	v_add_co_u32_e32 v4, vcc, s4, v2
	s_mov_b32 s4, 0x38000
	s_nop 0
	v_addc_co_u32_e32 v5, vcc, 0, v3, vcc
	global_load_dword v60, v[4:5], off
	v_add_co_u32_e32 v4, vcc, s4, v2
	s_mov_b32 s4, 0x3a000
	s_nop 0
	v_addc_co_u32_e32 v5, vcc, 0, v3, vcc
	global_load_dword v61, v[4:5], off
	v_add_co_u32_e32 v4, vcc, s4, v2
	s_mov_b32 s4, 0x3c000
	s_nop 0
	v_addc_co_u32_e32 v5, vcc, 0, v3, vcc
	global_load_dword v62, v[4:5], off
	v_add_co_u32_e32 v4, vcc, s4, v2
	s_mov_b32 s4, 0x3e000
	s_nop 0
	v_addc_co_u32_e32 v5, vcc, 0, v3, vcc
	v_add_co_u32_e32 v2, vcc, s4, v2
	global_load_dword v4, v[4:5], off
	s_nop 0
	v_addc_co_u32_e32 v3, vcc, 0, v3, vcc
	global_load_dword v2, v[2:3], off
	s_waitcnt vmcnt(30)
	ds_write2_b32 v30, v0, v24 offset1:66
	s_waitcnt vmcnt(28)
	ds_write2_b32 v30, v25, v36 offset0:132 offset1:198
	v_add_u32_e32 v0, 0x400, v30
	s_waitcnt vmcnt(26)
	ds_write2_b32 v0, v37, v38 offset0:8 offset1:74
	s_waitcnt vmcnt(24)
	ds_write2_b32 v0, v39, v40 offset0:140 offset1:206
	v_add_u32_e32 v0, 0x800, v30
	s_waitcnt vmcnt(22)
	ds_write2_b32 v0, v41, v42 offset0:16 offset1:82
	s_waitcnt vmcnt(20)
	ds_write2_b32 v0, v43, v44 offset0:148 offset1:214
	v_add_u32_e32 v0, 0xc00, v30
	s_waitcnt vmcnt(18)
; #define LAS __attribute__((address_space(3)))
; __device__ __forceinline__ unsigned pk2(float lo, float hi) { return f2bf(lo) | (f2bf(hi) << 16); }
; #define LDS_WAVE_SYNC() asm volatile("s_waitcnt lgkmcnt(0)" ::: "memory")
; template <bool HASG>
; __device__ __forceinline__ void tr_item(const float* W, int K, int N, bf16* WT, int rowmode, const float* g, LAS float* scr, int item, int lane) {
;     ...
;     for (int i = 0; i < 32; ++i) scr[(2 * i + (lane >> 5)) * 33 + (lane & 31)] = v[i];
;     LDS_WAVE_SYNC();
;     const int drow0 = rowmode == 0 ? n0 : ((n0 >> 7) * 256 + (n0 & 127) + (rowmode == 2 ? 128 : 0));
; #pragma unroll
;     for (int j = 0; j < 4; ++j) { const int n = (lane >> 3) + 8 * j; const LAS float* s = scr + (8 * c) * 33 + n;
;         u32x4 o; o.x = pk2(s[0 * 33] * g0.x, s[1 * 33] * g0.y); o.y = pk2(s[2 * 33] * g0.z, s[3 * 33] * g0.w);
;         o.z = pk2(s[4 * 33] * g1.x, s[5 * 33] * g1.y); o.w = pk2(s[6 * 33] * g1.z, s[7 * 33] * g1.w);
;         *(u32x4*)(WT + (size_t)(drow0 + n) * K + k0 + 8 * c) = o; }
;     LDS_WAVE_SYNC();
	ds_write2_b32 v0, v45, v46 offset0:24 offset1:90
	s_waitcnt vmcnt(16)
	ds_write2_b32 v0, v47, v48 offset0:156 offset1:222
	v_add_u32_e32 v0, 0x1000, v30
	s_waitcnt vmcnt(14)
	ds_write2_b32 v0, v49, v50 offset0:32 offset1:98
	s_waitcnt vmcnt(12)
	ds_write2_b32 v0, v51, v52 offset0:164 offset1:230
	v_add_u32_e32 v0, 0x1400, v30
	s_waitcnt vmcnt(10)
	ds_write2_b32 v0, v53, v54 offset0:40 offset1:106
	s_waitcnt vmcnt(8)
	ds_write2_b32 v0, v55, v56 offset0:172 offset1:238
	v_add_u32_e32 v0, 0x1800, v30
	s_waitcnt vmcnt(6)
	ds_write2_b32 v0, v57, v58 offset0:48 offset1:114
	s_waitcnt vmcnt(4)
	ds_write2_b32 v0, v59, v60 offset0:180 offset1:246
	v_add_u32_e32 v0, 0x1c00, v30
	s_waitcnt vmcnt(2)
	ds_write2_b32 v0, v61, v62 offset0:56 offset1:122
	s_waitcnt vmcnt(0)
	ds_write2_b32 v0, v4, v2 offset0:188 offset1:254
	s_waitcnt lgkmcnt(0)
	ds_read2_b32 v[4:5], v31 offset0:33 offset1:41
	ds_read2_b32 v[24:25], v31 offset1:8
	ds_read2_b32 v[40:41], v31 offset0:66 offset1:74
	ds_read2_b32 v[42:43], v31 offset0:99 offset1:107
	ds_read2_b32 v[44:45], v31 offset0:132 offset1:140
	ds_read2_b32 v[46:47], v31 offset0:165 offset1:173
	ds_read2_b32 v[48:49], v31 offset0:198 offset1:206
	ds_read2_b32 v[50:51], v31 offset0:231 offset1:239
	v_lshl_add_u64 v[2:3], v[10:11], 0, s[88:89]
	s_waitcnt lgkmcnt(6)
	v_bfe_u32 v0, v24, 16, 1
	v_add3_u32 v0, v24, v0, s91
	v_bfe_u32 v24, v4, 16, 1
	v_lshrrev_b32_e32 v0, 16, v0
	v_add3_u32 v4, v4, v24, s91
	v_and_or_b32 v36, v4, s35, v0
	s_waitcnt lgkmcnt(5)
	v_bfe_u32 v0, v40, 16, 1
	v_add3_u32 v0, v40, v0, s91
	s_waitcnt lgkmcnt(4)
	v_bfe_u32 v4, v42, 16, 1
	v_lshrrev_b32_e32 v0, 16, v0
	v_add3_u32 v4, v42, v4, s91
	v_and_or_b32 v37, v4, s35, v0
	s_waitcnt lgkmcnt(3)
	v_bfe_u32 v0, v44, 16, 1
	v_add3_u32 v0, v44, v0, s91
	s_waitcnt lgkmcnt(2)
	v_bfe_u32 v4, v46, 16, 1
	v_lshrrev_b32_e32 v0, 16, v0
	v_add3_u32 v4, v46, v4, s91
	v_and_or_b32 v38, v4, s35, v0
	s_waitcnt lgkmcnt(1)
	v_bfe_u32 v0, v48, 16, 1
	v_add3_u32 v0, v48, v0, s91
	s_waitcnt lgkmcnt(0)
	v_bfe_u32 v4, v50, 16, 1
	v_lshrrev_b32_e32 v0, 16, v0
	v_add3_u32 v4, v50, v4, s91
	v_and_or_b32 v39, v4, s35, v0
	v_or_b32_e32 v0, s0, v7
	v_lshlrev_b32_e32 v0, 11, v0
	v_lshl_add_u64 v[52:53], v[2:3], 0, v[0:1]
	v_bfe_u32 v0, v25, 16, 1
	v_add3_u32 v0, v25, v0, s91
	v_bfe_u32 v4, v5, 16, 1
	v_lshrrev_b32_e32 v0, 16, v0
	v_add3_u32 v4, v5, v4, s91
	global_store_dwordx4 v[52:53], v[36:39], off sc1
	v_readlane_b32 s8, v252, 4
	v_readlane_b32 s9, v252, 5
	v_and_or_b32 v36, v4, s35, v0
	v_bfe_u32 v0, v41, 16, 1
	v_add3_u32 v0, v41, v0, s91
	v_bfe_u32 v4, v43, 16, 1
	v_lshrrev_b32_e32 v0, 16, v0
	v_add3_u32 v4, v43, v4, s91
	v_and_or_b32 v37, v4, s35, v0
	v_bfe_u32 v0, v45, 16, 1
	v_add3_u32 v0, v45, v0, s91
	v_bfe_u32 v4, v47, 16, 1
	v_lshrrev_b32_e32 v0, 16, v0
	v_add3_u32 v4, v47, v4, s91
	v_and_or_b32 v38, v4, s35, v0
	v_bfe_u32 v0, v49, 16, 1
	v_add3_u32 v0, v49, v0, s91
	v_bfe_u32 v4, v51, 16, 1
	v_lshrrev_b32_e32 v0, 16, v0
	v_add3_u32 v4, v51, v4, s91
	v_and_or_b32 v39, v4, s35, v0
	v_or_b32_e32 v0, s0, v32
	v_lshlrev_b32_e32 v0, 11, v0
	v_lshl_add_u64 v[4:5], v[2:3], 0, v[0:1]
	global_store_dwordx4 v[4:5], v[36:39], off sc1
	ds_read2_b32 v[4:5], v31 offset0:49 offset1:57
	ds_read2_b32 v[24:25], v31 offset0:16 offset1:24
	ds_read2_b32 v[40:41], v31 offset0:82 offset1:90
	ds_read2_b32 v[42:43], v31 offset0:115 offset1:123
	ds_read2_b32 v[44:45], v31 offset0:148 offset1:156
	ds_read2_b32 v[46:47], v31 offset0:181 offset1:189
	ds_read2_b32 v[48:49], v31 offset0:214 offset1:222
	ds_read2_b32 v[50:51], v31 offset0:247 offset1:255
	s_mov_b64 s[8:9], s[26:27]
	s_waitcnt lgkmcnt(6)
	v_bfe_u32 v0, v24, 16, 1
	v_add3_u32 v0, v24, v0, s91
	v_bfe_u32 v24, v4, 16, 1
	v_lshrrev_b32_e32 v0, 16, v0
	v_add3_u32 v4, v4, v24, s91
	v_and_or_b32 v36, v4, s35, v0
	s_waitcnt lgkmcnt(5)
	v_bfe_u32 v0, v40, 16, 1
	v_add3_u32 v0, v40, v0, s91
	s_waitcnt lgkmcnt(4)
	v_bfe_u32 v4, v42, 16, 1
	v_lshrrev_b32_e32 v0, 16, v0
	v_add3_u32 v4, v42, v4, s91
	v_and_or_b32 v37, v4, s35, v0
	s_waitcnt lgkmcnt(3)
	v_bfe_u32 v0, v44, 16, 1
	v_add3_u32 v0, v44, v0, s91
	s_waitcnt lgkmcnt(2)
	v_bfe_u32 v4, v46, 16, 1
	v_lshrrev_b32_e32 v0, 16, v0
	v_add3_u32 v4, v46, v4, s91
	v_and_or_b32 v38, v4, s35, v0
	s_waitcnt lgkmcnt(1)
	v_bfe_u32 v0, v48, 16, 1
	v_add3_u32 v0, v48, v0, s91
	s_waitcnt lgkmcnt(0)
	v_bfe_u32 v4, v50, 16, 1
	v_lshrrev_b32_e32 v0, 16, v0
	v_add3_u32 v4, v50, v4, s91
	v_and_or_b32 v39, v4, s35, v0
	v_or_b32_e32 v0, s0, v34
	v_lshlrev_b32_e32 v0, 11, v0
	v_lshl_add_u64 v[52:53], v[2:3], 0, v[0:1]
	v_bfe_u32 v0, v25, 16, 1
	v_add3_u32 v0, v25, v0, s91
	v_bfe_u32 v4, v5, 16, 1
	v_lshrrev_b32_e32 v0, 16, v0
	v_add3_u32 v4, v5, v4, s91
	global_store_dwordx4 v[52:53], v[36:39], off sc1
	v_readlane_b32 s5, v252, 1
	v_readlane_b32 s6, v252, 2
	v_and_or_b32 v36, v4, s35, v0
	v_bfe_u32 v0, v41, 16, 1
	v_add3_u32 v0, v41, v0, s91
	v_bfe_u32 v4, v43, 16, 1
	v_lshrrev_b32_e32 v0, 16, v0
	v_add3_u32 v4, v43, v4, s91
	v_and_or_b32 v37, v4, s35, v0
	v_bfe_u32 v0, v45, 16, 1
	v_add3_u32 v0, v45, v0, s91
	v_bfe_u32 v4, v47, 16, 1
	v_lshrrev_b32_e32 v0, 16, v0
	v_add3_u32 v4, v47, v4, s91
	v_and_or_b32 v38, v4, s35, v0
	v_bfe_u32 v0, v49, 16, 1
	v_add3_u32 v0, v49, v0, s91
	v_bfe_u32 v4, v51, 16, 1
	v_lshrrev_b32_e32 v0, 16, v0
	v_add3_u32 v4, v51, v4, s91
	v_and_or_b32 v39, v4, s35, v0
	v_or_b32_e32 v0, s0, v35
	v_lshlrev_b32_e32 v0, 11, v0
	v_lshl_add_u64 v[2:3], v[2:3], 0, v[0:1]
	global_store_dwordx4 v[2:3], v[36:39], off sc1
	s_waitcnt lgkmcnt(0)
	v_readlane_b32 s7, v252, 3
	v_readlane_b32 s10, v252, 6
	v_readlane_b32 s11, v252, 7
	v_readlane_b32 s12, v252, 8
	v_readlane_b32 s13, v252, 9
	v_readlane_b32 s14, v252, 10
	v_readlane_b32 s15, v252, 11
	v_readlane_b32 s16, v252, 12
	v_readlane_b32 s17, v252, 13
	v_readlane_b32 s18, v252, 14
	v_readlane_b32 s19, v252, 15

; template <bool HASG>
; __device__ __forceinline__ void tr_item(const float* W, int K, int N, bf16* WT, int rowmode, const float* g, LAS float* scr, int item, int lane) {
;     const int nblk = N / 32, kb = item / nblk, nb = item % nblk, k0 = 64 * kb, n0 = 32 * nb;
;     const float* wp = W + (size_t)(k0 + (lane >> 5)) * N + n0 + (lane & 31);
;     const int c = lane & 7;
;     float v[32];
; #pragma unroll
;     for (int i = 0; i < 32; ++i) v[i] = wp[(size_t)(2 * i) * N];
;     f32x4 g0 = (f32x4){1.f, 1.f, 1.f, 1.f}, g1 = g0;
;     if (HASG) { g0 = *(const f32x4*)(g + k0 + 8 * c); g1 = *(const f32x4*)(g + k0 + 8 * c + 4); }
;     asm volatile("" ::: "memory");
; #pragma unroll
;     for (int i = 0; i < 32; ++i) scr[(2 * i + (lane >> 5)) * 33 + (lane & 31)] = v[i];
; __device__ __forceinline__ void convert_items(const Args& a, LAS unsigned char* lds, int l, int it_lo, int it_hi, int gw, int NGW, int wave, int lane) {
;     ...
;         if (r < I_IN) { tr_item<true>(a.in[6] + (size_t)l * D * DIN, D, DIN, wl + W_IN, 0, a.in[5] + l * D, scr, r, lane); continue; } r -= I_IN;
.LBB0_558:
	s_andn2_b64 vcc, exec, s[0:1]
	s_cbranch_vccnz .LBB0_560
	s_add_i32 s0, s46, 0xef80
	s_bfe_u32 s1, s0, 0xd0003
	s_mulk_i32 s1, 0x2493
	s_lshr_b32 s1, s1, 16
	s_mul_i32 s38, s1, 56
	s_sub_i32 s0, s0, s38
	s_lshl_b32 s0, s0, 5
	v_lshl_or_b32 v0, s1, 6, v33
	v_readlane_b32 s4, v252, 0
	s_and_b32 s0, s0, 0xffe0
	v_mul_u32_u24_e32 v0, 0x700, v0
	v_readlane_b32 s16, v252, 12
	v_readlane_b32 s17, v252, 13
	s_lshl_b32 s88, s0, 2
	s_movk_i32 s4, 0x3000
	v_lshl_add_u64 v[2:3], v[0:1], 2, s[16:17]
	v_lshl_add_u64 v[2:3], v[2:3], 0, s[88:89]
	v_lshlrev_b32_e32 v0, 2, v6
	v_lshl_add_u64 v[2:3], v[2:3], 0, v[0:1]
	v_add_co_u32_e32 v4, vcc, s4, v2
	s_movk_i32 s4, 0x7000
	s_nop 0
	v_addc_co_u32_e32 v5, vcc, 0, v3, vcc
	v_add_co_u32_e32 v24, vcc, s4, v2
	s_mov_b32 s4, 0xa000
	s_nop 0
	v_addc_co_u32_e32 v25, vcc, 0, v3, vcc
	v_add_co_u32_e32 v36, vcc, s4, v2
	s_mov_b32 s4, 0xe000
	s_nop 0
	v_addc_co_u32_e32 v37, vcc, 0, v3, vcc
	v_add_co_u32_e32 v38, vcc, s4, v2
	s_mov_b32 s4, 0x11000
	s_nop 0
	v_addc_co_u32_e32 v39, vcc, 0, v3, vcc
	v_add_co_u32_e32 v40, vcc, s4, v2
	s_mov_b32 s4, 0x15000
	s_nop 0
	v_addc_co_u32_e32 v41, vcc, 0, v3, vcc
	v_add_co_u32_e32 v42, vcc, s4, v2
	s_mov_b32 s4, 0x18000
	s_nop 0
	v_addc_co_u32_e32 v43, vcc, 0, v3, vcc
	v_add_co_u32_e32 v44, vcc, s4, v2
	s_mov_b32 s4, 0x1c000
	s_nop 0
	v_addc_co_u32_e32 v45, vcc, 0, v3, vcc
	global_load_dword v0, v[2:3], off
	global_load_dword v48, v[4:5], off offset:2048
	global_load_dword v49, v[24:25], off
	global_load_dword v50, v[36:37], off offset:2048
	global_load_dword v51, v[38:39], off
	global_load_dword v52, v[40:41], off offset:2048
	global_load_dword v53, v[42:43], off
	global_load_dword v54, v[44:45], off offset:2048
	v_add_co_u32_e32 v4, vcc, s4, v2
	s_mov_b32 s4, 0x1f000
	s_nop 0
	v_addc_co_u32_e32 v5, vcc, 0, v3, vcc
	v_add_co_u32_e32 v24, vcc, s4, v2
	s_mov_b32 s4, 0x23000
	s_nop 0
	v_addc_co_u32_e32 v25, vcc, 0, v3, vcc
	v_add_co_u32_e32 v36, vcc, s4, v2
	s_mov_b32 s4, 0x26000
	s_nop 0
	v_addc_co_u32_e32 v37, vcc, 0, v3, vcc
	v_add_co_u32_e32 v38, vcc, s4, v2
	s_mov_b32 s4, 0x2a000
	s_nop 0
	v_addc_co_u32_e32 v39, vcc, 0, v3, vcc
	v_add_co_u32_e32 v40, vcc, s4, v2
	s_mov_b32 s4, 0x2d000
	s_nop 0
	v_addc_co_u32_e32 v41, vcc, 0, v3, vcc
	v_add_co_u32_e32 v42, vcc, s4, v2
	s_mov_b32 s4, 0x31000
	s_nop 0
	v_addc_co_u32_e32 v43, vcc, 0, v3, vcc
	v_add_co_u32_e32 v44, vcc, s4, v2
	s_mov_b32 s4, 0x34000
	s_nop 0
	v_addc_co_u32_e32 v45, vcc, 0, v3, vcc
	v_add_co_u32_e32 v46, vcc, s4, v2
	s_mov_b32 s4, 0x38000
	s_nop 0
	v_addc_co_u32_e32 v47, vcc, 0, v3, vcc
	global_load_dword v55, v[4:5], off
	global_load_dword v56, v[24:25], off offset:2048
	global_load_dword v57, v[36:37], off
	global_load_dword v58, v[38:39], off offset:2048
	global_load_dword v59, v[40:41], off
	global_load_dword v60, v[42:43], off offset:2048
	global_load_dword v61, v[44:45], off
	global_load_dword v62, v[46:47], off offset:2048
	v_add_co_u32_e32 v4, vcc, s4, v2
	s_mov_b32 s4, 0x3b000
	s_nop 0
	v_addc_co_u32_e32 v5, vcc, 0, v3, vcc
	v_add_co_u32_e32 v24, vcc, s4, v2
	s_mov_b32 s4, 0x3f000
	s_nop 0
	v_addc_co_u32_e32 v25, vcc, 0, v3, vcc
	v_add_co_u32_e32 v36, vcc, s4, v2
	s_mov_b32 s4, 0x42000
	s_nop 0
	v_addc_co_u32_e32 v37, vcc, 0, v3, vcc
	v_add_co_u32_e32 v38, vcc, s4, v2
	s_mov_b32 s4, 0x46000
	s_nop 0
	v_addc_co_u32_e32 v39, vcc, 0, v3, vcc
	v_add_co_u32_e32 v40, vcc, s4, v2
	s_mov_b32 s4, 0x49000
	s_nop 0
	v_addc_co_u32_e32 v41, vcc, 0, v3, vcc
	v_add_co_u32_e32 v42, vcc, s4, v2
	s_mov_b32 s4, 0x4d000
	s_nop 0
	v_addc_co_u32_e32 v43, vcc, 0, v3, vcc
	v_add_co_u32_e32 v44, vcc, s4, v2
	s_mov_b32 s4, 0x50000
	s_nop 0
	v_addc_co_u32_e32 v45, vcc, 0, v3, vcc
	v_add_co_u32_e32 v46, vcc, s4, v2
	s_mov_b32 s4, 0x54000
	s_nop 0
	v_addc_co_u32_e32 v47, vcc, 0, v3, vcc
	global_load_dword v63, v[4:5], off
	global_load_dword v64, v[24:25], off offset:2048
	global_load_dword v65, v[36:37], off
	global_load_dword v66, v[38:39], off offset:2048
	global_load_dword v67, v[40:41], off
	global_load_dword v68, v[42:43], off offset:2048
	global_load_dword v69, v[44:45], off
	s_nop 0
	global_load_dword v46, v[46:47], off offset:2048
	v_add_co_u32_e32 v4, vcc, s4, v2
	s_mov_b32 s4, 0x57000
	s_nop 0
	v_addc_co_u32_e32 v5, vcc, 0, v3, vcc
	v_add_co_u32_e32 v24, vcc, s4, v2
	s_mov_b32 s4, 0x5b000
	s_nop 0
	v_addc_co_u32_e32 v25, vcc, 0, v3, vcc
	v_add_co_u32_e32 v36, vcc, s4, v2
	s_mov_b32 s4, 0x5e000
	s_nop 0
	v_addc_co_u32_e32 v37, vcc, 0, v3, vcc
	v_add_co_u32_e32 v38, vcc, s4, v2
	s_mov_b32 s4, 0x62000
	s_nop 0
	v_addc_co_u32_e32 v39, vcc, 0, v3, vcc
	v_add_co_u32_e32 v40, vcc, s4, v2
	s_mov_b32 s4, 0x65000
	s_nop 0
	v_addc_co_u32_e32 v41, vcc, 0, v3, vcc
	v_add_co_u32_e32 v42, vcc, s4, v2
	s_mov_b32 s4, 0x69000
	s_nop 0
	v_addc_co_u32_e32 v43, vcc, 0, v3, vcc
	v_add_co_u32_e32 v44, vcc, s4, v2
	s_mov_b32 s4, 0x6c000
	s_nop 0
	v_addc_co_u32_e32 v45, vcc, 0, v3, vcc
	v_add_co_u32_e32 v2, vcc, s4, v2
	s_lshl_b32 s88, s1, 8
	s_nop 0
	v_addc_co_u32_e32 v3, vcc, 0, v3, vcc
	global_load_dword v47, v[4:5], off
	global_load_dword v70, v[24:25], off offset:2048
	global_load_dword v71, v[36:37], off
	global_load_dword v72, v[38:39], off offset:2048
	s_nop 0
	global_load_dword v40, v[40:41], off
	s_nop 0
	global_load_dword v41, v[42:43], off offset:2048
	s_nop 0
	global_load_dword v42, v[44:45], off
	global_load_dword v43, v[2:3], off offset:2048
	v_lshl_add_u64 v[24:25], v[20:21], 0, s[88:89]
	global_load_dwordx4 v[2:5], v[24:25], off
	global_load_dwordx4 v[36:39], v[24:25], off offset:16
	s_waitcnt vmcnt(32)
	ds_write2_b32 v30, v0, v48 offset1:66
	s_waitcnt vmcnt(30)
	ds_write2_b32 v30, v49, v50 offset0:132 offset1:198
	v_add_u32_e32 v0, 0x400, v30
	s_waitcnt vmcnt(28)
; #define LAS __attribute__((address_space(3)))
; __device__ __forceinline__ unsigned pk2(float lo, float hi) { return f2bf(lo) | (f2bf(hi) << 16); }
; #define LDS_WAVE_SYNC() asm volatile("s_waitcnt lgkmcnt(0)" ::: "memory")
; template <bool HASG>
; __device__ __forceinline__ void tr_item(const float* W, int K, int N, bf16* WT, int rowmode, const float* g, LAS float* scr, int item, int lane) {
;     ...
;     for (int i = 0; i < 32; ++i) scr[(2 * i + (lane >> 5)) * 33 + (lane & 31)] = v[i];
;     LDS_WAVE_SYNC();
;     const int drow0 = rowmode == 0 ? n0 : ((n0 >> 7) * 256 + (n0 & 127) + (rowmode == 2 ? 128 : 0));
; #pragma unroll
;     for (int j = 0; j < 4; ++j) { const int n = (lane >> 3) + 8 * j; const LAS float* s = scr + (8 * c) * 33 + n;
;         u32x4 o; o.x = pk2(s[0 * 33] * g0.x, s[1 * 33] * g0.y); o.y = pk2(s[2 * 33] * g0.z, s[3 * 33] * g0.w);
;         o.z = pk2(s[4 * 33] * g1.x, s[5 * 33] * g1.y); o.w = pk2(s[6 * 33] * g1.z, s[7 * 33] * g1.w);
;         *(u32x4*)(WT + (size_t)(drow0 + n) * K + k0 + 8 * c) = o; }
	ds_write2_b32 v0, v51, v52 offset0:8 offset1:74
	s_waitcnt vmcnt(26)
	ds_write2_b32 v0, v53, v54 offset0:140 offset1:206
	v_add_u32_e32 v0, 0x800, v30
	s_waitcnt vmcnt(24)
	ds_write2_b32 v0, v55, v56 offset0:16 offset1:82
	s_waitcnt vmcnt(22)
	ds_write2_b32 v0, v57, v58 offset0:148 offset1:214
	v_add_u32_e32 v0, 0xc00, v30
	s_waitcnt vmcnt(20)
	ds_write2_b32 v0, v59, v60 offset0:24 offset1:90
	s_waitcnt vmcnt(18)
	ds_write2_b32 v0, v61, v62 offset0:156 offset1:222
	v_add_u32_e32 v0, 0x1000, v30
	s_waitcnt vmcnt(16)
	ds_write2_b32 v0, v63, v64 offset0:32 offset1:98
	s_waitcnt vmcnt(14)
	ds_write2_b32 v0, v65, v66 offset0:164 offset1:230
	v_add_u32_e32 v0, 0x1400, v30
	s_waitcnt vmcnt(12)
	ds_write2_b32 v0, v67, v68 offset0:40 offset1:106
	s_waitcnt vmcnt(10)
	ds_write2_b32 v0, v69, v46 offset0:172 offset1:238
	v_add_u32_e32 v0, 0x1800, v30
	s_waitcnt vmcnt(8)
	ds_write2_b32 v0, v47, v70 offset0:48 offset1:114
	s_waitcnt vmcnt(6)
	ds_write2_b32 v0, v71, v72 offset0:180 offset1:246
	v_add_u32_e32 v0, 0x1c00, v30
	s_waitcnt vmcnt(4)
	ds_write2_b32 v0, v40, v41 offset0:56 offset1:122
	s_waitcnt vmcnt(2)
	ds_write2_b32 v0, v42, v43 offset0:188 offset1:254
	s_waitcnt lgkmcnt(0)
	ds_read2_b32 v[44:45], v31 offset0:33 offset1:41
	ds_read2_b32 v[46:47], v31 offset1:8
	ds_read2_b32 v[48:49], v31 offset0:66 offset1:74
	ds_read2_b32 v[50:51], v31 offset0:99 offset1:107
	ds_read2_b32 v[54:55], v31 offset0:132 offset1:140
	ds_read2_b32 v[56:57], v31 offset0:165 offset1:173
	ds_read2_b32 v[58:59], v31 offset0:198 offset1:206
	ds_read2_b32 v[60:61], v31 offset0:231 offset1:239
	s_waitcnt vmcnt(1)
	v_mov_b32_e32 v52, v2
	v_mov_b32_e32 v53, v4
	v_mov_b32_e32 v4, v3
	s_waitcnt lgkmcnt(7)
	v_mov_b32_e32 v2, v44
	s_waitcnt lgkmcnt(4)
	v_mov_b32_e32 v3, v50
	s_waitcnt vmcnt(0)
	v_mov_b32_e32 v62, v36
	v_mov_b32_e32 v63, v38
	v_mov_b32_e32 v38, v37
	s_waitcnt lgkmcnt(2)
	v_mov_b32_e32 v36, v56
	s_waitcnt lgkmcnt(0)
	v_mov_b32_e32 v37, v60
	v_mov_b32_e32 v40, v46
	v_mov_b32_e32 v41, v48
	v_pk_mul_f32 v[2:3], v[4:5], v[2:3]
	v_mov_b32_e32 v42, v54
	v_mov_b32_e32 v43, v58
	v_pk_mul_f32 v[36:37], v[38:39], v[36:37]
	v_pk_mul_f32 v[40:41], v[52:53], v[40:41]
	v_pk_mul_f32 v[42:43], v[62:63], v[42:43]
	v_bfe_u32 v44, v36, 16, 1
	v_bfe_u32 v46, v3, 16, 1
	v_bfe_u32 v48, v2, 16, 1
	v_bfe_u32 v0, v37, 16, 1
	v_add3_u32 v2, v2, v48, s91
	v_add3_u32 v3, v3, v46, s91
	v_add3_u32 v36, v36, v44, s91
	v_bfe_u32 v44, v41, 16, 1
	v_bfe_u32 v46, v42, 16, 1
	v_bfe_u32 v48, v43, 16, 1
	v_add3_u32 v0, v37, v0, s91
	v_bfe_u32 v37, v40, 16, 1
	v_add3_u32 v43, v43, v48, s91
	v_add3_u32 v42, v42, v46, s91
	v_add3_u32 v41, v41, v44, s91
	v_add3_u32 v37, v40, v37, s91
	v_lshrrev_b32_e32 v40, 16, v41
	v_lshrrev_b32_e32 v41, 16, v42
	v_lshrrev_b32_e32 v42, 16, v43
	s_lshl_b32 s88, s1, 7
	v_and_or_b32 v43, v0, s35, v42
	v_or_b32_e32 v0, s0, v7
	v_lshl_add_u64 v[24:25], v[12:13], 0, s[88:89]
	v_lshrrev_b32_e32 v37, 16, v37
	v_lshlrev_b32_e32 v0, 11, v0
	v_mov_b32_e32 v50, v45
	v_and_or_b32 v42, v36, s35, v41
	v_and_or_b32 v41, v3, s35, v40
	v_and_or_b32 v40, v2, s35, v37
	v_lshl_add_u64 v[2:3], v[24:25], 0, v[0:1]
	v_pk_mul_f32 v[36:37], v[4:5], v[50:51]
	v_mov_b32_e32 v58, v55
	global_store_dwordx4 v[2:3], v[40:43], off sc1
	v_mov_b32_e32 v60, v57
	v_bfe_u32 v46, v36, 16, 1
	v_pk_mul_f32 v[40:41], v[62:63], v[58:59]
	v_mov_b32_e32 v48, v47
	v_pk_mul_f32 v[42:43], v[38:39], v[60:61]
	v_add3_u32 v36, v36, v46, s91
	v_bfe_u32 v46, v41, 16, 1
	v_pk_mul_f32 v[2:3], v[52:53], v[48:49]
	v_bfe_u32 v0, v43, 16, 1
	v_bfe_u32 v44, v42, 16, 1
	v_bfe_u32 v45, v37, 16, 1
	v_add3_u32 v41, v41, v46, s91
	v_add3_u32 v37, v37, v45, s91
	v_add3_u32 v42, v42, v44, s91
	v_add3_u32 v0, v43, v0, s91
	v_bfe_u32 v43, v2, 16, 1
	v_bfe_u32 v44, v3, 16, 1
	v_bfe_u32 v45, v40, 16, 1
	v_lshrrev_b32_e32 v41, 16, v41
	v_add3_u32 v40, v40, v45, s91
	v_add3_u32 v3, v3, v44, s91
	v_add3_u32 v2, v2, v43, s91
	v_and_or_b32 v43, v0, s35, v41
	v_or_b32_e32 v0, s0, v32
	v_lshrrev_b32_e32 v2, 16, v2
	v_lshrrev_b32_e32 v3, 16, v3
	v_lshrrev_b32_e32 v40, 16, v40
	v_lshlrev_b32_e32 v0, 11, v0
	v_and_or_b32 v42, v42, s35, v40
	v_and_or_b32 v41, v37, s35, v3
	v_and_or_b32 v40, v36, s35, v2
	v_lshl_add_u64 v[2:3], v[24:25], 0, v[0:1]
	ds_read2_b32 v[36:37], v31 offset0:16 offset1:24
	ds_read2_b32 v[44:45], v31 offset0:82 offset1:90
	global_store_dwordx4 v[2:3], v[40:43], off sc1
	ds_read2_b32 v[2:3], v31 offset0:49 offset1:57
	ds_read2_b32 v[46:47], v31 offset0:115 offset1:123
	ds_read2_b32 v[48:49], v31 offset0:148 offset1:156
	ds_read2_b32 v[50:51], v31 offset0:214 offset1:222
	ds_read2_b32 v[54:55], v31 offset0:181 offset1:189
	ds_read2_b32 v[56:57], v31 offset0:247 offset1:255
	s_waitcnt lgkmcnt(7)
; #define LAS __attribute__((address_space(3)))
; __device__ __forceinline__ unsigned pk2(float lo, float hi) { return f2bf(lo) | (f2bf(hi) << 16); }
; #define LDS_WAVE_SYNC() asm volatile("s_waitcnt lgkmcnt(0)" ::: "memory")
; template <bool HASG>
; __device__ __forceinline__ void tr_item(const float* W, int K, int N, bf16* WT, int rowmode, const float* g, LAS float* scr, int item, int lane) {
;     ...
;     for (int j = 0; j < 4; ++j) { const int n = (lane >> 3) + 8 * j; const LAS float* s = scr + (8 * c) * 33 + n;
;         u32x4 o; o.x = pk2(s[0 * 33] * g0.x, s[1 * 33] * g0.y); o.y = pk2(s[2 * 33] * g0.z, s[3 * 33] * g0.w);
;         o.z = pk2(s[4 * 33] * g1.x, s[5 * 33] * g1.y); o.w = pk2(s[6 * 33] * g1.z, s[7 * 33] * g1.w);
;         *(u32x4*)(WT + (size_t)(drow0 + n) * K + k0 + 8 * c) = o; }
;     LDS_WAVE_SYNC();
	v_mov_b32_e32 v40, v36
	s_waitcnt lgkmcnt(5)
	v_mov_b32_e32 v42, v2
	s_waitcnt lgkmcnt(4)
	v_mov_b32_e32 v43, v46
	s_waitcnt lgkmcnt(3)
	v_mov_b32_e32 v58, v48
	s_waitcnt lgkmcnt(2)
	v_mov_b32_e32 v59, v50
	v_mov_b32_e32 v41, v44
	v_pk_mul_f32 v[42:43], v[4:5], v[42:43]
	v_pk_mul_f32 v[58:59], v[62:63], v[58:59]
	s_waitcnt lgkmcnt(1)
	v_mov_b32_e32 v60, v54
	s_waitcnt lgkmcnt(0)
	v_mov_b32_e32 v61, v56
	v_pk_mul_f32 v[40:41], v[52:53], v[40:41]
	v_pk_mul_f32 v[60:61], v[38:39], v[60:61]
	v_bfe_u32 v36, v43, 16, 1
	v_bfe_u32 v48, v59, 16, 1
	v_bfe_u32 v0, v61, 16, 1
	v_bfe_u32 v44, v42, 16, 1
	v_add3_u32 v36, v43, v36, s91
	v_bfe_u32 v43, v41, 16, 1
	v_add3_u32 v48, v59, v48, s91
	v_add3_u32 v44, v42, v44, s91
	v_add3_u32 v0, v61, v0, s91
	v_bfe_u32 v42, v40, 16, 1
	v_bfe_u32 v46, v58, 16, 1
	v_add3_u32 v41, v41, v43, s91
	v_lshrrev_b32_e32 v43, 16, v48
	v_bfe_u32 v2, v60, 16, 1
	v_add3_u32 v46, v58, v46, s91
	v_add3_u32 v40, v40, v42, s91
	v_and_or_b32 v43, v0, s35, v43
	v_or_b32_e32 v0, s0, v34
	v_add3_u32 v2, v60, v2, s91
	v_lshrrev_b32_e32 v40, 16, v40
	v_lshrrev_b32_e32 v41, 16, v41
	v_lshrrev_b32_e32 v42, 16, v46
	v_lshlrev_b32_e32 v0, 11, v0
	v_mov_b32_e32 v46, v3
	v_and_or_b32 v42, v2, s35, v42
	v_and_or_b32 v41, v36, s35, v41
	v_and_or_b32 v40, v44, s35, v40
	v_lshl_add_u64 v[58:59], v[24:25], 0, v[0:1]
	v_pk_mul_f32 v[2:3], v[4:5], v[46:47]
	v_mov_b32_e32 v50, v49
	global_store_dwordx4 v[58:59], v[40:43], off sc1
	v_pk_mul_f32 v[4:5], v[62:63], v[50:51]
	v_mov_b32_e32 v56, v55
	v_bfe_u32 v42, v2, 16, 1
	v_mov_b32_e32 v44, v37
	v_pk_mul_f32 v[38:39], v[38:39], v[56:57]
	v_add3_u32 v2, v2, v42, s91
	v_bfe_u32 v42, v5, 16, 1
	v_pk_mul_f32 v[36:37], v[52:53], v[44:45]
	v_bfe_u32 v0, v39, 16, 1
	v_bfe_u32 v40, v38, 16, 1
	v_bfe_u32 v41, v3, 16, 1
	v_add3_u32 v5, v5, v42, s91
	v_add3_u32 v3, v3, v41, s91
	v_add3_u32 v38, v38, v40, s91
	v_add3_u32 v0, v39, v0, s91
	v_bfe_u32 v39, v36, 16, 1
	v_bfe_u32 v40, v37, 16, 1
	v_bfe_u32 v41, v4, 16, 1
	v_lshrrev_b32_e32 v5, 16, v5
	v_add3_u32 v4, v4, v41, s91
	v_add3_u32 v37, v37, v40, s91
	v_add3_u32 v36, v36, v39, s91
	v_and_or_b32 v5, v0, s35, v5
	v_or_b32_e32 v0, s0, v35
	v_lshrrev_b32_e32 v36, 16, v36
	v_lshrrev_b32_e32 v37, 16, v37
	v_lshrrev_b32_e32 v4, 16, v4
	v_lshlrev_b32_e32 v0, 11, v0
	v_and_or_b32 v4, v38, s35, v4
	v_and_or_b32 v3, v3, s35, v37
	v_and_or_b32 v2, v2, s35, v36
	v_lshl_add_u64 v[24:25], v[24:25], 0, v[0:1]
	global_store_dwordx4 v[24:25], v[2:5], off sc1
	s_waitcnt lgkmcnt(0)
	v_readlane_b32 s8, v252, 4
	v_readlane_b32 s9, v252, 5
	s_mov_b64 s[8:9], s[26:27]
	v_readlane_b32 s5, v252, 1
	v_readlane_b32 s6, v252, 2
	v_readlane_b32 s7, v252, 3
	v_readlane_b32 s10, v252, 6
	v_readlane_b32 s11, v252, 7
	v_readlane_b32 s12, v252, 8
	v_readlane_b32 s13, v252, 9
	v_readlane_b32 s14, v252, 10
	v_readlane_b32 s15, v252, 11
	v_readlane_b32 s18, v252, 14
	v_readlane_b32 s19, v252, 15

; template <bool HASG>
; __device__ __forceinline__ void tr_item(const float* W, int K, int N, bf16* WT, int rowmode, const float* g, LAS float* scr, int item, int lane) {
;     const int nblk = N / 32, kb = item / nblk, nb = item % nblk, k0 = 64 * kb, n0 = 32 * nb;
;     const float* wp = W + (size_t)(k0 + (lane >> 5)) * N + n0 + (lane & 31);
;     const int c = lane & 7;
;     float v[32];
; #pragma unroll
;     for (int i = 0; i < 32; ++i) v[i] = wp[(size_t)(2 * i) * N];
;     f32x4 g0 = (f32x4){1.f, 1.f, 1.f, 1.f}, g1 = g0;
;     if (HASG) { g0 = *(const f32x4*)(g + k0 + 8 * c); g1 = *(const f32x4*)(g + k0 + 8 * c + 4); }
;     asm volatile("" ::: "memory");
; #pragma unroll
;     for (int i = 0; i < 32; ++i) scr[(2 * i + (lane >> 5)) * 33 + (lane & 31)] = v[i];
; __device__ __forceinline__ void convert_items(const Args& a, LAS unsigned char* lds, int l, int it_lo, int it_hi, int gw, int NGW, int wave, int lane) {
;     ...
;         if (r < I_D) { tr_item<false>(a.in[4] + o_d, FF, D, wl + W_D1, 0, nullptr, scr, r, lane); continue; } r -= I_D;
.LBB0_561:
	s_andn2_b64 vcc, exec, s[0:1]
	s_cbranch_vccnz .LBB0_563
	s_add_i32 s0, s43, 0x1200
	s_and_b32 s1, s0, 0x1ffc0
	s_lshl_b32 s0, s46, 5
	v_or_b32_e32 v0, s1, v33
	v_readlane_b32 s4, v252, 0
	s_and_b32 s0, s0, 0x3e0
	v_lshlrev_b32_e32 v0, 12, v0
	v_readlane_b32 s12, v252, 8
	v_readlane_b32 s13, v252, 9
	s_lshl_b32 s88, s0, 2
	s_movk_i32 s4, 0x2000
	v_lshl_add_u64 v[2:3], s[12:13], 0, v[0:1]
	v_lshl_add_u64 v[2:3], v[2:3], 0, s[88:89]
	v_lshlrev_b32_e32 v0, 2, v6
	v_lshl_add_u64 v[2:3], v[2:3], 0, v[0:1]
	v_add_co_u32_e32 v4, vcc, s4, v2
	s_movk_i32 s4, 0x4000
	s_nop 0
	v_addc_co_u32_e32 v5, vcc, 0, v3, vcc
	global_load_dword v0, v[2:3], off
	global_load_dword v24, v[4:5], off
	v_add_co_u32_e32 v4, vcc, s4, v2
	s_movk_i32 s4, 0x6000
	s_nop 0
	v_addc_co_u32_e32 v5, vcc, 0, v3, vcc
	global_load_dword v25, v[4:5], off
	v_add_co_u32_e32 v4, vcc, s4, v2
	s_mov_b32 s4, 0x8000
	s_nop 0
	v_addc_co_u32_e32 v5, vcc, 0, v3, vcc
	global_load_dword v36, v[4:5], off
	v_add_co_u32_e32 v4, vcc, s4, v2
	s_mov_b32 s4, 0xa000
	s_nop 0
	v_addc_co_u32_e32 v5, vcc, 0, v3, vcc
	global_load_dword v37, v[4:5], off
	v_add_co_u32_e32 v4, vcc, s4, v2
	s_mov_b32 s4, 0xc000
	s_nop 0
	v_addc_co_u32_e32 v5, vcc, 0, v3, vcc
	global_load_dword v38, v[4:5], off
	v_add_co_u32_e32 v4, vcc, s4, v2
	s_mov_b32 s4, 0xe000
	s_nop 0
	v_addc_co_u32_e32 v5, vcc, 0, v3, vcc
	global_load_dword v39, v[4:5], off
	v_add_co_u32_e32 v4, vcc, s4, v2
	s_mov_b32 s4, 0x12000
	s_nop 0
	v_addc_co_u32_e32 v5, vcc, 0, v3, vcc
	global_load_dword v40, v[4:5], off
	v_add_co_u32_e32 v4, vcc, s70, v2
	s_lshl_b32 s88, s1, 1
	s_nop 0
	v_addc_co_u32_e32 v5, vcc, 0, v3, vcc
	global_load_dword v41, v[4:5], off
	v_add_co_u32_e32 v4, vcc, s4, v2
	s_mov_b32 s4, 0x14000
	s_nop 0
	v_addc_co_u32_e32 v5, vcc, 0, v3, vcc
	global_load_dword v42, v[4:5], off
	v_add_co_u32_e32 v4, vcc, s4, v2
	s_mov_b32 s4, 0x18000
	s_nop 0
	v_addc_co_u32_e32 v5, vcc, 0, v3, vcc
	global_load_dword v43, v[4:5], off
	v_add_co_u32_e32 v4, vcc, s71, v2
	v_readlane_b32 s8, v252, 4
	s_nop 0
	v_addc_co_u32_e32 v5, vcc, 0, v3, vcc
	global_load_dword v44, v[4:5], off
	v_add_co_u32_e32 v4, vcc, s4, v2
	s_mov_b32 s4, 0x1a000
	s_nop 0
	v_addc_co_u32_e32 v5, vcc, 0, v3, vcc
	global_load_dword v45, v[4:5], off
	v_add_co_u32_e32 v4, vcc, s4, v2
	s_mov_b32 s4, 0x1c000
	s_nop 0
	v_addc_co_u32_e32 v5, vcc, 0, v3, vcc
	global_load_dword v46, v[4:5], off
	v_add_co_u32_e32 v4, vcc, s4, v2
	s_mov_b32 s4, 0x1e000
	s_nop 0
	v_addc_co_u32_e32 v5, vcc, 0, v3, vcc
	global_load_dword v47, v[4:5], off
	v_add_co_u32_e32 v4, vcc, s4, v2
	s_mov_b32 s4, 0x20000
	s_nop 0
	v_addc_co_u32_e32 v5, vcc, 0, v3, vcc
	global_load_dword v48, v[4:5], off
	v_add_co_u32_e32 v4, vcc, s4, v2
	s_mov_b32 s4, 0x22000
	s_nop 0
	v_addc_co_u32_e32 v5, vcc, 0, v3, vcc
	global_load_dword v49, v[4:5], off
	v_add_co_u32_e32 v4, vcc, s4, v2
	s_mov_b32 s4, 0x24000
	s_nop 0
	v_addc_co_u32_e32 v5, vcc, 0, v3, vcc
	global_load_dword v50, v[4:5], off
	v_add_co_u32_e32 v4, vcc, s4, v2
	s_mov_b32 s4, 0x26000
	s_nop 0
	v_addc_co_u32_e32 v5, vcc, 0, v3, vcc
	global_load_dword v51, v[4:5], off
	v_add_co_u32_e32 v4, vcc, s4, v2
	s_mov_b32 s4, 0x28000
	s_nop 0
	v_addc_co_u32_e32 v5, vcc, 0, v3, vcc
	global_load_dword v52, v[4:5], off
	v_add_co_u32_e32 v4, vcc, s4, v2
	s_mov_b32 s4, 0x2a000
	s_nop 0
	v_addc_co_u32_e32 v5, vcc, 0, v3, vcc
	global_load_dword v53, v[4:5], off
	v_add_co_u32_e32 v4, vcc, s4, v2
	s_mov_b32 s4, 0x2c000
	s_nop 0
	v_addc_co_u32_e32 v5, vcc, 0, v3, vcc
	global_load_dword v54, v[4:5], off
	v_add_co_u32_e32 v4, vcc, s4, v2
	s_mov_b32 s4, 0x2e000
	s_nop 0
	v_addc_co_u32_e32 v5, vcc, 0, v3, vcc
	global_load_dword v55, v[4:5], off
	v_add_co_u32_e32 v4, vcc, s4, v2
	s_mov_b32 s4, 0x30000
	s_nop 0
	v_addc_co_u32_e32 v5, vcc, 0, v3, vcc
	global_load_dword v56, v[4:5], off
	v_add_co_u32_e32 v4, vcc, s4, v2
	s_mov_b32 s4, 0x32000
	s_nop 0
	v_addc_co_u32_e32 v5, vcc, 0, v3, vcc
	global_load_dword v57, v[4:5], off
	v_add_co_u32_e32 v4, vcc, s4, v2
	s_mov_b32 s4, 0x34000
	s_nop 0
	v_addc_co_u32_e32 v5, vcc, 0, v3, vcc
	global_load_dword v58, v[4:5], off
	v_add_co_u32_e32 v4, vcc, s4, v2
	s_mov_b32 s4, 0x36000
	s_nop 0
	v_addc_co_u32_e32 v5, vcc, 0, v3, vcc
	global_load_dword v59, v[4:5], off
	v_add_co_u32_e32 v4, vcc, s4, v2
	s_mov_b32 s4, 0x38000
	s_nop 0
	v_addc_co_u32_e32 v5, vcc, 0, v3, vcc
	global_load_dword v60, v[4:5], off
	v_add_co_u32_e32 v4, vcc, s4, v2
	s_mov_b32 s4, 0x3a000
	s_nop 0
	v_addc_co_u32_e32 v5, vcc, 0, v3, vcc
	global_load_dword v61, v[4:5], off
	v_add_co_u32_e32 v4, vcc, s4, v2
	s_mov_b32 s4, 0x3c000
	s_nop 0
	v_addc_co_u32_e32 v5, vcc, 0, v3, vcc
	global_load_dword v62, v[4:5], off
	v_add_co_u32_e32 v4, vcc, s4, v2
	s_mov_b32 s4, 0x3e000
	s_nop 0
	v_addc_co_u32_e32 v5, vcc, 0, v3, vcc
	v_add_co_u32_e32 v2, vcc, s4, v2
	global_load_dword v4, v[4:5], off
	s_nop 0
	v_addc_co_u32_e32 v3, vcc, 0, v3, vcc
	global_load_dword v2, v[2:3], off
	s_waitcnt vmcnt(30)
	ds_write2_b32 v30, v0, v24 offset1:66
	s_waitcnt vmcnt(28)
	ds_write2_b32 v30, v25, v36 offset0:132 offset1:198
	v_add_u32_e32 v0, 0x400, v30
	s_waitcnt vmcnt(26)
	ds_write2_b32 v0, v37, v38 offset0:8 offset1:74
	s_waitcnt vmcnt(24)
	ds_write2_b32 v0, v39, v40 offset0:140 offset1:206
	v_add_u32_e32 v0, 0x800, v30
	s_waitcnt vmcnt(22)
	ds_write2_b32 v0, v41, v42 offset0:16 offset1:82
	s_waitcnt vmcnt(20)
	ds_write2_b32 v0, v43, v44 offset0:148 offset1:214
	v_add_u32_e32 v0, 0xc00, v30
	s_waitcnt vmcnt(18)
	ds_write2_b32 v0, v45, v46 offset0:24 offset1:90
	s_waitcnt vmcnt(16)
	ds_write2_b32 v0, v47, v48 offset0:156 offset1:222
	v_add_u32_e32 v0, 0x1000, v30
	s_waitcnt vmcnt(14)
; #define LAS __attribute__((address_space(3)))
; __device__ __forceinline__ unsigned pk2(float lo, float hi) { return f2bf(lo) | (f2bf(hi) << 16); }
; #define LDS_WAVE_SYNC() asm volatile("s_waitcnt lgkmcnt(0)" ::: "memory")
; template <bool HASG>
; __device__ __forceinline__ void tr_item(const float* W, int K, int N, bf16* WT, int rowmode, const float* g, LAS float* scr, int item, int lane) {
;     ...
;     for (int i = 0; i < 32; ++i) scr[(2 * i + (lane >> 5)) * 33 + (lane & 31)] = v[i];
;     LDS_WAVE_SYNC();
;     const int drow0 = rowmode == 0 ? n0 : ((n0 >> 7) * 256 + (n0 & 127) + (rowmode == 2 ? 128 : 0));
; #pragma unroll
;     for (int j = 0; j < 4; ++j) { const int n = (lane >> 3) + 8 * j; const LAS float* s = scr + (8 * c) * 33 + n;
;         u32x4 o; o.x = pk2(s[0 * 33] * g0.x, s[1 * 33] * g0.y); o.y = pk2(s[2 * 33] * g0.z, s[3 * 33] * g0.w);
;         o.z = pk2(s[4 * 33] * g1.x, s[5 * 33] * g1.y); o.w = pk2(s[6 * 33] * g1.z, s[7 * 33] * g1.w);
;         *(u32x4*)(WT + (size_t)(drow0 + n) * K + k0 + 8 * c) = o; }
;     LDS_WAVE_SYNC();
	ds_write2_b32 v0, v49, v50 offset0:32 offset1:98
	s_waitcnt vmcnt(12)
	ds_write2_b32 v0, v51, v52 offset0:164 offset1:230
	v_add_u32_e32 v0, 0x1400, v30
	s_waitcnt vmcnt(10)
	ds_write2_b32 v0, v53, v54 offset0:40 offset1:106
	s_waitcnt vmcnt(8)
	ds_write2_b32 v0, v55, v56 offset0:172 offset1:238
	v_add_u32_e32 v0, 0x1800, v30
	s_waitcnt vmcnt(6)
	ds_write2_b32 v0, v57, v58 offset0:48 offset1:114
	s_waitcnt vmcnt(4)
	ds_write2_b32 v0, v59, v60 offset0:180 offset1:246
	v_add_u32_e32 v0, 0x1c00, v30
	s_waitcnt vmcnt(2)
	ds_write2_b32 v0, v61, v62 offset0:56 offset1:122
	s_waitcnt vmcnt(0)
	ds_write2_b32 v0, v4, v2 offset0:188 offset1:254
	s_waitcnt lgkmcnt(0)
	ds_read2_b32 v[4:5], v31 offset0:33 offset1:41
	ds_read2_b32 v[24:25], v31 offset1:8
	ds_read2_b32 v[40:41], v31 offset0:66 offset1:74
	ds_read2_b32 v[42:43], v31 offset0:99 offset1:107
	ds_read2_b32 v[44:45], v31 offset0:132 offset1:140
	ds_read2_b32 v[46:47], v31 offset0:165 offset1:173
	ds_read2_b32 v[48:49], v31 offset0:198 offset1:206
	ds_read2_b32 v[50:51], v31 offset0:231 offset1:239
	v_lshl_add_u64 v[2:3], v[14:15], 0, s[88:89]
	s_waitcnt lgkmcnt(6)
	v_bfe_u32 v0, v24, 16, 1
	v_add3_u32 v0, v24, v0, s91
	v_bfe_u32 v24, v4, 16, 1
	v_lshrrev_b32_e32 v0, 16, v0
	v_add3_u32 v4, v4, v24, s91
	v_and_or_b32 v36, v4, s35, v0
	s_waitcnt lgkmcnt(5)
	v_bfe_u32 v0, v40, 16, 1
	v_add3_u32 v0, v40, v0, s91
	s_waitcnt lgkmcnt(4)
	v_bfe_u32 v4, v42, 16, 1
	v_lshrrev_b32_e32 v0, 16, v0
	v_add3_u32 v4, v42, v4, s91
	v_and_or_b32 v37, v4, s35, v0
	s_waitcnt lgkmcnt(3)
	v_bfe_u32 v0, v44, 16, 1
	v_add3_u32 v0, v44, v0, s91
	s_waitcnt lgkmcnt(2)
	v_bfe_u32 v4, v46, 16, 1
	v_lshrrev_b32_e32 v0, 16, v0
	v_add3_u32 v4, v46, v4, s91
	v_and_or_b32 v38, v4, s35, v0
	s_waitcnt lgkmcnt(1)
	v_bfe_u32 v0, v48, 16, 1
	v_add3_u32 v0, v48, v0, s91
	s_waitcnt lgkmcnt(0)
	v_bfe_u32 v4, v50, 16, 1
	v_lshrrev_b32_e32 v0, 16, v0
	v_add3_u32 v4, v50, v4, s91
	v_and_or_b32 v39, v4, s35, v0
	v_or_b32_e32 v0, s0, v7
	v_mul_u32_u24_e32 v0, 0xb00, v0
	v_lshlrev_b32_e32 v0, 1, v0
	v_lshl_add_u64 v[52:53], v[2:3], 0, v[0:1]
	v_bfe_u32 v0, v25, 16, 1
	v_add3_u32 v0, v25, v0, s91
	v_bfe_u32 v4, v5, 16, 1
	v_lshrrev_b32_e32 v0, 16, v0
	v_add3_u32 v4, v5, v4, s91
	global_store_dwordx4 v[52:53], v[36:39], off sc1
	v_readlane_b32 s9, v252, 5
	s_mov_b64 s[8:9], s[26:27]
	v_and_or_b32 v36, v4, s35, v0
	v_bfe_u32 v0, v41, 16, 1
	v_add3_u32 v0, v41, v0, s91
	v_bfe_u32 v4, v43, 16, 1
	v_lshrrev_b32_e32 v0, 16, v0
	v_add3_u32 v4, v43, v4, s91
	v_and_or_b32 v37, v4, s35, v0
	v_bfe_u32 v0, v45, 16, 1
	v_add3_u32 v0, v45, v0, s91
	v_bfe_u32 v4, v47, 16, 1
	v_lshrrev_b32_e32 v0, 16, v0
	v_add3_u32 v4, v47, v4, s91
	v_and_or_b32 v38, v4, s35, v0
	v_bfe_u32 v0, v49, 16, 1
	v_add3_u32 v0, v49, v0, s91
	v_bfe_u32 v4, v51, 16, 1
	v_lshrrev_b32_e32 v0, 16, v0
	v_add3_u32 v4, v51, v4, s91
	v_and_or_b32 v39, v4, s35, v0
	v_or_b32_e32 v0, s0, v32
	v_mul_u32_u24_e32 v0, 0xb00, v0
	v_lshlrev_b32_e32 v0, 1, v0
	v_lshl_add_u64 v[4:5], v[2:3], 0, v[0:1]
	global_store_dwordx4 v[4:5], v[36:39], off sc1
	ds_read2_b32 v[4:5], v31 offset0:16 offset1:24
	ds_read2_b32 v[24:25], v31 offset0:49 offset1:57
	ds_read2_b32 v[40:41], v31 offset0:82 offset1:90
	ds_read2_b32 v[42:43], v31 offset0:115 offset1:123
	ds_read2_b32 v[44:45], v31 offset0:148 offset1:156
	ds_read2_b32 v[46:47], v31 offset0:181 offset1:189
	ds_read2_b32 v[48:49], v31 offset0:214 offset1:222
	ds_read2_b32 v[50:51], v31 offset0:247 offset1:255
	s_waitcnt lgkmcnt(7)
	v_bfe_u32 v0, v4, 16, 1
	v_add3_u32 v0, v4, v0, s91
	s_waitcnt lgkmcnt(6)
	v_bfe_u32 v4, v24, 16, 1
	v_lshrrev_b32_e32 v0, 16, v0
	v_add3_u32 v4, v24, v4, s91
	v_and_or_b32 v36, v4, s35, v0
	s_waitcnt lgkmcnt(5)
	v_bfe_u32 v0, v40, 16, 1
	v_add3_u32 v0, v40, v0, s91
	s_waitcnt lgkmcnt(4)
	v_bfe_u32 v4, v42, 16, 1
	v_lshrrev_b32_e32 v0, 16, v0
	v_add3_u32 v4, v42, v4, s91
	v_and_or_b32 v37, v4, s35, v0
	s_waitcnt lgkmcnt(3)
	v_bfe_u32 v0, v44, 16, 1
	v_add3_u32 v0, v44, v0, s91
	s_waitcnt lgkmcnt(2)
	v_bfe_u32 v4, v46, 16, 1
	v_lshrrev_b32_e32 v0, 16, v0
	v_add3_u32 v4, v46, v4, s91
	v_and_or_b32 v38, v4, s35, v0
	s_waitcnt lgkmcnt(1)
	v_bfe_u32 v0, v48, 16, 1
	v_add3_u32 v0, v48, v0, s91
	s_waitcnt lgkmcnt(0)
	v_bfe_u32 v4, v50, 16, 1
	v_lshrrev_b32_e32 v0, 16, v0
	v_add3_u32 v4, v50, v4, s91
	v_and_or_b32 v39, v4, s35, v0
	v_or_b32_e32 v0, s0, v34
	v_mul_u32_u24_e32 v0, 0xb00, v0
	v_lshlrev_b32_e32 v0, 1, v0
	v_lshl_add_u64 v[52:53], v[2:3], 0, v[0:1]
	v_bfe_u32 v0, v5, 16, 1
	v_add3_u32 v0, v5, v0, s91
	v_bfe_u32 v4, v25, 16, 1
	v_lshrrev_b32_e32 v0, 16, v0
	v_add3_u32 v4, v25, v4, s91
	global_store_dwordx4 v[52:53], v[36:39], off sc1
	v_readlane_b32 s5, v252, 1
	v_readlane_b32 s6, v252, 2
	v_and_or_b32 v36, v4, s35, v0
	v_bfe_u32 v0, v41, 16, 1
	v_add3_u32 v0, v41, v0, s91
	v_bfe_u32 v4, v43, 16, 1
	v_lshrrev_b32_e32 v0, 16, v0
	v_add3_u32 v4, v43, v4, s91
	v_and_or_b32 v37, v4, s35, v0
	v_bfe_u32 v0, v45, 16, 1
	v_add3_u32 v0, v45, v0, s91
	v_bfe_u32 v4, v47, 16, 1
	v_lshrrev_b32_e32 v0, 16, v0
	v_add3_u32 v4, v47, v4, s91
	v_and_or_b32 v38, v4, s35, v0
	v_bfe_u32 v0, v49, 16, 1
	v_add3_u32 v0, v49, v0, s91
	v_bfe_u32 v4, v51, 16, 1
	v_lshrrev_b32_e32 v0, 16, v0
	v_add3_u32 v4, v51, v4, s91
	v_and_or_b32 v39, v4, s35, v0
	v_or_b32_e32 v0, s0, v35
	v_mul_u32_u24_e32 v0, 0xb00, v0
	v_lshlrev_b32_e32 v0, 1, v0
	v_lshl_add_u64 v[2:3], v[2:3], 0, v[0:1]
	global_store_dwordx4 v[2:3], v[36:39], off sc1
	s_waitcnt lgkmcnt(0)
	v_readlane_b32 s7, v252, 3
	v_readlane_b32 s10, v252, 6
	v_readlane_b32 s11, v252, 7
	v_readlane_b32 s14, v252, 10
	v_readlane_b32 s15, v252, 11
	v_readlane_b32 s16, v252, 12
	v_readlane_b32 s17, v252, 13
	v_readlane_b32 s18, v252, 14
	v_readlane_b32 s19, v252, 15

; template <bool HASG>
; __device__ __forceinline__ void tr_item(const float* W, int K, int N, bf16* WT, int rowmode, const float* g, LAS float* scr, int item, int lane) {
;     const int nblk = N / 32, kb = item / nblk, nb = item % nblk, k0 = 64 * kb, n0 = 32 * nb;
;     const float* wp = W + (size_t)(k0 + (lane >> 5)) * N + n0 + (lane & 31);
;     const int c = lane & 7;
;     float v[32];
; #pragma unroll
;     for (int i = 0; i < 32; ++i) v[i] = wp[(size_t)(2 * i) * N];
;     f32x4 g0 = (f32x4){1.f, 1.f, 1.f, 1.f}, g1 = g0;
;     if (HASG) { g0 = *(const f32x4*)(g + k0 + 8 * c); g1 = *(const f32x4*)(g + k0 + 8 * c + 4); }
;     asm volatile("" ::: "memory");
; #pragma unroll
;     for (int i = 0; i < 32; ++i) scr[(2 * i + (lane >> 5)) * 33 + (lane & 31)] = v[i];
; __device__ __forceinline__ void convert_items(const Args& a, LAS unsigned char* lds, int l, int it_lo, int it_hi, int gw, int NGW, int wave, int lane) {
;     ...
;         if (r < I_G) { tr_item<true>(a.in[3] + o_gu, D, FF, wl + W_GU1, 2, a.in[1] + l * D, scr, r, lane); continue; } r -= I_G;
.LBB0_564:
	s_andn2_b64 vcc, exec, s[0:1]
	s_cbranch_vccnz .LBB0_566
	s_add_i32 s0, s46, 0xfa80
	s_and_b32 s1, s0, 0xffff
	s_mul_i32 s1, s1, 0xba2f
	s_lshr_b32 s38, s1, 16
	s_lshr_b32 s1, s1, 22
	s_mulk_i32 s1, 0x58
	s_sub_i32 s0, s0, s1
	s_and_b32 s1, s38, 0xffc0
	v_or_b32_e32 v0, s1, v33
	v_mul_u32_u24_e32 v0, 0xb00, v0
	v_readlane_b32 s4, v252, 0
	s_and_b32 s39, s0, 0xffff
	v_lshlrev_b32_e32 v0, 2, v0
	v_readlane_b32 s10, v252, 6
	v_readlane_b32 s11, v252, 7
	s_lshl_b32 s88, s39, 7
	s_movk_i32 s4, 0x5000
	v_lshl_add_u64 v[2:3], s[10:11], 0, v[0:1]
	v_lshl_add_u64 v[2:3], v[2:3], 0, s[88:89]
	v_lshlrev_b32_e32 v0, 2, v6
	v_lshl_add_u64 v[2:3], v[2:3], 0, v[0:1]
	v_add_co_u32_e32 v4, vcc, s4, v2
	s_mov_b32 s4, 0x1b000
	s_nop 0
	v_addc_co_u32_e32 v5, vcc, 0, v3, vcc
	v_add_co_u32_e32 v24, vcc, s90, v2
	s_lshl_b32 s88, s1, 2
	s_nop 0
	v_addc_co_u32_e32 v25, vcc, 0, v3, vcc
	v_add_co_u32_e32 v36, vcc, s70, v2
	s_lshl_b32 s38, s0, 5
	s_nop 0
	v_addc_co_u32_e32 v37, vcc, 0, v3, vcc
	v_add_co_u32_e32 v38, vcc, s71, v2
	s_lshl_b32 s0, s0, 6
	s_nop 0
	v_addc_co_u32_e32 v39, vcc, 0, v3, vcc
	v_add_co_u32_e32 v40, vcc, s4, v2
	s_mov_b32 s4, 0x21000
	s_nop 0
	v_addc_co_u32_e32 v41, vcc, 0, v3, vcc
	v_add_co_u32_e32 v42, vcc, s4, v2
	s_mov_b32 s4, 0x26000
	s_nop 0
	v_addc_co_u32_e32 v43, vcc, 0, v3, vcc
	v_add_co_u32_e32 v44, vcc, s4, v2
	s_mov_b32 s4, 0x2c000
	s_nop 0
	v_addc_co_u32_e32 v45, vcc, 0, v3, vcc
	global_load_dword v0, v[2:3], off
	global_load_dword v48, v[4:5], off offset:2048
	global_load_dword v49, v[24:25], off
	global_load_dword v50, v[36:37], off offset:2048
	global_load_dword v51, v[38:39], off
	global_load_dword v52, v[40:41], off offset:2048
	global_load_dword v53, v[42:43], off
	global_load_dword v54, v[44:45], off offset:2048
	v_add_co_u32_e32 v4, vcc, s4, v2
	s_mov_b32 s4, 0x31000
	s_nop 0
	v_addc_co_u32_e32 v5, vcc, 0, v3, vcc
	v_add_co_u32_e32 v24, vcc, s4, v2
	s_mov_b32 s4, 0x37000
	s_nop 0
	v_addc_co_u32_e32 v25, vcc, 0, v3, vcc
	v_add_co_u32_e32 v36, vcc, s4, v2
	s_mov_b32 s4, 0x3c000
	s_nop 0
	v_addc_co_u32_e32 v37, vcc, 0, v3, vcc
	v_add_co_u32_e32 v38, vcc, s4, v2
	s_mov_b32 s4, 0x42000
	s_nop 0
	v_addc_co_u32_e32 v39, vcc, 0, v3, vcc
	v_add_co_u32_e32 v40, vcc, s4, v2
	s_mov_b32 s4, 0x47000
	s_nop 0
	v_addc_co_u32_e32 v41, vcc, 0, v3, vcc
	v_add_co_u32_e32 v42, vcc, s4, v2
	s_mov_b32 s4, 0x4d000
	s_nop 0
	v_addc_co_u32_e32 v43, vcc, 0, v3, vcc
	v_add_co_u32_e32 v44, vcc, s4, v2
	s_mov_b32 s4, 0x52000
	s_nop 0
	v_addc_co_u32_e32 v45, vcc, 0, v3, vcc
	v_add_co_u32_e32 v46, vcc, s4, v2
	s_mov_b32 s4, 0x58000
	s_nop 0
	v_addc_co_u32_e32 v47, vcc, 0, v3, vcc
	global_load_dword v55, v[4:5], off
	global_load_dword v56, v[24:25], off offset:2048
	global_load_dword v57, v[36:37], off
	global_load_dword v58, v[38:39], off offset:2048
	global_load_dword v59, v[40:41], off
	global_load_dword v60, v[42:43], off offset:2048
	global_load_dword v61, v[44:45], off
	global_load_dword v62, v[46:47], off offset:2048
	v_add_co_u32_e32 v4, vcc, s4, v2
	s_mov_b32 s4, 0x5d000
	s_nop 0
	v_addc_co_u32_e32 v5, vcc, 0, v3, vcc
	v_add_co_u32_e32 v24, vcc, s4, v2
	s_mov_b32 s4, 0x63000
	s_nop 0
	v_addc_co_u32_e32 v25, vcc, 0, v3, vcc
	v_add_co_u32_e32 v36, vcc, s4, v2
	s_mov_b32 s4, 0x68000
	s_nop 0
	v_addc_co_u32_e32 v37, vcc, 0, v3, vcc
	v_add_co_u32_e32 v38, vcc, s4, v2
	s_mov_b32 s4, 0x6e000
	s_nop 0
	v_addc_co_u32_e32 v39, vcc, 0, v3, vcc
	v_add_co_u32_e32 v40, vcc, s4, v2
	s_mov_b32 s4, 0x73000
	s_nop 0
	v_addc_co_u32_e32 v41, vcc, 0, v3, vcc
	v_add_co_u32_e32 v42, vcc, s4, v2
	s_mov_b32 s4, 0x79000
	s_nop 0
	v_addc_co_u32_e32 v43, vcc, 0, v3, vcc
	v_add_co_u32_e32 v44, vcc, s4, v2
	s_mov_b32 s4, 0x7e000
	s_nop 0
	v_addc_co_u32_e32 v45, vcc, 0, v3, vcc
	v_add_co_u32_e32 v46, vcc, s4, v2
	s_mov_b32 s4, 0x84000
	s_nop 0
	v_addc_co_u32_e32 v47, vcc, 0, v3, vcc
	global_load_dword v63, v[4:5], off
	global_load_dword v64, v[24:25], off offset:2048
	global_load_dword v65, v[36:37], off
	global_load_dword v66, v[38:39], off offset:2048
	global_load_dword v67, v[40:41], off
	global_load_dword v68, v[42:43], off offset:2048
	global_load_dword v69, v[44:45], off
	s_nop 0
	global_load_dword v46, v[46:47], off offset:2048
	v_add_co_u32_e32 v4, vcc, s4, v2
	s_mov_b32 s4, 0x89000
	s_nop 0
	v_addc_co_u32_e32 v5, vcc, 0, v3, vcc
	v_add_co_u32_e32 v24, vcc, s4, v2
	s_mov_b32 s4, 0x8f000
	s_nop 0
	v_addc_co_u32_e32 v25, vcc, 0, v3, vcc
	v_add_co_u32_e32 v36, vcc, s4, v2
	s_mov_b32 s4, 0x94000
	s_nop 0
	v_addc_co_u32_e32 v37, vcc, 0, v3, vcc
	v_add_co_u32_e32 v38, vcc, s4, v2
	s_mov_b32 s4, 0x9a000
	s_nop 0
	v_addc_co_u32_e32 v39, vcc, 0, v3, vcc
	v_add_co_u32_e32 v40, vcc, s4, v2
	s_mov_b32 s4, 0x9f000
	s_nop 0
	v_addc_co_u32_e32 v41, vcc, 0, v3, vcc
	v_add_co_u32_e32 v42, vcc, s4, v2
	s_mov_b32 s4, 0xa5000
	s_nop 0
	v_addc_co_u32_e32 v43, vcc, 0, v3, vcc
	v_add_co_u32_e32 v44, vcc, s4, v2
	s_mov_b32 s4, 0xaa000
	s_nop 0
	v_addc_co_u32_e32 v45, vcc, 0, v3, vcc
	v_add_co_u32_e32 v2, vcc, s4, v2
	s_and_b32 s0, s0, 0x1f00
	s_nop 0
	v_addc_co_u32_e32 v3, vcc, 0, v3, vcc
	global_load_dword v47, v[4:5], off
	s_nop 0
	global_load_dword v24, v[24:25], off offset:2048
	s_nop 0
	global_load_dword v25, v[36:37], off
	global_load_dword v70, v[38:39], off offset:2048
	s_nop 0
	global_load_dword v40, v[40:41], off
	s_nop 0
	global_load_dword v41, v[42:43], off offset:2048
	s_nop 0
	global_load_dword v42, v[44:45], off
	global_load_dword v43, v[2:3], off offset:2048
	v_lshl_add_u64 v[2:3], v[22:23], 0, s[88:89]
	global_load_dwordx4 v[36:39], v[2:3], off
	s_nop 0
	global_load_dwordx4 v[2:5], v[2:3], off offset:16
	s_waitcnt vmcnt(32)
	ds_write2_b32 v30, v0, v48 offset1:66
	s_waitcnt vmcnt(30)
; #define LAS __attribute__((address_space(3)))
; __device__ __forceinline__ unsigned pk2(float lo, float hi) { return f2bf(lo) | (f2bf(hi) << 16); }
; #define LDS_WAVE_SYNC() asm volatile("s_waitcnt lgkmcnt(0)" ::: "memory")
; template <bool HASG>
; __device__ __forceinline__ void tr_item(const float* W, int K, int N, bf16* WT, int rowmode, const float* g, LAS float* scr, int item, int lane) {
;     ...
;     for (int i = 0; i < 32; ++i) scr[(2 * i + (lane >> 5)) * 33 + (lane & 31)] = v[i];
;     LDS_WAVE_SYNC();
;     const int drow0 = rowmode == 0 ? n0 : ((n0 >> 7) * 256 + (n0 & 127) + (rowmode == 2 ? 128 : 0));
; #pragma unroll
;     for (int j = 0; j < 4; ++j) { const int n = (lane >> 3) + 8 * j; const LAS float* s = scr + (8 * c) * 33 + n;
;         u32x4 o; o.x = pk2(s[0 * 33] * g0.x, s[1 * 33] * g0.y); o.y = pk2(s[2 * 33] * g0.z, s[3 * 33] * g0.w);
;         o.z = pk2(s[4 * 33] * g1.x, s[5 * 33] * g1.y); o.w = pk2(s[6 * 33] * g1.z, s[7 * 33] * g1.w);
;         *(u32x4*)(WT + (size_t)(drow0 + n) * K + k0 + 8 * c) = o; }
	ds_write2_b32 v30, v49, v50 offset0:132 offset1:198
	v_add_u32_e32 v0, 0x400, v30
	s_waitcnt vmcnt(28)
	ds_write2_b32 v0, v51, v52 offset0:8 offset1:74
	s_waitcnt vmcnt(26)
	ds_write2_b32 v0, v53, v54 offset0:140 offset1:206
	v_add_u32_e32 v0, 0x800, v30
	s_waitcnt vmcnt(24)
	ds_write2_b32 v0, v55, v56 offset0:16 offset1:82
	s_waitcnt vmcnt(22)
	ds_write2_b32 v0, v57, v58 offset0:148 offset1:214
	v_add_u32_e32 v0, 0xc00, v30
	s_waitcnt vmcnt(20)
	ds_write2_b32 v0, v59, v60 offset0:24 offset1:90
	s_waitcnt vmcnt(18)
	ds_write2_b32 v0, v61, v62 offset0:156 offset1:222
	v_add_u32_e32 v0, 0x1000, v30
	s_waitcnt vmcnt(16)
	ds_write2_b32 v0, v63, v64 offset0:32 offset1:98
	s_waitcnt vmcnt(14)
	ds_write2_b32 v0, v65, v66 offset0:164 offset1:230
	v_add_u32_e32 v0, 0x1400, v30
	s_waitcnt vmcnt(12)
	ds_write2_b32 v0, v67, v68 offset0:40 offset1:106
	s_waitcnt vmcnt(10)
	ds_write2_b32 v0, v69, v46 offset0:172 offset1:238
	v_add_u32_e32 v0, 0x1800, v30
	s_waitcnt vmcnt(8)
	ds_write2_b32 v0, v47, v24 offset0:48 offset1:114
	s_waitcnt vmcnt(6)
	ds_write2_b32 v0, v25, v70 offset0:180 offset1:246
	v_add_u32_e32 v0, 0x1c00, v30
	s_waitcnt vmcnt(4)
	ds_write2_b32 v0, v40, v41 offset0:56 offset1:122
	s_waitcnt vmcnt(2)
	ds_write2_b32 v0, v42, v43 offset0:188 offset1:254
	s_waitcnt lgkmcnt(0)
	ds_read2_b32 v[44:45], v31 offset0:33 offset1:41
	ds_read2_b32 v[46:47], v31 offset1:8
	ds_read2_b32 v[48:49], v31 offset0:66 offset1:74
	ds_read2_b32 v[50:51], v31 offset0:99 offset1:107
	ds_read2_b32 v[54:55], v31 offset0:132 offset1:140
	ds_read2_b32 v[56:57], v31 offset0:165 offset1:173
	ds_read2_b32 v[58:59], v31 offset0:198 offset1:206
	ds_read2_b32 v[60:61], v31 offset0:231 offset1:239
	s_waitcnt vmcnt(1)
	v_mov_b32_e32 v52, v36
	v_mov_b32_e32 v53, v38
	v_mov_b32_e32 v38, v37
	s_waitcnt lgkmcnt(7)
	v_mov_b32_e32 v36, v44
	s_waitcnt lgkmcnt(4)
	v_mov_b32_e32 v37, v50
	s_waitcnt vmcnt(0)
	v_mov_b32_e32 v62, v2
	v_mov_b32_e32 v63, v4
	v_mov_b32_e32 v4, v3
	s_waitcnt lgkmcnt(2)
	v_mov_b32_e32 v2, v56
	s_waitcnt lgkmcnt(0)
	v_mov_b32_e32 v3, v60
	v_mov_b32_e32 v40, v46
	v_mov_b32_e32 v41, v48
	v_pk_mul_f32 v[36:37], v[38:39], v[36:37]
	v_mov_b32_e32 v42, v54
	v_mov_b32_e32 v43, v58
	v_pk_mul_f32 v[2:3], v[4:5], v[2:3]
	v_pk_mul_f32 v[40:41], v[52:53], v[40:41]
	v_pk_mul_f32 v[42:43], v[62:63], v[42:43]
	v_bfe_u32 v44, v2, 16, 1
	v_bfe_u32 v46, v37, 16, 1
	v_bfe_u32 v48, v36, 16, 1
	s_and_b32 s38, s38, 0x60
	v_bfe_u32 v0, v3, 16, 1
	v_add3_u32 v36, v36, v48, s91
	v_add3_u32 v37, v37, v46, s91
	v_add3_u32 v2, v2, v44, s91
	v_bfe_u32 v44, v41, 16, 1
	v_bfe_u32 v46, v42, 16, 1
	v_bfe_u32 v48, v43, 16, 1
	s_or_b32 s0, s38, s0
	v_add3_u32 v0, v3, v0, s91
	v_bfe_u32 v3, v40, 16, 1
	v_add3_u32 v43, v43, v48, s91
	v_add3_u32 v42, v42, v46, s91
	v_add3_u32 v41, v41, v44, s91
	s_bitset1_b32 s0, 7
	v_add3_u32 v3, v40, v3, s91
	v_lshrrev_b32_e32 v40, 16, v41
	v_lshrrev_b32_e32 v41, 16, v42
	v_lshrrev_b32_e32 v42, 16, v43
	s_lshl_b32 s88, s1, 1
	v_and_or_b32 v43, v0, s35, v42
	v_or_b32_e32 v0, s0, v7
	v_lshl_add_u64 v[24:25], v[16:17], 0, s[88:89]
	v_lshrrev_b32_e32 v3, 16, v3
	v_lshlrev_b32_e32 v0, 11, v0
	v_mov_b32_e32 v50, v45
	v_and_or_b32 v42, v2, s35, v41
	v_and_or_b32 v41, v37, s35, v40
	v_and_or_b32 v40, v36, s35, v3
	v_lshl_add_u64 v[2:3], v[24:25], 0, v[0:1]
	v_pk_mul_f32 v[36:37], v[38:39], v[50:51]
	v_mov_b32_e32 v58, v55
	global_store_dwordx4 v[2:3], v[40:43], off sc1
	v_mov_b32_e32 v60, v57
	v_bfe_u32 v46, v36, 16, 1
	v_pk_mul_f32 v[40:41], v[62:63], v[58:59]
	v_mov_b32_e32 v48, v47
	v_pk_mul_f32 v[42:43], v[4:5], v[60:61]
	v_add3_u32 v36, v36, v46, s91
	v_bfe_u32 v46, v41, 16, 1
	v_pk_mul_f32 v[2:3], v[52:53], v[48:49]
	v_bfe_u32 v0, v43, 16, 1
	v_bfe_u32 v44, v42, 16, 1
	v_bfe_u32 v45, v37, 16, 1
	v_add3_u32 v41, v41, v46, s91
	v_add3_u32 v37, v37, v45, s91
	v_add3_u32 v42, v42, v44, s91
	v_add3_u32 v0, v43, v0, s91
	v_bfe_u32 v43, v2, 16, 1
	v_bfe_u32 v44, v3, 16, 1
	v_bfe_u32 v45, v40, 16, 1
	v_lshrrev_b32_e32 v41, 16, v41
	v_add3_u32 v40, v40, v45, s91
	v_add3_u32 v3, v3, v44, s91
	v_add3_u32 v2, v2, v43, s91
	v_and_or_b32 v43, v0, s35, v41
	v_or_b32_e32 v0, s0, v32
	v_lshrrev_b32_e32 v2, 16, v2
	v_lshrrev_b32_e32 v3, 16, v3
	v_lshrrev_b32_e32 v40, 16, v40
	v_lshlrev_b32_e32 v0, 11, v0
	v_and_or_b32 v42, v42, s35, v40
	v_and_or_b32 v41, v37, s35, v3
	v_and_or_b32 v40, v36, s35, v2
	v_lshl_add_u64 v[2:3], v[24:25], 0, v[0:1]
	ds_read2_b32 v[36:37], v31 offset0:16 offset1:24
	ds_read2_b32 v[44:45], v31 offset0:82 offset1:90
	global_store_dwordx4 v[2:3], v[40:43], off sc1
	ds_read2_b32 v[2:3], v31 offset0:49 offset1:57
	ds_read2_b32 v[46:47], v31 offset0:115 offset1:123
	ds_read2_b32 v[48:49], v31 offset0:148 offset1:156
	ds_read2_b32 v[50:51], v31 offset0:214 offset1:222
	ds_read2_b32 v[54:55], v31 offset0:181 offset1:189
	ds_read2_b32 v[56:57], v31 offset0:247 offset1:255
	s_waitcnt lgkmcnt(7)
; #define LAS __attribute__((address_space(3)))
; __device__ __forceinline__ unsigned pk2(float lo, float hi) { return f2bf(lo) | (f2bf(hi) << 16); }
; #define LDS_WAVE_SYNC() asm volatile("s_waitcnt lgkmcnt(0)" ::: "memory")
; template <bool HASG>
; __device__ __forceinline__ void tr_item(const float* W, int K, int N, bf16* WT, int rowmode, const float* g, LAS float* scr, int item, int lane) {
;     ...
;     for (int j = 0; j < 4; ++j) { const int n = (lane >> 3) + 8 * j; const LAS float* s = scr + (8 * c) * 33 + n;
;         u32x4 o; o.x = pk2(s[0 * 33] * g0.x, s[1 * 33] * g0.y); o.y = pk2(s[2 * 33] * g0.z, s[3 * 33] * g0.w);
;         o.z = pk2(s[4 * 33] * g1.x, s[5 * 33] * g1.y); o.w = pk2(s[6 * 33] * g1.z, s[7 * 33] * g1.w);
;         *(u32x4*)(WT + (size_t)(drow0 + n) * K + k0 + 8 * c) = o; }
;     LDS_WAVE_SYNC();
	v_mov_b32_e32 v40, v36
	s_waitcnt lgkmcnt(5)
	v_mov_b32_e32 v42, v2
	s_waitcnt lgkmcnt(4)
	v_mov_b32_e32 v43, v46
	s_waitcnt lgkmcnt(3)
	v_mov_b32_e32 v58, v48
	s_waitcnt lgkmcnt(2)
	v_mov_b32_e32 v59, v50
	v_mov_b32_e32 v41, v44
	v_pk_mul_f32 v[42:43], v[38:39], v[42:43]
	v_pk_mul_f32 v[58:59], v[62:63], v[58:59]
	s_waitcnt lgkmcnt(1)
	v_mov_b32_e32 v60, v54
	s_waitcnt lgkmcnt(0)
	v_mov_b32_e32 v61, v56
	v_pk_mul_f32 v[40:41], v[52:53], v[40:41]
	v_pk_mul_f32 v[60:61], v[4:5], v[60:61]
	v_bfe_u32 v36, v43, 16, 1
	v_bfe_u32 v48, v59, 16, 1
	v_bfe_u32 v0, v61, 16, 1
	v_bfe_u32 v44, v42, 16, 1
	v_add3_u32 v36, v43, v36, s91
	v_bfe_u32 v43, v41, 16, 1
	v_add3_u32 v48, v59, v48, s91
	v_add3_u32 v44, v42, v44, s91
	v_add3_u32 v0, v61, v0, s91
	v_bfe_u32 v42, v40, 16, 1
	v_bfe_u32 v46, v58, 16, 1
	v_add3_u32 v41, v41, v43, s91
	v_lshrrev_b32_e32 v43, 16, v48
	v_bfe_u32 v2, v60, 16, 1
	v_add3_u32 v46, v58, v46, s91
	v_add3_u32 v40, v40, v42, s91
	v_and_or_b32 v43, v0, s35, v43
	v_or_b32_e32 v0, s0, v34
	v_add3_u32 v2, v60, v2, s91
	v_lshrrev_b32_e32 v40, 16, v40
	v_lshrrev_b32_e32 v41, 16, v41
	v_lshrrev_b32_e32 v42, 16, v46
	v_lshlrev_b32_e32 v0, 11, v0
	v_mov_b32_e32 v46, v3
	v_mov_b32_e32 v56, v55
	v_and_or_b32 v42, v2, s35, v42
	v_and_or_b32 v41, v36, s35, v41
	v_and_or_b32 v40, v44, s35, v40
	v_lshl_add_u64 v[58:59], v[24:25], 0, v[0:1]
	v_mov_b32_e32 v44, v37
	v_pk_mul_f32 v[2:3], v[38:39], v[46:47]
	v_mov_b32_e32 v50, v49
	v_pk_mul_f32 v[4:5], v[4:5], v[56:57]
	global_store_dwordx4 v[58:59], v[40:43], off sc1
	v_pk_mul_f32 v[36:37], v[52:53], v[44:45]
	v_pk_mul_f32 v[38:39], v[62:63], v[50:51]
	v_bfe_u32 v0, v5, 16, 1
	v_bfe_u32 v42, v2, 16, 1
	v_add3_u32 v2, v2, v42, s91
	v_add3_u32 v0, v5, v0, s91
	v_bfe_u32 v5, v36, 16, 1
	v_bfe_u32 v42, v39, 16, 1
	v_bfe_u32 v40, v4, 16, 1
	v_bfe_u32 v41, v3, 16, 1
	v_add3_u32 v39, v39, v42, s91
	v_add3_u32 v5, v36, v5, s91
	v_add3_u32 v3, v3, v41, s91
	v_add3_u32 v4, v4, v40, s91
	v_bfe_u32 v40, v37, 16, 1
	v_bfe_u32 v41, v38, 16, 1
	v_lshrrev_b32_e32 v36, 16, v5
	v_lshrrev_b32_e32 v5, 16, v39
	v_add3_u32 v38, v38, v41, s91
	v_add3_u32 v37, v37, v40, s91
	v_and_or_b32 v5, v0, s35, v5
	v_or_b32_e32 v0, s0, v35
	v_lshrrev_b32_e32 v37, 16, v37
	v_lshrrev_b32_e32 v38, 16, v38
	v_lshlrev_b32_e32 v0, 11, v0
	v_and_or_b32 v4, v4, s35, v38
	v_and_or_b32 v3, v3, s35, v37
	v_and_or_b32 v2, v2, s35, v36
	v_lshl_add_u64 v[24:25], v[24:25], 0, v[0:1]
	global_store_dwordx4 v[24:25], v[2:5], off sc1
	s_waitcnt lgkmcnt(0)
	v_readlane_b32 s8, v252, 4
	v_readlane_b32 s9, v252, 5
	s_mov_b64 s[8:9], s[26:27]
	v_readlane_b32 s5, v252, 1
	v_readlane_b32 s6, v252, 2
	v_readlane_b32 s7, v252, 3
	v_readlane_b32 s12, v252, 8
	v_readlane_b32 s13, v252, 9
	v_readlane_b32 s14, v252, 10
	v_readlane_b32 s15, v252, 11
	v_readlane_b32 s16, v252, 12
	v_readlane_b32 s17, v252, 13
	v_readlane_b32 s18, v252, 14
	v_readlane_b32 s19, v252, 15

; template <bool HASG>
; __device__ __forceinline__ void tr_item(const float* W, int K, int N, bf16* WT, int rowmode, const float* g, LAS float* scr, int item, int lane) {
;     const int nblk = N / 32, kb = item / nblk, nb = item % nblk, k0 = 64 * kb, n0 = 32 * nb;
;     const float* wp = W + (size_t)(k0 + (lane >> 5)) * N + n0 + (lane & 31);
;     const int c = lane & 7;
;     float v[32];
; #pragma unroll
;     for (int i = 0; i < 32; ++i) v[i] = wp[(size_t)(2 * i) * N];
;     f32x4 g0 = (f32x4){1.f, 1.f, 1.f, 1.f}, g1 = g0;
;     if (HASG) { g0 = *(const f32x4*)(g + k0 + 8 * c); g1 = *(const f32x4*)(g + k0 + 8 * c + 4); }
;     asm volatile("" ::: "memory");
; #pragma unroll
;     for (int i = 0; i < 32; ++i) scr[(2 * i + (lane >> 5)) * 33 + (lane & 31)] = v[i];
; __device__ __forceinline__ void convert_items(const Args& a, LAS unsigned char* lds, int l, int it_lo, int it_hi, int gw, int NGW, int wave, int lane) {
;     ...
;         if (r < I_G) { tr_item<true>(a.in[2] + o_gu, D, FF, wl + W_GU1, 1, a.in[1] + l * D, scr, r, lane); continue; } r -= I_G;
.LBB0_567:
	s_andn2_b64 vcc, exec, s[0:1]
	s_cbranch_vccnz .LBB0_544
	s_mul_hi_i32 s0, s46, 0x2e8ba2e9
	s_lshr_b32 s1, s0, 31
	s_ashr_i32 s45, s0, 4
	s_add_i32 s45, s45, s1
	v_readlane_b32 s4, v252, 0
	s_lshl_b32 s0, s45, 6
	s_mul_i32 s1, s45, 0xfffff500
	v_readlane_b32 s8, v252, 4
	v_readlane_b32 s9, v252, 5
	s_add_i32 s38, s28, s1
	v_or_b32_e32 v0, s0, v33
	v_mov_b64_e32 v[2:3], s[8:9]
	s_movk_i32 s1, 0x2c00
	v_mad_i64_i32 v[2:3], s[60:61], v0, s1, v[2:3]
	s_ashr_i32 s39, s38, 31
	v_lshl_add_u64 v[2:3], s[38:39], 2, v[2:3]
	v_lshlrev_b32_e32 v0, 2, v6
	v_lshl_add_u64 v[2:3], v[2:3], 0, v[0:1]
	s_movk_i32 s1, 0x5000
	v_add_co_u32_e32 v4, vcc, s1, v2
	s_mov_b32 s1, 0x1b000
	s_nop 0
	v_addc_co_u32_e32 v5, vcc, 0, v3, vcc
	v_add_co_u32_e32 v24, vcc, s90, v2
	s_mulk_i32 s45, 0xea00
	s_nop 0
	v_addc_co_u32_e32 v25, vcc, 0, v3, vcc
	v_add_co_u32_e32 v36, vcc, s70, v2
	s_add_i32 s39, s41, s45
	s_nop 0
	v_addc_co_u32_e32 v37, vcc, 0, v3, vcc
	v_add_co_u32_e32 v38, vcc, s71, v2
	s_and_b32 s39, s39, 0xffffff00
	s_nop 0
	v_addc_co_u32_e32 v39, vcc, 0, v3, vcc
	v_add_co_u32_e32 v40, vcc, s1, v2
	s_mov_b32 s1, 0x21000
	s_nop 0
	v_addc_co_u32_e32 v41, vcc, 0, v3, vcc
	v_add_co_u32_e32 v42, vcc, s1, v2
	s_mov_b32 s1, 0x26000
	s_nop 0
	v_addc_co_u32_e32 v43, vcc, 0, v3, vcc
	v_add_co_u32_e32 v44, vcc, s1, v2
	s_mov_b32 s1, 0x2c000
	s_nop 0
	v_addc_co_u32_e32 v45, vcc, 0, v3, vcc
	global_load_dword v0, v[2:3], off
	global_load_dword v48, v[4:5], off offset:2048
	global_load_dword v49, v[24:25], off
	global_load_dword v50, v[36:37], off offset:2048
	global_load_dword v51, v[38:39], off
	global_load_dword v52, v[40:41], off offset:2048
	global_load_dword v53, v[42:43], off
	global_load_dword v54, v[44:45], off offset:2048
	v_add_co_u32_e32 v4, vcc, s1, v2
	s_mov_b32 s1, 0x31000
	s_nop 0
	v_addc_co_u32_e32 v5, vcc, 0, v3, vcc
	v_add_co_u32_e32 v24, vcc, s1, v2
	s_mov_b32 s1, 0x37000
	s_nop 0
	v_addc_co_u32_e32 v25, vcc, 0, v3, vcc
	v_add_co_u32_e32 v36, vcc, s1, v2
	s_mov_b32 s1, 0x3c000
	s_nop 0
	v_addc_co_u32_e32 v37, vcc, 0, v3, vcc
	v_add_co_u32_e32 v38, vcc, s1, v2
	s_mov_b32 s1, 0x42000
	s_nop 0
	v_addc_co_u32_e32 v39, vcc, 0, v3, vcc
	v_add_co_u32_e32 v40, vcc, s1, v2
	s_mov_b32 s1, 0x47000
	s_nop 0
	v_addc_co_u32_e32 v41, vcc, 0, v3, vcc
	v_add_co_u32_e32 v42, vcc, s1, v2
	s_mov_b32 s1, 0x4d000
	s_nop 0
	v_addc_co_u32_e32 v43, vcc, 0, v3, vcc
	v_add_co_u32_e32 v44, vcc, s1, v2
	s_mov_b32 s1, 0x52000
	s_nop 0
	v_addc_co_u32_e32 v45, vcc, 0, v3, vcc
	v_add_co_u32_e32 v46, vcc, s1, v2
	s_mov_b32 s1, 0x58000
	s_nop 0
	v_addc_co_u32_e32 v47, vcc, 0, v3, vcc
	global_load_dword v55, v[4:5], off
	global_load_dword v56, v[24:25], off offset:2048
	global_load_dword v57, v[36:37], off
	global_load_dword v58, v[38:39], off offset:2048
	global_load_dword v59, v[40:41], off
	global_load_dword v60, v[42:43], off offset:2048
	global_load_dword v61, v[44:45], off
	global_load_dword v62, v[46:47], off offset:2048
	v_add_co_u32_e32 v4, vcc, s1, v2
	s_mov_b32 s1, 0x5d000
	s_nop 0
	v_addc_co_u32_e32 v5, vcc, 0, v3, vcc
	v_add_co_u32_e32 v24, vcc, s1, v2
	s_mov_b32 s1, 0x63000
	s_nop 0
	v_addc_co_u32_e32 v25, vcc, 0, v3, vcc
	v_add_co_u32_e32 v36, vcc, s1, v2
	s_mov_b32 s1, 0x68000
	s_nop 0
	v_addc_co_u32_e32 v37, vcc, 0, v3, vcc
	v_add_co_u32_e32 v38, vcc, s1, v2
	s_mov_b32 s1, 0x6e000
	s_nop 0
	v_addc_co_u32_e32 v39, vcc, 0, v3, vcc
	v_add_co_u32_e32 v40, vcc, s1, v2
	s_mov_b32 s1, 0x73000
	s_nop 0
	v_addc_co_u32_e32 v41, vcc, 0, v3, vcc
	v_add_co_u32_e32 v42, vcc, s1, v2
	s_mov_b32 s1, 0x79000
	s_nop 0
	v_addc_co_u32_e32 v43, vcc, 0, v3, vcc
	v_add_co_u32_e32 v44, vcc, s1, v2
	s_mov_b32 s1, 0x7e000
	s_nop 0
	v_addc_co_u32_e32 v45, vcc, 0, v3, vcc
	v_add_co_u32_e32 v46, vcc, s1, v2
	s_mov_b32 s1, 0x84000
	s_nop 0
	v_addc_co_u32_e32 v47, vcc, 0, v3, vcc
	global_load_dword v63, v[4:5], off
	global_load_dword v64, v[24:25], off offset:2048
	global_load_dword v65, v[36:37], off
	global_load_dword v66, v[38:39], off offset:2048
	global_load_dword v67, v[40:41], off
	global_load_dword v68, v[42:43], off offset:2048
	global_load_dword v69, v[44:45], off
	s_nop 0
	global_load_dword v46, v[46:47], off offset:2048
	v_add_co_u32_e32 v4, vcc, s1, v2
	s_mov_b32 s1, 0x89000
	s_nop 0
	v_addc_co_u32_e32 v5, vcc, 0, v3, vcc
	v_add_co_u32_e32 v24, vcc, s1, v2
	s_mov_b32 s1, 0x8f000
	s_nop 0
	v_addc_co_u32_e32 v25, vcc, 0, v3, vcc
	v_add_co_u32_e32 v36, vcc, s1, v2
	s_mov_b32 s1, 0x94000
	s_nop 0
	v_addc_co_u32_e32 v37, vcc, 0, v3, vcc
	v_add_co_u32_e32 v38, vcc, s1, v2
	s_mov_b32 s1, 0x9a000
	s_nop 0
	v_addc_co_u32_e32 v39, vcc, 0, v3, vcc
	v_add_co_u32_e32 v40, vcc, s1, v2
	s_mov_b32 s1, 0x9f000
	s_nop 0
	v_addc_co_u32_e32 v41, vcc, 0, v3, vcc
	v_add_co_u32_e32 v42, vcc, s1, v2
	s_mov_b32 s1, 0xa5000
	s_nop 0
	v_addc_co_u32_e32 v43, vcc, 0, v3, vcc
	v_add_co_u32_e32 v44, vcc, s1, v2
	s_mov_b32 s1, 0xaa000
	s_nop 0
	v_addc_co_u32_e32 v45, vcc, 0, v3, vcc
	v_add_co_u32_e32 v2, vcc, s1, v2
	s_ashr_i32 s1, s0, 31
	s_nop 0
	v_addc_co_u32_e32 v3, vcc, 0, v3, vcc
	global_load_dword v47, v[4:5], off
	s_nop 0
	global_load_dword v24, v[24:25], off offset:2048
	s_nop 0
	global_load_dword v25, v[36:37], off
	global_load_dword v70, v[38:39], off offset:2048
	s_nop 0
	global_load_dword v40, v[40:41], off
	s_nop 0
	global_load_dword v41, v[42:43], off offset:2048
	s_nop 0
	global_load_dword v42, v[44:45], off
	global_load_dword v43, v[2:3], off offset:2048
	v_lshl_add_u64 v[2:3], s[0:1], 2, v[22:23]
	global_load_dwordx4 v[36:39], v[2:3], off
	s_nop 0
	global_load_dwordx4 v[2:5], v[2:3], off offset:16
	s_waitcnt vmcnt(32)
	ds_write2_b32 v30, v0, v48 offset1:66
	s_waitcnt vmcnt(30)
; #define LAS __attribute__((address_space(3)))
; __device__ __forceinline__ unsigned pk2(float lo, float hi) { return f2bf(lo) | (f2bf(hi) << 16); }
; #define LDS_WAVE_SYNC() asm volatile("s_waitcnt lgkmcnt(0)" ::: "memory")
; template <bool HASG>
; __device__ __forceinline__ void tr_item(const float* W, int K, int N, bf16* WT, int rowmode, const float* g, LAS float* scr, int item, int lane) {
;     ...
;     for (int i = 0; i < 32; ++i) scr[(2 * i + (lane >> 5)) * 33 + (lane & 31)] = v[i];
;     LDS_WAVE_SYNC();
;     const int drow0 = rowmode == 0 ? n0 : ((n0 >> 7) * 256 + (n0 & 127) + (rowmode == 2 ? 128 : 0));
; #pragma unroll
;     for (int j = 0; j < 4; ++j) { const int n = (lane >> 3) + 8 * j; const LAS float* s = scr + (8 * c) * 33 + n;
;         u32x4 o; o.x = pk2(s[0 * 33] * g0.x, s[1 * 33] * g0.y); o.y = pk2(s[2 * 33] * g0.z, s[3 * 33] * g0.w);
;         o.z = pk2(s[4 * 33] * g1.x, s[5 * 33] * g1.y); o.w = pk2(s[6 * 33] * g1.z, s[7 * 33] * g1.w);
;         *(u32x4*)(WT + (size_t)(drow0 + n) * K + k0 + 8 * c) = o; }
	ds_write2_b32 v30, v49, v50 offset0:132 offset1:198
	v_add_u32_e32 v0, 0x400, v30
	s_waitcnt vmcnt(28)
	ds_write2_b32 v0, v51, v52 offset0:8 offset1:74
	s_waitcnt vmcnt(26)
	ds_write2_b32 v0, v53, v54 offset0:140 offset1:206
	v_add_u32_e32 v0, 0x800, v30
	s_waitcnt vmcnt(24)
	ds_write2_b32 v0, v55, v56 offset0:16 offset1:82
	s_waitcnt vmcnt(22)
	ds_write2_b32 v0, v57, v58 offset0:148 offset1:214
	v_add_u32_e32 v0, 0xc00, v30
	s_waitcnt vmcnt(20)
	ds_write2_b32 v0, v59, v60 offset0:24 offset1:90
	s_waitcnt vmcnt(18)
	ds_write2_b32 v0, v61, v62 offset0:156 offset1:222
	v_add_u32_e32 v0, 0x1000, v30
	s_waitcnt vmcnt(16)
	ds_write2_b32 v0, v63, v64 offset0:32 offset1:98
	s_waitcnt vmcnt(14)
	ds_write2_b32 v0, v65, v66 offset0:164 offset1:230
	v_add_u32_e32 v0, 0x1400, v30
	s_waitcnt vmcnt(12)
	ds_write2_b32 v0, v67, v68 offset0:40 offset1:106
	s_waitcnt vmcnt(10)
	ds_write2_b32 v0, v69, v46 offset0:172 offset1:238
	v_add_u32_e32 v0, 0x1800, v30
	s_waitcnt vmcnt(8)
	ds_write2_b32 v0, v47, v24 offset0:48 offset1:114
	s_waitcnt vmcnt(6)
	ds_write2_b32 v0, v25, v70 offset0:180 offset1:246
	v_add_u32_e32 v0, 0x1c00, v30
	s_waitcnt vmcnt(4)
	ds_write2_b32 v0, v40, v41 offset0:56 offset1:122
	s_waitcnt vmcnt(2)
	ds_write2_b32 v0, v42, v43 offset0:188 offset1:254
	s_waitcnt lgkmcnt(0)
	ds_read2_b32 v[44:45], v31 offset0:33 offset1:41
	ds_read2_b32 v[46:47], v31 offset1:8
	ds_read2_b32 v[48:49], v31 offset0:66 offset1:74
	ds_read2_b32 v[50:51], v31 offset0:99 offset1:107
	ds_read2_b32 v[54:55], v31 offset0:132 offset1:140
	ds_read2_b32 v[56:57], v31 offset0:165 offset1:173
	ds_read2_b32 v[58:59], v31 offset0:198 offset1:206
	ds_read2_b32 v[60:61], v31 offset0:231 offset1:239
	s_waitcnt vmcnt(1)
	v_mov_b32_e32 v52, v36
	v_mov_b32_e32 v53, v38
	v_mov_b32_e32 v38, v37
	s_waitcnt lgkmcnt(7)
	v_mov_b32_e32 v36, v44
	s_waitcnt lgkmcnt(4)
	v_mov_b32_e32 v37, v50
	s_waitcnt vmcnt(0)
	v_mov_b32_e32 v62, v2
	v_mov_b32_e32 v63, v4
	v_mov_b32_e32 v4, v3
	s_waitcnt lgkmcnt(2)
	v_mov_b32_e32 v2, v56
	s_waitcnt lgkmcnt(0)
	v_mov_b32_e32 v3, v60
	v_mov_b32_e32 v40, v46
	v_mov_b32_e32 v41, v48
	v_pk_mul_f32 v[36:37], v[38:39], v[36:37]
	v_mov_b32_e32 v42, v54
	v_mov_b32_e32 v43, v58
	v_pk_mul_f32 v[2:3], v[4:5], v[2:3]
	v_pk_mul_f32 v[40:41], v[52:53], v[40:41]
	v_pk_mul_f32 v[42:43], v[62:63], v[42:43]
	v_bfe_u32 v44, v2, 16, 1
	v_bfe_u32 v46, v37, 16, 1
	v_bfe_u32 v48, v36, 16, 1
	v_bfe_u32 v0, v3, 16, 1
	v_add3_u32 v36, v36, v48, s91
	v_add3_u32 v37, v37, v46, s91
	v_add3_u32 v2, v2, v44, s91
	v_bfe_u32 v44, v41, 16, 1
	v_bfe_u32 v46, v42, 16, 1
	v_bfe_u32 v48, v43, 16, 1
	s_and_b32 s38, s38, 0x60
	v_add3_u32 v0, v3, v0, s91
	v_bfe_u32 v3, v40, 16, 1
	v_add3_u32 v43, v43, v48, s91
	v_add3_u32 v42, v42, v46, s91
	v_add3_u32 v41, v41, v44, s91
	s_or_b32 s38, s38, s39
	v_add3_u32 v3, v40, v3, s91
	v_lshrrev_b32_e32 v40, 16, v41
	v_lshrrev_b32_e32 v41, 16, v42
	v_lshrrev_b32_e32 v42, 16, v43
	v_lshrrev_b32_e32 v3, 16, v3
	v_and_or_b32 v43, v0, s35, v42
	v_and_or_b32 v42, v2, s35, v41
	v_or_b32_e32 v2, s38, v7
	v_and_or_b32 v41, v37, s35, v40
	v_and_or_b32 v40, v36, s35, v3
	v_ashrrev_i32_e32 v3, 31, v2
	v_lshl_add_u64 v[24:25], s[0:1], 1, v[16:17]
	v_lshlrev_b64 v[2:3], 11, v[2:3]
	v_lshl_add_u64 v[2:3], v[24:25], 0, v[2:3]
	v_mov_b32_e32 v50, v45
	v_mov_b32_e32 v60, v57
	global_store_dwordx4 v[2:3], v[40:43], off sc1
	v_mov_b32_e32 v48, v47
	v_pk_mul_f32 v[36:37], v[38:39], v[50:51]
	v_mov_b32_e32 v58, v55
	v_pk_mul_f32 v[42:43], v[4:5], v[60:61]
	v_pk_mul_f32 v[2:3], v[52:53], v[48:49]
	v_pk_mul_f32 v[40:41], v[62:63], v[58:59]
	v_bfe_u32 v0, v43, 16, 1
	v_bfe_u32 v45, v37, 16, 1
	v_bfe_u32 v44, v42, 16, 1
	v_bfe_u32 v46, v36, 16, 1
	v_add3_u32 v37, v37, v45, s91
	v_add3_u32 v0, v43, v0, s91
	v_bfe_u32 v43, v2, 16, 1
	v_bfe_u32 v45, v40, 16, 1
	v_add3_u32 v36, v36, v46, s91
	v_add3_u32 v42, v42, v44, s91
	v_bfe_u32 v44, v3, 16, 1
	v_bfe_u32 v46, v41, 16, 1
	v_add3_u32 v40, v40, v45, s91
	v_add3_u32 v2, v2, v43, s91
	v_add3_u32 v41, v41, v46, s91
	v_add3_u32 v3, v3, v44, s91
	v_lshrrev_b32_e32 v2, 16, v2
	v_lshrrev_b32_e32 v40, 16, v40
	v_lshrrev_b32_e32 v3, 16, v3
	v_lshrrev_b32_e32 v41, 16, v41
	v_and_or_b32 v42, v42, s35, v40
	v_and_or_b32 v40, v36, s35, v2
	v_or_b32_e32 v2, s38, v32
	v_and_or_b32 v43, v0, s35, v41
	v_and_or_b32 v41, v37, s35, v3
	v_ashrrev_i32_e32 v3, 31, v2
	v_lshlrev_b64 v[2:3], 11, v[2:3]
	v_lshl_add_u64 v[2:3], v[24:25], 0, v[2:3]
	ds_read2_b32 v[36:37], v31 offset0:16 offset1:24
	ds_read2_b32 v[44:45], v31 offset0:82 offset1:90
	global_store_dwordx4 v[2:3], v[40:43], off sc1
	ds_read2_b32 v[2:3], v31 offset0:49 offset1:57
	ds_read2_b32 v[46:47], v31 offset0:115 offset1:123
	ds_read2_b32 v[48:49], v31 offset0:148 offset1:156
	ds_read2_b32 v[50:51], v31 offset0:214 offset1:222
	ds_read2_b32 v[54:55], v31 offset0:181 offset1:189
	ds_read2_b32 v[56:57], v31 offset0:247 offset1:255
	s_waitcnt lgkmcnt(7)
; #define LAS __attribute__((address_space(3)))
; __device__ __forceinline__ unsigned pk2(float lo, float hi) { return f2bf(lo) | (f2bf(hi) << 16); }
; #define LDS_WAVE_SYNC() asm volatile("s_waitcnt lgkmcnt(0)" ::: "memory")
; template <bool HASG>
; __device__ __forceinline__ void tr_item(const float* W, int K, int N, bf16* WT, int rowmode, const float* g, LAS float* scr, int item, int lane) {
;     ...
;     for (int j = 0; j < 4; ++j) { const int n = (lane >> 3) + 8 * j; const LAS float* s = scr + (8 * c) * 33 + n;
;         u32x4 o; o.x = pk2(s[0 * 33] * g0.x, s[1 * 33] * g0.y); o.y = pk2(s[2 * 33] * g0.z, s[3 * 33] * g0.w);
;         o.z = pk2(s[4 * 33] * g1.x, s[5 * 33] * g1.y); o.w = pk2(s[6 * 33] * g1.z, s[7 * 33] * g1.w);
;         *(u32x4*)(WT + (size_t)(drow0 + n) * K + k0 + 8 * c) = o; }
;     LDS_WAVE_SYNC();
; __device__ __forceinline__ void convert_items(const Args& a, LAS unsigned char* lds, int l, int it_lo, int it_hi, int gw, int NGW, int wave, int lane) {
;     ...
;     for (int it = it_lo + gw; it < it_hi; it += NGW) {
	v_mov_b32_e32 v40, v36
	s_waitcnt lgkmcnt(5)
	v_mov_b32_e32 v42, v2
	s_waitcnt lgkmcnt(4)
	v_mov_b32_e32 v43, v46
	v_mov_b32_e32 v41, v44
	v_pk_mul_f32 v[42:43], v[38:39], v[42:43]
	s_waitcnt lgkmcnt(3)
	v_mov_b32_e32 v58, v48
	s_waitcnt lgkmcnt(2)
	v_mov_b32_e32 v59, v50
	v_pk_mul_f32 v[40:41], v[52:53], v[40:41]
	v_pk_mul_f32 v[58:59], v[62:63], v[58:59]
	v_bfe_u32 v44, v42, 16, 1
	s_waitcnt lgkmcnt(1)
	v_mov_b32_e32 v60, v54
	s_waitcnt lgkmcnt(0)
	v_mov_b32_e32 v61, v56
	v_bfe_u32 v36, v43, 16, 1
	v_add3_u32 v44, v42, v44, s91
	v_bfe_u32 v42, v40, 16, 1
	v_bfe_u32 v46, v58, 16, 1
	v_pk_mul_f32 v[60:61], v[4:5], v[60:61]
	v_add3_u32 v36, v43, v36, s91
	v_bfe_u32 v43, v41, 16, 1
	v_bfe_u32 v48, v59, 16, 1
	v_add3_u32 v46, v58, v46, s91
	v_add3_u32 v40, v40, v42, s91
	v_or_b32_e32 v58, s38, v34
	v_bfe_u32 v0, v61, 16, 1
	v_bfe_u32 v2, v60, 16, 1
	v_add3_u32 v48, v59, v48, s91
	v_add3_u32 v41, v41, v43, s91
	v_lshrrev_b32_e32 v40, 16, v40
	v_ashrrev_i32_e32 v59, 31, v58
	v_mov_b32_e32 v56, v55
	v_add3_u32 v2, v60, v2, s91
	v_add3_u32 v0, v61, v0, s91
	v_lshrrev_b32_e32 v41, 16, v41
	v_lshrrev_b32_e32 v42, 16, v46
	v_lshrrev_b32_e32 v43, 16, v48
	v_and_or_b32 v40, v44, s35, v40
	v_lshlrev_b64 v[58:59], 11, v[58:59]
	v_mov_b32_e32 v44, v37
	v_pk_mul_f32 v[4:5], v[4:5], v[56:57]
	v_and_or_b32 v43, v0, s35, v43
	v_and_or_b32 v42, v2, s35, v42
	v_and_or_b32 v41, v36, s35, v41
	v_lshl_add_u64 v[58:59], v[24:25], 0, v[58:59]
	v_pk_mul_f32 v[36:37], v[52:53], v[44:45]
	v_mov_b32_e32 v46, v3
	v_bfe_u32 v0, v5, 16, 1
	global_store_dwordx4 v[58:59], v[40:43], off sc1
	v_pk_mul_f32 v[2:3], v[38:39], v[46:47]
	v_add3_u32 v0, v5, v0, s91
	v_bfe_u32 v40, v4, 16, 1
	v_bfe_u32 v5, v36, 16, 1
	v_mov_b32_e32 v50, v49
	v_bfe_u32 v42, v2, 16, 1
	v_add3_u32 v4, v4, v40, s91
	v_bfe_u32 v40, v37, 16, 1
	v_add3_u32 v5, v36, v5, s91
	v_pk_mul_f32 v[38:39], v[62:63], v[50:51]
	v_bfe_u32 v41, v3, 16, 1
	v_add3_u32 v2, v2, v42, s91
	v_add3_u32 v37, v37, v40, s91
	v_lshrrev_b32_e32 v36, 16, v5
	v_add3_u32 v3, v3, v41, s91
	v_bfe_u32 v41, v38, 16, 1
	v_bfe_u32 v42, v39, 16, 1
	v_lshrrev_b32_e32 v37, 16, v37
	v_and_or_b32 v2, v2, s35, v36
	v_or_b32_e32 v36, s38, v35
	v_add3_u32 v39, v39, v42, s91
	v_add3_u32 v38, v38, v41, s91
	v_and_or_b32 v3, v3, s35, v37
	v_ashrrev_i32_e32 v37, 31, v36
	v_lshrrev_b32_e32 v38, 16, v38
	v_lshrrev_b32_e32 v5, 16, v39
	v_lshlrev_b64 v[36:37], 11, v[36:37]
	v_and_or_b32 v5, v0, s35, v5
	v_and_or_b32 v4, v4, s35, v38
	v_lshl_add_u64 v[24:25], v[24:25], 0, v[36:37]
	global_store_dwordx4 v[24:25], v[2:5], off sc1
	s_waitcnt lgkmcnt(0)
	s_mov_b64 s[8:9], s[26:27]
	v_readlane_b32 s5, v252, 1
	v_readlane_b32 s6, v252, 2
	v_readlane_b32 s7, v252, 3
	v_readlane_b32 s10, v252, 6
	v_readlane_b32 s11, v252, 7
	v_readlane_b32 s12, v252, 8
	v_readlane_b32 s13, v252, 9
	v_readlane_b32 s14, v252, 10
	v_readlane_b32 s15, v252, 11
	v_readlane_b32 s16, v252, 12
	v_readlane_b32 s17, v252, 13
	v_readlane_b32 s18, v252, 14
	v_readlane_b32 s19, v252, 15
	s_branch .LBB0_544

; template <bool HASG>
; __device__ __forceinline__ void tr_item(const float* W, int K, int N, bf16* WT, int rowmode, const float* g, LAS float* scr, int item, int lane) {
;     const int nblk = N / 32, kb = item / nblk, nb = item % nblk, k0 = 64 * kb, n0 = 32 * nb;
;     const float* wp = W + (size_t)(k0 + (lane >> 5)) * N + n0 + (lane & 31);
;     const int c = lane & 7;
;     float v[32];
; #pragma unroll
;     for (int i = 0; i < 32; ++i) v[i] = wp[(size_t)(2 * i) * N];
;     f32x4 g0 = (f32x4){1.f, 1.f, 1.f, 1.f}, g1 = g0;
;     if (HASG) { g0 = *(const f32x4*)(g + k0 + 8 * c); g1 = *(const f32x4*)(g + k0 + 8 * c + 4); }
; __device__ __forceinline__ void convert_items(const Args& a, LAS unsigned char* lds, int l, int it_lo, int it_hi, int gw, int NGW, int wave, int lane) {
;     ...
;     for (int it = it_lo + gw; it < it_hi; it += NGW) {
;         int r = it; bf16* wl = WB + (size_t)l * W_LAYER;
;         const size_t o_gu = (size_t)l * D * FF, o_d = (size_t)l * FF * D;
;         if (r < I_G) { tr_item<true>(a.in[2] + o_gu, D, FF, wl + W_GU1, 1, a.in[1] + l * D, scr, r, lane); continue; } r -= I_G;
;         if (r < I_G) { tr_item<true>(a.in[3] + o_gu, D, FF, wl + W_GU1, 2, a.in[1] + l * D, scr, r, lane); continue; } r -= I_G;
;         if (r < I_D) { tr_item<false>(a.in[4] + o_d, FF, D, wl + W_D1, 0, nullptr, scr, r, lane); continue; } r -= I_D;
;         if (r < I_IN) { tr_item<true>(a.in[6] + (size_t)l * D * DIN, D, DIN, wl + W_IN, 0, a.in[5] + l * D, scr, r, lane); continue; } r -= I_IN;
;         if (r < I_OUT) { tr_item<false>(a.in[18] + (size_t)l * D * D, D, D, wl + W_OUT, 0, nullptr, scr, r, lane); continue; } r -= I_OUT;
;         if (r < I_G) { tr_item<true>(a.in[20] + o_gu, D, FF, wl + W_GU2, 1, a.in[19] + l * D, scr, r, lane); continue; } r -= I_G;
;         if (r < I_G) { tr_item<true>(a.in[21] + o_gu, D, FF, wl + W_GU2, 2, a.in[19] + l * D, scr, r, lane); continue; } r -= I_G;
;         if (r < I_D) { tr_item<false>(a.in[22] + o_d, FF, D, wl + W_D2, 0, nullptr, scr, r, lane); continue; } r -= I_D;
;         { const int mat = r >> 1, nbk = r & 1, gate = mat & 1, blk = (mat >> 1) & 7, d = mat >> 4;
;           const float* src = (gate ? a.in[11] : a.in[9]) + (size_t)((l * 2 + d) * 8 + blk) * 4096;
;           tr_item<false>(src, 64, 64, wl + W_LRU + (size_t)((d * 8 + blk) * 2 + gate) * 4096, 0, nullptr, scr, nbk, lane); }
.LBB0_572:
	s_cmpk_gt_i32 s28, 0x57f
	s_mov_b64 s[0:1], -1
	s_cbranch_scc0 .LBB0_602
	s_cmpk_gt_u32 s28, 0xaff
	s_cbranch_scc0 .LBB0_599
	s_cmpk_gt_u32 s28, 0x107f
	s_cbranch_scc0 .LBB0_596
	s_cmpk_gt_u32 s28, 0x13ff
	s_cbranch_scc0 .LBB0_593
	s_cmpk_gt_u32 s28, 0x15ff
	s_cbranch_scc0 .LBB0_590
	s_cmpk_gt_u32 s28, 0x1b7f
	s_cbranch_scc0 .LBB0_587
	s_cmpk_gt_u32 s28, 0x20ff
	s_cbranch_scc0 .LBB0_584
	s_cmpk_gt_u32 s28, 0x267f
	s_cbranch_scc0 .LBB0_581
	s_add_i32 s0, s28, 0xffffd980
	s_bfe_u32 s38, s28, 0x10001
	s_bfe_u32 s39, s28, 0x30002
	s_lshr_b32 s45, s0, 5
	v_readlane_b32 s4, v252, 16
	s_cmp_eq_u32 s38, 0
	v_readlane_b32 s6, v252, 18
	v_readlane_b32 s7, v252, 19
	v_readlane_b32 s10, v252, 22
	v_readlane_b32 s11, v252, 23
	s_cselect_b32 s47, s7, s11
	s_cselect_b32 s46, s6, s10
	s_lshl_b32 s0, s45, 3
	s_or_b32 s88, s0, s39
	s_lshl_b64 s[0:1], s[88:89], 14
	s_add_u32 s46, s46, s0
	s_addc_u32 s47, s47, s1
	s_lshl_b32 s0, s45, 4
	s_lshl_b32 s1, s39, 1
	s_or_b32 s0, s0, s1
	s_or_b32 s88, s0, s38
	s_lshl_b32 s38, s28, 5
	s_and_b32 s38, s38, 32
	v_mov_b32_e32 v29, v1
	s_lshl_b64 s[0:1], s[88:89], 13
	v_lshl_add_u64 v[2:3], s[46:47], 0, v[28:29]
	s_lshl_b32 s88, s38, 2
	v_lshl_add_u64 v[2:3], v[2:3], 0, s[88:89]
	v_lshlrev_b32_e32 v0, 2, v6
	v_lshl_add_u64 v[2:3], v[2:3], 0, v[0:1]
	s_movk_i32 s4, 0x1000
	global_load_dword v0, v[2:3], off
	global_load_dword v29, v[2:3], off offset:512
	global_load_dword v38, v[2:3], off offset:1024
	global_load_dword v39, v[2:3], off offset:1536
	global_load_dword v40, v[2:3], off offset:2048
	global_load_dword v41, v[2:3], off offset:2560
	global_load_dword v42, v[2:3], off offset:3072
	global_load_dword v43, v[2:3], off offset:3584
	v_add_co_u32_e32 v4, vcc, s4, v2
	s_movk_i32 s4, 0x2000
	s_nop 0
	v_addc_co_u32_e32 v5, vcc, 0, v3, vcc
	v_add_co_u32_e32 v30, vcc, s4, v2
	s_movk_i32 s4, 0x3000
	s_nop 0
	v_addc_co_u32_e32 v31, vcc, 0, v3, vcc
	global_load_dword v44, v[30:31], off offset:-4096
	global_load_dword v45, v[4:5], off offset:512
	global_load_dword v46, v[4:5], off offset:1024
	global_load_dword v47, v[4:5], off offset:1536
	global_load_dword v48, v[4:5], off offset:2048
	global_load_dword v49, v[4:5], off offset:2560
	global_load_dword v50, v[4:5], off offset:3072
	s_nop 0
	global_load_dword v4, v[4:5], off offset:3584
	s_nop 0
	global_load_dword v5, v[30:31], off
	global_load_dword v51, v[30:31], off offset:512
	global_load_dword v52, v[30:31], off offset:1024
	global_load_dword v53, v[30:31], off offset:1536
	global_load_dword v54, v[30:31], off offset:2048
	global_load_dword v55, v[30:31], off offset:2560
	global_load_dword v56, v[30:31], off offset:3072
	s_nop 0
	global_load_dword v30, v[30:31], off offset:3584
	v_add_co_u32_e32 v2, vcc, s4, v2
	v_readlane_b32 s5, v252, 17
	s_nop 0
	v_addc_co_u32_e32 v3, vcc, 0, v3, vcc
	global_load_dword v31, v[2:3], off
	global_load_dword v57, v[2:3], off offset:512
	global_load_dword v58, v[2:3], off offset:1024
	global_load_dword v59, v[2:3], off offset:1536
	global_load_dword v60, v[2:3], off offset:2048
	global_load_dword v61, v[2:3], off offset:2560
	global_load_dword v62, v[2:3], off offset:3072
	s_nop 0
	global_load_dword v2, v[2:3], off offset:3584
	v_readlane_b32 s8, v252, 20
	v_readlane_b32 s9, v252, 21
	v_readlane_b32 s12, v252, 24
	v_readlane_b32 s13, v252, 25
	v_readlane_b32 s14, v252, 26
	v_readlane_b32 s15, v252, 27
	v_readlane_b32 s16, v252, 28
	v_readlane_b32 s17, v252, 29
	v_readlane_b32 s18, v252, 30
	v_readlane_b32 s19, v252, 31
	s_waitcnt vmcnt(30)
	ds_write2_b32 v36, v0, v29 offset1:66
	s_waitcnt vmcnt(28)
	ds_write2_b32 v36, v38, v39 offset0:132 offset1:198
	v_add_u32_e32 v0, 0x400, v36
	s_waitcnt vmcnt(26)
	ds_write2_b32 v0, v40, v41 offset0:8 offset1:74
	s_waitcnt vmcnt(24)
	ds_write2_b32 v0, v42, v43 offset0:140 offset1:206
	v_add_u32_e32 v0, 0x800, v36
	s_waitcnt vmcnt(22)
	ds_write2_b32 v0, v44, v45 offset0:16 offset1:82
	s_waitcnt vmcnt(20)
	ds_write2_b32 v0, v46, v47 offset0:148 offset1:214
	v_add_u32_e32 v0, 0xc00, v36
	s_waitcnt vmcnt(18)
	ds_write2_b32 v0, v48, v49 offset0:24 offset1:90
	s_waitcnt vmcnt(16)
	ds_write2_b32 v0, v50, v4 offset0:156 offset1:222
	v_add_u32_e32 v0, 0x1000, v36
	s_waitcnt vmcnt(14)
	ds_write2_b32 v0, v5, v51 offset0:32 offset1:98
	s_waitcnt vmcnt(12)
	ds_write2_b32 v0, v52, v53 offset0:164 offset1:230
	v_add_u32_e32 v0, 0x1400, v36
	s_waitcnt vmcnt(10)
	ds_write2_b32 v0, v54, v55 offset0:40 offset1:106
	s_waitcnt vmcnt(8)
	ds_write2_b32 v0, v56, v30 offset0:172 offset1:238
	v_add_u32_e32 v0, 0x1800, v36
	s_waitcnt vmcnt(6)
	ds_write2_b32 v0, v31, v57 offset0:48 offset1:114
	s_waitcnt vmcnt(4)
	ds_write2_b32 v0, v58, v59 offset0:180 offset1:246
	v_add_u32_e32 v0, 0x1c00, v36
	s_waitcnt vmcnt(2)
	ds_write2_b32 v0, v60, v61 offset0:56 offset1:122
	s_waitcnt vmcnt(0)
	ds_write2_b32 v0, v62, v2 offset0:188 offset1:254
	s_waitcnt lgkmcnt(0)
	ds_read2_b32 v[4:5], v37 offset0:33 offset1:41
	ds_read2_b32 v[30:31], v37 offset1:8
	ds_read2_b32 v[42:43], v37 offset0:66 offset1:74
	ds_read2_b32 v[44:45], v37 offset0:99 offset1:107
	ds_read2_b32 v[46:47], v37 offset0:132 offset1:140
	ds_read2_b32 v[48:49], v37 offset0:165 offset1:173
	ds_read2_b32 v[50:51], v37 offset0:198 offset1:206
	ds_read2_b32 v[52:53], v37 offset0:231 offset1:239
	s_waitcnt lgkmcnt(7)
	v_bfe_u32 v29, v4, 16, 1
	s_waitcnt lgkmcnt(6)
	v_bfe_u32 v0, v30, 16, 1
	v_add3_u32 v0, v30, v0, s91
	v_lshrrev_b32_e32 v0, 16, v0
	v_add3_u32 v4, v4, v29, s91
	v_and_or_b32 v38, v4, s35, v0
	s_waitcnt lgkmcnt(5)
	v_bfe_u32 v0, v42, 16, 1
	v_add3_u32 v0, v42, v0, s91
	s_waitcnt lgkmcnt(4)
	v_bfe_u32 v4, v44, 16, 1
	v_lshrrev_b32_e32 v0, 16, v0
	v_add3_u32 v4, v44, v4, s91
	v_and_or_b32 v39, v4, s35, v0
	s_waitcnt lgkmcnt(3)
; #define LAS __attribute__((address_space(3)))
; __device__ __forceinline__ unsigned pk2(float lo, float hi) { return f2bf(lo) | (f2bf(hi) << 16); }
; #define LDS_WAVE_SYNC() asm volatile("s_waitcnt lgkmcnt(0)" ::: "memory")
; template <bool HASG>
; __device__ __forceinline__ void tr_item(const float* W, int K, int N, bf16* WT, int rowmode, const float* g, LAS float* scr, int item, int lane) {
;     const int nblk = N / 32, kb = item / nblk, nb = item % nblk, k0 = 64 * kb, n0 = 32 * nb;
;     const float* wp = W + (size_t)(k0 + (lane >> 5)) * N + n0 + (lane & 31);
;     const int c = lane & 7;
;     float v[32];
; #pragma unroll
;     for (int i = 0; i < 32; ++i) v[i] = wp[(size_t)(2 * i) * N];
;     ...
;     for (int i = 0; i < 32; ++i) scr[(2 * i + (lane >> 5)) * 33 + (lane & 31)] = v[i];
;     LDS_WAVE_SYNC();
;     const int drow0 = rowmode == 0 ? n0 : ((n0 >> 7) * 256 + (n0 & 127) + (rowmode == 2 ? 128 : 0));
; #pragma unroll
;     for (int j = 0; j < 4; ++j) { const int n = (lane >> 3) + 8 * j; const LAS float* s = scr + (8 * c) * 33 + n;
;         u32x4 o; o.x = pk2(s[0 * 33] * g0.x, s[1 * 33] * g0.y); o.y = pk2(s[2 * 33] * g0.z, s[3 * 33] * g0.w);
;         o.z = pk2(s[4 * 33] * g1.x, s[5 * 33] * g1.y); o.w = pk2(s[6 * 33] * g1.z, s[7 * 33] * g1.w);
;         *(u32x4*)(WT + (size_t)(drow0 + n) * K + k0 + 8 * c) = o; }
;     LDS_WAVE_SYNC();
; __device__ __forceinline__ void convert_items(const Args& a, LAS unsigned char* lds, int l, int it_lo, int it_hi, int gw, int NGW, int wave, int lane) {
;     ...
;         if (r < I_D) { tr_item<false>(a.in[22] + o_d, FF, D, wl + W_D2, 0, nullptr, scr, r, lane); continue; } r -= I_D;
	v_bfe_u32 v0, v46, 16, 1
	v_add3_u32 v0, v46, v0, s91
	s_waitcnt lgkmcnt(2)
	v_bfe_u32 v4, v48, 16, 1
	v_lshrrev_b32_e32 v0, 16, v0
	v_add3_u32 v4, v48, v4, s91
	v_and_or_b32 v40, v4, s35, v0
	s_waitcnt lgkmcnt(1)
	v_bfe_u32 v0, v50, 16, 1
	v_add3_u32 v0, v50, v0, s91
	s_waitcnt lgkmcnt(0)
	v_bfe_u32 v4, v52, 16, 1
	v_lshrrev_b32_e32 v0, 16, v0
	v_add3_u32 v4, v52, v4, s91
	v_and_or_b32 v41, v4, s35, v0
	v_or_b32_e32 v0, s38, v7
	v_lshl_add_u64 v[2:3], v[8:9], 0, s[0:1]
	v_lshlrev_b32_e32 v0, 7, v0
	v_lshl_add_u64 v[54:55], v[2:3], 0, v[0:1]
	v_bfe_u32 v0, v31, 16, 1
	v_add3_u32 v0, v31, v0, s91
	v_bfe_u32 v4, v5, 16, 1
	v_lshrrev_b32_e32 v0, 16, v0
	v_add3_u32 v4, v5, v4, s91
	global_store_dwordx4 v[54:55], v[38:41], off sc1
	s_mov_b64 s[0:1], 0
	s_nop 0
	v_and_or_b32 v38, v4, s35, v0
	v_bfe_u32 v0, v43, 16, 1
	v_add3_u32 v0, v43, v0, s91
	v_bfe_u32 v4, v45, 16, 1
	v_lshrrev_b32_e32 v0, 16, v0
	v_add3_u32 v4, v45, v4, s91
	v_and_or_b32 v39, v4, s35, v0
	v_bfe_u32 v0, v47, 16, 1
	v_add3_u32 v0, v47, v0, s91
	v_bfe_u32 v4, v49, 16, 1
	v_lshrrev_b32_e32 v0, 16, v0
	v_add3_u32 v4, v49, v4, s91
	v_and_or_b32 v40, v4, s35, v0
	v_bfe_u32 v0, v51, 16, 1
	v_add3_u32 v0, v51, v0, s91
	v_bfe_u32 v4, v53, 16, 1
	v_lshrrev_b32_e32 v0, 16, v0
	v_add3_u32 v4, v53, v4, s91
	v_and_or_b32 v41, v4, s35, v0
	v_or_b32_e32 v0, s38, v32
	v_lshlrev_b32_e32 v0, 7, v0
	v_lshl_add_u64 v[4:5], v[2:3], 0, v[0:1]
	global_store_dwordx4 v[4:5], v[38:41], off sc1
	ds_read2_b32 v[4:5], v37 offset0:49 offset1:57
	ds_read2_b32 v[30:31], v37 offset0:16 offset1:24
	ds_read2_b32 v[42:43], v37 offset0:82 offset1:90
	ds_read2_b32 v[44:45], v37 offset0:115 offset1:123
	ds_read2_b32 v[46:47], v37 offset0:148 offset1:156
	ds_read2_b32 v[48:49], v37 offset0:181 offset1:189
	ds_read2_b32 v[50:51], v37 offset0:214 offset1:222
	ds_read2_b32 v[52:53], v37 offset0:247 offset1:255
	s_waitcnt lgkmcnt(7)
	v_bfe_u32 v29, v4, 16, 1
	s_waitcnt lgkmcnt(6)
	v_bfe_u32 v0, v30, 16, 1
	v_add3_u32 v0, v30, v0, s91
	v_lshrrev_b32_e32 v0, 16, v0
	v_add3_u32 v4, v4, v29, s91
	v_and_or_b32 v38, v4, s35, v0
	s_waitcnt lgkmcnt(5)
	v_bfe_u32 v0, v42, 16, 1
	v_add3_u32 v0, v42, v0, s91
	s_waitcnt lgkmcnt(4)
	v_bfe_u32 v4, v44, 16, 1
	v_lshrrev_b32_e32 v0, 16, v0
	v_add3_u32 v4, v44, v4, s91
	v_and_or_b32 v39, v4, s35, v0
	s_waitcnt lgkmcnt(3)
	v_bfe_u32 v0, v46, 16, 1
	v_add3_u32 v0, v46, v0, s91
	s_waitcnt lgkmcnt(2)
	v_bfe_u32 v4, v48, 16, 1
	v_lshrrev_b32_e32 v0, 16, v0
	v_add3_u32 v4, v48, v4, s91
	v_and_or_b32 v40, v4, s35, v0
	s_waitcnt lgkmcnt(1)
	v_bfe_u32 v0, v50, 16, 1
	v_add3_u32 v0, v50, v0, s91
	s_waitcnt lgkmcnt(0)
	v_bfe_u32 v4, v52, 16, 1
	v_lshrrev_b32_e32 v0, 16, v0
	v_add3_u32 v4, v52, v4, s91
	v_and_or_b32 v41, v4, s35, v0
	v_or_b32_e32 v0, s38, v34
	v_lshlrev_b32_e32 v0, 7, v0
	v_lshl_add_u64 v[54:55], v[2:3], 0, v[0:1]
	v_bfe_u32 v0, v31, 16, 1
	v_add3_u32 v0, v31, v0, s91
	v_bfe_u32 v4, v5, 16, 1
	v_lshrrev_b32_e32 v0, 16, v0
	v_add3_u32 v4, v5, v4, s91
	global_store_dwordx4 v[54:55], v[38:41], off sc1
	s_nop 1
	v_and_or_b32 v38, v4, s35, v0
	v_bfe_u32 v0, v43, 16, 1
	v_add3_u32 v0, v43, v0, s91
	v_bfe_u32 v4, v45, 16, 1
	v_lshrrev_b32_e32 v0, 16, v0
	v_add3_u32 v4, v45, v4, s91
	v_and_or_b32 v39, v4, s35, v0
	v_bfe_u32 v0, v47, 16, 1
	v_add3_u32 v0, v47, v0, s91
	v_bfe_u32 v4, v49, 16, 1
	v_lshrrev_b32_e32 v0, 16, v0
	v_add3_u32 v4, v49, v4, s91
	v_and_or_b32 v40, v4, s35, v0
	v_bfe_u32 v0, v51, 16, 1
	v_add3_u32 v0, v51, v0, s91
	v_bfe_u32 v4, v53, 16, 1
	v_lshrrev_b32_e32 v0, 16, v0
	v_add3_u32 v4, v53, v4, s91
	v_and_or_b32 v41, v4, s35, v0
	v_or_b32_e32 v0, s38, v35
	v_lshlrev_b32_e32 v0, 7, v0
	v_lshl_add_u64 v[2:3], v[2:3], 0, v[0:1]
	global_store_dwordx4 v[2:3], v[38:41], off sc1
	s_waitcnt lgkmcnt(0)
.LBB0_581:
	s_andn2_b64 vcc, exec, s[0:1]
	s_cbranch_vccnz .LBB0_583
	s_and_b32 s1, s43, 0x1ffc0
	s_lshl_b32 s0, s28, 5
	v_or_b32_e32 v0, s1, v33
	v_readlane_b32 s4, v252, 32
	s_and_b32 s0, s0, 0x3e0
	v_lshlrev_b32_e32 v0, 12, v0
	v_readlane_b32 s16, v252, 44
	v_readlane_b32 s17, v252, 45
	s_lshl_b32 s88, s0, 2
	v_readlane_b32 s5, v252, 33
	v_lshl_add_u64 v[2:3], s[16:17], 0, v[0:1]
	v_lshl_add_u64 v[2:3], v[2:3], 0, s[88:89]
	v_lshlrev_b32_e32 v0, 2, v6
	v_lshl_add_u64 v[2:3], v[2:3], 0, v[0:1]
	v_add_co_u32_e32 v4, vcc, 0x2000, v2
	global_load_dword v0, v[2:3], off
	s_nop 0
	v_addc_co_u32_e32 v5, vcc, 0, v3, vcc
	global_load_dword v29, v[4:5], off
	v_add_co_u32_e32 v4, vcc, 0x4000, v2
	v_readlane_b32 s6, v252, 34
	s_nop 0
	v_addc_co_u32_e32 v5, vcc, 0, v3, vcc
	global_load_dword v30, v[4:5], off
	v_add_co_u32_e32 v4, vcc, 0x6000, v2
	v_readlane_b32 s7, v252, 35
	s_nop 0
	v_addc_co_u32_e32 v5, vcc, 0, v3, vcc
	global_load_dword v31, v[4:5], off
	v_add_co_u32_e32 v4, vcc, 0x8000, v2
	v_readlane_b32 s8, v252, 36
	s_nop 0
	v_addc_co_u32_e32 v5, vcc, 0, v3, vcc
	global_load_dword v38, v[4:5], off
	v_add_co_u32_e32 v4, vcc, 0xa000, v2
	v_readlane_b32 s9, v252, 37
	s_nop 0
	v_addc_co_u32_e32 v5, vcc, 0, v3, vcc
	global_load_dword v39, v[4:5], off
	v_add_co_u32_e32 v4, vcc, 0xc000, v2
	v_readlane_b32 s10, v252, 38
	s_nop 0
	v_addc_co_u32_e32 v5, vcc, 0, v3, vcc
	global_load_dword v40, v[4:5], off
	v_add_co_u32_e32 v4, vcc, 0xe000, v2
	v_readlane_b32 s11, v252, 39
	v_readlane_b32 s12, v252, 40
	v_readlane_b32 s13, v252, 41
	v_readlane_b32 s14, v252, 42
	v_readlane_b32 s15, v252, 43
	v_readlane_b32 s18, v252, 46
	v_readlane_b32 s19, v252, 47
	v_addc_co_u32_e32 v5, vcc, 0, v3, vcc
	v_readlane_b32 s4, v252, 0
	global_load_dword v41, v[4:5], off
	v_add_co_u32_e32 v4, vcc, s70, v2
	s_mov_b32 s4, 0x12000
	s_nop 0
	v_addc_co_u32_e32 v5, vcc, 0, v3, vcc
	global_load_dword v42, v[4:5], off
; #define LDS_WAVE_SYNC() asm volatile("s_waitcnt lgkmcnt(0)" ::: "memory")
; template <bool HASG>
; __device__ __forceinline__ void tr_item(const float* W, int K, int N, bf16* WT, int rowmode, const float* g, LAS float* scr, int item, int lane) {
;     ...
;     const float* wp = W + (size_t)(k0 + (lane >> 5)) * N + n0 + (lane & 31);
;     const int c = lane & 7;
;     float v[32];
; #pragma unroll
;     for (int i = 0; i < 32; ++i) v[i] = wp[(size_t)(2 * i) * N];
;     f32x4 g0 = (f32x4){1.f, 1.f, 1.f, 1.f}, g1 = g0;
;     if (HASG) { g0 = *(const f32x4*)(g + k0 + 8 * c); g1 = *(const f32x4*)(g + k0 + 8 * c + 4); }
;     asm volatile("" ::: "memory");
; #pragma unroll
;     for (int i = 0; i < 32; ++i) scr[(2 * i + (lane >> 5)) * 33 + (lane & 31)] = v[i];
;     LDS_WAVE_SYNC();
	v_add_co_u32_e32 v4, vcc, s4, v2
	s_mov_b32 s4, 0x14000
	s_nop 0
	v_addc_co_u32_e32 v5, vcc, 0, v3, vcc
	global_load_dword v43, v[4:5], off
	v_add_co_u32_e32 v4, vcc, s4, v2
	s_mov_b32 s4, 0x18000
	s_nop 0
	v_addc_co_u32_e32 v5, vcc, 0, v3, vcc
	global_load_dword v44, v[4:5], off
	v_add_co_u32_e32 v4, vcc, s71, v2
	s_lshl_b32 s88, s1, 1
	s_nop 0
	v_addc_co_u32_e32 v5, vcc, 0, v3, vcc
	global_load_dword v45, v[4:5], off
	v_add_co_u32_e32 v4, vcc, s4, v2
	s_mov_b32 s4, 0x1a000
	s_nop 0
	v_addc_co_u32_e32 v5, vcc, 0, v3, vcc
	global_load_dword v46, v[4:5], off
	v_add_co_u32_e32 v4, vcc, s4, v2
	s_mov_b32 s4, 0x1c000
	s_nop 0
	v_addc_co_u32_e32 v5, vcc, 0, v3, vcc
	global_load_dword v47, v[4:5], off
	v_add_co_u32_e32 v4, vcc, s4, v2
	s_mov_b32 s4, 0x1e000
	s_nop 0
	v_addc_co_u32_e32 v5, vcc, 0, v3, vcc
	global_load_dword v48, v[4:5], off
	v_add_co_u32_e32 v4, vcc, s4, v2
	s_mov_b32 s4, 0x20000
	s_nop 0
	v_addc_co_u32_e32 v5, vcc, 0, v3, vcc
	global_load_dword v49, v[4:5], off
	v_add_co_u32_e32 v4, vcc, s4, v2
	s_mov_b32 s4, 0x22000
	s_nop 0
	v_addc_co_u32_e32 v5, vcc, 0, v3, vcc
	global_load_dword v50, v[4:5], off
	v_add_co_u32_e32 v4, vcc, s4, v2
	s_mov_b32 s4, 0x24000
	s_nop 0
	v_addc_co_u32_e32 v5, vcc, 0, v3, vcc
	global_load_dword v51, v[4:5], off
	v_add_co_u32_e32 v4, vcc, s4, v2
	s_mov_b32 s4, 0x26000
	s_nop 0
	v_addc_co_u32_e32 v5, vcc, 0, v3, vcc
	global_load_dword v52, v[4:5], off
	v_add_co_u32_e32 v4, vcc, s4, v2
	s_mov_b32 s4, 0x28000
	s_nop 0
	v_addc_co_u32_e32 v5, vcc, 0, v3, vcc
	global_load_dword v53, v[4:5], off
	v_add_co_u32_e32 v4, vcc, s4, v2
	s_mov_b32 s4, 0x2a000
	s_nop 0
	v_addc_co_u32_e32 v5, vcc, 0, v3, vcc
	global_load_dword v54, v[4:5], off
	v_add_co_u32_e32 v4, vcc, s4, v2
	s_mov_b32 s4, 0x2c000
	s_nop 0
	v_addc_co_u32_e32 v5, vcc, 0, v3, vcc
	global_load_dword v55, v[4:5], off
	v_add_co_u32_e32 v4, vcc, s4, v2
	s_mov_b32 s4, 0x2e000
	s_nop 0
	v_addc_co_u32_e32 v5, vcc, 0, v3, vcc
	global_load_dword v56, v[4:5], off
	v_add_co_u32_e32 v4, vcc, s4, v2
	s_mov_b32 s4, 0x30000
	s_nop 0
	v_addc_co_u32_e32 v5, vcc, 0, v3, vcc
	global_load_dword v57, v[4:5], off
	v_add_co_u32_e32 v4, vcc, s4, v2
	s_mov_b32 s4, 0x32000
	s_nop 0
	v_addc_co_u32_e32 v5, vcc, 0, v3, vcc
	global_load_dword v58, v[4:5], off
	v_add_co_u32_e32 v4, vcc, s4, v2
	s_mov_b32 s4, 0x34000
	s_nop 0
	v_addc_co_u32_e32 v5, vcc, 0, v3, vcc
	global_load_dword v59, v[4:5], off
	v_add_co_u32_e32 v4, vcc, s4, v2
	s_mov_b32 s4, 0x36000
	s_nop 0
	v_addc_co_u32_e32 v5, vcc, 0, v3, vcc
	global_load_dword v60, v[4:5], off
	v_add_co_u32_e32 v4, vcc, s4, v2
	s_mov_b32 s4, 0x38000
	s_nop 0
	v_addc_co_u32_e32 v5, vcc, 0, v3, vcc
	global_load_dword v61, v[4:5], off
	v_add_co_u32_e32 v4, vcc, s4, v2
	s_mov_b32 s4, 0x3a000
	s_nop 0
	v_addc_co_u32_e32 v5, vcc, 0, v3, vcc
	global_load_dword v62, v[4:5], off
	v_add_co_u32_e32 v4, vcc, s4, v2
	s_mov_b32 s4, 0x3c000
	s_nop 0
	v_addc_co_u32_e32 v5, vcc, 0, v3, vcc
	global_load_dword v63, v[4:5], off
	v_add_co_u32_e32 v4, vcc, s4, v2
	s_mov_b32 s4, 0x3e000
	s_nop 0
	v_addc_co_u32_e32 v5, vcc, 0, v3, vcc
	v_add_co_u32_e32 v2, vcc, s4, v2
	global_load_dword v4, v[4:5], off
	s_nop 0
	v_addc_co_u32_e32 v3, vcc, 0, v3, vcc
	global_load_dword v2, v[2:3], off
	s_waitcnt vmcnt(30)
	ds_write2_b32 v36, v0, v29 offset1:66
	s_waitcnt vmcnt(28)
	ds_write2_b32 v36, v30, v31 offset0:132 offset1:198
	v_add_u32_e32 v0, 0x400, v36
	s_waitcnt vmcnt(26)
	ds_write2_b32 v0, v38, v39 offset0:8 offset1:74
	s_waitcnt vmcnt(24)
	ds_write2_b32 v0, v40, v41 offset0:140 offset1:206
	v_add_u32_e32 v0, 0x800, v36
	s_waitcnt vmcnt(22)
	ds_write2_b32 v0, v42, v43 offset0:16 offset1:82
	s_waitcnt vmcnt(20)
	ds_write2_b32 v0, v44, v45 offset0:148 offset1:214
	v_add_u32_e32 v0, 0xc00, v36
	s_waitcnt vmcnt(18)
	ds_write2_b32 v0, v46, v47 offset0:24 offset1:90
	s_waitcnt vmcnt(16)
	ds_write2_b32 v0, v48, v49 offset0:156 offset1:222
	v_add_u32_e32 v0, 0x1000, v36
	s_waitcnt vmcnt(14)
	ds_write2_b32 v0, v50, v51 offset0:32 offset1:98
	s_waitcnt vmcnt(12)
	ds_write2_b32 v0, v52, v53 offset0:164 offset1:230
	v_add_u32_e32 v0, 0x1400, v36
	s_waitcnt vmcnt(10)
	ds_write2_b32 v0, v54, v55 offset0:40 offset1:106
	s_waitcnt vmcnt(8)
	ds_write2_b32 v0, v56, v57 offset0:172 offset1:238
	v_add_u32_e32 v0, 0x1800, v36
	s_waitcnt vmcnt(6)
	ds_write2_b32 v0, v58, v59 offset0:48 offset1:114
	s_waitcnt vmcnt(4)
	ds_write2_b32 v0, v60, v61 offset0:180 offset1:246
	v_add_u32_e32 v0, 0x1c00, v36
	s_waitcnt vmcnt(2)
	ds_write2_b32 v0, v62, v63 offset0:56 offset1:122
	s_waitcnt vmcnt(0)
	ds_write2_b32 v0, v4, v2 offset0:188 offset1:254
	s_waitcnt lgkmcnt(0)
	ds_read2_b32 v[4:5], v37 offset0:33 offset1:41
	ds_read2_b32 v[30:31], v37 offset1:8
	ds_read2_b32 v[42:43], v37 offset0:66 offset1:74
	ds_read2_b32 v[44:45], v37 offset0:99 offset1:107
	ds_read2_b32 v[46:47], v37 offset0:132 offset1:140
	ds_read2_b32 v[48:49], v37 offset0:165 offset1:173
	ds_read2_b32 v[50:51], v37 offset0:198 offset1:206
	ds_read2_b32 v[52:53], v37 offset0:231 offset1:239
	s_waitcnt lgkmcnt(7)
; #define LAS __attribute__((address_space(3)))
; __device__ __forceinline__ unsigned pk2(float lo, float hi) { return f2bf(lo) | (f2bf(hi) << 16); }
; #define LDS_WAVE_SYNC() asm volatile("s_waitcnt lgkmcnt(0)" ::: "memory")
; template <bool HASG>
; __device__ __forceinline__ void tr_item(const float* W, int K, int N, bf16* WT, int rowmode, const float* g, LAS float* scr, int item, int lane) {
;     ...
;     for (int j = 0; j < 4; ++j) { const int n = (lane >> 3) + 8 * j; const LAS float* s = scr + (8 * c) * 33 + n;
;         u32x4 o; o.x = pk2(s[0 * 33] * g0.x, s[1 * 33] * g0.y); o.y = pk2(s[2 * 33] * g0.z, s[3 * 33] * g0.w);
;         o.z = pk2(s[4 * 33] * g1.x, s[5 * 33] * g1.y); o.w = pk2(s[6 * 33] * g1.z, s[7 * 33] * g1.w);
;         *(u32x4*)(WT + (size_t)(drow0 + n) * K + k0 + 8 * c) = o; }
;     LDS_WAVE_SYNC();
	v_bfe_u32 v29, v4, 16, 1
	s_waitcnt lgkmcnt(6)
	v_bfe_u32 v0, v30, 16, 1
	v_add3_u32 v0, v30, v0, s91
	v_lshrrev_b32_e32 v0, 16, v0
	v_add3_u32 v4, v4, v29, s91
	v_and_or_b32 v38, v4, s35, v0
	s_waitcnt lgkmcnt(5)
	v_bfe_u32 v0, v42, 16, 1
	v_add3_u32 v0, v42, v0, s91
	s_waitcnt lgkmcnt(4)
	v_bfe_u32 v4, v44, 16, 1
	v_lshrrev_b32_e32 v0, 16, v0
	v_add3_u32 v4, v44, v4, s91
	v_and_or_b32 v39, v4, s35, v0
	s_waitcnt lgkmcnt(3)
	v_bfe_u32 v0, v46, 16, 1
	v_add3_u32 v0, v46, v0, s91
	s_waitcnt lgkmcnt(2)
	v_bfe_u32 v4, v48, 16, 1
	v_lshrrev_b32_e32 v0, 16, v0
	v_add3_u32 v4, v48, v4, s91
	v_and_or_b32 v40, v4, s35, v0
	s_waitcnt lgkmcnt(1)
	v_bfe_u32 v0, v50, 16, 1
	v_add3_u32 v0, v50, v0, s91
	s_waitcnt lgkmcnt(0)
	v_bfe_u32 v4, v52, 16, 1
	v_lshrrev_b32_e32 v0, 16, v0
	v_add3_u32 v4, v52, v4, s91
	v_and_or_b32 v41, v4, s35, v0
	v_or_b32_e32 v0, s0, v7
	v_mul_u32_u24_e32 v0, 0xb00, v0
	v_lshl_add_u64 v[2:3], v[10:11], 0, s[88:89]
	v_lshlrev_b32_e32 v0, 1, v0
	v_lshl_add_u64 v[54:55], v[2:3], 0, v[0:1]
	v_bfe_u32 v0, v31, 16, 1
	v_add3_u32 v0, v31, v0, s91
	v_bfe_u32 v4, v5, 16, 1
	v_lshrrev_b32_e32 v0, 16, v0
	v_add3_u32 v4, v5, v4, s91
	global_store_dwordx4 v[54:55], v[38:41], off sc1
	v_readlane_b32 s5, v252, 1
	v_readlane_b32 s6, v252, 2
	v_and_or_b32 v38, v4, s35, v0
	v_bfe_u32 v0, v43, 16, 1
	v_add3_u32 v0, v43, v0, s91
	v_bfe_u32 v4, v45, 16, 1
	v_lshrrev_b32_e32 v0, 16, v0
	v_add3_u32 v4, v45, v4, s91
	v_and_or_b32 v39, v4, s35, v0
	v_bfe_u32 v0, v47, 16, 1
	v_add3_u32 v0, v47, v0, s91
	v_bfe_u32 v4, v49, 16, 1
	v_lshrrev_b32_e32 v0, 16, v0
	v_add3_u32 v4, v49, v4, s91
	v_and_or_b32 v40, v4, s35, v0
	v_bfe_u32 v0, v51, 16, 1
	v_add3_u32 v0, v51, v0, s91
	v_bfe_u32 v4, v53, 16, 1
	v_lshrrev_b32_e32 v0, 16, v0
	v_add3_u32 v4, v53, v4, s91
	v_and_or_b32 v41, v4, s35, v0
	v_or_b32_e32 v0, s0, v32
	v_mul_u32_u24_e32 v0, 0xb00, v0
	v_lshlrev_b32_e32 v0, 1, v0
	v_lshl_add_u64 v[4:5], v[2:3], 0, v[0:1]
	global_store_dwordx4 v[4:5], v[38:41], off sc1
	ds_read2_b32 v[4:5], v37 offset0:16 offset1:24
	ds_read2_b32 v[30:31], v37 offset0:49 offset1:57
	ds_read2_b32 v[42:43], v37 offset0:82 offset1:90
	ds_read2_b32 v[44:45], v37 offset0:115 offset1:123
	ds_read2_b32 v[46:47], v37 offset0:148 offset1:156
	ds_read2_b32 v[48:49], v37 offset0:181 offset1:189
	ds_read2_b32 v[50:51], v37 offset0:214 offset1:222
	ds_read2_b32 v[52:53], v37 offset0:247 offset1:255
	s_waitcnt lgkmcnt(7)
	v_bfe_u32 v0, v4, 16, 1
	v_add3_u32 v0, v4, v0, s91
	s_waitcnt lgkmcnt(6)
	v_bfe_u32 v4, v30, 16, 1
	v_lshrrev_b32_e32 v0, 16, v0
	v_add3_u32 v4, v30, v4, s91
	v_and_or_b32 v38, v4, s35, v0
	s_waitcnt lgkmcnt(5)
	v_bfe_u32 v0, v42, 16, 1
	v_add3_u32 v0, v42, v0, s91
	s_waitcnt lgkmcnt(4)
	v_bfe_u32 v4, v44, 16, 1
	v_lshrrev_b32_e32 v0, 16, v0
	v_add3_u32 v4, v44, v4, s91
	v_and_or_b32 v39, v4, s35, v0
	s_waitcnt lgkmcnt(3)
	v_bfe_u32 v0, v46, 16, 1
	v_add3_u32 v0, v46, v0, s91
	s_waitcnt lgkmcnt(2)
	v_bfe_u32 v4, v48, 16, 1
	v_lshrrev_b32_e32 v0, 16, v0
	v_add3_u32 v4, v48, v4, s91
	v_and_or_b32 v40, v4, s35, v0
	s_waitcnt lgkmcnt(1)
	v_bfe_u32 v0, v50, 16, 1
	v_add3_u32 v0, v50, v0, s91
	s_waitcnt lgkmcnt(0)
	v_bfe_u32 v4, v52, 16, 1
	v_lshrrev_b32_e32 v0, 16, v0
	v_add3_u32 v4, v52, v4, s91
	v_and_or_b32 v41, v4, s35, v0
	v_or_b32_e32 v0, s0, v34
	v_mul_u32_u24_e32 v0, 0xb00, v0
	v_lshlrev_b32_e32 v0, 1, v0
	v_lshl_add_u64 v[54:55], v[2:3], 0, v[0:1]
	v_bfe_u32 v0, v5, 16, 1
	v_add3_u32 v0, v5, v0, s91
	v_bfe_u32 v4, v31, 16, 1
	v_lshrrev_b32_e32 v0, 16, v0
	v_add3_u32 v4, v31, v4, s91
	global_store_dwordx4 v[54:55], v[38:41], off sc1
	v_readlane_b32 s7, v252, 3
	v_readlane_b32 s8, v252, 4
	v_and_or_b32 v38, v4, s35, v0
	v_bfe_u32 v0, v43, 16, 1
	v_add3_u32 v0, v43, v0, s91
	v_bfe_u32 v4, v45, 16, 1
	v_lshrrev_b32_e32 v0, 16, v0
	v_add3_u32 v4, v45, v4, s91
	v_and_or_b32 v39, v4, s35, v0
	v_bfe_u32 v0, v47, 16, 1
	v_add3_u32 v0, v47, v0, s91
	v_bfe_u32 v4, v49, 16, 1
	v_lshrrev_b32_e32 v0, 16, v0
	v_add3_u32 v4, v49, v4, s91
	v_and_or_b32 v40, v4, s35, v0
	v_bfe_u32 v0, v51, 16, 1
	v_add3_u32 v0, v51, v0, s91
	v_bfe_u32 v4, v53, 16, 1
	v_lshrrev_b32_e32 v0, 16, v0
	v_add3_u32 v4, v53, v4, s91
	v_and_or_b32 v41, v4, s35, v0
	v_or_b32_e32 v0, s0, v35
	v_mul_u32_u24_e32 v0, 0xb00, v0
	v_lshlrev_b32_e32 v0, 1, v0
	v_lshl_add_u64 v[2:3], v[2:3], 0, v[0:1]
	global_store_dwordx4 v[2:3], v[38:41], off sc1
	s_waitcnt lgkmcnt(0)
	v_readlane_b32 s9, v252, 5
	v_readlane_b32 s10, v252, 6
	v_readlane_b32 s11, v252, 7
	v_readlane_b32 s12, v252, 8
	v_readlane_b32 s13, v252, 9
	v_readlane_b32 s14, v252, 10
	v_readlane_b32 s15, v252, 11
	v_readlane_b32 s16, v252, 12
	v_readlane_b32 s17, v252, 13
	v_readlane_b32 s18, v252, 14
	v_readlane_b32 s19, v252, 15

; template <bool HASG>
; __device__ __forceinline__ void tr_item(const float* W, int K, int N, bf16* WT, int rowmode, const float* g, LAS float* scr, int item, int lane) {
;     const int nblk = N / 32, kb = item / nblk, nb = item % nblk, k0 = 64 * kb, n0 = 32 * nb;
;     const float* wp = W + (size_t)(k0 + (lane >> 5)) * N + n0 + (lane & 31);
;     const int c = lane & 7;
;     float v[32];
; #pragma unroll
;     for (int i = 0; i < 32; ++i) v[i] = wp[(size_t)(2 * i) * N];
;     f32x4 g0 = (f32x4){1.f, 1.f, 1.f, 1.f}, g1 = g0;
;     if (HASG) { g0 = *(const f32x4*)(g + k0 + 8 * c); g1 = *(const f32x4*)(g + k0 + 8 * c + 4); }
;     asm volatile("" ::: "memory");
; #pragma unroll
;     for (int i = 0; i < 32; ++i) scr[(2 * i + (lane >> 5)) * 33 + (lane & 31)] = v[i];
; __device__ __forceinline__ void convert_items(const Args& a, LAS unsigned char* lds, int l, int it_lo, int it_hi, int gw, int NGW, int wave, int lane) {
;     ...
;         if (r < I_G) { tr_item<true>(a.in[21] + o_gu, D, FF, wl + W_GU2, 2, a.in[19] + l * D, scr, r, lane); continue; } r -= I_G;
.LBB0_584:
	s_andn2_b64 vcc, exec, s[0:1]
	s_cbranch_vccnz .LBB0_586
	s_add_i32 s0, s28, 0xe480
	s_and_b32 s1, s0, 0xffff
	s_mul_i32 s1, s1, 0xba2f
	s_lshr_b32 s38, s1, 16
	s_lshr_b32 s1, s1, 22
	s_mulk_i32 s1, 0x58
	s_sub_i32 s0, s0, s1
	s_and_b32 s1, s38, 0xffc0
	v_or_b32_e32 v0, s1, v33
	v_mul_u32_u24_e32 v0, 0xb00, v0
	v_readlane_b32 s4, v252, 32
	s_and_b32 s39, s0, 0xffff
	v_lshlrev_b32_e32 v0, 2, v0
	v_readlane_b32 s14, v252, 42
	v_readlane_b32 s15, v252, 43
	v_readlane_b32 s5, v252, 33
	v_readlane_b32 s6, v252, 34
	v_readlane_b32 s7, v252, 35
	v_readlane_b32 s8, v252, 36
	v_readlane_b32 s9, v252, 37
	v_readlane_b32 s10, v252, 38
	v_readlane_b32 s11, v252, 39
	v_readlane_b32 s12, v252, 40
	v_readlane_b32 s13, v252, 41
	v_readlane_b32 s16, v252, 44
	v_readlane_b32 s17, v252, 45
	v_readlane_b32 s18, v252, 46
	v_readlane_b32 s19, v252, 47
	v_lshl_add_u64 v[2:3], s[14:15], 0, v[0:1]
	s_lshl_b32 s88, s39, 7
	v_readlane_b32 s4, v252, 0
	v_lshl_add_u64 v[2:3], v[2:3], 0, s[88:89]
	v_lshlrev_b32_e32 v0, 2, v6
	v_lshl_add_u64 v[2:3], v[2:3], 0, v[0:1]
	s_movk_i32 s4, 0x5000
	v_add_co_u32_e32 v4, vcc, s4, v2
	s_mov_b32 s4, 0x1b000
	s_nop 0
	v_addc_co_u32_e32 v5, vcc, 0, v3, vcc
	v_add_co_u32_e32 v30, vcc, s90, v2
	s_lshl_b32 s88, s1, 2
	s_nop 0
	v_addc_co_u32_e32 v31, vcc, 0, v3, vcc
	v_add_co_u32_e32 v38, vcc, s70, v2
	s_lshl_b32 s38, s0, 5
	s_nop 0
	v_addc_co_u32_e32 v39, vcc, 0, v3, vcc
	v_add_co_u32_e32 v40, vcc, s71, v2
	s_lshl_b32 s0, s0, 6
	s_nop 0
	v_addc_co_u32_e32 v41, vcc, 0, v3, vcc
	v_add_co_u32_e32 v42, vcc, s4, v2
	s_mov_b32 s4, 0x21000
	s_nop 0
	v_addc_co_u32_e32 v43, vcc, 0, v3, vcc
	v_add_co_u32_e32 v44, vcc, s4, v2
	s_mov_b32 s4, 0x26000
	s_nop 0
	v_addc_co_u32_e32 v45, vcc, 0, v3, vcc
	v_add_co_u32_e32 v46, vcc, s4, v2
	s_mov_b32 s4, 0x2c000
	s_nop 0
	v_addc_co_u32_e32 v47, vcc, 0, v3, vcc
	global_load_dword v0, v[2:3], off
	global_load_dword v29, v[4:5], off offset:2048
	global_load_dword v50, v[30:31], off
	global_load_dword v51, v[38:39], off offset:2048
	global_load_dword v52, v[40:41], off
	global_load_dword v53, v[42:43], off offset:2048
	global_load_dword v54, v[44:45], off
	global_load_dword v55, v[46:47], off offset:2048
	v_add_co_u32_e32 v4, vcc, s4, v2
	s_mov_b32 s4, 0x31000
	s_nop 0
	v_addc_co_u32_e32 v5, vcc, 0, v3, vcc
	v_add_co_u32_e32 v30, vcc, s4, v2
	s_mov_b32 s4, 0x37000
	s_nop 0
	v_addc_co_u32_e32 v31, vcc, 0, v3, vcc
	v_add_co_u32_e32 v38, vcc, s4, v2
	s_mov_b32 s4, 0x3c000
	s_nop 0
	v_addc_co_u32_e32 v39, vcc, 0, v3, vcc
	v_add_co_u32_e32 v40, vcc, s4, v2
	s_mov_b32 s4, 0x42000
	s_nop 0
	v_addc_co_u32_e32 v41, vcc, 0, v3, vcc
	v_add_co_u32_e32 v42, vcc, s4, v2
	s_mov_b32 s4, 0x47000
	s_nop 0
	v_addc_co_u32_e32 v43, vcc, 0, v3, vcc
	v_add_co_u32_e32 v44, vcc, s4, v2
	s_mov_b32 s4, 0x4d000
	s_nop 0
	v_addc_co_u32_e32 v45, vcc, 0, v3, vcc
	v_add_co_u32_e32 v46, vcc, s4, v2
	s_mov_b32 s4, 0x52000
	s_nop 0
	v_addc_co_u32_e32 v47, vcc, 0, v3, vcc
	v_add_co_u32_e32 v48, vcc, s4, v2
	s_mov_b32 s4, 0x58000
	s_nop 0
	v_addc_co_u32_e32 v49, vcc, 0, v3, vcc
	global_load_dword v56, v[4:5], off
	global_load_dword v57, v[30:31], off offset:2048
	global_load_dword v58, v[38:39], off
	global_load_dword v59, v[40:41], off offset:2048
	global_load_dword v60, v[42:43], off
	global_load_dword v61, v[44:45], off offset:2048
	global_load_dword v62, v[46:47], off
	global_load_dword v63, v[48:49], off offset:2048
	v_add_co_u32_e32 v4, vcc, s4, v2
	s_mov_b32 s4, 0x5d000
	s_nop 0
	v_addc_co_u32_e32 v5, vcc, 0, v3, vcc
	v_add_co_u32_e32 v30, vcc, s4, v2
	s_mov_b32 s4, 0x63000
	s_nop 0
	v_addc_co_u32_e32 v31, vcc, 0, v3, vcc
	v_add_co_u32_e32 v38, vcc, s4, v2
	s_mov_b32 s4, 0x68000
	s_nop 0
	v_addc_co_u32_e32 v39, vcc, 0, v3, vcc
	v_add_co_u32_e32 v40, vcc, s4, v2
	s_mov_b32 s4, 0x6e000
	s_nop 0
	v_addc_co_u32_e32 v41, vcc, 0, v3, vcc
	v_add_co_u32_e32 v42, vcc, s4, v2
	s_mov_b32 s4, 0x73000
	s_nop 0
	v_addc_co_u32_e32 v43, vcc, 0, v3, vcc
	v_add_co_u32_e32 v44, vcc, s4, v2
	s_mov_b32 s4, 0x79000
	s_nop 0
	v_addc_co_u32_e32 v45, vcc, 0, v3, vcc
	v_add_co_u32_e32 v46, vcc, s4, v2
	s_mov_b32 s4, 0x7e000
	s_nop 0
	v_addc_co_u32_e32 v47, vcc, 0, v3, vcc
	v_add_co_u32_e32 v48, vcc, s4, v2
	s_mov_b32 s4, 0x84000
	s_nop 0
	v_addc_co_u32_e32 v49, vcc, 0, v3, vcc
	global_load_dword v64, v[4:5], off
	global_load_dword v65, v[30:31], off offset:2048
	global_load_dword v66, v[38:39], off
	global_load_dword v67, v[40:41], off offset:2048
	global_load_dword v68, v[42:43], off
	global_load_dword v69, v[44:45], off offset:2048
	global_load_dword v70, v[46:47], off
	s_nop 0
	global_load_dword v48, v[48:49], off offset:2048
	v_add_co_u32_e32 v4, vcc, s4, v2
	s_mov_b32 s4, 0x89000
	s_nop 0
	v_addc_co_u32_e32 v5, vcc, 0, v3, vcc
	v_add_co_u32_e32 v30, vcc, s4, v2
	s_mov_b32 s4, 0x8f000
	s_nop 0
	v_addc_co_u32_e32 v31, vcc, 0, v3, vcc
	v_add_co_u32_e32 v38, vcc, s4, v2
	s_mov_b32 s4, 0x94000
	s_nop 0
	v_addc_co_u32_e32 v39, vcc, 0, v3, vcc
	v_add_co_u32_e32 v40, vcc, s4, v2
	s_mov_b32 s4, 0x9a000
	s_nop 0
	v_addc_co_u32_e32 v41, vcc, 0, v3, vcc
	v_add_co_u32_e32 v42, vcc, s4, v2
	s_mov_b32 s4, 0x9f000
	s_nop 0
	v_addc_co_u32_e32 v43, vcc, 0, v3, vcc
	v_add_co_u32_e32 v44, vcc, s4, v2
	s_mov_b32 s4, 0xa5000
	s_nop 0
	v_addc_co_u32_e32 v45, vcc, 0, v3, vcc
	v_add_co_u32_e32 v46, vcc, s4, v2
	s_mov_b32 s4, 0xaa000
	s_nop 0
	v_addc_co_u32_e32 v47, vcc, 0, v3, vcc
	v_add_co_u32_e32 v2, vcc, s4, v2
	s_and_b32 s0, s0, 0x1f00
	s_nop 0
	v_addc_co_u32_e32 v3, vcc, 0, v3, vcc
	global_load_dword v49, v[4:5], off
	s_nop 0
	global_load_dword v30, v[30:31], off offset:2048
	s_nop 0
	global_load_dword v31, v[38:39], off
	global_load_dword v71, v[40:41], off offset:2048
	s_nop 0
	global_load_dword v42, v[42:43], off
	s_nop 0
	global_load_dword v43, v[44:45], off offset:2048
	s_nop 0
	global_load_dword v44, v[46:47], off
	global_load_dword v45, v[2:3], off offset:2048
	v_lshl_add_u64 v[2:3], v[22:23], 0, s[88:89]
	global_load_dwordx4 v[38:41], v[2:3], off
	s_nop 0
	global_load_dwordx4 v[2:5], v[2:3], off offset:16
	s_waitcnt vmcnt(32)
; #define LAS __attribute__((address_space(3)))
; __device__ __forceinline__ unsigned pk2(float lo, float hi) { return f2bf(lo) | (f2bf(hi) << 16); }
; #define LDS_WAVE_SYNC() asm volatile("s_waitcnt lgkmcnt(0)" ::: "memory")
; template <bool HASG>
; __device__ __forceinline__ void tr_item(const float* W, int K, int N, bf16* WT, int rowmode, const float* g, LAS float* scr, int item, int lane) {
;     ...
;     for (int i = 0; i < 32; ++i) scr[(2 * i + (lane >> 5)) * 33 + (lane & 31)] = v[i];
;     LDS_WAVE_SYNC();
;     const int drow0 = rowmode == 0 ? n0 : ((n0 >> 7) * 256 + (n0 & 127) + (rowmode == 2 ? 128 : 0));
; #pragma unroll
;     for (int j = 0; j < 4; ++j) { const int n = (lane >> 3) + 8 * j; const LAS float* s = scr + (8 * c) * 33 + n;
;         u32x4 o; o.x = pk2(s[0 * 33] * g0.x, s[1 * 33] * g0.y); o.y = pk2(s[2 * 33] * g0.z, s[3 * 33] * g0.w);
;         o.z = pk2(s[4 * 33] * g1.x, s[5 * 33] * g1.y); o.w = pk2(s[6 * 33] * g1.z, s[7 * 33] * g1.w);
;         *(u32x4*)(WT + (size_t)(drow0 + n) * K + k0 + 8 * c) = o; }
	ds_write2_b32 v36, v0, v29 offset1:66
	s_waitcnt vmcnt(30)
	ds_write2_b32 v36, v50, v51 offset0:132 offset1:198
	v_add_u32_e32 v0, 0x400, v36
	s_waitcnt vmcnt(28)
	ds_write2_b32 v0, v52, v53 offset0:8 offset1:74
	s_waitcnt vmcnt(26)
	ds_write2_b32 v0, v54, v55 offset0:140 offset1:206
	v_add_u32_e32 v0, 0x800, v36
	s_waitcnt vmcnt(24)
	ds_write2_b32 v0, v56, v57 offset0:16 offset1:82
	s_waitcnt vmcnt(22)
	ds_write2_b32 v0, v58, v59 offset0:148 offset1:214
	v_add_u32_e32 v0, 0xc00, v36
	s_waitcnt vmcnt(20)
	ds_write2_b32 v0, v60, v61 offset0:24 offset1:90
	s_waitcnt vmcnt(18)
	ds_write2_b32 v0, v62, v63 offset0:156 offset1:222
	v_add_u32_e32 v0, 0x1000, v36
	s_waitcnt vmcnt(16)
	ds_write2_b32 v0, v64, v65 offset0:32 offset1:98
	s_waitcnt vmcnt(14)
	ds_write2_b32 v0, v66, v67 offset0:164 offset1:230
	v_add_u32_e32 v0, 0x1400, v36
	s_waitcnt vmcnt(12)
	ds_write2_b32 v0, v68, v69 offset0:40 offset1:106
	s_waitcnt vmcnt(10)
	ds_write2_b32 v0, v70, v48 offset0:172 offset1:238
	v_add_u32_e32 v0, 0x1800, v36
	s_waitcnt vmcnt(8)
	ds_write2_b32 v0, v49, v30 offset0:48 offset1:114
	s_waitcnt vmcnt(6)
	ds_write2_b32 v0, v31, v71 offset0:180 offset1:246
	v_add_u32_e32 v0, 0x1c00, v36
	s_waitcnt vmcnt(4)
	ds_write2_b32 v0, v42, v43 offset0:56 offset1:122
	s_waitcnt vmcnt(2)
	ds_write2_b32 v0, v44, v45 offset0:188 offset1:254
	s_waitcnt lgkmcnt(0)
	ds_read2_b32 v[46:47], v37 offset0:33 offset1:41
	ds_read2_b32 v[48:49], v37 offset1:8
	ds_read2_b32 v[50:51], v37 offset0:66 offset1:74
	ds_read2_b32 v[52:53], v37 offset0:99 offset1:107
	ds_read2_b32 v[56:57], v37 offset0:132 offset1:140
	ds_read2_b32 v[58:59], v37 offset0:165 offset1:173
	ds_read2_b32 v[60:61], v37 offset0:198 offset1:206
	ds_read2_b32 v[62:63], v37 offset0:231 offset1:239
	s_waitcnt vmcnt(1)
	v_mov_b32_e32 v54, v38
	v_mov_b32_e32 v55, v40
	v_mov_b32_e32 v40, v39
	s_waitcnt lgkmcnt(7)
	v_mov_b32_e32 v38, v46
	s_waitcnt lgkmcnt(4)
	v_mov_b32_e32 v39, v52
	v_pk_mul_f32 v[38:39], v[40:41], v[38:39]
	s_waitcnt vmcnt(0)
	v_mov_b32_e32 v64, v2
	v_mov_b32_e32 v65, v4
	s_waitcnt lgkmcnt(3)
	v_mov_b32_e32 v44, v56
	s_waitcnt lgkmcnt(1)
	v_mov_b32_e32 v45, v60
	v_mov_b32_e32 v4, v3
	v_mov_b32_e32 v2, v58
	s_waitcnt lgkmcnt(0)
	v_mov_b32_e32 v3, v62
	v_mov_b32_e32 v42, v48
	v_mov_b32_e32 v43, v50
	v_pk_mul_f32 v[44:45], v[64:65], v[44:45]
	v_pk_mul_f32 v[2:3], v[4:5], v[2:3]
	v_bfe_u32 v48, v38, 16, 1
	s_and_b32 s38, s38, 0x60
	v_pk_mul_f32 v[42:43], v[54:55], v[42:43]
	v_bfe_u32 v29, v2, 16, 1
	v_add3_u32 v38, v38, v48, s91
	v_bfe_u32 v48, v45, 16, 1
	s_or_b32 s0, s38, s0
	v_bfe_u32 v0, v3, 16, 1
	v_bfe_u32 v46, v39, 16, 1
	v_add3_u32 v2, v2, v29, s91
	v_bfe_u32 v29, v43, 16, 1
	v_add3_u32 v45, v45, v48, s91
	s_bitset1_b32 s0, 7
	v_add3_u32 v39, v39, v46, s91
	v_add3_u32 v0, v3, v0, s91
	v_bfe_u32 v3, v42, 16, 1
	v_bfe_u32 v46, v44, 16, 1
	v_add3_u32 v29, v43, v29, s91
	v_lshrrev_b32_e32 v43, 16, v45
	s_lshl_b32 s88, s1, 1
	v_add3_u32 v44, v44, v46, s91
	v_add3_u32 v3, v42, v3, s91
	v_and_or_b32 v45, v0, s35, v43
	v_or_b32_e32 v0, s0, v7
	v_lshl_add_u64 v[30:31], v[12:13], 0, s[88:89]
	v_lshrrev_b32_e32 v3, 16, v3
	v_lshrrev_b32_e32 v29, 16, v29
	v_lshrrev_b32_e32 v42, 16, v44
	v_lshlrev_b32_e32 v0, 11, v0
	v_mov_b32_e32 v52, v47
	v_and_or_b32 v44, v2, s35, v42
	v_and_or_b32 v43, v39, s35, v29
	v_and_or_b32 v42, v38, s35, v3
	v_lshl_add_u64 v[2:3], v[30:31], 0, v[0:1]
	v_pk_mul_f32 v[38:39], v[40:41], v[52:53]
	v_mov_b32_e32 v60, v57
	global_store_dwordx4 v[2:3], v[42:45], off sc1
	v_mov_b32_e32 v62, v59
	v_bfe_u32 v47, v38, 16, 1
	v_pk_mul_f32 v[42:43], v[64:65], v[60:61]
	v_mov_b32_e32 v50, v49
	v_pk_mul_f32 v[44:45], v[4:5], v[62:63]
	v_add3_u32 v38, v38, v47, s91
	v_bfe_u32 v47, v43, 16, 1
	v_pk_mul_f32 v[2:3], v[54:55], v[50:51]
	v_bfe_u32 v0, v45, 16, 1
	v_bfe_u32 v29, v44, 16, 1
	v_bfe_u32 v46, v39, 16, 1
	v_add3_u32 v43, v43, v47, s91
	v_add3_u32 v39, v39, v46, s91
	v_add3_u32 v29, v44, v29, s91
	v_add3_u32 v0, v45, v0, s91
	v_bfe_u32 v44, v2, 16, 1
	v_bfe_u32 v45, v3, 16, 1
	v_bfe_u32 v46, v42, 16, 1
	v_lshrrev_b32_e32 v43, 16, v43
	v_add3_u32 v42, v42, v46, s91
	v_add3_u32 v3, v3, v45, s91
	v_add3_u32 v2, v2, v44, s91
	v_and_or_b32 v45, v0, s35, v43
	v_or_b32_e32 v0, s0, v32
	v_lshrrev_b32_e32 v2, 16, v2
	v_lshrrev_b32_e32 v3, 16, v3
	v_lshrrev_b32_e32 v42, 16, v42
	v_lshlrev_b32_e32 v0, 11, v0
	v_and_or_b32 v44, v29, s35, v42
	v_and_or_b32 v43, v39, s35, v3
	v_and_or_b32 v42, v38, s35, v2
	v_lshl_add_u64 v[2:3], v[30:31], 0, v[0:1]
	ds_read2_b32 v[38:39], v37 offset0:16 offset1:24
	ds_read2_b32 v[46:47], v37 offset0:82 offset1:90
	global_store_dwordx4 v[2:3], v[42:45], off sc1
	ds_read2_b32 v[2:3], v37 offset0:49 offset1:57
	ds_read2_b32 v[48:49], v37 offset0:115 offset1:123
	ds_read2_b32 v[50:51], v37 offset0:148 offset1:156
	ds_read2_b32 v[52:53], v37 offset0:214 offset1:222
	ds_read2_b32 v[56:57], v37 offset0:181 offset1:189
	ds_read2_b32 v[58:59], v37 offset0:247 offset1:255
	s_waitcnt lgkmcnt(7)
; #define LAS __attribute__((address_space(3)))
; __device__ __forceinline__ unsigned pk2(float lo, float hi) { return f2bf(lo) | (f2bf(hi) << 16); }
; #define LDS_WAVE_SYNC() asm volatile("s_waitcnt lgkmcnt(0)" ::: "memory")
; template <bool HASG>
; __device__ __forceinline__ void tr_item(const float* W, int K, int N, bf16* WT, int rowmode, const float* g, LAS float* scr, int item, int lane) {
;     ...
;     for (int j = 0; j < 4; ++j) { const int n = (lane >> 3) + 8 * j; const LAS float* s = scr + (8 * c) * 33 + n;
;         u32x4 o; o.x = pk2(s[0 * 33] * g0.x, s[1 * 33] * g0.y); o.y = pk2(s[2 * 33] * g0.z, s[3 * 33] * g0.w);
;         o.z = pk2(s[4 * 33] * g1.x, s[5 * 33] * g1.y); o.w = pk2(s[6 * 33] * g1.z, s[7 * 33] * g1.w);
;         *(u32x4*)(WT + (size_t)(drow0 + n) * K + k0 + 8 * c) = o; }
;     LDS_WAVE_SYNC();
	v_mov_b32_e32 v42, v38
	s_waitcnt lgkmcnt(5)
	v_mov_b32_e32 v44, v2
	s_waitcnt lgkmcnt(4)
	v_mov_b32_e32 v45, v48
	s_waitcnt lgkmcnt(3)
	v_mov_b32_e32 v60, v50
	s_waitcnt lgkmcnt(2)
	v_mov_b32_e32 v61, v52
	v_mov_b32_e32 v43, v46
	v_pk_mul_f32 v[44:45], v[40:41], v[44:45]
	v_pk_mul_f32 v[60:61], v[64:65], v[60:61]
	s_waitcnt lgkmcnt(1)
	v_mov_b32_e32 v62, v56
	s_waitcnt lgkmcnt(0)
	v_mov_b32_e32 v63, v58
	v_pk_mul_f32 v[42:43], v[54:55], v[42:43]
	v_pk_mul_f32 v[62:63], v[4:5], v[62:63]
	v_bfe_u32 v29, v45, 16, 1
	v_bfe_u32 v48, v61, 16, 1
	v_bfe_u32 v0, v63, 16, 1
	v_bfe_u32 v38, v44, 16, 1
	v_add3_u32 v29, v45, v29, s91
	v_bfe_u32 v45, v43, 16, 1
	v_add3_u32 v48, v61, v48, s91
	v_add3_u32 v38, v44, v38, s91
	v_add3_u32 v0, v63, v0, s91
	v_bfe_u32 v44, v42, 16, 1
	v_bfe_u32 v46, v60, 16, 1
	v_add3_u32 v43, v43, v45, s91
	v_lshrrev_b32_e32 v45, 16, v48
	v_bfe_u32 v2, v62, 16, 1
	v_add3_u32 v46, v60, v46, s91
	v_add3_u32 v42, v42, v44, s91
	v_and_or_b32 v45, v0, s35, v45
	v_or_b32_e32 v0, s0, v34
	v_add3_u32 v2, v62, v2, s91
	v_lshrrev_b32_e32 v42, 16, v42
	v_lshrrev_b32_e32 v43, 16, v43
	v_lshrrev_b32_e32 v44, 16, v46
	v_lshlrev_b32_e32 v0, 11, v0
	v_mov_b32_e32 v48, v3
	v_mov_b32_e32 v58, v57
	v_and_or_b32 v44, v2, s35, v44
	v_and_or_b32 v43, v29, s35, v43
	v_and_or_b32 v42, v38, s35, v42
	v_lshl_add_u64 v[60:61], v[30:31], 0, v[0:1]
	v_mov_b32_e32 v46, v39
	v_pk_mul_f32 v[2:3], v[40:41], v[48:49]
	v_mov_b32_e32 v52, v51
	v_pk_mul_f32 v[4:5], v[4:5], v[58:59]
	global_store_dwordx4 v[60:61], v[42:45], off sc1
	v_pk_mul_f32 v[38:39], v[54:55], v[46:47]
	v_pk_mul_f32 v[40:41], v[64:65], v[52:53]
	v_bfe_u32 v0, v5, 16, 1
	v_bfe_u32 v43, v2, 16, 1
	v_add3_u32 v2, v2, v43, s91
	v_add3_u32 v0, v5, v0, s91
	v_bfe_u32 v5, v38, 16, 1
	v_bfe_u32 v43, v41, 16, 1
	v_bfe_u32 v29, v4, 16, 1
	v_bfe_u32 v42, v3, 16, 1
	v_add3_u32 v41, v41, v43, s91
	v_add3_u32 v5, v38, v5, s91
	v_add3_u32 v3, v3, v42, s91
	v_add3_u32 v4, v4, v29, s91
	v_bfe_u32 v29, v39, 16, 1
	v_bfe_u32 v42, v40, 16, 1
	v_lshrrev_b32_e32 v38, 16, v5
	v_lshrrev_b32_e32 v5, 16, v41
	v_add3_u32 v40, v40, v42, s91
	v_add3_u32 v29, v39, v29, s91
	v_and_or_b32 v5, v0, s35, v5
	v_or_b32_e32 v0, s0, v35
	v_lshrrev_b32_e32 v29, 16, v29
	v_lshrrev_b32_e32 v39, 16, v40
	v_lshlrev_b32_e32 v0, 11, v0
	v_and_or_b32 v4, v4, s35, v39
	v_and_or_b32 v3, v3, s35, v29
	v_and_or_b32 v2, v2, s35, v38
	v_lshl_add_u64 v[30:31], v[30:31], 0, v[0:1]
	global_store_dwordx4 v[30:31], v[2:5], off sc1
	s_waitcnt lgkmcnt(0)
	v_readlane_b32 s5, v252, 1
	v_readlane_b32 s6, v252, 2
	v_readlane_b32 s7, v252, 3
	v_readlane_b32 s8, v252, 4
	v_readlane_b32 s9, v252, 5
	v_readlane_b32 s10, v252, 6
	v_readlane_b32 s11, v252, 7
	v_readlane_b32 s12, v252, 8
	v_readlane_b32 s13, v252, 9
	v_readlane_b32 s14, v252, 10
	v_readlane_b32 s15, v252, 11
	v_readlane_b32 s16, v252, 12
	v_readlane_b32 s17, v252, 13
	v_readlane_b32 s18, v252, 14
	v_readlane_b32 s19, v252, 15

; template <bool HASG>
; __device__ __forceinline__ void tr_item(const float* W, int K, int N, bf16* WT, int rowmode, const float* g, LAS float* scr, int item, int lane) {
;     const int nblk = N / 32, kb = item / nblk, nb = item % nblk, k0 = 64 * kb, n0 = 32 * nb;
;     const float* wp = W + (size_t)(k0 + (lane >> 5)) * N + n0 + (lane & 31);
;     const int c = lane & 7;
;     float v[32];
; #pragma unroll
;     for (int i = 0; i < 32; ++i) v[i] = wp[(size_t)(2 * i) * N];
;     f32x4 g0 = (f32x4){1.f, 1.f, 1.f, 1.f}, g1 = g0;
;     if (HASG) { g0 = *(const f32x4*)(g + k0 + 8 * c); g1 = *(const f32x4*)(g + k0 + 8 * c + 4); }
;     asm volatile("" ::: "memory");
; #pragma unroll
;     for (int i = 0; i < 32; ++i) scr[(2 * i + (lane >> 5)) * 33 + (lane & 31)] = v[i];
; __device__ __forceinline__ void convert_items(const Args& a, LAS unsigned char* lds, int l, int it_lo, int it_hi, int gw, int NGW, int wave, int lane) {
;     ...
;         if (r < I_G) { tr_item<true>(a.in[20] + o_gu, D, FF, wl + W_GU2, 1, a.in[19] + l * D, scr, r, lane); continue; } r -= I_G;
.LBB0_587:
	s_andn2_b64 vcc, exec, s[0:1]
	s_cbranch_vccnz .LBB0_589
	s_add_i32 s0, s28, 0xea00
	s_and_b32 s1, s0, 0xffff
	s_mul_i32 s1, s1, 0xba2f
	s_lshr_b32 s38, s1, 16
	s_lshr_b32 s1, s1, 22
	s_mulk_i32 s1, 0x58
	s_sub_i32 s0, s0, s1
	s_and_b32 s1, s38, 0xffc0
	v_or_b32_e32 v0, s1, v33
	v_mul_u32_u24_e32 v0, 0xb00, v0
	v_readlane_b32 s4, v252, 32
	s_and_b32 s39, s0, 0xffff
	v_lshlrev_b32_e32 v0, 2, v0
	v_readlane_b32 s12, v252, 40
	v_readlane_b32 s13, v252, 41
	v_readlane_b32 s5, v252, 33
	v_readlane_b32 s6, v252, 34
	v_readlane_b32 s7, v252, 35
	v_readlane_b32 s8, v252, 36
	v_readlane_b32 s9, v252, 37
	v_readlane_b32 s10, v252, 38
	v_readlane_b32 s11, v252, 39
	v_readlane_b32 s14, v252, 42
	v_readlane_b32 s15, v252, 43
	v_readlane_b32 s16, v252, 44
	v_readlane_b32 s17, v252, 45
	v_readlane_b32 s18, v252, 46
	v_readlane_b32 s19, v252, 47
	v_lshl_add_u64 v[2:3], s[12:13], 0, v[0:1]
	s_lshl_b32 s88, s39, 7
	v_readlane_b32 s4, v252, 0
	v_lshl_add_u64 v[2:3], v[2:3], 0, s[88:89]
	v_lshlrev_b32_e32 v0, 2, v6
	v_lshl_add_u64 v[2:3], v[2:3], 0, v[0:1]
	s_movk_i32 s4, 0x5000
	v_add_co_u32_e32 v4, vcc, s4, v2
	s_mov_b32 s4, 0x1b000
	s_nop 0
	v_addc_co_u32_e32 v5, vcc, 0, v3, vcc
	v_add_co_u32_e32 v30, vcc, s90, v2
	s_lshl_b32 s88, s1, 2
	s_nop 0
	v_addc_co_u32_e32 v31, vcc, 0, v3, vcc
	v_add_co_u32_e32 v38, vcc, s70, v2
	s_lshl_b32 s38, s0, 5
	s_nop 0
	v_addc_co_u32_e32 v39, vcc, 0, v3, vcc
	v_add_co_u32_e32 v40, vcc, s71, v2
	s_lshl_b32 s0, s0, 6
	s_nop 0
	v_addc_co_u32_e32 v41, vcc, 0, v3, vcc
	v_add_co_u32_e32 v42, vcc, s4, v2
	s_mov_b32 s4, 0x21000
	s_nop 0
	v_addc_co_u32_e32 v43, vcc, 0, v3, vcc
	v_add_co_u32_e32 v44, vcc, s4, v2
	s_mov_b32 s4, 0x26000
	s_nop 0
	v_addc_co_u32_e32 v45, vcc, 0, v3, vcc
	v_add_co_u32_e32 v46, vcc, s4, v2
	s_mov_b32 s4, 0x2c000
	s_nop 0
	v_addc_co_u32_e32 v47, vcc, 0, v3, vcc
	global_load_dword v0, v[2:3], off
	global_load_dword v29, v[4:5], off offset:2048
	global_load_dword v50, v[30:31], off
	global_load_dword v51, v[38:39], off offset:2048
	global_load_dword v52, v[40:41], off
	global_load_dword v53, v[42:43], off offset:2048
	global_load_dword v54, v[44:45], off
	global_load_dword v55, v[46:47], off offset:2048
	v_add_co_u32_e32 v4, vcc, s4, v2
	s_mov_b32 s4, 0x31000
	s_nop 0
	v_addc_co_u32_e32 v5, vcc, 0, v3, vcc
	v_add_co_u32_e32 v30, vcc, s4, v2
	s_mov_b32 s4, 0x37000
	s_nop 0
	v_addc_co_u32_e32 v31, vcc, 0, v3, vcc
	v_add_co_u32_e32 v38, vcc, s4, v2
	s_mov_b32 s4, 0x3c000
	s_nop 0
	v_addc_co_u32_e32 v39, vcc, 0, v3, vcc
	v_add_co_u32_e32 v40, vcc, s4, v2
	s_mov_b32 s4, 0x42000
	s_nop 0
	v_addc_co_u32_e32 v41, vcc, 0, v3, vcc
	v_add_co_u32_e32 v42, vcc, s4, v2
	s_mov_b32 s4, 0x47000
	s_nop 0
	v_addc_co_u32_e32 v43, vcc, 0, v3, vcc
	v_add_co_u32_e32 v44, vcc, s4, v2
	s_mov_b32 s4, 0x4d000
	s_nop 0
	v_addc_co_u32_e32 v45, vcc, 0, v3, vcc
	v_add_co_u32_e32 v46, vcc, s4, v2
	s_mov_b32 s4, 0x52000
	s_nop 0
	v_addc_co_u32_e32 v47, vcc, 0, v3, vcc
	v_add_co_u32_e32 v48, vcc, s4, v2
	s_mov_b32 s4, 0x58000
	s_nop 0
	v_addc_co_u32_e32 v49, vcc, 0, v3, vcc
	global_load_dword v56, v[4:5], off
	global_load_dword v57, v[30:31], off offset:2048
	global_load_dword v58, v[38:39], off
	global_load_dword v59, v[40:41], off offset:2048
	global_load_dword v60, v[42:43], off
	global_load_dword v61, v[44:45], off offset:2048
	global_load_dword v62, v[46:47], off
	global_load_dword v63, v[48:49], off offset:2048
	v_add_co_u32_e32 v4, vcc, s4, v2
	s_mov_b32 s4, 0x5d000
	s_nop 0
	v_addc_co_u32_e32 v5, vcc, 0, v3, vcc
	v_add_co_u32_e32 v30, vcc, s4, v2
	s_mov_b32 s4, 0x63000
	s_nop 0
	v_addc_co_u32_e32 v31, vcc, 0, v3, vcc
	v_add_co_u32_e32 v38, vcc, s4, v2
	s_mov_b32 s4, 0x68000
	s_nop 0
	v_addc_co_u32_e32 v39, vcc, 0, v3, vcc
	v_add_co_u32_e32 v40, vcc, s4, v2
	s_mov_b32 s4, 0x6e000
	s_nop 0
	v_addc_co_u32_e32 v41, vcc, 0, v3, vcc
	v_add_co_u32_e32 v42, vcc, s4, v2
	s_mov_b32 s4, 0x73000
	s_nop 0
	v_addc_co_u32_e32 v43, vcc, 0, v3, vcc
	v_add_co_u32_e32 v44, vcc, s4, v2
	s_mov_b32 s4, 0x79000
	s_nop 0
	v_addc_co_u32_e32 v45, vcc, 0, v3, vcc
	v_add_co_u32_e32 v46, vcc, s4, v2
	s_mov_b32 s4, 0x7e000
	s_nop 0
	v_addc_co_u32_e32 v47, vcc, 0, v3, vcc
	v_add_co_u32_e32 v48, vcc, s4, v2
	s_mov_b32 s4, 0x84000
	s_nop 0
	v_addc_co_u32_e32 v49, vcc, 0, v3, vcc
	global_load_dword v64, v[4:5], off
	global_load_dword v65, v[30:31], off offset:2048
	global_load_dword v66, v[38:39], off
	global_load_dword v67, v[40:41], off offset:2048
	global_load_dword v68, v[42:43], off
	global_load_dword v69, v[44:45], off offset:2048
	global_load_dword v70, v[46:47], off
	s_nop 0
	global_load_dword v48, v[48:49], off offset:2048
	v_add_co_u32_e32 v4, vcc, s4, v2
	s_mov_b32 s4, 0x89000
	s_nop 0
	v_addc_co_u32_e32 v5, vcc, 0, v3, vcc
	v_add_co_u32_e32 v30, vcc, s4, v2
	s_mov_b32 s4, 0x8f000
	s_nop 0
	v_addc_co_u32_e32 v31, vcc, 0, v3, vcc
	v_add_co_u32_e32 v38, vcc, s4, v2
	s_mov_b32 s4, 0x94000
	s_nop 0
	v_addc_co_u32_e32 v39, vcc, 0, v3, vcc
	v_add_co_u32_e32 v40, vcc, s4, v2
	s_mov_b32 s4, 0x9a000
	s_nop 0
	v_addc_co_u32_e32 v41, vcc, 0, v3, vcc
	v_add_co_u32_e32 v42, vcc, s4, v2
	s_mov_b32 s4, 0x9f000
	s_nop 0
	v_addc_co_u32_e32 v43, vcc, 0, v3, vcc
	v_add_co_u32_e32 v44, vcc, s4, v2
	s_mov_b32 s4, 0xa5000
	s_nop 0
	v_addc_co_u32_e32 v45, vcc, 0, v3, vcc
	v_add_co_u32_e32 v46, vcc, s4, v2
	s_mov_b32 s4, 0xaa000
	s_nop 0
	v_addc_co_u32_e32 v47, vcc, 0, v3, vcc
	v_add_co_u32_e32 v2, vcc, s4, v2
	s_and_b32 s0, s0, 0x1f00
	s_nop 0
	v_addc_co_u32_e32 v3, vcc, 0, v3, vcc
	global_load_dword v49, v[4:5], off
	s_nop 0
	global_load_dword v30, v[30:31], off offset:2048
	s_nop 0
	global_load_dword v31, v[38:39], off
	global_load_dword v71, v[40:41], off offset:2048
	s_nop 0
	global_load_dword v42, v[42:43], off
	s_nop 0
	global_load_dword v43, v[44:45], off offset:2048
	s_nop 0
	global_load_dword v44, v[46:47], off
	global_load_dword v45, v[2:3], off offset:2048
	v_lshl_add_u64 v[2:3], v[22:23], 0, s[88:89]
	global_load_dwordx4 v[38:41], v[2:3], off
	s_nop 0
	global_load_dwordx4 v[2:5], v[2:3], off offset:16
	s_waitcnt vmcnt(32)
; #define LAS __attribute__((address_space(3)))
; __device__ __forceinline__ unsigned pk2(float lo, float hi) { return f2bf(lo) | (f2bf(hi) << 16); }
; #define LDS_WAVE_SYNC() asm volatile("s_waitcnt lgkmcnt(0)" ::: "memory")
; template <bool HASG>
; __device__ __forceinline__ void tr_item(const float* W, int K, int N, bf16* WT, int rowmode, const float* g, LAS float* scr, int item, int lane) {
;     ...
;     for (int i = 0; i < 32; ++i) scr[(2 * i + (lane >> 5)) * 33 + (lane & 31)] = v[i];
;     LDS_WAVE_SYNC();
;     const int drow0 = rowmode == 0 ? n0 : ((n0 >> 7) * 256 + (n0 & 127) + (rowmode == 2 ? 128 : 0));
; #pragma unroll
;     for (int j = 0; j < 4; ++j) { const int n = (lane >> 3) + 8 * j; const LAS float* s = scr + (8 * c) * 33 + n;
;         u32x4 o; o.x = pk2(s[0 * 33] * g0.x, s[1 * 33] * g0.y); o.y = pk2(s[2 * 33] * g0.z, s[3 * 33] * g0.w);
;         o.z = pk2(s[4 * 33] * g1.x, s[5 * 33] * g1.y); o.w = pk2(s[6 * 33] * g1.z, s[7 * 33] * g1.w);
;         *(u32x4*)(WT + (size_t)(drow0 + n) * K + k0 + 8 * c) = o; }
	ds_write2_b32 v36, v0, v29 offset1:66
	s_waitcnt vmcnt(30)
	ds_write2_b32 v36, v50, v51 offset0:132 offset1:198
	v_add_u32_e32 v0, 0x400, v36
	s_waitcnt vmcnt(28)
	ds_write2_b32 v0, v52, v53 offset0:8 offset1:74
	s_waitcnt vmcnt(26)
	ds_write2_b32 v0, v54, v55 offset0:140 offset1:206
	v_add_u32_e32 v0, 0x800, v36
	s_waitcnt vmcnt(24)
	ds_write2_b32 v0, v56, v57 offset0:16 offset1:82
	s_waitcnt vmcnt(22)
	ds_write2_b32 v0, v58, v59 offset0:148 offset1:214
	v_add_u32_e32 v0, 0xc00, v36
	s_waitcnt vmcnt(20)
	ds_write2_b32 v0, v60, v61 offset0:24 offset1:90
	s_waitcnt vmcnt(18)
	ds_write2_b32 v0, v62, v63 offset0:156 offset1:222
	v_add_u32_e32 v0, 0x1000, v36
	s_waitcnt vmcnt(16)
	ds_write2_b32 v0, v64, v65 offset0:32 offset1:98
	s_waitcnt vmcnt(14)
	ds_write2_b32 v0, v66, v67 offset0:164 offset1:230
	v_add_u32_e32 v0, 0x1400, v36
	s_waitcnt vmcnt(12)
	ds_write2_b32 v0, v68, v69 offset0:40 offset1:106
	s_waitcnt vmcnt(10)
	ds_write2_b32 v0, v70, v48 offset0:172 offset1:238
	v_add_u32_e32 v0, 0x1800, v36
	s_waitcnt vmcnt(8)
	ds_write2_b32 v0, v49, v30 offset0:48 offset1:114
	s_waitcnt vmcnt(6)
	ds_write2_b32 v0, v31, v71 offset0:180 offset1:246
	v_add_u32_e32 v0, 0x1c00, v36
	s_waitcnt vmcnt(4)
	ds_write2_b32 v0, v42, v43 offset0:56 offset1:122
	s_waitcnt vmcnt(2)
	ds_write2_b32 v0, v44, v45 offset0:188 offset1:254
	s_waitcnt lgkmcnt(0)
	ds_read2_b32 v[46:47], v37 offset0:33 offset1:41
	ds_read2_b32 v[48:49], v37 offset1:8
	ds_read2_b32 v[50:51], v37 offset0:66 offset1:74
	ds_read2_b32 v[52:53], v37 offset0:99 offset1:107
	ds_read2_b32 v[56:57], v37 offset0:132 offset1:140
	ds_read2_b32 v[58:59], v37 offset0:165 offset1:173
	ds_read2_b32 v[60:61], v37 offset0:198 offset1:206
	ds_read2_b32 v[62:63], v37 offset0:231 offset1:239
	s_waitcnt vmcnt(1)
	v_mov_b32_e32 v54, v38
	v_mov_b32_e32 v55, v40
	v_mov_b32_e32 v40, v39
	s_waitcnt lgkmcnt(7)
	v_mov_b32_e32 v38, v46
	s_waitcnt lgkmcnt(4)
	v_mov_b32_e32 v39, v52
	v_pk_mul_f32 v[38:39], v[40:41], v[38:39]
	s_waitcnt vmcnt(0)
	v_mov_b32_e32 v64, v2
	v_mov_b32_e32 v65, v4
	s_waitcnt lgkmcnt(3)
	v_mov_b32_e32 v44, v56
	s_waitcnt lgkmcnt(1)
	v_mov_b32_e32 v45, v60
	v_mov_b32_e32 v4, v3
	v_mov_b32_e32 v2, v58
	s_waitcnt lgkmcnt(0)
	v_mov_b32_e32 v3, v62
	v_mov_b32_e32 v42, v48
	v_mov_b32_e32 v43, v50
	v_pk_mul_f32 v[44:45], v[64:65], v[44:45]
	v_pk_mul_f32 v[2:3], v[4:5], v[2:3]
	v_bfe_u32 v48, v38, 16, 1
	v_pk_mul_f32 v[42:43], v[54:55], v[42:43]
	v_bfe_u32 v29, v2, 16, 1
	v_add3_u32 v38, v38, v48, s91
	v_bfe_u32 v48, v45, 16, 1
	s_and_b32 s38, s38, 0x60
	v_bfe_u32 v0, v3, 16, 1
	v_bfe_u32 v46, v39, 16, 1
	v_add3_u32 v2, v2, v29, s91
	v_bfe_u32 v29, v43, 16, 1
	v_add3_u32 v45, v45, v48, s91
	s_or_b32 s0, s38, s0
	v_add3_u32 v39, v39, v46, s91
	v_add3_u32 v0, v3, v0, s91
	v_bfe_u32 v3, v42, 16, 1
	v_bfe_u32 v46, v44, 16, 1
	v_add3_u32 v29, v43, v29, s91
	v_lshrrev_b32_e32 v43, 16, v45
	s_lshl_b32 s88, s1, 1
	v_add3_u32 v44, v44, v46, s91
	v_add3_u32 v3, v42, v3, s91
	v_and_or_b32 v45, v0, s35, v43
	v_or_b32_e32 v0, s0, v7
	v_lshl_add_u64 v[30:31], v[12:13], 0, s[88:89]
	v_lshrrev_b32_e32 v3, 16, v3
	v_lshrrev_b32_e32 v29, 16, v29
	v_lshrrev_b32_e32 v42, 16, v44
	v_lshlrev_b32_e32 v0, 11, v0
	v_mov_b32_e32 v52, v47
	v_and_or_b32 v44, v2, s35, v42
	v_and_or_b32 v43, v39, s35, v29
	v_and_or_b32 v42, v38, s35, v3
	v_lshl_add_u64 v[2:3], v[30:31], 0, v[0:1]
	v_pk_mul_f32 v[38:39], v[40:41], v[52:53]
	v_mov_b32_e32 v60, v57
	global_store_dwordx4 v[2:3], v[42:45], off sc1
	v_mov_b32_e32 v62, v59
	v_bfe_u32 v47, v38, 16, 1
	v_pk_mul_f32 v[42:43], v[64:65], v[60:61]
	v_mov_b32_e32 v50, v49
	v_pk_mul_f32 v[44:45], v[4:5], v[62:63]
	v_add3_u32 v38, v38, v47, s91
	v_bfe_u32 v47, v43, 16, 1
	v_pk_mul_f32 v[2:3], v[54:55], v[50:51]
	v_bfe_u32 v0, v45, 16, 1
	v_bfe_u32 v29, v44, 16, 1
	v_bfe_u32 v46, v39, 16, 1
	v_add3_u32 v43, v43, v47, s91
	v_add3_u32 v39, v39, v46, s91
	v_add3_u32 v29, v44, v29, s91
	v_add3_u32 v0, v45, v0, s91
	v_bfe_u32 v44, v2, 16, 1
	v_bfe_u32 v45, v3, 16, 1
	v_bfe_u32 v46, v42, 16, 1
	v_lshrrev_b32_e32 v43, 16, v43
	v_add3_u32 v42, v42, v46, s91
	v_add3_u32 v3, v3, v45, s91
	v_add3_u32 v2, v2, v44, s91
	v_and_or_b32 v45, v0, s35, v43
	v_or_b32_e32 v0, s0, v32
	v_lshrrev_b32_e32 v2, 16, v2
	v_lshrrev_b32_e32 v3, 16, v3
	v_lshrrev_b32_e32 v42, 16, v42
	v_lshlrev_b32_e32 v0, 11, v0
	v_and_or_b32 v44, v29, s35, v42
	v_and_or_b32 v43, v39, s35, v3
	v_and_or_b32 v42, v38, s35, v2
	v_lshl_add_u64 v[2:3], v[30:31], 0, v[0:1]
	ds_read2_b32 v[38:39], v37 offset0:16 offset1:24
	ds_read2_b32 v[46:47], v37 offset0:82 offset1:90
	global_store_dwordx4 v[2:3], v[42:45], off sc1
	ds_read2_b32 v[2:3], v37 offset0:49 offset1:57
	ds_read2_b32 v[48:49], v37 offset0:115 offset1:123
	ds_read2_b32 v[50:51], v37 offset0:148 offset1:156
	ds_read2_b32 v[52:53], v37 offset0:214 offset1:222
	ds_read2_b32 v[56:57], v37 offset0:181 offset1:189
	ds_read2_b32 v[58:59], v37 offset0:247 offset1:255
	s_waitcnt lgkmcnt(7)
; #define LAS __attribute__((address_space(3)))
; __device__ __forceinline__ unsigned pk2(float lo, float hi) { return f2bf(lo) | (f2bf(hi) << 16); }
; #define LDS_WAVE_SYNC() asm volatile("s_waitcnt lgkmcnt(0)" ::: "memory")
; template <bool HASG>
; __device__ __forceinline__ void tr_item(const float* W, int K, int N, bf16* WT, int rowmode, const float* g, LAS float* scr, int item, int lane) {
;     ...
;     for (int j = 0; j < 4; ++j) { const int n = (lane >> 3) + 8 * j; const LAS float* s = scr + (8 * c) * 33 + n;
;         u32x4 o; o.x = pk2(s[0 * 33] * g0.x, s[1 * 33] * g0.y); o.y = pk2(s[2 * 33] * g0.z, s[3 * 33] * g0.w);
;         o.z = pk2(s[4 * 33] * g1.x, s[5 * 33] * g1.y); o.w = pk2(s[6 * 33] * g1.z, s[7 * 33] * g1.w);
;         *(u32x4*)(WT + (size_t)(drow0 + n) * K + k0 + 8 * c) = o; }
;     LDS_WAVE_SYNC();
	v_mov_b32_e32 v42, v38
	s_waitcnt lgkmcnt(5)
	v_mov_b32_e32 v44, v2
	s_waitcnt lgkmcnt(4)
	v_mov_b32_e32 v45, v48
	s_waitcnt lgkmcnt(3)
	v_mov_b32_e32 v60, v50
	s_waitcnt lgkmcnt(2)
	v_mov_b32_e32 v61, v52
	v_mov_b32_e32 v43, v46
	v_pk_mul_f32 v[44:45], v[40:41], v[44:45]
	v_pk_mul_f32 v[60:61], v[64:65], v[60:61]
	s_waitcnt lgkmcnt(1)
	v_mov_b32_e32 v62, v56
	s_waitcnt lgkmcnt(0)
	v_mov_b32_e32 v63, v58
	v_pk_mul_f32 v[42:43], v[54:55], v[42:43]
	v_pk_mul_f32 v[62:63], v[4:5], v[62:63]
	v_bfe_u32 v29, v45, 16, 1
	v_bfe_u32 v48, v61, 16, 1
	v_bfe_u32 v0, v63, 16, 1
	v_bfe_u32 v38, v44, 16, 1
	v_add3_u32 v29, v45, v29, s91
	v_bfe_u32 v45, v43, 16, 1
	v_add3_u32 v48, v61, v48, s91
	v_add3_u32 v38, v44, v38, s91
	v_add3_u32 v0, v63, v0, s91
	v_bfe_u32 v44, v42, 16, 1
	v_bfe_u32 v46, v60, 16, 1
	v_add3_u32 v43, v43, v45, s91
	v_lshrrev_b32_e32 v45, 16, v48
	v_bfe_u32 v2, v62, 16, 1
	v_add3_u32 v46, v60, v46, s91
	v_add3_u32 v42, v42, v44, s91
	v_and_or_b32 v45, v0, s35, v45
	v_or_b32_e32 v0, s0, v34
	v_add3_u32 v2, v62, v2, s91
	v_lshrrev_b32_e32 v42, 16, v42
	v_lshrrev_b32_e32 v43, 16, v43
	v_lshrrev_b32_e32 v44, 16, v46
	v_lshlrev_b32_e32 v0, 11, v0
	v_mov_b32_e32 v48, v3
	v_mov_b32_e32 v58, v57
	v_and_or_b32 v44, v2, s35, v44
	v_and_or_b32 v43, v29, s35, v43
	v_and_or_b32 v42, v38, s35, v42
	v_lshl_add_u64 v[60:61], v[30:31], 0, v[0:1]
	v_mov_b32_e32 v46, v39
	v_pk_mul_f32 v[2:3], v[40:41], v[48:49]
	v_mov_b32_e32 v52, v51
	v_pk_mul_f32 v[4:5], v[4:5], v[58:59]
	global_store_dwordx4 v[60:61], v[42:45], off sc1
	v_pk_mul_f32 v[38:39], v[54:55], v[46:47]
	v_pk_mul_f32 v[40:41], v[64:65], v[52:53]
	v_bfe_u32 v0, v5, 16, 1
	v_bfe_u32 v43, v2, 16, 1
	v_add3_u32 v2, v2, v43, s91
	v_add3_u32 v0, v5, v0, s91
	v_bfe_u32 v5, v38, 16, 1
	v_bfe_u32 v43, v41, 16, 1
	v_bfe_u32 v29, v4, 16, 1
	v_bfe_u32 v42, v3, 16, 1
	v_add3_u32 v41, v41, v43, s91
	v_add3_u32 v5, v38, v5, s91
	v_add3_u32 v3, v3, v42, s91
	v_add3_u32 v4, v4, v29, s91
	v_bfe_u32 v29, v39, 16, 1
	v_bfe_u32 v42, v40, 16, 1
	v_lshrrev_b32_e32 v38, 16, v5
	v_lshrrev_b32_e32 v5, 16, v41
	v_add3_u32 v40, v40, v42, s91
	v_add3_u32 v29, v39, v29, s91
	v_and_or_b32 v5, v0, s35, v5
	v_or_b32_e32 v0, s0, v35
	v_lshrrev_b32_e32 v29, 16, v29
	v_lshrrev_b32_e32 v39, 16, v40
	v_lshlrev_b32_e32 v0, 11, v0
	v_and_or_b32 v4, v4, s35, v39
	v_and_or_b32 v3, v3, s35, v29
	v_and_or_b32 v2, v2, s35, v38
	v_lshl_add_u64 v[30:31], v[30:31], 0, v[0:1]
	global_store_dwordx4 v[30:31], v[2:5], off sc1
	s_waitcnt lgkmcnt(0)
	v_readlane_b32 s5, v252, 1
	v_readlane_b32 s6, v252, 2
	v_readlane_b32 s7, v252, 3
	v_readlane_b32 s8, v252, 4
	v_readlane_b32 s9, v252, 5
	v_readlane_b32 s10, v252, 6
	v_readlane_b32 s11, v252, 7
	v_readlane_b32 s12, v252, 8
	v_readlane_b32 s13, v252, 9
	v_readlane_b32 s14, v252, 10
	v_readlane_b32 s15, v252, 11
	v_readlane_b32 s16, v252, 12
	v_readlane_b32 s17, v252, 13
	v_readlane_b32 s18, v252, 14
	v_readlane_b32 s19, v252, 15

; template <bool HASG>
; __device__ __forceinline__ void tr_item(const float* W, int K, int N, bf16* WT, int rowmode, const float* g, LAS float* scr, int item, int lane) {
;     const int nblk = N / 32, kb = item / nblk, nb = item % nblk, k0 = 64 * kb, n0 = 32 * nb;
;     const float* wp = W + (size_t)(k0 + (lane >> 5)) * N + n0 + (lane & 31);
;     const int c = lane & 7;
;     float v[32];
; #pragma unroll
;     for (int i = 0; i < 32; ++i) v[i] = wp[(size_t)(2 * i) * N];
;     f32x4 g0 = (f32x4){1.f, 1.f, 1.f, 1.f}, g1 = g0;
;     if (HASG) { g0 = *(const f32x4*)(g + k0 + 8 * c); g1 = *(const f32x4*)(g + k0 + 8 * c + 4); }
;     asm volatile("" ::: "memory");
; #pragma unroll
;     for (int i = 0; i < 32; ++i) scr[(2 * i + (lane >> 5)) * 33 + (lane & 31)] = v[i];
; __device__ __forceinline__ void convert_items(const Args& a, LAS unsigned char* lds, int l, int it_lo, int it_hi, int gw, int NGW, int wave, int lane) {
;     ...
;         if (r < I_OUT) { tr_item<false>(a.in[18] + (size_t)l * D * D, D, D, wl + W_OUT, 0, nullptr, scr, r, lane); continue; } r -= I_OUT;
.LBB0_590:
	s_andn2_b64 vcc, exec, s[0:1]
	s_cbranch_vccnz .LBB0_592
	s_add_i32 s0, s43, 0x1a00
	s_and_b32 s1, s0, 0x1ffc0
	s_lshl_b32 s0, s28, 5
	v_or_b32_e32 v0, s1, v33
	v_readlane_b32 s4, v252, 32
	s_and_b32 s0, s0, 0x3e0
	v_lshlrev_b32_e32 v0, 12, v0
	v_readlane_b32 s8, v252, 36
	v_readlane_b32 s9, v252, 37
	v_readlane_b32 s5, v252, 33
	v_readlane_b32 s6, v252, 34
	v_readlane_b32 s7, v252, 35
	v_readlane_b32 s10, v252, 38
	v_readlane_b32 s11, v252, 39
	v_readlane_b32 s12, v252, 40
	v_readlane_b32 s13, v252, 41
	v_readlane_b32 s14, v252, 42
	v_readlane_b32 s15, v252, 43
	v_readlane_b32 s16, v252, 44
	v_readlane_b32 s17, v252, 45
	v_readlane_b32 s18, v252, 46
	v_readlane_b32 s19, v252, 47
	v_lshl_add_u64 v[2:3], s[8:9], 0, v[0:1]
	s_lshl_b32 s88, s0, 2
	v_readlane_b32 s4, v252, 0
	v_lshl_add_u64 v[2:3], v[2:3], 0, s[88:89]
	v_lshlrev_b32_e32 v0, 2, v6
	v_lshl_add_u64 v[2:3], v[2:3], 0, v[0:1]
	s_movk_i32 s4, 0x2000
	v_add_co_u32_e32 v4, vcc, s4, v2
	s_movk_i32 s4, 0x4000
	s_nop 0
	v_addc_co_u32_e32 v5, vcc, 0, v3, vcc
	global_load_dword v0, v[2:3], off
	global_load_dword v29, v[4:5], off
	v_add_co_u32_e32 v4, vcc, s4, v2
	s_movk_i32 s4, 0x6000
	s_nop 0
	v_addc_co_u32_e32 v5, vcc, 0, v3, vcc
	global_load_dword v30, v[4:5], off
	v_add_co_u32_e32 v4, vcc, s4, v2
	s_mov_b32 s4, 0x8000
	s_nop 0
	v_addc_co_u32_e32 v5, vcc, 0, v3, vcc
	global_load_dword v31, v[4:5], off
	v_add_co_u32_e32 v4, vcc, s4, v2
	s_mov_b32 s4, 0xa000
	s_nop 0
	v_addc_co_u32_e32 v5, vcc, 0, v3, vcc
	global_load_dword v38, v[4:5], off
	v_add_co_u32_e32 v4, vcc, s4, v2
	s_mov_b32 s4, 0xc000
	s_nop 0
	v_addc_co_u32_e32 v5, vcc, 0, v3, vcc
	global_load_dword v39, v[4:5], off
	v_add_co_u32_e32 v4, vcc, s4, v2
	s_mov_b32 s4, 0xe000
	s_nop 0
	v_addc_co_u32_e32 v5, vcc, 0, v3, vcc
	global_load_dword v40, v[4:5], off
	v_add_co_u32_e32 v4, vcc, s4, v2
	s_mov_b32 s4, 0x12000
	s_nop 0
	v_addc_co_u32_e32 v5, vcc, 0, v3, vcc
	global_load_dword v41, v[4:5], off
	v_add_co_u32_e32 v4, vcc, s70, v2
	s_lshl_b32 s88, s1, 1
	s_nop 0
	v_addc_co_u32_e32 v5, vcc, 0, v3, vcc
	global_load_dword v42, v[4:5], off
	v_add_co_u32_e32 v4, vcc, s4, v2
	s_mov_b32 s4, 0x14000
	s_nop 0
	v_addc_co_u32_e32 v5, vcc, 0, v3, vcc
	global_load_dword v43, v[4:5], off
	v_add_co_u32_e32 v4, vcc, s4, v2
	s_mov_b32 s4, 0x18000
	s_nop 0
	v_addc_co_u32_e32 v5, vcc, 0, v3, vcc
	global_load_dword v44, v[4:5], off
	v_add_co_u32_e32 v4, vcc, s71, v2
	v_readlane_b32 s5, v252, 1
	s_nop 0
	v_addc_co_u32_e32 v5, vcc, 0, v3, vcc
	global_load_dword v45, v[4:5], off
	v_add_co_u32_e32 v4, vcc, s4, v2
	s_mov_b32 s4, 0x1a000
	s_nop 0
	v_addc_co_u32_e32 v5, vcc, 0, v3, vcc
	global_load_dword v46, v[4:5], off
	v_add_co_u32_e32 v4, vcc, s4, v2
	s_mov_b32 s4, 0x1c000
	s_nop 0
	v_addc_co_u32_e32 v5, vcc, 0, v3, vcc
	global_load_dword v47, v[4:5], off
	v_add_co_u32_e32 v4, vcc, s4, v2
	s_mov_b32 s4, 0x1e000
	s_nop 0
	v_addc_co_u32_e32 v5, vcc, 0, v3, vcc
	global_load_dword v48, v[4:5], off
	v_add_co_u32_e32 v4, vcc, s4, v2
	s_mov_b32 s4, 0x20000
	s_nop 0
	v_addc_co_u32_e32 v5, vcc, 0, v3, vcc
	global_load_dword v49, v[4:5], off
	v_add_co_u32_e32 v4, vcc, s4, v2
	s_mov_b32 s4, 0x22000
	s_nop 0
	v_addc_co_u32_e32 v5, vcc, 0, v3, vcc
	global_load_dword v50, v[4:5], off
	v_add_co_u32_e32 v4, vcc, s4, v2
	s_mov_b32 s4, 0x24000
	s_nop 0
	v_addc_co_u32_e32 v5, vcc, 0, v3, vcc
	global_load_dword v51, v[4:5], off
	v_add_co_u32_e32 v4, vcc, s4, v2
	s_mov_b32 s4, 0x26000
	s_nop 0
	v_addc_co_u32_e32 v5, vcc, 0, v3, vcc
	global_load_dword v52, v[4:5], off
	v_add_co_u32_e32 v4, vcc, s4, v2
	s_mov_b32 s4, 0x28000
	s_nop 0
	v_addc_co_u32_e32 v5, vcc, 0, v3, vcc
	global_load_dword v53, v[4:5], off
	v_add_co_u32_e32 v4, vcc, s4, v2
	s_mov_b32 s4, 0x2a000
	s_nop 0
	v_addc_co_u32_e32 v5, vcc, 0, v3, vcc
	global_load_dword v54, v[4:5], off
	v_add_co_u32_e32 v4, vcc, s4, v2
	s_mov_b32 s4, 0x2c000
	s_nop 0
	v_addc_co_u32_e32 v5, vcc, 0, v3, vcc
	global_load_dword v55, v[4:5], off
	v_add_co_u32_e32 v4, vcc, s4, v2
	s_mov_b32 s4, 0x2e000
	s_nop 0
	v_addc_co_u32_e32 v5, vcc, 0, v3, vcc
	global_load_dword v56, v[4:5], off
	v_add_co_u32_e32 v4, vcc, s4, v2
	s_mov_b32 s4, 0x30000
	s_nop 0
	v_addc_co_u32_e32 v5, vcc, 0, v3, vcc
	global_load_dword v57, v[4:5], off
	v_add_co_u32_e32 v4, vcc, s4, v2
	s_mov_b32 s4, 0x32000
	s_nop 0
	v_addc_co_u32_e32 v5, vcc, 0, v3, vcc
	global_load_dword v58, v[4:5], off
	v_add_co_u32_e32 v4, vcc, s4, v2
	s_mov_b32 s4, 0x34000
	s_nop 0
	v_addc_co_u32_e32 v5, vcc, 0, v3, vcc
	global_load_dword v59, v[4:5], off
	v_add_co_u32_e32 v4, vcc, s4, v2
	s_mov_b32 s4, 0x36000
	s_nop 0
	v_addc_co_u32_e32 v5, vcc, 0, v3, vcc
	global_load_dword v60, v[4:5], off
	v_add_co_u32_e32 v4, vcc, s4, v2
	s_mov_b32 s4, 0x38000
	s_nop 0
	v_addc_co_u32_e32 v5, vcc, 0, v3, vcc
	global_load_dword v61, v[4:5], off
	v_add_co_u32_e32 v4, vcc, s4, v2
	s_mov_b32 s4, 0x3a000
	s_nop 0
	v_addc_co_u32_e32 v5, vcc, 0, v3, vcc
	global_load_dword v62, v[4:5], off
	v_add_co_u32_e32 v4, vcc, s4, v2
	s_mov_b32 s4, 0x3c000
	s_nop 0
	v_addc_co_u32_e32 v5, vcc, 0, v3, vcc
	global_load_dword v63, v[4:5], off
	v_add_co_u32_e32 v4, vcc, s4, v2
	s_mov_b32 s4, 0x3e000
	s_nop 0
	v_addc_co_u32_e32 v5, vcc, 0, v3, vcc
	v_add_co_u32_e32 v2, vcc, s4, v2
	global_load_dword v4, v[4:5], off
	s_nop 0
	v_addc_co_u32_e32 v3, vcc, 0, v3, vcc
	global_load_dword v2, v[2:3], off
	s_waitcnt vmcnt(30)
	ds_write2_b32 v36, v0, v29 offset1:66
	s_waitcnt vmcnt(28)
	ds_write2_b32 v36, v30, v31 offset0:132 offset1:198
	v_add_u32_e32 v0, 0x400, v36
	s_waitcnt vmcnt(26)
	ds_write2_b32 v0, v38, v39 offset0:8 offset1:74
	s_waitcnt vmcnt(24)
	ds_write2_b32 v0, v40, v41 offset0:140 offset1:206
	v_add_u32_e32 v0, 0x800, v36
	s_waitcnt vmcnt(22)
; #define LAS __attribute__((address_space(3)))
; __device__ __forceinline__ unsigned pk2(float lo, float hi) { return f2bf(lo) | (f2bf(hi) << 16); }
; #define LDS_WAVE_SYNC() asm volatile("s_waitcnt lgkmcnt(0)" ::: "memory")
; template <bool HASG>
; __device__ __forceinline__ void tr_item(const float* W, int K, int N, bf16* WT, int rowmode, const float* g, LAS float* scr, int item, int lane) {
;     ...
;     for (int i = 0; i < 32; ++i) scr[(2 * i + (lane >> 5)) * 33 + (lane & 31)] = v[i];
;     LDS_WAVE_SYNC();
;     const int drow0 = rowmode == 0 ? n0 : ((n0 >> 7) * 256 + (n0 & 127) + (rowmode == 2 ? 128 : 0));
; #pragma unroll
;     for (int j = 0; j < 4; ++j) { const int n = (lane >> 3) + 8 * j; const LAS float* s = scr + (8 * c) * 33 + n;
;         u32x4 o; o.x = pk2(s[0 * 33] * g0.x, s[1 * 33] * g0.y); o.y = pk2(s[2 * 33] * g0.z, s[3 * 33] * g0.w);
;         o.z = pk2(s[4 * 33] * g1.x, s[5 * 33] * g1.y); o.w = pk2(s[6 * 33] * g1.z, s[7 * 33] * g1.w);
;         *(u32x4*)(WT + (size_t)(drow0 + n) * K + k0 + 8 * c) = o; }
;     LDS_WAVE_SYNC();
	ds_write2_b32 v0, v42, v43 offset0:16 offset1:82
	s_waitcnt vmcnt(20)
	ds_write2_b32 v0, v44, v45 offset0:148 offset1:214
	v_add_u32_e32 v0, 0xc00, v36
	s_waitcnt vmcnt(18)
	ds_write2_b32 v0, v46, v47 offset0:24 offset1:90
	s_waitcnt vmcnt(16)
	ds_write2_b32 v0, v48, v49 offset0:156 offset1:222
	v_add_u32_e32 v0, 0x1000, v36
	s_waitcnt vmcnt(14)
	ds_write2_b32 v0, v50, v51 offset0:32 offset1:98
	s_waitcnt vmcnt(12)
	ds_write2_b32 v0, v52, v53 offset0:164 offset1:230
	v_add_u32_e32 v0, 0x1400, v36
	s_waitcnt vmcnt(10)
	ds_write2_b32 v0, v54, v55 offset0:40 offset1:106
	s_waitcnt vmcnt(8)
	ds_write2_b32 v0, v56, v57 offset0:172 offset1:238
	v_add_u32_e32 v0, 0x1800, v36
	s_waitcnt vmcnt(6)
	ds_write2_b32 v0, v58, v59 offset0:48 offset1:114
	s_waitcnt vmcnt(4)
	ds_write2_b32 v0, v60, v61 offset0:180 offset1:246
	v_add_u32_e32 v0, 0x1c00, v36
	s_waitcnt vmcnt(2)
	ds_write2_b32 v0, v62, v63 offset0:56 offset1:122
	s_waitcnt vmcnt(0)
	ds_write2_b32 v0, v4, v2 offset0:188 offset1:254
	s_waitcnt lgkmcnt(0)
	ds_read2_b32 v[4:5], v37 offset0:33 offset1:41
	ds_read2_b32 v[30:31], v37 offset1:8
	ds_read2_b32 v[42:43], v37 offset0:66 offset1:74
	ds_read2_b32 v[44:45], v37 offset0:99 offset1:107
	ds_read2_b32 v[46:47], v37 offset0:132 offset1:140
	ds_read2_b32 v[48:49], v37 offset0:165 offset1:173
	ds_read2_b32 v[50:51], v37 offset0:198 offset1:206
	ds_read2_b32 v[52:53], v37 offset0:231 offset1:239
	s_waitcnt lgkmcnt(7)
	v_bfe_u32 v29, v4, 16, 1
	s_waitcnt lgkmcnt(6)
	v_bfe_u32 v0, v30, 16, 1
	v_add3_u32 v0, v30, v0, s91
	v_lshrrev_b32_e32 v0, 16, v0
	v_add3_u32 v4, v4, v29, s91
	v_and_or_b32 v38, v4, s35, v0
	s_waitcnt lgkmcnt(5)
	v_bfe_u32 v0, v42, 16, 1
	v_add3_u32 v0, v42, v0, s91
	s_waitcnt lgkmcnt(4)
	v_bfe_u32 v4, v44, 16, 1
	v_lshrrev_b32_e32 v0, 16, v0
	v_add3_u32 v4, v44, v4, s91
	v_and_or_b32 v39, v4, s35, v0
	s_waitcnt lgkmcnt(3)
	v_bfe_u32 v0, v46, 16, 1
	v_add3_u32 v0, v46, v0, s91
	s_waitcnt lgkmcnt(2)
	v_bfe_u32 v4, v48, 16, 1
	v_lshrrev_b32_e32 v0, 16, v0
	v_add3_u32 v4, v48, v4, s91
	v_and_or_b32 v40, v4, s35, v0
	s_waitcnt lgkmcnt(1)
	v_bfe_u32 v0, v50, 16, 1
	v_add3_u32 v0, v50, v0, s91
	s_waitcnt lgkmcnt(0)
	v_bfe_u32 v4, v52, 16, 1
	v_lshrrev_b32_e32 v0, 16, v0
	v_add3_u32 v4, v52, v4, s91
	v_and_or_b32 v41, v4, s35, v0
	v_or_b32_e32 v0, s0, v7
	v_lshl_add_u64 v[2:3], v[14:15], 0, s[88:89]
	v_lshlrev_b32_e32 v0, 11, v0
	v_lshl_add_u64 v[54:55], v[2:3], 0, v[0:1]
	v_bfe_u32 v0, v31, 16, 1
	v_add3_u32 v0, v31, v0, s91
	v_bfe_u32 v4, v5, 16, 1
	v_lshrrev_b32_e32 v0, 16, v0
	v_add3_u32 v4, v5, v4, s91
	global_store_dwordx4 v[54:55], v[38:41], off sc1
	v_readlane_b32 s6, v252, 2
	v_readlane_b32 s7, v252, 3
	v_and_or_b32 v38, v4, s35, v0
	v_bfe_u32 v0, v43, 16, 1
	v_add3_u32 v0, v43, v0, s91
	v_bfe_u32 v4, v45, 16, 1
	v_lshrrev_b32_e32 v0, 16, v0
	v_add3_u32 v4, v45, v4, s91
	v_and_or_b32 v39, v4, s35, v0
	v_bfe_u32 v0, v47, 16, 1
	v_add3_u32 v0, v47, v0, s91
	v_bfe_u32 v4, v49, 16, 1
	v_lshrrev_b32_e32 v0, 16, v0
	v_add3_u32 v4, v49, v4, s91
	v_and_or_b32 v40, v4, s35, v0
	v_bfe_u32 v0, v51, 16, 1
	v_add3_u32 v0, v51, v0, s91
	v_bfe_u32 v4, v53, 16, 1
	v_lshrrev_b32_e32 v0, 16, v0
	v_add3_u32 v4, v53, v4, s91
	v_and_or_b32 v41, v4, s35, v0
	v_or_b32_e32 v0, s0, v32
	v_lshlrev_b32_e32 v0, 11, v0
	v_lshl_add_u64 v[4:5], v[2:3], 0, v[0:1]
	global_store_dwordx4 v[4:5], v[38:41], off sc1
	ds_read2_b32 v[4:5], v37 offset0:49 offset1:57
	ds_read2_b32 v[30:31], v37 offset0:16 offset1:24
	ds_read2_b32 v[42:43], v37 offset0:82 offset1:90
	ds_read2_b32 v[44:45], v37 offset0:115 offset1:123
	ds_read2_b32 v[46:47], v37 offset0:148 offset1:156
	ds_read2_b32 v[48:49], v37 offset0:181 offset1:189
	ds_read2_b32 v[50:51], v37 offset0:214 offset1:222
	ds_read2_b32 v[52:53], v37 offset0:247 offset1:255
	s_waitcnt lgkmcnt(7)
	v_bfe_u32 v29, v4, 16, 1
	s_waitcnt lgkmcnt(6)
	v_bfe_u32 v0, v30, 16, 1
	v_add3_u32 v0, v30, v0, s91
	v_lshrrev_b32_e32 v0, 16, v0
	v_add3_u32 v4, v4, v29, s91
	v_and_or_b32 v38, v4, s35, v0
	s_waitcnt lgkmcnt(5)
	v_bfe_u32 v0, v42, 16, 1
	v_add3_u32 v0, v42, v0, s91
	s_waitcnt lgkmcnt(4)
	v_bfe_u32 v4, v44, 16, 1
	v_lshrrev_b32_e32 v0, 16, v0
	v_add3_u32 v4, v44, v4, s91
	v_and_or_b32 v39, v4, s35, v0
	s_waitcnt lgkmcnt(3)
	v_bfe_u32 v0, v46, 16, 1
	v_add3_u32 v0, v46, v0, s91
	s_waitcnt lgkmcnt(2)
	v_bfe_u32 v4, v48, 16, 1
	v_lshrrev_b32_e32 v0, 16, v0
	v_add3_u32 v4, v48, v4, s91
	v_and_or_b32 v40, v4, s35, v0
	s_waitcnt lgkmcnt(1)
	v_bfe_u32 v0, v50, 16, 1
	v_add3_u32 v0, v50, v0, s91
	s_waitcnt lgkmcnt(0)
	v_bfe_u32 v4, v52, 16, 1
	v_lshrrev_b32_e32 v0, 16, v0
	v_add3_u32 v4, v52, v4, s91
	v_and_or_b32 v41, v4, s35, v0
	v_or_b32_e32 v0, s0, v34
	v_lshlrev_b32_e32 v0, 11, v0
	v_lshl_add_u64 v[54:55], v[2:3], 0, v[0:1]
	v_bfe_u32 v0, v31, 16, 1
	v_add3_u32 v0, v31, v0, s91
	v_bfe_u32 v4, v5, 16, 1
	v_lshrrev_b32_e32 v0, 16, v0
	v_add3_u32 v4, v5, v4, s91
	global_store_dwordx4 v[54:55], v[38:41], off sc1
	v_readlane_b32 s8, v252, 4
	v_readlane_b32 s9, v252, 5
	v_and_or_b32 v38, v4, s35, v0
	v_bfe_u32 v0, v43, 16, 1
	v_add3_u32 v0, v43, v0, s91
	v_bfe_u32 v4, v45, 16, 1
	v_lshrrev_b32_e32 v0, 16, v0
	v_add3_u32 v4, v45, v4, s91
	v_and_or_b32 v39, v4, s35, v0
	v_bfe_u32 v0, v47, 16, 1
	v_add3_u32 v0, v47, v0, s91
	v_bfe_u32 v4, v49, 16, 1
	v_lshrrev_b32_e32 v0, 16, v0
	v_add3_u32 v4, v49, v4, s91
	v_and_or_b32 v40, v4, s35, v0
	v_bfe_u32 v0, v51, 16, 1
	v_add3_u32 v0, v51, v0, s91
	v_bfe_u32 v4, v53, 16, 1
	v_lshrrev_b32_e32 v0, 16, v0
	v_add3_u32 v4, v53, v4, s91
	v_and_or_b32 v41, v4, s35, v0
	v_or_b32_e32 v0, s0, v35
	v_lshlrev_b32_e32 v0, 11, v0
	v_lshl_add_u64 v[2:3], v[2:3], 0, v[0:1]
	global_store_dwordx4 v[2:3], v[38:41], off sc1
	s_waitcnt lgkmcnt(0)
	v_readlane_b32 s10, v252, 6
	v_readlane_b32 s11, v252, 7
	v_readlane_b32 s12, v252, 8
	v_readlane_b32 s13, v252, 9
	v_readlane_b32 s14, v252, 10
	v_readlane_b32 s15, v252, 11
	v_readlane_b32 s16, v252, 12
	v_readlane_b32 s17, v252, 13
	v_readlane_b32 s18, v252, 14
	v_readlane_b32 s19, v252, 15

; template <bool HASG>
; __device__ __forceinline__ void tr_item(const float* W, int K, int N, bf16* WT, int rowmode, const float* g, LAS float* scr, int item, int lane) {
;     const int nblk = N / 32, kb = item / nblk, nb = item % nblk, k0 = 64 * kb, n0 = 32 * nb;
;     const float* wp = W + (size_t)(k0 + (lane >> 5)) * N + n0 + (lane & 31);
;     const int c = lane & 7;
;     float v[32];
; #pragma unroll
;     for (int i = 0; i < 32; ++i) v[i] = wp[(size_t)(2 * i) * N];
;     f32x4 g0 = (f32x4){1.f, 1.f, 1.f, 1.f}, g1 = g0;
;     if (HASG) { g0 = *(const f32x4*)(g + k0 + 8 * c); g1 = *(const f32x4*)(g + k0 + 8 * c + 4); }
; __device__ __forceinline__ void convert_items(const Args& a, LAS unsigned char* lds, int l, int it_lo, int it_hi, int gw, int NGW, int wave, int lane) {
;     ...
;         if (r < I_IN) { tr_item<true>(a.in[6] + (size_t)l * D * DIN, D, DIN, wl + W_IN, 0, a.in[5] + l * D, scr, r, lane); continue; } r -= I_IN;
.LBB0_593:
	s_andn2_b64 vcc, exec, s[0:1]
	s_cbranch_vccnz .LBB0_595
	s_add_i32 s0, s28, 0xef80
	s_bfe_u32 s1, s0, 0xd0003
	s_mulk_i32 s1, 0x2493
	s_lshr_b32 s1, s1, 16
	s_mul_i32 s38, s1, 56
	s_sub_i32 s0, s0, s38
	s_lshl_b32 s0, s0, 5
	v_lshl_or_b32 v0, s1, 6, v33
	v_readlane_b32 s4, v252, 0
	s_and_b32 s0, s0, 0xffe0
	v_mul_u32_u24_e32 v0, 0x700, v0
	v_readlane_b32 s16, v252, 12
	v_readlane_b32 s17, v252, 13
	s_lshl_b32 s88, s0, 2
	s_movk_i32 s4, 0x3000
	v_lshl_add_u64 v[2:3], v[0:1], 2, s[16:17]
	v_lshl_add_u64 v[2:3], v[2:3], 0, s[88:89]
	v_lshlrev_b32_e32 v0, 2, v6
	v_lshl_add_u64 v[2:3], v[2:3], 0, v[0:1]
	v_add_co_u32_e32 v4, vcc, s4, v2
	s_movk_i32 s4, 0x7000
	s_nop 0
	v_addc_co_u32_e32 v5, vcc, 0, v3, vcc
	v_add_co_u32_e32 v30, vcc, s4, v2
	s_mov_b32 s4, 0xa000
	s_nop 0
	v_addc_co_u32_e32 v31, vcc, 0, v3, vcc
	v_add_co_u32_e32 v38, vcc, s4, v2
	s_mov_b32 s4, 0xe000
	s_nop 0
	v_addc_co_u32_e32 v39, vcc, 0, v3, vcc
	v_add_co_u32_e32 v40, vcc, s4, v2
	s_mov_b32 s4, 0x11000
	s_nop 0
	v_addc_co_u32_e32 v41, vcc, 0, v3, vcc
	v_add_co_u32_e32 v42, vcc, s4, v2
	s_mov_b32 s4, 0x15000
	s_nop 0
	v_addc_co_u32_e32 v43, vcc, 0, v3, vcc
	v_add_co_u32_e32 v44, vcc, s4, v2
	s_mov_b32 s4, 0x18000
	s_nop 0
	v_addc_co_u32_e32 v45, vcc, 0, v3, vcc
	v_add_co_u32_e32 v46, vcc, s4, v2
	s_mov_b32 s4, 0x1c000
	s_nop 0
	v_addc_co_u32_e32 v47, vcc, 0, v3, vcc
	global_load_dword v0, v[2:3], off
	global_load_dword v29, v[4:5], off offset:2048
	global_load_dword v50, v[30:31], off
	global_load_dword v51, v[38:39], off offset:2048
	global_load_dword v52, v[40:41], off
	global_load_dword v53, v[42:43], off offset:2048
	global_load_dword v54, v[44:45], off
	global_load_dword v55, v[46:47], off offset:2048
	v_add_co_u32_e32 v4, vcc, s4, v2
	s_mov_b32 s4, 0x1f000
	s_nop 0
	v_addc_co_u32_e32 v5, vcc, 0, v3, vcc
	v_add_co_u32_e32 v30, vcc, s4, v2
	s_mov_b32 s4, 0x23000
	s_nop 0
	v_addc_co_u32_e32 v31, vcc, 0, v3, vcc
	v_add_co_u32_e32 v38, vcc, s4, v2
	s_mov_b32 s4, 0x26000
	s_nop 0
	v_addc_co_u32_e32 v39, vcc, 0, v3, vcc
	v_add_co_u32_e32 v40, vcc, s4, v2
	s_mov_b32 s4, 0x2a000
	s_nop 0
	v_addc_co_u32_e32 v41, vcc, 0, v3, vcc
	v_add_co_u32_e32 v42, vcc, s4, v2
	s_mov_b32 s4, 0x2d000
	s_nop 0
	v_addc_co_u32_e32 v43, vcc, 0, v3, vcc
	v_add_co_u32_e32 v44, vcc, s4, v2
	s_mov_b32 s4, 0x31000
	s_nop 0
	v_addc_co_u32_e32 v45, vcc, 0, v3, vcc
	v_add_co_u32_e32 v46, vcc, s4, v2
	s_mov_b32 s4, 0x34000
	s_nop 0
	v_addc_co_u32_e32 v47, vcc, 0, v3, vcc
	v_add_co_u32_e32 v48, vcc, s4, v2
	s_mov_b32 s4, 0x38000
	s_nop 0
	v_addc_co_u32_e32 v49, vcc, 0, v3, vcc
	global_load_dword v56, v[4:5], off
	global_load_dword v57, v[30:31], off offset:2048
	global_load_dword v58, v[38:39], off
	global_load_dword v59, v[40:41], off offset:2048
	global_load_dword v60, v[42:43], off
	global_load_dword v61, v[44:45], off offset:2048
	global_load_dword v62, v[46:47], off
	global_load_dword v63, v[48:49], off offset:2048
	v_add_co_u32_e32 v4, vcc, s4, v2
	s_mov_b32 s4, 0x3b000
	s_nop 0
	v_addc_co_u32_e32 v5, vcc, 0, v3, vcc
	v_add_co_u32_e32 v30, vcc, s4, v2
	s_mov_b32 s4, 0x3f000
	s_nop 0
	v_addc_co_u32_e32 v31, vcc, 0, v3, vcc
	v_add_co_u32_e32 v38, vcc, s4, v2
	s_mov_b32 s4, 0x42000
	s_nop 0
	v_addc_co_u32_e32 v39, vcc, 0, v3, vcc
	v_add_co_u32_e32 v40, vcc, s4, v2
	s_mov_b32 s4, 0x46000
	s_nop 0
	v_addc_co_u32_e32 v41, vcc, 0, v3, vcc
	v_add_co_u32_e32 v42, vcc, s4, v2
	s_mov_b32 s4, 0x49000
	s_nop 0
	v_addc_co_u32_e32 v43, vcc, 0, v3, vcc
	v_add_co_u32_e32 v44, vcc, s4, v2
	s_mov_b32 s4, 0x4d000
	s_nop 0
	v_addc_co_u32_e32 v45, vcc, 0, v3, vcc
	v_add_co_u32_e32 v46, vcc, s4, v2
	s_mov_b32 s4, 0x50000
	s_nop 0
	v_addc_co_u32_e32 v47, vcc, 0, v3, vcc
	v_add_co_u32_e32 v48, vcc, s4, v2
	s_mov_b32 s4, 0x54000
	s_nop 0
	v_addc_co_u32_e32 v49, vcc, 0, v3, vcc
	global_load_dword v64, v[4:5], off
	global_load_dword v65, v[30:31], off offset:2048
	global_load_dword v66, v[38:39], off
	global_load_dword v67, v[40:41], off offset:2048
	global_load_dword v68, v[42:43], off
	global_load_dword v69, v[44:45], off offset:2048
	global_load_dword v70, v[46:47], off
	s_nop 0
	global_load_dword v48, v[48:49], off offset:2048
	v_add_co_u32_e32 v4, vcc, s4, v2
	s_mov_b32 s4, 0x57000
	s_nop 0
	v_addc_co_u32_e32 v5, vcc, 0, v3, vcc
	v_add_co_u32_e32 v30, vcc, s4, v2
	s_mov_b32 s4, 0x5b000
	s_nop 0
	v_addc_co_u32_e32 v31, vcc, 0, v3, vcc
	v_add_co_u32_e32 v38, vcc, s4, v2
	s_mov_b32 s4, 0x5e000
	s_nop 0
	v_addc_co_u32_e32 v39, vcc, 0, v3, vcc
	v_add_co_u32_e32 v40, vcc, s4, v2
	s_mov_b32 s4, 0x62000
	s_nop 0
	v_addc_co_u32_e32 v41, vcc, 0, v3, vcc
	v_add_co_u32_e32 v42, vcc, s4, v2
	s_mov_b32 s4, 0x65000
	s_nop 0
	v_addc_co_u32_e32 v43, vcc, 0, v3, vcc
	v_add_co_u32_e32 v44, vcc, s4, v2
	s_mov_b32 s4, 0x69000
	s_nop 0
	v_addc_co_u32_e32 v45, vcc, 0, v3, vcc
	v_add_co_u32_e32 v46, vcc, s4, v2
	s_mov_b32 s4, 0x6c000
	s_nop 0
	v_addc_co_u32_e32 v47, vcc, 0, v3, vcc
	v_add_co_u32_e32 v2, vcc, s4, v2
	s_lshl_b32 s88, s1, 8
	s_nop 0
	v_addc_co_u32_e32 v3, vcc, 0, v3, vcc
	global_load_dword v49, v[4:5], off
	global_load_dword v71, v[30:31], off offset:2048
	global_load_dword v72, v[38:39], off
	global_load_dword v73, v[40:41], off offset:2048
	s_nop 0
	global_load_dword v42, v[42:43], off
	s_nop 0
	global_load_dword v43, v[44:45], off offset:2048
	s_nop 0
	global_load_dword v44, v[46:47], off
	global_load_dword v45, v[2:3], off offset:2048
	v_lshl_add_u64 v[30:31], v[24:25], 0, s[88:89]
	global_load_dwordx4 v[2:5], v[30:31], off
	global_load_dwordx4 v[38:41], v[30:31], off offset:16
	s_waitcnt vmcnt(32)
	ds_write2_b32 v36, v0, v29 offset1:66
	s_waitcnt vmcnt(30)
	ds_write2_b32 v36, v50, v51 offset0:132 offset1:198
	v_add_u32_e32 v0, 0x400, v36
	s_waitcnt vmcnt(28)
; #define LAS __attribute__((address_space(3)))
; __device__ __forceinline__ unsigned pk2(float lo, float hi) { return f2bf(lo) | (f2bf(hi) << 16); }
; #define LDS_WAVE_SYNC() asm volatile("s_waitcnt lgkmcnt(0)" ::: "memory")
; template <bool HASG>
; __device__ __forceinline__ void tr_item(const float* W, int K, int N, bf16* WT, int rowmode, const float* g, LAS float* scr, int item, int lane) {
;     ...
;     for (int i = 0; i < 32; ++i) scr[(2 * i + (lane >> 5)) * 33 + (lane & 31)] = v[i];
;     LDS_WAVE_SYNC();
;     const int drow0 = rowmode == 0 ? n0 : ((n0 >> 7) * 256 + (n0 & 127) + (rowmode == 2 ? 128 : 0));
; #pragma unroll
;     for (int j = 0; j < 4; ++j) { const int n = (lane >> 3) + 8 * j; const LAS float* s = scr + (8 * c) * 33 + n;
;         u32x4 o; o.x = pk2(s[0 * 33] * g0.x, s[1 * 33] * g0.y); o.y = pk2(s[2 * 33] * g0.z, s[3 * 33] * g0.w);
;         o.z = pk2(s[4 * 33] * g1.x, s[5 * 33] * g1.y); o.w = pk2(s[6 * 33] * g1.z, s[7 * 33] * g1.w);
;         *(u32x4*)(WT + (size_t)(drow0 + n) * K + k0 + 8 * c) = o; }
	ds_write2_b32 v0, v52, v53 offset0:8 offset1:74
	s_waitcnt vmcnt(26)
	ds_write2_b32 v0, v54, v55 offset0:140 offset1:206
	v_add_u32_e32 v0, 0x800, v36
	s_waitcnt vmcnt(24)
	ds_write2_b32 v0, v56, v57 offset0:16 offset1:82
	s_waitcnt vmcnt(22)
	ds_write2_b32 v0, v58, v59 offset0:148 offset1:214
	v_add_u32_e32 v0, 0xc00, v36
	s_waitcnt vmcnt(20)
	ds_write2_b32 v0, v60, v61 offset0:24 offset1:90
	s_waitcnt vmcnt(18)
	ds_write2_b32 v0, v62, v63 offset0:156 offset1:222
	v_add_u32_e32 v0, 0x1000, v36
	s_waitcnt vmcnt(16)
	ds_write2_b32 v0, v64, v65 offset0:32 offset1:98
	s_waitcnt vmcnt(14)
	ds_write2_b32 v0, v66, v67 offset0:164 offset1:230
	v_add_u32_e32 v0, 0x1400, v36
	s_waitcnt vmcnt(12)
	ds_write2_b32 v0, v68, v69 offset0:40 offset1:106
	s_waitcnt vmcnt(10)
	ds_write2_b32 v0, v70, v48 offset0:172 offset1:238
	v_add_u32_e32 v0, 0x1800, v36
	s_waitcnt vmcnt(8)
	ds_write2_b32 v0, v49, v71 offset0:48 offset1:114
	s_waitcnt vmcnt(6)
	ds_write2_b32 v0, v72, v73 offset0:180 offset1:246
	v_add_u32_e32 v0, 0x1c00, v36
	s_waitcnt vmcnt(4)
	ds_write2_b32 v0, v42, v43 offset0:56 offset1:122
	s_waitcnt vmcnt(2)
	ds_write2_b32 v0, v44, v45 offset0:188 offset1:254
	s_waitcnt lgkmcnt(0)
	ds_read2_b32 v[46:47], v37 offset0:33 offset1:41
	ds_read2_b32 v[48:49], v37 offset1:8
	ds_read2_b32 v[50:51], v37 offset0:66 offset1:74
	ds_read2_b32 v[52:53], v37 offset0:99 offset1:107
	ds_read2_b32 v[56:57], v37 offset0:132 offset1:140
	ds_read2_b32 v[58:59], v37 offset0:165 offset1:173
	ds_read2_b32 v[60:61], v37 offset0:198 offset1:206
	ds_read2_b32 v[62:63], v37 offset0:231 offset1:239
	s_waitcnt vmcnt(1)
	v_mov_b32_e32 v54, v2
	v_mov_b32_e32 v55, v4
	v_mov_b32_e32 v4, v3
	s_waitcnt lgkmcnt(7)
	v_mov_b32_e32 v2, v46
	s_waitcnt lgkmcnt(4)
	v_mov_b32_e32 v3, v52
	v_pk_mul_f32 v[2:3], v[4:5], v[2:3]
	s_waitcnt vmcnt(0)
	v_mov_b32_e32 v64, v38
	v_mov_b32_e32 v65, v40
	s_waitcnt lgkmcnt(3)
	v_mov_b32_e32 v44, v56
	s_waitcnt lgkmcnt(1)
	v_mov_b32_e32 v45, v60
	v_mov_b32_e32 v40, v39
	v_mov_b32_e32 v38, v58
	s_waitcnt lgkmcnt(0)
	v_mov_b32_e32 v39, v62
	v_mov_b32_e32 v42, v48
	v_mov_b32_e32 v43, v50
	v_pk_mul_f32 v[44:45], v[64:65], v[44:45]
	v_pk_mul_f32 v[38:39], v[40:41], v[38:39]
	v_bfe_u32 v48, v2, 16, 1
	v_pk_mul_f32 v[42:43], v[54:55], v[42:43]
	v_bfe_u32 v0, v39, 16, 1
	v_add3_u32 v2, v2, v48, s91
	v_bfe_u32 v48, v45, 16, 1
	v_bfe_u32 v29, v38, 16, 1
	v_bfe_u32 v46, v3, 16, 1
	v_add3_u32 v0, v39, v0, s91
	v_bfe_u32 v39, v43, 16, 1
	v_add3_u32 v45, v45, v48, s91
	v_add3_u32 v3, v3, v46, s91
	v_add3_u32 v29, v38, v29, s91
	v_bfe_u32 v38, v42, 16, 1
	v_bfe_u32 v46, v44, 16, 1
	v_add3_u32 v39, v43, v39, s91
	v_lshrrev_b32_e32 v43, 16, v45
	s_lshl_b32 s88, s1, 7
	v_add3_u32 v44, v44, v46, s91
	v_add3_u32 v38, v42, v38, s91
	v_and_or_b32 v45, v0, s35, v43
	v_or_b32_e32 v0, s0, v7
	v_lshl_add_u64 v[30:31], v[16:17], 0, s[88:89]
	v_lshrrev_b32_e32 v38, 16, v38
	v_lshrrev_b32_e32 v39, 16, v39
	v_lshrrev_b32_e32 v42, 16, v44
	v_lshlrev_b32_e32 v0, 11, v0
	v_mov_b32_e32 v52, v47
	v_and_or_b32 v44, v29, s35, v42
	v_and_or_b32 v43, v3, s35, v39
	v_and_or_b32 v42, v2, s35, v38
	v_lshl_add_u64 v[2:3], v[30:31], 0, v[0:1]
	v_pk_mul_f32 v[38:39], v[4:5], v[52:53]
	v_mov_b32_e32 v60, v57
	global_store_dwordx4 v[2:3], v[42:45], off sc1
	v_mov_b32_e32 v62, v59
	v_bfe_u32 v47, v38, 16, 1
	v_pk_mul_f32 v[42:43], v[64:65], v[60:61]
	v_mov_b32_e32 v50, v49
	v_pk_mul_f32 v[44:45], v[40:41], v[62:63]
	v_add3_u32 v38, v38, v47, s91
	v_bfe_u32 v47, v43, 16, 1
	v_pk_mul_f32 v[2:3], v[54:55], v[50:51]
	v_bfe_u32 v0, v45, 16, 1
	v_bfe_u32 v29, v44, 16, 1
	v_bfe_u32 v46, v39, 16, 1
	v_add3_u32 v43, v43, v47, s91
	v_add3_u32 v39, v39, v46, s91
	v_add3_u32 v29, v44, v29, s91
	v_add3_u32 v0, v45, v0, s91
	v_bfe_u32 v44, v2, 16, 1
	v_bfe_u32 v45, v3, 16, 1
	v_bfe_u32 v46, v42, 16, 1
	v_lshrrev_b32_e32 v43, 16, v43
	v_add3_u32 v42, v42, v46, s91
	v_add3_u32 v3, v3, v45, s91
	v_add3_u32 v2, v2, v44, s91
	v_and_or_b32 v45, v0, s35, v43
	v_or_b32_e32 v0, s0, v32
	v_lshrrev_b32_e32 v2, 16, v2
	v_lshrrev_b32_e32 v3, 16, v3
	v_lshrrev_b32_e32 v42, 16, v42
	v_lshlrev_b32_e32 v0, 11, v0
	v_and_or_b32 v44, v29, s35, v42
	v_and_or_b32 v43, v39, s35, v3
	v_and_or_b32 v42, v38, s35, v2
	v_lshl_add_u64 v[2:3], v[30:31], 0, v[0:1]
	ds_read2_b32 v[38:39], v37 offset0:16 offset1:24
	ds_read2_b32 v[46:47], v37 offset0:82 offset1:90
	global_store_dwordx4 v[2:3], v[42:45], off sc1
	ds_read2_b32 v[2:3], v37 offset0:49 offset1:57
	ds_read2_b32 v[48:49], v37 offset0:115 offset1:123
	ds_read2_b32 v[50:51], v37 offset0:148 offset1:156
	ds_read2_b32 v[52:53], v37 offset0:214 offset1:222
	ds_read2_b32 v[56:57], v37 offset0:181 offset1:189
	ds_read2_b32 v[58:59], v37 offset0:247 offset1:255
	s_waitcnt lgkmcnt(7)
; #define LAS __attribute__((address_space(3)))
; __device__ __forceinline__ unsigned pk2(float lo, float hi) { return f2bf(lo) | (f2bf(hi) << 16); }
; #define LDS_WAVE_SYNC() asm volatile("s_waitcnt lgkmcnt(0)" ::: "memory")
; template <bool HASG>
; __device__ __forceinline__ void tr_item(const float* W, int K, int N, bf16* WT, int rowmode, const float* g, LAS float* scr, int item, int lane) {
;     ...
;     for (int j = 0; j < 4; ++j) { const int n = (lane >> 3) + 8 * j; const LAS float* s = scr + (8 * c) * 33 + n;
;         u32x4 o; o.x = pk2(s[0 * 33] * g0.x, s[1 * 33] * g0.y); o.y = pk2(s[2 * 33] * g0.z, s[3 * 33] * g0.w);
;         o.z = pk2(s[4 * 33] * g1.x, s[5 * 33] * g1.y); o.w = pk2(s[6 * 33] * g1.z, s[7 * 33] * g1.w);
;         *(u32x4*)(WT + (size_t)(drow0 + n) * K + k0 + 8 * c) = o; }
;     LDS_WAVE_SYNC();
	v_mov_b32_e32 v42, v38
	s_waitcnt lgkmcnt(5)
	v_mov_b32_e32 v44, v2
	s_waitcnt lgkmcnt(4)
	v_mov_b32_e32 v45, v48
	s_waitcnt lgkmcnt(3)
	v_mov_b32_e32 v60, v50
	s_waitcnt lgkmcnt(2)
	v_mov_b32_e32 v61, v52
	v_mov_b32_e32 v43, v46
	v_pk_mul_f32 v[44:45], v[4:5], v[44:45]
	v_pk_mul_f32 v[60:61], v[64:65], v[60:61]
	s_waitcnt lgkmcnt(1)
	v_mov_b32_e32 v62, v56
	s_waitcnt lgkmcnt(0)
	v_mov_b32_e32 v63, v58
	v_pk_mul_f32 v[42:43], v[54:55], v[42:43]
	v_pk_mul_f32 v[62:63], v[40:41], v[62:63]
	v_bfe_u32 v29, v45, 16, 1
	v_bfe_u32 v48, v61, 16, 1
	v_bfe_u32 v0, v63, 16, 1
	v_bfe_u32 v38, v44, 16, 1
	v_add3_u32 v29, v45, v29, s91
	v_bfe_u32 v45, v43, 16, 1
	v_add3_u32 v48, v61, v48, s91
	v_add3_u32 v38, v44, v38, s91
	v_add3_u32 v0, v63, v0, s91
	v_bfe_u32 v44, v42, 16, 1
	v_bfe_u32 v46, v60, 16, 1
	v_add3_u32 v43, v43, v45, s91
	v_lshrrev_b32_e32 v45, 16, v48
	v_bfe_u32 v2, v62, 16, 1
	v_add3_u32 v46, v60, v46, s91
	v_add3_u32 v42, v42, v44, s91
	v_and_or_b32 v45, v0, s35, v45
	v_or_b32_e32 v0, s0, v34
	v_add3_u32 v2, v62, v2, s91
	v_lshrrev_b32_e32 v42, 16, v42
	v_lshrrev_b32_e32 v43, 16, v43
	v_lshrrev_b32_e32 v44, 16, v46
	v_lshlrev_b32_e32 v0, 11, v0
	v_mov_b32_e32 v48, v3
	v_and_or_b32 v44, v2, s35, v44
	v_and_or_b32 v43, v29, s35, v43
	v_and_or_b32 v42, v38, s35, v42
	v_lshl_add_u64 v[60:61], v[30:31], 0, v[0:1]
	v_pk_mul_f32 v[2:3], v[4:5], v[48:49]
	v_mov_b32_e32 v52, v51
	global_store_dwordx4 v[60:61], v[42:45], off sc1
	v_pk_mul_f32 v[4:5], v[64:65], v[52:53]
	v_mov_b32_e32 v58, v57
	v_bfe_u32 v43, v2, 16, 1
	v_mov_b32_e32 v46, v39
	v_pk_mul_f32 v[40:41], v[40:41], v[58:59]
	v_add3_u32 v2, v2, v43, s91
	v_bfe_u32 v43, v5, 16, 1
	v_pk_mul_f32 v[38:39], v[54:55], v[46:47]
	v_bfe_u32 v0, v41, 16, 1
	v_bfe_u32 v29, v40, 16, 1
	v_bfe_u32 v42, v3, 16, 1
	v_add3_u32 v5, v5, v43, s91
	v_add3_u32 v3, v3, v42, s91
	v_add3_u32 v29, v40, v29, s91
	v_add3_u32 v0, v41, v0, s91
	v_bfe_u32 v40, v38, 16, 1
	v_bfe_u32 v41, v39, 16, 1
	v_bfe_u32 v42, v4, 16, 1
	v_lshrrev_b32_e32 v5, 16, v5
	v_add3_u32 v4, v4, v42, s91
	v_add3_u32 v39, v39, v41, s91
	v_add3_u32 v38, v38, v40, s91
	v_and_or_b32 v5, v0, s35, v5
	v_or_b32_e32 v0, s0, v35
	v_lshrrev_b32_e32 v38, 16, v38
	v_lshrrev_b32_e32 v39, 16, v39
	v_lshrrev_b32_e32 v4, 16, v4
	v_lshlrev_b32_e32 v0, 11, v0
	v_and_or_b32 v4, v29, s35, v4
	v_and_or_b32 v3, v3, s35, v39
	v_and_or_b32 v2, v2, s35, v38
	v_lshl_add_u64 v[30:31], v[30:31], 0, v[0:1]
	global_store_dwordx4 v[30:31], v[2:5], off sc1
	s_waitcnt lgkmcnt(0)
	v_readlane_b32 s5, v252, 1
	v_readlane_b32 s6, v252, 2
	v_readlane_b32 s7, v252, 3
	v_readlane_b32 s8, v252, 4
	v_readlane_b32 s9, v252, 5
	v_readlane_b32 s10, v252, 6
	v_readlane_b32 s11, v252, 7
	v_readlane_b32 s12, v252, 8
	v_readlane_b32 s13, v252, 9
	v_readlane_b32 s14, v252, 10
	v_readlane_b32 s15, v252, 11
	v_readlane_b32 s18, v252, 14
	v_readlane_b32 s19, v252, 15

; template <bool HASG>
; __device__ __forceinline__ void tr_item(const float* W, int K, int N, bf16* WT, int rowmode, const float* g, LAS float* scr, int item, int lane) {
;     const int nblk = N / 32, kb = item / nblk, nb = item % nblk, k0 = 64 * kb, n0 = 32 * nb;
;     const float* wp = W + (size_t)(k0 + (lane >> 5)) * N + n0 + (lane & 31);
;     const int c = lane & 7;
;     float v[32];
; #pragma unroll
;     for (int i = 0; i < 32; ++i) v[i] = wp[(size_t)(2 * i) * N];
; __device__ __forceinline__ void convert_items(const Args& a, LAS unsigned char* lds, int l, int it_lo, int it_hi, int gw, int NGW, int wave, int lane) {
;     ...
;         if (r < I_D) { tr_item<false>(a.in[4] + o_d, FF, D, wl + W_D1, 0, nullptr, scr, r, lane); continue; } r -= I_D;
.LBB0_596:
	s_andn2_b64 vcc, exec, s[0:1]
	s_cbranch_vccnz .LBB0_598
	s_add_i32 s0, s43, 0x2c00
	s_and_b32 s1, s0, 0x1ffc0
	s_lshl_b32 s0, s28, 5
	v_or_b32_e32 v0, s1, v33
	v_readlane_b32 s4, v252, 0
	s_and_b32 s0, s0, 0x3e0
	v_lshlrev_b32_e32 v0, 12, v0
	v_readlane_b32 s12, v252, 8
	v_readlane_b32 s13, v252, 9
	s_lshl_b32 s88, s0, 2
	s_movk_i32 s4, 0x2000
	v_lshl_add_u64 v[2:3], s[12:13], 0, v[0:1]
	v_lshl_add_u64 v[2:3], v[2:3], 0, s[88:89]
	v_lshlrev_b32_e32 v0, 2, v6
	v_lshl_add_u64 v[2:3], v[2:3], 0, v[0:1]
	v_add_co_u32_e32 v4, vcc, s4, v2
	s_movk_i32 s4, 0x4000
	s_nop 0
	v_addc_co_u32_e32 v5, vcc, 0, v3, vcc
	global_load_dword v0, v[2:3], off
	global_load_dword v29, v[4:5], off
	v_add_co_u32_e32 v4, vcc, s4, v2
	s_movk_i32 s4, 0x6000
	s_nop 0
	v_addc_co_u32_e32 v5, vcc, 0, v3, vcc
	global_load_dword v30, v[4:5], off
	v_add_co_u32_e32 v4, vcc, s4, v2
	s_mov_b32 s4, 0x8000
	s_nop 0
	v_addc_co_u32_e32 v5, vcc, 0, v3, vcc
	global_load_dword v31, v[4:5], off
	v_add_co_u32_e32 v4, vcc, s4, v2
	s_mov_b32 s4, 0xa000
	s_nop 0
	v_addc_co_u32_e32 v5, vcc, 0, v3, vcc
	global_load_dword v38, v[4:5], off
	v_add_co_u32_e32 v4, vcc, s4, v2
	s_mov_b32 s4, 0xc000
	s_nop 0
	v_addc_co_u32_e32 v5, vcc, 0, v3, vcc
	global_load_dword v39, v[4:5], off
	v_add_co_u32_e32 v4, vcc, s4, v2
	s_mov_b32 s4, 0xe000
	s_nop 0
	v_addc_co_u32_e32 v5, vcc, 0, v3, vcc
	global_load_dword v40, v[4:5], off
	v_add_co_u32_e32 v4, vcc, s4, v2
	s_mov_b32 s4, 0x12000
	s_nop 0
	v_addc_co_u32_e32 v5, vcc, 0, v3, vcc
	global_load_dword v41, v[4:5], off
	v_add_co_u32_e32 v4, vcc, s70, v2
	s_lshl_b32 s88, s1, 1
	s_nop 0
	v_addc_co_u32_e32 v5, vcc, 0, v3, vcc
	global_load_dword v42, v[4:5], off
	v_add_co_u32_e32 v4, vcc, s4, v2
	s_mov_b32 s4, 0x14000
	s_nop 0
	v_addc_co_u32_e32 v5, vcc, 0, v3, vcc
	global_load_dword v43, v[4:5], off
	v_add_co_u32_e32 v4, vcc, s4, v2
	s_mov_b32 s4, 0x18000
	s_nop 0
	v_addc_co_u32_e32 v5, vcc, 0, v3, vcc
	global_load_dword v44, v[4:5], off
	v_add_co_u32_e32 v4, vcc, s71, v2
	v_readlane_b32 s5, v252, 1
	s_nop 0
	v_addc_co_u32_e32 v5, vcc, 0, v3, vcc
	global_load_dword v45, v[4:5], off
	v_add_co_u32_e32 v4, vcc, s4, v2
	s_mov_b32 s4, 0x1a000
	s_nop 0
	v_addc_co_u32_e32 v5, vcc, 0, v3, vcc
	global_load_dword v46, v[4:5], off
	v_add_co_u32_e32 v4, vcc, s4, v2
	s_mov_b32 s4, 0x1c000
	s_nop 0
	v_addc_co_u32_e32 v5, vcc, 0, v3, vcc
	global_load_dword v47, v[4:5], off
	v_add_co_u32_e32 v4, vcc, s4, v2
	s_mov_b32 s4, 0x1e000
	s_nop 0
	v_addc_co_u32_e32 v5, vcc, 0, v3, vcc
	global_load_dword v48, v[4:5], off
	v_add_co_u32_e32 v4, vcc, s4, v2
	s_mov_b32 s4, 0x20000
	s_nop 0
	v_addc_co_u32_e32 v5, vcc, 0, v3, vcc
	global_load_dword v49, v[4:5], off
	v_add_co_u32_e32 v4, vcc, s4, v2
	s_mov_b32 s4, 0x22000
	s_nop 0
	v_addc_co_u32_e32 v5, vcc, 0, v3, vcc
	global_load_dword v50, v[4:5], off
	v_add_co_u32_e32 v4, vcc, s4, v2
	s_mov_b32 s4, 0x24000
	s_nop 0
	v_addc_co_u32_e32 v5, vcc, 0, v3, vcc
	global_load_dword v51, v[4:5], off
	v_add_co_u32_e32 v4, vcc, s4, v2
	s_mov_b32 s4, 0x26000
	s_nop 0
	v_addc_co_u32_e32 v5, vcc, 0, v3, vcc
	global_load_dword v52, v[4:5], off
	v_add_co_u32_e32 v4, vcc, s4, v2
	s_mov_b32 s4, 0x28000
	s_nop 0
	v_addc_co_u32_e32 v5, vcc, 0, v3, vcc
	global_load_dword v53, v[4:5], off
	v_add_co_u32_e32 v4, vcc, s4, v2
	s_mov_b32 s4, 0x2a000
	s_nop 0
	v_addc_co_u32_e32 v5, vcc, 0, v3, vcc
	global_load_dword v54, v[4:5], off
	v_add_co_u32_e32 v4, vcc, s4, v2
	s_mov_b32 s4, 0x2c000
	s_nop 0
	v_addc_co_u32_e32 v5, vcc, 0, v3, vcc
	global_load_dword v55, v[4:5], off
	v_add_co_u32_e32 v4, vcc, s4, v2
	s_mov_b32 s4, 0x2e000
	s_nop 0
	v_addc_co_u32_e32 v5, vcc, 0, v3, vcc
	global_load_dword v56, v[4:5], off
	v_add_co_u32_e32 v4, vcc, s4, v2
	s_mov_b32 s4, 0x30000
	s_nop 0
	v_addc_co_u32_e32 v5, vcc, 0, v3, vcc
	global_load_dword v57, v[4:5], off
	v_add_co_u32_e32 v4, vcc, s4, v2
	s_mov_b32 s4, 0x32000
	s_nop 0
	v_addc_co_u32_e32 v5, vcc, 0, v3, vcc
	global_load_dword v58, v[4:5], off
	v_add_co_u32_e32 v4, vcc, s4, v2
	s_mov_b32 s4, 0x34000
	s_nop 0
	v_addc_co_u32_e32 v5, vcc, 0, v3, vcc
	global_load_dword v59, v[4:5], off
	v_add_co_u32_e32 v4, vcc, s4, v2
	s_mov_b32 s4, 0x36000
	s_nop 0
	v_addc_co_u32_e32 v5, vcc, 0, v3, vcc
	global_load_dword v60, v[4:5], off
	v_add_co_u32_e32 v4, vcc, s4, v2
	s_mov_b32 s4, 0x38000
	s_nop 0
	v_addc_co_u32_e32 v5, vcc, 0, v3, vcc
	global_load_dword v61, v[4:5], off
	v_add_co_u32_e32 v4, vcc, s4, v2
	s_mov_b32 s4, 0x3a000
	s_nop 0
	v_addc_co_u32_e32 v5, vcc, 0, v3, vcc
	global_load_dword v62, v[4:5], off
	v_add_co_u32_e32 v4, vcc, s4, v2
	s_mov_b32 s4, 0x3c000
	s_nop 0
	v_addc_co_u32_e32 v5, vcc, 0, v3, vcc
	global_load_dword v63, v[4:5], off
	v_add_co_u32_e32 v4, vcc, s4, v2
	s_mov_b32 s4, 0x3e000
	s_nop 0
	v_addc_co_u32_e32 v5, vcc, 0, v3, vcc
	v_add_co_u32_e32 v2, vcc, s4, v2
	global_load_dword v4, v[4:5], off
	s_nop 0
	v_addc_co_u32_e32 v3, vcc, 0, v3, vcc
	global_load_dword v2, v[2:3], off
	s_waitcnt vmcnt(30)
	ds_write2_b32 v36, v0, v29 offset1:66
	s_waitcnt vmcnt(28)
	ds_write2_b32 v36, v30, v31 offset0:132 offset1:198
	v_add_u32_e32 v0, 0x400, v36
	s_waitcnt vmcnt(26)
	ds_write2_b32 v0, v38, v39 offset0:8 offset1:74
	s_waitcnt vmcnt(24)
	ds_write2_b32 v0, v40, v41 offset0:140 offset1:206
	v_add_u32_e32 v0, 0x800, v36
	s_waitcnt vmcnt(22)
	ds_write2_b32 v0, v42, v43 offset0:16 offset1:82
	s_waitcnt vmcnt(20)
	ds_write2_b32 v0, v44, v45 offset0:148 offset1:214
	v_add_u32_e32 v0, 0xc00, v36
	s_waitcnt vmcnt(18)
	ds_write2_b32 v0, v46, v47 offset0:24 offset1:90
	s_waitcnt vmcnt(16)
	ds_write2_b32 v0, v48, v49 offset0:156 offset1:222
	v_add_u32_e32 v0, 0x1000, v36
	s_waitcnt vmcnt(14)
; #define LAS __attribute__((address_space(3)))
; __device__ __forceinline__ unsigned pk2(float lo, float hi) { return f2bf(lo) | (f2bf(hi) << 16); }
; #define LDS_WAVE_SYNC() asm volatile("s_waitcnt lgkmcnt(0)" ::: "memory")
; template <bool HASG>
; __device__ __forceinline__ void tr_item(const float* W, int K, int N, bf16* WT, int rowmode, const float* g, LAS float* scr, int item, int lane) {
;     ...
;     for (int i = 0; i < 32; ++i) scr[(2 * i + (lane >> 5)) * 33 + (lane & 31)] = v[i];
;     LDS_WAVE_SYNC();
;     const int drow0 = rowmode == 0 ? n0 : ((n0 >> 7) * 256 + (n0 & 127) + (rowmode == 2 ? 128 : 0));
; #pragma unroll
;     for (int j = 0; j < 4; ++j) { const int n = (lane >> 3) + 8 * j; const LAS float* s = scr + (8 * c) * 33 + n;
;         u32x4 o; o.x = pk2(s[0 * 33] * g0.x, s[1 * 33] * g0.y); o.y = pk2(s[2 * 33] * g0.z, s[3 * 33] * g0.w);
;         o.z = pk2(s[4 * 33] * g1.x, s[5 * 33] * g1.y); o.w = pk2(s[6 * 33] * g1.z, s[7 * 33] * g1.w);
;         *(u32x4*)(WT + (size_t)(drow0 + n) * K + k0 + 8 * c) = o; }
;     LDS_WAVE_SYNC();
	ds_write2_b32 v0, v50, v51 offset0:32 offset1:98
	s_waitcnt vmcnt(12)
	ds_write2_b32 v0, v52, v53 offset0:164 offset1:230
	v_add_u32_e32 v0, 0x1400, v36
	s_waitcnt vmcnt(10)
	ds_write2_b32 v0, v54, v55 offset0:40 offset1:106
	s_waitcnt vmcnt(8)
	ds_write2_b32 v0, v56, v57 offset0:172 offset1:238
	v_add_u32_e32 v0, 0x1800, v36
	s_waitcnt vmcnt(6)
	ds_write2_b32 v0, v58, v59 offset0:48 offset1:114
	s_waitcnt vmcnt(4)
	ds_write2_b32 v0, v60, v61 offset0:180 offset1:246
	v_add_u32_e32 v0, 0x1c00, v36
	s_waitcnt vmcnt(2)
	ds_write2_b32 v0, v62, v63 offset0:56 offset1:122
	s_waitcnt vmcnt(0)
	ds_write2_b32 v0, v4, v2 offset0:188 offset1:254
	s_waitcnt lgkmcnt(0)
	ds_read2_b32 v[4:5], v37 offset0:33 offset1:41
	ds_read2_b32 v[30:31], v37 offset1:8
	ds_read2_b32 v[42:43], v37 offset0:66 offset1:74
	ds_read2_b32 v[44:45], v37 offset0:99 offset1:107
	ds_read2_b32 v[46:47], v37 offset0:132 offset1:140
	ds_read2_b32 v[48:49], v37 offset0:165 offset1:173
	ds_read2_b32 v[50:51], v37 offset0:198 offset1:206
	ds_read2_b32 v[52:53], v37 offset0:231 offset1:239
	s_waitcnt lgkmcnt(7)
	v_bfe_u32 v29, v4, 16, 1
	s_waitcnt lgkmcnt(6)
	v_bfe_u32 v0, v30, 16, 1
	v_add3_u32 v0, v30, v0, s91
	v_lshrrev_b32_e32 v0, 16, v0
	v_add3_u32 v4, v4, v29, s91
	v_and_or_b32 v38, v4, s35, v0
	s_waitcnt lgkmcnt(5)
	v_bfe_u32 v0, v42, 16, 1
	v_add3_u32 v0, v42, v0, s91
	s_waitcnt lgkmcnt(4)
	v_bfe_u32 v4, v44, 16, 1
	v_lshrrev_b32_e32 v0, 16, v0
	v_add3_u32 v4, v44, v4, s91
	v_and_or_b32 v39, v4, s35, v0
	s_waitcnt lgkmcnt(3)
	v_bfe_u32 v0, v46, 16, 1
	v_add3_u32 v0, v46, v0, s91
	s_waitcnt lgkmcnt(2)
	v_bfe_u32 v4, v48, 16, 1
	v_lshrrev_b32_e32 v0, 16, v0
	v_add3_u32 v4, v48, v4, s91
	v_and_or_b32 v40, v4, s35, v0
	s_waitcnt lgkmcnt(1)
	v_bfe_u32 v0, v50, 16, 1
	v_add3_u32 v0, v50, v0, s91
	s_waitcnt lgkmcnt(0)
	v_bfe_u32 v4, v52, 16, 1
	v_lshrrev_b32_e32 v0, 16, v0
	v_add3_u32 v4, v52, v4, s91
	v_and_or_b32 v41, v4, s35, v0
	v_or_b32_e32 v0, s0, v7
	v_mul_u32_u24_e32 v0, 0xb00, v0
	v_lshl_add_u64 v[2:3], v[18:19], 0, s[88:89]
	v_lshlrev_b32_e32 v0, 1, v0
	v_lshl_add_u64 v[54:55], v[2:3], 0, v[0:1]
	v_bfe_u32 v0, v31, 16, 1
	v_add3_u32 v0, v31, v0, s91
	v_bfe_u32 v4, v5, 16, 1
	v_lshrrev_b32_e32 v0, 16, v0
	v_add3_u32 v4, v5, v4, s91
	global_store_dwordx4 v[54:55], v[38:41], off sc1
	v_readlane_b32 s6, v252, 2
	v_readlane_b32 s7, v252, 3
	v_and_or_b32 v38, v4, s35, v0
	v_bfe_u32 v0, v43, 16, 1
	v_add3_u32 v0, v43, v0, s91
	v_bfe_u32 v4, v45, 16, 1
	v_lshrrev_b32_e32 v0, 16, v0
	v_add3_u32 v4, v45, v4, s91
	v_and_or_b32 v39, v4, s35, v0
	v_bfe_u32 v0, v47, 16, 1
	v_add3_u32 v0, v47, v0, s91
	v_bfe_u32 v4, v49, 16, 1
	v_lshrrev_b32_e32 v0, 16, v0
	v_add3_u32 v4, v49, v4, s91
	v_and_or_b32 v40, v4, s35, v0
	v_bfe_u32 v0, v51, 16, 1
	v_add3_u32 v0, v51, v0, s91
	v_bfe_u32 v4, v53, 16, 1
	v_lshrrev_b32_e32 v0, 16, v0
	v_add3_u32 v4, v53, v4, s91
	v_and_or_b32 v41, v4, s35, v0
	v_or_b32_e32 v0, s0, v32
	v_mul_u32_u24_e32 v0, 0xb00, v0
	v_lshlrev_b32_e32 v0, 1, v0
	v_lshl_add_u64 v[4:5], v[2:3], 0, v[0:1]
	global_store_dwordx4 v[4:5], v[38:41], off sc1
	ds_read2_b32 v[4:5], v37 offset0:16 offset1:24
	ds_read2_b32 v[30:31], v37 offset0:49 offset1:57
	ds_read2_b32 v[42:43], v37 offset0:82 offset1:90
	ds_read2_b32 v[44:45], v37 offset0:115 offset1:123
	ds_read2_b32 v[46:47], v37 offset0:148 offset1:156
	ds_read2_b32 v[48:49], v37 offset0:181 offset1:189
	ds_read2_b32 v[50:51], v37 offset0:214 offset1:222
	ds_read2_b32 v[52:53], v37 offset0:247 offset1:255
	s_waitcnt lgkmcnt(7)
	v_bfe_u32 v0, v4, 16, 1
	v_add3_u32 v0, v4, v0, s91
	s_waitcnt lgkmcnt(6)
	v_bfe_u32 v4, v30, 16, 1
	v_lshrrev_b32_e32 v0, 16, v0
	v_add3_u32 v4, v30, v4, s91
	v_and_or_b32 v38, v4, s35, v0
	s_waitcnt lgkmcnt(5)
	v_bfe_u32 v0, v42, 16, 1
	v_add3_u32 v0, v42, v0, s91
	s_waitcnt lgkmcnt(4)
	v_bfe_u32 v4, v44, 16, 1
	v_lshrrev_b32_e32 v0, 16, v0
	v_add3_u32 v4, v44, v4, s91
	v_and_or_b32 v39, v4, s35, v0
	s_waitcnt lgkmcnt(3)
	v_bfe_u32 v0, v46, 16, 1
	v_add3_u32 v0, v46, v0, s91
	s_waitcnt lgkmcnt(2)
	v_bfe_u32 v4, v48, 16, 1
	v_lshrrev_b32_e32 v0, 16, v0
	v_add3_u32 v4, v48, v4, s91
	v_and_or_b32 v40, v4, s35, v0
	s_waitcnt lgkmcnt(1)
	v_bfe_u32 v0, v50, 16, 1
	v_add3_u32 v0, v50, v0, s91
	s_waitcnt lgkmcnt(0)
	v_bfe_u32 v4, v52, 16, 1
	v_lshrrev_b32_e32 v0, 16, v0
	v_add3_u32 v4, v52, v4, s91
	v_and_or_b32 v41, v4, s35, v0
	v_or_b32_e32 v0, s0, v34
	v_mul_u32_u24_e32 v0, 0xb00, v0
	v_lshlrev_b32_e32 v0, 1, v0
	v_lshl_add_u64 v[54:55], v[2:3], 0, v[0:1]
	v_bfe_u32 v0, v5, 16, 1
	v_add3_u32 v0, v5, v0, s91
	v_bfe_u32 v4, v31, 16, 1
	v_lshrrev_b32_e32 v0, 16, v0
	v_add3_u32 v4, v31, v4, s91
	global_store_dwordx4 v[54:55], v[38:41], off sc1
	v_readlane_b32 s8, v252, 4
	v_readlane_b32 s9, v252, 5
	v_and_or_b32 v38, v4, s35, v0
	v_bfe_u32 v0, v43, 16, 1
	v_add3_u32 v0, v43, v0, s91
	v_bfe_u32 v4, v45, 16, 1
	v_lshrrev_b32_e32 v0, 16, v0
	v_add3_u32 v4, v45, v4, s91
	v_and_or_b32 v39, v4, s35, v0
	v_bfe_u32 v0, v47, 16, 1
	v_add3_u32 v0, v47, v0, s91
	v_bfe_u32 v4, v49, 16, 1
	v_lshrrev_b32_e32 v0, 16, v0
	v_add3_u32 v4, v49, v4, s91
	v_and_or_b32 v40, v4, s35, v0
	v_bfe_u32 v0, v51, 16, 1
	v_add3_u32 v0, v51, v0, s91
	v_bfe_u32 v4, v53, 16, 1
	v_lshrrev_b32_e32 v0, 16, v0
	v_add3_u32 v4, v53, v4, s91
	v_and_or_b32 v41, v4, s35, v0
	v_or_b32_e32 v0, s0, v35
	v_mul_u32_u24_e32 v0, 0xb00, v0
	v_lshlrev_b32_e32 v0, 1, v0
	v_lshl_add_u64 v[2:3], v[2:3], 0, v[0:1]
	global_store_dwordx4 v[2:3], v[38:41], off sc1
	s_waitcnt lgkmcnt(0)
	v_readlane_b32 s10, v252, 6
	v_readlane_b32 s11, v252, 7
	v_readlane_b32 s14, v252, 10
	v_readlane_b32 s15, v252, 11
	v_readlane_b32 s16, v252, 12
	v_readlane_b32 s17, v252, 13
	v_readlane_b32 s18, v252, 14
	v_readlane_b32 s19, v252, 15

; template <bool HASG>
; __device__ __forceinline__ void tr_item(const float* W, int K, int N, bf16* WT, int rowmode, const float* g, LAS float* scr, int item, int lane) {
;     const int nblk = N / 32, kb = item / nblk, nb = item % nblk, k0 = 64 * kb, n0 = 32 * nb;
;     const float* wp = W + (size_t)(k0 + (lane >> 5)) * N + n0 + (lane & 31);
;     const int c = lane & 7;
;     float v[32];
; #pragma unroll
;     for (int i = 0; i < 32; ++i) v[i] = wp[(size_t)(2 * i) * N];
;     f32x4 g0 = (f32x4){1.f, 1.f, 1.f, 1.f}, g1 = g0;
;     if (HASG) { g0 = *(const f32x4*)(g + k0 + 8 * c); g1 = *(const f32x4*)(g + k0 + 8 * c + 4); }
; __device__ __forceinline__ void convert_items(const Args& a, LAS unsigned char* lds, int l, int it_lo, int it_hi, int gw, int NGW, int wave, int lane) {
;     ...
;         if (r < I_G) { tr_item<true>(a.in[3] + o_gu, D, FF, wl + W_GU1, 2, a.in[1] + l * D, scr, r, lane); continue; } r -= I_G;
.LBB0_599:
	s_andn2_b64 vcc, exec, s[0:1]
	s_cbranch_vccnz .LBB0_601
	s_add_i32 s0, s28, 0xfa80
	s_and_b32 s1, s0, 0xffff
	s_mul_i32 s1, s1, 0xba2f
	s_lshr_b32 s38, s1, 16
	s_lshr_b32 s1, s1, 22
	s_mulk_i32 s1, 0x58
	s_sub_i32 s0, s0, s1
	s_and_b32 s1, s38, 0xffc0
	v_or_b32_e32 v0, s1, v33
	v_mul_u32_u24_e32 v0, 0xb00, v0
	v_readlane_b32 s4, v252, 0
	s_and_b32 s39, s0, 0xffff
	v_lshlrev_b32_e32 v0, 2, v0
	v_readlane_b32 s10, v252, 6
	v_readlane_b32 s11, v252, 7
	s_lshl_b32 s88, s39, 7
	s_movk_i32 s4, 0x5000
	v_lshl_add_u64 v[2:3], s[10:11], 0, v[0:1]
	v_lshl_add_u64 v[2:3], v[2:3], 0, s[88:89]
	v_lshlrev_b32_e32 v0, 2, v6
	v_lshl_add_u64 v[2:3], v[2:3], 0, v[0:1]
	v_add_co_u32_e32 v4, vcc, s4, v2
	s_mov_b32 s4, 0x1b000
	s_nop 0
	v_addc_co_u32_e32 v5, vcc, 0, v3, vcc
	v_add_co_u32_e32 v30, vcc, s90, v2
	s_lshl_b32 s88, s1, 2
	s_nop 0
	v_addc_co_u32_e32 v31, vcc, 0, v3, vcc
	v_add_co_u32_e32 v38, vcc, s70, v2
	s_lshl_b32 s38, s0, 5
	s_nop 0
	v_addc_co_u32_e32 v39, vcc, 0, v3, vcc
	v_add_co_u32_e32 v40, vcc, s71, v2
	s_lshl_b32 s0, s0, 6
	s_nop 0
	v_addc_co_u32_e32 v41, vcc, 0, v3, vcc
	v_add_co_u32_e32 v42, vcc, s4, v2
	s_mov_b32 s4, 0x21000
	s_nop 0
	v_addc_co_u32_e32 v43, vcc, 0, v3, vcc
	v_add_co_u32_e32 v44, vcc, s4, v2
	s_mov_b32 s4, 0x26000
	s_nop 0
	v_addc_co_u32_e32 v45, vcc, 0, v3, vcc
	v_add_co_u32_e32 v46, vcc, s4, v2
	s_mov_b32 s4, 0x2c000
	s_nop 0
	v_addc_co_u32_e32 v47, vcc, 0, v3, vcc
	global_load_dword v0, v[2:3], off
	global_load_dword v29, v[4:5], off offset:2048
	global_load_dword v50, v[30:31], off
	global_load_dword v51, v[38:39], off offset:2048
	global_load_dword v52, v[40:41], off
	global_load_dword v53, v[42:43], off offset:2048
	global_load_dword v54, v[44:45], off
	global_load_dword v55, v[46:47], off offset:2048
	v_add_co_u32_e32 v4, vcc, s4, v2
	s_mov_b32 s4, 0x31000
	s_nop 0
	v_addc_co_u32_e32 v5, vcc, 0, v3, vcc
	v_add_co_u32_e32 v30, vcc, s4, v2
	s_mov_b32 s4, 0x37000
	s_nop 0
	v_addc_co_u32_e32 v31, vcc, 0, v3, vcc
	v_add_co_u32_e32 v38, vcc, s4, v2
	s_mov_b32 s4, 0x3c000
	s_nop 0
	v_addc_co_u32_e32 v39, vcc, 0, v3, vcc
	v_add_co_u32_e32 v40, vcc, s4, v2
	s_mov_b32 s4, 0x42000
	s_nop 0
	v_addc_co_u32_e32 v41, vcc, 0, v3, vcc
	v_add_co_u32_e32 v42, vcc, s4, v2
	s_mov_b32 s4, 0x47000
	s_nop 0
	v_addc_co_u32_e32 v43, vcc, 0, v3, vcc
	v_add_co_u32_e32 v44, vcc, s4, v2
	s_mov_b32 s4, 0x4d000
	s_nop 0
	v_addc_co_u32_e32 v45, vcc, 0, v3, vcc
	v_add_co_u32_e32 v46, vcc, s4, v2
	s_mov_b32 s4, 0x52000
	s_nop 0
	v_addc_co_u32_e32 v47, vcc, 0, v3, vcc
	v_add_co_u32_e32 v48, vcc, s4, v2
	s_mov_b32 s4, 0x58000
	s_nop 0
	v_addc_co_u32_e32 v49, vcc, 0, v3, vcc
	global_load_dword v56, v[4:5], off
	global_load_dword v57, v[30:31], off offset:2048
	global_load_dword v58, v[38:39], off
	global_load_dword v59, v[40:41], off offset:2048
	global_load_dword v60, v[42:43], off
	global_load_dword v61, v[44:45], off offset:2048
	global_load_dword v62, v[46:47], off
	global_load_dword v63, v[48:49], off offset:2048
	v_add_co_u32_e32 v4, vcc, s4, v2
	s_mov_b32 s4, 0x5d000
	s_nop 0
	v_addc_co_u32_e32 v5, vcc, 0, v3, vcc
	v_add_co_u32_e32 v30, vcc, s4, v2
	s_mov_b32 s4, 0x63000
	s_nop 0
	v_addc_co_u32_e32 v31, vcc, 0, v3, vcc
	v_add_co_u32_e32 v38, vcc, s4, v2
	s_mov_b32 s4, 0x68000
	s_nop 0
	v_addc_co_u32_e32 v39, vcc, 0, v3, vcc
	v_add_co_u32_e32 v40, vcc, s4, v2
	s_mov_b32 s4, 0x6e000
	s_nop 0
	v_addc_co_u32_e32 v41, vcc, 0, v3, vcc
	v_add_co_u32_e32 v42, vcc, s4, v2
	s_mov_b32 s4, 0x73000
	s_nop 0
	v_addc_co_u32_e32 v43, vcc, 0, v3, vcc
	v_add_co_u32_e32 v44, vcc, s4, v2
	s_mov_b32 s4, 0x79000
	s_nop 0
	v_addc_co_u32_e32 v45, vcc, 0, v3, vcc
	v_add_co_u32_e32 v46, vcc, s4, v2
	s_mov_b32 s4, 0x7e000
	s_nop 0
	v_addc_co_u32_e32 v47, vcc, 0, v3, vcc
	v_add_co_u32_e32 v48, vcc, s4, v2
	s_mov_b32 s4, 0x84000
	s_nop 0
	v_addc_co_u32_e32 v49, vcc, 0, v3, vcc
	global_load_dword v64, v[4:5], off
	global_load_dword v65, v[30:31], off offset:2048
	global_load_dword v66, v[38:39], off
	global_load_dword v67, v[40:41], off offset:2048
	global_load_dword v68, v[42:43], off
	global_load_dword v69, v[44:45], off offset:2048
	global_load_dword v70, v[46:47], off
	s_nop 0
	global_load_dword v48, v[48:49], off offset:2048
	v_add_co_u32_e32 v4, vcc, s4, v2
	s_mov_b32 s4, 0x89000
	s_nop 0
	v_addc_co_u32_e32 v5, vcc, 0, v3, vcc
	v_add_co_u32_e32 v30, vcc, s4, v2
	s_mov_b32 s4, 0x8f000
	s_nop 0
	v_addc_co_u32_e32 v31, vcc, 0, v3, vcc
	v_add_co_u32_e32 v38, vcc, s4, v2
	s_mov_b32 s4, 0x94000
	s_nop 0
	v_addc_co_u32_e32 v39, vcc, 0, v3, vcc
	v_add_co_u32_e32 v40, vcc, s4, v2
	s_mov_b32 s4, 0x9a000
	s_nop 0
	v_addc_co_u32_e32 v41, vcc, 0, v3, vcc
	v_add_co_u32_e32 v42, vcc, s4, v2
	s_mov_b32 s4, 0x9f000
	s_nop 0
	v_addc_co_u32_e32 v43, vcc, 0, v3, vcc
	v_add_co_u32_e32 v44, vcc, s4, v2
	s_mov_b32 s4, 0xa5000
	s_nop 0
	v_addc_co_u32_e32 v45, vcc, 0, v3, vcc
	v_add_co_u32_e32 v46, vcc, s4, v2
	s_mov_b32 s4, 0xaa000
	s_nop 0
	v_addc_co_u32_e32 v47, vcc, 0, v3, vcc
	v_add_co_u32_e32 v2, vcc, s4, v2
	s_and_b32 s0, s0, 0x1f00
	s_nop 0
	v_addc_co_u32_e32 v3, vcc, 0, v3, vcc
	global_load_dword v49, v[4:5], off
	s_nop 0
	global_load_dword v30, v[30:31], off offset:2048
	s_nop 0
	global_load_dword v31, v[38:39], off
	global_load_dword v71, v[40:41], off offset:2048
	s_nop 0
	global_load_dword v42, v[42:43], off
	s_nop 0
	global_load_dword v43, v[44:45], off offset:2048
	s_nop 0
	global_load_dword v44, v[46:47], off
	global_load_dword v45, v[2:3], off offset:2048
	v_lshl_add_u64 v[2:3], v[26:27], 0, s[88:89]
	global_load_dwordx4 v[38:41], v[2:3], off
	s_nop 0
	global_load_dwordx4 v[2:5], v[2:3], off offset:16
	s_waitcnt vmcnt(32)
	ds_write2_b32 v36, v0, v29 offset1:66
	s_waitcnt vmcnt(30)
; #define LAS __attribute__((address_space(3)))
; __device__ __forceinline__ unsigned pk2(float lo, float hi) { return f2bf(lo) | (f2bf(hi) << 16); }
; #define LDS_WAVE_SYNC() asm volatile("s_waitcnt lgkmcnt(0)" ::: "memory")
; template <bool HASG>
; __device__ __forceinline__ void tr_item(const float* W, int K, int N, bf16* WT, int rowmode, const float* g, LAS float* scr, int item, int lane) {
;     ...
;     for (int i = 0; i < 32; ++i) scr[(2 * i + (lane >> 5)) * 33 + (lane & 31)] = v[i];
;     LDS_WAVE_SYNC();
;     const int drow0 = rowmode == 0 ? n0 : ((n0 >> 7) * 256 + (n0 & 127) + (rowmode == 2 ? 128 : 0));
; #pragma unroll
;     for (int j = 0; j < 4; ++j) { const int n = (lane >> 3) + 8 * j; const LAS float* s = scr + (8 * c) * 33 + n;
;         u32x4 o; o.x = pk2(s[0 * 33] * g0.x, s[1 * 33] * g0.y); o.y = pk2(s[2 * 33] * g0.z, s[3 * 33] * g0.w);
;         o.z = pk2(s[4 * 33] * g1.x, s[5 * 33] * g1.y); o.w = pk2(s[6 * 33] * g1.z, s[7 * 33] * g1.w);
;         *(u32x4*)(WT + (size_t)(drow0 + n) * K + k0 + 8 * c) = o; }
	ds_write2_b32 v36, v50, v51 offset0:132 offset1:198
	v_add_u32_e32 v0, 0x400, v36
	s_waitcnt vmcnt(28)
	ds_write2_b32 v0, v52, v53 offset0:8 offset1:74
	s_waitcnt vmcnt(26)
	ds_write2_b32 v0, v54, v55 offset0:140 offset1:206
	v_add_u32_e32 v0, 0x800, v36
	s_waitcnt vmcnt(24)
	ds_write2_b32 v0, v56, v57 offset0:16 offset1:82
	s_waitcnt vmcnt(22)
	ds_write2_b32 v0, v58, v59 offset0:148 offset1:214
	v_add_u32_e32 v0, 0xc00, v36
	s_waitcnt vmcnt(20)
	ds_write2_b32 v0, v60, v61 offset0:24 offset1:90
	s_waitcnt vmcnt(18)
	ds_write2_b32 v0, v62, v63 offset0:156 offset1:222
	v_add_u32_e32 v0, 0x1000, v36
	s_waitcnt vmcnt(16)
	ds_write2_b32 v0, v64, v65 offset0:32 offset1:98
	s_waitcnt vmcnt(14)
	ds_write2_b32 v0, v66, v67 offset0:164 offset1:230
	v_add_u32_e32 v0, 0x1400, v36
	s_waitcnt vmcnt(12)
	ds_write2_b32 v0, v68, v69 offset0:40 offset1:106
	s_waitcnt vmcnt(10)
	ds_write2_b32 v0, v70, v48 offset0:172 offset1:238
	v_add_u32_e32 v0, 0x1800, v36
	s_waitcnt vmcnt(8)
	ds_write2_b32 v0, v49, v30 offset0:48 offset1:114
	s_waitcnt vmcnt(6)
	ds_write2_b32 v0, v31, v71 offset0:180 offset1:246
	v_add_u32_e32 v0, 0x1c00, v36
	s_waitcnt vmcnt(4)
	ds_write2_b32 v0, v42, v43 offset0:56 offset1:122
	s_waitcnt vmcnt(2)
	ds_write2_b32 v0, v44, v45 offset0:188 offset1:254
	s_waitcnt lgkmcnt(0)
	ds_read2_b32 v[46:47], v37 offset0:33 offset1:41
	ds_read2_b32 v[48:49], v37 offset1:8
	ds_read2_b32 v[50:51], v37 offset0:66 offset1:74
	ds_read2_b32 v[52:53], v37 offset0:99 offset1:107
	ds_read2_b32 v[56:57], v37 offset0:132 offset1:140
	ds_read2_b32 v[58:59], v37 offset0:165 offset1:173
	ds_read2_b32 v[60:61], v37 offset0:198 offset1:206
	ds_read2_b32 v[62:63], v37 offset0:231 offset1:239
	s_waitcnt vmcnt(1)
	v_mov_b32_e32 v54, v38
	v_mov_b32_e32 v55, v40
	v_mov_b32_e32 v40, v39
	s_waitcnt lgkmcnt(7)
	v_mov_b32_e32 v38, v46
	s_waitcnt lgkmcnt(4)
	v_mov_b32_e32 v39, v52
	v_pk_mul_f32 v[38:39], v[40:41], v[38:39]
	s_waitcnt vmcnt(0)
	v_mov_b32_e32 v64, v2
	v_mov_b32_e32 v65, v4
	s_waitcnt lgkmcnt(3)
	v_mov_b32_e32 v44, v56
	s_waitcnt lgkmcnt(1)
	v_mov_b32_e32 v45, v60
	v_mov_b32_e32 v4, v3
	v_mov_b32_e32 v2, v58
	s_waitcnt lgkmcnt(0)
	v_mov_b32_e32 v3, v62
	v_mov_b32_e32 v42, v48
	v_mov_b32_e32 v43, v50
	v_pk_mul_f32 v[44:45], v[64:65], v[44:45]
	v_pk_mul_f32 v[2:3], v[4:5], v[2:3]
	v_bfe_u32 v48, v38, 16, 1
	s_and_b32 s38, s38, 0x60
	v_pk_mul_f32 v[42:43], v[54:55], v[42:43]
	v_bfe_u32 v29, v2, 16, 1
	v_add3_u32 v38, v38, v48, s91
	v_bfe_u32 v48, v45, 16, 1
	s_or_b32 s0, s38, s0
	v_bfe_u32 v0, v3, 16, 1
	v_bfe_u32 v46, v39, 16, 1
	v_add3_u32 v2, v2, v29, s91
	v_bfe_u32 v29, v43, 16, 1
	v_add3_u32 v45, v45, v48, s91
	s_bitset1_b32 s0, 7
	v_add3_u32 v39, v39, v46, s91
	v_add3_u32 v0, v3, v0, s91
	v_bfe_u32 v3, v42, 16, 1
	v_bfe_u32 v46, v44, 16, 1
	v_add3_u32 v29, v43, v29, s91
	v_lshrrev_b32_e32 v43, 16, v45
	s_lshl_b32 s88, s1, 1
	v_add3_u32 v44, v44, v46, s91
	v_add3_u32 v3, v42, v3, s91
	v_and_or_b32 v45, v0, s35, v43
	v_or_b32_e32 v0, s0, v7
	v_lshl_add_u64 v[30:31], v[20:21], 0, s[88:89]
	v_lshrrev_b32_e32 v3, 16, v3
	v_lshrrev_b32_e32 v29, 16, v29
	v_lshrrev_b32_e32 v42, 16, v44
	v_lshlrev_b32_e32 v0, 11, v0
	v_mov_b32_e32 v52, v47
	v_and_or_b32 v44, v2, s35, v42
	v_and_or_b32 v43, v39, s35, v29
	v_and_or_b32 v42, v38, s35, v3
	v_lshl_add_u64 v[2:3], v[30:31], 0, v[0:1]
	v_pk_mul_f32 v[38:39], v[40:41], v[52:53]
	v_mov_b32_e32 v60, v57
	global_store_dwordx4 v[2:3], v[42:45], off sc1
	v_mov_b32_e32 v62, v59
	v_bfe_u32 v47, v38, 16, 1
	v_pk_mul_f32 v[42:43], v[64:65], v[60:61]
	v_mov_b32_e32 v50, v49
	v_pk_mul_f32 v[44:45], v[4:5], v[62:63]
	v_add3_u32 v38, v38, v47, s91
	v_bfe_u32 v47, v43, 16, 1
	v_pk_mul_f32 v[2:3], v[54:55], v[50:51]
	v_bfe_u32 v0, v45, 16, 1
	v_bfe_u32 v29, v44, 16, 1
	v_bfe_u32 v46, v39, 16, 1
	v_add3_u32 v43, v43, v47, s91
	v_add3_u32 v39, v39, v46, s91
	v_add3_u32 v29, v44, v29, s91
	v_add3_u32 v0, v45, v0, s91
	v_bfe_u32 v44, v2, 16, 1
	v_bfe_u32 v45, v3, 16, 1
	v_bfe_u32 v46, v42, 16, 1
	v_lshrrev_b32_e32 v43, 16, v43
	v_add3_u32 v42, v42, v46, s91
	v_add3_u32 v3, v3, v45, s91
	v_add3_u32 v2, v2, v44, s91
	v_and_or_b32 v45, v0, s35, v43
	v_or_b32_e32 v0, s0, v32
	v_lshrrev_b32_e32 v2, 16, v2
	v_lshrrev_b32_e32 v3, 16, v3
	v_lshrrev_b32_e32 v42, 16, v42
	v_lshlrev_b32_e32 v0, 11, v0
	v_and_or_b32 v44, v29, s35, v42
	v_and_or_b32 v43, v39, s35, v3
	v_and_or_b32 v42, v38, s35, v2
	v_lshl_add_u64 v[2:3], v[30:31], 0, v[0:1]
	ds_read2_b32 v[38:39], v37 offset0:16 offset1:24
	ds_read2_b32 v[46:47], v37 offset0:82 offset1:90
	global_store_dwordx4 v[2:3], v[42:45], off sc1
	ds_read2_b32 v[2:3], v37 offset0:49 offset1:57
	ds_read2_b32 v[48:49], v37 offset0:115 offset1:123
	ds_read2_b32 v[50:51], v37 offset0:148 offset1:156
	ds_read2_b32 v[52:53], v37 offset0:214 offset1:222
	ds_read2_b32 v[56:57], v37 offset0:181 offset1:189
	ds_read2_b32 v[58:59], v37 offset0:247 offset1:255
	s_waitcnt lgkmcnt(7)
; #define LAS __attribute__((address_space(3)))
; __device__ __forceinline__ unsigned pk2(float lo, float hi) { return f2bf(lo) | (f2bf(hi) << 16); }
; #define LDS_WAVE_SYNC() asm volatile("s_waitcnt lgkmcnt(0)" ::: "memory")
; template <bool HASG>
; __device__ __forceinline__ void tr_item(const float* W, int K, int N, bf16* WT, int rowmode, const float* g, LAS float* scr, int item, int lane) {
;     ...
;     for (int j = 0; j < 4; ++j) { const int n = (lane >> 3) + 8 * j; const LAS float* s = scr + (8 * c) * 33 + n;
;         u32x4 o; o.x = pk2(s[0 * 33] * g0.x, s[1 * 33] * g0.y); o.y = pk2(s[2 * 33] * g0.z, s[3 * 33] * g0.w);
;         o.z = pk2(s[4 * 33] * g1.x, s[5 * 33] * g1.y); o.w = pk2(s[6 * 33] * g1.z, s[7 * 33] * g1.w);
;         *(u32x4*)(WT + (size_t)(drow0 + n) * K + k0 + 8 * c) = o; }
;     LDS_WAVE_SYNC();
	v_mov_b32_e32 v42, v38
	s_waitcnt lgkmcnt(5)
	v_mov_b32_e32 v44, v2
	s_waitcnt lgkmcnt(4)
	v_mov_b32_e32 v45, v48
	s_waitcnt lgkmcnt(3)
	v_mov_b32_e32 v60, v50
	s_waitcnt lgkmcnt(2)
	v_mov_b32_e32 v61, v52
	v_mov_b32_e32 v43, v46
	v_pk_mul_f32 v[44:45], v[40:41], v[44:45]
	v_pk_mul_f32 v[60:61], v[64:65], v[60:61]
	s_waitcnt lgkmcnt(1)
	v_mov_b32_e32 v62, v56
	s_waitcnt lgkmcnt(0)
	v_mov_b32_e32 v63, v58
	v_pk_mul_f32 v[42:43], v[54:55], v[42:43]
	v_pk_mul_f32 v[62:63], v[4:5], v[62:63]
	v_bfe_u32 v29, v45, 16, 1
	v_bfe_u32 v48, v61, 16, 1
	v_bfe_u32 v0, v63, 16, 1
	v_bfe_u32 v38, v44, 16, 1
	v_add3_u32 v29, v45, v29, s91
	v_bfe_u32 v45, v43, 16, 1
	v_add3_u32 v48, v61, v48, s91
	v_add3_u32 v38, v44, v38, s91
	v_add3_u32 v0, v63, v0, s91
	v_bfe_u32 v44, v42, 16, 1
	v_bfe_u32 v46, v60, 16, 1
	v_add3_u32 v43, v43, v45, s91
	v_lshrrev_b32_e32 v45, 16, v48
	v_bfe_u32 v2, v62, 16, 1
	v_add3_u32 v46, v60, v46, s91
	v_add3_u32 v42, v42, v44, s91
	v_and_or_b32 v45, v0, s35, v45
	v_or_b32_e32 v0, s0, v34
	v_add3_u32 v2, v62, v2, s91
	v_lshrrev_b32_e32 v42, 16, v42
	v_lshrrev_b32_e32 v43, 16, v43
	v_lshrrev_b32_e32 v44, 16, v46
	v_lshlrev_b32_e32 v0, 11, v0
	v_mov_b32_e32 v48, v3
	v_mov_b32_e32 v58, v57
	v_and_or_b32 v44, v2, s35, v44
	v_and_or_b32 v43, v29, s35, v43
	v_and_or_b32 v42, v38, s35, v42
	v_lshl_add_u64 v[60:61], v[30:31], 0, v[0:1]
	v_mov_b32_e32 v46, v39
	v_pk_mul_f32 v[2:3], v[40:41], v[48:49]
	v_mov_b32_e32 v52, v51
	v_pk_mul_f32 v[4:5], v[4:5], v[58:59]
	global_store_dwordx4 v[60:61], v[42:45], off sc1
	v_pk_mul_f32 v[38:39], v[54:55], v[46:47]
	v_pk_mul_f32 v[40:41], v[64:65], v[52:53]
	v_bfe_u32 v0, v5, 16, 1
	v_bfe_u32 v43, v2, 16, 1
	v_add3_u32 v2, v2, v43, s91
	v_add3_u32 v0, v5, v0, s91
	v_bfe_u32 v5, v38, 16, 1
	v_bfe_u32 v43, v41, 16, 1
	v_bfe_u32 v29, v4, 16, 1
	v_bfe_u32 v42, v3, 16, 1
	v_add3_u32 v41, v41, v43, s91
	v_add3_u32 v5, v38, v5, s91
	v_add3_u32 v3, v3, v42, s91
	v_add3_u32 v4, v4, v29, s91
	v_bfe_u32 v29, v39, 16, 1
	v_bfe_u32 v42, v40, 16, 1
	v_lshrrev_b32_e32 v38, 16, v5
	v_lshrrev_b32_e32 v5, 16, v41
	v_add3_u32 v40, v40, v42, s91
	v_add3_u32 v29, v39, v29, s91
	v_and_or_b32 v5, v0, s35, v5
	v_or_b32_e32 v0, s0, v35
	v_lshrrev_b32_e32 v29, 16, v29
	v_lshrrev_b32_e32 v39, 16, v40
	v_lshlrev_b32_e32 v0, 11, v0
	v_and_or_b32 v4, v4, s35, v39
	v_and_or_b32 v3, v3, s35, v29
	v_and_or_b32 v2, v2, s35, v38
	v_lshl_add_u64 v[30:31], v[30:31], 0, v[0:1]
	global_store_dwordx4 v[30:31], v[2:5], off sc1
	s_waitcnt lgkmcnt(0)
	v_readlane_b32 s5, v252, 1
	v_readlane_b32 s6, v252, 2
	v_readlane_b32 s7, v252, 3
	v_readlane_b32 s8, v252, 4
	v_readlane_b32 s9, v252, 5
	v_readlane_b32 s12, v252, 8
	v_readlane_b32 s13, v252, 9
	v_readlane_b32 s14, v252, 10
	v_readlane_b32 s15, v252, 11
	v_readlane_b32 s16, v252, 12
	v_readlane_b32 s17, v252, 13
	v_readlane_b32 s18, v252, 14
	v_readlane_b32 s19, v252, 15

; template <bool HASG>
; __device__ __forceinline__ void tr_item(const float* W, int K, int N, bf16* WT, int rowmode, const float* g, LAS float* scr, int item, int lane) {
;     const int nblk = N / 32, kb = item / nblk, nb = item % nblk, k0 = 64 * kb, n0 = 32 * nb;
;     const float* wp = W + (size_t)(k0 + (lane >> 5)) * N + n0 + (lane & 31);
;     const int c = lane & 7;
;     float v[32];
; #pragma unroll
;     for (int i = 0; i < 32; ++i) v[i] = wp[(size_t)(2 * i) * N];
;     f32x4 g0 = (f32x4){1.f, 1.f, 1.f, 1.f}, g1 = g0;
;     if (HASG) { g0 = *(const f32x4*)(g + k0 + 8 * c); g1 = *(const f32x4*)(g + k0 + 8 * c + 4); }
; __device__ __forceinline__ void convert_items(const Args& a, LAS unsigned char* lds, int l, int it_lo, int it_hi, int gw, int NGW, int wave, int lane) {
;     ...
;         if (r < I_G) { tr_item<true>(a.in[2] + o_gu, D, FF, wl + W_GU1, 1, a.in[1] + l * D, scr, r, lane); continue; } r -= I_G;
.LBB0_602:
	s_andn2_b64 vcc, exec, s[0:1]
	s_cbranch_vccnz .LBB0_571
	s_mul_hi_i32 s0, s28, 0x2e8ba2e9
	s_lshr_b32 s1, s0, 31
	s_ashr_i32 s45, s0, 4
	s_add_i32 s45, s45, s1
	v_readlane_b32 s4, v252, 0
	s_lshl_b32 s0, s45, 6
	s_mul_i32 s1, s45, 0xfffff500
	v_readlane_b32 s8, v252, 4
	v_readlane_b32 s9, v252, 5
	s_add_i32 s38, s29, s1
	v_or_b32_e32 v0, s0, v33
	v_mov_b64_e32 v[2:3], s[8:9]
	s_movk_i32 s1, 0x2c00
	v_mad_i64_i32 v[2:3], s[46:47], v0, s1, v[2:3]
	s_ashr_i32 s39, s38, 31
	v_lshl_add_u64 v[2:3], s[38:39], 2, v[2:3]
	v_lshlrev_b32_e32 v0, 2, v6
	v_lshl_add_u64 v[2:3], v[2:3], 0, v[0:1]
	s_movk_i32 s1, 0x5000
	v_add_co_u32_e32 v4, vcc, s1, v2
	s_mov_b32 s1, 0x1b000
	s_nop 0
	v_addc_co_u32_e32 v5, vcc, 0, v3, vcc
	v_add_co_u32_e32 v30, vcc, s90, v2
	s_mulk_i32 s45, 0xea00
	s_nop 0
	v_addc_co_u32_e32 v31, vcc, 0, v3, vcc
	v_add_co_u32_e32 v38, vcc, s70, v2
	s_add_i32 s39, s41, s45
	s_nop 0
	v_addc_co_u32_e32 v39, vcc, 0, v3, vcc
	v_add_co_u32_e32 v40, vcc, s71, v2
	s_and_b32 s39, s39, 0xffffff00
	s_nop 0
	v_addc_co_u32_e32 v41, vcc, 0, v3, vcc
	v_add_co_u32_e32 v42, vcc, s1, v2
	s_mov_b32 s1, 0x21000
	s_nop 0
	v_addc_co_u32_e32 v43, vcc, 0, v3, vcc
	v_add_co_u32_e32 v44, vcc, s1, v2
	s_mov_b32 s1, 0x26000
	s_nop 0
	v_addc_co_u32_e32 v45, vcc, 0, v3, vcc
	v_add_co_u32_e32 v46, vcc, s1, v2
	s_mov_b32 s1, 0x2c000
	s_nop 0
	v_addc_co_u32_e32 v47, vcc, 0, v3, vcc
	global_load_dword v0, v[2:3], off
	global_load_dword v29, v[4:5], off offset:2048
	global_load_dword v50, v[30:31], off
	global_load_dword v51, v[38:39], off offset:2048
	global_load_dword v52, v[40:41], off
	global_load_dword v53, v[42:43], off offset:2048
	global_load_dword v54, v[44:45], off
	global_load_dword v55, v[46:47], off offset:2048
	v_add_co_u32_e32 v4, vcc, s1, v2
	s_mov_b32 s1, 0x31000
	s_nop 0
	v_addc_co_u32_e32 v5, vcc, 0, v3, vcc
	v_add_co_u32_e32 v30, vcc, s1, v2
	s_mov_b32 s1, 0x37000
	s_nop 0
	v_addc_co_u32_e32 v31, vcc, 0, v3, vcc
	v_add_co_u32_e32 v38, vcc, s1, v2
	s_mov_b32 s1, 0x3c000
	s_nop 0
	v_addc_co_u32_e32 v39, vcc, 0, v3, vcc
	v_add_co_u32_e32 v40, vcc, s1, v2
	s_mov_b32 s1, 0x42000
	s_nop 0
	v_addc_co_u32_e32 v41, vcc, 0, v3, vcc
	v_add_co_u32_e32 v42, vcc, s1, v2
	s_mov_b32 s1, 0x47000
	s_nop 0
	v_addc_co_u32_e32 v43, vcc, 0, v3, vcc
	v_add_co_u32_e32 v44, vcc, s1, v2
	s_mov_b32 s1, 0x4d000
	s_nop 0
	v_addc_co_u32_e32 v45, vcc, 0, v3, vcc
	v_add_co_u32_e32 v46, vcc, s1, v2
	s_mov_b32 s1, 0x52000
	s_nop 0
	v_addc_co_u32_e32 v47, vcc, 0, v3, vcc
	v_add_co_u32_e32 v48, vcc, s1, v2
	s_mov_b32 s1, 0x58000
	s_nop 0
	v_addc_co_u32_e32 v49, vcc, 0, v3, vcc
	global_load_dword v56, v[4:5], off
	global_load_dword v57, v[30:31], off offset:2048
	global_load_dword v58, v[38:39], off
	global_load_dword v59, v[40:41], off offset:2048
	global_load_dword v60, v[42:43], off
	global_load_dword v61, v[44:45], off offset:2048
	global_load_dword v62, v[46:47], off
	global_load_dword v63, v[48:49], off offset:2048
	v_add_co_u32_e32 v4, vcc, s1, v2
	s_mov_b32 s1, 0x5d000
	s_nop 0
	v_addc_co_u32_e32 v5, vcc, 0, v3, vcc
	v_add_co_u32_e32 v30, vcc, s1, v2
	s_mov_b32 s1, 0x63000
	s_nop 0
	v_addc_co_u32_e32 v31, vcc, 0, v3, vcc
	v_add_co_u32_e32 v38, vcc, s1, v2
	s_mov_b32 s1, 0x68000
	s_nop 0
	v_addc_co_u32_e32 v39, vcc, 0, v3, vcc
	v_add_co_u32_e32 v40, vcc, s1, v2
	s_mov_b32 s1, 0x6e000
	s_nop 0
	v_addc_co_u32_e32 v41, vcc, 0, v3, vcc
	v_add_co_u32_e32 v42, vcc, s1, v2
	s_mov_b32 s1, 0x73000
	s_nop 0
	v_addc_co_u32_e32 v43, vcc, 0, v3, vcc
	v_add_co_u32_e32 v44, vcc, s1, v2
	s_mov_b32 s1, 0x79000
	s_nop 0
	v_addc_co_u32_e32 v45, vcc, 0, v3, vcc
	v_add_co_u32_e32 v46, vcc, s1, v2
	s_mov_b32 s1, 0x7e000
	s_nop 0
	v_addc_co_u32_e32 v47, vcc, 0, v3, vcc
	v_add_co_u32_e32 v48, vcc, s1, v2
	s_mov_b32 s1, 0x84000
	s_nop 0
	v_addc_co_u32_e32 v49, vcc, 0, v3, vcc
	global_load_dword v64, v[4:5], off
	global_load_dword v65, v[30:31], off offset:2048
	global_load_dword v66, v[38:39], off
	global_load_dword v67, v[40:41], off offset:2048
	global_load_dword v68, v[42:43], off
	global_load_dword v69, v[44:45], off offset:2048
	global_load_dword v70, v[46:47], off
	s_nop 0
	global_load_dword v48, v[48:49], off offset:2048
	v_add_co_u32_e32 v4, vcc, s1, v2
	s_mov_b32 s1, 0x89000
	s_nop 0
	v_addc_co_u32_e32 v5, vcc, 0, v3, vcc
	v_add_co_u32_e32 v30, vcc, s1, v2
	s_mov_b32 s1, 0x8f000
	s_nop 0
	v_addc_co_u32_e32 v31, vcc, 0, v3, vcc
	v_add_co_u32_e32 v38, vcc, s1, v2
	s_mov_b32 s1, 0x94000
	s_nop 0
	v_addc_co_u32_e32 v39, vcc, 0, v3, vcc
	v_add_co_u32_e32 v40, vcc, s1, v2
	s_mov_b32 s1, 0x9a000
	s_nop 0
	v_addc_co_u32_e32 v41, vcc, 0, v3, vcc
	v_add_co_u32_e32 v42, vcc, s1, v2
	s_mov_b32 s1, 0x9f000
	s_nop 0
	v_addc_co_u32_e32 v43, vcc, 0, v3, vcc
	v_add_co_u32_e32 v44, vcc, s1, v2
	s_mov_b32 s1, 0xa5000
	s_nop 0
	v_addc_co_u32_e32 v45, vcc, 0, v3, vcc
	v_add_co_u32_e32 v46, vcc, s1, v2
	s_mov_b32 s1, 0xaa000
	s_nop 0
	v_addc_co_u32_e32 v47, vcc, 0, v3, vcc
	v_add_co_u32_e32 v2, vcc, s1, v2
	s_ashr_i32 s1, s0, 31
	s_nop 0
	v_addc_co_u32_e32 v3, vcc, 0, v3, vcc
	global_load_dword v49, v[4:5], off
	s_nop 0
	global_load_dword v30, v[30:31], off offset:2048
	s_nop 0
	global_load_dword v31, v[38:39], off
	global_load_dword v71, v[40:41], off offset:2048
	s_nop 0
	global_load_dword v42, v[42:43], off
	s_nop 0
	global_load_dword v43, v[44:45], off offset:2048
	s_nop 0
	global_load_dword v44, v[46:47], off
	global_load_dword v45, v[2:3], off offset:2048
	v_lshl_add_u64 v[2:3], s[0:1], 2, v[26:27]
	global_load_dwordx4 v[38:41], v[2:3], off
	s_nop 0
	global_load_dwordx4 v[2:5], v[2:3], off offset:16
	s_waitcnt vmcnt(32)
	ds_write2_b32 v36, v0, v29 offset1:66
	s_waitcnt vmcnt(30)
; #define LAS __attribute__((address_space(3)))
; __device__ __forceinline__ unsigned pk2(float lo, float hi) { return f2bf(lo) | (f2bf(hi) << 16); }
; #define LDS_WAVE_SYNC() asm volatile("s_waitcnt lgkmcnt(0)" ::: "memory")
; template <bool HASG>
; __device__ __forceinline__ void tr_item(const float* W, int K, int N, bf16* WT, int rowmode, const float* g, LAS float* scr, int item, int lane) {
;     ...
;     for (int i = 0; i < 32; ++i) scr[(2 * i + (lane >> 5)) * 33 + (lane & 31)] = v[i];
;     LDS_WAVE_SYNC();
;     const int drow0 = rowmode == 0 ? n0 : ((n0 >> 7) * 256 + (n0 & 127) + (rowmode == 2 ? 128 : 0));
; #pragma unroll
;     for (int j = 0; j < 4; ++j) { const int n = (lane >> 3) + 8 * j; const LAS float* s = scr + (8 * c) * 33 + n;
;         u32x4 o; o.x = pk2(s[0 * 33] * g0.x, s[1 * 33] * g0.y); o.y = pk2(s[2 * 33] * g0.z, s[3 * 33] * g0.w);
;         o.z = pk2(s[4 * 33] * g1.x, s[5 * 33] * g1.y); o.w = pk2(s[6 * 33] * g1.z, s[7 * 33] * g1.w);
;         *(u32x4*)(WT + (size_t)(drow0 + n) * K + k0 + 8 * c) = o; }
	ds_write2_b32 v36, v50, v51 offset0:132 offset1:198
	v_add_u32_e32 v0, 0x400, v36
	s_waitcnt vmcnt(28)
	ds_write2_b32 v0, v52, v53 offset0:8 offset1:74
	s_waitcnt vmcnt(26)
	ds_write2_b32 v0, v54, v55 offset0:140 offset1:206
	v_add_u32_e32 v0, 0x800, v36
	s_waitcnt vmcnt(24)
	ds_write2_b32 v0, v56, v57 offset0:16 offset1:82
	s_waitcnt vmcnt(22)
	ds_write2_b32 v0, v58, v59 offset0:148 offset1:214
	v_add_u32_e32 v0, 0xc00, v36
	s_waitcnt vmcnt(20)
	ds_write2_b32 v0, v60, v61 offset0:24 offset1:90
	s_waitcnt vmcnt(18)
	ds_write2_b32 v0, v62, v63 offset0:156 offset1:222
	v_add_u32_e32 v0, 0x1000, v36
	s_waitcnt vmcnt(16)
	ds_write2_b32 v0, v64, v65 offset0:32 offset1:98
	s_waitcnt vmcnt(14)
	ds_write2_b32 v0, v66, v67 offset0:164 offset1:230
	v_add_u32_e32 v0, 0x1400, v36
	s_waitcnt vmcnt(12)
	ds_write2_b32 v0, v68, v69 offset0:40 offset1:106
	s_waitcnt vmcnt(10)
	ds_write2_b32 v0, v70, v48 offset0:172 offset1:238
	v_add_u32_e32 v0, 0x1800, v36
	s_waitcnt vmcnt(8)
	ds_write2_b32 v0, v49, v30 offset0:48 offset1:114
	s_waitcnt vmcnt(6)
	ds_write2_b32 v0, v31, v71 offset0:180 offset1:246
	v_add_u32_e32 v0, 0x1c00, v36
	s_waitcnt vmcnt(4)
	ds_write2_b32 v0, v42, v43 offset0:56 offset1:122
	s_waitcnt vmcnt(2)
	ds_write2_b32 v0, v44, v45 offset0:188 offset1:254
	s_waitcnt lgkmcnt(0)
	ds_read2_b32 v[46:47], v37 offset0:33 offset1:41
	ds_read2_b32 v[48:49], v37 offset1:8
	ds_read2_b32 v[50:51], v37 offset0:66 offset1:74
	ds_read2_b32 v[52:53], v37 offset0:99 offset1:107
	ds_read2_b32 v[56:57], v37 offset0:132 offset1:140
	ds_read2_b32 v[58:59], v37 offset0:165 offset1:173
	ds_read2_b32 v[60:61], v37 offset0:198 offset1:206
	ds_read2_b32 v[62:63], v37 offset0:231 offset1:239
	s_waitcnt vmcnt(1)
	v_mov_b32_e32 v54, v38
	v_mov_b32_e32 v55, v40
	v_mov_b32_e32 v40, v39
	s_waitcnt lgkmcnt(7)
	v_mov_b32_e32 v38, v46
	s_waitcnt lgkmcnt(4)
	v_mov_b32_e32 v39, v52
	v_pk_mul_f32 v[38:39], v[40:41], v[38:39]
	s_waitcnt vmcnt(0)
	v_mov_b32_e32 v64, v2
	v_mov_b32_e32 v65, v4
	s_waitcnt lgkmcnt(3)
	v_mov_b32_e32 v44, v56
	s_waitcnt lgkmcnt(1)
	v_mov_b32_e32 v45, v60
	v_mov_b32_e32 v4, v3
	v_mov_b32_e32 v2, v58
	s_waitcnt lgkmcnt(0)
	v_mov_b32_e32 v3, v62
	v_mov_b32_e32 v42, v48
	v_mov_b32_e32 v43, v50
	v_pk_mul_f32 v[44:45], v[64:65], v[44:45]
	v_pk_mul_f32 v[2:3], v[4:5], v[2:3]
	v_bfe_u32 v46, v39, 16, 1
	v_pk_mul_f32 v[42:43], v[54:55], v[42:43]
	v_bfe_u32 v0, v3, 16, 1
	v_add3_u32 v39, v39, v46, s91
	v_bfe_u32 v46, v44, 16, 1
	s_and_b32 s38, s38, 0x60
	v_bfe_u32 v29, v2, 16, 1
	v_add3_u32 v0, v3, v0, s91
	v_bfe_u32 v3, v42, 16, 1
	v_add3_u32 v44, v44, v46, s91
	s_or_b32 s38, s38, s39
	v_bfe_u32 v48, v38, 16, 1
	v_add3_u32 v2, v2, v29, s91
	v_add3_u32 v3, v42, v3, s91
	v_lshrrev_b32_e32 v42, 16, v44
	v_add3_u32 v38, v38, v48, s91
	v_bfe_u32 v29, v43, 16, 1
	v_bfe_u32 v48, v45, 16, 1
	v_lshrrev_b32_e32 v3, 16, v3
	v_and_or_b32 v44, v2, s35, v42
	v_or_b32_e32 v2, s38, v7
	v_add3_u32 v45, v45, v48, s91
	v_add3_u32 v29, v43, v29, s91
	v_and_or_b32 v42, v38, s35, v3
	v_ashrrev_i32_e32 v3, 31, v2
	v_lshl_add_u64 v[30:31], s[0:1], 1, v[20:21]
	v_lshrrev_b32_e32 v29, 16, v29
	v_lshrrev_b32_e32 v43, 16, v45
	v_lshlrev_b64 v[2:3], 11, v[2:3]
	v_and_or_b32 v45, v0, s35, v43
	v_and_or_b32 v43, v39, s35, v29
	v_lshl_add_u64 v[2:3], v[30:31], 0, v[2:3]
	v_mov_b32_e32 v52, v47
	v_mov_b32_e32 v62, v59
	global_store_dwordx4 v[2:3], v[42:45], off sc1
	v_mov_b32_e32 v50, v49
	v_pk_mul_f32 v[38:39], v[40:41], v[52:53]
	v_mov_b32_e32 v60, v57
	v_pk_mul_f32 v[44:45], v[4:5], v[62:63]
	v_pk_mul_f32 v[2:3], v[54:55], v[50:51]
	v_pk_mul_f32 v[42:43], v[64:65], v[60:61]
	v_bfe_u32 v29, v44, 16, 1
	v_bfe_u32 v46, v39, 16, 1
	v_bfe_u32 v0, v45, 16, 1
	v_bfe_u32 v47, v38, 16, 1
	v_add3_u32 v39, v39, v46, s91
	v_add3_u32 v29, v44, v29, s91
	v_bfe_u32 v44, v2, 16, 1
	v_bfe_u32 v46, v42, 16, 1
	v_add3_u32 v38, v38, v47, s91
	v_add3_u32 v0, v45, v0, s91
	v_bfe_u32 v45, v3, 16, 1
	v_bfe_u32 v47, v43, 16, 1
	v_add3_u32 v42, v42, v46, s91
	v_add3_u32 v2, v2, v44, s91
	v_add3_u32 v43, v43, v47, s91
	v_add3_u32 v3, v3, v45, s91
	v_lshrrev_b32_e32 v2, 16, v2
	v_lshrrev_b32_e32 v42, 16, v42
	v_lshrrev_b32_e32 v3, 16, v3
	v_lshrrev_b32_e32 v43, 16, v43
	v_and_or_b32 v44, v29, s35, v42
	v_and_or_b32 v42, v38, s35, v2
	v_or_b32_e32 v2, s38, v32
	v_and_or_b32 v45, v0, s35, v43
	v_and_or_b32 v43, v39, s35, v3
	v_ashrrev_i32_e32 v3, 31, v2
	v_lshlrev_b64 v[2:3], 11, v[2:3]
	v_lshl_add_u64 v[2:3], v[30:31], 0, v[2:3]
	ds_read2_b32 v[38:39], v37 offset0:16 offset1:24
	ds_read2_b32 v[46:47], v37 offset0:82 offset1:90
	global_store_dwordx4 v[2:3], v[42:45], off sc1
	ds_read2_b32 v[2:3], v37 offset0:49 offset1:57
	ds_read2_b32 v[48:49], v37 offset0:115 offset1:123
	ds_read2_b32 v[50:51], v37 offset0:148 offset1:156
	ds_read2_b32 v[52:53], v37 offset0:214 offset1:222
	ds_read2_b32 v[56:57], v37 offset0:181 offset1:189
	ds_read2_b32 v[58:59], v37 offset0:247 offset1:255
	s_waitcnt lgkmcnt(7)
; #define LAS __attribute__((address_space(3)))
; __device__ __forceinline__ unsigned pk2(float lo, float hi) { return f2bf(lo) | (f2bf(hi) << 16); }
; #define LDS_WAVE_SYNC() asm volatile("s_waitcnt lgkmcnt(0)" ::: "memory")
; template <bool HASG>
; __device__ __forceinline__ void tr_item(const float* W, int K, int N, bf16* WT, int rowmode, const float* g, LAS float* scr, int item, int lane) {
;     ...
;     for (int j = 0; j < 4; ++j) { const int n = (lane >> 3) + 8 * j; const LAS float* s = scr + (8 * c) * 33 + n;
;         u32x4 o; o.x = pk2(s[0 * 33] * g0.x, s[1 * 33] * g0.y); o.y = pk2(s[2 * 33] * g0.z, s[3 * 33] * g0.w);
;         o.z = pk2(s[4 * 33] * g1.x, s[5 * 33] * g1.y); o.w = pk2(s[6 * 33] * g1.z, s[7 * 33] * g1.w);
;         *(u32x4*)(WT + (size_t)(drow0 + n) * K + k0 + 8 * c) = o; }
;     LDS_WAVE_SYNC();
; __device__ __forceinline__ void convert_items(const Args& a, LAS unsigned char* lds, int l, int it_lo, int it_hi, int gw, int NGW, int wave, int lane) {
;     ...
;     for (int it = it_lo + gw; it < it_hi; it += NGW) {
	v_mov_b32_e32 v42, v38
	s_waitcnt lgkmcnt(5)
	v_mov_b32_e32 v44, v2
	s_waitcnt lgkmcnt(4)
	v_mov_b32_e32 v45, v48
	s_waitcnt lgkmcnt(3)
	v_mov_b32_e32 v60, v50
	s_waitcnt lgkmcnt(2)
	v_mov_b32_e32 v61, v52
	v_mov_b32_e32 v43, v46
	v_pk_mul_f32 v[44:45], v[40:41], v[44:45]
	v_pk_mul_f32 v[60:61], v[64:65], v[60:61]
	v_pk_mul_f32 v[42:43], v[54:55], v[42:43]
	s_waitcnt lgkmcnt(1)
	v_mov_b32_e32 v62, v56
	s_waitcnt lgkmcnt(0)
	v_mov_b32_e32 v63, v58
	v_bfe_u32 v29, v45, 16, 1
	v_bfe_u32 v38, v44, 16, 1
	v_bfe_u32 v46, v60, 16, 1
	v_pk_mul_f32 v[62:63], v[4:5], v[62:63]
	v_add3_u32 v38, v44, v38, s91
	v_add3_u32 v29, v45, v29, s91
	v_bfe_u32 v44, v42, 16, 1
	v_bfe_u32 v45, v43, 16, 1
	v_bfe_u32 v48, v61, 16, 1
	v_add3_u32 v46, v60, v46, s91
	v_or_b32_e32 v60, s38, v34
	v_bfe_u32 v0, v63, 16, 1
	v_bfe_u32 v2, v62, 16, 1
	v_add3_u32 v48, v61, v48, s91
	v_add3_u32 v43, v43, v45, s91
	v_add3_u32 v42, v42, v44, s91
	v_ashrrev_i32_e32 v61, 31, v60
	v_mov_b32_e32 v58, v57
	v_add3_u32 v2, v62, v2, s91
	v_add3_u32 v0, v63, v0, s91
	v_lshrrev_b32_e32 v42, 16, v42
	v_lshrrev_b32_e32 v43, 16, v43
	v_lshrrev_b32_e32 v44, 16, v46
	v_lshrrev_b32_e32 v45, 16, v48
	v_lshlrev_b64 v[60:61], 11, v[60:61]
	v_mov_b32_e32 v46, v39
	v_mov_b32_e32 v48, v3
	v_pk_mul_f32 v[4:5], v[4:5], v[58:59]
	v_and_or_b32 v45, v0, s35, v45
	v_and_or_b32 v44, v2, s35, v44
	v_and_or_b32 v43, v29, s35, v43
	v_and_or_b32 v42, v38, s35, v42
	v_lshl_add_u64 v[60:61], v[30:31], 0, v[60:61]
	v_pk_mul_f32 v[38:39], v[54:55], v[46:47]
	v_pk_mul_f32 v[2:3], v[40:41], v[48:49]
	v_mov_b32_e32 v52, v51
	v_bfe_u32 v0, v5, 16, 1
	global_store_dwordx4 v[60:61], v[42:45], off sc1
	v_pk_mul_f32 v[40:41], v[64:65], v[52:53]
	v_add3_u32 v0, v5, v0, s91
	v_bfe_u32 v42, v3, 16, 1
	v_bfe_u32 v5, v38, 16, 1
	v_bfe_u32 v29, v4, 16, 1
	v_bfe_u32 v43, v2, 16, 1
	v_add3_u32 v3, v3, v42, s91
	v_bfe_u32 v42, v40, 16, 1
	v_add3_u32 v5, v38, v5, s91
	v_add3_u32 v2, v2, v43, s91
	v_add3_u32 v4, v4, v29, s91
	v_bfe_u32 v29, v39, 16, 1
	v_add3_u32 v40, v40, v42, s91
	v_lshrrev_b32_e32 v38, 16, v5
	v_bfe_u32 v43, v41, 16, 1
	v_add3_u32 v29, v39, v29, s91
	v_lshrrev_b32_e32 v39, 16, v40
	v_and_or_b32 v2, v2, s35, v38
	v_or_b32_e32 v38, s38, v35
	v_add3_u32 v41, v41, v43, s91
	v_and_or_b32 v4, v4, s35, v39
	v_ashrrev_i32_e32 v39, 31, v38
	v_lshrrev_b32_e32 v29, 16, v29
	v_lshrrev_b32_e32 v5, 16, v41
	v_lshlrev_b64 v[38:39], 11, v[38:39]
	v_and_or_b32 v5, v0, s35, v5
	v_and_or_b32 v3, v3, s35, v29
	v_lshl_add_u64 v[30:31], v[30:31], 0, v[38:39]
	global_store_dwordx4 v[30:31], v[2:5], off sc1
	s_waitcnt lgkmcnt(0)
	v_readlane_b32 s5, v252, 1
	v_readlane_b32 s6, v252, 2
	v_readlane_b32 s7, v252, 3
	v_readlane_b32 s10, v252, 6
	v_readlane_b32 s11, v252, 7
	v_readlane_b32 s12, v252, 8
	v_readlane_b32 s13, v252, 9
	v_readlane_b32 s14, v252, 10
	v_readlane_b32 s15, v252, 11
	v_readlane_b32 s16, v252, 12
	v_readlane_b32 s17, v252, 13
	v_readlane_b32 s18, v252, 14
	v_readlane_b32 s19, v252, 15
	s_branch .LBB0_571

; __device__ __forceinline__ unsigned xb_add(unsigned* p, unsigned v) { return __hip_atomic_fetch_add(p, v, __ATOMIC_RELAXED, __HIP_MEMORY_SCOPE_AGENT); }
; __device__ __forceinline__ void xcd_barrier(const XcdBarrier& b) {
;     ...
;     if (threadIdx.x == 0) {
;         unsigned* bar = b.bar;
;         __builtin_amdgcn_s_waitcnt(0);
;         unsigned nloc = b.st[0], nx = b.st[1];
;         if (nloc == 0u) { xcd_barrier_complete(bar, b.x, nloc, nx); b.st[0] = nloc; b.st[1] = nx; }
;         const unsigned old = xb_add(&bar[XB_XSUB(b.x)], 1u);
;         const unsigned gen = old / nloc;
;         if (old + 1u == (gen + 1u) * nloc) {
.LBB0_623:
	s_or_b64 exec, exec, s[28:29]
	buffer_inv sc1
	s_cmpk_lt_u32 s2, 0x80
	s_cbranch_scc1 .Lcd_skip
	v_mov_b32_e32 v5, 0x3f00
	v_mov_b32_e32 v6, 1
	global_atomic_add v5, v6, s[50:51]
.Lcd_skip:
	v_cvt_f32_u32_e32 v5, v3
	s_waitcnt vmcnt(0)
	v_readfirstlane_b32 s28, v4
	v_sub_u32_e32 v4, 0, v3
	v_rcp_iflag_f32_e32 v5, v5
	v_add_u32_e32 v6, s28, v0
	v_mul_f32_e32 v5, 0x4f7ffffe, v5
	v_cvt_u32_f32_e32 v5, v5
	v_mul_lo_u32 v0, v4, v5
	v_mul_hi_u32 v0, v5, v0
	v_add_u32_e32 v0, v5, v0
	v_mul_hi_u32 v0, v6, v0
	v_mul_lo_u32 v4, v0, v3
	v_sub_u32_e32 v4, v6, v4
	v_add_u32_e32 v5, 1, v0
	v_cmp_ge_u32_e32 vcc, v4, v3
	s_nop 1
	v_cndmask_b32_e32 v0, v0, v5, vcc
	v_sub_u32_e32 v5, v4, v3
	v_cndmask_b32_e32 v4, v4, v5, vcc
	v_add_u32_e32 v5, 1, v0
	v_cmp_ge_u32_e32 vcc, v4, v3
	v_add_u32_e32 v4, 1, v6
	s_nop 0
	v_cndmask_b32_e32 v0, v0, v5, vcc
	v_mul_lo_u32 v5, v3, v0
	v_add_u32_e32 v3, v5, v3
	v_cmp_ne_u32_e32 vcc, v4, v3
	s_and_saveexec_b64 s[28:29], vcc
	s_xor_b64 s[28:29], exec, s[28:29]
	s_cbranch_execz .LBB0_637
	v_readlane_b32 s4, v253, 22
	v_readlane_b32 s5, v253, 23
	s_waitcnt lgkmcnt(0)
	s_nop 3
	global_load_dword v2, v1, s[4:5] sc1
	s_waitcnt vmcnt(0)
	v_cmp_eq_u32_e32 vcc, v2, v0
	s_and_saveexec_b64 s[38:39], vcc
	s_cbranch_execz .LBB0_636
	s_mov_b32 s59, 1
	s_mov_b64 s[40:41], 0
	s_branch .LBB0_627

; __device__ __forceinline__ unsigned xb_ld(unsigned* p)              { return __hip_atomic_load(p, __ATOMIC_RELAXED, __HIP_MEMORY_SCOPE_AGENT); }
; __device__ __forceinline__ unsigned xb_add(unsigned* p, unsigned v) { return __hip_atomic_fetch_add(p, v, __ATOMIC_RELAXED, __HIP_MEMORY_SCOPE_AGENT); }
; #define XB_SPIN(cond, bar) do { unsigned _sp = 0; while (cond) { __builtin_amdgcn_s_sleep(1); \
;     if ((++_sp & 255u) == 0u) { if (xb_ld(&(bar)[XB_TMO])) break; if (_sp > XB_SPIN_CAP) { atomicAdd(&(bar)[XB_TMO], 1u); break; } } } } while (0)
; __device__ __forceinline__ void xcd_barrier(const XcdBarrier& b) {
;     ...
;             __builtin_amdgcn_fence(__ATOMIC_RELEASE, "agent");
;             asm volatile("s_waitcnt vmcnt(0)" ::: "memory");
;             const unsigned og = xb_add(&bar[XB_TOP], 1u);
;             const unsigned tg = og / nx;
;             if (og + 1u == (tg + 1u) * nx) xb_add(&bar[XB_TOPGEN], 1u);
;             else XB_SPIN(xb_ld(&bar[XB_TOPGEN]) == tg, bar);
.LBB0_637:
	s_andn2_saveexec_b64 s[28:29], s[28:29]
	s_cbranch_execz .LBB0_657
	s_mov_b64 s[28:29], exec
	v_mov_b32_e32 v5, 0x2000c
	ds_read_b32 v5, v5
	s_waitcnt lgkmcnt(0)
	v_readfirstlane_b32 s4, v5
	s_cmp_lg_u32 s4, 0
	s_cbranch_scc1 .Lsyncg_global
	v_readlane_b32 s4, v254, 51
	s_cmp_lg_u32 s4, 0
	s_cbranch_scc1 .Lsyncg_local
.Lsyncg_global:
	buffer_wbl2 sc1
	s_waitcnt lgkmcnt(0)
	s_waitcnt vmcnt(0)
	v_mbcnt_lo_u32_b32 v0, s28, 0
	v_mbcnt_hi_u32_b32 v0, s29, v0
	v_cmp_eq_u32_e32 vcc, 0, v0
	s_and_saveexec_b64 s[38:39], vcc
	s_cbranch_execz .LBB0_640
	s_bcnt1_i32_b64 s28, s[28:29]
	v_readlane_b32 s4, v253, 24
	v_mov_b32_e32 v3, s28
	v_readlane_b32 s5, v253, 25
	s_nop 4
	global_atomic_add v3, v1, v3, s[4:5] sc0
